# packed f32 VALU ops (v_pk_mul/add/fma_f32) split into scalar f32 ops everywhere (bit-identical)
# baseline (speedup 1.0000x reference)
.LBB0_30:
	ds_read_b128 v[136:139], v149
	ds_read_b128 v[140:143], v149 offset:16
	ds_read_b128 v[132:135], v149 offset:32
	ds_read_b128 v[128:131], v149 offset:48
	ds_read_b128 v[144:147], v149 offset:4096
	ds_read_b128 v[160:163], v149 offset:8192
	ds_read_b128 v[164:167], v149 offset:4112
	ds_read_b128 v[168:171], v149 offset:12288
	ds_read_b128 v[176:179], v149 offset:8208
	ds_read_b128 v[180:183], v149 offset:16384
	ds_read_b128 v[184:187], v149 offset:12304
	s_waitcnt vmcnt(0) lgkmcnt(0)
	v_fma_f32 v172, v0, v136, 0
	v_fma_f32 v173, v1, v136, 0
	v_fma_f32 v192, v2, v136, 0
	v_fma_f32 v193, v3, v136, 0
	s_waitcnt lgkmcnt(6)
	v_fma_f32 v194, v0, v144, 0
	v_fma_f32 v195, v1, v144, 0
	v_fma_f32 v196, v2, v144, 0
	v_fma_f32 v197, v3, v144, 0
	s_waitcnt vmcnt(30)
	v_fma_f32 v192, v6, v137, v192
	v_fma_f32 v193, v7, v137, v193
	v_fma_f32 v136, v4, v137, v172
	v_fma_f32 v137, v5, v137, v173
	s_waitcnt lgkmcnt(5)
	v_fma_f32 v198, v0, v160, 0
	v_fma_f32 v199, v1, v160, 0
	v_fma_f32 v200, v2, v160, 0
	v_fma_f32 v201, v3, v160, 0
	s_waitcnt lgkmcnt(3)
	v_fma_f32 v202, v0, v168, 0
	v_fma_f32 v203, v1, v168, 0
	v_fma_f32 v204, v2, v168, 0
	v_fma_f32 v205, v3, v168, 0
	ds_read_b128 v[188:191], v149 offset:16400
	v_fma_f32 v172, v6, v145, v196
	v_fma_f32 v173, v7, v145, v197
	v_fma_f32 v144, v4, v145, v194
	v_fma_f32 v145, v5, v145, v195
	s_waitcnt vmcnt(29)
	v_fma_f32 v136, v8, v138, v136
	v_fma_f32 v137, v9, v138, v137
	v_fma_f32 v192, v10, v138, v192
	v_fma_f32 v193, v11, v138, v193
	v_mov_b32_e32 v138, v139
	s_waitcnt lgkmcnt(2)
	v_fma_f32 v206, v0, v180, 0
	v_fma_f32 v207, v1, v180, 0
	v_fma_f32 v208, v2, v180, 0
	v_fma_f32 v209, v3, v180, 0
	v_fma_f32 v194, v6, v161, v200
	v_fma_f32 v195, v7, v161, v201
	v_fma_f32 v160, v4, v161, v198
	v_fma_f32 v161, v5, v161, v199
	v_fma_f32 v196, v6, v169, v204
	v_fma_f32 v197, v7, v169, v205
	v_fma_f32 v168, v4, v169, v202
	v_fma_f32 v169, v5, v169, v203
	v_fma_f32 v144, v8, v146, v144
	v_fma_f32 v145, v9, v146, v145
	v_fma_f32 v172, v10, v146, v172
	v_fma_f32 v173, v11, v146, v173
	s_waitcnt vmcnt(28)
	v_fma_f32 v192, v14, v138, v192
	v_fma_f32 v193, v15, v138, v193
	v_fma_f32 v136, v12, v138, v136
	v_fma_f32 v137, v13, v138, v137
	v_mov_b32_e32 v138, v147
	v_fma_f32 v198, v6, v181, v208
	v_fma_f32 v199, v7, v181, v209
	v_fma_f32 v180, v4, v181, v206
	v_fma_f32 v181, v5, v181, v207
	v_fma_f32 v160, v8, v162, v160
	v_fma_f32 v161, v9, v162, v161
	v_fma_f32 v194, v10, v162, v194
	v_fma_f32 v195, v11, v162, v195
	v_fma_f32 v168, v8, v170, v168
	v_fma_f32 v169, v9, v170, v169
	v_fma_f32 v196, v10, v170, v196
	v_fma_f32 v197, v11, v170, v197
	v_fma_f32 v146, v14, v138, v172
	v_fma_f32 v147, v15, v138, v173
	v_fma_f32 v139, v13, v138, v145
	v_fma_f32 v138, v12, v138, v144
	v_mov_b32_e32 v144, v163
	v_mov_b32_e32 v156, v171
	v_fma_f32 v180, v8, v182, v180
	v_fma_f32 v181, v9, v182, v181
	v_fma_f32 v198, v10, v182, v198
	v_fma_f32 v199, v11, v182, v199
	v_fma_f32 v162, v14, v144, v194
	v_fma_f32 v163, v15, v144, v195
	v_fma_f32 v145, v13, v144, v161
	v_fma_f32 v144, v12, v144, v160
	v_fma_f32 v160, v14, v156, v196
	v_fma_f32 v161, v15, v156, v197
	v_fma_f32 v168, v12, v156, v168
	v_fma_f32 v169, v13, v156, v169
	v_mov_b32_e32 v156, v183
	v_fma_f32 v170, v14, v156, v198
	v_fma_f32 v171, v15, v156, v199
	v_fma_f32 v172, v12, v156, v180
	v_fma_f32 v173, v13, v156, v181
	s_waitcnt vmcnt(27)
	v_fma_f32 v136, v16, v140, v136
	v_fma_f32 v137, v17, v140, v137
	v_fma_f32 v180, v18, v140, v192
	v_fma_f32 v181, v19, v140, v193
	v_fma_f32 v138, v16, v164, v138
	v_fma_f32 v139, v17, v164, v139
	v_fma_f32 v146, v18, v164, v146
	v_fma_f32 v147, v19, v164, v147
	s_waitcnt lgkmcnt(0)
	v_fma_f32 v170, v18, v188, v170
	v_fma_f32 v171, v19, v188, v171
	s_waitcnt vmcnt(26)
	v_fma_f32 v180, v22, v141, v180
	v_fma_f32 v181, v23, v141, v181
	v_fma_f32 v136, v20, v141, v136
	v_fma_f32 v137, v21, v141, v137
	v_fma_f32 v144, v16, v176, v144
	v_fma_f32 v145, v17, v176, v145
	v_fma_f32 v162, v18, v176, v162
	v_fma_f32 v163, v19, v176, v163
	v_fma_f32 v140, v22, v165, v146
	v_fma_f32 v141, v23, v165, v147
	v_fma_f32 v138, v20, v165, v138
	v_fma_f32 v139, v21, v165, v139
	v_fma_f32 v164, v22, v189, v170
	v_fma_f32 v165, v23, v189, v171
	s_waitcnt vmcnt(25)
	v_fma_f32 v136, v24, v142, v136
	v_fma_f32 v137, v25, v142, v137
	v_fma_f32 v170, v26, v142, v180
	v_fma_f32 v171, v27, v142, v181
	v_mov_b32_e32 v142, v143
	v_fma_f32 v168, v16, v184, v168
	v_fma_f32 v169, v17, v184, v169
	v_fma_f32 v160, v18, v184, v160
	v_fma_f32 v161, v19, v184, v161
	v_fma_f32 v172, v16, v188, v172
	v_fma_f32 v173, v17, v188, v173
	v_fma_f32 v146, v22, v177, v162
	v_fma_f32 v147, v23, v177, v163
	v_fma_f32 v144, v20, v177, v144
	v_fma_f32 v145, v21, v177, v145
	v_fma_f32 v138, v24, v166, v138
	v_fma_f32 v139, v25, v166, v139
	v_fma_f32 v140, v26, v166, v140
	v_fma_f32 v141, v27, v166, v141
	s_waitcnt vmcnt(24)
	v_fma_f32 v170, v30, v142, v170
	v_fma_f32 v171, v31, v142, v171
	v_fma_f32 v143, v29, v142, v137
	v_fma_f32 v142, v28, v142, v136
	v_mov_b32_e32 v136, v167
	v_fma_f32 v160, v22, v185, v160
	v_fma_f32 v161, v23, v185, v161
	v_fma_f32 v162, v20, v185, v168
	v_fma_f32 v163, v21, v185, v169
	v_fma_f32 v168, v20, v189, v172
	v_fma_f32 v169, v21, v189, v173
	v_fma_f32 v144, v24, v178, v144
	v_fma_f32 v145, v25, v178, v145
	v_fma_f32 v146, v26, v178, v146
	v_fma_f32 v147, v27, v178, v147
	v_fma_f32 v166, v30, v136, v140
	v_fma_f32 v167, v31, v136, v141
	v_fma_f32 v172, v28, v136, v138
	v_fma_f32 v173, v29, v136, v139
	v_mov_b32_e32 v136, v179
	v_fma_f32 v162, v24, v186, v162
	v_fma_f32 v163, v25, v186, v163
	v_fma_f32 v160, v26, v186, v160
	v_fma_f32 v161, v27, v186, v161
	v_fma_f32 v176, v30, v136, v146
	v_fma_f32 v177, v31, v136, v147
	v_fma_f32 v178, v28, v136, v144
	v_fma_f32 v179, v29, v136, v145
	v_mov_b32_e32 v136, v187
	v_fma_f32 v168, v24, v190, v168
	v_fma_f32 v169, v25, v190, v169
	v_fma_f32 v164, v26, v190, v164
	v_fma_f32 v165, v27, v190, v165
	v_fma_f32 v180, v30, v136, v160
	v_fma_f32 v181, v31, v136, v161
	v_fma_f32 v182, v28, v136, v162
	v_fma_f32 v183, v29, v136, v163
	v_mov_b32_e32 v136, v191
	v_fma_f32 v184, v30, v136, v164
	v_fma_f32 v185, v31, v136, v165
	v_fma_f32 v186, v28, v136, v168
	v_fma_f32 v187, v29, v136, v169
	ds_read_b128 v[136:139], v149 offset:4128
	s_waitcnt vmcnt(23)
	v_fma_f32 v188, v32, v132, v142
	v_fma_f32 v189, v33, v132, v143
	ds_read_b128 v[140:143], v149 offset:8224
	ds_read_b128 v[144:147], v149 offset:4144
	v_fma_f32 v190, v34, v132, v170
	v_fma_f32 v191, v35, v132, v171
	s_add_i32 s48, s48, 1
	s_waitcnt lgkmcnt(2)
	v_fma_f32 v192, v34, v136, v166
	v_fma_f32 v193, v35, v136, v167
	ds_read_b128 v[160:163], v149 offset:12320
	ds_read_b128 v[164:167], v149 offset:8240
	s_waitcnt lgkmcnt(3)
	v_fma_f32 v194, v32, v140, v178
	v_fma_f32 v195, v33, v140, v179
	v_fma_f32 v196, v34, v140, v176
	v_fma_f32 v197, v35, v140, v177
	ds_read_b128 v[168:171], v149 offset:16416
	ds_read_b128 v[176:179], v149 offset:12336
	v_fma_f32 v172, v32, v136, v172
	v_fma_f32 v173, v33, v136, v173
	s_waitcnt vmcnt(22)
	v_fma_f32 v190, v38, v133, v190
	v_fma_f32 v191, v39, v133, v191
	v_fma_f32 v132, v36, v133, v188
	v_fma_f32 v133, v37, v133, v189
	s_waitcnt lgkmcnt(1)
	v_fma_f32 v186, v32, v168, v186
	v_fma_f32 v187, v33, v168, v187
	v_fma_f32 v184, v34, v168, v184
	v_fma_f32 v185, v35, v168, v185
	v_fma_f32 v188, v38, v137, v192
	v_fma_f32 v189, v39, v137, v193
	v_fma_f32 v136, v36, v137, v172
	v_fma_f32 v137, v37, v137, v173
	v_fma_f32 v184, v38, v169, v184
	v_fma_f32 v185, v39, v169, v185
	v_fma_f32 v168, v36, v169, v186
	v_fma_f32 v169, v37, v169, v187
	s_waitcnt vmcnt(21)
	v_fma_f32 v132, v40, v134, v132
	v_fma_f32 v133, v41, v134, v133
	v_fma_f32 v186, v42, v134, v190
	v_fma_f32 v187, v43, v134, v191
	v_mov_b32_e32 v134, v135
	v_fma_f32 v200, v34, v160, v180
	v_fma_f32 v201, v35, v160, v181
	v_fma_f32 v172, v38, v141, v196
	v_fma_f32 v173, v39, v141, v197
	v_fma_f32 v140, v36, v141, v194
	v_fma_f32 v141, v37, v141, v195
	v_fma_f32 v136, v40, v138, v136
	v_fma_f32 v137, v41, v138, v137
	v_fma_f32 v188, v42, v138, v188
	v_fma_f32 v189, v43, v138, v189
	s_waitcnt vmcnt(20)
	v_fma_f32 v186, v46, v134, v186
	v_fma_f32 v187, v47, v134, v187
	v_fma_f32 v132, v44, v134, v132
	v_fma_f32 v133, v45, v134, v133
	v_mov_b32_e32 v134, v139
	v_fma_f32 v198, v32, v160, v182
	v_fma_f32 v199, v33, v160, v183
	ds_read_b128 v[180:183], v149 offset:16432
	v_fma_f32 v192, v38, v161, v200
	v_fma_f32 v193, v39, v161, v201
	v_fma_f32 v140, v40, v142, v140
	v_fma_f32 v141, v41, v142, v141
	v_fma_f32 v172, v42, v142, v172
	v_fma_f32 v173, v43, v142, v173
	v_fma_f32 v138, v46, v134, v188
	v_fma_f32 v139, v47, v134, v189
	v_fma_f32 v135, v45, v134, v137
	v_fma_f32 v134, v44, v134, v136
	v_mov_b32_e32 v136, v143
	v_fma_f32 v160, v36, v161, v198
	v_fma_f32 v161, v37, v161, v199
	v_fma_f32 v190, v42, v162, v192
	v_fma_f32 v191, v43, v162, v193
	v_fma_f32 v142, v46, v136, v172
	v_fma_f32 v143, v47, v136, v173
	v_fma_f32 v137, v45, v136, v141
	v_fma_f32 v136, v44, v136, v140
	v_mov_b32_e32 v140, v163
	v_fma_f32 v160, v40, v162, v160
	v_fma_f32 v161, v41, v162, v161
	v_fma_f32 v168, v40, v170, v168
	v_fma_f32 v169, v41, v170, v169
	v_fma_f32 v184, v42, v170, v184
	v_fma_f32 v185, v43, v170, v185
	v_fma_f32 v162, v46, v140, v190
	v_fma_f32 v163, v47, v140, v191
	v_mov_b32_e32 v156, v171
	s_waitcnt vmcnt(19)
	v_fma_f32 v132, v48, v128, v132
	v_fma_f32 v133, v49, v128, v133
	v_fma_f32 v170, v50, v128, v186
	v_fma_f32 v171, v51, v128, v187
	v_fma_f32 v134, v48, v144, v134
	v_fma_f32 v135, v49, v144, v135
	v_fma_f32 v138, v50, v144, v138
	v_fma_f32 v139, v51, v144, v139
	v_fma_f32 v142, v50, v164, v142
	v_fma_f32 v143, v51, v164, v143
	s_waitcnt lgkmcnt(1)
	v_fma_f32 v162, v50, v176, v162
	v_fma_f32 v163, v51, v176, v163
	s_waitcnt vmcnt(18)
	v_fma_f32 v170, v54, v129, v170
	v_fma_f32 v171, v55, v129, v171
	v_fma_f32 v128, v52, v129, v132
	v_fma_f32 v129, v53, v129, v133
	v_fma_f32 v141, v45, v140, v161
	v_fma_f32 v140, v44, v140, v160
	v_fma_f32 v160, v46, v156, v184
	v_fma_f32 v161, v47, v156, v185
	v_fma_f32 v168, v44, v156, v168
	v_fma_f32 v169, v45, v156, v169
	v_fma_f32 v136, v48, v164, v136
	v_fma_f32 v137, v49, v164, v137
	v_fma_f32 v132, v54, v145, v138
	v_fma_f32 v133, v55, v145, v139
	v_fma_f32 v134, v52, v145, v134
	v_fma_f32 v135, v53, v145, v135
	v_fma_f32 v138, v54, v165, v142
	v_fma_f32 v139, v55, v165, v143
	v_fma_f32 v142, v54, v177, v162
	v_fma_f32 v143, v55, v177, v163
	s_waitcnt vmcnt(17)
	v_fma_f32 v128, v56, v130, v128
	v_fma_f32 v129, v57, v130, v129
	v_fma_f32 v162, v58, v130, v170
	v_fma_f32 v163, v59, v130, v171
	v_mov_b32_e32 v130, v131
	v_fma_f32 v140, v48, v176, v140
	v_fma_f32 v141, v49, v176, v141
	s_waitcnt lgkmcnt(0)
	v_fma_f32 v168, v48, v180, v168
	v_fma_f32 v169, v49, v180, v169
	v_fma_f32 v160, v50, v180, v160
	v_fma_f32 v161, v51, v180, v161
	v_fma_f32 v136, v52, v165, v136
	v_fma_f32 v137, v53, v165, v137
	v_fma_f32 v134, v56, v146, v134
	v_fma_f32 v135, v57, v146, v135
	v_fma_f32 v132, v58, v146, v132
	v_fma_f32 v133, v59, v146, v133
	s_waitcnt vmcnt(16)
	v_fma_f32 v164, v60, v130, v128
	v_fma_f32 v165, v61, v130, v129
	v_mov_b32_e32 v128, v147
	v_fma_f32 v140, v52, v177, v140
	v_fma_f32 v141, v53, v177, v141
	v_fma_f32 v144, v54, v181, v160
	v_fma_f32 v145, v55, v181, v161
	v_fma_f32 v160, v52, v181, v168
	v_fma_f32 v161, v53, v181, v169
	v_fma_f32 v136, v56, v166, v136
	v_fma_f32 v137, v57, v166, v137
	v_fma_f32 v138, v58, v166, v138
	v_fma_f32 v139, v59, v166, v139
	v_fma_f32 v168, v62, v128, v132
	v_fma_f32 v169, v63, v128, v133
	v_fma_f32 v170, v60, v128, v134
	v_fma_f32 v171, v61, v128, v135
	v_mov_b32_e32 v128, v167
	v_fma_f32 v140, v56, v178, v140
	v_fma_f32 v141, v57, v178, v141
	v_fma_f32 v142, v58, v178, v142
	v_fma_f32 v143, v59, v178, v143
	v_fma_f32 v172, v62, v128, v138
	v_fma_f32 v173, v63, v128, v139
	v_fma_f32 v176, v60, v128, v136
	v_fma_f32 v177, v61, v128, v137
	v_mov_b32_e32 v128, v179
	v_fma_f32 v160, v56, v182, v160
	v_fma_f32 v161, v57, v182, v161
	v_fma_f32 v144, v58, v182, v144
	v_fma_f32 v145, v59, v182, v145
	v_fma_f32 v162, v62, v130, v162
	v_fma_f32 v163, v63, v130, v163
	v_fma_f32 v180, v62, v128, v142
	v_fma_f32 v181, v63, v128, v143
	v_fma_f32 v184, v60, v128, v140
	v_fma_f32 v185, v61, v128, v141
	v_mov_b32_e32 v132, v183
	ds_read_b128 v[128:131], v149 offset:64
	v_fma_f32 v186, v62, v132, v144
	v_fma_f32 v187, v63, v132, v145
	v_fma_f32 v188, v60, v132, v160
	v_fma_f32 v189, v61, v132, v161
	ds_read_b128 v[132:135], v149 offset:4160
	ds_read_b128 v[136:139], v149 offset:80
	ds_read_b128 v[140:143], v149 offset:8256
	ds_read_b128 v[144:147], v149 offset:4176
	s_waitcnt vmcnt(15) lgkmcnt(4)
	v_fma_f32 v190, v64, v128, v164
	v_fma_f32 v191, v65, v128, v165
	v_fma_f32 v192, v66, v128, v162
	v_fma_f32 v193, v67, v128, v163
	s_waitcnt lgkmcnt(3)
	v_fma_f32 v194, v64, v132, v170
	v_fma_f32 v195, v65, v132, v171
	v_fma_f32 v196, v66, v132, v168
	v_fma_f32 v197, v67, v132, v169
	ds_read_b128 v[160:163], v149 offset:12352
	ds_read_b128 v[164:167], v149 offset:8272
	s_waitcnt lgkmcnt(3)
	v_fma_f32 v198, v64, v140, v176
	v_fma_f32 v199, v65, v140, v177
	ds_read_b128 v[168:171], v149 offset:16448
	ds_read_b128 v[176:179], v149 offset:12368
	s_waitcnt vmcnt(14)
	v_fma_f32 v192, v70, v129, v192
	v_fma_f32 v193, v71, v129, v193
	s_waitcnt lgkmcnt(3)
	v_fma_f32 v184, v64, v160, v184
	v_fma_f32 v185, v65, v160, v185
	v_fma_f32 v200, v66, v160, v180
	v_fma_f32 v201, v67, v160, v181
	s_waitcnt lgkmcnt(1)
	v_fma_f32 v186, v66, v168, v186
	v_fma_f32 v187, v67, v168, v187
	v_fma_f32 v128, v68, v129, v190
	v_fma_f32 v129, v69, v129, v191
	v_fma_f32 v172, v66, v140, v172
	v_fma_f32 v173, v67, v140, v173
	v_fma_f32 v188, v64, v168, v188
	v_fma_f32 v189, v65, v168, v189
	v_fma_f32 v190, v70, v133, v196
	v_fma_f32 v191, v71, v133, v197
	v_fma_f32 v132, v68, v133, v194
	v_fma_f32 v133, v69, v133, v195
	v_fma_f32 v194, v70, v161, v200
	v_fma_f32 v195, v71, v161, v201
	v_fma_f32 v160, v68, v161, v184
	v_fma_f32 v161, v69, v161, v185
	v_fma_f32 v184, v70, v169, v186
	v_fma_f32 v185, v71, v169, v187
	s_waitcnt vmcnt(13)
	v_fma_f32 v128, v72, v130, v128
	v_fma_f32 v129, v73, v130, v129
	v_fma_f32 v186, v74, v130, v192
	v_fma_f32 v187, v75, v130, v193
	v_mov_b32_e32 v130, v131
	v_fma_f32 v172, v70, v141, v172
	v_fma_f32 v173, v71, v141, v173
	v_fma_f32 v140, v68, v141, v198
	v_fma_f32 v141, v69, v141, v199
	v_fma_f32 v168, v68, v169, v188
	v_fma_f32 v169, v69, v169, v189
	v_fma_f32 v132, v72, v134, v132
	v_fma_f32 v133, v73, v134, v133
	v_fma_f32 v188, v74, v134, v190
	v_fma_f32 v189, v75, v134, v191
	s_waitcnt vmcnt(12)
	v_fma_f32 v186, v78, v130, v186
	v_fma_f32 v187, v79, v130, v187
	v_fma_f32 v128, v76, v130, v128
	v_fma_f32 v129, v77, v130, v129
	v_mov_b32_e32 v130, v135
	ds_read_b128 v[180:183], v149 offset:16464
	v_fma_f32 v140, v72, v142, v140
	v_fma_f32 v141, v73, v142, v141
	v_fma_f32 v172, v74, v142, v172
	v_fma_f32 v173, v75, v142, v173
	v_fma_f32 v134, v78, v130, v188
	v_fma_f32 v135, v79, v130, v189
	v_fma_f32 v131, v77, v130, v133
	v_fma_f32 v130, v76, v130, v132
	v_mov_b32_e32 v132, v143
	v_fma_f32 v190, v74, v162, v194
	v_fma_f32 v191, v75, v162, v195
	v_fma_f32 v142, v78, v132, v172
	v_fma_f32 v143, v79, v132, v173
	v_fma_f32 v133, v77, v132, v141
	v_fma_f32 v132, v76, v132, v140
	v_mov_b32_e32 v140, v163
	v_fma_f32 v160, v72, v162, v160
	v_fma_f32 v161, v73, v162, v161
	v_fma_f32 v168, v72, v170, v168
	v_fma_f32 v169, v73, v170, v169
	v_fma_f32 v184, v74, v170, v184
	v_fma_f32 v185, v75, v170, v185
	v_fma_f32 v162, v78, v140, v190
	v_fma_f32 v163, v79, v140, v191
	v_mov_b32_e32 v156, v171
	s_waitcnt vmcnt(11)
	v_fma_f32 v128, v80, v136, v128
	v_fma_f32 v129, v81, v136, v129
	v_fma_f32 v170, v82, v136, v186
	v_fma_f32 v171, v83, v136, v187
	v_fma_f32 v130, v80, v144, v130
	v_fma_f32 v131, v81, v144, v131
	v_fma_f32 v134, v82, v144, v134
	v_fma_f32 v135, v83, v144, v135
	v_fma_f32 v142, v82, v164, v142
	v_fma_f32 v143, v83, v164, v143
	s_waitcnt lgkmcnt(1)
	v_fma_f32 v162, v82, v176, v162
	v_fma_f32 v163, v83, v176, v163
	s_waitcnt vmcnt(10)
	v_fma_f32 v170, v86, v137, v170
	v_fma_f32 v171, v87, v137, v171
	v_fma_f32 v128, v84, v137, v128
	v_fma_f32 v129, v85, v137, v129
	v_fma_f32 v141, v77, v140, v161
	v_fma_f32 v140, v76, v140, v160
	v_fma_f32 v160, v78, v156, v184
	v_fma_f32 v161, v79, v156, v185
	v_fma_f32 v168, v76, v156, v168
	v_fma_f32 v169, v77, v156, v169
	v_fma_f32 v132, v80, v164, v132
	v_fma_f32 v133, v81, v164, v133
	v_fma_f32 v134, v86, v145, v134
	v_fma_f32 v135, v87, v145, v135
	v_fma_f32 v130, v84, v145, v130
	v_fma_f32 v131, v85, v145, v131
	v_fma_f32 v136, v86, v165, v142
	v_fma_f32 v137, v87, v165, v143
	v_fma_f32 v142, v86, v177, v162
	v_fma_f32 v143, v87, v177, v163
	s_waitcnt vmcnt(9)
	v_fma_f32 v128, v88, v138, v128
	v_fma_f32 v129, v89, v138, v129
	v_fma_f32 v162, v90, v138, v170
	v_fma_f32 v163, v91, v138, v171
	v_mov_b32_e32 v138, v139
	v_fma_f32 v140, v80, v176, v140
	v_fma_f32 v141, v81, v176, v141
	s_waitcnt lgkmcnt(0)
	v_fma_f32 v168, v80, v180, v168
	v_fma_f32 v169, v81, v180, v169
	v_fma_f32 v160, v82, v180, v160
	v_fma_f32 v161, v83, v180, v161
	v_fma_f32 v132, v84, v165, v132
	v_fma_f32 v133, v85, v165, v133
	v_fma_f32 v130, v88, v146, v130
	v_fma_f32 v131, v89, v146, v131
	v_fma_f32 v134, v90, v146, v134
	v_fma_f32 v135, v91, v146, v135
	s_waitcnt vmcnt(8)
	v_fma_f32 v164, v92, v138, v128
	v_fma_f32 v165, v93, v138, v129
	v_mov_b32_e32 v128, v147
	v_fma_f32 v140, v84, v177, v140
	v_fma_f32 v141, v85, v177, v141
	v_fma_f32 v144, v86, v181, v160
	v_fma_f32 v145, v87, v181, v161
	v_fma_f32 v160, v84, v181, v168
	v_fma_f32 v161, v85, v181, v169
	v_fma_f32 v132, v88, v166, v132
	v_fma_f32 v133, v89, v166, v133
	v_fma_f32 v136, v90, v166, v136
	v_fma_f32 v137, v91, v166, v137
	v_fma_f32 v168, v94, v128, v134
	v_fma_f32 v169, v95, v128, v135
	v_fma_f32 v170, v92, v128, v130
	v_fma_f32 v171, v93, v128, v131
	v_mov_b32_e32 v128, v167
	v_fma_f32 v140, v88, v178, v140
	v_fma_f32 v141, v89, v178, v141
	v_fma_f32 v142, v90, v178, v142
	v_fma_f32 v143, v91, v178, v143
	v_fma_f32 v172, v94, v128, v136
	v_fma_f32 v173, v95, v128, v137
	v_fma_f32 v176, v92, v128, v132
	v_fma_f32 v177, v93, v128, v133
	v_mov_b32_e32 v128, v179
	v_fma_f32 v160, v88, v182, v160
	v_fma_f32 v161, v89, v182, v161
	v_fma_f32 v144, v90, v182, v144
	v_fma_f32 v145, v91, v182, v145
	v_fma_f32 v180, v94, v128, v142
	v_fma_f32 v181, v95, v128, v143
	v_fma_f32 v184, v92, v128, v140
	v_fma_f32 v185, v93, v128, v141
	v_mov_b32_e32 v132, v183
	ds_read_b128 v[128:131], v149 offset:96
	v_fma_f32 v162, v94, v138, v162
	v_fma_f32 v163, v95, v138, v163
	v_fma_f32 v186, v94, v132, v144
	v_fma_f32 v187, v95, v132, v145
	v_fma_f32 v188, v92, v132, v160
	v_fma_f32 v189, v93, v132, v161
	ds_read_b128 v[132:135], v149 offset:4192
	ds_read_b128 v[136:139], v149 offset:112
	ds_read_b128 v[140:143], v149 offset:8288
	ds_read_b128 v[144:147], v149 offset:4208
	s_waitcnt vmcnt(7) lgkmcnt(4)
	v_fma_f32 v190, v96, v128, v164
	v_fma_f32 v191, v97, v128, v165
	v_fma_f32 v192, v98, v128, v162
	v_fma_f32 v193, v99, v128, v163
	s_waitcnt lgkmcnt(3)
	v_fma_f32 v194, v96, v132, v170
	v_fma_f32 v195, v97, v132, v171
	v_fma_f32 v196, v98, v132, v168
	v_fma_f32 v197, v99, v132, v169
	ds_read_b128 v[160:163], v149 offset:12384
	ds_read_b128 v[164:167], v149 offset:8304
	s_waitcnt lgkmcnt(3)
	v_fma_f32 v198, v96, v140, v176
	v_fma_f32 v199, v97, v140, v177
	ds_read_b128 v[168:171], v149 offset:16480
	ds_read_b128 v[176:179], v149 offset:12400
	s_waitcnt vmcnt(6)
	v_fma_f32 v192, v102, v129, v192
	v_fma_f32 v193, v103, v129, v193
	s_waitcnt lgkmcnt(3)
	v_fma_f32 v184, v96, v160, v184
	v_fma_f32 v185, v97, v160, v185
	v_fma_f32 v200, v98, v160, v180
	v_fma_f32 v201, v99, v160, v181
	s_waitcnt lgkmcnt(1)
	v_fma_f32 v186, v98, v168, v186
	v_fma_f32 v187, v99, v168, v187
	v_fma_f32 v128, v100, v129, v190
	v_fma_f32 v129, v101, v129, v191
	v_fma_f32 v172, v98, v140, v172
	v_fma_f32 v173, v99, v140, v173
	ds_read_b128 v[180:183], v149 offset:16496
	v_fma_f32 v188, v96, v168, v188
	v_fma_f32 v189, v97, v168, v189
	v_fma_f32 v190, v102, v133, v196
	v_fma_f32 v191, v103, v133, v197
	v_fma_f32 v132, v100, v133, v194
	v_fma_f32 v133, v101, v133, v195
	v_fma_f32 v194, v102, v161, v200
	v_fma_f32 v195, v103, v161, v201
	v_fma_f32 v160, v100, v161, v184
	v_fma_f32 v161, v101, v161, v185
	v_fma_f32 v184, v102, v169, v186
	v_fma_f32 v185, v103, v169, v187
	s_waitcnt vmcnt(5)
	v_fma_f32 v128, v104, v130, v128
	v_fma_f32 v129, v105, v130, v129
	v_fma_f32 v186, v106, v130, v192
	v_fma_f32 v187, v107, v130, v193
	v_mov_b32_e32 v130, v131
	v_fma_f32 v172, v102, v141, v172
	v_fma_f32 v173, v103, v141, v173
	v_fma_f32 v140, v100, v141, v198
	v_fma_f32 v141, v101, v141, v199
	v_fma_f32 v168, v100, v169, v188
	v_fma_f32 v169, v101, v169, v189
	v_fma_f32 v132, v104, v134, v132
	v_fma_f32 v133, v105, v134, v133
	v_fma_f32 v188, v106, v134, v190
	v_fma_f32 v189, v107, v134, v191
	s_waitcnt vmcnt(4)
	v_fma_f32 v186, v110, v130, v186
	v_fma_f32 v187, v111, v130, v187
	v_fma_f32 v128, v108, v130, v128
	v_fma_f32 v129, v109, v130, v129
	v_mov_b32_e32 v130, v135
	v_fma_f32 v140, v104, v142, v140
	v_fma_f32 v141, v105, v142, v141
	v_fma_f32 v172, v106, v142, v172
	v_fma_f32 v173, v107, v142, v173
	v_fma_f32 v134, v110, v130, v188
	v_fma_f32 v135, v111, v130, v189
	v_fma_f32 v131, v109, v130, v133
	v_fma_f32 v130, v108, v130, v132
	v_mov_b32_e32 v132, v143
	v_fma_f32 v160, v104, v162, v160
	v_fma_f32 v161, v105, v162, v161
	v_fma_f32 v190, v106, v162, v194
	v_fma_f32 v191, v107, v162, v195
	v_fma_f32 v168, v104, v170, v168
	v_fma_f32 v169, v105, v170, v169
	v_fma_f32 v184, v106, v170, v184
	v_fma_f32 v185, v107, v170, v185
	v_fma_f32 v142, v110, v132, v172
	v_fma_f32 v143, v111, v132, v173
	v_fma_f32 v133, v109, v132, v141
	v_fma_f32 v132, v108, v132, v140
	v_mov_b32_e32 v140, v163
	v_mov_b32_e32 v156, v171
	v_fma_f32 v162, v110, v140, v190
	v_fma_f32 v163, v111, v140, v191
	v_fma_f32 v141, v109, v140, v161
	v_fma_f32 v140, v108, v140, v160
	v_fma_f32 v160, v110, v156, v184
	v_fma_f32 v161, v111, v156, v185
	v_fma_f32 v168, v108, v156, v168
	v_fma_f32 v169, v109, v156, v169
	s_waitcnt vmcnt(3)
	v_fma_f32 v128, v112, v136, v128
	v_fma_f32 v129, v113, v136, v129
	v_fma_f32 v170, v114, v136, v186
	v_fma_f32 v171, v115, v136, v187
	v_fma_f32 v130, v112, v144, v130
	v_fma_f32 v131, v113, v144, v131
	v_fma_f32 v134, v114, v144, v134
	v_fma_f32 v135, v115, v144, v135
	v_fma_f32 v132, v112, v164, v132
	v_fma_f32 v133, v113, v164, v133
	v_fma_f32 v142, v114, v164, v142
	v_fma_f32 v143, v115, v164, v143
	s_waitcnt lgkmcnt(1)
	v_fma_f32 v140, v112, v176, v140
	v_fma_f32 v141, v113, v176, v141
	v_fma_f32 v162, v114, v176, v162
	v_fma_f32 v163, v115, v176, v163
	s_waitcnt lgkmcnt(0)
	v_fma_f32 v168, v112, v180, v168
	v_fma_f32 v169, v113, v180, v169
	v_fma_f32 v160, v114, v180, v160
	v_fma_f32 v161, v115, v180, v161
	s_waitcnt vmcnt(2)
	v_fma_f32 v170, v118, v137, v170
	v_fma_f32 v171, v119, v137, v171
	v_fma_f32 v128, v116, v137, v128
	v_fma_f32 v129, v117, v137, v129
	v_fma_f32 v134, v118, v145, v134
	v_fma_f32 v135, v119, v145, v135
	v_fma_f32 v130, v116, v145, v130
	v_fma_f32 v131, v117, v145, v131
	v_fma_f32 v136, v118, v165, v142
	v_fma_f32 v137, v119, v165, v143
	v_fma_f32 v132, v116, v165, v132
	v_fma_f32 v133, v117, v165, v133
	v_fma_f32 v142, v118, v177, v162
	v_fma_f32 v143, v119, v177, v163
	v_fma_f32 v140, v116, v177, v140
	v_fma_f32 v141, v117, v177, v141
	v_fma_f32 v144, v118, v181, v160
	v_fma_f32 v145, v119, v181, v161
	v_fma_f32 v160, v116, v181, v168
	v_fma_f32 v161, v117, v181, v169
	s_waitcnt vmcnt(1)
	v_fma_f32 v128, v120, v138, v128
	v_fma_f32 v129, v121, v138, v129
	v_fma_f32 v162, v122, v138, v170
	v_fma_f32 v163, v123, v138, v171
	v_fma_f32 v164, v120, v146, v130
	v_fma_f32 v165, v121, v146, v131
	v_fma_f32 v134, v122, v146, v134
	v_fma_f32 v135, v123, v146, v135
	v_fma_f32 v168, v120, v166, v132
	v_fma_f32 v169, v121, v166, v133
	v_fma_f32 v136, v122, v166, v136
	v_fma_f32 v137, v123, v166, v137
	v_mov_b32_e32 v132, v139
	v_mov_b32_e32 v146, v167
	v_fma_f32 v140, v120, v178, v140
	v_fma_f32 v141, v121, v178, v141
	v_fma_f32 v142, v122, v178, v142
	v_fma_f32 v143, v123, v178, v143
	v_fma_f32 v160, v120, v182, v160
	v_fma_f32 v161, v121, v182, v161
	v_fma_f32 v144, v122, v182, v144
	v_fma_f32 v145, v123, v182, v145
	s_waitcnt vmcnt(0)
	v_fma_f32 v130, v126, v132, v162
	v_fma_f32 v131, v127, v132, v163
	v_fma_f32 v128, v124, v132, v128
	v_fma_f32 v129, v125, v132, v129
	v_mov_b32_e32 v132, v147
	v_fma_f32 v138, v126, v146, v136
	v_fma_f32 v139, v127, v146, v137
	v_fma_f32 v136, v124, v146, v168
	v_fma_f32 v137, v125, v146, v169
	v_mov_b32_e32 v146, v179
	v_mov_b32_e32 v156, v183
	v_fma_f32 v134, v126, v132, v134
	v_fma_f32 v135, v127, v132, v135
	v_fma_f32 v133, v125, v132, v165
	v_fma_f32 v132, v124, v132, v164
	v_fma_f32 v142, v126, v146, v142
	v_fma_f32 v143, v127, v146, v143
	v_fma_f32 v140, v124, v146, v140
	v_fma_f32 v141, v125, v146, v141
	v_fma_f32 v146, v126, v156, v144
	v_fma_f32 v147, v127, v156, v145
	s_cmp_ge_u32 s48, s18
	v_fma_f32 v144, v124, v156, v160
	v_fma_f32 v145, v125, v156, v161
	s_cbranch_scc1 .LBB0_32
	s_add_i32 s10, s2, 0x70
	s_mul_hi_u32 s16, s10, 0xaaaaaaab
	s_lshr_b32 s49, s16, 6
	v_mad_u64_u32 v[0:1], s[16:17], s49, v158, v[150:151]
	s_mulk_i32 s49, 0x60
	s_sub_i32 s10, s10, s49
	s_lshl_b32 s10, s10, 6
	v_lshl_add_u64 v[120:121], s[10:11], 2, v[0:1]
	s_nop 0
	v_add_co_u32_e32 v4, vcc, s19, v120
	s_nop 1
	v_addc_co_u32_e32 v5, vcc, 0, v121, vcc
	v_add_co_u32_e32 v8, vcc, s20, v120
	flat_load_dwordx4 v[0:3], v[120:121]
	s_nop 0
	flat_load_dwordx4 v[4:7], v[4:5]
	v_addc_co_u32_e32 v9, vcc, 0, v121, vcc
	v_add_co_u32_e32 v12, vcc, s22, v120
	s_nop 1
	v_addc_co_u32_e32 v13, vcc, 0, v121, vcc
	v_add_co_u32_e32 v16, vcc, s23, v120
	flat_load_dwordx4 v[8:11], v[8:9]
	s_nop 0
	flat_load_dwordx4 v[12:15], v[12:13]
	v_addc_co_u32_e32 v17, vcc, 0, v121, vcc
	v_add_co_u32_e32 v20, vcc, s24, v120
	s_nop 1
	v_addc_co_u32_e32 v21, vcc, 0, v121, vcc
	v_add_co_u32_e32 v24, vcc, s25, v120
	flat_load_dwordx4 v[16:19], v[16:17]
	s_nop 0
	flat_load_dwordx4 v[20:23], v[20:21]
	v_addc_co_u32_e32 v25, vcc, 0, v121, vcc
	v_add_co_u32_e32 v28, vcc, s26, v120
	s_nop 1
	v_addc_co_u32_e32 v29, vcc, 0, v121, vcc
	v_add_co_u32_e32 v32, vcc, s27, v120
	flat_load_dwordx4 v[24:27], v[24:25]
	s_nop 0
	flat_load_dwordx4 v[28:31], v[28:29]
	v_addc_co_u32_e32 v33, vcc, 0, v121, vcc
	v_add_co_u32_e32 v36, vcc, s28, v120
	s_nop 1
	v_addc_co_u32_e32 v37, vcc, 0, v121, vcc
	v_add_co_u32_e32 v40, vcc, s29, v120
	flat_load_dwordx4 v[32:35], v[32:33]
	s_nop 0
	flat_load_dwordx4 v[36:39], v[36:37]
	v_addc_co_u32_e32 v41, vcc, 0, v121, vcc
	v_add_co_u32_e32 v44, vcc, s30, v120
	s_nop 1
	v_addc_co_u32_e32 v45, vcc, 0, v121, vcc
	v_add_co_u32_e32 v48, vcc, s31, v120
	flat_load_dwordx4 v[40:43], v[40:41]
	s_nop 0
	flat_load_dwordx4 v[44:47], v[44:45]
	v_addc_co_u32_e32 v49, vcc, 0, v121, vcc
	v_add_co_u32_e32 v52, vcc, s33, v120
	s_nop 1
	v_addc_co_u32_e32 v53, vcc, 0, v121, vcc
	v_add_co_u32_e32 v56, vcc, s34, v120
	flat_load_dwordx4 v[48:51], v[48:49]
	s_nop 0
	flat_load_dwordx4 v[52:55], v[52:53]
	v_addc_co_u32_e32 v57, vcc, 0, v121, vcc
	v_add_co_u32_e32 v60, vcc, s35, v120
	s_nop 1
	v_addc_co_u32_e32 v61, vcc, 0, v121, vcc
	v_add_co_u32_e32 v64, vcc, s36, v120
	flat_load_dwordx4 v[56:59], v[56:57]
	s_nop 0
	flat_load_dwordx4 v[60:63], v[60:61]
	v_addc_co_u32_e32 v65, vcc, 0, v121, vcc
	v_add_co_u32_e32 v68, vcc, s37, v120
	s_nop 1
	v_addc_co_u32_e32 v69, vcc, 0, v121, vcc
	v_add_co_u32_e32 v72, vcc, s38, v120
	flat_load_dwordx4 v[64:67], v[64:65]
	s_nop 0
	flat_load_dwordx4 v[68:71], v[68:69]
	v_addc_co_u32_e32 v73, vcc, 0, v121, vcc
	v_add_co_u32_e32 v76, vcc, s39, v120
	s_nop 1
	v_addc_co_u32_e32 v77, vcc, 0, v121, vcc
	v_add_co_u32_e32 v80, vcc, s40, v120
	flat_load_dwordx4 v[72:75], v[72:73]
	s_nop 0
	flat_load_dwordx4 v[76:79], v[76:77]
	v_addc_co_u32_e32 v81, vcc, 0, v121, vcc
	v_add_co_u32_e32 v84, vcc, s41, v120
	s_nop 1
	v_addc_co_u32_e32 v85, vcc, 0, v121, vcc
	v_add_co_u32_e32 v88, vcc, s42, v120
	flat_load_dwordx4 v[80:83], v[80:81]
	s_nop 0
	flat_load_dwordx4 v[84:87], v[84:85]
	v_addc_co_u32_e32 v89, vcc, 0, v121, vcc
	v_add_co_u32_e32 v92, vcc, s43, v120
	s_nop 1
	v_addc_co_u32_e32 v93, vcc, 0, v121, vcc
	v_add_co_u32_e32 v96, vcc, s44, v120
	flat_load_dwordx4 v[88:91], v[88:89]
	s_nop 0
	flat_load_dwordx4 v[92:95], v[92:93]
	v_addc_co_u32_e32 v97, vcc, 0, v121, vcc
	v_add_co_u32_e32 v100, vcc, s45, v120
	s_nop 1
	v_addc_co_u32_e32 v101, vcc, 0, v121, vcc
	v_add_co_u32_e32 v104, vcc, s46, v120
	flat_load_dwordx4 v[96:99], v[96:97]
	s_nop 0
	flat_load_dwordx4 v[100:103], v[100:101]
	v_addc_co_u32_e32 v105, vcc, 0, v121, vcc
	v_add_co_u32_e32 v108, vcc, s47, v120
	s_nop 1
	v_addc_co_u32_e32 v109, vcc, 0, v121, vcc
	v_add_co_u32_e32 v112, vcc, 0xa8000, v120
	flat_load_dwordx4 v[104:107], v[104:105]
	s_nop 0
	flat_load_dwordx4 v[108:111], v[108:109]
	v_addc_co_u32_e32 v113, vcc, 0, v121, vcc
	v_add_co_u32_e32 v116, vcc, 0xae000, v120
	s_nop 1
	v_addc_co_u32_e32 v117, vcc, 0, v121, vcc
	v_add_co_u32_e32 v122, vcc, 0xb4000, v120
	flat_load_dwordx4 v[112:115], v[112:113]
	s_nop 0
	flat_load_dwordx4 v[116:119], v[116:117]
	v_addc_co_u32_e32 v123, vcc, 0, v121, vcc
	v_add_co_u32_e32 v124, vcc, 0xba000, v120
	s_nop 1
	v_addc_co_u32_e32 v125, vcc, 0, v121, vcc
	flat_load_dwordx4 v[120:123], v[122:123]
	s_nop 0
	flat_load_dwordx4 v[124:127], v[124:125]

.LBB0_36:
	v_add_u32_e32 v53, s25, v7
	v_add_u32_e32 v52, s23, v48
	v_cvt_f32_i32_e32 v53, v53
	v_cvt_f32_i32_e32 v52, v52
	v_add_u32_e32 v54, s23, v46
	v_lshl_or_b32 v86, v54, 8, v6
	v_div_scale_f32 v56, s[4:5], v50, v50, v53
	v_div_scale_f32 v58, s[4:5], v50, v50, v52
	v_mul_f32 v54, v52, s20
	v_mul_f32 v55, v53, s20
	v_rcp_f32_e32 v60, v56
	v_rcp_f32_e32 v61, v58
	v_div_scale_f32 v62, s[6:7], v49, v49, v55
	v_div_scale_f32 v64, s[8:9], v49, v49, v54
	v_rcp_f32_e32 v66, v62
	v_rcp_f32_e32 v67, v64
	v_fma_f32 v68, -v56, v60, 1.0
	v_div_scale_f32 v57, vcc, v53, v50, v53
	v_fma_f32 v69, -v58, v61, 1.0
	v_fmac_f32_e32 v60, v68, v60
	v_div_scale_f32 v59, s[4:5], v52, v50, v52
	v_fmac_f32_e32 v61, v69, v61
	v_fma_f32 v68, -v62, v66, 1.0
	v_mul_f32_e32 v70, v57, v60
	v_div_scale_f32 v63, s[6:7], v55, v49, v55
	v_fma_f32 v69, -v64, v67, 1.0
	v_mul_f32_e32 v71, v59, v61
	v_fmac_f32_e32 v66, v68, v66
	v_fma_f32 v68, -v56, v70, v57
	v_div_scale_f32 v65, s[8:9], v54, v49, v54
	v_fmac_f32_e32 v67, v69, v67
	v_fma_f32 v69, -v58, v71, v59
	v_mul_f32_e32 v72, v63, v66
	v_fmac_f32_e32 v70, v68, v60
	v_mul_f32_e32 v73, v65, v67
	v_fmac_f32_e32 v71, v69, v61
	v_fma_f32 v68, -v62, v72, v63
	v_fma_f32 v56, -v56, v70, v57
	v_fma_f32 v69, -v64, v73, v65
	v_fma_f32 v57, -v58, v71, v59
	v_fmac_f32_e32 v72, v68, v66
	v_div_fmas_f32 v56, v56, v60, v70
	s_mov_b64 vcc, s[4:5]
	v_fmac_f32_e32 v73, v69, v67
	v_fma_f32 v58, -v62, v72, v63
	v_div_fixup_f32 v53, v56, v50, v53
	v_div_fmas_f32 v56, v57, v61, v71
	s_mov_b64 vcc, s[6:7]
	v_fma_f32 v59, -v64, v73, v65
	v_div_fixup_f32 v52, v56, v50, v52
	v_div_fmas_f32 v56, v58, v66, v72
	s_mov_b64 vcc, s[8:9]
	v_div_fixup_f32 v55, v56, v49, v55
	v_div_fmas_f32 v56, v59, v67, v73
	s_add_i32 s23, s23, 2
	v_div_fixup_f32 v54, v56, v49, v54
	v_add_u32_e32 v51, s25, v5
	s_add_i32 s25, s25, 2
	v_mul_f32 v56, v54, s22
	v_mul_f32 v57, v55, s22
	v_mul_f32 v58, v54, s24
	v_mul_f32 v59, v55, s24
	v_mul_f32 v60, v54, s26
	v_mul_f32 v61, v55, s26
	v_mul_f32 v62, v54, s28
	v_mul_f32 v63, v55, s28
	v_mul_f32 v64, v54, s30
	v_mul_f32 v65, v55, s30
	v_mul_f32 v66, v54, s34
	v_mul_f32 v67, v55, s34
	v_mul_f32 v68, v54, s36
	v_mul_f32 v69, v55, s36
	v_mul_f32 v54, v54, s40
	v_mul_f32 v55, v55, s40
	v_mul_f32_e32 v57, 0.15915494, v57
	v_mul_f32_e32 v56, 0.15915494, v56
	v_mul_f32_e32 v84, 0.15915494, v55
	v_mul_f32_e32 v87, 0.15915494, v54
	v_cos_f32_e32 v55, v57
	v_cos_f32_e32 v54, v56
	v_mul_f32_e32 v70, 0.15915494, v59
	v_mul_f32_e32 v71, 0.15915494, v58
	v_sin_f32_e32 v57, v57
	v_sin_f32_e32 v56, v56
	v_cos_f32_e32 v59, v70
	v_cos_f32_e32 v58, v71
	v_mul_f32_e32 v72, 0.15915494, v61
	v_mul_f32_e32 v73, 0.15915494, v60
	v_sin_f32_e32 v61, v70
	v_sin_f32_e32 v60, v71
	v_mul_f32 v54, v22, v54
	v_mul_f32 v55, v23, v55
	v_mul_f32_e32 v74, 0.15915494, v63
	v_mul_f32_e32 v75, 0.15915494, v62
	v_cos_f32_e32 v63, v72
	v_cos_f32_e32 v62, v73
	v_fma_f32 v52, v24, v52, v54
	v_fma_f32 v53, v25, v53, v55
	v_mul_f32_e32 v76, 0.15915494, v65
	v_mul_f32_e32 v77, 0.15915494, v64
	v_sin_f32_e32 v65, v72
	v_sin_f32_e32 v64, v73
	v_fma_f32 v52, -v30, v56, v52
	v_fma_f32 v53, -v31, v57, v53
	v_mul_f32_e32 v78, 0.15915494, v67
	v_mul_f32_e32 v79, 0.15915494, v66
	v_cos_f32_e32 v67, v74
	v_cos_f32_e32 v66, v75
	v_fma_f32 v52, v20, v58, v52
	v_fma_f32 v53, v21, v59, v53
	v_mul_f32_e32 v80, 0.15915494, v69
	v_mul_f32_e32 v82, 0.15915494, v68
	v_sin_f32_e32 v69, v74
	v_sin_f32_e32 v68, v75
	v_fma_f32 v52, -v34, v60, v52
	v_fma_f32 v53, -v35, v61, v53
	v_cos_f32_e32 v71, v76
	v_cos_f32_e32 v70, v77
	v_fma_f32 v52, v18, v62, v52
	v_fma_f32 v53, v19, v63, v53
	v_sin_f32_e32 v73, v76
	v_sin_f32_e32 v72, v77
	v_fma_f32 v52, -v32, v64, v52
	v_fma_f32 v53, -v33, v65, v53
	v_cos_f32_e32 v75, v78
	v_cos_f32_e32 v74, v79
	v_fma_f32 v52, v16, v66, v52
	v_fma_f32 v53, v17, v67, v53
	v_sin_f32_e32 v77, v78
	v_sin_f32_e32 v76, v79
	v_fma_f32 v52, -v42, v68, v52
	v_fma_f32 v53, -v43, v69, v53
	v_cos_f32_e32 v79, v80
	v_cos_f32_e32 v78, v82
	v_fma_f32 v52, v14, v70, v52
	v_fma_f32 v53, v15, v71, v53
	v_sin_f32_e32 v81, v80
	v_sin_f32_e32 v80, v82
	v_fma_f32 v52, -v40, v72, v52
	v_fma_f32 v53, -v41, v73, v53
	v_cos_f32_e32 v83, v84
	v_cos_f32_e32 v82, v87
	v_fma_f32 v52, v12, v74, v52
	v_fma_f32 v53, v13, v75, v53
	v_sin_f32_e32 v85, v84
	v_sin_f32_e32 v84, v87
	v_fma_f32 v52, -v38, v76, v52
	v_fma_f32 v53, -v39, v77, v53
	s_add_i32 s17, s17, -2
	v_fma_f32 v52, v10, v78, v52
	v_fma_f32 v53, v11, v79, v53
	s_cmp_lg_u32 s17, 0
	v_fma_f32 v52, -v36, v80, v52
	v_fma_f32 v53, -v37, v81, v53
	v_lshl_or_b32 v51, v51, 8, v6
	v_fma_f32 v52, v28, v82, v52
	v_fma_f32 v53, v29, v83, v53
	s_nop 0
	v_fma_f32 v52, -v44, v84, v52
	v_fma_f32 v53, -v45, v85, v53
	s_nop 0
	v_add_f32 v52, v26, v52
	v_add_f32 v53, v27, v53
	s_nop 0
	v_mul_f32 v52, v8, v52
	v_mul_f32 v53, v9, v53
	s_nop 0
	v_mul_f32_e32 v52, 0.15915494, v52
	v_mul_f32_e32 v53, 0.15915494, v53
	v_sin_f32_e32 v52, v52
	v_sin_f32_e32 v53, v53
	ds_write_b32 v86, v52
	ds_write_b32 v51, v53
	s_cbranch_scc1 .LBB0_36
	s_add_u32 s8, s92, s21
	s_addc_u32 s9, s93, s3
	s_waitcnt lgkmcnt(0)
	s_barrier
	s_load_dwordx4 s[4:7], s[8:9], 0xd8
	v_lshlrev_b32_e32 v72, 2, v4
	v_mov_b32_e32 v73, 0
	s_waitcnt lgkmcnt(0)
	v_mov_b32_e32 v70, s6
	v_mov_b32_e32 v71, s7
	s_lshl_b64 s[6:7], s[10:11], 14
	s_add_u32 s4, s4, s6
	s_addc_u32 s5, s5, s7
	v_lshl_add_u64 v[22:23], s[4:5], 0, v[72:73]
	global_load_dword v44, v72, s[4:5]
	global_load_dword v45, v72, s[4:5] offset:256
	global_load_dword v46, v72, s[4:5] offset:512
	global_load_dword v48, v72, s[4:5] offset:768
	global_load_dword v49, v72, s[4:5] offset:1024
	global_load_dword v50, v72, s[4:5] offset:1280
	global_load_dword v51, v72, s[4:5] offset:1536
	global_load_dword v52, v72, s[4:5] offset:1792
	global_load_dword v53, v72, s[4:5] offset:2048
	global_load_dword v54, v72, s[4:5] offset:2304
	global_load_dword v55, v72, s[4:5] offset:2560
	global_load_dword v56, v72, s[4:5] offset:2816
	global_load_dword v57, v72, s[4:5] offset:3072
	global_load_dword v58, v72, s[4:5] offset:3328
	global_load_dword v59, v72, s[4:5] offset:3584
	global_load_dword v60, v72, s[4:5] offset:3840
	s_movk_i32 s4, 0x1000
	v_add_co_u32_e32 v36, vcc, s4, v22
	s_movk_i32 s4, 0x2000
	s_nop 0
	v_addc_co_u32_e32 v37, vcc, 0, v23, vcc
	v_add_co_u32_e32 v24, vcc, s4, v22
	s_movk_i32 s4, 0x3000
	s_nop 0
	v_addc_co_u32_e32 v25, vcc, 0, v23, vcc
	global_load_dword v61, v[36:37], off offset:256
	global_load_dword v62, v[36:37], off offset:512
	global_load_dword v63, v[36:37], off offset:768
	global_load_dword v64, v[36:37], off offset:1024
	global_load_dword v65, v[36:37], off offset:1280
	global_load_dword v66, v[36:37], off offset:1536
	global_load_dword v67, v[36:37], off offset:1792
	global_load_dword v4, v[36:37], off offset:2048
	global_load_dword v68, v[24:25], off offset:-4096
	global_load_dword v6, v[24:25], off
	global_load_dword v8, v[24:25], off offset:256
	global_load_dword v10, v[24:25], off offset:512
	global_load_dword v12, v[24:25], off offset:768
	global_load_dword v7, v[24:25], off offset:1024
	global_load_dword v9, v[24:25], off offset:1280
	global_load_dword v11, v[24:25], off offset:1536
	global_load_dword v13, v[24:25], off offset:1792
	global_load_dword v14, v[24:25], off offset:2048
	global_load_dword v16, v[24:25], off offset:2304
	global_load_dword v18, v[24:25], off offset:2560
	global_load_dword v20, v[24:25], off offset:2816
	global_load_dword v15, v[24:25], off offset:3072
	global_load_dword v17, v[24:25], off offset:3328
	global_load_dword v19, v[24:25], off offset:3584
	global_load_dword v21, v[24:25], off offset:3840
	v_add_co_u32_e32 v74, vcc, s4, v22
	v_lshl_add_u64 v[70:71], v[0:1], 2, v[70:71]
	s_nop 0
	v_addc_co_u32_e32 v75, vcc, 0, v23, vcc
	global_load_dword v22, v[36:37], off offset:2304
	global_load_dword v24, v[36:37], off offset:2560
	global_load_dword v26, v[36:37], off offset:2816
	global_load_dword v5, v[36:37], off offset:3072
	global_load_dword v23, v[36:37], off offset:3328
	global_load_dword v25, v[36:37], off offset:3584
	global_load_dword v27, v[36:37], off offset:3840
	global_load_dword v28, v[74:75], off
	global_load_dword v30, v[74:75], off offset:256
	global_load_dword v32, v[74:75], off offset:512
	global_load_dword v34, v[74:75], off offset:768
	global_load_dword v29, v[74:75], off offset:1024
	global_load_dword v31, v[74:75], off offset:1280
	global_load_dword v33, v[74:75], off offset:1536
	global_load_dword v35, v[74:75], off offset:1792
	global_load_dword v36, v[74:75], off offset:2048
	global_load_dword v38, v[74:75], off offset:2304
	global_load_dword v40, v[74:75], off offset:2560
	global_load_dword v42, v[74:75], off offset:2816
	global_load_dword v37, v[74:75], off offset:3072
	global_load_dword v39, v[74:75], off offset:3328
	global_load_dword v41, v[74:75], off offset:3584
	global_load_dword v43, v[74:75], off offset:3840
	global_load_dword v0, v[70:71], off
	global_load_dword v1, v[2:3], off offset:256
	v_lshlrev_b32_e32 v2, 8, v47
	v_and_b32_e32 v2, 0xfffffc00, v2
	v_or_b32_e32 v3, v2, v72
	s_mov_b32 s4, 0
	v_add_u32_e32 v3, 0x2000, v3
.LBB0_38:
	v_add_u32_e32 v47, s4, v2
	ds_read_b128 v[70:73], v47
	ds_read_b128 v[74:77], v47 offset:16
	ds_read_b128 v[78:81], v47 offset:32
	ds_read_b128 v[82:85], v47 offset:48
	ds_read_b128 v[86:89], v47 offset:64
	ds_read_b128 v[90:93], v47 offset:80
	ds_read_b128 v[94:97], v47 offset:96
	ds_read_b128 v[98:101], v47 offset:112
	ds_read_b128 v[102:105], v47 offset:128
	ds_read_b128 v[106:109], v47 offset:144
	ds_read_b128 v[110:113], v47 offset:160
	ds_read_b128 v[114:117], v47 offset:176
	ds_read_b128 v[118:121], v47 offset:192
	ds_read_b128 v[122:125], v47 offset:208
	ds_read_b128 v[126:129], v47 offset:224
	ds_read_b128 v[130:133], v47 offset:240
	s_waitcnt vmcnt(62) lgkmcnt(14)
	v_mul_f32_e32 v47, v45, v71
	s_waitcnt vmcnt(60)
	v_mul_f32_e32 v69, v50, v75
	v_fmac_f32_e32 v47, v44, v70
	s_waitcnt vmcnt(56) lgkmcnt(13)
	v_mul_f32_e32 v136, v54, v79
	v_fmac_f32_e32 v69, v49, v74
	v_fmac_f32_e32 v47, v46, v72
	s_waitcnt vmcnt(52) lgkmcnt(12)
	v_mul_f32_e32 v137, v58, v83
	v_fmac_f32_e32 v136, v53, v78
	v_fmac_f32_e32 v69, v51, v76
	v_fmac_f32_e32 v47, v48, v73
	s_waitcnt vmcnt(49) lgkmcnt(11)
	v_mul_f32_e32 v138, v61, v87
	v_fmac_f32_e32 v137, v57, v82
	v_fmac_f32_e32 v136, v55, v80
	v_fmac_f32_e32 v69, v52, v77
	v_add_f32_e32 v47, 0, v47
	s_waitcnt vmcnt(45) lgkmcnt(10)
	v_mul_f32_e32 v91, v65, v91
	s_waitcnt lgkmcnt(8)
	v_mov_b32_e32 v135, v98
	v_mov_b32_e32 v98, v95
	s_waitcnt vmcnt(41)
	v_fmac_f32_e32 v138, v68, v86
	v_fmac_f32_e32 v137, v59, v84
	v_fmac_f32_e32 v136, v56, v81
	v_add_f32_e32 v47, v47, v69
	v_mov_b32_e32 v134, v94
	v_fmac_f32_e32 v91, v64, v90
	s_waitcnt vmcnt(20)
	v_mul_f32 v70, v22, v98
	v_mul_f32 v71, v23, v99
	v_fmac_f32_e32 v138, v62, v88
	v_fmac_f32_e32 v137, v60, v85
	v_add_f32_e32 v47, v47, v136
	v_mov_b32_e32 v94, v96
	v_mov_b32_e32 v95, v100
	v_mov_b32_e32 v100, v97
	s_waitcnt lgkmcnt(6)
	v_mov_b32_e32 v97, v106
	v_mov_b32_e32 v106, v103
	v_fmac_f32_e32 v91, v66, v92
	v_fma_f32 v70, v4, v134, v70
	v_fma_f32 v71, v5, v135, v71
	v_fmac_f32_e32 v138, v63, v89
	v_add_f32_e32 v47, v47, v137
	v_mov_b32_e32 v96, v102
	v_mul_f32 v74, v8, v106
	v_mul_f32 v75, v9, v107
	v_fmac_f32_e32 v91, v67, v93
	s_waitcnt vmcnt(19)
	v_fma_f32 v70, v24, v94, v70
	v_fma_f32 v71, v25, v95, v71
	v_add_f32_e32 v47, v47, v138
	v_mov_b32_e32 v102, v104
	v_mov_b32_e32 v103, v108
	v_mov_b32_e32 v108, v105
	s_waitcnt lgkmcnt(4)
	v_mov_b32_e32 v105, v114
	v_mov_b32_e32 v114, v111
	v_fma_f32 v74, v6, v96, v74
	v_fma_f32 v75, v7, v97, v75
	s_waitcnt vmcnt(18)
	v_fma_f32 v70, v26, v100, v70
	v_fma_f32 v71, v27, v101, v71
	v_add_f32_e32 v47, v47, v91
	v_mov_b32_e32 v104, v110
	v_mul_f32 v78, v16, v114
	v_mul_f32 v79, v17, v115
	v_fma_f32 v72, v10, v102, v74
	v_fma_f32 v73, v11, v103, v75
	v_add_f32_e32 v47, v47, v70
	v_mov_b32_e32 v110, v112
	v_mov_b32_e32 v111, v116
	v_mov_b32_e32 v116, v113
	s_waitcnt lgkmcnt(2)
	v_mov_b32_e32 v113, v122
	v_mov_b32_e32 v122, v119
	v_fma_f32 v78, v14, v104, v78
	v_fma_f32 v79, v15, v105, v79
	v_fma_f32 v72, v12, v108, v72
	v_fma_f32 v73, v13, v109, v73
	v_add_f32_e32 v47, v47, v71
	v_mov_b32_e32 v112, v118
	s_waitcnt vmcnt(12)
	v_mul_f32 v82, v30, v122
	v_mul_f32 v83, v31, v123
	v_fma_f32 v74, v18, v110, v78
	v_fma_f32 v75, v19, v111, v79
	v_add_f32_e32 v47, v47, v72
	v_mov_b32_e32 v118, v120
	v_mov_b32_e32 v119, v124
	v_mov_b32_e32 v124, v121
	s_waitcnt lgkmcnt(0)
	v_mov_b32_e32 v121, v130
	v_mov_b32_e32 v130, v127
	v_fma_f32 v82, v28, v112, v82
	v_fma_f32 v83, v29, v113, v83
	v_fma_f32 v74, v20, v116, v74
	v_fma_f32 v75, v21, v117, v75
	v_add_f32_e32 v47, v47, v73
	v_mov_b32_e32 v120, v126
	s_waitcnt vmcnt(4)
	v_mul_f32 v86, v38, v130
	v_mul_f32 v87, v39, v131
	v_fma_f32 v76, v32, v118, v82
	v_fma_f32 v77, v33, v119, v83
	v_add_f32_e32 v47, v47, v74
	v_mov_b32_e32 v126, v128
	v_mov_b32_e32 v127, v132
	v_fma_f32 v86, v36, v120, v86
	v_fma_f32 v87, v37, v121, v87
	v_fma_f32 v76, v34, v124, v76
	v_fma_f32 v77, v35, v125, v77
	v_add_f32_e32 v47, v47, v75
	v_mov_b32_e32 v132, v129
	s_waitcnt vmcnt(3)
	v_fma_f32 v78, v40, v126, v86
	v_fma_f32 v79, v41, v127, v87
	v_add_f32_e32 v47, v47, v76
	s_waitcnt vmcnt(2)
	v_fma_f32 v78, v42, v132, v78
	v_fma_f32 v79, v43, v133, v79
	v_add_f32_e32 v47, v47, v77
	v_add_f32_e32 v47, v47, v78
	v_add_f32_e32 v47, v47, v79
	s_waitcnt vmcnt(1)
	v_add_f32_e32 v47, v0, v47
	s_waitcnt vmcnt(0)
	v_mul_f32_e32 v47, v1, v47
	v_mul_f32_e32 v47, 0.15915494, v47
	v_sin_f32_e32 v47, v47
	v_add_u32_e32 v69, s4, v3
	s_addk_i32 s4, 0x100
	s_cmpk_eq_i32 s4, 0x400
	ds_write_b32 v69, v47
	s_cbranch_scc0 .LBB0_38
	s_add_u32 s4, s92, s21
	s_addc_u32 s5, s93, s3
	s_waitcnt lgkmcnt(0)
	s_barrier
	s_load_dwordx2 s[6:7], s[4:5], 0xe8
	s_lshl_b64 s[8:9], s[10:11], 17
	v_ashrrev_i32_e32 v149, 31, v148
	s_movk_i32 s3, 0x1000
	s_load_dwordx2 s[4:5], s[4:5], 0xf8
	s_waitcnt lgkmcnt(0)
	s_add_u32 s6, s6, s8
	s_addc_u32 s7, s7, s9
	v_lshl_add_u64 v[22:23], v[148:149], 2, s[6:7]
	v_add_co_u32_e32 v0, vcc, s3, v22
	s_movk_i32 s3, 0x2000
	s_nop 0
	v_addc_co_u32_e32 v1, vcc, 0, v23, vcc
	v_add_co_u32_e32 v2, vcc, s3, v22
	s_movk_i32 s3, 0x3000
	s_nop 0
	v_addc_co_u32_e32 v3, vcc, 0, v23, vcc
	v_add_co_u32_e32 v4, vcc, s3, v22
	s_movk_i32 s3, 0x4000
	s_nop 0
	v_addc_co_u32_e32 v5, vcc, 0, v23, vcc
	v_add_co_u32_e32 v6, vcc, s3, v22
	s_movk_i32 s3, 0x5000
	s_nop 0
	v_addc_co_u32_e32 v7, vcc, 0, v23, vcc
	v_add_co_u32_e32 v8, vcc, s3, v22
	s_movk_i32 s3, 0x6000
	s_nop 0
	v_addc_co_u32_e32 v9, vcc, 0, v23, vcc
	v_add_co_u32_e32 v10, vcc, s3, v22
	s_movk_i32 s3, 0x7000
	s_nop 0
	v_addc_co_u32_e32 v11, vcc, 0, v23, vcc
	global_load_dword v24, v[2:3], off offset:-4096
	global_load_dword v25, v[2:3], off
	global_load_dword v26, v[2:3], off offset:2048
	global_load_dword v27, v[6:7], off offset:-4096
	global_load_dword v28, v[6:7], off
	global_load_dword v29, v[6:7], off offset:2048
	global_load_dword v30, v[10:11], off offset:-4096
	global_load_dword v31, v[10:11], off
	v_add_co_u32_e32 v2, vcc, s3, v22
	s_mov_b32 s3, 0x8000
	s_nop 0
	v_addc_co_u32_e32 v3, vcc, 0, v23, vcc
	v_add_co_u32_e32 v6, vcc, s3, v22
	s_mov_b32 s3, 0x9000
	s_nop 0
	v_addc_co_u32_e32 v7, vcc, 0, v23, vcc
	v_add_co_u32_e32 v12, vcc, s3, v22
	s_mov_b32 s3, 0xa000
	s_nop 0
	v_addc_co_u32_e32 v13, vcc, 0, v23, vcc
	v_add_co_u32_e32 v14, vcc, s3, v22
	s_mov_b32 s3, 0xb000
	s_nop 0
	v_addc_co_u32_e32 v15, vcc, 0, v23, vcc
	v_add_co_u32_e32 v16, vcc, s3, v22
	s_mov_b32 s3, 0xc000
	s_nop 0
	v_addc_co_u32_e32 v17, vcc, 0, v23, vcc
	v_add_co_u32_e32 v18, vcc, s3, v22
	s_mov_b32 s3, 0xd000
	s_nop 0
	v_addc_co_u32_e32 v19, vcc, 0, v23, vcc
	global_load_dword v32, v[10:11], off offset:2048
	global_load_dword v33, v[6:7], off offset:-4096
	global_load_dword v34, v[6:7], off
	global_load_dword v35, v[6:7], off offset:2048
	global_load_dword v36, v[14:15], off offset:-4096
	global_load_dword v37, v[14:15], off
	global_load_dword v38, v[14:15], off offset:2048
	global_load_dword v39, v[18:19], off offset:-4096
	global_load_dword v40, v[22:23], off
	global_load_dword v41, v[22:23], off offset:2048
	global_load_dword v42, v[0:1], off offset:2048
	global_load_dword v43, v[4:5], off offset:2048
	global_load_dword v44, v[8:9], off offset:2048
	global_load_dword v45, v[2:3], off offset:2048
	global_load_dword v46, v[12:13], off offset:2048
	global_load_dword v47, v[16:17], off offset:2048
	v_add_co_u32_e32 v16, vcc, s3, v22
	s_mov_b32 s3, 0xe000
	s_nop 0
	v_addc_co_u32_e32 v17, vcc, 0, v23, vcc
	v_add_co_u32_e32 v0, vcc, s3, v22
	s_mov_b32 s3, 0xf000
	s_nop 0
	v_addc_co_u32_e32 v1, vcc, 0, v23, vcc
	v_add_co_u32_e32 v20, vcc, s3, v22
	s_mov_b32 s3, 0x10000
	s_nop 0
	v_addc_co_u32_e32 v21, vcc, 0, v23, vcc
	v_add_co_u32_e32 v2, vcc, s3, v22
	s_mov_b32 s3, 0x11000
	s_nop 0
	v_addc_co_u32_e32 v3, vcc, 0, v23, vcc
	global_load_dword v48, v[18:19], off
	global_load_dword v49, v[18:19], off offset:2048
	global_load_dword v50, v[0:1], off offset:-4096
	global_load_dword v51, v[0:1], off
	global_load_dword v52, v[0:1], off offset:2048
	global_load_dword v53, v[2:3], off offset:-4096
	global_load_dword v54, v[2:3], off
	global_load_dword v55, v[2:3], off offset:2048
	v_add_co_u32_e32 v18, vcc, s3, v22
	s_mov_b32 s3, 0x12000
	s_nop 0
	v_addc_co_u32_e32 v19, vcc, 0, v23, vcc
	v_add_co_u32_e32 v6, vcc, s3, v22
	s_mov_b32 s3, 0x13000
	s_nop 0
	v_addc_co_u32_e32 v7, vcc, 0, v23, vcc
	v_add_co_u32_e32 v64, vcc, s3, v22
	s_mov_b32 s3, 0x14000
	s_nop 0
	v_addc_co_u32_e32 v65, vcc, 0, v23, vcc
	v_add_co_u32_e32 v8, vcc, s3, v22
	s_mov_b32 s3, 0x15000
	s_nop 0
	v_addc_co_u32_e32 v9, vcc, 0, v23, vcc
	v_add_co_u32_e32 v66, vcc, s3, v22
	s_mov_b32 s3, 0x16000
	s_nop 0
	v_addc_co_u32_e32 v67, vcc, 0, v23, vcc
	v_add_co_u32_e32 v68, vcc, s3, v22
	s_mov_b32 s3, 0x17000
	s_nop 0
	v_addc_co_u32_e32 v69, vcc, 0, v23, vcc
	v_add_co_u32_e32 v70, vcc, s3, v22
	s_mov_b32 s3, 0x18000
	s_nop 0
	v_addc_co_u32_e32 v71, vcc, 0, v23, vcc
	v_add_co_u32_e32 v72, vcc, s3, v22
	s_mov_b32 s3, 0x19000
	s_nop 0
	v_addc_co_u32_e32 v73, vcc, 0, v23, vcc
	v_add_co_u32_e32 v74, vcc, s3, v22
	s_mov_b32 s3, 0x1a000
	s_nop 0
	v_addc_co_u32_e32 v75, vcc, 0, v23, vcc
	v_add_co_u32_e32 v76, vcc, s3, v22
	s_mov_b32 s3, 0x1b000
	s_nop 0
	v_addc_co_u32_e32 v77, vcc, 0, v23, vcc
	v_add_co_u32_e32 v78, vcc, s3, v22
	s_mov_b32 s3, 0x1c000
	s_nop 0
	v_addc_co_u32_e32 v79, vcc, 0, v23, vcc
	v_add_co_u32_e32 v80, vcc, s3, v22
	global_load_dword v56, v[6:7], off offset:-4096
	global_load_dword v57, v[6:7], off
	global_load_dword v58, v[6:7], off offset:2048
	global_load_dword v59, v[8:9], off offset:-4096
	global_load_dword v0, v[8:9], off
	global_load_dword v2, v[8:9], off offset:2048
	global_load_dword v4, v[68:69], off offset:-4096
	global_load_dword v1, v[68:69], off
	v_addc_co_u32_e32 v81, vcc, 0, v23, vcc
	global_load_dword v3, v[68:69], off offset:2048
	global_load_dword v5, v[72:73], off offset:-4096
	global_load_dword v6, v[72:73], off
	global_load_dword v8, v[72:73], off offset:2048
	global_load_dword v10, v[76:77], off offset:-4096
	global_load_dword v7, v[76:77], off
	global_load_dword v9, v[76:77], off offset:2048
	global_load_dword v11, v[80:81], off offset:-4096
	global_load_dword v60, v[16:17], off offset:2048
	global_load_dword v61, v[20:21], off offset:2048
	global_load_dword v62, v[18:19], off offset:2048
	global_load_dword v63, v[64:65], off offset:2048
	global_load_dword v12, v[66:67], off offset:2048
	global_load_dword v13, v[70:71], off offset:2048
	global_load_dword v14, v[74:75], off offset:2048
	global_load_dword v15, v[78:79], off offset:2048
	s_mov_b32 s3, 0x1d000
	v_add_co_u32_e32 v64, vcc, s3, v22
	s_mov_b32 s3, 0x1e000
	s_nop 0
	v_addc_co_u32_e32 v65, vcc, 0, v23, vcc
	v_add_co_u32_e32 v66, vcc, s3, v22
	s_mov_b32 s3, 0x1f000
	s_nop 0
	v_addc_co_u32_e32 v67, vcc, 0, v23, vcc
	global_load_dword v16, v[80:81], off
	global_load_dword v18, v[80:81], off offset:2048
	global_load_dword v20, v[66:67], off offset:-4096
	global_load_dword v17, v[66:67], off
	global_load_dword v19, v[66:67], off offset:2048
	v_add_co_u32_e32 v66, vcc, s3, v22
	s_lshr_b32 s2, s2, 1
	s_nop 0
	v_addc_co_u32_e32 v67, vcc, 0, v23, vcc
	global_load_dword v22, v[64:65], off offset:2048
	global_load_dword v21, v[66:67], off
	global_load_dword v23, v[66:67], off offset:2048
	v_lshl_add_u32 v64, s10, 9, v148
	v_ashrrev_i32_e32 v65, 31, v64
	v_lshl_add_u64 v[64:65], v[64:65], 2, s[4:5]
	global_load_dword v64, v[64:65], off
	v_cvt_f32_u32_e32 v65, s2
	v_mov_b32_e32 v66, 0x4000
	s_mov_b32 s3, 0
	v_lshl_add_u32 v66, v148, 1, v66
	s_sub_i32 s2, s16, s2
	s_movk_i32 s4, 0x7fff
.LBB0_40:
	v_cvt_f32_i32_e32 v134, s2
	v_mov_b32_e32 v67, s3
	ds_read_b128 v[68:71], v67 offset:8192
	ds_read_b128 v[72:75], v67 offset:8208
	ds_read_b128 v[76:79], v67 offset:8224
	ds_read_b128 v[80:83], v67 offset:8240
	ds_read_b128 v[84:87], v67 offset:8256
	ds_read_b128 v[88:91], v67 offset:8272
	ds_read_b128 v[92:95], v67 offset:8288
	ds_read_b128 v[96:99], v67 offset:8304
	ds_read_b128 v[100:103], v67 offset:8320
	ds_read_b128 v[104:107], v67 offset:8336
	ds_read_b128 v[108:111], v67 offset:8352
	ds_read_b128 v[112:115], v67 offset:8368
	ds_read_b128 v[116:119], v67 offset:8384
	ds_read_b128 v[120:123], v67 offset:8400
	ds_read_b128 v[124:127], v67 offset:8416
	ds_read_b128 v[128:131], v67 offset:8432
	s_waitcnt vmcnt(47) lgkmcnt(14)
	v_mul_f32_e32 v136, v41, v69
	v_and_b32_e32 v67, 0x7fffffff, v134
	v_div_scale_f32 v135, s[6:7], v65, v65, v67
	v_mul_f32_e32 v137, v26, v73
	v_fmac_f32_e32 v136, v40, v68
	s_waitcnt lgkmcnt(13)
	v_mul_f32_e32 v138, v29, v77
	s_waitcnt lgkmcnt(5)
	v_mov_b32_e32 v132, v108
	v_mov_b32_e32 v108, v110
	s_waitcnt lgkmcnt(3)
	v_mov_b32_e32 v110, v116
	v_mov_b32_e32 v116, v118
	s_waitcnt lgkmcnt(1)
	v_mov_b32_e32 v118, v124
	v_mov_b32_e32 v124, v126
	v_rcp_f32_e32 v126, v135
	v_fmac_f32_e32 v137, v25, v72
	v_fmac_f32_e32 v136, v24, v70
	v_mul_f32_e32 v81, v32, v81
	v_fmac_f32_e32 v138, v28, v76
	v_fmac_f32_e32 v137, v27, v74
	s_waitcnt vmcnt(46)
	v_fmac_f32_e32 v136, v42, v71
	v_mul_f32_e32 v85, v35, v85
	v_fmac_f32_e32 v81, v31, v80
	v_fmac_f32_e32 v138, v30, v78
	s_waitcnt vmcnt(45)
	v_fmac_f32_e32 v137, v43, v75
	v_add_f32_e32 v74, 0, v136
	v_mul_f32_e32 v89, v38, v89
	v_fmac_f32_e32 v85, v34, v84
	v_fmac_f32_e32 v81, v33, v82
	s_waitcnt vmcnt(44)
	v_fmac_f32_e32 v138, v44, v79
	v_add_f32_e32 v74, v74, v137
	s_waitcnt vmcnt(39)
	v_mul_f32_e32 v93, v49, v93
	v_mov_b32_e32 v133, v112
	v_mov_b32_e32 v112, v109
	v_mov_b32_e32 v109, v114
	v_mov_b32_e32 v114, v111
	v_mov_b32_e32 v111, v120
	v_mov_b32_e32 v120, v117
	v_mov_b32_e32 v117, v122
	v_mov_b32_e32 v122, v119
	s_waitcnt lgkmcnt(0)
	v_mov_b32_e32 v119, v128
	v_mov_b32_e32 v128, v125
	v_fmac_f32_e32 v89, v37, v88
	v_fmac_f32_e32 v85, v36, v86
	v_fmac_f32_e32 v81, v45, v83
	v_fma_f32 v75, -v135, v126, 1.0
	v_add_f32_e32 v74, v74, v138
	v_div_scale_f32 v67, vcc, v67, v65, v67
	s_waitcnt vmcnt(36)
	v_mul_f32_e32 v97, v52, v97
	v_fmac_f32_e32 v93, v48, v92
	s_waitcnt vmcnt(18)
	v_mul_f32 v72, v8, v120
	v_mul_f32 v73, v9, v121
	s_waitcnt vmcnt(4)
	v_mul_f32 v76, v18, v128
	v_mul_f32 v77, v19, v129
	v_fmac_f32_e32 v89, v39, v90
	v_fmac_f32_e32 v85, v46, v87
	v_fmac_f32_e32 v126, v75, v126
	v_add_f32_e32 v74, v74, v81
	v_mul_f32_e32 v101, v55, v101
	v_mov_b32_e32 v125, v130
	v_fmac_f32_e32 v97, v51, v96
	v_fmac_f32_e32 v93, v50, v94
	v_fma_f32 v72, v6, v110, v72
	v_fma_f32 v73, v7, v111, v73
	v_fma_f32 v76, v16, v118, v76
	v_fma_f32 v77, v17, v119, v77
	v_fmac_f32_e32 v89, v47, v91
	v_mul_f32_e32 v75, v67, v126
	v_add_f32_e32 v74, v74, v85
	v_mul_f32_e32 v105, v58, v105
	v_fmac_f32_e32 v101, v54, v100
	v_fmac_f32_e32 v97, v53, v98
	v_fmac_f32_e32 v93, v60, v95
	v_fma_f32 v70, v10, v116, v72
	v_fma_f32 v71, v11, v117, v73
	s_waitcnt vmcnt(2)
	v_fma_f32 v72, v20, v124, v76
	v_fma_f32 v73, v21, v125, v77
	v_fma_f32 v76, -v135, v75, v67
	v_add_f32_e32 v74, v74, v89
	v_fmac_f32_e32 v105, v57, v104
	v_mul_f32 v68, v2, v112
	v_mul_f32 v69, v3, v113
	v_fmac_f32_e32 v101, v56, v102
	v_fmac_f32_e32 v97, v61, v99
	v_fmac_f32_e32 v75, v76, v126
	v_add_f32_e32 v74, v74, v93
	v_fmac_f32_e32 v105, v59, v106
	v_fma_f32 v68, v0, v132, v68
	v_fma_f32 v69, v1, v133, v69
	v_fmac_f32_e32 v101, v62, v103
	v_fma_f32 v67, -v135, v75, v67
	v_add_f32_e32 v74, v74, v97
	v_fmac_f32_e32 v105, v63, v107
	v_fma_f32 v68, v4, v108, v68
	v_fma_f32 v69, v5, v109, v69
	v_div_fmas_f32 v67, v67, v126, v75
	v_add_f32_e32 v74, v74, v101
	v_fma_f32 v68, v12, v114, v68
	v_fma_f32 v69, v13, v115, v69
	v_div_fixup_f32 v67, v67, v65, |v134|
	v_add_f32_e32 v74, v74, v105
	s_waitcnt vmcnt(0)
	v_mul_f32_e64 v67, |v64|, v67
	v_add_f32_e32 v68, v74, v68
	v_fma_f32 v70, v14, v122, v70
	v_fma_f32 v71, v15, v123, v71
	v_mul_f32_e32 v67, 0xbfb8aa3b, v67
	v_add_f32_e32 v68, v68, v69
	v_mov_b32_e32 v130, v127
	v_exp_f32_e32 v67, v67
	v_add_f32_e32 v68, v68, v70
	v_fma_f32 v72, v22, v130, v72
	v_fma_f32 v73, v23, v131, v73
	v_add_f32_e32 v68, v68, v71
	v_add_f32_e32 v68, v68, v72
	v_add_f32_e32 v68, v68, v73
	v_mul_f32_e32 v67, v67, v68
	v_bfe_u32 v68, v67, 16, 1
	s_addk_i32 s3, 0x100
	s_add_i32 s2, s2, 1
	v_add3_u32 v67, v67, v68, s4
	s_cmpk_lg_i32 s3, 0x2000
	ds_write_b16_d16_hi v66, v67
	v_add_u32_e32 v66, 0x400, v66
	s_cbranch_scc1 .LBB0_40
	s_ashr_i32 s17, s16, 31
	s_and_b64 s[2:3], s[18:19], exec
	s_cselect_b32 s2, 11, 8
	s_mul_i32 s4, s10, 0x240000
	v_lshlrev_b64 v[0:1], s2, v[148:149]
	s_cselect_b32 s2, 0x40000, 0
	s_mul_hi_i32 s3, s10, 0x240000
	s_add_u32 s4, s14, s4
	s_addc_u32 s3, s15, s3
	s_add_u32 s2, s4, s2
	s_addc_u32 s3, s3, 0
	v_lshlrev_b32_e32 v8, 1, v148
	v_lshl_add_u64 v[0:1], v[0:1], 1, s[2:3]
	v_lshl_add_u64 v[4:5], s[16:17], 1, v[0:1]
	ds_read_u16 v0, v8 offset:16384
	ds_read_u16 v1, v8 offset:17408
	ds_read_u16 v2, v8 offset:18432
	ds_read_u16 v3, v8 offset:19456
	ds_read_u16 v6, v8 offset:20480
	ds_read_u16 v7, v8 offset:21504
	ds_read_u16 v9, v8 offset:22528
	ds_read_u16 v10, v8 offset:23552
	s_mov_b32 s4, 0x3b7c000
	s_waitcnt lgkmcnt(6)
	v_lshl_or_b32 v0, v1, 16, v0
	s_waitcnt lgkmcnt(4)
	v_lshl_or_b32 v1, v3, 16, v2
	s_waitcnt lgkmcnt(2)
	v_lshl_or_b32 v2, v7, 16, v6
	v_add_co_u32_e32 v6, vcc, s4, v4
	s_waitcnt lgkmcnt(0)
	v_lshl_or_b32 v3, v10, 16, v9
	v_addc_co_u32_e32 v7, vcc, 0, v5, vcc
	flat_store_dwordx4 v[6:7], v[0:3]
	ds_read_u16 v0, v8 offset:24576
	ds_read_u16 v1, v8 offset:25600
	ds_read_u16 v2, v8 offset:26624
	ds_read_u16 v3, v8 offset:27648
	ds_read_u16 v6, v8 offset:28672
	ds_read_u16 v7, v8 offset:29696
	ds_read_u16 v9, v8 offset:30720
	ds_read_u16 v10, v8 offset:31744
	s_mov_b64 s[2:3], 0x3b7c000
	v_lshl_add_u64 v[4:5], v[4:5], 0, s[2:3]
	s_waitcnt lgkmcnt(0)
	v_lshl_or_b32 v0, v1, 16, v0
	v_lshl_or_b32 v1, v3, 16, v2
	v_lshl_or_b32 v2, v7, 16, v6
	v_lshl_or_b32 v3, v10, 16, v9
	flat_store_dwordx4 v[4:5], v[0:3] offset:16
	ds_read_u16 v0, v8 offset:32768
	ds_read_u16 v1, v8 offset:33792
	ds_read_u16 v2, v8 offset:34816
	ds_read_u16 v3, v8 offset:35840
	ds_read_u16 v6, v8 offset:36864
	ds_read_u16 v7, v8 offset:37888
	ds_read_u16 v9, v8 offset:38912
	ds_read_u16 v10, v8 offset:39936
	s_waitcnt lgkmcnt(0)
	v_lshl_or_b32 v0, v1, 16, v0
	v_lshl_or_b32 v1, v3, 16, v2
	v_lshl_or_b32 v2, v7, 16, v6
	s_mov_b32 s6, s66
	v_lshl_or_b32 v3, v10, 16, v9
	flat_store_dwordx4 v[4:5], v[0:3] offset:32
	ds_read_u16 v0, v8 offset:40960
	ds_read_u16 v1, v8 offset:41984
	ds_read_u16 v2, v8 offset:43008
	ds_read_u16 v3, v8 offset:44032
	ds_read_u16 v6, v8 offset:45056
	ds_read_u16 v7, v8 offset:46080
	ds_read_u16 v9, v8 offset:47104
	ds_read_u16 v8, v8 offset:48128
	s_waitcnt lgkmcnt(0)
	v_lshl_or_b32 v0, v1, 16, v0
	v_lshl_or_b32 v1, v3, 16, v2
	v_lshl_or_b32 v2, v7, 16, v6
	v_lshl_or_b32 v3, v8, 16, v9
	flat_store_dwordx4 v[4:5], v[0:3] offset:48
	s_waitcnt lgkmcnt(0)
	s_barrier

.LBB0_54:
	v_add_u32_e32 v47, s19, v1
	v_cvt_f32_i32_e32 v47, v47
	v_add_u32_e32 v46, s18, v42
	v_cvt_f32_i32_e32 v46, v46
	v_add_u32_e32 v45, s19, v141
	v_div_scale_f32 v48, s[88:89], v44, v44, v47
	v_rcp_f32_e32 v49, v48
	v_add_u32_e32 v52, s18, v142
	s_add_i32 s18, s18, 2
	s_add_i32 s19, s19, 2
	v_fma_f32 v50, -v48, v49, 1.0
	v_fmac_f32_e32 v49, v50, v49
	v_div_scale_f32 v50, vcc, v47, v44, v47
	v_mul_f32_e32 v51, v50, v49
	v_fma_f32 v53, -v48, v51, v50
	v_fmac_f32_e32 v51, v53, v49
	v_fma_f32 v48, -v48, v51, v50
	v_div_fmas_f32 v48, v48, v49, v51
	v_div_fixup_f32 v49, v48, v44, v47
	v_div_scale_f32 v48, s[88:89], v44, v44, v46
	v_rcp_f32_e32 v50, v48
	s_mov_b32 s88, 0x40c90fdb
	s_add_i32 s16, s16, -2
	s_cmp_lg_u32 s16, 0
	v_fma_f32 v51, -v48, v50, 1.0
	v_fmac_f32_e32 v50, v51, v50
	v_div_scale_f32 v51, vcc, v46, v44, v46
	v_mul_f32_e32 v53, v51, v50
	v_fma_f32 v54, -v48, v53, v51
	v_fmac_f32_e32 v53, v54, v50
	v_fma_f32 v48, -v48, v53, v51
	v_div_fmas_f32 v48, v48, v50, v53
	v_div_fixup_f32 v48, v48, v44, v46
	v_mul_f32 v46, v46, s88
	v_mul_f32 v47, v47, s88
	v_lshl_or_b32 v45, v45, 8, v151
	v_div_scale_f32 v50, s[88:89], v43, v43, v47
	v_rcp_f32_e32 v51, v50
	s_nop 0
	v_fma_f32 v53, -v50, v51, 1.0
	v_fmac_f32_e32 v51, v53, v51
	v_div_scale_f32 v53, vcc, v47, v43, v47
	v_mul_f32_e32 v54, v53, v51
	v_fma_f32 v55, -v50, v54, v53
	v_fmac_f32_e32 v54, v55, v51
	v_fma_f32 v50, -v50, v54, v53
	v_div_fmas_f32 v50, v50, v51, v54
	v_div_fixup_f32 v47, v50, v43, v47
	v_div_scale_f32 v50, s[88:89], v43, v43, v46
	v_rcp_f32_e32 v51, v50
	s_mov_b32 s88, 0x38d1b717
	v_fma_f32 v53, -v50, v51, 1.0
	v_fmac_f32_e32 v51, v53, v51
	v_div_scale_f32 v53, vcc, v46, v43, v46
	v_mul_f32_e32 v54, v53, v51
	v_fma_f32 v55, -v50, v54, v53
	v_fmac_f32_e32 v54, v55, v51
	v_fma_f32 v50, -v50, v54, v53
	v_div_fmas_f32 v50, v50, v51, v54
	v_div_fixup_f32 v46, v50, v43, v46
	v_mul_f32 v50, v46, s88
	v_mul_f32 v51, v47, s88
	s_mov_b32 s88, 0x3f8002cf
	v_mul_f32_e32 v53, 0.15915494, v51
	v_mul_f32_e32 v54, 0.15915494, v50
	v_cos_f32_e32 v51, v53
	v_cos_f32_e32 v50, v54
	s_nop 0
	v_mul_f32 v50, v10, v50
	v_mul_f32 v51, v11, v51
	s_nop 0
	v_fma_f32 v48, v12, v48, v50
	v_fma_f32 v49, v13, v49, v51
	v_sin_f32_e32 v51, v53
	v_sin_f32_e32 v50, v54
	s_nop 0
	v_fma_f32 v48, -v24, v50, v48
	v_fma_f32 v49, -v25, v51, v49
	v_mul_f32 v50, v46, s88
	v_mul_f32 v51, v47, s88
	s_mov_b32 s88, 0x4000012b
	v_mul_f32_e32 v53, 0.15915494, v51
	v_mul_f32_e32 v54, 0.15915494, v50
	v_cos_f32_e32 v51, v53
	v_cos_f32_e32 v50, v54
	s_nop 0
	v_fma_f32 v48, v8, v50, v48
	v_fma_f32 v49, v9, v51, v49
	v_sin_f32_e32 v51, v53
	v_sin_f32_e32 v50, v54
	s_nop 0
	v_fma_f32 v48, -v28, v50, v48
	v_fma_f32 v49, -v29, v51, v49
	v_mul_f32 v50, v46, s88
	v_mul_f32 v51, v47, s88
	s_mov_b32 s88, 0x404000ef
	v_mul_f32_e32 v53, 0.15915494, v51
	v_mul_f32_e32 v54, 0.15915494, v50
	v_cos_f32_e32 v51, v53
	v_cos_f32_e32 v50, v54
	s_nop 0
	v_fma_f32 v48, v30, v50, v48
	v_fma_f32 v49, v31, v51, v49
	v_sin_f32_e32 v51, v53
	v_sin_f32_e32 v50, v54
	s_nop 0
	v_fma_f32 v48, -v26, v50, v48
	v_fma_f32 v49, -v27, v51, v49
	v_mul_f32 v50, v46, s88
	v_mul_f32 v51, v47, s88
	s_mov_b32 s88, 0x4080005a
	v_mul_f32_e32 v53, 0.15915494, v51
	v_mul_f32_e32 v54, 0.15915494, v50
	v_cos_f32_e32 v51, v53
	v_cos_f32_e32 v50, v54
	s_nop 0
	v_fma_f32 v48, v32, v50, v48
	v_fma_f32 v49, v33, v51, v49
	v_sin_f32_e32 v51, v53
	v_sin_f32_e32 v50, v54
	s_nop 0
	v_fma_f32 v48, -v22, v50, v48
	v_fma_f32 v49, -v23, v51, v49
	v_mul_f32 v50, v46, s88
	v_mul_f32 v51, v47, s88
	s_mov_b32 s88, 0x40a0003c
	v_mul_f32_e32 v53, 0.15915494, v51
	v_mul_f32_e32 v54, 0.15915494, v50
	v_cos_f32_e32 v51, v53
	v_cos_f32_e32 v50, v54
	s_nop 0
	v_fma_f32 v48, v38, v50, v48
	v_fma_f32 v49, v39, v51, v49
	v_sin_f32_e32 v51, v53
	v_sin_f32_e32 v50, v54
	s_nop 0
	v_fma_f32 v48, -v20, v50, v48
	v_fma_f32 v49, -v21, v51, v49
	v_mul_f32 v50, v46, s88
	v_mul_f32 v51, v47, s88
	s_mov_b32 s88, 0x40c0001e
	v_mul_f32_e32 v53, 0.15915494, v51
	v_mul_f32_e32 v54, 0.15915494, v50
	v_cos_f32_e32 v51, v53
	v_cos_f32_e32 v50, v54
	s_nop 0
	v_fma_f32 v48, v36, v50, v48
	v_fma_f32 v49, v37, v51, v49
	v_sin_f32_e32 v51, v53
	v_sin_f32_e32 v50, v54
	s_nop 0
	v_fma_f32 v48, -v18, v50, v48
	v_fma_f32 v49, -v19, v51, v49
	v_mul_f32 v50, v46, s88
	v_mul_f32 v51, v47, s88
	s_mov_b32 s88, 0x40e00000
	v_mul_f32_e32 v53, 0.15915494, v51
	v_mul_f32_e32 v54, 0.15915494, v50
	v_cos_f32_e32 v51, v53
	v_cos_f32_e32 v50, v54
	v_mul_f32 v46, v46, s88
	v_mul_f32 v47, v47, s88
	v_fma_f32 v48, v34, v50, v48
	v_fma_f32 v49, v35, v51, v49
	v_sin_f32_e32 v51, v53
	v_sin_f32_e32 v50, v54
	s_nop 0
	v_fma_f32 v48, -v16, v50, v48
	v_fma_f32 v49, -v17, v51, v49
	v_mul_f32_e32 v50, 0.15915494, v47
	v_mul_f32_e32 v51, 0.15915494, v46
	v_cos_f32_e32 v47, v50
	v_cos_f32_e32 v46, v51
	s_nop 0
	v_fma_f32 v46, v14, v46, v48
	v_fma_f32 v47, v15, v47, v49
	v_sin_f32_e32 v49, v50
	v_sin_f32_e32 v48, v51
	s_nop 0
	v_fma_f32 v46, -v40, v48, v46
	v_fma_f32 v47, -v41, v49, v47
	s_nop 0
	v_add_f32 v46, v6, v46
	v_add_f32 v47, v7, v47
	v_lshl_or_b32 v48, v52, 8, v151
	v_mul_f32 v46, v4, v46
	v_mul_f32 v47, v5, v47
	s_nop 0
	v_mul_f32_e32 v46, 0.15915494, v46
	v_mul_f32_e32 v47, 0.15915494, v47
	v_sin_f32_e32 v46, v46
	v_sin_f32_e32 v47, v47
	ds_write_b32 v48, v46
	ds_write_b32 v45, v47
	s_cbranch_scc1 .LBB0_54
	s_waitcnt lgkmcnt(0)
	s_barrier
	s_load_dwordx4 s[16:19], s[20:21], 0xd8
	s_and_b64 s[88:89], s[56:57], exec
	s_cselect_b32 s53, 0x4000, 0
	v_mov_b32_e32 v157, v145
	v_lshlrev_b32_e32 v0, 2, v0
	s_waitcnt lgkmcnt(0)
	s_add_u32 s16, s16, s53
	s_addc_u32 s17, s17, 0
	v_lshl_add_u64 v[4:5], s[16:17], 0, v[156:157]
	v_add_co_u32_e32 v6, vcc, s61, v4
	global_load_dword v72, v156, s[16:17]
	global_load_dword v73, v156, s[16:17] offset:256
	global_load_dword v74, v156, s[16:17] offset:512
	global_load_dword v75, v156, s[16:17] offset:768
	global_load_dword v76, v156, s[16:17] offset:1024
	global_load_dword v77, v156, s[16:17] offset:1280
	global_load_dword v78, v156, s[16:17] offset:1536
	global_load_dword v79, v156, s[16:17] offset:1792
	global_load_dword v80, v156, s[16:17] offset:2048
	global_load_dword v81, v156, s[16:17] offset:2304
	global_load_dword v82, v156, s[16:17] offset:2560
	global_load_dword v83, v156, s[16:17] offset:2816
	global_load_dword v84, v156, s[16:17] offset:3072
	global_load_dword v85, v156, s[16:17] offset:3328
	global_load_dword v86, v156, s[16:17] offset:3584
	global_load_dword v87, v156, s[16:17] offset:3840
	v_addc_co_u32_e32 v7, vcc, 0, v5, vcc
	v_add_co_u32_e32 v8, vcc, s60, v4
	s_mov_b32 s16, 0
	s_nop 0
	v_addc_co_u32_e32 v9, vcc, 0, v5, vcc
	global_load_dword v88, v[6:7], off offset:256
	global_load_dword v89, v[6:7], off offset:512
	global_load_dword v90, v[6:7], off offset:768
	global_load_dword v91, v[6:7], off offset:1024
	global_load_dword v92, v[6:7], off offset:1280
	global_load_dword v93, v[6:7], off offset:1536
	global_load_dword v94, v[6:7], off offset:1792
	global_load_dword v32, v[6:7], off offset:2048
	global_load_dword v95, v[8:9], off offset:-4096
	global_load_dword v34, v[8:9], off
	global_load_dword v36, v[8:9], off offset:256
	global_load_dword v38, v[8:9], off offset:512
	global_load_dword v40, v[8:9], off offset:768
	global_load_dword v35, v[8:9], off offset:1024
	global_load_dword v37, v[8:9], off offset:1280
	global_load_dword v39, v[8:9], off offset:1536
	global_load_dword v41, v[8:9], off offset:1792
	global_load_dword v42, v[8:9], off offset:2048
	global_load_dword v44, v[8:9], off offset:2304
	global_load_dword v46, v[8:9], off offset:2560
	global_load_dword v48, v[8:9], off offset:2816
	global_load_dword v43, v[8:9], off offset:3072
	global_load_dword v45, v[8:9], off offset:3328
	global_load_dword v47, v[8:9], off offset:3584
	global_load_dword v49, v[8:9], off offset:3840
	v_add_co_u32_e32 v4, vcc, s62, v4
	s_nop 1
	v_addc_co_u32_e32 v5, vcc, 0, v5, vcc
	global_load_dword v50, v[6:7], off offset:2304
	global_load_dword v52, v[6:7], off offset:2560
	global_load_dword v54, v[6:7], off offset:2816
	global_load_dword v33, v[6:7], off offset:3072
	global_load_dword v51, v[6:7], off offset:3328
	global_load_dword v53, v[6:7], off offset:3584
	global_load_dword v55, v[6:7], off offset:3840
	global_load_dword v56, v[4:5], off
	global_load_dword v58, v[4:5], off offset:256
	global_load_dword v60, v[4:5], off offset:512
	global_load_dword v62, v[4:5], off offset:768
	global_load_dword v57, v[4:5], off offset:1024
	global_load_dword v59, v[4:5], off offset:1280
	global_load_dword v61, v[4:5], off offset:1536
	global_load_dword v63, v[4:5], off offset:1792
	global_load_dword v64, v[4:5], off offset:2048
	global_load_dword v66, v[4:5], off offset:2304
	global_load_dword v68, v[4:5], off offset:2560
	global_load_dword v70, v[4:5], off offset:2816
	global_load_dword v65, v[4:5], off offset:3072
	global_load_dword v67, v[4:5], off offset:3328
	global_load_dword v69, v[4:5], off offset:3584
	global_load_dword v71, v[4:5], off offset:3840
	global_load_dword v96, v0, s[18:19]
	global_load_dword v97, v[2:3], off offset:256
.LBB0_56:
	v_add_u32_e32 v126, s16, v169
	ds_read_b128 v[0:3], v126
	ds_read_b128 v[4:7], v126 offset:16
	ds_read_b128 v[8:11], v126 offset:32
	ds_read_b128 v[12:15], v126 offset:48
	ds_read_b128 v[16:19], v126 offset:64
	ds_read_b128 v[20:23], v126 offset:80
	ds_read_b128 v[98:101], v126 offset:96
	ds_read_b128 v[24:27], v126 offset:112
	ds_read_b128 v[102:105], v126 offset:128
	ds_read_b128 v[28:31], v126 offset:144
	ds_read_b128 v[106:109], v126 offset:160
	ds_read_b128 v[110:113], v126 offset:176
	ds_read_b128 v[114:117], v126 offset:192
	ds_read_b128 v[118:121], v126 offset:208
	ds_read_b128 v[122:125], v126 offset:224
	ds_read_b128 v[126:129], v126 offset:240
	s_waitcnt vmcnt(62) lgkmcnt(14)
	v_mul_f32_e32 v132, v73, v1
	s_waitcnt vmcnt(60)
	v_mul_f32_e32 v133, v77, v5
	v_fmac_f32_e32 v132, v72, v0
	s_waitcnt vmcnt(56) lgkmcnt(13)
	v_mul_f32_e32 v134, v81, v9
	v_fmac_f32_e32 v133, v76, v4
	v_fmac_f32_e32 v132, v74, v2
	s_waitcnt vmcnt(52) lgkmcnt(12)
	v_mul_f32_e32 v135, v85, v13
	v_fmac_f32_e32 v134, v80, v8
	v_fmac_f32_e32 v133, v78, v6
	v_fmac_f32_e32 v132, v75, v3
	s_waitcnt vmcnt(49) lgkmcnt(11)
	v_mul_f32_e32 v136, v88, v17
	v_fmac_f32_e32 v135, v84, v12
	v_fmac_f32_e32 v134, v82, v10
	v_fmac_f32_e32 v133, v79, v7
	v_add_f32_e32 v10, 0, v132
	s_waitcnt vmcnt(45) lgkmcnt(10)
	v_mul_f32_e32 v21, v92, v21
	s_waitcnt lgkmcnt(8)
	v_mov_b32_e32 v131, v24
	v_mov_b32_e32 v24, v99
	s_waitcnt vmcnt(41)
	v_fmac_f32_e32 v136, v95, v16
	v_fmac_f32_e32 v135, v86, v14
	v_fmac_f32_e32 v134, v83, v11
	v_add_f32_e32 v10, v10, v133
	v_mov_b32_e32 v130, v98
	v_fmac_f32_e32 v21, v91, v20
	s_waitcnt vmcnt(20)
	v_mul_f32 v0, v50, v24
	v_mul_f32 v1, v51, v25
	v_fmac_f32_e32 v136, v89, v18
	v_fmac_f32_e32 v135, v87, v15
	v_add_f32_e32 v10, v10, v134
	v_mov_b32_e32 v98, v100
	v_mov_b32_e32 v99, v26
	v_mov_b32_e32 v26, v101
	s_waitcnt lgkmcnt(6)
	v_mov_b32_e32 v101, v28
	v_mov_b32_e32 v28, v103
	v_fmac_f32_e32 v21, v93, v22
	v_fma_f32 v0, v32, v130, v0
	v_fma_f32 v1, v33, v131, v1
	v_fmac_f32_e32 v136, v90, v19
	v_add_f32_e32 v10, v10, v135
	v_mov_b32_e32 v100, v102
	v_mul_f32 v4, v36, v28
	v_mul_f32 v5, v37, v29
	v_fmac_f32_e32 v21, v94, v23
	s_waitcnt vmcnt(19)
	v_fma_f32 v0, v52, v98, v0
	v_fma_f32 v1, v53, v99, v1
	v_add_f32_e32 v10, v10, v136
	v_mov_b32_e32 v102, v104
	v_mov_b32_e32 v103, v30
	v_mov_b32_e32 v30, v105
	s_waitcnt lgkmcnt(4)
	v_mov_b32_e32 v105, v110
	v_mov_b32_e32 v110, v107
	v_fma_f32 v4, v34, v100, v4
	v_fma_f32 v5, v35, v101, v5
	s_waitcnt vmcnt(18)
	v_fma_f32 v0, v54, v26, v0
	v_fma_f32 v1, v55, v27, v1
	v_add_f32_e32 v10, v10, v21
	v_mov_b32_e32 v104, v106
	v_mul_f32 v8, v44, v110
	v_mul_f32 v9, v45, v111
	v_fma_f32 v2, v38, v102, v4
	v_fma_f32 v3, v39, v103, v5
	v_add_f32_e32 v0, v10, v0
	v_mov_b32_e32 v106, v108
	v_mov_b32_e32 v107, v112
	v_mov_b32_e32 v112, v109
	s_waitcnt lgkmcnt(2)
	v_mov_b32_e32 v109, v118
	v_mov_b32_e32 v118, v115
	v_fma_f32 v8, v42, v104, v8
	v_fma_f32 v9, v43, v105, v9
	v_fma_f32 v2, v40, v30, v2
	v_fma_f32 v3, v41, v31, v3
	v_add_f32_e32 v0, v0, v1
	v_mov_b32_e32 v108, v114
	s_waitcnt vmcnt(12)
	v_mul_f32 v12, v58, v118
	v_mul_f32 v13, v59, v119
	v_fma_f32 v4, v46, v106, v8
	v_fma_f32 v5, v47, v107, v9
	v_add_f32_e32 v0, v0, v2
	v_mov_b32_e32 v114, v116
	v_mov_b32_e32 v115, v120
	v_mov_b32_e32 v120, v117
	s_waitcnt lgkmcnt(0)
	v_mov_b32_e32 v117, v126
	v_mov_b32_e32 v126, v123
	v_fma_f32 v12, v56, v108, v12
	v_fma_f32 v13, v57, v109, v13
	v_fma_f32 v4, v48, v112, v4
	v_fma_f32 v5, v49, v113, v5
	v_add_f32_e32 v0, v0, v3
	v_mov_b32_e32 v116, v122
	s_waitcnt vmcnt(4)
	v_mul_f32 v16, v66, v126
	v_mul_f32 v17, v67, v127
	v_fma_f32 v6, v60, v114, v12
	v_fma_f32 v7, v61, v115, v13
	v_add_f32_e32 v0, v0, v4
	v_mov_b32_e32 v122, v124
	v_mov_b32_e32 v123, v128
	v_fma_f32 v16, v64, v116, v16
	v_fma_f32 v17, v65, v117, v17
	v_fma_f32 v6, v62, v120, v6
	v_fma_f32 v7, v63, v121, v7
	v_add_f32_e32 v0, v0, v5
	v_mov_b32_e32 v128, v125
	s_waitcnt vmcnt(3)
	v_fma_f32 v8, v68, v122, v16
	v_fma_f32 v9, v69, v123, v17
	v_add_f32_e32 v0, v0, v6
	s_waitcnt vmcnt(2)
	v_fma_f32 v8, v70, v128, v8
	v_fma_f32 v9, v71, v129, v9
	v_add_f32_e32 v0, v0, v7
	v_add_f32_e32 v0, v0, v8
	v_add_f32_e32 v0, v0, v9
	s_waitcnt vmcnt(1)
	v_add_f32_e32 v0, v96, v0
	s_waitcnt vmcnt(0)
	v_mul_f32_e32 v0, v97, v0
	v_mul_f32_e32 v0, 0.15915494, v0
	v_sin_f32_e32 v0, v0
	v_add_u32_e32 v1, s16, v170
	s_addk_i32 s16, 0x100
	s_cmpk_eq_i32 s16, 0x400
	ds_write_b32 v1, v0
	s_cbranch_scc0 .LBB0_56
	s_waitcnt lgkmcnt(0)
	s_barrier
	s_load_dwordx2 s[18:19], s[20:21], 0xe8
	s_and_b64 s[16:17], s[56:57], exec
	s_cselect_b32 s53, 0x20000, 0
	s_load_dwordx2 s[16:17], s[20:21], 0xf8
	v_readlane_b32 s88, v252, 5
	s_waitcnt lgkmcnt(0)
	s_add_u32 s18, s18, s53
	s_addc_u32 s19, s19, 0
	v_lshl_add_u64 v[22:23], v[148:149], 2, s[18:19]
	v_add_co_u32_e32 v0, vcc, s61, v22
	s_movk_i32 s18, 0x4000
	s_nop 0
	v_addc_co_u32_e32 v1, vcc, 0, v23, vcc
	v_add_co_u32_e32 v2, vcc, s60, v22
	s_nop 1
	v_addc_co_u32_e32 v3, vcc, 0, v23, vcc
	v_add_co_u32_e32 v4, vcc, s62, v22
	s_nop 1
	v_addc_co_u32_e32 v5, vcc, 0, v23, vcc
	v_add_co_u32_e32 v6, vcc, s18, v22
	s_movk_i32 s18, 0x5000
	s_nop 0
	v_addc_co_u32_e32 v7, vcc, 0, v23, vcc
	v_add_co_u32_e32 v8, vcc, s18, v22
	s_movk_i32 s18, 0x7000
	s_nop 0
	v_addc_co_u32_e32 v9, vcc, 0, v23, vcc
	v_add_co_u32_e32 v10, vcc, s39, v22
	s_nop 1
	v_addc_co_u32_e32 v11, vcc, 0, v23, vcc
	global_load_dword v24, v[2:3], off offset:-4096
	global_load_dword v25, v[2:3], off
	global_load_dword v26, v[2:3], off offset:2048
	global_load_dword v27, v[6:7], off offset:-4096
	global_load_dword v28, v[6:7], off
	global_load_dword v29, v[6:7], off offset:2048
	global_load_dword v30, v[10:11], off offset:-4096
	global_load_dword v31, v[10:11], off
	v_add_co_u32_e32 v2, vcc, s18, v22
	s_mov_b32 s18, 0x8000
	s_nop 0
	v_addc_co_u32_e32 v3, vcc, 0, v23, vcc
	v_add_co_u32_e32 v6, vcc, s18, v22
	s_mov_b32 s18, 0x9000
	s_nop 0
	v_addc_co_u32_e32 v7, vcc, 0, v23, vcc
	v_add_co_u32_e32 v12, vcc, s18, v22
	s_mov_b32 s18, 0xa000
	s_nop 0
	v_addc_co_u32_e32 v13, vcc, 0, v23, vcc
	v_add_co_u32_e32 v14, vcc, s18, v22
	s_mov_b32 s18, 0xb000
	s_nop 0
	v_addc_co_u32_e32 v15, vcc, 0, v23, vcc
	v_add_co_u32_e32 v16, vcc, s18, v22
	s_mov_b32 s18, 0xd000
	s_nop 0
	v_addc_co_u32_e32 v17, vcc, 0, v23, vcc
	v_add_co_u32_e32 v18, vcc, s63, v22
	s_nop 1
	v_addc_co_u32_e32 v19, vcc, 0, v23, vcc
	global_load_dword v32, v[10:11], off offset:2048
	global_load_dword v33, v[6:7], off offset:-4096
	global_load_dword v34, v[6:7], off
	global_load_dword v35, v[6:7], off offset:2048
	global_load_dword v36, v[14:15], off offset:-4096
	global_load_dword v37, v[14:15], off
	global_load_dword v38, v[14:15], off offset:2048
	global_load_dword v39, v[18:19], off offset:-4096
	global_load_dword v40, v[22:23], off
	global_load_dword v41, v[22:23], off offset:2048
	global_load_dword v42, v[0:1], off offset:2048
	global_load_dword v43, v[4:5], off offset:2048
	global_load_dword v44, v[8:9], off offset:2048
	global_load_dword v45, v[2:3], off offset:2048
	global_load_dword v46, v[12:13], off offset:2048
	global_load_dword v47, v[16:17], off offset:2048
	v_add_co_u32_e32 v12, vcc, s18, v22
	s_mov_b32 s18, 0xe000
	s_nop 0
	v_addc_co_u32_e32 v13, vcc, 0, v23, vcc
	v_add_co_u32_e32 v0, vcc, s18, v22
	s_mov_b32 s18, 0xf000
	s_nop 0
	v_addc_co_u32_e32 v1, vcc, 0, v23, vcc
	v_add_co_u32_e32 v14, vcc, s18, v22
	s_mov_b32 s18, 0x10000
	s_nop 0
	v_addc_co_u32_e32 v15, vcc, 0, v23, vcc
	v_add_co_u32_e32 v2, vcc, s18, v22
	s_mov_b32 s18, 0x11000
	s_nop 0
	v_addc_co_u32_e32 v3, vcc, 0, v23, vcc
	v_add_co_u32_e32 v16, vcc, s18, v22
	global_load_dword v48, v[18:19], off
	global_load_dword v49, v[18:19], off offset:2048
	global_load_dword v50, v[0:1], off offset:-4096
	global_load_dword v51, v[0:1], off
	global_load_dword v52, v[0:1], off offset:2048
	global_load_dword v53, v[2:3], off offset:-4096
	global_load_dword v54, v[2:3], off
	global_load_dword v55, v[2:3], off offset:2048
	v_addc_co_u32_e32 v17, vcc, 0, v23, vcc
	v_add_co_u32_e32 v0, vcc, s64, v22
	s_mov_b32 s18, 0x13000
	s_nop 0
	v_addc_co_u32_e32 v1, vcc, 0, v23, vcc
	v_add_co_u32_e32 v18, vcc, s18, v22
	s_mov_b32 s18, 0x14000
	s_nop 0
	v_addc_co_u32_e32 v19, vcc, 0, v23, vcc
	v_add_co_u32_e32 v2, vcc, s18, v22
	s_mov_b32 s18, 0x15000
	s_nop 0
	v_addc_co_u32_e32 v3, vcc, 0, v23, vcc
	v_add_co_u32_e32 v20, vcc, s18, v22
	s_mov_b32 s18, 0x16000
	s_nop 0
	v_addc_co_u32_e32 v21, vcc, 0, v23, vcc
	v_add_co_u32_e32 v6, vcc, s18, v22
	s_mov_b32 s18, 0x17000
	s_nop 0
	v_addc_co_u32_e32 v7, vcc, 0, v23, vcc
	v_add_co_u32_e32 v64, vcc, s18, v22
	s_mov_b32 s18, 0x19000
	s_nop 0
	v_addc_co_u32_e32 v65, vcc, 0, v23, vcc
	v_add_co_u32_e32 v8, vcc, s65, v22
	global_load_dword v56, v[0:1], off offset:-4096
	global_load_dword v57, v[0:1], off
	global_load_dword v58, v[0:1], off offset:2048
	global_load_dword v59, v[2:3], off offset:-4096
	s_nop 0
	global_load_dword v0, v[2:3], off
	s_nop 0
	global_load_dword v2, v[2:3], off offset:2048
	s_nop 0
	global_load_dword v4, v[6:7], off offset:-4096
	global_load_dword v1, v[6:7], off
	v_addc_co_u32_e32 v9, vcc, 0, v23, vcc
	v_add_co_u32_e32 v66, vcc, s18, v22
	s_mov_b32 s18, 0x1a000
	s_nop 0
	v_addc_co_u32_e32 v67, vcc, 0, v23, vcc
	v_add_co_u32_e32 v60, vcc, s18, v22
	s_mov_b32 s18, 0x1b000
	s_nop 0
	v_addc_co_u32_e32 v61, vcc, 0, v23, vcc
	v_add_co_u32_e32 v68, vcc, s18, v22
	s_mov_b32 s18, 0x1c000
	s_nop 0
	v_addc_co_u32_e32 v69, vcc, 0, v23, vcc
	v_add_co_u32_e32 v70, vcc, s18, v22
	s_mov_b32 s18, 0x1d000
	s_nop 0
	v_addc_co_u32_e32 v71, vcc, 0, v23, vcc
	global_load_dword v3, v[6:7], off offset:2048
	global_load_dword v5, v[8:9], off offset:-4096
	s_nop 0
	global_load_dword v6, v[8:9], off
	s_nop 0
	global_load_dword v8, v[8:9], off offset:2048
	s_nop 0
	global_load_dword v10, v[60:61], off offset:-4096
	global_load_dword v7, v[60:61], off
	global_load_dword v9, v[60:61], off offset:2048
	global_load_dword v11, v[70:71], off offset:-4096
	s_nop 0
	global_load_dword v60, v[12:13], off offset:2048
	global_load_dword v61, v[14:15], off offset:2048
	global_load_dword v62, v[16:17], off offset:2048
	global_load_dword v63, v[18:19], off offset:2048
	s_nop 0
	global_load_dword v12, v[20:21], off offset:2048
	global_load_dword v13, v[64:65], off offset:2048
	global_load_dword v14, v[66:67], off offset:2048
	global_load_dword v15, v[68:69], off offset:2048
	v_add_co_u32_e32 v64, vcc, s18, v22
	s_mov_b32 s18, 0x1f000
	s_nop 0
	v_addc_co_u32_e32 v65, vcc, 0, v23, vcc
	v_add_co_u32_e32 v66, vcc, s67, v22
	s_nop 1
	v_addc_co_u32_e32 v67, vcc, 0, v23, vcc
	global_load_dword v16, v[70:71], off
	global_load_dword v18, v[70:71], off offset:2048
	global_load_dword v20, v[66:67], off offset:-4096
	global_load_dword v17, v[66:67], off
	global_load_dword v19, v[66:67], off offset:2048
	v_add_co_u32_e32 v66, vcc, s18, v22
	s_and_b64 s[18:19], s[56:57], exec
	s_cselect_b32 s18, 0x200, 0
	v_addc_co_u32_e32 v67, vcc, 0, v23, vcc
	global_load_dword v22, v[64:65], off offset:2048
	global_load_dword v21, v[66:67], off
	global_load_dword v23, v[66:67], off offset:2048
	v_add_u32_e32 v64, s18, v148
	v_ashrrev_i32_e32 v65, 31, v64
	v_lshl_add_u64 v[64:65], v[64:65], 2, s[16:17]
	global_load_dword v64, v[64:65], off
	s_lshr_b32 s17, s26, 1
	v_cvt_f32_u32_e32 v65, s17
	s_mov_b32 s16, 0
	s_sub_i32 s17, s52, s17
	v_mov_b32_e32 v66, v171
.LBB0_58:
	v_mov_b32_e32 v67, s16
	ds_read_b128 v[68:71], v67 offset:8192
	ds_read_b128 v[72:75], v67 offset:8208
	ds_read_b128 v[76:79], v67 offset:8224
	ds_read_b128 v[80:83], v67 offset:8240
	s_addk_i32 s16, 0x100
	s_waitcnt vmcnt(47) lgkmcnt(3)
	v_mul_f32_e32 v69, v41, v69
	v_fmac_f32_e32 v69, v40, v68
	v_fmac_f32_e32 v69, v24, v70
	s_waitcnt vmcnt(46)
	v_fmac_f32_e32 v69, v42, v71
	v_add_f32_e32 v68, 0, v69
	s_waitcnt lgkmcnt(2)
	v_mul_f32_e32 v69, v26, v73
	v_fmac_f32_e32 v69, v25, v72
	v_fmac_f32_e32 v69, v27, v74
	s_waitcnt vmcnt(45)
	v_fmac_f32_e32 v69, v43, v75
	v_add_f32_e32 v68, v68, v69
	s_waitcnt lgkmcnt(1)
	v_mul_f32_e32 v69, v29, v77
	v_fmac_f32_e32 v69, v28, v76
	v_fmac_f32_e32 v69, v30, v78
	s_waitcnt vmcnt(44)
	v_fmac_f32_e32 v69, v44, v79
	v_add_f32_e32 v68, v68, v69
	s_waitcnt lgkmcnt(0)
	v_mul_f32_e32 v69, v32, v81
	v_fmac_f32_e32 v69, v31, v80
	v_fmac_f32_e32 v69, v33, v82
	s_waitcnt vmcnt(43)
	v_fmac_f32_e32 v69, v45, v83
	v_add_f32_e32 v72, v68, v69
	ds_read_b128 v[68:71], v67 offset:8256
	s_waitcnt lgkmcnt(0)
	v_mul_f32_e32 v69, v35, v69
	v_fmac_f32_e32 v69, v34, v68
	v_fmac_f32_e32 v69, v36, v70
	s_waitcnt vmcnt(42)
	v_fmac_f32_e32 v69, v46, v71
	v_add_f32_e32 v72, v72, v69
	ds_read_b128 v[68:71], v67 offset:8272
	s_waitcnt lgkmcnt(0)
	v_mul_f32_e32 v69, v38, v69
	v_fmac_f32_e32 v69, v37, v68
	v_fmac_f32_e32 v69, v39, v70
	s_waitcnt vmcnt(41)
	v_fmac_f32_e32 v69, v47, v71
	v_add_f32_e32 v72, v72, v69
	ds_read_b128 v[68:71], v67 offset:8288
	s_waitcnt vmcnt(39) lgkmcnt(0)
	v_mul_f32_e32 v69, v49, v69
	v_fmac_f32_e32 v69, v48, v68
	s_waitcnt vmcnt(38)
	v_fmac_f32_e32 v69, v50, v70
	s_waitcnt vmcnt(16)
	v_fmac_f32_e32 v69, v60, v71
	v_add_f32_e32 v72, v72, v69
	ds_read_b128 v[68:71], v67 offset:8304
	s_waitcnt lgkmcnt(0)
	v_mul_f32_e32 v69, v52, v69
	v_fmac_f32_e32 v69, v51, v68
	v_fmac_f32_e32 v69, v53, v70
	s_waitcnt vmcnt(15)
	v_fmac_f32_e32 v69, v61, v71
	v_add_f32_e32 v72, v72, v69
	ds_read_b128 v[68:71], v67 offset:8320
	s_waitcnt lgkmcnt(0)
	v_mul_f32_e32 v69, v55, v69
	v_fmac_f32_e32 v69, v54, v68
	v_fmac_f32_e32 v69, v56, v70
	s_waitcnt vmcnt(14)
	v_fmac_f32_e32 v69, v62, v71
	v_add_f32_e32 v72, v72, v69
	ds_read_b128 v[68:71], v67 offset:8336
	s_waitcnt lgkmcnt(0)
	v_mul_f32_e32 v69, v58, v69
	v_fmac_f32_e32 v69, v57, v68
	v_fmac_f32_e32 v69, v59, v70
	s_waitcnt vmcnt(13)
	v_fmac_f32_e32 v69, v63, v71
	v_add_f32_e32 v78, v72, v69
	ds_read_b128 v[68:71], v67 offset:8352
	ds_read_b128 v[72:75], v67 offset:8368
	s_waitcnt lgkmcnt(1)
	v_mov_b32_e32 v76, v68
	s_waitcnt lgkmcnt(0)
	v_mov_b32_e32 v77, v72
	v_mov_b32_e32 v72, v69
	v_mul_f32 v68, v2, v72
	v_mul_f32 v69, v3, v73
	v_mov_b32_e32 v72, v70
	v_fma_f32 v68, v0, v76, v68
	v_fma_f32 v69, v1, v77, v69
	v_mov_b32_e32 v73, v74
	v_fma_f32 v68, v4, v72, v68
	v_fma_f32 v69, v5, v73, v69
	v_mov_b32_e32 v74, v71
	s_waitcnt vmcnt(11)
	v_fma_f32 v68, v12, v74, v68
	v_fma_f32 v69, v13, v75, v69
	s_nop 0
	v_add_f32_e32 v68, v78, v68
	v_add_f32_e32 v78, v68, v69
	ds_read_b128 v[68:71], v67 offset:8384
	ds_read_b128 v[72:75], v67 offset:8400
	s_waitcnt lgkmcnt(1)
	v_mov_b32_e32 v76, v68
	s_waitcnt lgkmcnt(0)
	v_mov_b32_e32 v77, v72
	v_mov_b32_e32 v72, v69
	v_mul_f32 v68, v8, v72
	v_mul_f32 v69, v9, v73
	v_mov_b32_e32 v72, v70
	v_fma_f32 v68, v6, v76, v68
	v_fma_f32 v69, v7, v77, v69
	v_mov_b32_e32 v73, v74
	v_fma_f32 v68, v10, v72, v68
	v_fma_f32 v69, v11, v73, v69
	v_mov_b32_e32 v74, v71
	s_waitcnt vmcnt(9)
	v_fma_f32 v68, v14, v74, v68
	v_fma_f32 v69, v15, v75, v69
	s_nop 0
	v_add_f32_e32 v68, v78, v68
	v_add_f32_e32 v78, v68, v69
	ds_read_b128 v[68:71], v67 offset:8416
	ds_read_b128 v[72:75], v67 offset:8432
	s_waitcnt lgkmcnt(1)
	v_mov_b32_e32 v76, v68
	s_waitcnt lgkmcnt(0)
	v_mov_b32_e32 v77, v72
	v_mov_b32_e32 v72, v69
	s_waitcnt vmcnt(4)
	v_mul_f32 v68, v18, v72
	v_mul_f32 v69, v19, v73
	v_mov_b32_e32 v72, v70
	v_fma_f32 v68, v16, v76, v68
	v_fma_f32 v69, v17, v77, v69
	v_mov_b32_e32 v73, v74
	s_waitcnt vmcnt(2)
	v_fma_f32 v68, v20, v72, v68
	v_fma_f32 v69, v21, v73, v69
	v_mov_b32_e32 v74, v71
	s_waitcnt vmcnt(1)
	v_fma_f32 v68, v22, v74, v68
	v_fma_f32 v69, v23, v75, v69
	s_nop 0
	v_add_f32_e32 v67, v78, v68
	v_cvt_f32_i32_e32 v68, s17
	v_add_f32_e32 v67, v67, v69
	s_add_i32 s17, s17, 1
	s_cmpk_lg_i32 s16, 0x2000
	v_and_b32_e32 v69, 0x7fffffff, v68
	v_div_scale_f32 v70, s[18:19], v65, v65, v69
	v_rcp_f32_e32 v71, v70
	v_div_scale_f32 v69, vcc, v69, v65, v69
	v_fma_f32 v72, -v70, v71, 1.0
	v_fmac_f32_e32 v71, v72, v71
	v_mul_f32_e32 v72, v69, v71
	v_fma_f32 v73, -v70, v72, v69
	v_fmac_f32_e32 v72, v73, v71
	v_fma_f32 v69, -v70, v72, v69
	v_div_fmas_f32 v69, v69, v71, v72
	v_div_fixup_f32 v68, v69, v65, |v68|
	s_waitcnt vmcnt(0)
	v_mul_f32_e64 v68, |v64|, v68
	v_mul_f32_e32 v68, 0xbfb8aa3b, v68
	v_exp_f32_e32 v68, v68
	s_nop 0
	v_mul_f32_e32 v67, v68, v67
	v_bfe_u32 v68, v67, 16, 1
	v_add3_u32 v67, v67, v68, s68
	ds_write_b16_d16_hi v66, v67
	v_add_u32_e32 v66, 0x400, v66
	s_cbranch_scc1 .LBB0_58
	s_ashr_i32 s53, s52, 31
	s_and_b64 s[16:17], s[58:59], exec
	s_cselect_b32 s16, 11, 8
	v_lshlrev_b64 v[0:1], s16, v[148:149]
	s_cselect_b32 s18, 0x40000, 0
	s_and_b64 s[16:17], s[56:57], exec
	s_cselect_b32 s16, 0x240000, 0
	s_add_u32 s16, s33, s16
	ds_read_u16 v2, v153 offset:16384
	ds_read_u16 v3, v153 offset:17408
	ds_read_u16 v6, v153 offset:18432
	ds_read_u16 v7, v153 offset:19456
	ds_read_u16 v8, v153 offset:20480
	ds_read_u16 v9, v153 offset:21504
	ds_read_u16 v10, v153 offset:22528
	ds_read_u16 v11, v153 offset:23552
	s_addc_u32 s17, s38, 0
	s_add_u32 s16, s16, s18
	s_addc_u32 s17, s17, 0
	v_lshl_add_u64 v[0:1], v[0:1], 1, s[16:17]
	v_lshl_add_u64 v[4:5], s[52:53], 1, v[0:1]
	s_waitcnt lgkmcnt(6)
	v_lshl_or_b32 v0, v3, 16, v2
	s_waitcnt lgkmcnt(4)
	v_lshl_or_b32 v1, v7, 16, v6
	s_waitcnt lgkmcnt(2)
	v_lshl_or_b32 v2, v9, 16, v8
	s_waitcnt lgkmcnt(0)
	v_lshl_or_b32 v3, v11, 16, v10
	flat_store_dwordx4 v[4:5], v[0:3]
	ds_read_u16 v0, v153 offset:24576
	ds_read_u16 v1, v153 offset:25600
	ds_read_u16 v2, v153 offset:26624
	ds_read_u16 v3, v153 offset:27648
	ds_read_u16 v6, v153 offset:28672
	ds_read_u16 v7, v153 offset:29696
	ds_read_u16 v8, v153 offset:30720
	ds_read_u16 v9, v153 offset:31744
	s_waitcnt lgkmcnt(0)
	v_lshl_or_b32 v0, v1, 16, v0
	v_lshl_or_b32 v1, v3, 16, v2
	v_lshl_or_b32 v2, v7, 16, v6
	v_lshl_or_b32 v3, v9, 16, v8
	flat_store_dwordx4 v[4:5], v[0:3] offset:16
	ds_read_u16 v0, v153 offset:32768
	ds_read_u16 v1, v153 offset:33792
	ds_read_u16 v2, v153 offset:34816
	ds_read_u16 v3, v153 offset:35840
	ds_read_u16 v6, v153 offset:36864
	ds_read_u16 v7, v153 offset:37888
	ds_read_u16 v8, v153 offset:38912
	ds_read_u16 v9, v153 offset:39936
	s_waitcnt lgkmcnt(0)
	v_lshl_or_b32 v0, v1, 16, v0
	v_lshl_or_b32 v1, v3, 16, v2
	v_lshl_or_b32 v2, v7, 16, v6
	v_lshl_or_b32 v3, v9, 16, v8
	flat_store_dwordx4 v[4:5], v[0:3] offset:32
	ds_read_u16 v0, v153 offset:40960
	ds_read_u16 v1, v153 offset:41984
	ds_read_u16 v2, v153 offset:43008
	ds_read_u16 v3, v153 offset:44032
	ds_read_u16 v6, v153 offset:45056
	ds_read_u16 v7, v153 offset:46080
	ds_read_u16 v8, v153 offset:47104
	ds_read_u16 v9, v153 offset:48128
	s_waitcnt lgkmcnt(0)
	v_lshl_or_b32 v0, v1, 16, v0
	v_lshl_or_b32 v1, v3, 16, v2
	v_lshl_or_b32 v2, v7, 16, v6
	v_lshl_or_b32 v3, v9, 16, v8
	flat_store_dwordx4 v[4:5], v[0:3] offset:48
	s_waitcnt lgkmcnt(0)
	s_barrier

.LBB0_68:
	s_or_b64 exec, exec, s[18:19]
	s_waitcnt lgkmcnt(0)
	s_barrier
	ds_read_b128 v[178:181], v158
	ds_read_b128 v[136:139], v158 offset:16
	ds_read_b128 v[132:135], v158 offset:32
	ds_read_b128 v[108:111], v158 offset:48
	ds_read_b128 v[182:185], v158 offset:4096
	ds_read_b128 v[186:189], v158 offset:8192
	ds_read_b128 v[190:193], v158 offset:4112
	ds_read_b128 v[194:197], v158 offset:12288
	ds_read_b128 v[198:201], v158 offset:8208
	ds_read_b128 v[202:205], v158 offset:16384
	ds_read_b128 v[206:209], v158 offset:12304
	s_waitcnt vmcnt(0) lgkmcnt(0)
	v_fma_f32 v214, v128, v178, 0
	v_fma_f32 v215, v129, v178, 0
	v_fma_f32 v216, v130, v178, 0
	v_fma_f32 v217, v131, v178, 0
	v_fma_f32 v218, v128, v182, 0
	v_fma_f32 v219, v129, v182, 0
	v_fma_f32 v220, v130, v182, 0
	v_fma_f32 v221, v131, v182, 0
	v_fma_f32 v222, v128, v186, 0
	v_fma_f32 v223, v129, v186, 0
	v_fma_f32 v224, v130, v186, 0
	v_fma_f32 v225, v131, v186, 0
	v_fma_f32 v226, v128, v194, 0
	v_fma_f32 v227, v129, v194, 0
	v_fma_f32 v228, v130, v194, 0
	v_fma_f32 v229, v131, v194, 0
	v_fma_f32 v128, v128, v202, 0
	v_fma_f32 v129, v129, v202, 0
	v_fma_f32 v130, v130, v202, 0
	v_fma_f32 v131, v131, v202, 0
	v_fma_f32 v216, v126, v179, v216
	v_fma_f32 v217, v127, v179, v217
	v_fma_f32 v178, v124, v179, v214
	v_fma_f32 v179, v125, v179, v215
	v_fma_f32 v214, v126, v183, v220
	v_fma_f32 v215, v127, v183, v221
	v_fma_f32 v182, v124, v183, v218
	v_fma_f32 v183, v125, v183, v219
	v_fma_f32 v218, v126, v187, v224
	v_fma_f32 v219, v127, v187, v225
	v_fma_f32 v186, v124, v187, v222
	v_fma_f32 v187, v125, v187, v223
	v_fma_f32 v220, v126, v195, v228
	v_fma_f32 v221, v127, v195, v229
	v_fma_f32 v194, v124, v195, v226
	v_fma_f32 v195, v125, v195, v227
	v_fma_f32 v124, v124, v203, v128
	v_fma_f32 v125, v125, v203, v129
	ds_read_b128 v[210:213], v158 offset:16400
	v_fma_f32 v126, v126, v203, v130
	v_fma_f32 v127, v127, v203, v131
	v_fma_f32 v128, v120, v180, v178
	v_fma_f32 v129, v121, v180, v179
	v_fma_f32 v130, v122, v180, v216
	v_fma_f32 v131, v123, v180, v217
	v_fma_f32 v178, v120, v184, v182
	v_fma_f32 v179, v121, v184, v183
	v_fma_f32 v186, v120, v188, v186
	v_fma_f32 v187, v121, v188, v187
	v_fma_f32 v194, v120, v196, v194
	v_fma_f32 v195, v121, v196, v195
	v_fma_f32 v120, v120, v204, v124
	v_fma_f32 v121, v121, v204, v125
	v_mov_b32_e32 v124, v181
	v_fma_f32 v182, v122, v184, v214
	v_fma_f32 v183, v123, v184, v215
	v_fma_f32 v202, v122, v188, v218
	v_fma_f32 v203, v123, v188, v219
	v_fma_f32 v214, v122, v196, v220
	v_fma_f32 v215, v123, v196, v221
	v_fma_f32 v122, v122, v204, v126
	v_fma_f32 v123, v123, v204, v127
	v_fma_f32 v126, v118, v124, v130
	v_fma_f32 v127, v119, v124, v131
	v_fma_f32 v125, v117, v124, v129
	v_fma_f32 v124, v116, v124, v128
	v_mov_b32_e32 v128, v185
	v_mov_b32_e32 v144, v189
	v_fma_f32 v130, v118, v128, v182
	v_fma_f32 v131, v119, v128, v183
	v_fma_f32 v129, v117, v128, v179
	v_fma_f32 v128, v116, v128, v178
	v_fma_f32 v178, v118, v144, v202
	v_fma_f32 v179, v119, v144, v203
	v_fma_f32 v180, v116, v144, v186
	v_fma_f32 v181, v117, v144, v187
	v_mov_b32_e32 v144, v197
	v_fma_f32 v182, v118, v144, v214
	v_fma_f32 v183, v119, v144, v215
	v_fma_f32 v184, v116, v144, v194
	v_fma_f32 v185, v117, v144, v195
	v_mov_b32_e32 v144, v205
	v_fma_f32 v116, v116, v144, v120
	v_fma_f32 v117, v117, v144, v121
	v_fma_f32 v118, v118, v144, v122
	v_fma_f32 v119, v119, v144, v123
	v_fma_f32 v120, v112, v136, v124
	v_fma_f32 v121, v113, v136, v125
	v_fma_f32 v122, v114, v136, v126
	v_fma_f32 v123, v115, v136, v127
	v_fma_f32 v124, v112, v190, v128
	v_fma_f32 v125, v113, v190, v129
	v_fma_f32 v126, v114, v190, v130
	v_fma_f32 v127, v115, v190, v131
	v_fma_f32 v128, v112, v198, v180
	v_fma_f32 v129, v113, v198, v181
	v_fma_f32 v130, v114, v198, v178
	v_fma_f32 v131, v115, v198, v179
	v_fma_f32 v178, v112, v206, v184
	v_fma_f32 v179, v113, v206, v185
	s_waitcnt lgkmcnt(0)
	v_fma_f32 v112, v112, v210, v116
	v_fma_f32 v113, v113, v210, v117
	v_fma_f32 v180, v114, v206, v182
	v_fma_f32 v181, v115, v206, v183
	v_fma_f32 v114, v114, v210, v118
	v_fma_f32 v115, v115, v210, v119
	v_fma_f32 v116, v106, v137, v122
	v_fma_f32 v117, v107, v137, v123
	v_fma_f32 v118, v104, v137, v120
	v_fma_f32 v119, v105, v137, v121
	v_fma_f32 v120, v106, v191, v126
	v_fma_f32 v121, v107, v191, v127
	v_fma_f32 v122, v104, v191, v124
	v_fma_f32 v123, v105, v191, v125
	v_fma_f32 v124, v106, v199, v130
	v_fma_f32 v125, v107, v199, v131
	v_fma_f32 v126, v104, v199, v128
	v_fma_f32 v127, v105, v199, v129
	v_fma_f32 v130, v104, v207, v178
	v_fma_f32 v131, v105, v207, v179
	v_fma_f32 v104, v104, v211, v112
	v_fma_f32 v105, v105, v211, v113
	v_fma_f32 v128, v106, v207, v180
	v_fma_f32 v129, v107, v207, v181
	v_fma_f32 v106, v106, v211, v114
	v_fma_f32 v107, v107, v211, v115
	v_fma_f32 v112, v100, v138, v118
	v_fma_f32 v113, v101, v138, v119
	v_fma_f32 v114, v102, v138, v116
	v_fma_f32 v115, v103, v138, v117
	v_fma_f32 v116, v100, v192, v122
	v_fma_f32 v117, v101, v192, v123
	v_fma_f32 v118, v102, v192, v120
	v_fma_f32 v119, v103, v192, v121
	v_fma_f32 v120, v100, v200, v126
	v_fma_f32 v121, v101, v200, v127
	v_fma_f32 v122, v102, v200, v124
	v_fma_f32 v123, v103, v200, v125
	v_fma_f32 v124, v100, v208, v130
	v_fma_f32 v125, v101, v208, v131
	v_fma_f32 v100, v100, v212, v104
	v_fma_f32 v101, v101, v212, v105
	v_mov_b32_e32 v104, v139
	v_fma_f32 v126, v102, v208, v128
	v_fma_f32 v127, v103, v208, v129
	v_fma_f32 v102, v102, v212, v106
	v_fma_f32 v103, v103, v212, v107
	v_fma_f32 v106, v98, v104, v114
	v_fma_f32 v107, v99, v104, v115
	v_fma_f32 v105, v97, v104, v113
	v_fma_f32 v104, v96, v104, v112
	v_mov_b32_e32 v112, v193
	v_fma_f32 v114, v98, v112, v118
	v_fma_f32 v115, v99, v112, v119
	v_fma_f32 v113, v97, v112, v117
	v_fma_f32 v112, v96, v112, v116
	v_mov_b32_e32 v116, v201
	v_fma_f32 v122, v98, v116, v122
	v_fma_f32 v123, v99, v116, v123
	v_fma_f32 v120, v96, v116, v120
	v_fma_f32 v121, v97, v116, v121
	v_mov_b32_e32 v116, v209
	v_fma_f32 v128, v98, v116, v126
	v_fma_f32 v129, v99, v116, v127
	v_fma_f32 v130, v96, v116, v124
	v_fma_f32 v131, v97, v116, v125
	v_mov_b32_e32 v116, v213
	v_fma_f32 v136, v98, v116, v102
	v_fma_f32 v137, v99, v116, v103
	v_fma_f32 v138, v96, v116, v100
	v_fma_f32 v139, v97, v116, v101
	ds_read_b128 v[96:99], v158 offset:4128
	v_fma_f32 v178, v92, v132, v104
	v_fma_f32 v179, v93, v132, v105
	v_fma_f32 v180, v94, v132, v106
	v_fma_f32 v181, v95, v132, v107
	ds_read_b128 v[100:103], v158 offset:8224
	ds_read_b128 v[104:107], v158 offset:4144
	s_waitcnt lgkmcnt(2)
	v_fma_f32 v182, v92, v96, v112
	v_fma_f32 v183, v93, v96, v113
	v_fma_f32 v184, v94, v96, v114
	v_fma_f32 v185, v95, v96, v115
	ds_read_b128 v[112:115], v158 offset:12320
	ds_read_b128 v[116:119], v158 offset:8240
	s_waitcnt lgkmcnt(3)
	v_fma_f32 v186, v92, v100, v120
	v_fma_f32 v187, v93, v100, v121
	v_fma_f32 v188, v94, v100, v122
	v_fma_f32 v189, v95, v100, v123
	ds_read_b128 v[120:123], v158 offset:16416
	ds_read_b128 v[124:127], v158 offset:12336
	s_waitcnt lgkmcnt(3)
	v_fma_f32 v190, v92, v112, v130
	v_fma_f32 v191, v93, v112, v131
	v_fma_f32 v192, v94, v112, v128
	v_fma_f32 v193, v95, v112, v129
	ds_read_b128 v[128:131], v158 offset:16432
	s_waitcnt lgkmcnt(2)
	v_fma_f32 v92, v92, v120, v138
	v_fma_f32 v93, v93, v120, v139
	v_fma_f32 v94, v94, v120, v136
	v_fma_f32 v95, v95, v120, v137
	v_fma_f32 v136, v86, v133, v180
	v_fma_f32 v137, v87, v133, v181
	v_fma_f32 v132, v84, v133, v178
	v_fma_f32 v133, v85, v133, v179
	v_fma_f32 v138, v86, v97, v184
	v_fma_f32 v139, v87, v97, v185
	v_fma_f32 v96, v84, v97, v182
	v_fma_f32 v97, v85, v97, v183
	v_fma_f32 v178, v86, v101, v188
	v_fma_f32 v179, v87, v101, v189
	v_fma_f32 v100, v84, v101, v186
	v_fma_f32 v101, v85, v101, v187
	v_fma_f32 v180, v86, v113, v192
	v_fma_f32 v181, v87, v113, v193
	v_fma_f32 v112, v84, v113, v190
	v_fma_f32 v113, v85, v113, v191
	v_fma_f32 v84, v84, v121, v92
	v_fma_f32 v85, v85, v121, v93
	v_fma_f32 v86, v86, v121, v94
	v_fma_f32 v87, v87, v121, v95
	v_fma_f32 v92, v88, v134, v132
	v_fma_f32 v93, v89, v134, v133
	v_fma_f32 v94, v90, v134, v136
	v_fma_f32 v95, v91, v134, v137
	v_fma_f32 v96, v88, v98, v96
	v_fma_f32 v97, v89, v98, v97
	v_fma_f32 v100, v88, v102, v100
	v_fma_f32 v101, v89, v102, v101
	v_fma_f32 v112, v88, v114, v112
	v_fma_f32 v113, v89, v114, v113
	v_fma_f32 v84, v88, v122, v84
	v_fma_f32 v85, v89, v122, v85
	v_mov_b32_e32 v88, v135
	v_fma_f32 v120, v90, v98, v138
	v_fma_f32 v121, v91, v98, v139
	v_fma_f32 v132, v90, v102, v178
	v_fma_f32 v133, v91, v102, v179
	v_fma_f32 v136, v90, v114, v180
	v_fma_f32 v137, v91, v114, v181
	v_fma_f32 v86, v90, v122, v86
	v_fma_f32 v87, v91, v122, v87
	v_fma_f32 v90, v82, v88, v94
	v_fma_f32 v91, v83, v88, v95
	v_fma_f32 v89, v81, v88, v93
	v_fma_f32 v88, v80, v88, v92
	v_mov_b32_e32 v92, v99
	v_fma_f32 v94, v82, v92, v120
	v_fma_f32 v95, v83, v92, v121
	v_fma_f32 v93, v81, v92, v97
	v_fma_f32 v92, v80, v92, v96
	v_mov_b32_e32 v96, v103
	v_fma_f32 v98, v82, v96, v132
	v_fma_f32 v99, v83, v96, v133
	v_fma_f32 v97, v81, v96, v101
	v_fma_f32 v96, v80, v96, v100
	v_mov_b32_e32 v100, v115
	v_fma_f32 v102, v82, v100, v136
	v_fma_f32 v103, v83, v100, v137
	v_fma_f32 v101, v81, v100, v113
	v_fma_f32 v100, v80, v100, v112
	v_mov_b32_e32 v112, v123
	v_fma_f32 v80, v80, v112, v84
	v_fma_f32 v81, v81, v112, v85
	v_fma_f32 v82, v82, v112, v86
	v_fma_f32 v83, v83, v112, v87
	v_fma_f32 v84, v76, v108, v88
	v_fma_f32 v85, v77, v108, v89
	v_fma_f32 v86, v78, v108, v90
	v_fma_f32 v87, v79, v108, v91
	v_fma_f32 v88, v76, v104, v92
	v_fma_f32 v89, v77, v104, v93
	v_fma_f32 v90, v78, v104, v94
	v_fma_f32 v91, v79, v104, v95
	v_fma_f32 v92, v76, v116, v96
	v_fma_f32 v93, v77, v116, v97
	v_fma_f32 v94, v78, v116, v98
	v_fma_f32 v95, v79, v116, v99
	s_waitcnt lgkmcnt(1)
	v_fma_f32 v96, v76, v124, v100
	v_fma_f32 v97, v77, v124, v101
	s_waitcnt lgkmcnt(0)
	v_fma_f32 v76, v76, v128, v80
	v_fma_f32 v77, v77, v128, v81
	v_fma_f32 v98, v78, v124, v102
	v_fma_f32 v99, v79, v124, v103
	v_fma_f32 v78, v78, v128, v82
	v_fma_f32 v79, v79, v128, v83
	v_fma_f32 v80, v74, v109, v86
	v_fma_f32 v81, v75, v109, v87
	v_fma_f32 v82, v72, v109, v84
	v_fma_f32 v83, v73, v109, v85
	v_fma_f32 v84, v74, v105, v90
	v_fma_f32 v85, v75, v105, v91
	v_fma_f32 v86, v72, v105, v88
	v_fma_f32 v87, v73, v105, v89
	v_fma_f32 v88, v74, v117, v94
	v_fma_f32 v89, v75, v117, v95
	v_fma_f32 v90, v72, v117, v92
	v_fma_f32 v91, v73, v117, v93
	v_fma_f32 v94, v72, v125, v96
	v_fma_f32 v95, v73, v125, v97
	v_fma_f32 v72, v72, v129, v76
	v_fma_f32 v73, v73, v129, v77
	v_fma_f32 v92, v74, v125, v98
	v_fma_f32 v93, v75, v125, v99
	v_fma_f32 v74, v74, v129, v78
	v_fma_f32 v75, v75, v129, v79
	v_fma_f32 v76, v68, v110, v82
	v_fma_f32 v77, v69, v110, v83
	v_fma_f32 v78, v70, v110, v80
	v_fma_f32 v79, v71, v110, v81
	v_fma_f32 v80, v68, v106, v86
	v_fma_f32 v81, v69, v106, v87
	v_fma_f32 v82, v70, v106, v84
	v_fma_f32 v83, v71, v106, v85
	v_fma_f32 v84, v68, v118, v90
	v_fma_f32 v85, v69, v118, v91
	v_fma_f32 v86, v70, v118, v88
	v_fma_f32 v87, v71, v118, v89
	v_fma_f32 v88, v68, v126, v94
	v_fma_f32 v89, v69, v126, v95
	v_fma_f32 v72, v68, v130, v72
	v_fma_f32 v73, v69, v130, v73
	v_mov_b32_e32 v68, v111
	v_fma_f32 v78, v66, v68, v78
	v_fma_f32 v79, v67, v68, v79
	v_fma_f32 v76, v64, v68, v76
	v_fma_f32 v77, v65, v68, v77
	v_mov_b32_e32 v68, v107
	v_fma_f32 v90, v70, v126, v92
	v_fma_f32 v91, v71, v126, v93
	v_fma_f32 v92, v66, v68, v82
	v_fma_f32 v93, v67, v68, v83
	v_fma_f32 v94, v64, v68, v80
	v_fma_f32 v95, v65, v68, v81
	v_mov_b32_e32 v68, v119
	v_fma_f32 v96, v66, v68, v86
	v_fma_f32 v97, v67, v68, v87
	v_fma_f32 v98, v64, v68, v84
	v_fma_f32 v99, v65, v68, v85
	v_mov_b32_e32 v68, v127
	v_fma_f32 v74, v70, v130, v74
	v_fma_f32 v75, v71, v130, v75
	v_fma_f32 v100, v66, v68, v90
	v_fma_f32 v101, v67, v68, v91
	v_fma_f32 v102, v64, v68, v88
	v_fma_f32 v103, v65, v68, v89
	ds_read_b128 v[68:71], v158 offset:64
	v_mov_b32_e32 v80, v131
	v_fma_f32 v104, v66, v80, v74
	v_fma_f32 v105, v67, v80, v75
	v_fma_f32 v106, v64, v80, v72
	v_fma_f32 v107, v65, v80, v73
	ds_read_b128 v[64:67], v158 offset:4160
	ds_read_b128 v[72:75], v158 offset:80
	s_waitcnt lgkmcnt(2)
	v_fma_f32 v108, v60, v68, v76
	v_fma_f32 v109, v61, v68, v77
	v_fma_f32 v110, v62, v68, v78
	v_fma_f32 v111, v63, v68, v79
	ds_read_b128 v[76:79], v158 offset:8256
	ds_read_b128 v[80:83], v158 offset:4176
	s_waitcnt lgkmcnt(3)
	v_fma_f32 v112, v60, v64, v94
	v_fma_f32 v113, v61, v64, v95
	v_fma_f32 v114, v62, v64, v92
	v_fma_f32 v115, v63, v64, v93
	ds_read_b128 v[84:87], v158 offset:12352
	ds_read_b128 v[88:91], v158 offset:8272
	s_waitcnt lgkmcnt(3)
	v_fma_f32 v116, v60, v76, v98
	v_fma_f32 v117, v61, v76, v99
	v_fma_f32 v118, v62, v76, v96
	v_fma_f32 v119, v63, v76, v97
	ds_read_b128 v[92:95], v158 offset:16448
	ds_read_b128 v[96:99], v158 offset:12368
	s_waitcnt lgkmcnt(3)
	v_fma_f32 v120, v60, v84, v102
	v_fma_f32 v121, v61, v84, v103
	v_fma_f32 v122, v62, v84, v100
	v_fma_f32 v123, v63, v84, v101
	ds_read_b128 v[100:103], v158 offset:16464
	s_waitcnt lgkmcnt(2)
	v_fma_f32 v60, v60, v92, v106
	v_fma_f32 v61, v61, v92, v107
	v_fma_f32 v62, v62, v92, v104
	v_fma_f32 v63, v63, v92, v105
	v_fma_f32 v104, v58, v69, v110
	v_fma_f32 v105, v59, v69, v111
	v_fma_f32 v68, v56, v69, v108
	v_fma_f32 v69, v57, v69, v109
	v_fma_f32 v106, v58, v65, v114
	v_fma_f32 v107, v59, v65, v115
	v_fma_f32 v64, v56, v65, v112
	v_fma_f32 v65, v57, v65, v113
	v_fma_f32 v108, v58, v77, v118
	v_fma_f32 v109, v59, v77, v119
	v_fma_f32 v76, v56, v77, v116
	v_fma_f32 v77, v57, v77, v117
	v_fma_f32 v110, v58, v85, v122
	v_fma_f32 v111, v59, v85, v123
	v_fma_f32 v84, v56, v85, v120
	v_fma_f32 v85, v57, v85, v121
	v_fma_f32 v56, v56, v93, v60
	v_fma_f32 v57, v57, v93, v61
	v_fma_f32 v58, v58, v93, v62
	v_fma_f32 v59, v59, v93, v63
	v_fma_f32 v60, v52, v70, v68
	v_fma_f32 v61, v53, v70, v69
	v_fma_f32 v62, v54, v70, v104
	v_fma_f32 v63, v55, v70, v105
	v_fma_f32 v64, v52, v66, v64
	v_fma_f32 v65, v53, v66, v65
	v_fma_f32 v76, v52, v78, v76
	v_fma_f32 v77, v53, v78, v77
	v_fma_f32 v84, v52, v86, v84
	v_fma_f32 v85, v53, v86, v85
	v_fma_f32 v52, v52, v94, v56
	v_fma_f32 v53, v53, v94, v57
	v_mov_b32_e32 v56, v71
	v_fma_f32 v68, v54, v66, v106
	v_fma_f32 v69, v55, v66, v107
	v_fma_f32 v92, v54, v78, v108
	v_fma_f32 v93, v55, v78, v109
	v_fma_f32 v104, v54, v86, v110
	v_fma_f32 v105, v55, v86, v111
	v_fma_f32 v54, v54, v94, v58
	v_fma_f32 v55, v55, v94, v59
	v_fma_f32 v58, v50, v56, v62
	v_fma_f32 v59, v51, v56, v63
	v_fma_f32 v57, v49, v56, v61
	v_fma_f32 v56, v48, v56, v60
	v_mov_b32_e32 v60, v67
	v_fma_f32 v62, v50, v60, v68
	v_fma_f32 v63, v51, v60, v69
	v_fma_f32 v61, v49, v60, v65
	v_fma_f32 v60, v48, v60, v64
	v_mov_b32_e32 v64, v79
	v_fma_f32 v66, v50, v64, v92
	v_fma_f32 v67, v51, v64, v93
	v_fma_f32 v65, v49, v64, v77
	v_fma_f32 v64, v48, v64, v76
	v_mov_b32_e32 v68, v87
	v_mov_b32_e32 v76, v95
	v_fma_f32 v70, v50, v68, v104
	v_fma_f32 v71, v51, v68, v105
	v_fma_f32 v69, v49, v68, v85
	v_fma_f32 v68, v48, v68, v84
	v_fma_f32 v48, v48, v76, v52
	v_fma_f32 v49, v49, v76, v53
	v_fma_f32 v50, v50, v76, v54
	v_fma_f32 v51, v51, v76, v55
	v_fma_f32 v52, v44, v72, v56
	v_fma_f32 v53, v45, v72, v57
	v_fma_f32 v54, v46, v72, v58
	v_fma_f32 v55, v47, v72, v59
	v_fma_f32 v56, v44, v80, v60
	v_fma_f32 v57, v45, v80, v61
	v_fma_f32 v58, v46, v80, v62
	v_fma_f32 v59, v47, v80, v63
	v_fma_f32 v60, v44, v88, v64
	v_fma_f32 v61, v45, v88, v65
	v_fma_f32 v62, v46, v88, v66
	v_fma_f32 v63, v47, v88, v67
	s_waitcnt lgkmcnt(1)
	v_fma_f32 v64, v44, v96, v68
	v_fma_f32 v65, v45, v96, v69
	s_waitcnt lgkmcnt(0)
	v_fma_f32 v44, v44, v100, v48
	v_fma_f32 v45, v45, v100, v49
	v_fma_f32 v66, v46, v96, v70
	v_fma_f32 v67, v47, v96, v71
	v_fma_f32 v46, v46, v100, v50
	v_fma_f32 v47, v47, v100, v51
	v_fma_f32 v48, v42, v73, v54
	v_fma_f32 v49, v43, v73, v55
	v_fma_f32 v50, v40, v73, v52
	v_fma_f32 v51, v41, v73, v53
	v_fma_f32 v52, v42, v81, v58
	v_fma_f32 v53, v43, v81, v59
	v_fma_f32 v54, v40, v81, v56
	v_fma_f32 v55, v41, v81, v57
	v_fma_f32 v56, v42, v89, v62
	v_fma_f32 v57, v43, v89, v63
	v_fma_f32 v58, v40, v89, v60
	v_fma_f32 v59, v41, v89, v61
	v_fma_f32 v62, v40, v97, v64
	v_fma_f32 v63, v41, v97, v65
	v_fma_f32 v40, v40, v101, v44
	v_fma_f32 v41, v41, v101, v45
	v_fma_f32 v60, v42, v97, v66
	v_fma_f32 v61, v43, v97, v67
	v_fma_f32 v42, v42, v101, v46
	v_fma_f32 v43, v43, v101, v47
	v_fma_f32 v44, v36, v74, v50
	v_fma_f32 v45, v37, v74, v51
	v_fma_f32 v46, v38, v74, v48
	v_fma_f32 v47, v39, v74, v49
	v_fma_f32 v48, v36, v82, v54
	v_fma_f32 v49, v37, v82, v55
	v_fma_f32 v50, v38, v82, v52
	v_fma_f32 v51, v39, v82, v53
	v_fma_f32 v52, v36, v90, v58
	v_fma_f32 v53, v37, v90, v59
	v_fma_f32 v54, v38, v90, v56
	v_fma_f32 v55, v39, v90, v57
	v_fma_f32 v56, v36, v98, v62
	v_fma_f32 v57, v37, v98, v63
	v_fma_f32 v40, v36, v102, v40
	v_fma_f32 v41, v37, v102, v41
	v_mov_b32_e32 v36, v75
	v_fma_f32 v46, v34, v36, v46
	v_fma_f32 v47, v35, v36, v47
	v_fma_f32 v44, v32, v36, v44
	v_fma_f32 v45, v33, v36, v45
	v_mov_b32_e32 v36, v83
	v_fma_f32 v58, v38, v98, v60
	v_fma_f32 v59, v39, v98, v61
	v_fma_f32 v60, v34, v36, v50
	v_fma_f32 v61, v35, v36, v51
	v_fma_f32 v62, v32, v36, v48
	v_fma_f32 v63, v33, v36, v49
	v_mov_b32_e32 v36, v91
	v_fma_f32 v64, v34, v36, v54
	v_fma_f32 v65, v35, v36, v55
	v_fma_f32 v66, v32, v36, v52
	v_fma_f32 v67, v33, v36, v53
	v_mov_b32_e32 v36, v99
	v_fma_f32 v42, v38, v102, v42
	v_fma_f32 v43, v39, v102, v43
	v_fma_f32 v68, v34, v36, v58
	v_fma_f32 v69, v35, v36, v59
	v_fma_f32 v70, v32, v36, v56
	v_fma_f32 v71, v33, v36, v57
	ds_read_b128 v[36:39], v158 offset:96
	v_mov_b32_e32 v48, v103
	v_fma_f32 v72, v34, v48, v42
	v_fma_f32 v73, v35, v48, v43
	v_fma_f32 v74, v32, v48, v40
	v_fma_f32 v75, v33, v48, v41
	ds_read_b128 v[32:35], v158 offset:4192
	ds_read_b128 v[40:43], v158 offset:112
	s_waitcnt lgkmcnt(2)
	v_fma_f32 v76, v28, v36, v44
	v_fma_f32 v77, v29, v36, v45
	v_fma_f32 v78, v30, v36, v46
	v_fma_f32 v79, v31, v36, v47
	ds_read_b128 v[44:47], v158 offset:8288
	ds_read_b128 v[48:51], v158 offset:4208
	s_waitcnt lgkmcnt(3)
	v_fma_f32 v80, v28, v32, v62
	v_fma_f32 v81, v29, v32, v63
	v_fma_f32 v82, v30, v32, v60
	v_fma_f32 v83, v31, v32, v61
	ds_read_b128 v[52:55], v158 offset:12384
	ds_read_b128 v[56:59], v158 offset:8304
	s_waitcnt lgkmcnt(3)
	v_fma_f32 v84, v28, v44, v66
	v_fma_f32 v85, v29, v44, v67
	v_fma_f32 v86, v30, v44, v64
	v_fma_f32 v87, v31, v44, v65
	ds_read_b128 v[60:63], v158 offset:16480
	ds_read_b128 v[64:67], v158 offset:12400
	s_waitcnt lgkmcnt(3)
	v_fma_f32 v88, v28, v52, v70
	v_fma_f32 v89, v29, v52, v71
	v_fma_f32 v90, v30, v52, v68
	v_fma_f32 v91, v31, v52, v69
	ds_read_b128 v[68:71], v158 offset:16496
	s_waitcnt lgkmcnt(2)
	v_fma_f32 v28, v28, v60, v74
	v_fma_f32 v29, v29, v60, v75
	v_fma_f32 v30, v30, v60, v72
	v_fma_f32 v31, v31, v60, v73
	v_fma_f32 v72, v22, v37, v78
	v_fma_f32 v73, v23, v37, v79
	v_fma_f32 v36, v20, v37, v76
	v_fma_f32 v37, v21, v37, v77
	v_fma_f32 v74, v22, v33, v82
	v_fma_f32 v75, v23, v33, v83
	v_fma_f32 v32, v20, v33, v80
	v_fma_f32 v33, v21, v33, v81
	v_fma_f32 v76, v22, v45, v86
	v_fma_f32 v77, v23, v45, v87
	v_fma_f32 v44, v20, v45, v84
	v_fma_f32 v45, v21, v45, v85
	v_fma_f32 v78, v22, v53, v90
	v_fma_f32 v79, v23, v53, v91
	v_fma_f32 v52, v20, v53, v88
	v_fma_f32 v53, v21, v53, v89
	v_fma_f32 v20, v20, v61, v28
	v_fma_f32 v21, v21, v61, v29
	v_fma_f32 v22, v22, v61, v30
	v_fma_f32 v23, v23, v61, v31
	v_fma_f32 v28, v24, v38, v36
	v_fma_f32 v29, v25, v38, v37
	v_fma_f32 v30, v26, v38, v72
	v_fma_f32 v31, v27, v38, v73
	v_fma_f32 v32, v24, v34, v32
	v_fma_f32 v33, v25, v34, v33
	v_fma_f32 v44, v24, v46, v44
	v_fma_f32 v45, v25, v46, v45
	v_fma_f32 v52, v24, v54, v52
	v_fma_f32 v53, v25, v54, v53
	v_fma_f32 v20, v24, v62, v20
	v_fma_f32 v21, v25, v62, v21
	v_mov_b32_e32 v24, v39
	v_fma_f32 v36, v26, v34, v74
	v_fma_f32 v37, v27, v34, v75
	v_fma_f32 v60, v26, v46, v76
	v_fma_f32 v61, v27, v46, v77
	v_fma_f32 v72, v26, v54, v78
	v_fma_f32 v73, v27, v54, v79
	v_fma_f32 v22, v26, v62, v22
	v_fma_f32 v23, v27, v62, v23
	v_fma_f32 v26, v18, v24, v30
	v_fma_f32 v27, v19, v24, v31
	v_fma_f32 v25, v17, v24, v29
	v_fma_f32 v24, v16, v24, v28
	v_mov_b32_e32 v28, v35
	v_fma_f32 v30, v18, v28, v36
	v_fma_f32 v31, v19, v28, v37
	v_fma_f32 v29, v17, v28, v33
	v_fma_f32 v28, v16, v28, v32
	v_mov_b32_e32 v32, v47
	v_fma_f32 v34, v18, v32, v60
	v_fma_f32 v35, v19, v32, v61
	v_fma_f32 v33, v17, v32, v45
	v_fma_f32 v32, v16, v32, v44
	v_mov_b32_e32 v36, v55
	v_mov_b32_e32 v44, v63
	v_fma_f32 v38, v18, v36, v72
	v_fma_f32 v39, v19, v36, v73
	v_fma_f32 v37, v17, v36, v53
	v_fma_f32 v36, v16, v36, v52
	v_fma_f32 v16, v16, v44, v20
	v_fma_f32 v17, v17, v44, v21
	v_fma_f32 v18, v18, v44, v22
	v_fma_f32 v19, v19, v44, v23
	v_fma_f32 v20, v12, v40, v24
	v_fma_f32 v21, v13, v40, v25
	v_fma_f32 v22, v14, v40, v26
	v_fma_f32 v23, v15, v40, v27
	v_fma_f32 v24, v12, v48, v28
	v_fma_f32 v25, v13, v48, v29
	v_fma_f32 v26, v14, v48, v30
	v_fma_f32 v27, v15, v48, v31
	v_fma_f32 v28, v12, v56, v32
	v_fma_f32 v29, v13, v56, v33
	v_fma_f32 v30, v14, v56, v34
	v_fma_f32 v31, v15, v56, v35
	s_waitcnt lgkmcnt(1)
	v_fma_f32 v32, v12, v64, v36
	v_fma_f32 v33, v13, v64, v37
	v_fma_f32 v34, v14, v64, v38
	v_fma_f32 v35, v15, v64, v39
	s_waitcnt lgkmcnt(0)
	v_fma_f32 v12, v12, v68, v16
	v_fma_f32 v13, v13, v68, v17
	v_fma_f32 v14, v14, v68, v18
	v_fma_f32 v15, v15, v68, v19
	v_fma_f32 v16, v10, v41, v22
	v_fma_f32 v17, v11, v41, v23
	v_fma_f32 v18, v8, v41, v20
	v_fma_f32 v19, v9, v41, v21
	v_fma_f32 v20, v10, v49, v26
	v_fma_f32 v21, v11, v49, v27
	v_fma_f32 v22, v8, v49, v24
	v_fma_f32 v23, v9, v49, v25
	v_fma_f32 v24, v10, v57, v30
	v_fma_f32 v25, v11, v57, v31
	v_fma_f32 v26, v8, v57, v28
	v_fma_f32 v27, v9, v57, v29
	v_fma_f32 v28, v10, v65, v34
	v_fma_f32 v29, v11, v65, v35
	v_fma_f32 v30, v8, v65, v32
	v_fma_f32 v31, v9, v65, v33
	v_fma_f32 v8, v8, v69, v12
	v_fma_f32 v9, v9, v69, v13
	v_fma_f32 v10, v10, v69, v14
	v_fma_f32 v11, v11, v69, v15
	v_fma_f32 v12, v4, v42, v18
	v_fma_f32 v13, v5, v42, v19
	v_fma_f32 v14, v6, v42, v16
	v_fma_f32 v15, v7, v42, v17
	v_fma_f32 v16, v4, v50, v22
	v_fma_f32 v17, v5, v50, v23
	v_fma_f32 v18, v6, v50, v20
	v_fma_f32 v19, v7, v50, v21
	v_fma_f32 v20, v4, v58, v26
	v_fma_f32 v21, v5, v58, v27
	v_fma_f32 v22, v6, v58, v24
	v_fma_f32 v23, v7, v58, v25
	v_fma_f32 v24, v4, v66, v30
	v_fma_f32 v25, v5, v66, v31
	v_fma_f32 v26, v6, v66, v28
	v_fma_f32 v27, v7, v66, v29
	v_fma_f32 v28, v4, v70, v8
	v_fma_f32 v29, v5, v70, v9
	v_mov_b32_e32 v4, v43
	v_fma_f32 v30, v6, v70, v10
	v_fma_f32 v31, v7, v70, v11
	v_fma_f32 v6, v2, v4, v14
	v_fma_f32 v7, v3, v4, v15
	v_fma_f32 v5, v1, v4, v13
	v_fma_f32 v4, v0, v4, v12
	v_mov_b32_e32 v8, v51
	v_mov_b32_e32 v12, v59
	v_fma_f32 v10, v2, v8, v18
	v_fma_f32 v11, v3, v8, v19
	v_fma_f32 v9, v1, v8, v17
	v_fma_f32 v8, v0, v8, v16
	v_fma_f32 v14, v2, v12, v22
	v_fma_f32 v15, v3, v12, v23
	v_fma_f32 v13, v1, v12, v21
	v_fma_f32 v12, v0, v12, v20
	v_mov_b32_e32 v16, v67
	v_mov_b32_e32 v20, v71
	v_fma_f32 v18, v2, v16, v26
	v_fma_f32 v19, v3, v16, v27
	v_fma_f32 v17, v1, v16, v25
	v_fma_f32 v16, v0, v16, v24
	v_fma_f32 v2, v2, v20, v30
	v_fma_f32 v3, v3, v20, v31
	v_fma_f32 v0, v0, v20, v28
	v_fma_f32 v1, v1, v20, v29
	ds_write_b128 v172, v[4:7] offset:20480
	ds_write_b128 v172, v[8:11] offset:20736
	ds_write_b128 v172, v[12:15] offset:20992
	ds_write_b128 v172, v[16:19] offset:21248
	ds_write_b128 v172, v[0:3] offset:21504
	s_waitcnt lgkmcnt(0)
	s_barrier
	s_and_saveexec_b64 s[18:19], s[6:7]
	s_cbranch_execz .LBB0_70
	v_mad_u64_u32 v[0:1], s[52:53], s26, 5, v[152:153]
	s_load_dwordx2 s[52:53], s[20:21], 0x50
	s_mulk_i32 s26, 0x1800
	s_add_i32 s26, s26, s16
	v_or_b32_e32 v2, s26, v140
	v_ashrrev_i32_e32 v3, 31, v2
	s_waitcnt lgkmcnt(0)
	v_lshl_add_u64 v[2:3], v[2:3], 2, s[52:53]
	global_load_dword v1, v[2:3], off
	ds_read2st64_b32 v[2:3], v173 offset0:80 offset1:85
	v_mov_b32_e32 v157, v145
	s_waitcnt vmcnt(0) lgkmcnt(0)
	v_add_f32_e32 v1, v1, v2
	v_add_f32_e32 v1, v1, v3
	ds_read2st64_b32 v[2:3], v173 offset0:90 offset1:95
	s_waitcnt lgkmcnt(0)
	v_add_f32_e32 v1, v1, v2
	v_add_f32_e32 v1, v1, v3
	ds_read2st64_b32 v[2:3], v173 offset0:100 offset1:105
	s_waitcnt lgkmcnt(0)
	v_add_f32_e32 v1, v1, v2
	v_add_f32_e32 v1, v1, v3
	ds_read2st64_b32 v[2:3], v173 offset0:110 offset1:115
	s_waitcnt lgkmcnt(0)
	v_add_f32_e32 v1, v1, v2
	v_add_f32_e32 v1, v1, v3
	ds_read2st64_b32 v[2:3], v173 offset0:120 offset1:125
	s_waitcnt lgkmcnt(0)
	v_add_f32_e32 v1, v1, v2
	v_add_f32_e32 v1, v1, v3
	ds_read2st64_b32 v[2:3], v173 offset0:130 offset1:135
	s_waitcnt lgkmcnt(0)
	v_add_f32_e32 v1, v1, v2
	v_add_f32_e32 v1, v1, v3
	ds_read2st64_b32 v[2:3], v173 offset0:140 offset1:145
	s_waitcnt lgkmcnt(0)
	v_add_f32_e32 v1, v1, v2
	v_add_f32_e32 v1, v1, v3
	ds_read2st64_b32 v[2:3], v173 offset0:150 offset1:155
	s_waitcnt lgkmcnt(0)
	v_add_f32_e32 v1, v1, v2
	v_add_f32_e32 v1, v1, v3
	ds_read2st64_b32 v[2:3], v173 offset0:160 offset1:165
	s_waitcnt lgkmcnt(0)
	v_add_f32_e32 v1, v1, v2
	v_add_f32_e32 v1, v1, v3
	ds_read2st64_b32 v[2:3], v173 offset0:170 offset1:175
	s_waitcnt lgkmcnt(0)
	v_add_f32_e32 v1, v1, v2
	v_add_f32_e32 v1, v1, v3
	ds_read2st64_b32 v[2:3], v173 offset0:180 offset1:185
	s_waitcnt lgkmcnt(0)
	v_add_f32_e32 v1, v1, v2
	v_add_f32_e32 v1, v1, v3
	ds_read2st64_b32 v[2:3], v173 offset0:190 offset1:195
	s_waitcnt lgkmcnt(0)
	v_add_f32_e32 v1, v1, v2
	v_add_f32_e32 v1, v1, v3
	ds_read2st64_b32 v[2:3], v173 offset0:200 offset1:205
	s_waitcnt lgkmcnt(0)
	v_add_f32_e32 v1, v1, v2
	v_add_f32_e32 v1, v1, v3
	ds_read2st64_b32 v[2:3], v173 offset0:210 offset1:215
	s_waitcnt lgkmcnt(0)
	v_add_f32_e32 v1, v1, v2
	v_add_f32_e32 v1, v1, v3
	ds_read2st64_b32 v[2:3], v173 offset0:220 offset1:225
	s_waitcnt lgkmcnt(0)
	v_add_f32_e32 v1, v1, v2
	v_add_f32_e32 v1, v1, v3
	ds_read2st64_b32 v[2:3], v173 offset0:230 offset1:235
	s_waitcnt lgkmcnt(0)
	v_add_f32_e32 v1, v1, v2
	v_add_f32_e32 v4, v1, v3
	v_mov_b64_e32 v[2:3], s[22:23]
	v_mad_i64_i32 v[0:1], s[52:53], v0, s39, v[2:3]
	v_lshl_add_u64 v[0:1], s[16:17], 2, v[0:1]
	v_lshl_add_u64 v[0:1], v[0:1], 0, v[156:157]
	flat_store_dword v[0:1], v4

.LBB0_183:
	s_and_b64 vcc, exec, s[8:9]
	s_cbranch_vccnz .LBB0_158
	v_lshrrev_b32_e32 v64, 11, v109
	v_add_u32_e32 v64, 1, v64
	v_cmp_lt_i32_e32 vcc, s38, v106
	v_mov_b32_e32 v109, v97
	v_mov_b32_e32 v111, v97
	v_cndmask_b32_e32 v66, 0, v64, vcc
	v_mov_b64_e32 v[64:65], s[26:27]
	v_mad_u64_u32 v[64:65], s[8:9], v66, s39, v[64:65]
	v_lshl_add_u64 v[66:67], v[64:65], 0, s[30:31]
	v_lshl_add_u64 v[68:69], v[66:67], 0, v[96:97]
	flat_load_dwordx4 v[80:83], v[68:69]
	v_lshl_add_u64 v[68:69], v[66:67], 0, v[108:109]
	v_mov_b32_e32 v113, v97
	flat_load_dwordx4 v[84:87], v[68:69]
	v_lshl_add_u64 v[68:69], v[66:67], 0, v[110:111]
	v_lshl_add_u64 v[66:67], v[66:67], 0, v[112:113]
	flat_load_dwordx4 v[88:91], v[68:69]
	flat_load_dwordx4 v[92:95], v[66:67]
	global_load_dwordx4 v[114:117], v[100:101], off
	global_load_dwordx4 v[120:123], v[100:101], off offset:16
	global_load_dwordx4 v[124:127], v[100:101], off offset:2048
	global_load_dwordx4 v[128:131], v[100:101], off offset:2064
	v_lshl_add_u64 v[64:65], v[64:65], 0, v[96:97]
	flat_load_dwordx4 v[76:79], v[64:65]
	flat_load_dwordx4 v[72:75], v[64:65] offset:16
	flat_load_dwordx4 v[68:71], v[64:65] offset:2048
	v_mul_f32_e32 v107, v1, v1
	flat_load_dwordx4 v[64:67], v[64:65] offset:2064
	v_mul_f32_e32 v109, v5, v5
	v_mul_f32_e32 v119, v33, v33
	v_mul_f32_e32 v132, v37, v37
	v_mul_f32_e32 v111, v9, v9
	v_mul_f32_e32 v133, v41, v41
	v_fmac_f32_e32 v107, v0, v0
	v_fmac_f32_e32 v109, v4, v4
	v_fmac_f32_e32 v119, v32, v32
	v_fmac_f32_e32 v132, v36, v36
	v_mul_f32_e32 v113, v13, v13
	v_mul_f32_e32 v134, v45, v45
	v_fmac_f32_e32 v111, v8, v8
	v_fmac_f32_e32 v133, v40, v40
	v_fmac_f32_e32 v107, v2, v2
	v_fmac_f32_e32 v109, v6, v6
	v_fmac_f32_e32 v119, v34, v34
	v_fmac_f32_e32 v132, v38, v38
	v_fmac_f32_e32 v113, v12, v12
	v_fmac_f32_e32 v111, v10, v10
	v_fmac_f32_e32 v133, v42, v42
	v_fmac_f32_e32 v107, v3, v3
	v_fmac_f32_e32 v109, v7, v7
	v_fmac_f32_e32 v119, v35, v35
	v_fmac_f32_e32 v132, v39, v39
	v_fmac_f32_e32 v134, v44, v44
	v_fmac_f32_e32 v113, v14, v14
	v_fmac_f32_e32 v111, v11, v11
	v_fmac_f32_e32 v133, v43, v43
	v_add_f32_e32 v107, v109, v107
	v_add_f32_e32 v109, v119, v132
	v_fmac_f32_e32 v134, v46, v46
	v_fmac_f32_e32 v113, v15, v15
	v_add_f32_e32 v107, v111, v107
	v_add_f32_e32 v109, v109, v133
	v_fmac_f32_e32 v134, v47, v47
	v_add_f32_e32 v107, v113, v107
	s_waitcnt vmcnt(0) lgkmcnt(0)
	v_add_f32 v80, v80, 1.0
	v_add_f32 v81, v81, 1.0
	v_add_f32_dpp v107, v107, v107 quad_perm:[1,0,3,2] row_mask:0xf bank_mask:0xf bound_ctrl:1
	v_add_f32 v82, v82, 1.0
	v_add_f32 v83, v83, 1.0
	v_add_f32 v94, v94, 1.0
	v_add_f32 v95, v95, 1.0
	v_add_f32_dpp v107, v107, v107 quad_perm:[2,3,0,1] row_mask:0xf bank_mask:0xf bound_ctrl:1
	v_add_f32 v84, v84, 1.0
	v_add_f32 v85, v85, 1.0
	v_add_f32 v136, v90, 1.0
	v_add_f32 v137, v91, 1.0
	v_mul_f32 v90, v114, v80
	v_mul_f32 v91, v115, v81
	v_mul_f32 v80, v130, v94
	v_mul_f32 v81, v131, v95
	v_add_f32_e32 v94, v109, v134
	v_add_f32_dpp v107, v107, v107 row_half_mirror row_mask:0xf bank_mask:0xf bound_ctrl:1
	v_mov_b64_e32 v[114:115], s[36:37]
	v_add_f32_dpp v94, v94, v94 quad_perm:[1,0,3,2] row_mask:0xf bank_mask:0xf bound_ctrl:1
	v_add_f32_dpp v107, v107, v107 row_mirror row_mask:0xf bank_mask:0xf bound_ctrl:1
	v_mov_b32_e32 v111, v107
	v_add_f32_dpp v94, v94, v94 quad_perm:[2,3,0,1] row_mask:0xf bank_mask:0xf bound_ctrl:1
	s_nop 0
	v_permlane16_swap_b32_e32 v107, v111
	v_add_f32_dpp v94, v94, v94 row_half_mirror row_mask:0xf bank_mask:0xf bound_ctrl:1
	v_add_f32_e32 v133, v107, v111
	v_mov_b32_e32 v135, v133
	v_add_f32_dpp v94, v94, v94 row_mirror row_mask:0xf bank_mask:0xf bound_ctrl:1
	v_mov_b32_e32 v95, v94
	s_nop 1
	v_permlane16_swap_b32_e32 v94, v95
	v_add_f32_e32 v132, v94, v95
	v_mov_b32_e32 v134, v132
	v_permlane32_swap_b32_e32 v133, v135
	s_nop 0
	v_permlane32_swap_b32_e32 v132, v134
	v_add_f32 v94, v132, v134
	v_add_f32 v95, v133, v135
	v_add_f32 v138, v88, 1.0
	v_add_f32 v139, v89, 1.0
	v_mul_f32 v88, v116, v82
	v_mul_f32 v89, v117, v83
	v_fma_f32 v116, v94, s34, v114
	v_fma_f32 v117, v95, s34, v114
	v_add_f32 v86, v86, 1.0
	v_add_f32 v87, v87, 1.0
	v_mul_f32_e32 v94, 0x4b800000, v117
	v_cmp_gt_f32_e32 vcc, s42, v117
	v_add_f32 v140, v92, 1.0
	v_add_f32 v141, v93, 1.0
	v_mul_f32 v92, v120, v84
	v_mul_f32 v93, v121, v85
	v_cndmask_b32_e32 v94, v117, v94, vcc
	v_rsq_f32_e32 v107, v94
	v_mul_f32 v86, v122, v86
	v_mul_f32 v87, v123, v87
	v_add_u32_e32 v109, 0xffffe400, v99
	v_mul_f32 v82, v126, v136
	v_mul_f32 v83, v127, v137
	v_mul_f32_e32 v113, 0x45800000, v107
	v_cndmask_b32_e32 v120, v107, v113, vcc
	v_mul_f32 v0, v0, v120
	v_mul_f32 v1, v1, v120
	v_mul_f32 v4, v4, v120
	v_mul_f32 v5, v5, v120
	v_mul_f32 v2, v2, v120
	v_mul_f32 v3, v3, v120
	v_mul_f32 v6, v6, v120
	v_mul_f32 v7, v7, v120
	v_fma_f32 v0, v90, v0, v76
	v_fma_f32 v1, v91, v1, v77
	v_fma_f32 v4, v92, v4, v72
	v_fma_f32 v5, v93, v5, v73
	v_fma_f32 v2, v88, v2, v78
	v_fma_f32 v3, v89, v3, v79
	v_fma_f32 v6, v86, v6, v74
	v_fma_f32 v7, v87, v7, v75
	v_cvt_pk_bf16_f32 v0, v0, v1
	v_cvt_pk_bf16_f32 v1, v2, v3
	v_cvt_pk_bf16_f32 v2, v4, v5
	v_cvt_pk_bf16_f32 v3, v6, v7
	v_mul_f32 v84, v124, v138
	v_mul_f32 v85, v125, v139
	buffer_store_dwordx4 v[0:3], v109, s[16:19], 0 offen sc1
	v_mul_f32 v4, v10, v120
	v_mul_f32 v5, v11, v120
	v_cmp_gt_f32_e32 vcc, s42, v116
	v_mul_f32 v0, v8, v120
	v_mul_f32 v1, v9, v120
	v_fma_f32 v4, v82, v4, v70
	v_fma_f32 v5, v83, v5, v71
	v_fma_f32 v0, v84, v0, v68
	v_fma_f32 v1, v85, v1, v69
	v_mul_f32 v94, v128, v140
	v_mul_f32 v95, v129, v141
	v_cvt_pk_bf16_f32 v0, v0, v1
	v_cvt_pk_bf16_f32 v1, v4, v5
	v_mul_f32_e32 v4, 0x4b800000, v116
	v_cndmask_b32_e32 v4, v116, v4, vcc
	v_rsq_f32_e32 v4, v4
	v_mul_f32 v2, v12, v120
	v_mul_f32 v3, v13, v120
	v_mul_f32 v6, v14, v120
	v_mul_f32 v7, v15, v120
	v_fma_f32 v2, v94, v2, v64
	v_fma_f32 v3, v95, v3, v65
	v_fma_f32 v6, v80, v6, v66
	v_fma_f32 v7, v81, v7, v67
	v_add_u32_e32 v111, 0xffffe800, v99
	v_cvt_pk_bf16_f32 v2, v2, v3
	v_cvt_pk_bf16_f32 v3, v6, v7
	buffer_store_dwordx4 v[0:3], v111, s[16:19], 0 offen sc1
	v_add_u32_e32 v12, 0xfffff800, v99
	s_nop 0
	v_mul_f32_e32 v0, 0x45800000, v4
	v_cndmask_b32_e32 v4, v4, v0, vcc
	v_mul_f32 v0, v32, v4
	v_mul_f32 v1, v33, v4
	v_mul_f32 v2, v36, v4
	v_mul_f32 v3, v37, v4
	v_mul_f32 v6, v34, v4
	v_mul_f32 v7, v35, v4
	v_mul_f32 v8, v38, v4
	v_mul_f32 v9, v39, v4
	v_fma_f32 v0, v90, v0, v76
	v_fma_f32 v1, v91, v1, v77
	v_fma_f32 v2, v92, v2, v72
	v_fma_f32 v3, v93, v3, v73
	v_fma_f32 v6, v88, v6, v78
	v_fma_f32 v7, v89, v7, v79
	v_fma_f32 v8, v86, v8, v74
	v_fma_f32 v9, v87, v9, v75
	v_cvt_pk_bf16_f32 v0, v0, v1
	v_cvt_pk_bf16_f32 v1, v6, v7
	v_cvt_pk_bf16_f32 v2, v2, v3
	v_cvt_pk_bf16_f32 v3, v8, v9
	v_add_u32_e32 v5, 0xffffec00, v99
	buffer_store_dwordx4 v[0:3], v5, s[16:19], 0 offen sc1
	v_mul_f32 v6, v42, v4
	v_mul_f32 v7, v43, v4
	v_add_u32_e32 v8, 0xfffff000, v99
	v_mul_f32 v0, v40, v4
	v_mul_f32 v1, v41, v4
	v_mul_f32 v2, v44, v4
	v_mul_f32 v3, v45, v4
	v_mul_f32 v5, v47, v4
	v_mul_f32 v4, v46, v4
	v_fma_f32 v2, v94, v2, v64
	v_fma_f32 v3, v95, v3, v65
	v_fma_f32 v4, v80, v4, v66
	v_fma_f32 v5, v81, v5, v67
	v_cvt_pk_bf16_f32 v2, v2, v3
	v_cvt_pk_bf16_f32 v3, v4, v5
	v_mul_f32_e32 v4, v17, v17
	v_mul_f32_e32 v5, v21, v21
	v_fmac_f32_e32 v4, v16, v16
	v_fmac_f32_e32 v5, v20, v20
	v_fmac_f32_e32 v4, v18, v18
	v_fmac_f32_e32 v5, v22, v22
	v_fmac_f32_e32 v4, v19, v19
	v_fmac_f32_e32 v5, v23, v23
	v_add_f32_e32 v4, v4, v5
	v_mul_f32_e32 v5, v25, v25
	v_fmac_f32_e32 v5, v24, v24
	v_fmac_f32_e32 v5, v26, v26
	v_fmac_f32_e32 v5, v27, v27
	v_add_f32_e32 v4, v4, v5
	v_mul_f32_e32 v5, v29, v29
	v_fmac_f32_e32 v5, v28, v28
	v_fmac_f32_e32 v5, v30, v30
	v_fmac_f32_e32 v5, v31, v31
	v_add_f32_e32 v4, v4, v5
	v_fma_f32 v0, v84, v0, v68
	v_fma_f32 v1, v85, v1, v69
	v_fma_f32 v6, v82, v6, v70
	v_fma_f32 v7, v83, v7, v71
	v_add_f32_dpp v4, v4, v4 quad_perm:[1,0,3,2] row_mask:0xf bank_mask:0xf bound_ctrl:1
	v_cvt_pk_bf16_f32 v0, v0, v1
	v_cvt_pk_bf16_f32 v1, v6, v7
	v_add_f32_dpp v4, v4, v4 quad_perm:[2,3,0,1] row_mask:0xf bank_mask:0xf bound_ctrl:1
	v_mul_f32_e32 v6, v53, v53
	v_fmac_f32_e32 v6, v52, v52
	v_add_f32_dpp v4, v4, v4 row_half_mirror row_mask:0xf bank_mask:0xf bound_ctrl:1
	v_fmac_f32_e32 v6, v54, v54
	v_fmac_f32_e32 v6, v55, v55
	v_add_f32_dpp v4, v4, v4 row_mirror row_mask:0xf bank_mask:0xf bound_ctrl:1
	v_mov_b32_e32 v5, v4
	s_nop 1
	v_permlane16_swap_b32_e32 v4, v5
	v_add_f32_e32 v5, v4, v5
	v_mul_f32_e32 v4, v49, v49
	v_fmac_f32_e32 v4, v48, v48
	v_fmac_f32_e32 v4, v50, v50
	v_fmac_f32_e32 v4, v51, v51
	v_add_f32_e32 v4, v4, v6
	v_mul_f32_e32 v6, v57, v57
	v_fmac_f32_e32 v6, v56, v56
	v_fmac_f32_e32 v6, v58, v58
	v_fmac_f32_e32 v6, v59, v59
	v_add_f32_e32 v4, v4, v6
	v_mul_f32_e32 v6, v61, v61
	v_fmac_f32_e32 v6, v60, v60
	v_fmac_f32_e32 v6, v62, v62
	v_fmac_f32_e32 v6, v63, v63
	v_add_f32_e32 v4, v4, v6
	v_mov_b32_e32 v7, v5
	s_nop 1
	v_permlane32_swap_b32_e32 v5, v7
	v_add_f32_dpp v4, v4, v4 quad_perm:[1,0,3,2] row_mask:0xf bank_mask:0xf bound_ctrl:1
	buffer_store_dwordx4 v[0:3], v8, s[16:19], 0 offen sc1
	s_nop 0
	v_add_f32_dpp v4, v4, v4 quad_perm:[2,3,0,1] row_mask:0xf bank_mask:0xf bound_ctrl:1
	s_nop 1
	v_add_f32_dpp v4, v4, v4 row_half_mirror row_mask:0xf bank_mask:0xf bound_ctrl:1
	s_nop 1
	v_add_f32_dpp v4, v4, v4 row_mirror row_mask:0xf bank_mask:0xf bound_ctrl:1
	v_mov_b32_e32 v6, v4
	s_nop 1
	v_permlane16_swap_b32_e32 v4, v6
	v_add_f32_e32 v4, v4, v6
	v_mov_b32_e32 v6, v4
	s_nop 1
	v_permlane32_swap_b32_e32 v4, v6
	v_add_f32 v4, v4, v6
	v_add_f32 v5, v5, v7
	v_add_u32_e32 v7, 0xfffff400, v99
	v_fma_f32 v4, v4, s34, v114
	v_fma_f32 v5, v5, s34, v114
	s_nop 0
	v_mul_f32_e32 v6, 0x4b800000, v5
	v_cmp_gt_f32_e32 vcc, s42, v5
	s_nop 1
	v_cndmask_b32_e32 v5, v5, v6, vcc
	v_rsq_f32_e32 v5, v5
	s_nop 0
	v_mul_f32_e32 v0, 0x45800000, v5
	v_cndmask_b32_e32 v6, v5, v0, vcc
	v_mul_f32 v0, v16, v6
	v_mul_f32 v1, v17, v6
	v_mul_f32 v2, v20, v6
	v_mul_f32 v3, v21, v6
	v_mul_f32 v8, v18, v6
	v_mul_f32 v9, v19, v6
	v_mul_f32 v10, v22, v6
	v_mul_f32 v11, v23, v6
	v_mul_f32_e32 v5, 0x4b800000, v4
	v_cmp_gt_f32_e32 vcc, s42, v4
	v_fma_f32 v0, v90, v0, v76
	v_fma_f32 v1, v91, v1, v77
	v_fma_f32 v2, v92, v2, v72
	v_fma_f32 v3, v93, v3, v73
	v_fma_f32 v8, v88, v8, v78
	v_fma_f32 v9, v89, v9, v79
	v_fma_f32 v10, v86, v10, v74
	v_fma_f32 v11, v87, v11, v75
	v_cndmask_b32_e32 v4, v4, v5, vcc
	v_cvt_pk_bf16_f32 v0, v0, v1
	v_cvt_pk_bf16_f32 v1, v8, v9
	v_cvt_pk_bf16_f32 v2, v2, v3
	v_cvt_pk_bf16_f32 v3, v10, v11
	v_rsq_f32_e32 v4, v4
	buffer_store_dwordx4 v[0:3], v7, s[16:19], 0 offen sc1
	v_mul_f32 v8, v26, v6
	v_mul_f32 v9, v27, v6
	s_nop 0
	v_mul_f32 v0, v24, v6
	v_mul_f32 v1, v25, v6
	v_mul_f32 v2, v28, v6
	v_mul_f32 v3, v29, v6
	v_mul_f32 v7, v31, v6
	v_mul_f32 v6, v30, v6
	v_fma_f32 v0, v84, v0, v68
	v_fma_f32 v1, v85, v1, v69
	v_fma_f32 v2, v94, v2, v64
	v_fma_f32 v3, v95, v3, v65
	v_fma_f32 v8, v82, v8, v70
	v_fma_f32 v9, v83, v9, v71
	v_fma_f32 v6, v80, v6, v66
	v_fma_f32 v7, v81, v7, v67
	v_cvt_pk_bf16_f32 v0, v0, v1
	v_cvt_pk_bf16_f32 v1, v8, v9
	v_cvt_pk_bf16_f32 v2, v2, v3
	v_cvt_pk_bf16_f32 v3, v6, v7
	buffer_store_dwordx4 v[0:3], v12, s[16:19], 0 offen sc1
	s_nop 1
	v_mul_f32_e32 v0, 0x45800000, v4
	v_cndmask_b32_e32 v4, v4, v0, vcc
	v_mul_f32 v0, v48, v4
	v_mul_f32 v1, v49, v4
	v_mul_f32 v2, v52, v4
	v_mul_f32 v3, v53, v4
	v_mul_f32 v6, v50, v4
	v_mul_f32 v7, v51, v4
	v_mul_f32 v8, v54, v4
	v_mul_f32 v9, v55, v4
	v_fma_f32 v0, v90, v0, v76
	v_fma_f32 v1, v91, v1, v77
	v_fma_f32 v2, v92, v2, v72
	v_fma_f32 v3, v93, v3, v73
	v_fma_f32 v6, v88, v6, v78
	v_fma_f32 v7, v89, v7, v79
	v_fma_f32 v8, v86, v8, v74
	v_fma_f32 v9, v87, v9, v75
	v_cvt_pk_bf16_f32 v0, v0, v1
	v_cvt_pk_bf16_f32 v1, v6, v7
	v_cvt_pk_bf16_f32 v2, v2, v3
	v_cvt_pk_bf16_f32 v3, v8, v9
	v_add_u32_e32 v5, 0xfffffc00, v99
	buffer_store_dwordx4 v[0:3], v5, s[16:19], 0 offen sc1
	v_mul_f32 v6, v58, v4
	v_mul_f32 v7, v59, v4
	s_nop 0
	v_mul_f32 v0, v56, v4
	v_mul_f32 v1, v57, v4
	v_mul_f32 v2, v60, v4
	v_mul_f32 v3, v61, v4
	v_mul_f32 v5, v63, v4
	v_mul_f32 v4, v62, v4
	v_fma_f32 v0, v84, v0, v68
	v_fma_f32 v1, v85, v1, v69
	v_fma_f32 v2, v94, v2, v64
	v_fma_f32 v3, v95, v3, v65
	v_fma_f32 v6, v82, v6, v70
	v_fma_f32 v7, v83, v7, v71
	v_fma_f32 v4, v80, v4, v66
	v_fma_f32 v5, v81, v5, v67
	v_cvt_pk_bf16_f32 v0, v0, v1
	v_cvt_pk_bf16_f32 v1, v6, v7
	v_cvt_pk_bf16_f32 v2, v2, v3
	v_cvt_pk_bf16_f32 v3, v4, v5
	buffer_store_dwordx4 v[0:3], v99, s[16:19], 0 offen sc1
	s_waitcnt vmcnt(0)
	s_and_saveexec_b64 s[8:9], s[4:5]
	s_cbranch_execz .LBB0_157
	v_ashrrev_i32_e32 v0, 2, v106
	v_and_b32_e32 v0, 0xffffffc0, v0
	v_ashrrev_i32_e32 v1, 31, v0
	v_lshl_add_u64 v[0:1], v[0:1], 2, s[24:25]
	flat_atomic_add v[0:1], v118
	s_branch .LBB0_157

.LBB0_473:
	s_or_b64 exec, exec, s[4:5]
	s_waitcnt lgkmcnt(0)
	v_lshl_add_u64 v[40:41], v[38:39], 2, s[10:11]
	global_load_dwordx4 v[46:49], v[40:41], off
	global_load_dwordx4 v[52:55], v[40:41], off offset:3072
	v_add_co_u32_e32 v38, vcc, s31, v40
	s_waitcnt vmcnt(0)
	v_lshlrev_b32_e32 v68, 16, v20
	v_addc_co_u32_e32 v39, vcc, 0, v41, vcc
	global_load_dwordx4 v[56:59], v[38:39], off offset:2048
	global_load_dwordx4 v[60:63], v[40:41], off offset:16
	global_load_dwordx4 v[64:67], v[40:41], off offset:3088
	v_and_b32_e32 v69, 0xffff0000, v20
	v_lshlrev_b32_e32 v70, 16, v21
	v_and_b32_e32 v71, 0xffff0000, v21
	v_lshl_add_u64 v[20:21], v[40:41], 0, s[18:19]
	v_mad_u64_u32 v[38:39], s[4:5], v32, s33, v[24:25]
	v_lshlrev_b32_e32 v72, 16, v22
	v_and_b32_e32 v73, 0xffff0000, v22
	v_lshlrev_b32_e32 v24, 16, v23
	v_and_b32_e32 v74, 0xffff0000, v23
	global_load_dwordx4 v[20:23], v[20:21], off offset:16
	v_lshlrev_b32_e32 v76, 16, v16
	v_and_b32_e32 v77, 0xffff0000, v16
	v_lshlrev_b32_e32 v16, 16, v17
	v_and_b32_e32 v17, 0xffff0000, v17
	v_lshlrev_b32_e32 v40, 16, v12
	v_and_b32_e32 v41, 0xffff0000, v12
	v_lshlrev_b32_e32 v12, 16, v13
	v_and_b32_e32 v13, 0xffff0000, v13
	v_and_b32_e32 v75, 0xffff0000, v15
	v_lshlrev_b32_e32 v80, 16, v14
	v_and_b32_e32 v81, 0xffff0000, v14
	v_lshlrev_b32_e32 v78, 16, v18
	v_and_b32_e32 v79, 0xffff0000, v18
	v_lshlrev_b32_e32 v18, 16, v19
	v_and_b32_e32 v19, 0xffff0000, v19
	v_mul_f32 v52, v52, v76
	v_mul_f32 v53, v53, v77
	v_mul_f32 v16, v54, v16
	v_mul_f32 v17, v55, v17
	v_fma_f32 v46, v46, v68, v52
	v_fma_f32 v47, v47, v69, v53
	v_fma_f32 v16, v48, v70, v16
	v_fma_f32 v17, v49, v71, v17
	s_waitcnt vmcnt(3)
	v_fma_f32 v40, v56, v40, v46
	v_fma_f32 v41, v57, v41, v47
	v_fma_f32 v16, v58, v12, v16
	v_fma_f32 v17, v59, v13, v17
	v_mul_f32_e32 v12, 0xbfb8aa3b, v40
	v_mul_f32_e32 v13, 0xbfb8aa3b, v41
	v_exp_f32_e32 v12, v12
	v_exp_f32_e32 v13, v13
	v_mul_f32_e32 v31, 0xbfb8aa3b, v16
	v_mul_f32_e32 v33, 0xbfb8aa3b, v17
	v_exp_f32_e32 v46, v31
	v_exp_f32_e32 v47, v33
	v_add_f32 v12, v12, 1.0
	v_add_f32 v13, v13, 1.0
	v_lshlrev_b32_e32 v31, 16, v15
	v_div_scale_f32 v33, s[4:5], v13, v13, v41
	v_add_f32 v14, v46, 1.0
	v_add_f32 v15, v47, 1.0
	v_div_scale_f32 v46, s[4:5], v12, v12, v40
	v_rcp_f32_e32 v53, v33
	v_div_scale_f32 v48, s[6:7], v15, v15, v17
	v_rcp_f32_e32 v54, v46
	v_rcp_f32_e32 v55, v48
	v_fma_f32 v57, -v33, v53, 1.0
	v_div_scale_f32 v39, vcc, v41, v13, v41
	v_fma_f32 v58, -v46, v54, 1.0
	v_fmac_f32_e32 v53, v57, v53
	v_div_scale_f32 v47, s[4:5], v40, v12, v40
	v_fma_f32 v59, -v48, v55, 1.0
	v_fmac_f32_e32 v54, v58, v54
	v_mul_f32_e32 v57, v39, v53
	v_div_scale_f32 v49, s[6:7], v17, v15, v17
	v_fmac_f32_e32 v55, v59, v55
	v_mul_f32_e32 v58, v47, v54
	v_fma_f32 v69, -v33, v57, v39
	v_mul_f32_e32 v59, v49, v55
	v_fma_f32 v70, -v46, v58, v47
	v_fmac_f32_e32 v57, v69, v53
	v_fma_f32 v71, -v48, v59, v49
	v_fmac_f32_e32 v58, v70, v54
	v_fma_f32 v33, -v33, v57, v39
	v_fmac_f32_e32 v59, v71, v55
	v_fma_f32 v39, -v46, v58, v47
	v_div_fmas_f32 v33, v33, v53, v57
	s_mov_b64 vcc, s[4:5]
	v_fma_f32 v46, -v48, v59, v49
	v_div_fixup_f32 v13, v33, v13, v41
	v_div_fmas_f32 v33, v39, v54, v58
	s_mov_b64 vcc, s[6:7]
	v_div_fixup_f32 v12, v33, v12, v40
	v_div_fmas_f32 v33, v46, v55, v59
	s_waitcnt vmcnt(1)
	v_mul_f32 v46, v64, v78
	v_mul_f32 v47, v65, v79
	v_div_scale_f32 v51, s[8:9], v14, v14, v16
	v_fma_f32 v46, v60, v72, v46
	v_fma_f32 v47, v61, v73, v47
	v_div_fixup_f32 v15, v33, v15, v17
	s_waitcnt vmcnt(0)
	v_fma_f32 v20, v20, v80, v46
	v_fma_f32 v21, v21, v81, v47
	v_rcp_f32_e32 v56, v51
	v_mul_f32_e32 v17, 0xbfb8aa3b, v20
	v_exp_f32_e32 v46, v17
	v_mul_f32_e32 v17, 0xbfb8aa3b, v21
	v_exp_f32_e32 v47, v17
	v_fma_f32 v68, -v51, v56, 1.0
	v_div_scale_f32 v52, s[8:9], v16, v14, v16
	v_fmac_f32_e32 v56, v68, v56
	v_add_f32 v46, v46, 1.0
	v_add_f32 v47, v47, 1.0
	v_mul_f32_e32 v68, v52, v56
	v_div_scale_f32 v33, s[4:5], v47, v47, v21
	v_fma_f32 v17, -v51, v68, v52
	v_rcp_f32_e32 v39, v33
	v_fmac_f32_e32 v68, v17, v56
	v_fma_f32 v17, -v51, v68, v52
	s_mov_b64 vcc, s[8:9]
	v_div_fmas_f32 v17, v17, v56, v68
	v_div_fixup_f32 v14, v17, v14, v16
	v_fma_f32 v16, -v33, v39, 1.0
	v_fmac_f32_e32 v39, v16, v39
	v_div_scale_f32 v16, vcc, v21, v47, v21
	v_mul_f32_e32 v17, v16, v39
	v_fma_f32 v51, -v33, v17, v16
	v_mul_f32_e32 v54, v22, v31
	v_mov_b32_e32 v22, v63
	v_fmac_f32_e32 v17, v51, v39
	v_mul_f32 v22, v22, v74
	v_mul_f32 v23, v23, v75
	v_fma_f32 v16, -v33, v17, v16
	v_div_scale_f32 v33, s[4:5], v46, v46, v20
	v_mul_f32_e32 v52, v62, v24
	v_mov_b32_e32 v53, v22
	v_rcp_f32_e32 v51, v33
	v_fma_f32 v18, v66, v18, v52
	v_fma_f32 v19, v67, v19, v53
	v_mov_b32_e32 v55, v23
	v_add_f32 v18, v18, v54
	v_add_f32 v19, v19, v55
	v_div_fmas_f32 v16, v16, v39, v17
	v_mul_f32_e32 v22, 0xbfb8aa3b, v18
	v_mul_f32_e32 v23, 0xbfb8aa3b, v19
	v_exp_f32_e32 v22, v22
	v_exp_f32_e32 v23, v23
	v_div_fixup_f32 v17, v16, v47, v21
	v_fma_f32 v16, -v33, v51, 1.0
	v_fmac_f32_e32 v51, v16, v51
	v_div_scale_f32 v16, vcc, v20, v46, v20
	v_mul_f32_e32 v21, v16, v51
	v_fma_f32 v24, -v33, v21, v16
	v_add_f32 v22, v22, 1.0
	v_add_f32 v23, v23, 1.0
	v_fmac_f32_e32 v21, v24, v51
	v_div_scale_f32 v24, s[4:5], v23, v23, v19
	v_rcp_f32_e32 v31, v24
	v_fma_f32 v16, -v33, v21, v16
	v_div_fmas_f32 v16, v16, v51, v21
	v_div_fixup_f32 v16, v16, v46, v20
	v_fma_f32 v33, -v24, v31, 1.0
	v_fmac_f32_e32 v31, v33, v31
	v_div_scale_f32 v33, vcc, v19, v23, v19
	v_mul_f32_e32 v39, v33, v31
	v_fma_f32 v46, -v24, v39, v33
	v_fmac_f32_e32 v39, v46, v31
	v_fma_f32 v24, -v24, v39, v33
	v_div_scale_f32 v33, s[4:5], v22, v22, v18
	v_rcp_f32_e32 v46, v33
	v_div_fmas_f32 v24, v24, v31, v39
	v_div_fixup_f32 v19, v24, v23, v19
	v_mul_f32 v40, v12, v12
	v_mul_f32 v41, v13, v13
	v_fma_f32 v23, -v33, v46, 1.0
	v_fmac_f32_e32 v46, v23, v46
	v_div_scale_f32 v23, vcc, v18, v22, v18
	v_mul_f32_e32 v24, v23, v46
	v_fma_f32 v31, -v33, v24, v23
	v_fmac_f32_e32 v24, v31, v46
	v_fma_f32 v23, -v33, v24, v23
	v_mul_f32 v48, v14, v14
	v_mul_f32 v49, v15, v15
	v_div_fmas_f32 v23, v23, v46, v24
	v_add_f32_e32 v24, v40, v41
	v_add_f32_e32 v24, v24, v48
	v_mul_f32 v20, v16, v16
	v_mul_f32 v21, v17, v17
	v_add_f32_e32 v24, v24, v49
	v_div_fixup_f32 v18, v23, v22, v18
	v_add_f32_e32 v20, v24, v20
	v_mul_f32 v22, v18, v18
	v_mul_f32 v23, v19, v19
	v_add_f32_e32 v20, v20, v21
	v_add_f32_e32 v20, v20, v22
	v_add_f32_e32 v20, v20, v23
	v_cmp_gt_i32_e32 vcc, 64, v38
	s_nop 0
	v_add_f32_dpp v20, v20, v20 quad_perm:[1,0,3,2] row_mask:0xf bank_mask:0xf bound_ctrl:1
	s_nop 1
	v_add_f32_dpp v20, v20, v20 quad_perm:[2,3,0,1] row_mask:0xf bank_mask:0xf bound_ctrl:1
	s_nop 1
	v_mov_b32_dpp v21, v20 row_half_mirror row_mask:0xf bank_mask:0xf bound_ctrl:1
	s_and_saveexec_b64 s[6:7], vcc
	s_cbranch_execz .LBB0_475
	v_add_f32_e32 v20, v20, v21
	v_add_f32_e32 v20, 0x358637bd, v20
	v_mul_f32_e32 v21, 0x4b800000, v20
	v_cmp_gt_f32_e32 vcc, s34, v20
	v_cmp_gt_i32_e64 s[4:5], 32, v38
	s_nop 0
	v_cndmask_b32_e32 v20, v20, v21, vcc
	v_rsq_f32_e32 v20, v20
	v_cndmask_b32_e64 v21, 1.0, v43, s[4:5]
	v_mul_f32_e32 v22, 0x45800000, v20
	v_cndmask_b32_e32 v20, v20, v22, vcc
	v_mul_f32_e32 v20, v21, v20
	v_mul_f32 v18, v18, v20
	v_mul_f32 v19, v19, v20
	v_mul_f32 v16, v16, v20
	v_mul_f32 v17, v17, v20
	v_mul_f32 v14, v14, v20
	v_mul_f32 v15, v15, v20
	v_mul_f32 v12, v12, v20
	v_mul_f32 v13, v13, v20
.LBB0_475:
	s_or_b64 exec, exec, s[6:7]
	v_ashrrev_i32_e32 v33, 31, v32
	v_ashrrev_i32_e32 v22, 5, v38
	v_mov_b64_e32 v[20:21], s[12:13]
	v_mad_i64_i32 v[20:21], s[4:5], v22, s35, v[20:21]
	v_lshlrev_b64 v[22:23], 9, v[32:33]
	v_lshl_add_u64 v[20:21], v[20:21], 0, v[22:23]
	v_lshlrev_b32_e32 v24, 1, v26
	v_lshl_add_u64 v[20:21], v[20:21], 0, v[24:25]
	v_cvt_pk_bf16_f32 v12, v12, v13
	v_cvt_pk_bf16_f32 v13, v14, v15
	v_cvt_pk_bf16_f32 v14, v16, v17
	v_cvt_pk_bf16_f32 v15, v18, v19
	flat_store_dwordx4 v[20:21], v[12:15]
	v_lshl_add_u64 v[22:23], v[36:37], 2, s[10:11]
	global_load_dwordx4 v[14:17], v[22:23], off
	global_load_dwordx4 v[18:21], v[22:23], off offset:3072
	v_add_co_u32_e32 v12, vcc, s31, v22
	v_lshlrev_b32_e32 v32, 16, v8
	s_nop 0
	v_addc_co_u32_e32 v13, vcc, 0, v23, vcc
	global_load_dwordx4 v[36:39], v[12:13], off offset:2048
	global_load_dwordx4 v[46:49], v[22:23], off offset:16
	global_load_dwordx4 v[52:55], v[22:23], off offset:3088
	v_mad_u64_u32 v[12:13], s[4:5], v30, s33, v[34:35]
	v_and_b32_e32 v33, 0xffff0000, v8
	v_lshlrev_b32_e32 v40, 16, v9
	v_and_b32_e32 v41, 0xffff0000, v9
	v_lshl_add_u64 v[8:9], v[22:23], 0, s[18:19]
	v_lshlrev_b32_e32 v56, 16, v10
	v_and_b32_e32 v57, 0xffff0000, v10
	v_lshlrev_b32_e32 v13, 16, v11
	v_and_b32_e32 v58, 0xffff0000, v11
	global_load_dwordx4 v[8:11], v[8:9], off offset:16
	v_lshlrev_b32_e32 v60, 16, v4
	v_and_b32_e32 v61, 0xffff0000, v4
	v_lshlrev_b32_e32 v4, 16, v5
	v_and_b32_e32 v5, 0xffff0000, v5
	v_lshlrev_b32_e32 v22, 16, v0
	v_and_b32_e32 v23, 0xffff0000, v0
	v_lshlrev_b32_e32 v0, 16, v1
	v_and_b32_e32 v1, 0xffff0000, v1
	v_and_b32_e32 v59, 0xffff0000, v3
	v_lshlrev_b32_e32 v64, 16, v2
	v_and_b32_e32 v65, 0xffff0000, v2
	v_lshlrev_b32_e32 v62, 16, v6
	v_and_b32_e32 v63, 0xffff0000, v6
	v_lshlrev_b32_e32 v6, 16, v7
	v_and_b32_e32 v7, 0xffff0000, v7
	s_waitcnt vmcnt(0)
	v_mul_f32 v18, v18, v60
	v_mul_f32 v19, v19, v61
	v_mul_f32 v4, v20, v4
	v_mul_f32 v5, v21, v5
	v_fma_f32 v14, v14, v32, v18
	v_fma_f32 v15, v15, v33, v19
	v_fma_f32 v4, v16, v40, v4
	v_fma_f32 v5, v17, v41, v5
	v_fma_f32 v14, v36, v22, v14
	v_fma_f32 v15, v37, v23, v15
	v_fma_f32 v4, v38, v0, v4
	v_fma_f32 v5, v39, v1, v5
	v_mul_f32_e32 v0, 0xbfb8aa3b, v14
	v_mul_f32_e32 v1, 0xbfb8aa3b, v15
	v_mul_f32_e32 v16, 0xbfb8aa3b, v4
	v_mul_f32_e32 v17, 0xbfb8aa3b, v5
	v_exp_f32_e32 v0, v0
	v_exp_f32_e32 v1, v1
	v_exp_f32_e32 v16, v16
	v_exp_f32_e32 v17, v17
	v_lshlrev_b32_e32 v21, 16, v3
	v_add_f32 v0, v0, 1.0
	v_add_f32 v1, v1, 1.0
	v_add_f32 v2, v16, 1.0
	v_add_f32 v3, v17, 1.0
	v_div_scale_f32 v16, s[4:5], v1, v1, v15
	v_div_scale_f32 v18, s[4:5], v0, v0, v14
	v_rcp_f32_e32 v22, v16
	v_div_scale_f32 v20, s[6:7], v3, v3, v5
	v_rcp_f32_e32 v23, v18
	v_rcp_f32_e32 v31, v20
	v_fma_f32 v33, -v16, v22, 1.0
	v_div_scale_f32 v17, vcc, v15, v1, v15
	v_fma_f32 v34, -v18, v23, 1.0
	v_fmac_f32_e32 v22, v33, v22
	v_div_scale_f32 v19, s[4:5], v14, v0, v14
	v_fma_f32 v36, -v20, v31, 1.0
	v_fmac_f32_e32 v23, v34, v23
	v_mul_f32_e32 v33, v17, v22
	v_div_scale_f32 v32, s[6:7], v5, v3, v5
	v_fmac_f32_e32 v31, v36, v31
	v_mul_f32_e32 v34, v19, v23
	v_fma_f32 v37, -v16, v33, v17
	v_mul_f32_e32 v36, v32, v31
	v_fma_f32 v38, -v18, v34, v19
	v_fmac_f32_e32 v33, v37, v22
	v_fma_f32 v39, -v20, v36, v32
	v_fmac_f32_e32 v34, v38, v23
	v_fma_f32 v16, -v16, v33, v17
	v_fmac_f32_e32 v36, v39, v31
	v_fma_f32 v17, -v18, v34, v19
	v_div_fmas_f32 v16, v16, v22, v33
	s_mov_b64 vcc, s[4:5]
	v_fma_f32 v18, -v20, v36, v32
	v_div_fixup_f32 v1, v16, v1, v15
	v_div_fmas_f32 v15, v17, v23, v34
	s_mov_b64 vcc, s[6:7]
	v_div_fmas_f32 v16, v18, v31, v36
	v_div_scale_f32 v19, s[4:5], v2, v2, v4
	v_div_fixup_f32 v3, v16, v3, v5
	v_mul_f32 v16, v52, v62
	v_mul_f32 v17, v53, v63
	v_rcp_f32_e32 v20, v19
	v_fma_f32 v16, v46, v56, v16
	v_fma_f32 v17, v47, v57, v17
	v_div_fixup_f32 v0, v15, v0, v14
	v_fma_f32 v8, v8, v64, v16
	v_fma_f32 v9, v9, v65, v17
	v_fma_f32 v5, -v19, v20, 1.0
	v_mul_f32_e32 v16, 0xbfb8aa3b, v8
	v_mul_f32_e32 v17, 0xbfb8aa3b, v9
	v_exp_f32_e32 v16, v16
	v_exp_f32_e32 v17, v17
	v_fmac_f32_e32 v20, v5, v20
	v_div_scale_f32 v5, vcc, v4, v2, v4
	v_mul_f32_e32 v18, v5, v20
	v_fma_f32 v22, -v19, v18, v5
	v_add_f32 v16, v16, 1.0
	v_add_f32 v17, v17, 1.0
	v_fmac_f32_e32 v18, v22, v20
	v_div_scale_f32 v22, s[4:5], v17, v17, v9
	v_rcp_f32_e32 v23, v22
	v_fma_f32 v5, -v19, v18, v5
	v_div_fmas_f32 v5, v5, v20, v18
	v_div_fixup_f32 v2, v5, v2, v4
	v_fma_f32 v4, -v22, v23, 1.0
	v_fmac_f32_e32 v23, v4, v23
	v_div_scale_f32 v4, vcc, v9, v17, v9
	v_mul_f32_e32 v5, v4, v23
	v_fma_f32 v20, -v22, v5, v4
	v_fmac_f32_e32 v5, v20, v23
	v_fma_f32 v4, -v22, v5, v4
	v_mul_f32_e32 v22, v10, v21
	v_mov_b32_e32 v10, v49
	v_mul_f32 v10, v10, v58
	v_mul_f32 v11, v11, v59
	v_div_scale_f32 v31, s[4:5], v16, v16, v8
	v_mul_f32_e32 v20, v48, v13
	v_mov_b32_e32 v21, v10
	v_rcp_f32_e32 v32, v31
	v_div_fmas_f32 v4, v4, v23, v5
	v_fma_f32 v6, v54, v6, v20
	v_fma_f32 v7, v55, v7, v21
	v_mov_b32_e32 v23, v11
	v_add_f32 v6, v6, v22
	v_add_f32 v7, v7, v23
	v_div_fixup_f32 v5, v4, v17, v9
	v_mul_f32_e32 v10, 0xbfb8aa3b, v6
	v_mul_f32_e32 v11, 0xbfb8aa3b, v7
	v_exp_f32_e32 v10, v10
	v_exp_f32_e32 v11, v11
	v_fma_f32 v4, -v31, v32, 1.0
	v_fmac_f32_e32 v32, v4, v32
	v_div_scale_f32 v4, vcc, v8, v16, v8
	v_mul_f32_e32 v9, v4, v32
	v_fma_f32 v13, -v31, v9, v4
	v_add_f32 v10, v10, 1.0
	v_add_f32 v11, v11, 1.0
	v_fmac_f32_e32 v9, v13, v32
	v_div_scale_f32 v13, s[4:5], v11, v11, v7
	v_rcp_f32_e32 v17, v13
	v_fma_f32 v4, -v31, v9, v4
	v_div_fmas_f32 v4, v4, v32, v9
	v_div_fixup_f32 v4, v4, v16, v8
	v_fma_f32 v16, -v13, v17, 1.0
	v_fmac_f32_e32 v17, v16, v17
	v_div_scale_f32 v16, vcc, v7, v11, v7
	v_mul_f32_e32 v20, v16, v17
	v_fma_f32 v21, -v13, v20, v16
	v_fmac_f32_e32 v20, v21, v17
	v_fma_f32 v13, -v13, v20, v16
	v_div_scale_f32 v16, s[4:5], v10, v10, v6
	v_rcp_f32_e32 v21, v16
	v_div_fmas_f32 v13, v13, v17, v20
	v_div_fixup_f32 v7, v13, v11, v7
	v_mul_f32 v14, v0, v0
	v_mul_f32 v15, v1, v1
	v_fma_f32 v11, -v16, v21, 1.0
	v_fmac_f32_e32 v21, v11, v21
	v_div_scale_f32 v11, vcc, v6, v10, v6
	v_mul_f32_e32 v13, v11, v21
	v_fma_f32 v17, -v16, v13, v11
	v_fmac_f32_e32 v13, v17, v21
	v_fma_f32 v11, -v16, v13, v11
	v_mul_f32 v18, v2, v2
	v_mul_f32 v19, v3, v3
	v_div_fmas_f32 v11, v11, v21, v13
	v_add_f32_e32 v13, v14, v15
	v_add_f32_e32 v13, v13, v18
	v_mul_f32 v8, v4, v4
	v_mul_f32 v9, v5, v5
	v_add_f32_e32 v13, v13, v19
	v_div_fixup_f32 v6, v11, v10, v6
	v_add_f32_e32 v8, v13, v8
	v_mul_f32 v10, v6, v6
	v_mul_f32 v11, v7, v7
	v_add_f32_e32 v8, v8, v9
	v_add_f32_e32 v8, v8, v10
	v_add_f32_e32 v8, v8, v11
	v_cmp_gt_i32_e32 vcc, 64, v12
	s_nop 0
	v_add_f32_dpp v8, v8, v8 quad_perm:[1,0,3,2] row_mask:0xf bank_mask:0xf bound_ctrl:1
	s_nop 1
	v_add_f32_dpp v8, v8, v8 quad_perm:[2,3,0,1] row_mask:0xf bank_mask:0xf bound_ctrl:1
	s_nop 1
	v_mov_b32_dpp v9, v8 row_half_mirror row_mask:0xf bank_mask:0xf bound_ctrl:1
	s_and_saveexec_b64 s[6:7], vcc
	s_cbranch_execz .LBB0_464
	v_add_f32_e32 v8, v8, v9
	v_add_f32_e32 v8, 0x358637bd, v8
	v_mul_f32_e32 v9, 0x4b800000, v8
	v_cmp_gt_f32_e32 vcc, s34, v8
	v_cmp_gt_i32_e64 s[4:5], 32, v12
	s_nop 0
	v_cndmask_b32_e32 v8, v8, v9, vcc
	v_rsq_f32_e32 v8, v8
	v_cndmask_b32_e64 v9, 1.0, v43, s[4:5]
	v_mul_f32_e32 v10, 0x45800000, v8
	v_cndmask_b32_e32 v8, v8, v10, vcc
	v_mul_f32_e32 v8, v9, v8
	v_mul_f32 v6, v6, v8
	v_mul_f32 v7, v7, v8
	v_mul_f32 v4, v4, v8
	v_mul_f32 v5, v5, v8
	v_mul_f32 v2, v2, v8
	v_mul_f32 v3, v3, v8
	v_mul_f32 v0, v0, v8
	v_mul_f32 v1, v1, v8
	s_branch .LBB0_464

.LBB0_484:
	s_or_b64 exec, exec, s[4:5]
	s_waitcnt lgkmcnt(0)
	v_lshl_add_u64 v[26:27], v[24:25], 2, s[10:11]
	global_load_dwordx4 v[30:33], v[26:27], off
	global_load_dwordx4 v[34:37], v[26:27], off offset:3072
	v_add_co_u32_e32 v24, vcc, s26, v26
	s_waitcnt vmcnt(0)
	v_lshlrev_b32_e32 v48, 16, v8
	v_addc_co_u32_e32 v25, vcc, 0, v27, vcc
	global_load_dwordx4 v[38:41], v[24:25], off offset:2048
	global_load_dwordx4 v[44:47], v[26:27], off offset:16
	global_load_dwordx4 v[52:55], v[26:27], off offset:3088
	v_and_b32_e32 v49, 0xffff0000, v8
	v_lshlrev_b32_e32 v56, 16, v9
	v_and_b32_e32 v57, 0xffff0000, v9
	v_lshl_add_u64 v[8:9], v[26:27], 0, s[18:19]
	v_lshlrev_b32_e32 v58, 16, v10
	v_and_b32_e32 v59, 0xffff0000, v10
	v_lshlrev_b32_e32 v23, 16, v11
	v_and_b32_e32 v60, 0xffff0000, v11
	global_load_dwordx4 v[8:11], v[8:9], off offset:16
	v_lshlrev_b32_e32 v62, 16, v4
	v_and_b32_e32 v63, 0xffff0000, v4
	v_lshlrev_b32_e32 v4, 16, v5
	v_and_b32_e32 v5, 0xffff0000, v5
	v_lshlrev_b32_e32 v26, 16, v0
	v_and_b32_e32 v27, 0xffff0000, v0
	v_lshlrev_b32_e32 v0, 16, v1
	v_and_b32_e32 v1, 0xffff0000, v1
	v_mad_u64_u32 v[24:25], s[4:5], v22, s27, v[14:15]
	v_and_b32_e32 v61, 0xffff0000, v3
	v_lshlrev_b32_e32 v66, 16, v2
	v_and_b32_e32 v67, 0xffff0000, v2
	v_lshlrev_b32_e32 v64, 16, v6
	v_and_b32_e32 v65, 0xffff0000, v6
	v_lshlrev_b32_e32 v6, 16, v7
	v_and_b32_e32 v7, 0xffff0000, v7
	v_mul_f32 v34, v34, v62
	v_mul_f32 v35, v35, v63
	v_mul_f32 v4, v36, v4
	v_mul_f32 v5, v37, v5
	v_fma_f32 v30, v30, v48, v34
	v_fma_f32 v31, v31, v49, v35
	v_fma_f32 v4, v32, v56, v4
	v_fma_f32 v5, v33, v57, v5
	s_waitcnt vmcnt(3)
	v_fma_f32 v26, v38, v26, v30
	v_fma_f32 v27, v39, v27, v31
	v_fma_f32 v4, v40, v0, v4
	v_fma_f32 v5, v41, v1, v5
	v_mul_f32_e32 v0, 0xbfb8aa3b, v26
	v_mul_f32_e32 v1, 0xbfb8aa3b, v27
	v_exp_f32_e32 v0, v0
	v_exp_f32_e32 v1, v1
	v_mul_f32_e32 v25, 0xbfb8aa3b, v4
	v_mul_f32_e32 v29, 0xbfb8aa3b, v5
	v_exp_f32_e32 v30, v25
	v_exp_f32_e32 v31, v29
	v_add_f32 v0, v0, 1.0
	v_add_f32 v1, v1, 1.0
	v_lshlrev_b32_e32 v25, 16, v3
	v_div_scale_f32 v29, s[4:5], v1, v1, v27
	v_add_f32 v2, v30, 1.0
	v_add_f32 v3, v31, 1.0
	v_div_scale_f32 v31, s[4:5], v0, v0, v26
	v_rcp_f32_e32 v37, v29
	v_div_scale_f32 v33, s[6:7], v3, v3, v5
	v_rcp_f32_e32 v38, v31
	v_rcp_f32_e32 v39, v33
	v_fma_f32 v41, -v29, v37, 1.0
	v_div_scale_f32 v30, vcc, v27, v1, v27
	v_fma_f32 v43, -v31, v38, 1.0
	v_fmac_f32_e32 v37, v41, v37
	v_div_scale_f32 v32, s[4:5], v26, v0, v26
	v_fma_f32 v48, -v33, v39, 1.0
	v_fmac_f32_e32 v38, v43, v38
	v_mul_f32_e32 v41, v30, v37
	v_div_scale_f32 v34, s[6:7], v5, v3, v5
	v_fmac_f32_e32 v39, v48, v39
	v_mul_f32_e32 v43, v32, v38
	v_fma_f32 v51, -v29, v41, v30
	v_mul_f32_e32 v48, v34, v39
	v_fma_f32 v56, -v31, v43, v32
	v_fmac_f32_e32 v41, v51, v37
	v_fma_f32 v57, -v33, v48, v34
	v_fmac_f32_e32 v43, v56, v38
	v_fma_f32 v29, -v29, v41, v30
	v_fmac_f32_e32 v48, v57, v39
	v_fma_f32 v30, -v31, v43, v32
	v_div_fmas_f32 v29, v29, v37, v41
	s_mov_b64 vcc, s[4:5]
	v_fma_f32 v31, -v33, v48, v34
	v_div_fixup_f32 v1, v29, v1, v27
	v_div_fmas_f32 v27, v30, v38, v43
	s_mov_b64 vcc, s[6:7]
	v_div_fmas_f32 v29, v31, v39, v48
	s_waitcnt vmcnt(1)
	v_mul_f32 v30, v52, v64
	v_mul_f32 v31, v53, v65
	v_div_scale_f32 v35, s[8:9], v2, v2, v4
	v_fma_f32 v30, v44, v58, v30
	v_fma_f32 v31, v45, v59, v31
	v_div_fixup_f32 v3, v29, v3, v5
	s_waitcnt vmcnt(0)
	v_fma_f32 v8, v8, v66, v30
	v_fma_f32 v9, v9, v67, v31
	v_rcp_f32_e32 v40, v35
	v_mul_f32_e32 v5, 0xbfb8aa3b, v8
	v_exp_f32_e32 v30, v5
	v_mul_f32_e32 v5, 0xbfb8aa3b, v9
	v_exp_f32_e32 v31, v5
	v_fma_f32 v49, -v35, v40, 1.0
	v_div_scale_f32 v36, s[8:9], v4, v2, v4
	v_fmac_f32_e32 v40, v49, v40
	v_add_f32 v30, v30, 1.0
	v_add_f32 v31, v31, 1.0
	v_mul_f32_e32 v49, v36, v40
	v_div_scale_f32 v29, s[4:5], v31, v31, v9
	v_fma_f32 v5, -v35, v49, v36
	v_rcp_f32_e32 v34, v29
	v_fmac_f32_e32 v49, v5, v40
	v_fma_f32 v5, -v35, v49, v36
	s_mov_b64 vcc, s[8:9]
	v_div_fmas_f32 v5, v5, v40, v49
	v_div_fixup_f32 v2, v5, v2, v4
	v_fma_f32 v4, -v29, v34, 1.0
	v_fmac_f32_e32 v34, v4, v34
	v_div_scale_f32 v4, vcc, v9, v31, v9
	v_mul_f32_e32 v5, v4, v34
	v_fma_f32 v35, -v29, v5, v4
	v_fmac_f32_e32 v5, v35, v34
	v_mul_f32_e32 v36, v10, v25
	v_mov_b32_e32 v10, v47
	v_fma_f32 v4, -v29, v5, v4
	v_mul_f32 v10, v10, v60
	v_mul_f32 v11, v11, v61
	v_div_scale_f32 v29, s[4:5], v30, v30, v8
	v_div_fmas_f32 v4, v4, v34, v5
	v_mul_f32_e32 v34, v46, v23
	v_mov_b32_e32 v35, v10
	v_rcp_f32_e32 v38, v29
	v_fma_f32 v6, v54, v6, v34
	v_fma_f32 v7, v55, v7, v35
	v_mov_b32_e32 v37, v11
	v_add_f32 v6, v6, v36
	v_add_f32 v7, v7, v37
	v_div_fixup_f32 v5, v4, v31, v9
	v_mul_f32_e32 v10, 0xbfb8aa3b, v6
	v_mul_f32_e32 v11, 0xbfb8aa3b, v7
	v_exp_f32_e32 v10, v10
	v_exp_f32_e32 v11, v11
	v_fma_f32 v4, -v29, v38, 1.0
	v_fmac_f32_e32 v38, v4, v38
	v_div_scale_f32 v4, vcc, v8, v30, v8
	v_mul_f32_e32 v9, v4, v38
	v_fma_f32 v23, -v29, v9, v4
	v_add_f32 v10, v10, 1.0
	v_add_f32 v11, v11, 1.0
	v_fmac_f32_e32 v9, v23, v38
	v_div_scale_f32 v23, s[4:5], v11, v11, v7
	v_rcp_f32_e32 v25, v23
	v_fma_f32 v4, -v29, v9, v4
	v_div_fmas_f32 v4, v4, v38, v9
	v_div_fixup_f32 v4, v4, v30, v8
	v_fma_f32 v29, -v23, v25, 1.0
	v_fmac_f32_e32 v25, v29, v25
	v_div_scale_f32 v29, vcc, v7, v11, v7
	v_mul_f32_e32 v30, v29, v25
	v_fma_f32 v31, -v23, v30, v29
	v_fmac_f32_e32 v30, v31, v25
	v_fma_f32 v23, -v23, v30, v29
	v_div_scale_f32 v29, s[4:5], v10, v10, v6
	v_rcp_f32_e32 v31, v29
	v_div_fmas_f32 v23, v23, v25, v30
	v_div_fixup_f32 v7, v23, v11, v7
	v_div_fixup_f32 v0, v27, v0, v26
	v_fma_f32 v11, -v29, v31, 1.0
	v_fmac_f32_e32 v31, v11, v31
	v_div_scale_f32 v11, vcc, v6, v10, v6
	v_mul_f32_e32 v23, v11, v31
	v_fma_f32 v25, -v29, v23, v11
	v_fmac_f32_e32 v23, v25, v31
	v_mul_f32 v26, v0, v0
	v_mul_f32 v27, v1, v1
	v_fma_f32 v11, -v29, v23, v11
	v_mul_f32 v32, v2, v2
	v_mul_f32 v33, v3, v3
	v_div_fmas_f32 v11, v11, v31, v23
	v_add_f32_e32 v23, v26, v27
	v_add_f32_e32 v23, v23, v32
	v_mul_f32 v8, v4, v4
	v_mul_f32 v9, v5, v5
	v_add_f32_e32 v23, v23, v33
	v_div_fixup_f32 v6, v11, v10, v6
	v_add_f32_e32 v8, v23, v8
	v_mul_f32 v10, v6, v6
	v_mul_f32 v11, v7, v7
	v_add_f32_e32 v8, v8, v9
	v_add_f32_e32 v8, v8, v10
	v_add_f32_e32 v8, v8, v11
	v_cmp_gt_i32_e32 vcc, 64, v24
	s_nop 0
	v_add_f32_dpp v8, v8, v8 quad_perm:[1,0,3,2] row_mask:0xf bank_mask:0xf bound_ctrl:1
	s_nop 1
	v_add_f32_dpp v8, v8, v8 quad_perm:[2,3,0,1] row_mask:0xf bank_mask:0xf bound_ctrl:1
	s_nop 1
	v_mov_b32_dpp v9, v8 row_half_mirror row_mask:0xf bank_mask:0xf bound_ctrl:1
	s_and_saveexec_b64 s[6:7], vcc
	s_cbranch_execz .LBB0_479
	v_add_f32_e32 v8, v8, v9
	v_add_f32_e32 v8, 0x358637bd, v8
	v_mul_f32_e32 v9, 0x4b800000, v8
	v_cmp_gt_f32_e32 vcc, s28, v8
	v_cmp_gt_i32_e64 s[4:5], 32, v24
	s_nop 0
	v_cndmask_b32_e32 v8, v8, v9, vcc
	v_rsq_f32_e32 v8, v8
	v_cndmask_b32_e64 v9, 1.0, v28, s[4:5]
	v_mul_f32_e32 v10, 0x45800000, v8
	v_cndmask_b32_e32 v8, v8, v10, vcc
	v_mul_f32_e32 v8, v9, v8
	v_mul_f32 v6, v6, v8
	v_mul_f32 v7, v7, v8
	v_mul_f32 v4, v4, v8
	v_mul_f32 v5, v5, v8
	v_mul_f32 v2, v2, v8
	v_mul_f32 v3, v3, v8
	v_mul_f32 v0, v0, v8
	v_mul_f32 v1, v1, v8
	s_branch .LBB0_479

.LBB0_489:
	v_add_u32_e32 v20, s13, v50
	v_ashrrev_i32_e32 v36, 4, v20
	v_mad_i64_i32 v[0:1], s[4:5], v36, s17, v[26:27]
	flat_load_dwordx4 v[12:15], v[0:1] offset:768
	v_add_u32_e32 v33, s13, v39
	v_add_u32_e32 v31, s13, v40
	v_add_u32_e32 v43, s13, v38
	v_ashrrev_i32_e32 v34, 4, v33
	global_load_dwordx4 v[44:47], v[24:25], off offset:16
	global_load_dwordx4 v[16:19], v[24:25], off
	v_ashrrev_i32_e32 v32, 4, v31
	v_ashrrev_i32_e32 v30, 4, v43
	v_mad_i64_i32 v[48:49], s[4:5], v34, s17, v[26:27]
	v_mad_i64_i32 v[52:53], s[4:5], v32, s17, v[26:27]
	v_mad_i64_i32 v[54:55], s[4:5], v30, s17, v[26:27]
	flat_load_dwordx4 v[8:11], v[48:49] offset:768
	flat_load_dwordx4 v[4:7], v[52:53] offset:768
	flat_load_dwordx4 v[0:3], v[54:55] offset:768
	v_ashrrev_i32_e32 v37, 31, v36
	v_cmp_gt_i32_e64 s[4:5], s18, v36
	s_waitcnt vmcnt(0) lgkmcnt(0)
	v_lshlrev_b32_e32 v48, 16, v12
	v_and_b32_e32 v49, 0xffff0000, v12
	v_lshlrev_b32_e32 v12, 16, v13
	v_and_b32_e32 v13, 0xffff0000, v13
	v_mul_f32 v60, v48, v48
	v_mul_f32 v61, v49, v49
	v_mul_f32 v58, v12, v12
	v_mul_f32 v59, v13, v13
	v_add_f32_e32 v29, v60, v61
	v_lshlrev_b32_e32 v52, 16, v14
	v_and_b32_e32 v53, 0xffff0000, v14
	v_add_f32_e32 v29, v29, v58
	v_mul_f32 v56, v52, v52
	v_mul_f32 v57, v53, v53
	v_add_f32_e32 v29, v59, v29
	v_lshlrev_b32_e32 v14, 16, v15
	v_and_b32_e32 v15, 0xffff0000, v15
	v_add_f32_e32 v29, v56, v29
	v_mul_f32 v54, v14, v14
	v_mul_f32 v55, v15, v15
	v_add_f32_e32 v29, v57, v29
	v_add_f32_e32 v29, v54, v29
	v_add_f32_e32 v29, v55, v29
	v_lshlrev_b64 v[54:55], 8, v[36:37]
	s_nop 0
	v_add_f32_dpp v29, v29, v29 quad_perm:[1,0,3,2] row_mask:0xf bank_mask:0xf bound_ctrl:1
	s_nop 1
	v_add_f32_dpp v29, v29, v29 quad_perm:[2,3,0,1] row_mask:0xf bank_mask:0xf bound_ctrl:1
	s_nop 1
	v_add_f32_dpp v29, v29, v29 row_half_mirror row_mask:0xf bank_mask:0xf bound_ctrl:1
	s_nop 1
	v_add_f32_dpp v29, v29, v29 row_mirror row_mask:0xf bank_mask:0xf bound_ctrl:1
	v_fmamk_f32 v29, v29, 0x3c000000, v41
	v_mul_f32_e32 v35, 0x4b800000, v29
	v_cmp_gt_f32_e32 vcc, s19, v29
	s_nop 1
	v_cndmask_b32_e32 v29, v29, v35, vcc
	v_rsq_f32_e32 v29, v29
	s_nop 0
	v_mul_f32_e32 v35, 0x45800000, v29
	v_cndmask_b32_e32 v56, v29, v35, vcc
	v_mul_f32 v48, v56, v48
	v_mul_f32 v49, v56, v49
	v_mul_f32 v12, v56, v12
	v_mul_f32 v13, v56, v13
	v_mul_f32 v52, v56, v52
	v_mul_f32 v53, v56, v53
	v_mul_f32 v14, v56, v14
	v_mul_f32 v15, v56, v15
	v_mul_f32 v16, v16, v48
	v_mul_f32 v17, v17, v49
	v_mul_f32 v18, v18, v12
	v_mul_f32 v19, v19, v13
	v_mul_f32 v12, v44, v52
	v_mul_f32 v13, v45, v53
	v_mul_f32 v14, v46, v14
	v_mul_f32 v15, v47, v15
	v_cvt_pk_bf16_f32 v44, v16, v17
	v_cvt_pk_bf16_f32 v45, v18, v19
	v_cvt_pk_bf16_f32 v46, v12, v13
	v_cvt_pk_bf16_f32 v47, v14, v15
	v_lshl_add_u64 v[48:49], v[22:23], 0, v[54:55]
	flat_store_dwordx4 v[48:49], v[44:47]
	s_and_saveexec_b64 s[10:11], s[4:5]
	s_cbranch_execz .LBB0_491
	v_ashrrev_i32_e32 v20, 11, v20
	v_and_b32_e32 v44, -2, v20
	v_ashrrev_i32_e32 v45, 31, v44
	v_lshlrev_b64 v[44:45], 17, v[44:45]
	v_lshlrev_b32_e32 v20, 9, v36
	v_lshl_add_u64 v[44:45], s[8:9], 0, v[44:45]
	v_and_b32_e32 v20, 0x1fe00, v20
	v_lshl_add_u64 v[36:37], v[44:45], 0, v[20:21]
	v_mov_b32_e32 v29, v21
	v_lshl_add_u64 v[36:37], v[36:37], 0, v[28:29]
	flat_store_dwordx4 v[36:37], v[16:19]
	flat_store_dwordx4 v[36:37], v[12:15] offset:16
.LBB0_491:
	s_or_b64 exec, exec, s[10:11]
	global_load_dwordx4 v[12:15], v[24:25], off
	global_load_dwordx4 v[16:19], v[24:25], off offset:16
	v_lshlrev_b32_e32 v36, 16, v8
	v_and_b32_e32 v37, 0xffff0000, v8
	v_lshlrev_b32_e32 v8, 16, v9
	v_and_b32_e32 v9, 0xffff0000, v9
	v_mul_f32 v54, v36, v36
	v_mul_f32 v55, v37, v37
	v_mul_f32 v52, v8, v8
	v_mul_f32 v53, v9, v9
	v_add_f32_e32 v20, v54, v55
	v_lshlrev_b32_e32 v44, 16, v10
	v_and_b32_e32 v45, 0xffff0000, v10
	v_add_f32_e32 v20, v20, v52
	v_mul_f32 v48, v44, v44
	v_mul_f32 v49, v45, v45
	v_add_f32_e32 v20, v53, v20
	v_lshlrev_b32_e32 v10, 16, v11
	v_and_b32_e32 v11, 0xffff0000, v11
	v_add_f32_e32 v20, v48, v20
	v_mul_f32 v46, v10, v10
	v_mul_f32 v47, v11, v11
	v_add_f32_e32 v20, v49, v20
	v_add_f32_e32 v20, v46, v20
	v_add_f32_e32 v20, v47, v20
	v_ashrrev_i32_e32 v35, 31, v34
	v_lshlrev_b64 v[46:47], 8, v[34:35]
	v_add_f32_dpp v20, v20, v20 quad_perm:[1,0,3,2] row_mask:0xf bank_mask:0xf bound_ctrl:1
	v_cmp_gt_i32_e64 s[4:5], s18, v34
	s_nop 0
	v_add_f32_dpp v20, v20, v20 quad_perm:[2,3,0,1] row_mask:0xf bank_mask:0xf bound_ctrl:1
	s_nop 1
	v_add_f32_dpp v20, v20, v20 row_half_mirror row_mask:0xf bank_mask:0xf bound_ctrl:1
	s_nop 1
	v_add_f32_dpp v20, v20, v20 row_mirror row_mask:0xf bank_mask:0xf bound_ctrl:1
	v_fmamk_f32 v20, v20, 0x3c000000, v41
	v_mul_f32_e32 v29, 0x4b800000, v20
	v_cmp_gt_f32_e32 vcc, s19, v20
	s_nop 1
	v_cndmask_b32_e32 v20, v20, v29, vcc
	v_rsq_f32_e32 v20, v20
	s_nop 0
	v_mul_f32_e32 v29, 0x45800000, v20
	v_cndmask_b32_e32 v20, v20, v29, vcc
	v_mul_f32 v36, v20, v36
	v_mul_f32 v37, v20, v37
	v_mul_f32 v8, v20, v8
	v_mul_f32 v9, v20, v9
	v_mul_f32 v44, v20, v44
	v_mul_f32 v45, v20, v45
	v_mul_f32 v10, v20, v10
	v_mul_f32 v11, v20, v11
	s_waitcnt vmcnt(0)
	v_mul_f32 v12, v12, v36
	v_mul_f32 v13, v13, v37
	v_mul_f32 v14, v14, v8
	v_mul_f32 v15, v15, v9
	v_mul_f32 v8, v16, v44
	v_mul_f32 v9, v17, v45
	v_mul_f32 v10, v18, v10
	v_mul_f32 v11, v19, v11
	v_cvt_pk_bf16_f32 v16, v12, v13
	v_cvt_pk_bf16_f32 v17, v14, v15
	v_cvt_pk_bf16_f32 v18, v8, v9
	v_cvt_pk_bf16_f32 v19, v10, v11
	v_lshl_add_u64 v[36:37], v[22:23], 0, v[46:47]
	flat_store_dwordx4 v[36:37], v[16:19]
	s_and_saveexec_b64 s[10:11], s[4:5]
	s_cbranch_execz .LBB0_493
	v_ashrrev_i32_e32 v16, 11, v33
	v_and_b32_e32 v16, -2, v16
	v_ashrrev_i32_e32 v17, 31, v16
	v_lshlrev_b64 v[16:17], 17, v[16:17]
	v_lshlrev_b32_e32 v18, 9, v34
	v_lshl_add_u64 v[16:17], s[8:9], 0, v[16:17]
	v_and_b32_e32 v20, 0x1fe00, v18
	v_lshl_add_u64 v[16:17], v[16:17], 0, v[20:21]
	v_mov_b32_e32 v29, v21
	v_lshl_add_u64 v[16:17], v[16:17], 0, v[28:29]
	flat_store_dwordx4 v[16:17], v[12:15]
	flat_store_dwordx4 v[16:17], v[8:11] offset:16
.LBB0_493:
	s_or_b64 exec, exec, s[10:11]
	global_load_dwordx4 v[8:11], v[24:25], off
	global_load_dwordx4 v[12:15], v[24:25], off offset:16
	v_lshlrev_b32_e32 v16, 16, v4
	v_and_b32_e32 v17, 0xffff0000, v4
	v_lshlrev_b32_e32 v4, 16, v5
	v_and_b32_e32 v5, 0xffff0000, v5
	v_mul_f32 v46, v16, v16
	v_mul_f32 v47, v17, v17
	v_mul_f32 v44, v4, v4
	v_mul_f32 v45, v5, v5
	v_add_f32_e32 v20, v46, v47
	v_lshlrev_b32_e32 v18, 16, v6
	v_and_b32_e32 v19, 0xffff0000, v6
	v_add_f32_e32 v20, v20, v44
	v_mul_f32 v36, v18, v18
	v_mul_f32 v37, v19, v19
	v_add_f32_e32 v20, v45, v20
	v_lshlrev_b32_e32 v6, 16, v7
	v_and_b32_e32 v7, 0xffff0000, v7
	v_add_f32_e32 v20, v36, v20
	v_mul_f32 v34, v6, v6
	v_mul_f32 v35, v7, v7
	v_add_f32_e32 v20, v37, v20
	v_add_f32_e32 v20, v34, v20
	v_add_f32_e32 v20, v35, v20
	v_ashrrev_i32_e32 v33, 31, v32
	v_lshlrev_b64 v[34:35], 8, v[32:33]
	v_add_f32_dpp v20, v20, v20 quad_perm:[1,0,3,2] row_mask:0xf bank_mask:0xf bound_ctrl:1
	v_cmp_gt_i32_e64 s[4:5], s18, v32
	s_nop 0
	v_add_f32_dpp v20, v20, v20 quad_perm:[2,3,0,1] row_mask:0xf bank_mask:0xf bound_ctrl:1
	s_nop 1
	v_add_f32_dpp v20, v20, v20 row_half_mirror row_mask:0xf bank_mask:0xf bound_ctrl:1
	s_nop 1
	v_add_f32_dpp v20, v20, v20 row_mirror row_mask:0xf bank_mask:0xf bound_ctrl:1
	v_fmamk_f32 v20, v20, 0x3c000000, v41
	v_mul_f32_e32 v29, 0x4b800000, v20
	v_cmp_gt_f32_e32 vcc, s19, v20
	s_nop 1
	v_cndmask_b32_e32 v20, v20, v29, vcc
	v_rsq_f32_e32 v20, v20
	s_nop 0
	v_mul_f32_e32 v29, 0x45800000, v20
	v_cndmask_b32_e32 v20, v20, v29, vcc
	v_mul_f32 v16, v20, v16
	v_mul_f32 v17, v20, v17
	v_mul_f32 v4, v20, v4
	v_mul_f32 v5, v20, v5
	v_mul_f32 v18, v20, v18
	v_mul_f32 v19, v20, v19
	v_mul_f32 v6, v20, v6
	v_mul_f32 v7, v20, v7
	s_waitcnt vmcnt(0)
	v_mul_f32 v8, v8, v16
	v_mul_f32 v9, v9, v17
	v_mul_f32 v10, v10, v4
	v_mul_f32 v11, v11, v5
	v_mul_f32 v4, v12, v18
	v_mul_f32 v5, v13, v19
	v_mul_f32 v6, v14, v6
	v_mul_f32 v7, v15, v7
	v_cvt_pk_bf16_f32 v12, v8, v9
	v_cvt_pk_bf16_f32 v13, v10, v11
	v_cvt_pk_bf16_f32 v14, v4, v5
	v_cvt_pk_bf16_f32 v15, v6, v7
	v_lshl_add_u64 v[16:17], v[22:23], 0, v[34:35]
	flat_store_dwordx4 v[16:17], v[12:15]
	s_and_saveexec_b64 s[10:11], s[4:5]
	s_cbranch_execz .LBB0_495
	v_ashrrev_i32_e32 v12, 11, v31
	v_and_b32_e32 v12, -2, v12
	v_ashrrev_i32_e32 v13, 31, v12
	v_lshlrev_b64 v[12:13], 17, v[12:13]
	v_lshlrev_b32_e32 v14, 9, v32
	v_lshl_add_u64 v[12:13], s[8:9], 0, v[12:13]
	v_and_b32_e32 v20, 0x1fe00, v14
	v_lshl_add_u64 v[12:13], v[12:13], 0, v[20:21]
	v_mov_b32_e32 v29, v21
	v_lshl_add_u64 v[12:13], v[12:13], 0, v[28:29]
	flat_store_dwordx4 v[12:13], v[8:11]
	flat_store_dwordx4 v[12:13], v[4:7] offset:16
.LBB0_495:
	s_or_b64 exec, exec, s[10:11]
	global_load_dwordx4 v[4:7], v[24:25], off
	global_load_dwordx4 v[8:11], v[24:25], off offset:16
	v_lshlrev_b32_e32 v12, 16, v0
	v_and_b32_e32 v13, 0xffff0000, v0
	v_lshlrev_b32_e32 v0, 16, v1
	v_and_b32_e32 v1, 0xffff0000, v1
	v_mul_f32 v34, v12, v12
	v_mul_f32 v35, v13, v13
	v_mul_f32 v32, v0, v0
	v_mul_f32 v33, v1, v1
	v_add_f32_e32 v20, v34, v35
	v_lshlrev_b32_e32 v14, 16, v2
	v_and_b32_e32 v15, 0xffff0000, v2
	v_add_f32_e32 v20, v20, v32
	v_mul_f32 v18, v14, v14
	v_mul_f32 v19, v15, v15
	v_add_f32_e32 v20, v33, v20
	v_lshlrev_b32_e32 v2, 16, v3
	v_and_b32_e32 v3, 0xffff0000, v3
	v_add_f32_e32 v18, v18, v20
	v_mul_f32 v16, v2, v2
	v_mul_f32 v17, v3, v3
	v_add_f32_e32 v18, v19, v18
	v_add_f32_e32 v16, v16, v18
	v_add_f32_e32 v16, v17, v16
	v_ashrrev_i32_e32 v31, 31, v30
	v_cmp_gt_i32_e64 s[4:5], s18, v30
	v_add_f32_dpp v16, v16, v16 quad_perm:[1,0,3,2] row_mask:0xf bank_mask:0xf bound_ctrl:1
	s_nop 1
	v_add_f32_dpp v16, v16, v16 quad_perm:[2,3,0,1] row_mask:0xf bank_mask:0xf bound_ctrl:1
	s_nop 1
	v_add_f32_dpp v16, v16, v16 row_half_mirror row_mask:0xf bank_mask:0xf bound_ctrl:1
	s_nop 1
	v_add_f32_dpp v16, v16, v16 row_mirror row_mask:0xf bank_mask:0xf bound_ctrl:1
	v_fmamk_f32 v16, v16, 0x3c000000, v41
	v_mul_f32_e32 v17, 0x4b800000, v16
	v_cmp_gt_f32_e32 vcc, s19, v16
	s_nop 1
	v_cndmask_b32_e32 v16, v16, v17, vcc
	v_rsq_f32_e32 v18, v16
	v_lshlrev_b64 v[16:17], 8, v[30:31]
	v_mul_f32_e32 v19, 0x45800000, v18
	v_cndmask_b32_e32 v18, v18, v19, vcc
	v_mul_f32 v12, v18, v12
	v_mul_f32 v13, v18, v13
	v_mul_f32 v0, v18, v0
	v_mul_f32 v1, v18, v1
	v_mul_f32 v14, v18, v14
	v_mul_f32 v15, v18, v15
	v_mul_f32 v2, v18, v2
	v_mul_f32 v3, v18, v3
	s_waitcnt vmcnt(0)
	v_mul_f32 v4, v4, v12
	v_mul_f32 v5, v5, v13
	v_mul_f32 v6, v6, v0
	v_mul_f32 v7, v7, v1
	v_mul_f32 v0, v8, v14
	v_mul_f32 v1, v9, v15
	v_mul_f32 v2, v10, v2
	v_mul_f32 v3, v11, v3
	v_cvt_pk_bf16_f32 v8, v4, v5
	v_cvt_pk_bf16_f32 v9, v6, v7
	v_cvt_pk_bf16_f32 v10, v0, v1
	v_cvt_pk_bf16_f32 v11, v2, v3
	v_lshl_add_u64 v[12:13], v[22:23], 0, v[16:17]
	flat_store_dwordx4 v[12:13], v[8:11]
	s_and_saveexec_b64 s[10:11], s[4:5]
	s_cbranch_execz .LBB0_488
	v_ashrrev_i32_e32 v8, 11, v43
	v_and_b32_e32 v8, -2, v8
	v_ashrrev_i32_e32 v9, 31, v8
	v_lshlrev_b64 v[8:9], 17, v[8:9]
	v_lshlrev_b32_e32 v10, 9, v30
	v_lshl_add_u64 v[8:9], s[8:9], 0, v[8:9]
	v_and_b32_e32 v20, 0x1fe00, v10
	v_lshl_add_u64 v[8:9], v[8:9], 0, v[20:21]
	v_mov_b32_e32 v29, v21
	v_lshl_add_u64 v[8:9], v[8:9], 0, v[28:29]
	flat_store_dwordx4 v[8:9], v[4:7]
	flat_store_dwordx4 v[8:9], v[0:3] offset:16
	s_branch .LBB0_488

.LBB0_501:
	v_ashrrev_i32_e32 v24, 4, v26
	v_mad_i64_i32 v[0:1], s[10:11], v24, s16, v[18:19]
	flat_load_dwordx4 v[4:7], v[0:1] offset:768
	global_load_dwordx4 v[8:11], v[16:17], off
	global_load_dwordx4 v[30:33], v[16:17], off offset:16
	v_lshl_add_u32 v28, s4, 9, v50
	v_ashrrev_i32_e32 v22, 4, v28
	v_mad_i64_i32 v[0:1], s[4:5], v22, s16, v[18:19]
	flat_load_dwordx4 v[0:3], v[0:1] offset:768
	v_ashrrev_i32_e32 v25, 31, v24
	v_cmp_gt_i32_e64 s[4:5], s17, v24
	s_waitcnt vmcnt(0) lgkmcnt(0)
	v_lshlrev_b32_e32 v34, 16, v4
	v_and_b32_e32 v35, 0xffff0000, v4
	v_lshlrev_b32_e32 v4, 16, v5
	v_and_b32_e32 v5, 0xffff0000, v5
	v_mul_f32 v46, v34, v34
	v_mul_f32 v47, v35, v35
	v_mul_f32 v44, v4, v4
	v_mul_f32 v45, v5, v5
	v_add_f32_e32 v12, v46, v47
	v_lshlrev_b32_e32 v36, 16, v6
	v_and_b32_e32 v37, 0xffff0000, v6
	v_add_f32_e32 v12, v12, v44
	v_mul_f32 v40, v36, v36
	v_mul_f32 v41, v37, v37
	v_add_f32_e32 v12, v45, v12
	v_lshlrev_b32_e32 v6, 16, v7
	v_and_b32_e32 v7, 0xffff0000, v7
	v_add_f32_e32 v12, v40, v12
	v_mul_f32 v38, v6, v6
	v_mul_f32 v39, v7, v7
	v_add_f32_e32 v12, v41, v12
	v_add_f32_e32 v12, v38, v12
	v_add_f32_e32 v12, v39, v12
	v_lshlrev_b64 v[38:39], 8, v[24:25]
	s_nop 0
	v_add_f32_dpp v12, v12, v12 quad_perm:[1,0,3,2] row_mask:0xf bank_mask:0xf bound_ctrl:1
	s_nop 1
	v_add_f32_dpp v12, v12, v12 quad_perm:[2,3,0,1] row_mask:0xf bank_mask:0xf bound_ctrl:1
	s_nop 1
	v_add_f32_dpp v12, v12, v12 row_half_mirror row_mask:0xf bank_mask:0xf bound_ctrl:1
	s_nop 1
	v_add_f32_dpp v12, v12, v12 row_mirror row_mask:0xf bank_mask:0xf bound_ctrl:1
	v_fmamk_f32 v12, v12, 0x3c000000, v27
	v_mul_f32_e32 v21, 0x4b800000, v12
	v_cmp_gt_f32_e32 vcc, s18, v12
	s_nop 1
	v_cndmask_b32_e32 v12, v12, v21, vcc
	v_rsq_f32_e32 v12, v12
	s_nop 0
	v_mul_f32_e32 v21, 0x45800000, v12
	v_cndmask_b32_e32 v12, v12, v21, vcc
	v_mul_f32 v34, v12, v34
	v_mul_f32 v35, v12, v35
	v_mul_f32 v4, v12, v4
	v_mul_f32 v5, v12, v5
	v_mul_f32 v36, v12, v36
	v_mul_f32 v37, v12, v37
	v_mul_f32 v6, v12, v6
	v_mul_f32 v7, v12, v7
	v_mul_f32 v8, v8, v34
	v_mul_f32 v9, v9, v35
	v_mul_f32 v10, v10, v4
	v_mul_f32 v11, v11, v5
	v_mul_f32 v4, v30, v36
	v_mul_f32 v5, v31, v37
	v_mul_f32 v6, v32, v6
	v_mul_f32 v7, v33, v7
	v_cvt_pk_bf16_f32 v30, v8, v9
	v_cvt_pk_bf16_f32 v31, v10, v11
	v_cvt_pk_bf16_f32 v32, v4, v5
	v_cvt_pk_bf16_f32 v33, v6, v7
	v_lshl_add_u64 v[34:35], v[14:15], 0, v[38:39]
	flat_store_dwordx4 v[34:35], v[30:33]
	s_and_saveexec_b64 s[10:11], s[4:5]
	s_cbranch_execz .LBB0_503
	v_ashrrev_i32_e32 v12, 11, v26
	v_and_b32_e32 v30, -2, v12
	v_ashrrev_i32_e32 v31, 31, v30
	v_lshlrev_b64 v[30:31], 17, v[30:31]
	v_lshlrev_b32_e32 v12, 9, v24
	v_lshl_add_u64 v[30:31], s[8:9], 0, v[30:31]
	v_and_b32_e32 v12, 0x1fe00, v12
	v_lshl_add_u64 v[24:25], v[30:31], 0, v[12:13]
	v_mov_b32_e32 v21, v13
	v_lshl_add_u64 v[24:25], v[24:25], 0, v[20:21]
	flat_store_dwordx4 v[24:25], v[8:11]
	flat_store_dwordx4 v[24:25], v[4:7] offset:16
.LBB0_503:
	s_or_b64 exec, exec, s[10:11]
	global_load_dwordx4 v[4:7], v[16:17], off
	global_load_dwordx4 v[8:11], v[16:17], off offset:16
	v_lshlrev_b32_e32 v24, 16, v0
	v_and_b32_e32 v25, 0xffff0000, v0
	v_lshlrev_b32_e32 v0, 16, v1
	v_and_b32_e32 v1, 0xffff0000, v1
	v_mul_f32 v38, v24, v24
	v_mul_f32 v39, v25, v25
	v_mul_f32 v36, v0, v0
	v_mul_f32 v37, v1, v1
	v_add_f32_e32 v12, v38, v39
	v_lshlrev_b32_e32 v30, 16, v2
	v_and_b32_e32 v31, 0xffff0000, v2
	v_add_f32_e32 v12, v12, v36
	v_mul_f32 v34, v30, v30
	v_mul_f32 v35, v31, v31
	v_add_f32_e32 v12, v37, v12
	v_lshlrev_b32_e32 v2, 16, v3
	v_and_b32_e32 v3, 0xffff0000, v3
	v_add_f32_e32 v12, v34, v12
	v_mul_f32 v32, v2, v2
	v_mul_f32 v33, v3, v3
	v_add_f32_e32 v12, v35, v12
	v_add_f32_e32 v12, v32, v12
	v_add_f32_e32 v12, v33, v12
	v_ashrrev_i32_e32 v23, 31, v22
	v_lshlrev_b64 v[32:33], 8, v[22:23]
	v_add_f32_dpp v12, v12, v12 quad_perm:[1,0,3,2] row_mask:0xf bank_mask:0xf bound_ctrl:1
	v_cmp_gt_i32_e64 s[4:5], s17, v22
	s_nop 0
	v_add_f32_dpp v12, v12, v12 quad_perm:[2,3,0,1] row_mask:0xf bank_mask:0xf bound_ctrl:1
	s_nop 1
	v_add_f32_dpp v12, v12, v12 row_half_mirror row_mask:0xf bank_mask:0xf bound_ctrl:1
	s_nop 1
	v_add_f32_dpp v12, v12, v12 row_mirror row_mask:0xf bank_mask:0xf bound_ctrl:1
	v_fmamk_f32 v12, v12, 0x3c000000, v27
	v_mul_f32_e32 v21, 0x4b800000, v12
	v_cmp_gt_f32_e32 vcc, s18, v12
	s_nop 1
	v_cndmask_b32_e32 v12, v12, v21, vcc
	v_rsq_f32_e32 v12, v12
	s_nop 0
	v_mul_f32_e32 v21, 0x45800000, v12
	v_cndmask_b32_e32 v12, v12, v21, vcc
	v_mul_f32 v24, v12, v24
	v_mul_f32 v25, v12, v25
	v_mul_f32 v0, v12, v0
	v_mul_f32 v1, v12, v1
	v_mul_f32 v30, v12, v30
	v_mul_f32 v31, v12, v31
	v_mul_f32 v2, v12, v2
	v_mul_f32 v3, v12, v3
	s_waitcnt vmcnt(0)
	v_mul_f32 v4, v4, v24
	v_mul_f32 v5, v5, v25
	v_mul_f32 v6, v6, v0
	v_mul_f32 v7, v7, v1
	v_mul_f32 v0, v8, v30
	v_mul_f32 v1, v9, v31
	v_mul_f32 v2, v10, v2
	v_mul_f32 v3, v11, v3
	v_cvt_pk_bf16_f32 v8, v4, v5
	v_cvt_pk_bf16_f32 v9, v6, v7
	v_cvt_pk_bf16_f32 v10, v0, v1
	v_cvt_pk_bf16_f32 v11, v2, v3
	v_lshl_add_u64 v[24:25], v[14:15], 0, v[32:33]
	flat_store_dwordx4 v[24:25], v[8:11]
	s_and_saveexec_b64 s[10:11], s[4:5]
	s_cbranch_execz .LBB0_500
	v_ashrrev_i32_e32 v8, 11, v28
	v_and_b32_e32 v8, -2, v8
	v_ashrrev_i32_e32 v9, 31, v8
	v_lshlrev_b64 v[8:9], 17, v[8:9]
	v_lshlrev_b32_e32 v10, 9, v22
	v_lshl_add_u64 v[8:9], s[8:9], 0, v[8:9]
	v_and_b32_e32 v12, 0x1fe00, v10
	v_lshl_add_u64 v[8:9], v[8:9], 0, v[12:13]
	v_mov_b32_e32 v21, v13
	v_lshl_add_u64 v[8:9], v[8:9], 0, v[20:21]
	flat_store_dwordx4 v[8:9], v[4:7]
	flat_store_dwordx4 v[8:9], v[0:3] offset:16
	s_branch .LBB0_500

.LBB0_508:
	v_ashrrev_i32_e32 v18, 4, v20
	v_mad_i64_i32 v[26:27], s[4:5], v18, s11, v[14:15]
	flat_load_dwordx4 v[0:3], v[26:27] offset:768
	global_load_dwordx4 v[4:7], v[12:13], off
	global_load_dwordx4 v[22:25], v[12:13], off offset:16
	v_ashrrev_i32_e32 v19, 31, v18
	v_cmp_gt_i32_e64 s[4:5], s12, v18
	s_waitcnt vmcnt(0) lgkmcnt(0)
	v_lshlrev_b32_e32 v26, 16, v0
	v_and_b32_e32 v27, 0xffff0000, v0
	v_lshlrev_b32_e32 v0, 16, v1
	v_and_b32_e32 v1, 0xffff0000, v1
	v_mul_f32 v36, v26, v26
	v_mul_f32 v37, v27, v27
	v_mul_f32 v34, v0, v0
	v_mul_f32 v35, v1, v1
	v_add_f32_e32 v8, v36, v37
	v_lshlrev_b32_e32 v28, 16, v2
	v_and_b32_e32 v29, 0xffff0000, v2
	v_add_f32_e32 v8, v8, v34
	v_mul_f32 v32, v28, v28
	v_mul_f32 v33, v29, v29
	v_add_f32_e32 v8, v35, v8
	v_lshlrev_b32_e32 v2, 16, v3
	v_and_b32_e32 v3, 0xffff0000, v3
	v_add_f32_e32 v8, v32, v8
	v_mul_f32 v30, v2, v2
	v_mul_f32 v31, v3, v3
	v_add_f32_e32 v8, v33, v8
	v_add_f32_e32 v8, v30, v8
	v_add_f32_e32 v8, v31, v8
	v_lshlrev_b64 v[30:31], 8, v[18:19]
	s_nop 0
	v_add_f32_dpp v8, v8, v8 quad_perm:[1,0,3,2] row_mask:0xf bank_mask:0xf bound_ctrl:1
	s_nop 1
	v_add_f32_dpp v8, v8, v8 quad_perm:[2,3,0,1] row_mask:0xf bank_mask:0xf bound_ctrl:1
	s_nop 1
	v_add_f32_dpp v8, v8, v8 row_half_mirror row_mask:0xf bank_mask:0xf bound_ctrl:1
	s_nop 1
	v_add_f32_dpp v8, v8, v8 row_mirror row_mask:0xf bank_mask:0xf bound_ctrl:1
	v_fmamk_f32 v8, v8, 0x3c000000, v21
	v_mul_f32_e32 v17, 0x4b800000, v8
	v_cmp_gt_f32_e32 vcc, s13, v8
	s_nop 1
	v_cndmask_b32_e32 v8, v8, v17, vcc
	v_rsq_f32_e32 v8, v8
	s_nop 0
	v_mul_f32_e32 v17, 0x45800000, v8
	v_cndmask_b32_e32 v8, v8, v17, vcc
	v_mul_f32 v26, v8, v26
	v_mul_f32 v27, v8, v27
	v_mul_f32 v0, v8, v0
	v_mul_f32 v1, v8, v1
	v_mul_f32 v28, v8, v28
	v_mul_f32 v29, v8, v29
	v_mul_f32 v2, v8, v2
	v_mul_f32 v3, v8, v3
	v_mul_f32 v4, v4, v26
	v_mul_f32 v5, v5, v27
	v_mul_f32 v6, v6, v0
	v_mul_f32 v7, v7, v1
	v_mul_f32 v0, v22, v28
	v_mul_f32 v1, v23, v29
	v_mul_f32 v2, v24, v2
	v_mul_f32 v3, v25, v3
	v_cvt_pk_bf16_f32 v22, v4, v5
	v_cvt_pk_bf16_f32 v23, v6, v7
	v_cvt_pk_bf16_f32 v24, v0, v1
	v_cvt_pk_bf16_f32 v25, v2, v3
	v_lshl_add_u64 v[26:27], v[10:11], 0, v[30:31]
	flat_store_dwordx4 v[26:27], v[22:25]
	s_and_saveexec_b64 s[8:9], s[4:5]
	s_cbranch_execz .LBB0_507
	v_ashrrev_i32_e32 v8, 11, v20
	v_and_b32_e32 v22, -2, v8
	v_ashrrev_i32_e32 v23, 31, v22
	v_lshlrev_b64 v[22:23], 17, v[22:23]
	v_lshlrev_b32_e32 v8, 9, v18
	v_lshl_add_u64 v[22:23], s[6:7], 0, v[22:23]
	v_and_b32_e32 v8, 0x1fe00, v8
	v_lshl_add_u64 v[18:19], v[22:23], 0, v[8:9]
	v_mov_b32_e32 v17, v9
	v_lshl_add_u64 v[18:19], v[18:19], 0, v[16:17]
	flat_store_dwordx4 v[18:19], v[4:7]
	flat_store_dwordx4 v[18:19], v[0:3] offset:16
	s_branch .LBB0_507

.LBB0_619:
	v_cmp_ne_u64_e64 s[8:9], 0, v[32:33]
	s_and_saveexec_b64 s[12:13], s[8:9]
	s_cbranch_execz .LBB0_621
	flat_load_dwordx4 v[52:55], v[32:33]
	s_nop 0
	flat_load_dwordx4 v[30:33], v[32:33] offset:16
	s_waitcnt vmcnt(0)
	v_lshlrev_b32_e32 v18, 16, v12
	v_and_b32_e32 v12, 0xffff0000, v12
	v_and_b32_e32 v34, 0xffff0000, v13
	v_lshlrev_b32_e32 v56, 16, v14
	v_and_b32_e32 v14, 0xffff0000, v14
	v_and_b32_e32 v60, 0xffff0000, v15
	v_lshlrev_b32_e32 v26, 16, v13
	v_lshlrev_b32_e32 v58, 16, v15
	s_waitcnt lgkmcnt(0)
	v_mul_f32 v13, v52, v12
	v_mul_f32 v12, v53, v12
	v_mul_f32 v35, v54, v34
	v_mul_f32 v34, v55, v34
	v_mul_f32 v15, v30, v14
	v_mul_f32 v14, v31, v14
	v_mul_f32 v61, v32, v60
	v_mul_f32 v60, v33, v60
	v_fma_f32 v62, v52, v18, -v12
	v_fma_f32 v63, v53, v19, -v13
	v_fma_f32 v12, v52, v18, v12
	v_fma_f32 v13, v53, v18, v13
	v_fma_f32 v52, v54, v26, -v34
	v_fma_f32 v53, v55, v27, -v35
	v_fma_f32 v27, v55, v26, v35
	v_fma_f32 v26, v54, v26, v34
	v_fma_f32 v34, v30, v56, -v14
	v_fma_f32 v35, v31, v57, -v15
	v_fma_f32 v14, v30, v56, v14
	v_fma_f32 v15, v31, v56, v15
	v_fma_f32 v30, v32, v58, -v60
	v_fma_f32 v31, v33, v59, -v61
	v_fma_f32 v32, v32, v58, v60
	v_fma_f32 v33, v33, v58, v61
	v_cvt_pk_bf16_f32 v12, v62, v13
	v_cvt_pk_bf16_f32 v13, v52, v27
	v_cvt_pk_bf16_f32 v14, v34, v15
	v_cvt_pk_bf16_f32 v15, v30, v33

.LBB0_647:
	v_cmp_ne_u64_e64 s[6:7], 0, v[26:27]
	s_and_saveexec_b64 s[10:11], s[6:7]
	s_cbranch_execz .LBB0_649
	flat_load_dwordx4 v[28:31], v[26:27]
	s_nop 0
	flat_load_dwordx4 v[24:27], v[26:27] offset:16
	v_lshlrev_b32_e32 v14, 16, v8
	v_and_b32_e32 v8, 0xffff0000, v8
	v_and_b32_e32 v32, 0xffff0000, v9
	v_lshlrev_b32_e32 v34, 16, v10
	v_and_b32_e32 v10, 0xffff0000, v10
	v_and_b32_e32 v52, 0xffff0000, v11
	v_lshlrev_b32_e32 v18, 16, v9
	v_lshlrev_b32_e32 v48, 16, v11
	s_waitcnt vmcnt(0) lgkmcnt(0)
	v_mul_f32 v9, v28, v8
	v_mul_f32 v8, v29, v8
	v_mul_f32 v33, v30, v32
	v_mul_f32 v32, v31, v32
	v_mul_f32 v11, v24, v10
	v_mul_f32 v10, v25, v10
	v_mul_f32 v53, v26, v52
	v_mul_f32 v52, v27, v52
	v_fma_f32 v54, v28, v14, -v8
	v_fma_f32 v55, v29, v15, -v9
	v_fma_f32 v8, v28, v14, v8
	v_fma_f32 v9, v29, v14, v9
	v_fma_f32 v14, v30, v18, -v32
	v_fma_f32 v15, v31, v19, -v33
	v_fma_f32 v28, v30, v18, v32
	v_fma_f32 v29, v31, v18, v33
	v_fma_f32 v30, v24, v34, -v10
	v_fma_f32 v31, v25, v35, -v11
	v_fma_f32 v10, v24, v34, v10
	v_fma_f32 v11, v25, v34, v11
	v_fma_f32 v24, v26, v48, -v52
	v_fma_f32 v25, v27, v49, -v53
	v_fma_f32 v26, v26, v48, v52
	v_fma_f32 v27, v27, v48, v53
	v_cvt_pk_bf16_f32 v8, v54, v9
	v_cvt_pk_bf16_f32 v9, v14, v29
	v_cvt_pk_bf16_f32 v10, v30, v11
	v_cvt_pk_bf16_f32 v11, v24, v27

.LBB0_675:
	v_cmp_ne_u64_e64 s[4:5], 0, v[12:13]
	s_and_saveexec_b64 s[8:9], s[4:5]
	s_cbranch_execz .LBB0_677
	flat_load_dwordx4 v[22:25], v[12:13]
	s_nop 0
	flat_load_dwordx4 v[10:13], v[12:13] offset:16
	s_waitcnt lgkmcnt(0)
	v_lshlrev_b32_e32 v14, 16, v4
	v_and_b32_e32 v4, 0xffff0000, v4
	v_and_b32_e32 v26, 0xffff0000, v5
	v_lshlrev_b32_e32 v28, 16, v6
	v_and_b32_e32 v6, 0xffff0000, v6
	v_and_b32_e32 v32, 0xffff0000, v7
	v_lshlrev_b32_e32 v18, 16, v5
	v_lshlrev_b32_e32 v30, 16, v7
	s_waitcnt vmcnt(0)
	v_mul_f32 v5, v22, v4
	v_mul_f32 v4, v23, v4
	v_mul_f32 v27, v24, v26
	v_mul_f32 v26, v25, v26
	v_mul_f32 v7, v10, v6
	v_mul_f32 v6, v11, v6
	v_mul_f32 v33, v12, v32
	v_mul_f32 v32, v13, v32
	v_fma_f32 v34, v22, v14, -v4
	v_fma_f32 v35, v23, v15, -v5
	v_fma_f32 v4, v22, v14, v4
	v_fma_f32 v5, v23, v14, v5
	v_fma_f32 v14, v24, v18, -v26
	v_fma_f32 v15, v25, v19, -v27
	v_fma_f32 v22, v24, v18, v26
	v_fma_f32 v23, v25, v18, v27
	v_fma_f32 v24, v10, v28, -v6
	v_fma_f32 v25, v11, v29, -v7
	v_fma_f32 v6, v10, v28, v6
	v_fma_f32 v7, v11, v28, v7
	v_fma_f32 v10, v12, v30, -v32
	v_fma_f32 v11, v13, v31, -v33
	v_fma_f32 v12, v12, v30, v32
	v_fma_f32 v13, v13, v30, v33
	v_cvt_pk_bf16_f32 v4, v34, v5
	v_cvt_pk_bf16_f32 v5, v14, v23
	v_cvt_pk_bf16_f32 v6, v24, v7
	v_cvt_pk_bf16_f32 v7, v10, v13

.LBB0_703:
	v_cmp_ne_u64_e32 vcc, 0, v[8:9]
	s_and_saveexec_b64 s[6:7], vcc
	s_cbranch_execz .LBB0_512
	flat_load_dwordx4 v[10:13], v[8:9]
	s_nop 0
	flat_load_dwordx4 v[6:9], v[8:9] offset:16
	v_lshlrev_b32_e32 v14, 16, v0
	v_and_b32_e32 v0, 0xffff0000, v0
	v_and_b32_e32 v20, 0xffff0000, v1
	v_lshlrev_b32_e32 v22, 16, v2
	v_and_b32_e32 v2, 0xffff0000, v2
	v_and_b32_e32 v26, 0xffff0000, v3
	v_lshlrev_b32_e32 v18, 16, v1
	v_lshlrev_b32_e32 v24, 16, v3
	s_waitcnt vmcnt(0) lgkmcnt(0)
	v_mul_f32 v1, v10, v0
	v_mul_f32 v0, v11, v0
	v_mul_f32 v21, v12, v20
	v_mul_f32 v20, v13, v20
	v_mul_f32 v3, v6, v2
	v_mul_f32 v2, v7, v2
	v_mul_f32 v27, v8, v26
	v_mul_f32 v26, v9, v26
	v_fma_f32 v28, v10, v14, -v0
	v_fma_f32 v29, v11, v15, -v1
	v_fma_f32 v0, v10, v14, v0
	v_fma_f32 v1, v11, v14, v1
	v_fma_f32 v10, v12, v18, -v20
	v_fma_f32 v11, v13, v19, -v21
	v_fma_f32 v12, v12, v18, v20
	v_fma_f32 v13, v13, v18, v21
	v_fma_f32 v14, v6, v22, -v2
	v_fma_f32 v15, v7, v23, -v3
	v_fma_f32 v2, v6, v22, v2
	v_fma_f32 v3, v7, v22, v3
	v_fma_f32 v6, v8, v24, -v26
	v_fma_f32 v7, v9, v25, -v27
	v_fma_f32 v8, v8, v24, v26
	v_fma_f32 v9, v9, v24, v27
	v_cvt_pk_bf16_f32 v0, v28, v1
	v_cvt_pk_bf16_f32 v1, v10, v13
	v_cvt_pk_bf16_f32 v2, v14, v3
	v_cvt_pk_bf16_f32 v3, v6, v9
	s_branch .LBB0_512

.LBB0_775:
	v_cmp_ne_u64_e64 s[4:5], 0, v[26:27]
	s_and_saveexec_b64 s[8:9], s[4:5]
	s_cbranch_execz .LBB0_777
	flat_load_dwordx4 v[44:47], v[26:27]
	s_nop 0
	flat_load_dwordx4 v[24:27], v[26:27] offset:16
	s_waitcnt vmcnt(0) lgkmcnt(0)
	v_lshlrev_b32_e32 v12, 16, v4
	v_and_b32_e32 v4, 0xffff0000, v4
	v_and_b32_e32 v28, 0xffff0000, v5
	v_lshlrev_b32_e32 v40, 16, v6
	v_and_b32_e32 v6, 0xffff0000, v6
	v_and_b32_e32 v52, 0xffff0000, v7
	v_lshlrev_b32_e32 v20, 16, v5
	v_lshlrev_b32_e32 v48, 16, v7
	v_mul_f32 v5, v44, v4
	v_mul_f32 v4, v45, v4
	v_mul_f32 v29, v46, v28
	v_mul_f32 v28, v47, v28
	v_mul_f32 v7, v24, v6
	v_mul_f32 v6, v25, v6
	v_mul_f32 v53, v26, v52
	v_mul_f32 v52, v27, v52
	v_fma_f32 v54, v44, v12, -v4
	v_fma_f32 v55, v45, v13, -v5
	v_fma_f32 v4, v44, v12, v4
	v_fma_f32 v5, v45, v12, v5
	v_fma_f32 v44, v46, v20, -v28
	v_fma_f32 v45, v47, v21, -v29
	v_fma_f32 v21, v47, v20, v29
	v_fma_f32 v20, v46, v20, v28
	v_fma_f32 v28, v24, v40, -v6
	v_fma_f32 v29, v25, v41, -v7
	v_fma_f32 v6, v24, v40, v6
	v_fma_f32 v7, v25, v40, v7
	v_fma_f32 v24, v26, v48, -v52
	v_fma_f32 v25, v27, v49, -v53
	v_fma_f32 v26, v26, v48, v52
	v_fma_f32 v27, v27, v48, v53
	v_cvt_pk_bf16_f32 v4, v54, v5
	v_cvt_pk_bf16_f32 v5, v44, v21
	v_cvt_pk_bf16_f32 v6, v28, v7
	v_cvt_pk_bf16_f32 v7, v24, v27

.LBB0_803:
	v_cmp_ne_u64_e32 vcc, 0, v[18:19]
	s_and_saveexec_b64 s[6:7], vcc
	s_cbranch_execz .LBB0_708
	flat_load_dwordx4 v[14:17], v[18:19]
	s_nop 0
	flat_load_dwordx4 v[18:21], v[18:19] offset:16
	v_lshlrev_b32_e32 v6, 16, v0
	v_and_b32_e32 v0, 0xffff0000, v0
	v_and_b32_e32 v22, 0xffff0000, v1
	v_lshlrev_b32_e32 v24, 16, v2
	v_and_b32_e32 v2, 0xffff0000, v2
	v_and_b32_e32 v28, 0xffff0000, v3
	v_lshlrev_b32_e32 v12, 16, v1
	v_lshlrev_b32_e32 v26, 16, v3
	s_waitcnt vmcnt(0) lgkmcnt(0)
	v_mul_f32 v1, v14, v0
	v_mul_f32 v0, v15, v0
	v_mul_f32 v23, v16, v22
	v_mul_f32 v22, v17, v22
	v_mul_f32 v3, v18, v2
	v_mul_f32 v2, v19, v2
	v_mul_f32 v29, v20, v28
	v_mul_f32 v28, v21, v28
	v_fma_f32 v40, v14, v6, -v0
	v_fma_f32 v41, v15, v7, -v1
	v_fma_f32 v0, v14, v6, v0
	v_fma_f32 v1, v15, v6, v1
	v_fma_f32 v6, v16, v12, -v22
	v_fma_f32 v7, v17, v13, -v23
	v_fma_f32 v14, v16, v12, v22
	v_fma_f32 v15, v17, v12, v23
	v_fma_f32 v16, v18, v24, -v2
	v_fma_f32 v17, v19, v25, -v3
	v_fma_f32 v2, v18, v24, v2
	v_fma_f32 v3, v19, v24, v3
	v_fma_f32 v18, v20, v26, -v28
	v_fma_f32 v19, v21, v27, -v29
	v_fma_f32 v20, v20, v26, v28
	v_fma_f32 v21, v21, v26, v29
	v_cvt_pk_bf16_f32 v0, v40, v1
	v_cvt_pk_bf16_f32 v1, v6, v15
	v_cvt_pk_bf16_f32 v2, v16, v3
	v_cvt_pk_bf16_f32 v3, v18, v21
	s_branch .LBB0_708

.LBB0_854:
	v_cmp_ne_u64_e32 vcc, 0, v[16:17]
	s_and_saveexec_b64 s[6:7], vcc
	s_cbranch_execz .LBB0_807
	flat_load_dwordx4 v[12:15], v[16:17]
	s_nop 0
	flat_load_dwordx4 v[16:19], v[16:17] offset:16
	s_waitcnt vmcnt(0) lgkmcnt(0)
	v_lshlrev_b32_e32 v8, 16, v0
	v_and_b32_e32 v0, 0xffff0000, v0
	v_and_b32_e32 v30, 0xffff0000, v1
	v_lshlrev_b32_e32 v32, 16, v2
	v_and_b32_e32 v2, 0xffff0000, v2
	v_and_b32_e32 v36, 0xffff0000, v3
	v_lshlrev_b32_e32 v28, 16, v1
	v_lshlrev_b32_e32 v34, 16, v3
	v_mul_f32 v1, v12, v0
	v_mul_f32 v0, v13, v0
	v_mul_f32 v31, v14, v30
	v_mul_f32 v30, v15, v30
	v_mul_f32 v3, v16, v2
	v_mul_f32 v2, v17, v2
	v_mul_f32 v37, v18, v36
	v_mul_f32 v36, v19, v36
	v_fma_f32 v38, v12, v8, -v0
	v_fma_f32 v39, v13, v9, -v1
	v_fma_f32 v0, v12, v8, v0
	v_fma_f32 v1, v13, v8, v1
	v_fma_f32 v12, v14, v28, -v30
	v_fma_f32 v13, v15, v29, -v31
	v_fma_f32 v14, v14, v28, v30
	v_fma_f32 v15, v15, v28, v31
	v_fma_f32 v28, v16, v32, -v2
	v_fma_f32 v29, v17, v33, -v3
	v_fma_f32 v2, v16, v32, v2
	v_fma_f32 v3, v17, v32, v3
	v_fma_f32 v16, v18, v34, -v36
	v_fma_f32 v17, v19, v35, -v37
	v_fma_f32 v18, v18, v34, v36
	v_fma_f32 v19, v19, v34, v37
	v_cvt_pk_bf16_f32 v0, v38, v1
	v_cvt_pk_bf16_f32 v1, v12, v15
	v_cvt_pk_bf16_f32 v2, v28, v3
	v_cvt_pk_bf16_f32 v3, v16, v19
	s_branch .LBB0_807

.LBB0_858:
	v_add_u32_e32 v18, s39, v53
	v_mad_i64_i32 v[22:23], s[4:5], v18, s54, v[16:17]
	s_waitcnt lgkmcnt(0)
	global_load_dwordx4 v[8:11], v51, s[56:57] offset:16
	global_load_dwordx4 v[0:3], v51, s[58:59] offset:16
	global_load_dwordx4 v[12:15], v51, s[56:57]
	global_load_dwordx4 v[4:7], v51, s[58:59]
	v_add_co_u32_e32 v36, vcc, 0x1000, v22
	v_add_u32_e32 v20, s2, v53
	s_nop 0
	v_addc_co_u32_e32 v37, vcc, 0, v23, vcc
	v_mad_i64_i32 v[34:35], s[4:5], v20, s54, v[16:17]
	flat_load_dwordx4 v[26:29], v[36:37] offset:64
	flat_load_dwordx4 v[30:33], v[36:37] offset:80
	v_add_co_u32_e32 v42, vcc, s55, v34
	s_add_i32 s3, s3, s33
	s_nop 0
	v_addc_co_u32_e32 v43, vcc, 0, v35, vcc
	flat_load_dwordx4 v[34:37], v[42:43] offset:64
	flat_load_dwordx4 v[38:41], v[42:43] offset:80
	s_add_i32 s4, s76, s3
	s_cmp_gt_i32 s4, 23
	v_ashrrev_i32_e32 v19, 31, v18
	v_lshlrev_b64 v[18:19], 5, v[18:19]
	v_lshl_add_u64 v[24:25], s[70:71], 0, v[18:19]
	v_lshl_add_u64 v[22:23], s[72:73], 0, v[18:19]
	v_ashrrev_i32_e32 v21, 31, v20
	v_lshlrev_b64 v[20:21], 5, v[20:21]
	v_lshl_add_u64 v[18:19], s[70:71], 0, v[20:21]
	v_lshl_add_u64 v[20:21], s[72:73], 0, v[20:21]
	v_add_u32_e32 v53, s38, v53
	s_waitcnt vmcnt(0)
	v_mul_f32_e32 v8, 0x3fb8aa3b, v8
	v_mul_f32_e32 v9, 0x3fb8aa3b, v9
	v_mul_f32_e32 v12, 0x3fb8aa3b, v12
	v_mul_f32_e32 v14, 0x3fb8aa3b, v14
	v_mul_f32_e32 v13, 0x3fb8aa3b, v13
	v_mul_f32_e32 v15, 0x3fb8aa3b, v15
	v_mul_f32_e32 v10, 0x3fb8aa3b, v10
	v_mul_f32_e32 v11, 0x3fb8aa3b, v11
	v_exp_f32_e32 v42, v12
	v_exp_f32_e32 v44, v14
	v_exp_f32_e32 v43, v13
	v_exp_f32_e32 v45, v15
	v_exp_f32_e32 v46, v8
	v_exp_f32_e32 v47, v9
	v_exp_f32_e32 v48, v10
	v_exp_f32_e32 v49, v11
	s_waitcnt lgkmcnt(0)
	v_lshlrev_b32_e32 v8, 16, v26
	v_and_b32_e32 v9, 0xffff0000, v26
	v_lshlrev_b32_e32 v10, 16, v27
	v_and_b32_e32 v11, 0xffff0000, v27
	v_lshlrev_b32_e32 v14, 16, v30
	v_and_b32_e32 v26, 0xffff0000, v30
	v_lshlrev_b32_e32 v27, 16, v31
	v_lshlrev_b32_e32 v12, 16, v28
	v_and_b32_e32 v13, 0xffff0000, v28
	v_lshlrev_b32_e32 v28, 16, v29
	v_and_b32_e32 v29, 0xffff0000, v29
	v_and_b32_e32 v30, 0xffff0000, v31
	v_lshlrev_b32_e32 v31, 16, v32
	v_and_b32_e32 v32, 0xffff0000, v32
	v_mul_f32_e32 v56, 0xbfb8aa3b, v14
	v_add_f32 v14, v4, v8
	v_add_f32 v15, v5, v9
	v_mul_f32_e32 v57, 0xbfb8aa3b, v26
	v_mul_f32_e32 v58, 0xbfb8aa3b, v27
	v_add_f32 v26, v6, v10
	v_add_f32 v27, v7, v11
	v_lshlrev_b32_e32 v54, 16, v33
	v_and_b32_e32 v55, 0xffff0000, v33
	v_xor_b32_e32 v8, 0x80000000, v42
	v_xor_b32_e32 v10, 0x80000000, v44
	v_mul_f32_e32 v42, 0xbfb8aa3b, v30
	v_mul_f32_e32 v44, 0xbfb8aa3b, v32
	v_add_f32 v32, v2, v28
	v_add_f32 v33, v3, v29
	v_lshlrev_b32_e32 v2, 16, v36
	v_and_b32_e32 v3, 0xffff0000, v36
	v_mul_f32_e32 v62, 0x3fb8aa3b, v15
	v_exp_f32_e32 v36, v58
	v_mul_f32_e32 v58, 0x3fb8aa3b, v27
	v_xor_b32_e32 v9, 0x80000000, v43
	v_xor_b32_e32 v11, 0x80000000, v45
	v_mul_f32_e32 v43, 0xbfb8aa3b, v31
	v_add_f32 v30, v0, v12
	v_add_f32 v31, v1, v13
	v_mul_f32_e32 v45, 0xbfb8aa3b, v54
	v_xor_b32_e32 v13, 0x80000000, v47
	v_xor_b32_e32 v12, 0x80000000, v46
	v_xor_b32_e32 v29, 0x80000000, v49
	v_xor_b32_e32 v28, 0x80000000, v48
	v_mul_f32_e32 v46, 0xbfb8aa3b, v55
	v_lshlrev_b32_e32 v6, 16, v34
	v_and_b32_e32 v7, 0xffff0000, v34
	v_lshlrev_b32_e32 v4, 16, v35
	v_and_b32_e32 v5, 0xffff0000, v35
	v_lshlrev_b32_e32 v0, 16, v37
	v_and_b32_e32 v1, 0xffff0000, v37
	v_lshlrev_b32_e32 v47, 16, v38
	v_and_b32_e32 v48, 0xffff0000, v38
	v_lshlrev_b32_e32 v49, 16, v39
	v_and_b32_e32 v54, 0xffff0000, v39
	v_lshlrev_b32_e32 v55, 16, v40
	v_and_b32_e32 v59, 0xffff0000, v40
	v_lshlrev_b32_e32 v60, 16, v41
	v_and_b32_e32 v61, 0xffff0000, v41
	v_exp_f32_e32 v34, v56
	v_mul_f32_e32 v56, 0x3fb8aa3b, v14
	v_exp_f32_e32 v35, v57
	v_mul_f32_e32 v57, 0x3fb8aa3b, v26
	v_exp_f32_e32 v37, v42
	v_exp_f32_e32 v62, v62
	v_exp_f32_e32 v58, v58
	v_exp_f32_e32 v38, v43
	v_mul_f32_e32 v42, 0x3fb8aa3b, v30
	v_mul_f32_e32 v43, 0x3fb8aa3b, v31
	v_exp_f32_e32 v40, v45
	v_exp_f32_e32 v41, v46
	v_mul_f32_e32 v46, 0xbfb8aa3b, v47
	v_mul_f32_e32 v47, 0xbfb8aa3b, v48
	v_mul_f32_e32 v48, 0xbfb8aa3b, v49
	v_mul_f32_e32 v49, 0xbfb8aa3b, v54
	v_mul_f32_e32 v54, 0xbfb8aa3b, v55
	v_mul_f32_e32 v55, 0xbfb8aa3b, v59
	v_mul_f32_e32 v59, 0xbfb8aa3b, v60
	v_mul_f32_e32 v60, 0xbfb8aa3b, v61
	v_exp_f32_e32 v61, v56
	v_exp_f32_e32 v63, v57
	v_exp_f32_e32 v39, v44
	v_mul_f32_e32 v44, 0x3fb8aa3b, v32
	v_mul_f32_e32 v45, 0x3fb8aa3b, v33
	v_exp_f32_e32 v64, v42
	v_exp_f32_e32 v65, v43
	v_exp_f32_e32 v42, v46
	v_exp_f32_e32 v43, v47
	v_exp_f32_e32 v46, v48
	v_exp_f32_e32 v47, v49
	v_exp_f32_e32 v54, v54
	v_exp_f32_e32 v55, v55
	v_exp_f32_e32 v56, v59
	v_exp_f32_e32 v57, v60
	v_exp_f32_e32 v66, v44
	v_exp_f32_e32 v67, v45
	v_add_f32 v48, v36, 1.0
	v_add_f32 v49, v37, 1.0
	v_add_f32_e32 v60, 1.0, v62
	v_add_f32_e32 v58, 1.0, v58
	v_add_f32 v44, v34, 1.0
	v_add_f32 v45, v35, 1.0
	v_add_f32 v40, v40, 1.0
	v_add_f32 v41, v41, 1.0
	v_add_f32_e32 v59, 1.0, v61
	v_add_f32_e32 v61, 1.0, v63
	v_div_scale_f32 v62, s[4:5], v49, v49, 1.0
	v_cmp_gt_f32_e64 s[40:41], s60, v60
	v_cmp_gt_f32_e64 s[44:45], s60, v58
	v_add_f32 v36, v38, 1.0
	v_add_f32 v37, v39, 1.0
	v_div_scale_f32 v68, s[4:5], v48, v48, 1.0
	v_div_scale_f32 v72, s[4:5], v44, v44, 1.0
	v_div_scale_f32 v74, s[4:5], v41, v41, 1.0
	v_add_f32 v42, v42, 1.0
	v_add_f32 v43, v43, 1.0
	v_add_f32 v46, v46, 1.0
	v_add_f32 v47, v47, 1.0
	v_add_f32 v34, v54, 1.0
	v_add_f32 v35, v55, 1.0
	v_add_f32 v38, v56, 1.0
	v_add_f32 v39, v57, 1.0
	v_cndmask_b32_e64 v55, 0, 32, s[40:41]
	v_cmp_gt_f32_e64 s[42:43], s60, v61
	v_cndmask_b32_e64 v57, 0, 32, s[44:45]
	v_rcp_f32_e32 v82, v62
	v_div_scale_f32 v70, s[4:5], v45, v45, 1.0
	v_add_f32_e32 v64, 1.0, v64
	v_add_f32_e32 v65, 1.0, v65
	v_add_f32_e32 v66, 1.0, v66
	v_add_f32_e32 v67, 1.0, v67
	v_div_scale_f32 v76, s[4:5], v40, v40, 1.0
	v_cmp_gt_f32_e64 s[36:37], s60, v59
	v_cndmask_b32_e64 v56, 0, 32, s[42:43]
	v_rcp_f32_e32 v83, v68
	v_rcp_f32_e32 v85, v72
	v_rcp_f32_e32 v90, v74
	v_div_scale_f32 v96, s[16:17], v46, v46, 1.0
	v_div_scale_f32 v100, s[16:17], v42, v42, 1.0
	v_div_scale_f32 v102, s[16:17], v39, v39, 1.0
	v_ldexp_f32 v55, v60, v55
	v_ldexp_f32 v57, v58, v57
	v_cndmask_b32_e64 v54, 0, 32, s[36:37]
	v_rcp_f32_e32 v84, v70
	v_cmp_gt_f32_e64 s[46:47], s60, v64
	v_cmp_gt_f32_e64 s[48:49], s60, v65
	v_cmp_gt_f32_e64 s[50:51], s60, v66
	v_cmp_gt_f32_e64 s[52:53], s60, v67
	v_rcp_f32_e32 v91, v76
	v_div_scale_f32 v98, s[16:17], v43, v43, 1.0
	v_div_scale_f32 v104, s[16:17], v38, v38, 1.0
	v_ldexp_f32 v56, v61, v56
	v_rcp_f32_e32 v111, v96
	v_rcp_f32_e32 v113, v100
	v_rcp_f32_e32 v114, v102
	v_log_f32_e32 v55, v55
	v_log_f32_e32 v57, v57
	v_div_scale_f32 v78, s[4:5], v37, v37, 1.0
	v_cndmask_b32_e64 v86, 0, 32, s[46:47]
	v_cndmask_b32_e64 v87, 0, 32, s[48:49]
	v_cndmask_b32_e64 v88, 0, 32, s[50:51]
	v_cndmask_b32_e64 v89, 0, 32, s[52:53]
	v_div_scale_f32 v94, s[16:17], v47, v47, 1.0
	v_ldexp_f32 v54, v59, v54
	v_rcp_f32_e32 v112, v98
	v_rcp_f32_e32 v115, v104
	v_log_f32_e32 v56, v56
	v_div_scale_f32 v80, s[4:5], v36, v36, 1.0
	v_rcp_f32_e32 v92, v78
	v_div_scale_f32 v106, s[16:17], v35, v35, 1.0
	v_ldexp_f32 v64, v64, v86
	v_ldexp_f32 v65, v65, v87
	v_ldexp_f32 v66, v66, v88
	v_ldexp_f32 v67, v67, v89
	v_rcp_f32_e32 v110, v94
	v_log_f32_e32 v54, v54
	v_fma_f32 v118, -v62, v82, 1.0
	v_div_scale_f32 v63, vcc, 1.0, v49, 1.0
	v_rcp_f32_e32 v93, v80
	v_div_scale_f32 v108, s[16:17], v34, v34, 1.0
	v_rcp_f32_e32 v116, v106
	v_log_f32_e32 v64, v64
	v_log_f32_e32 v65, v65
	v_log_f32_e32 v66, v66
	v_log_f32_e32 v67, v67
	v_fma_f32 v119, -v68, v83, 1.0
	v_fma_f32 v121, -v72, v85, 1.0
	v_fma_f32 v122, -v74, v90, 1.0
	v_fmac_f32_e32 v82, v118, v82
	v_div_scale_f32 v69, s[30:31], 1.0, v48, 1.0
	v_rcp_f32_e32 v117, v108
	v_fma_f32 v120, -v70, v84, 1.0
	v_fma_f32 v123, -v76, v91, 1.0
	v_fmac_f32_e32 v83, v119, v83
	v_fmac_f32_e32 v85, v121, v85
	v_fmac_f32_e32 v90, v122, v90
	v_fma_f32 v119, -v96, v111, 1.0
	v_fma_f32 v121, -v100, v113, 1.0
	v_fma_f32 v122, -v102, v114, 1.0
	v_mul_f32_e32 v127, 0x3f317217, v55
	v_mul_f32_e32 v129, 0x3f317217, v57
	v_mul_f32_e32 v130, v63, v82
	v_fmac_f32_e32 v84, v120, v84
	v_fmac_f32_e32 v91, v123, v91
	v_fma_f32 v120, -v98, v112, 1.0
	v_fma_f32 v123, -v104, v115, 1.0
	v_mul_f32_e32 v128, 0x3f317217, v56
	v_mul_f32_e32 v131, v69, v83
	v_fmac_f32_e32 v111, v119, v111
	v_fmac_f32_e32 v113, v121, v113
	v_fmac_f32_e32 v114, v122, v114
	v_fma_f32 v119, v55, s61, -v127
	v_fma_f32 v121, v57, s61, -v129
	v_fma_f32 v122, -v62, v130, v63
	v_div_scale_f32 v71, s[14:15], 1.0, v45, 1.0
	v_fma_f32 v124, -v78, v92, 1.0
	v_fma_f32 v118, -v94, v110, 1.0
	v_mul_f32_e32 v126, 0x3f317217, v54
	v_fmac_f32_e32 v112, v120, v112
	v_fmac_f32_e32 v115, v123, v115
	v_fma_f32 v120, v56, s61, -v128
	v_fma_f32 v123, -v68, v131, v69
	v_fmac_f32_e32 v119, 0x3377d1cf, v55
	v_fmac_f32_e32 v121, 0x3377d1cf, v57
	v_fmac_f32_e32 v130, v122, v82
	v_div_scale_f32 v73, s[10:11], 1.0, v44, 1.0
	v_cndmask_b32_e64 v59, 0, v52, s[36:37]
	v_cndmask_b32_e64 v61, 0, v52, s[42:43]
	v_fma_f32 v125, -v80, v93, 1.0
	v_fmac_f32_e32 v92, v124, v92
	v_fma_f32 v124, -v106, v116, 1.0
	v_mul_f32_e32 v132, v71, v84
	v_mul_f32_e32 v134, 0x3f317217, v64
	v_mul_f32_e32 v135, 0x3f317217, v65
	v_mul_f32_e32 v136, 0x3f317217, v66
	v_mul_f32_e32 v137, 0x3f317217, v67
	v_fmac_f32_e32 v110, v118, v110
	v_fma_f32 v118, v54, s61, -v126
	v_fmac_f32_e32 v120, 0x3377d1cf, v56
	v_fmac_f32_e32 v131, v123, v83
	v_fmac_f32_e32 v119, 0x3f317217, v55
	v_cmp_lt_f32_e64 s[36:37], |v55|, s62
	v_fmac_f32_e32 v121, 0x3f317217, v57
	v_cmp_lt_f32_e64 s[42:43], |v57|, s62
	v_fma_f32 v62, -v62, v130, v63
	v_div_scale_f32 v75, s[12:13], 1.0, v41, 1.0
	v_cndmask_b32_e64 v60, 0, v52, s[40:41]
	v_cndmask_b32_e64 v58, 0, v52, s[44:45]
	v_fmac_f32_e32 v93, v125, v93
	v_fma_f32 v125, -v108, v117, 1.0
	v_mul_f32_e32 v133, v73, v85
	v_fmac_f32_e32 v116, v124, v116
	v_fma_f32 v124, -v70, v132, v71
	v_fma_f32 v126, v64, s61, -v134
	v_fma_f32 v127, v65, s61, -v135
	v_fma_f32 v128, v66, s61, -v136
	v_fma_f32 v129, v67, s61, -v137
	v_fmac_f32_e32 v118, 0x3377d1cf, v54
	v_fmac_f32_e32 v120, 0x3f317217, v56
	v_cmp_lt_f32_e64 s[40:41], |v56|, s62
	v_fma_f32 v63, -v68, v131, v69
	v_cndmask_b32_e64 v55, v55, v119, s[36:37]
	v_cndmask_b32_e64 v57, v57, v121, s[42:43]
	v_div_fmas_f32 v62, v62, v82, v130
	s_mov_b64 vcc, s[30:31]
	v_div_scale_f32 v77, s[8:9], 1.0, v40, 1.0
	v_cndmask_b32_e64 v89, 0, v52, s[52:53]
	v_mul_f32_e32 v138, v75, v90
	v_fmac_f32_e32 v117, v125, v117
	v_fma_f32 v125, -v72, v133, v73
	v_fmac_f32_e32 v132, v124, v84
	v_fmac_f32_e32 v126, 0x3377d1cf, v64
	v_fmac_f32_e32 v127, 0x3377d1cf, v65
	v_fmac_f32_e32 v128, 0x3377d1cf, v66
	v_fmac_f32_e32 v129, 0x3377d1cf, v67
	v_fmac_f32_e32 v118, 0x3f317217, v54
	v_cmp_lt_f32_e64 s[52:53], |v54|, s62
	v_cndmask_b32_e64 v56, v56, v120, s[40:41]
	v_sub_f32_e32 v55, v55, v60
	v_sub_f32_e32 v58, v57, v58
	v_div_fixup_f32 v57, v62, v49, 1.0
	v_div_fmas_f32 v49, v63, v83, v131
	v_cmp_lt_f32_e32 vcc, s63, v15
	v_div_scale_f32 v79, s[6:7], 1.0, v37, 1.0
	v_cndmask_b32_e64 v86, 0, v52, s[46:47]
	v_cndmask_b32_e64 v87, 0, v52, s[48:49]
	v_cndmask_b32_e64 v88, 0, v52, s[50:51]
	v_mul_f32_e32 v139, v77, v91
	v_fma_f32 v134, -v74, v138, v75
	v_fmac_f32_e32 v133, v125, v85
	v_fma_f32 v68, -v70, v132, v71
	v_fmac_f32_e32 v126, 0x3f317217, v64
	v_cmp_lt_f32_e64 s[44:45], |v64|, s62
	v_fmac_f32_e32 v127, 0x3f317217, v65
	v_cmp_lt_f32_e64 s[46:47], |v65|, s62
	v_fmac_f32_e32 v128, 0x3f317217, v66
	v_cmp_lt_f32_e64 s[48:49], |v66|, s62
	v_fmac_f32_e32 v129, 0x3f317217, v67
	v_cmp_lt_f32_e64 s[50:51], |v67|, s62
	v_cndmask_b32_e64 v54, v54, v118, s[52:53]
	v_sub_f32_e32 v56, v56, v61
	v_cmp_lt_f32_e64 s[36:37], s63, v26
	v_cmp_lt_f32_e64 s[40:41], s63, v27
	v_cndmask_b32_e32 v15, v55, v15, vcc
	s_mov_b64 vcc, s[14:15]
	v_div_scale_f32 v81, s[4:5], 1.0, v36, 1.0
	v_mul_f32_e32 v140, v79, v92
	v_fma_f32 v135, -v76, v139, v77
	v_fmac_f32_e32 v138, v134, v90
	v_fma_f32 v69, -v72, v133, v73
	v_cndmask_b32_e64 v64, v64, v126, s[44:45]
	v_cndmask_b32_e64 v65, v65, v127, s[46:47]
	v_cndmask_b32_e64 v66, v66, v128, s[48:49]
	v_cndmask_b32_e64 v67, v67, v129, s[50:51]
	v_sub_f32_e32 v54, v54, v59
	v_cmp_lt_f32_e64 s[42:43], s63, v14
	v_cndmask_b32_e64 v27, v58, v27, s[40:41]
	v_cndmask_b32_e64 v26, v56, v26, s[36:37]
	v_div_fixup_f32 v56, v49, v48, 1.0
	v_div_fmas_f32 v48, v68, v84, v132
	s_mov_b64 vcc, s[10:11]
	v_mul_f32_e32 v141, v81, v93
	v_fma_f32 v136, -v78, v140, v79
	v_fmac_f32_e32 v139, v135, v91
	v_fma_f32 v70, -v74, v138, v75
	v_sub_f32_e32 v59, v64, v86
	v_sub_f32_e32 v60, v65, v87
	v_sub_f32_e32 v61, v66, v88
	v_sub_f32_e32 v62, v67, v89
	v_cmp_lt_f32_e64 s[30:31], s63, v32
	v_cmp_lt_f32_e64 s[44:45], s63, v33
	v_cmp_lt_f32_e64 s[46:47], s63, v30
	v_cmp_lt_f32_e64 s[48:49], s63, v31
	v_cndmask_b32_e64 v14, v54, v14, s[42:43]
	v_mul_f32 v10, v26, v10
	v_mul_f32 v11, v27, v11
	v_div_fmas_f32 v26, v69, v85, v133
	s_mov_b64 vcc, s[12:13]
	v_div_scale_f32 v95, s[34:35], 1.0, v47, 1.0
	v_fma_f32 v137, -v80, v141, v81
	v_fmac_f32_e32 v140, v136, v92
	v_fma_f32 v71, -v76, v139, v77
	v_cndmask_b32_e64 v31, v60, v31, s[48:49]
	v_cndmask_b32_e64 v30, v59, v30, s[46:47]
	v_cndmask_b32_e64 v33, v62, v33, s[44:45]
	v_cndmask_b32_e64 v32, v61, v32, s[30:31]
	v_mul_f32 v8, v14, v8
	v_mul_f32 v9, v15, v9
	v_div_fixup_f32 v54, v26, v44, 1.0
	v_div_fmas_f32 v26, v70, v90, v138
	s_mov_b64 vcc, s[8:9]
	v_mul_f32_e32 v142, v95, v110
	v_fmac_f32_e32 v141, v137, v93
	v_fma_f32 v72, -v78, v140, v79
	v_mul_f32 v14, v32, v28
	v_mul_f32 v15, v33, v29
	v_mul_f32 v12, v30, v12
	v_mul_f32 v13, v31, v13
	flat_store_dwordx4 v[24:25], v[8:11]
	flat_store_dwordx4 v[24:25], v[12:15] offset:16
	v_fma_f32 v122, -v94, v142, v95
	v_div_fmas_f32 v8, v71, v91, v139
	s_mov_b64 vcc, s[6:7]
	v_fma_f32 v73, -v80, v141, v81
	v_div_fixup_f32 v10, v8, v40, 1.0
	v_div_fmas_f32 v8, v72, v92, v140
	s_mov_b64 vcc, s[4:5]
	v_fmac_f32_e32 v142, v122, v110
	v_div_fixup_f32 v9, v8, v37, 1.0
	v_div_fmas_f32 v8, v73, v93, v141
	v_fma_f32 v74, -v94, v142, v95
	v_div_fixup_f32 v55, v48, v45, 1.0
	v_div_fixup_f32 v11, v26, v41, 1.0
	v_div_fixup_f32 v8, v8, v36, 1.0
	s_mov_b64 vcc, s[34:35]
	flat_store_dwordx4 v[22:23], v[54:57]
	v_div_fmas_f32 v12, v74, v110, v142
	flat_store_dwordx4 v[22:23], v[8:11] offset:16
	v_div_scale_f32 v97, s[28:29], 1.0, v46, 1.0
	s_nop 0
	v_div_fixup_f32 v11, v12, v47, 1.0
	global_load_dwordx4 v[12:15], v51, s[56:57]
	global_load_dwordx4 v[22:25], v51, s[58:59]
	global_load_dwordx4 v[26:29], v51, s[56:57] offset:16
	global_load_dwordx4 v[30:33], v51, s[58:59] offset:16
	v_div_scale_f32 v99, s[26:27], 1.0, v43, 1.0
	v_mul_f32_e32 v143, v97, v111
	v_div_scale_f32 v101, s[24:25], 1.0, v42, 1.0
	v_mul_f32_e32 v144, v99, v112
	v_fma_f32 v123, -v96, v143, v97
	v_div_scale_f32 v103, s[22:23], 1.0, v39, 1.0
	v_mul_f32_e32 v145, v101, v113
	v_fma_f32 v124, -v98, v144, v99
	v_fmac_f32_e32 v143, v123, v111
	v_div_scale_f32 v105, s[20:21], 1.0, v38, 1.0
	v_mul_f32_e32 v146, v103, v114
	v_fma_f32 v125, -v100, v145, v101
	v_fmac_f32_e32 v144, v124, v112
	v_fma_f32 v75, -v96, v143, v97
	s_mov_b64 vcc, s[28:29]
	v_div_scale_f32 v107, s[18:19], 1.0, v35, 1.0
	v_mul_f32_e32 v147, v105, v115
	v_fma_f32 v134, -v102, v146, v103
	v_fmac_f32_e32 v145, v125, v113
	v_fma_f32 v76, -v98, v144, v99
	v_div_fmas_f32 v8, v75, v111, v143
	s_mov_b64 vcc, s[26:27]
	v_div_scale_f32 v109, s[16:17], 1.0, v34, 1.0
	v_mul_f32_e32 v148, v107, v116
	v_fma_f32 v135, -v104, v147, v105
	v_fmac_f32_e32 v146, v134, v114
	v_fma_f32 v77, -v100, v145, v101
	v_div_fixup_f32 v10, v8, v46, 1.0
	v_div_fmas_f32 v8, v76, v112, v144
	s_mov_b64 vcc, s[24:25]
	v_mul_f32_e32 v149, v109, v117
	v_fma_f32 v136, -v106, v148, v107
	v_fmac_f32_e32 v147, v135, v115
	v_fma_f32 v78, -v102, v146, v103
	v_div_fixup_f32 v9, v8, v43, 1.0
	v_div_fmas_f32 v8, v77, v113, v145
	s_mov_b64 vcc, s[22:23]
	v_fma_f32 v137, -v108, v149, v109
	v_fmac_f32_e32 v148, v136, v116
	v_fma_f32 v79, -v104, v147, v105
	v_div_fmas_f32 v36, v78, v114, v146
	s_mov_b64 vcc, s[20:21]
	v_fmac_f32_e32 v149, v137, v117
	v_fma_f32 v80, -v106, v148, v107
	v_div_fixup_f32 v8, v8, v42, 1.0
	v_div_fixup_f32 v37, v36, v39, 1.0
	v_div_fmas_f32 v36, v79, v115, v147
	s_mov_b64 vcc, s[18:19]
	v_fma_f32 v81, -v108, v149, v109
	flat_store_dwordx4 v[20:21], v[8:11]
	v_div_fixup_f32 v36, v36, v38, 1.0
	s_waitcnt vmcnt(0)
	v_add_f32 v6, v22, v6
	v_add_f32 v7, v23, v7
	v_div_fmas_f32 v8, v80, v116, v148
	s_mov_b64 vcc, s[16:17]
	v_div_fixup_f32 v35, v8, v35, 1.0
	v_div_fmas_f32 v8, v81, v117, v149
	v_div_fixup_f32 v34, v8, v34, 1.0
	v_mul_f32_e32 v8, 0x3fb8aa3b, v12
	v_mul_f32_e32 v9, 0x3fb8aa3b, v13
	v_add_f32 v4, v24, v4
	v_add_f32 v5, v25, v5
	flat_store_dwordx4 v[20:21], v[34:37] offset:16
	v_mul_f32_e32 v10, 0x3fb8aa3b, v14
	v_mul_f32_e32 v11, 0x3fb8aa3b, v15
	v_mul_f32_e32 v12, 0x3fb8aa3b, v26
	v_mul_f32_e32 v13, 0x3fb8aa3b, v27
	v_add_f32 v2, v30, v2
	v_add_f32 v3, v31, v3
	v_add_f32 v0, v32, v0
	v_add_f32 v1, v33, v1
	v_exp_f32_e32 v20, v8
	v_exp_f32_e32 v21, v9
	v_mul_f32_e32 v8, 0x3fb8aa3b, v6
	v_mul_f32_e32 v9, 0x3fb8aa3b, v7
	v_mul_f32_e32 v22, 0x3fb8aa3b, v4
	v_mul_f32_e32 v23, 0x3fb8aa3b, v5
	v_mul_f32_e32 v14, 0x3fb8aa3b, v28
	v_mul_f32_e32 v15, 0x3fb8aa3b, v29
	v_exp_f32_e32 v10, v10
	v_exp_f32_e32 v11, v11
	v_exp_f32_e32 v24, v12
	v_exp_f32_e32 v25, v13
	v_mul_f32_e32 v12, 0x3fb8aa3b, v2
	v_mul_f32_e32 v13, 0x3fb8aa3b, v3
	v_mul_f32_e32 v26, 0x3fb8aa3b, v0
	v_mul_f32_e32 v27, 0x3fb8aa3b, v1
	v_exp_f32_e32 v28, v8
	v_exp_f32_e32 v29, v9
	v_exp_f32_e32 v22, v22
	v_exp_f32_e32 v23, v23
	v_exp_f32_e32 v14, v14
	v_exp_f32_e32 v15, v15
	v_exp_f32_e32 v30, v12
	v_exp_f32_e32 v31, v13
	v_exp_f32_e32 v26, v26
	v_exp_f32_e32 v27, v27
	v_xor_b32_e32 v9, 0x80000000, v11
	v_xor_b32_e32 v8, 0x80000000, v10
	v_xor_b32_e32 v11, 0x80000000, v21
	v_xor_b32_e32 v10, 0x80000000, v20
	v_add_f32_e32 v20, 1.0, v28
	v_add_f32_e32 v21, 1.0, v29
	v_add_f32_e32 v22, 1.0, v22
	v_add_f32_e32 v23, 1.0, v23
	v_xor_b32_e32 v13, 0x80000000, v15
	v_xor_b32_e32 v12, 0x80000000, v14
	v_xor_b32_e32 v15, 0x80000000, v25
	v_xor_b32_e32 v14, 0x80000000, v24
	v_add_f32_e32 v24, 1.0, v30
	v_add_f32_e32 v25, 1.0, v31
	v_add_f32_e32 v26, 1.0, v26
	v_add_f32_e32 v27, 1.0, v27
	v_cmp_gt_f32_e32 vcc, s60, v20
	v_cmp_gt_f32_e64 s[4:5], s60, v21
	v_cmp_gt_f32_e64 s[6:7], s60, v22
	v_cmp_gt_f32_e64 s[8:9], s60, v23
	v_cndmask_b32_e64 v28, 0, 32, vcc
	v_cndmask_b32_e64 v29, 0, 32, s[4:5]
	v_cndmask_b32_e64 v30, 0, 32, s[6:7]
	v_cndmask_b32_e64 v31, 0, 32, s[8:9]
	v_cmp_gt_f32_e64 s[10:11], s60, v24
	v_cmp_gt_f32_e64 s[12:13], s60, v25
	v_cmp_gt_f32_e64 s[14:15], s60, v26
	v_cmp_gt_f32_e64 s[16:17], s60, v27
	v_cndmask_b32_e64 v32, 0, 32, s[10:11]
	v_cndmask_b32_e64 v33, 0, 32, s[12:13]
	v_cndmask_b32_e64 v34, 0, 32, s[14:15]
	v_cndmask_b32_e64 v35, 0, 32, s[16:17]
	v_ldexp_f32 v20, v20, v28
	v_ldexp_f32 v21, v21, v29
	v_ldexp_f32 v22, v22, v30
	v_ldexp_f32 v23, v23, v31
	v_ldexp_f32 v24, v24, v32
	v_ldexp_f32 v25, v25, v33
	v_ldexp_f32 v26, v26, v34
	v_ldexp_f32 v27, v27, v35
	v_log_f32_e32 v20, v20
	v_log_f32_e32 v21, v21
	v_log_f32_e32 v22, v22
	v_log_f32_e32 v23, v23
	v_log_f32_e32 v24, v24
	v_log_f32_e32 v25, v25
	v_log_f32_e32 v26, v26
	v_log_f32_e32 v27, v27
	v_mul_f32_e32 v36, 0x3f317217, v20
	v_mul_f32_e32 v37, 0x3f317217, v21
	v_mul_f32_e32 v38, 0x3f317217, v22
	v_mul_f32_e32 v39, 0x3f317217, v23
	v_mul_f32_e32 v40, 0x3f317217, v24
	v_mul_f32_e32 v41, 0x3f317217, v25
	v_mul_f32_e32 v42, 0x3f317217, v26
	v_mul_f32_e32 v43, 0x3f317217, v27
	v_fma_f32 v36, v20, s61, -v36
	v_fma_f32 v37, v21, s61, -v37
	v_fma_f32 v38, v22, s61, -v38
	v_fma_f32 v39, v23, s61, -v39
	v_fma_f32 v40, v24, s61, -v40
	v_fma_f32 v41, v25, s61, -v41
	v_fma_f32 v42, v26, s61, -v42
	v_fma_f32 v43, v27, s61, -v43
	v_fmac_f32_e32 v36, 0x3377d1cf, v20
	v_fmac_f32_e32 v37, 0x3377d1cf, v21
	v_fmac_f32_e32 v38, 0x3377d1cf, v22
	v_fmac_f32_e32 v39, 0x3377d1cf, v23
	v_cndmask_b32_e32 v28, 0, v52, vcc
	v_cndmask_b32_e64 v29, 0, v52, s[4:5]
	v_cndmask_b32_e64 v30, 0, v52, s[6:7]
	v_cndmask_b32_e64 v35, 0, v52, s[16:17]
	v_fmac_f32_e32 v40, 0x3377d1cf, v24
	v_fmac_f32_e32 v41, 0x3377d1cf, v25
	v_fmac_f32_e32 v42, 0x3377d1cf, v26
	v_fmac_f32_e32 v43, 0x3377d1cf, v27
	v_fmac_f32_e32 v36, 0x3f317217, v20
	v_fmac_f32_e32 v37, 0x3f317217, v21
	v_cmp_lt_f32_e64 vcc, |v21|, s62
	v_fmac_f32_e32 v38, 0x3f317217, v22
	v_cmp_lt_f32_e64 s[4:5], |v22|, s62
	v_fmac_f32_e32 v39, 0x3f317217, v23
	v_cmp_lt_f32_e64 s[6:7], |v23|, s62
	v_cmp_lt_f32_e64 s[16:17], |v20|, s62
	v_cndmask_b32_e64 v31, 0, v52, s[8:9]
	v_cndmask_b32_e64 v32, 0, v52, s[10:11]
	v_cndmask_b32_e64 v33, 0, v52, s[12:13]
	v_cndmask_b32_e64 v34, 0, v52, s[14:15]
	v_fmac_f32_e32 v40, 0x3f317217, v24
	v_cmp_lt_f32_e64 s[8:9], |v24|, s62
	v_fmac_f32_e32 v41, 0x3f317217, v25
	v_cmp_lt_f32_e64 s[10:11], |v25|, s62
	v_fmac_f32_e32 v42, 0x3f317217, v26
	v_cmp_lt_f32_e64 s[12:13], |v26|, s62
	v_fmac_f32_e32 v43, 0x3f317217, v27
	v_cmp_lt_f32_e64 s[14:15], |v27|, s62
	v_cndmask_b32_e64 v20, v20, v36, s[16:17]
	v_cndmask_b32_e32 v21, v21, v37, vcc
	v_cndmask_b32_e64 v22, v22, v38, s[4:5]
	v_cndmask_b32_e64 v23, v23, v39, s[6:7]
	v_cndmask_b32_e64 v24, v24, v40, s[8:9]
	v_cndmask_b32_e64 v25, v25, v41, s[10:11]
	v_cndmask_b32_e64 v26, v26, v42, s[12:13]
	v_cndmask_b32_e64 v27, v27, v43, s[14:15]
	v_sub_f32_e32 v20, v20, v28
	v_sub_f32_e32 v21, v21, v29
	v_sub_f32_e32 v22, v22, v30
	v_sub_f32_e32 v23, v23, v31
	v_cmp_lt_f32_e32 vcc, s63, v6
	v_cmp_lt_f32_e64 s[4:5], s63, v7
	v_cmp_lt_f32_e64 s[6:7], s63, v4
	v_cmp_lt_f32_e64 s[16:17], s63, v5
	v_sub_f32_e32 v24, v24, v32
	v_sub_f32_e32 v25, v25, v33
	v_sub_f32_e32 v26, v26, v34
	v_sub_f32_e32 v27, v27, v35
	v_cmp_lt_f32_e64 s[8:9], s63, v2
	v_cmp_lt_f32_e64 s[10:11], s63, v3
	v_cmp_lt_f32_e64 s[12:13], s63, v0
	v_cmp_lt_f32_e64 s[14:15], s63, v1
	v_cndmask_b32_e64 v5, v23, v5, s[16:17]
	v_cndmask_b32_e64 v4, v22, v4, s[6:7]
	v_cndmask_b32_e64 v7, v21, v7, s[4:5]
	v_cndmask_b32_e32 v6, v20, v6, vcc
	v_cndmask_b32_e64 v21, v27, v1, s[14:15]
	v_cndmask_b32_e64 v20, v26, v0, s[12:13]
	v_cndmask_b32_e64 v23, v25, v3, s[10:11]
	v_cndmask_b32_e64 v22, v24, v2, s[8:9]
	v_mul_f32 v0, v6, v10
	v_mul_f32 v1, v7, v11
	v_mul_f32 v2, v4, v8
	v_mul_f32 v3, v5, v9
	v_mul_f32 v4, v22, v14
	v_mul_f32 v5, v23, v15
	v_mul_f32 v6, v20, v12
	v_mul_f32 v7, v21, v13
	flat_store_dwordx4 v[18:19], v[0:3]
	flat_store_dwordx4 v[18:19], v[4:7] offset:16
	s_cbranch_scc0 .LBB0_858

.LBB0_861:
	v_mad_i64_i32 v[0:1], s[4:5], v16, s10, v[18:19]
	global_load_dwordx4 v[8:11], v22, s[12:13]
	v_add_co_u32_e32 v0, vcc, 0x1000, v0
	v_ashrrev_i32_e32 v17, 31, v16
	s_nop 0
	v_addc_co_u32_e32 v1, vcc, 0, v1, vcc
	flat_load_dwordx4 v[12:15], v[0:1] offset:64
	flat_load_dwordx4 v[24:27], v[0:1] offset:80
	global_load_dwordx4 v[28:31], v22, s[14:15]
	s_nop 0
	global_load_dwordx4 v[0:3], v22, s[12:13] offset:16
	global_load_dwordx4 v[4:7], v22, s[14:15] offset:16
	s_add_i32 s3, s3, s76
	s_cmp_lt_i32 s3, 24
	s_waitcnt vmcnt(0)
	v_mul_f32_e32 v8, 0x3fb8aa3b, v8
	v_mul_f32_e32 v9, 0x3fb8aa3b, v9
	v_exp_f32_e32 v34, v8
	v_exp_f32_e32 v35, v9
	s_waitcnt lgkmcnt(0)
	v_lshlrev_b32_e32 v8, 16, v12
	v_and_b32_e32 v9, 0xffff0000, v12
	v_mul_f32_e32 v10, 0x3fb8aa3b, v10
	v_mul_f32_e32 v11, 0x3fb8aa3b, v11
	v_add_f32 v8, v28, v8
	v_add_f32 v9, v29, v9
	v_exp_f32_e32 v36, v10
	v_exp_f32_e32 v37, v11
	v_lshlrev_b32_e32 v10, 16, v13
	v_and_b32_e32 v11, 0xffff0000, v13
	v_lshlrev_b32_e32 v12, 16, v24
	v_and_b32_e32 v13, 0xffff0000, v24
	v_mul_f32_e32 v24, 0x3fb8aa3b, v8
	v_lshlrev_b32_e32 v32, 16, v14
	v_and_b32_e32 v33, 0xffff0000, v14
	v_lshlrev_b32_e32 v20, 16, v15
	v_and_b32_e32 v21, 0xffff0000, v15
	v_lshlrev_b32_e32 v14, 16, v25
	v_and_b32_e32 v15, 0xffff0000, v25
	v_add_f32 v10, v30, v10
	v_add_f32 v11, v31, v11
	v_mul_f32_e32 v25, 0x3fb8aa3b, v9
	v_exp_f32_e32 v24, v24
	v_lshlrev_b32_e32 v38, 16, v26
	v_and_b32_e32 v39, 0xffff0000, v26
	v_mul_f32_e32 v26, 0x3fb8aa3b, v10
	v_exp_f32_e32 v25, v25
	v_lshlrev_b32_e32 v40, 16, v27
	v_and_b32_e32 v41, 0xffff0000, v27
	v_mul_f32_e32 v27, 0x3fb8aa3b, v11
	v_exp_f32_e32 v26, v26
	v_exp_f32_e32 v27, v27
	v_add_f32_e32 v24, 1.0, v24
	v_add_f32_e32 v25, 1.0, v25
	v_cmp_gt_f32_e32 vcc, s11, v24
	v_add_f32_e32 v26, 1.0, v26
	v_cmp_gt_f32_e64 s[4:5], s11, v25
	v_cndmask_b32_e64 v28, 0, 32, vcc
	v_add_f32_e32 v27, 1.0, v27
	v_cndmask_b32_e64 v29, 0, 32, s[4:5]
	v_cmp_gt_f32_e64 s[6:7], s11, v26
	v_ldexp_f32 v24, v24, v28
	v_cmp_gt_f32_e64 s[8:9], s11, v27
	v_cndmask_b32_e64 v30, 0, 32, s[6:7]
	v_ldexp_f32 v25, v25, v29
	v_log_f32_e32 v24, v24
	v_cndmask_b32_e64 v31, 0, 32, s[8:9]
	v_ldexp_f32 v26, v26, v30
	v_log_f32_e32 v25, v25
	v_ldexp_f32 v27, v27, v31
	v_log_f32_e32 v26, v26
	v_log_f32_e32 v27, v27
	v_mul_f32_e32 v31, 0x3f317217, v24
	v_mul_f32_e32 v42, 0x3f317217, v25
	v_fma_f32 v31, v24, s16, -v31
	v_mul_f32_e32 v14, 0xbfb8aa3b, v14
	v_mul_f32_e32 v43, 0x3f317217, v26
	v_fma_f32 v42, v25, s16, -v42
	v_fmac_f32_e32 v31, 0x3377d1cf, v24
	v_mul_f32_e32 v15, 0xbfb8aa3b, v15
	v_exp_f32_e32 v14, v14
	v_cndmask_b32_e32 v28, 0, v23, vcc
	v_mul_f32_e32 v44, 0x3f317217, v27
	v_fma_f32 v43, v26, s16, -v43
	v_fmac_f32_e32 v42, 0x3377d1cf, v25
	v_fmac_f32_e32 v31, 0x3f317217, v24
	v_cmp_lt_f32_e64 vcc, |v24|, s17
	v_exp_f32_e32 v15, v15
	v_fma_f32 v44, v27, s16, -v44
	v_fmac_f32_e32 v43, 0x3377d1cf, v26
	v_fmac_f32_e32 v42, 0x3f317217, v25
	v_cndmask_b32_e32 v24, v24, v31, vcc
	v_cmp_lt_f32_e64 vcc, |v25|, s17
	v_fmac_f32_e32 v44, 0x3377d1cf, v27
	v_fmac_f32_e32 v43, 0x3f317217, v26
	v_cndmask_b32_e32 v25, v25, v42, vcc
	v_cmp_lt_f32_e64 vcc, |v26|, s17
	v_fmac_f32_e32 v44, 0x3f317217, v27
	v_sub_f32_e32 v24, v24, v28
	v_cndmask_b32_e32 v26, v26, v43, vcc
	v_cmp_lt_f32_e64 vcc, |v27|, s17
	v_cndmask_b32_e64 v28, 0, v23, s[8:9]
	v_add_f32 v14, v14, 1.0
	v_add_f32 v15, v15, 1.0
	v_cndmask_b32_e32 v27, v27, v44, vcc
	v_cndmask_b32_e64 v29, 0, v23, s[4:5]
	v_sub_f32_e32 v27, v27, v28
	v_div_scale_f32 v28, s[4:5], v15, v15, 1.0
	v_sub_f32_e32 v25, v25, v29
	v_rcp_f32_e32 v29, v28
	v_cmp_lt_f32_e32 vcc, s18, v9
	v_cndmask_b32_e64 v30, 0, v23, s[6:7]
	v_sub_f32_e32 v26, v26, v30
	v_cndmask_b32_e32 v9, v25, v9, vcc
	v_cmp_lt_f32_e32 vcc, s18, v8
	v_xor_b32_e32 v25, 0x80000000, v35
	v_mul_f32_e32 v12, 0xbfb8aa3b, v12
	v_cndmask_b32_e32 v8, v24, v8, vcc
	v_cmp_lt_f32_e32 vcc, s18, v11
	v_xor_b32_e32 v24, 0x80000000, v34
	v_mul_f32 v8, v8, v24
	v_mul_f32 v9, v9, v25
	v_cndmask_b32_e32 v11, v27, v11, vcc
	v_cmp_lt_f32_e32 vcc, s18, v10
	v_fma_f32 v24, -v28, v29, 1.0
	v_fmac_f32_e32 v29, v24, v29
	v_cndmask_b32_e32 v10, v26, v10, vcc
	v_div_scale_f32 v24, vcc, 1.0, v15, 1.0
	v_xor_b32_e32 v27, 0x80000000, v37
	v_xor_b32_e32 v26, 0x80000000, v36
	v_mul_f32_e32 v25, v24, v29
	v_mul_f32 v10, v10, v26
	v_mul_f32 v11, v11, v27
	v_fma_f32 v26, -v28, v25, v24
	v_fmac_f32_e32 v25, v26, v29
	v_div_scale_f32 v26, s[4:5], v14, v14, 1.0
	v_rcp_f32_e32 v27, v26
	v_fma_f32 v24, -v28, v25, v24
	v_mul_f32_e32 v13, 0xbfb8aa3b, v13
	v_div_fmas_f32 v24, v24, v29, v25
	v_exp_f32_e32 v12, v12
	v_exp_f32_e32 v13, v13
	v_div_fixup_f32 v15, v24, v15, 1.0
	v_fma_f32 v24, -v26, v27, 1.0
	v_fmac_f32_e32 v27, v24, v27
	v_div_scale_f32 v24, vcc, 1.0, v14, 1.0
	v_mul_f32_e32 v25, v24, v27
	v_fma_f32 v28, -v26, v25, v24
	v_add_f32 v12, v12, 1.0
	v_add_f32 v13, v13, 1.0
	v_fmac_f32_e32 v25, v28, v27
	v_fma_f32 v24, -v26, v25, v24
	v_div_scale_f32 v26, s[4:5], v13, v13, 1.0
	v_rcp_f32_e32 v28, v26
	v_div_fmas_f32 v24, v24, v27, v25
	v_div_fixup_f32 v14, v24, v14, 1.0
	v_add_f32 v4, v4, v32
	v_add_f32 v5, v5, v33
	v_fma_f32 v24, -v26, v28, 1.0
	v_fmac_f32_e32 v28, v24, v28
	v_div_scale_f32 v24, vcc, 1.0, v13, 1.0
	v_mul_f32_e32 v25, v24, v28
	v_fma_f32 v27, -v26, v25, v24
	v_fmac_f32_e32 v25, v27, v28
	v_fma_f32 v24, -v26, v25, v24
	v_div_scale_f32 v26, s[4:5], v12, v12, 1.0
	v_rcp_f32_e32 v27, v26
	v_div_fmas_f32 v24, v24, v28, v25
	v_div_fixup_f32 v13, v24, v13, 1.0
	v_mul_f32_e32 v0, 0x3fb8aa3b, v0
	v_fma_f32 v24, -v26, v27, 1.0
	v_fmac_f32_e32 v27, v24, v27
	v_div_scale_f32 v24, vcc, 1.0, v12, 1.0
	v_mul_f32_e32 v25, v24, v27
	v_fma_f32 v28, -v26, v25, v24
	v_fmac_f32_e32 v25, v28, v27
	v_fma_f32 v24, -v26, v25, v24
	v_div_fmas_f32 v24, v24, v27, v25
	v_div_fixup_f32 v12, v24, v12, 1.0
	v_mul_f32_e32 v24, 0x3fb8aa3b, v4
	v_exp_f32_e32 v24, v24
	v_exp_f32_e32 v26, v0
	v_mul_f32_e32 v0, 0xbfb8aa3b, v38
	v_mul_f32_e32 v3, 0x3fb8aa3b, v3
	v_add_f32_e32 v24, 1.0, v24
	v_cmp_gt_f32_e32 vcc, s11, v24
	v_mul_f32_e32 v2, 0x3fb8aa3b, v2
	s_nop 0
	v_cndmask_b32_e64 v25, 0, 32, vcc
	v_ldexp_f32 v24, v24, v25
	v_log_f32_e32 v25, v24
	v_exp_f32_e32 v24, v0
	v_mul_f32_e32 v0, 0x3fb8aa3b, v1
	v_mul_f32_e32 v1, 0x3fb8aa3b, v5
	v_exp_f32_e32 v1, v1
	v_exp_f32_e32 v27, v0
	v_mul_f32_e32 v0, 0x3f317217, v25
	v_fma_f32 v0, v25, s16, -v0
	v_add_f32_e32 v1, 1.0, v1
	v_cmp_gt_f32_e64 s[4:5], s11, v1
	v_fmac_f32_e32 v0, 0x3377d1cf, v25
	v_fmac_f32_e32 v0, 0x3f317217, v25
	v_cndmask_b32_e64 v28, 0, 32, s[4:5]
	v_ldexp_f32 v1, v1, v28
	v_log_f32_e32 v1, v1
	v_cmp_lt_f32_e64 s[6:7], |v25|, s17
	s_nop 1
	v_cndmask_b32_e64 v0, v25, v0, s[6:7]
	v_cndmask_b32_e32 v25, 0, v23, vcc
	v_sub_f32_e32 v28, v0, v25
	v_mul_f32_e32 v0, 0x3f317217, v1
	v_fma_f32 v0, v1, s16, -v0
	v_fmac_f32_e32 v0, 0x3377d1cf, v1
	v_fmac_f32_e32 v0, 0x3f317217, v1
	v_cmp_lt_f32_e64 vcc, |v1|, s17
	s_nop 1
	v_cndmask_b32_e32 v0, v1, v0, vcc
	v_cndmask_b32_e64 v1, 0, v23, s[4:5]
	v_sub_f32_e32 v29, v0, v1
	v_mul_f32_e32 v0, 0xbfb8aa3b, v39
	v_exp_f32_e32 v25, v0
	v_add_f32 v0, v6, v20
	v_add_f32 v1, v7, v21
	v_exp_f32_e32 v21, v3
	v_mul_f32_e32 v6, 0x3fb8aa3b, v0
	v_exp_f32_e32 v6, v6
	v_exp_f32_e32 v20, v2
	v_mul_f32_e32 v2, 0xbfb8aa3b, v40
	v_exp_f32_e32 v2, v2
	v_add_f32_e32 v6, 1.0, v6
	v_cmp_gt_f32_e32 vcc, s11, v6
	v_xor_b32_e32 v21, 0x80000000, v21
	v_xor_b32_e32 v20, 0x80000000, v20
	v_cndmask_b32_e64 v7, 0, 32, vcc
	v_ldexp_f32 v6, v6, v7
	v_mul_f32_e32 v7, 0x3fb8aa3b, v1
	v_exp_f32_e32 v7, v7
	v_log_f32_e32 v6, v6
	v_add_f32_e32 v7, 1.0, v7
	v_cmp_gt_f32_e64 s[4:5], s11, v7
	v_mul_f32_e32 v3, 0x3f317217, v6
	v_fma_f32 v3, v6, s16, -v3
	v_cndmask_b32_e64 v30, 0, 32, s[4:5]
	v_ldexp_f32 v7, v7, v30
	v_log_f32_e32 v7, v7
	v_fmac_f32_e32 v3, 0x3377d1cf, v6
	v_fmac_f32_e32 v3, 0x3f317217, v6
	v_cmp_lt_f32_e64 s[6:7], |v6|, s17
	s_nop 1
	v_cndmask_b32_e64 v3, v6, v3, s[6:7]
	v_cndmask_b32_e32 v6, 0, v23, vcc
	v_sub_f32_e32 v3, v3, v6
	v_mul_f32_e32 v6, 0x3f317217, v7
	v_fma_f32 v6, v7, s16, -v6
	v_fmac_f32_e32 v6, 0x3377d1cf, v7
	v_fmac_f32_e32 v6, 0x3f317217, v7
	v_cmp_lt_f32_e64 vcc, |v7|, s17
	s_nop 1
	v_cndmask_b32_e32 v6, v7, v6, vcc
	v_cmp_lt_f32_e32 vcc, s18, v5
	v_cndmask_b32_e64 v7, 0, v23, s[4:5]
	v_sub_f32_e32 v6, v6, v7
	v_cndmask_b32_e32 v5, v29, v5, vcc
	v_cmp_lt_f32_e32 vcc, s18, v4
	v_xor_b32_e32 v7, 0x80000000, v27
	s_nop 0
	v_cndmask_b32_e32 v4, v28, v4, vcc
	v_cmp_lt_f32_e32 vcc, s18, v1
	s_nop 1
	v_cndmask_b32_e32 v1, v6, v1, vcc
	v_cmp_lt_f32_e32 vcc, s18, v0
	v_xor_b32_e32 v6, 0x80000000, v26
	s_nop 0
	v_cndmask_b32_e32 v0, v3, v0, vcc
	v_mul_f32_e32 v3, 0xbfb8aa3b, v41
	v_exp_f32_e32 v3, v3
	s_nop 0
	v_add_f32 v26, v2, 1.0
	v_add_f32 v27, v3, 1.0
	s_nop 0
	v_div_scale_f32 v28, s[4:5], v27, v27, 1.0
	v_rcp_f32_e32 v29, v28
	v_mul_f32 v2, v0, v20
	v_mul_f32 v3, v1, v21
	v_mul_f32 v0, v4, v6
	v_mul_f32 v1, v5, v7
	v_add_f32 v4, v24, 1.0
	v_add_f32 v5, v25, 1.0
	v_fma_f32 v6, -v28, v29, 1.0
	v_fmac_f32_e32 v29, v6, v29
	v_div_scale_f32 v6, vcc, 1.0, v27, 1.0
	v_mul_f32_e32 v7, v6, v29
	v_fma_f32 v20, -v28, v7, v6
	v_fmac_f32_e32 v7, v20, v29
	v_div_scale_f32 v20, s[4:5], v26, v26, 1.0
	v_rcp_f32_e32 v21, v20
	v_fma_f32 v6, -v28, v7, v6
	v_div_fmas_f32 v6, v6, v29, v7
	v_div_fixup_f32 v7, v6, v27, 1.0
	v_fma_f32 v6, -v20, v21, 1.0
	v_fmac_f32_e32 v21, v6, v21
	v_div_scale_f32 v6, vcc, 1.0, v26, 1.0
	v_mul_f32_e32 v24, v6, v21
	v_fma_f32 v25, -v20, v24, v6
	v_fmac_f32_e32 v24, v25, v21
	v_fma_f32 v6, -v20, v24, v6
	v_div_scale_f32 v20, s[4:5], v5, v5, 1.0
	v_rcp_f32_e32 v25, v20
	v_div_fmas_f32 v6, v6, v21, v24
	v_div_fixup_f32 v6, v6, v26, 1.0
	v_fma_f32 v21, -v20, v25, 1.0
	v_fmac_f32_e32 v25, v21, v25
	v_div_scale_f32 v21, vcc, 1.0, v5, 1.0
	v_mul_f32_e32 v24, v21, v25
	v_fma_f32 v26, -v20, v24, v21
	v_fmac_f32_e32 v24, v26, v25
	v_fma_f32 v20, -v20, v24, v21
	v_div_scale_f32 v21, s[4:5], v4, v4, 1.0
	v_rcp_f32_e32 v26, v21
	v_div_fmas_f32 v20, v20, v25, v24
	v_div_fixup_f32 v5, v20, v5, 1.0
	v_fma_f32 v20, -v21, v26, 1.0
	v_fmac_f32_e32 v26, v20, v26
	v_div_scale_f32 v20, vcc, 1.0, v4, 1.0
	v_mul_f32_e32 v24, v20, v26
	v_fma_f32 v25, -v21, v24, v20
	v_fmac_f32_e32 v24, v25, v26
	v_fma_f32 v20, -v21, v24, v20
	v_div_fmas_f32 v20, v20, v26, v24
	v_div_fixup_f32 v4, v20, v4, 1.0
	v_lshlrev_b64 v[20:21], 5, v[16:17]
	v_lshl_add_u64 v[24:25], s[70:71], 0, v[20:21]
	flat_store_dwordx4 v[24:25], v[8:11]
	flat_store_dwordx4 v[24:25], v[0:3] offset:16
	v_add_u32_e32 v16, s2, v16
	s_nop 0
	v_lshl_add_u64 v[0:1], s[72:73], 0, v[20:21]
	flat_store_dwordx4 v[0:1], v[12:15]
	flat_store_dwordx4 v[0:1], v[4:7] offset:16
	s_cbranch_scc1 .LBB0_861

.LBB0_864:
	s_or_b64 exec, exec, s[6:7]
	s_waitcnt lgkmcnt(0)
	v_lshl_add_u64 v[40:41], v[54:55], 2, s[18:19]
	global_load_dwordx4 v[24:27], v[40:41], off offset:16
	global_load_dwordx4 v[74:77], v[40:41], off
	global_load_dwordx4 v[28:31], v[40:41], off offset:3088
	global_load_dwordx4 v[78:81], v[40:41], off offset:3072
	v_add_co_u32_e32 v88, vcc, s22, v40
	v_lshl_add_u64 v[86:87], v[40:41], 0, s[14:15]
	s_nop 0
	v_addc_co_u32_e32 v89, vcc, 0, v41, vcc
	global_load_dwordx4 v[82:85], v[88:89], off offset:2048
	global_load_dwordx4 v[40:43], v[86:87], off offset:16
	s_waitcnt vmcnt(0)
	v_lshlrev_b32_e32 v87, 16, v0
	v_lshlrev_b32_e32 v86, 16, v4
	v_lshlrev_b32_e32 v91, 16, v1
	v_lshlrev_b32_e32 v90, 16, v5
	v_and_b32_e32 v93, 0xffff0000, v1
	v_and_b32_e32 v92, 0xffff0000, v5
	v_lshlrev_b32_e32 v95, 16, v2
	v_and_b32_e32 v97, 0xffff0000, v2
	v_lshlrev_b32_e32 v5, 16, v3
	v_and_b32_e32 v1, 0xffff0000, v3
	v_lshlrev_b32_e32 v3, 16, v20
	v_lshlrev_b32_e32 v2, 16, v16
	v_pk_mov_b32 v[130:131], v[86:87], v[2:3] op_sel:[1,0]
	v_and_b32_e32 v89, 0xffff0000, v0
	v_and_b32_e32 v88, 0xffff0000, v4
	v_lshlrev_b32_e32 v94, 16, v6
	v_and_b32_e32 v96, 0xffff0000, v6
	v_lshlrev_b32_e32 v4, 16, v7
	v_and_b32_e32 v0, 0xffff0000, v7
	v_and_b32_e32 v7, 0xffff0000, v20
	v_and_b32_e32 v6, 0xffff0000, v16
	v_lshlrev_b32_e32 v98, 16, v17
	v_and_b32_e32 v20, 0xffff0000, v17
	v_lshlrev_b32_e32 v17, 16, v22
	v_lshlrev_b32_e32 v16, 16, v18
	v_and_b32_e32 v101, 0xffff0000, v22
	v_and_b32_e32 v100, 0xffff0000, v18
	v_lshlrev_b32_e32 v102, 16, v19
	v_and_b32_e32 v22, 0xffff0000, v19
	v_lshlrev_b32_e32 v19, 16, v36
	v_lshlrev_b32_e32 v18, 16, v32
	v_and_b32_e32 v105, 0xffff0000, v36
	v_and_b32_e32 v104, 0xffff0000, v32
	v_lshlrev_b32_e32 v106, 16, v33
	v_and_b32_e32 v36, 0xffff0000, v33
	v_lshlrev_b32_e32 v33, 16, v38
	v_lshlrev_b32_e32 v32, 16, v34
	v_and_b32_e32 v109, 0xffff0000, v38
	v_and_b32_e32 v108, 0xffff0000, v34
	v_lshlrev_b32_e32 v110, 16, v35
	v_and_b32_e32 v38, 0xffff0000, v35
	v_lshlrev_b32_e32 v34, 16, v48
	v_lshlrev_b32_e32 v35, 16, v44
	v_lshlrev_b32_e32 v129, 16, v12
	v_mov_b32_e32 v128, v35
	v_mov_b32_e32 v126, v129
	v_and_b32_e32 v113, 0xffff0000, v44
	v_and_b32_e32 v112, 0xffff0000, v48
	v_lshlrev_b32_e32 v99, 16, v21
	v_lshlrev_b32_e32 v44, 16, v49
	v_and_b32_e32 v114, 0xffff0000, v49
	v_lshlrev_b32_e32 v48, 16, v50
	v_lshlrev_b32_e32 v49, 16, v46
	v_and_b32_e32 v117, 0xffff0000, v46
	v_and_b32_e32 v116, 0xffff0000, v50
	v_lshlrev_b32_e32 v46, 16, v51
	v_and_b32_e32 v118, 0xffff0000, v51
	v_and_b32_e32 v51, 0xffff0000, v12
	v_mov_b32_e32 v50, v113
	v_lshlrev_b32_e32 v127, 16, v8
	v_lshlrev_b32_e32 v107, 16, v37
	v_and_b32_e32 v115, 0xffff0000, v45
	v_lshlrev_b32_e32 v45, 16, v45
	v_and_b32_e32 v121, 0xffff0000, v13
	v_lshlrev_b32_e32 v13, 16, v13
	v_mov_b32_e32 v12, v45
	v_and_b32_e32 v21, 0xffff0000, v21
	v_and_b32_e32 v37, 0xffff0000, v37
	v_mov_b32_e32 v120, v115
	v_and_b32_e32 v123, 0xffff0000, v14
	v_mov_b32_e32 v122, v117
	v_lshlrev_b32_e32 v103, 16, v23
	v_and_b32_e32 v119, 0xffff0000, v47
	v_mul_f32 v130, v78, v130
	v_mul_f32 v131, v78, v131
	v_fma_f32 v86, v74, v86, v130
	v_fma_f32 v87, v74, v87, v131
	v_pk_mov_b32 v[130:131], v[2:3], v[18:19] op_sel:[1,0]
	v_mul_f32 v128, v78, v128
	v_mul_f32 v129, v78, v129
	v_mul_f32 v130, v78, v130
	v_mul_f32 v131, v78, v131
	v_fma_f32 v86, v82, v2, v86
	v_fma_f32 v87, v82, v3, v87
	v_fma_f32 v2, v74, v2, v130
	v_fma_f32 v3, v74, v3, v131
	v_pk_mov_b32 v[130:131], v[18:19], v[34:35] op_sel:[1,0]
	v_fma_f32 v2, v82, v18, v2
	v_fma_f32 v3, v82, v19, v3
	v_mul_f32 v130, v78, v130
	v_mul_f32 v131, v78, v131
	v_fma_f32 v18, v74, v18, v130
	v_fma_f32 v19, v74, v19, v131
	v_fma_f32 v18, v82, v34, v18
	v_fma_f32 v19, v82, v35, v19
	v_fma_f32 v34, v74, v34, v128
	v_fma_f32 v35, v74, v35, v129
	v_pk_mov_b32 v[128:129], v[88:89], v[6:7] op_sel:[1,0]
	v_fma_f32 v34, v82, v126, v34
	v_fma_f32 v35, v82, v127, v35
	v_mul_f32 v128, v79, v128
	v_mul_f32 v129, v79, v129
	v_mov_b32_e32 v126, v51
	v_fma_f32 v88, v75, v88, v128
	v_fma_f32 v89, v75, v89, v129
	v_pk_mov_b32 v[128:129], v[6:7], v[104:105] op_sel:[1,0]
	v_fma_f32 v88, v83, v6, v88
	v_fma_f32 v89, v83, v7, v89
	v_mul_f32 v128, v79, v128
	v_mul_f32 v129, v79, v129
	v_mul_f32 v50, v79, v50
	v_mul_f32 v51, v79, v51
	v_fma_f32 v6, v75, v6, v128
	v_fma_f32 v7, v75, v7, v129
	v_pk_mov_b32 v[128:129], v[104:105], v[112:113] op_sel:[1,0]
	v_and_b32_e32 v127, 0xffff0000, v8
	v_mul_f32 v128, v79, v128
	v_mul_f32 v129, v79, v129
	v_pk_mov_b32 v[78:79], v[90:91], v[98:99] op_sel:[1,0]
	v_fma_f32 v6, v83, v104, v6
	v_fma_f32 v7, v83, v105, v7
	v_mul_f32 v78, v80, v78
	v_mul_f32 v79, v80, v79
	v_fma_f32 v104, v75, v104, v128
	v_fma_f32 v105, v75, v105, v129
	v_fma_f32 v50, v75, v112, v50
	v_fma_f32 v51, v75, v113, v51
	v_fma_f32 v78, v76, v90, v78
	v_fma_f32 v79, v76, v91, v79
	v_pk_mov_b32 v[90:91], v[106:107], v[44:45] op_sel:[1,0]
	v_fma_f32 v104, v83, v112, v104
	v_fma_f32 v105, v83, v113, v105
	v_fma_f32 v50, v83, v126, v50
	v_fma_f32 v51, v83, v127, v51
	v_pk_mov_b32 v[82:83], v[98:99], v[106:107] op_sel:[1,0]
	v_mul_f32 v90, v80, v90
	v_mul_f32 v91, v80, v91
	v_mov_b32_e32 v74, v13
	v_mul_f32 v12, v80, v12
	v_mul_f32 v13, v80, v13
	v_lshlrev_b32_e32 v75, 16, v9
	v_mul_f32 v82, v80, v82
	v_mul_f32 v83, v80, v83
	v_fma_f32 v90, v76, v106, v90
	v_fma_f32 v91, v76, v107, v91
	v_fma_f32 v12, v76, v44, v12
	v_fma_f32 v13, v76, v45, v13
	v_fma_f32 v82, v76, v98, v82
	v_fma_f32 v83, v76, v99, v83
	v_fma_f32 v90, v84, v44, v90
	v_fma_f32 v91, v84, v45, v91
	v_fma_f32 v12, v84, v74, v12
	v_fma_f32 v13, v84, v75, v13
	v_mov_b32_e32 v44, v77
	v_mov_b32_e32 v74, v81
	v_pk_mov_b32 v[76:77], v[92:93], v[20:21] op_sel:[1,0]
	v_fma_f32 v78, v84, v98, v78
	v_fma_f32 v79, v84, v99, v79
	v_fma_f32 v82, v84, v106, v82
	v_fma_f32 v83, v84, v107, v83
	v_mul_f32 v76, v74, v76
	v_mul_f32 v77, v74, v77
	v_mov_b32_e32 v80, v85
	v_pk_mov_b32 v[84:85], v[20:21], v[36:37] op_sel:[1,0]
	v_fma_f32 v76, v44, v92, v76
	v_fma_f32 v77, v44, v93, v77
	v_mul_f32 v84, v74, v84
	v_mul_f32 v85, v74, v85
	v_fma_f32 v76, v80, v20, v76
	v_fma_f32 v77, v80, v21, v77
	v_fma_f32 v20, v44, v20, v84
	v_fma_f32 v21, v44, v21, v85
	v_pk_mov_b32 v[84:85], v[36:37], v[114:115] op_sel:[1,0]
	v_and_b32_e32 v9, 0xffff0000, v9
	v_mul_f32 v84, v74, v84
	v_mul_f32 v85, v74, v85
	v_mul_f32 v75, v74, v121
	v_mul_f32 v74, v74, v120
	v_mov_b32_e32 v8, v121
	v_fma_f32 v20, v80, v36, v20
	v_fma_f32 v21, v80, v37, v21
	v_fma_f32 v36, v44, v36, v84
	v_fma_f32 v37, v44, v37, v85
	v_fma_f32 v45, v44, v115, v75
	v_fma_f32 v44, v44, v114, v74
	v_fma_f32 v36, v80, v114, v36
	v_fma_f32 v37, v80, v115, v37
	v_fma_f32 v8, v80, v8, v44
	v_fma_f32 v9, v80, v9, v45
	v_pk_mov_b32 v[80:81], v[94:95], v[16:17] op_sel:[1,0]
	v_pk_mov_b32 v[84:85], v[16:17], v[32:33] op_sel:[1,0]
	v_mul_f32 v80, v28, v80
	v_mul_f32 v81, v28, v81
	v_fma_f32 v80, v24, v94, v80
	v_fma_f32 v81, v24, v95, v81
	v_mul_f32 v84, v28, v84
	v_mul_f32 v85, v28, v85
	v_fma_f32 v80, v40, v16, v80
	v_fma_f32 v81, v40, v17, v81
	v_fma_f32 v16, v24, v16, v84
	v_fma_f32 v17, v24, v17, v85
	v_pk_mov_b32 v[84:85], v[32:33], v[48:49] op_sel:[1,0]
	v_lshlrev_b32_e32 v75, 16, v14
	v_mov_b32_e32 v74, v49
	v_mul_f32 v84, v28, v84
	v_mul_f32 v85, v28, v85
	v_fma_f32 v16, v40, v32, v16
	v_fma_f32 v17, v40, v33, v17
	v_fma_f32 v32, v24, v32, v84
	v_fma_f32 v33, v24, v33, v85
	v_mov_b32_e32 v44, v75
	v_mul_f32 v74, v28, v74
	v_mul_f32 v75, v28, v75
	v_fma_f32 v32, v40, v48, v32
	v_fma_f32 v33, v40, v49, v33
	v_fma_f32 v48, v24, v48, v74
	v_fma_f32 v49, v24, v49, v75
	v_pk_mov_b32 v[74:75], v[96:97], v[100:101] op_sel:[1,0]
	v_pk_mov_b32 v[84:85], v[100:101], v[108:109] op_sel:[1,0]
	v_pk_mov_b32 v[92:93], v[108:109], v[116:117] op_sel:[1,0]
	v_lshlrev_b32_e32 v45, 16, v10
	v_mul_f32 v74, v29, v74
	v_mul_f32 v75, v29, v75
	v_mul_f32 v84, v29, v84
	v_mul_f32 v85, v29, v85
	v_mul_f32 v92, v29, v92
	v_mul_f32 v93, v29, v93
	v_mul_f32 v28, v29, v122
	v_mul_f32 v29, v29, v123
	v_lshlrev_b32_e32 v47, 16, v47
	v_fma_f32 v44, v40, v44, v48
	v_fma_f32 v45, v40, v45, v49
	v_and_b32_e32 v49, 0xffff0000, v10
	v_mov_b32_e32 v48, v123
	v_fma_f32 v74, v25, v96, v74
	v_fma_f32 v75, v25, v97, v75
	v_fma_f32 v84, v25, v100, v84
	v_fma_f32 v85, v25, v101, v85
	v_fma_f32 v92, v25, v108, v92
	v_fma_f32 v93, v25, v109, v93
	v_fma_f32 v24, v25, v116, v28
	v_fma_f32 v25, v25, v117, v29
	v_and_b32_e32 v125, 0xffff0000, v15
	v_fma_f32 v74, v41, v100, v74
	v_fma_f32 v75, v41, v101, v75
	v_fma_f32 v84, v41, v108, v84
	v_fma_f32 v85, v41, v109, v85
	v_fma_f32 v92, v41, v116, v92
	v_fma_f32 v93, v41, v117, v93
	v_fma_f32 v24, v41, v48, v24
	v_fma_f32 v25, v41, v49, v25
	v_lshlrev_b32_e32 v15, 16, v15
	v_mov_b32_e32 v14, v47
	v_pk_mov_b32 v[40:41], v[4:5], v[102:103] op_sel:[1,0]
	v_lshlrev_b32_e32 v111, 16, v39
	v_mul_f32 v40, v30, v40
	v_mul_f32 v41, v30, v41
	v_mov_b32_e32 v28, v15
	v_mul_f32 v14, v30, v14
	v_mul_f32 v15, v30, v15
	v_and_b32_e32 v23, 0xffff0000, v23
	v_lshlrev_b32_e32 v29, 16, v11
	v_fma_f32 v4, v26, v4, v40
	v_fma_f32 v5, v26, v5, v41
	v_pk_mov_b32 v[40:41], v[102:103], v[110:111] op_sel:[1,0]
	v_pk_mov_b32 v[48:49], v[110:111], v[46:47] op_sel:[1,0]
	v_fma_f32 v14, v26, v46, v14
	v_fma_f32 v15, v26, v47, v15
	v_mul_f32 v40, v30, v40
	v_mul_f32 v41, v30, v41
	v_mul_f32 v48, v30, v48
	v_mul_f32 v49, v30, v49
	v_fma_f32 v14, v42, v28, v14
	v_fma_f32 v15, v42, v29, v15
	v_mov_b32_e32 v28, v31
	v_pk_mov_b32 v[30:31], v[0:1], v[22:23] op_sel:[1,0]
	v_fma_f32 v40, v26, v102, v40
	v_fma_f32 v41, v26, v103, v41
	v_fma_f32 v48, v26, v110, v48
	v_fma_f32 v49, v26, v111, v49
	v_mov_b32_e32 v26, v27
	v_mul_f32 v30, v28, v30
	v_mul_f32 v31, v28, v31
	v_and_b32_e32 v39, 0xffff0000, v39
	v_fma_f32 v0, v26, v0, v30
	v_fma_f32 v1, v26, v1, v31
	v_mov_b32_e32 v30, v43
	v_fma_f32 v4, v42, v102, v4
	v_fma_f32 v5, v42, v103, v5
	v_fma_f32 v40, v42, v110, v40
	v_fma_f32 v41, v42, v111, v41
	v_fma_f32 v48, v42, v46, v48
	v_fma_f32 v49, v42, v47, v49
	v_fma_f32 v42, v30, v22, v0
	v_fma_f32 v43, v30, v23, v1
	v_pk_mov_b32 v[0:1], v[22:23], v[38:39] op_sel:[1,0]
	v_mov_b32_e32 v124, v119
	v_mul_f32 v0, v28, v0
	v_mul_f32 v1, v28, v1
	v_fma_f32 v0, v26, v22, v0
	v_fma_f32 v1, v26, v23, v1
	v_fma_f32 v22, v30, v38, v0
	v_fma_f32 v23, v30, v39, v1
	v_pk_mov_b32 v[0:1], v[38:39], v[118:119] op_sel:[1,0]
	s_ashr_i32 s13, s12, 31
	v_mul_f32 v0, v28, v0
	v_mul_f32 v1, v28, v1
	v_fma_f32 v0, v26, v38, v0
	v_fma_f32 v1, v26, v39, v1
	v_fma_f32 v38, v30, v118, v0
	v_fma_f32 v39, v30, v119, v1
	v_mul_f32 v0, v28, v124
	v_mul_f32 v1, v28, v125
	v_and_b32_e32 v11, 0xffff0000, v11
	v_mov_b32_e32 v10, v125
	v_fma_f32 v0, v26, v118, v0
	v_fma_f32 v1, v26, v119, v1
	s_lshl_b64 s[6:7], s[12:13], 1
	v_fma_f32 v10, v30, v10, v0
	v_fma_f32 v11, v30, v11, v1
	v_lshl_add_u64 v[26:27], v[58:59], 0, s[6:7]
	v_cvt_pk_bf16_f32 v0, v86, v87
	v_cvt_pk_bf16_f32 v1, v2, v3
	v_cvt_pk_bf16_f32 v2, v18, v19
	v_cvt_pk_bf16_f32 v3, v34, v35
	flat_store_dwordx4 v[26:27], v[0:3]
	v_lshl_add_u64 v[18:19], v[60:61], 0, s[6:7]
	s_nop 0
	v_cvt_pk_bf16_f32 v0, v88, v89
	v_cvt_pk_bf16_f32 v1, v6, v7
	v_cvt_pk_bf16_f32 v2, v104, v105
	v_cvt_pk_bf16_f32 v3, v50, v51
	flat_store_dwordx4 v[18:19], v[0:3]
	v_lshl_add_u64 v[6:7], v[62:63], 0, s[6:7]
	s_nop 0
	v_cvt_pk_bf16_f32 v0, v78, v79
	v_cvt_pk_bf16_f32 v1, v82, v83
	v_cvt_pk_bf16_f32 v2, v90, v91
	v_cvt_pk_bf16_f32 v3, v12, v13
	flat_store_dwordx4 v[6:7], v[0:3]
	v_lshl_add_u64 v[6:7], v[64:65], 0, s[6:7]
	s_nop 0
	v_cvt_pk_bf16_f32 v0, v76, v77
	v_cvt_pk_bf16_f32 v1, v20, v21
	v_cvt_pk_bf16_f32 v2, v36, v37
	v_cvt_pk_bf16_f32 v3, v8, v9
	flat_store_dwordx4 v[6:7], v[0:3]
	v_lshl_add_u64 v[6:7], v[66:67], 0, s[6:7]
	s_nop 0
	v_cvt_pk_bf16_f32 v0, v80, v81
	v_cvt_pk_bf16_f32 v1, v16, v17
	v_cvt_pk_bf16_f32 v2, v32, v33
	v_cvt_pk_bf16_f32 v3, v44, v45
	flat_store_dwordx4 v[6:7], v[0:3]
	v_lshl_add_u64 v[6:7], v[68:69], 0, s[6:7]
	s_nop 0
	v_cvt_pk_bf16_f32 v0, v74, v75
	v_cvt_pk_bf16_f32 v1, v84, v85
	v_cvt_pk_bf16_f32 v2, v92, v93
	v_cvt_pk_bf16_f32 v3, v24, v25
	flat_store_dwordx4 v[6:7], v[0:3]
	v_lshl_add_u64 v[6:7], v[70:71], 0, s[6:7]
	s_nop 0
	v_cvt_pk_bf16_f32 v0, v4, v5
	v_cvt_pk_bf16_f32 v1, v40, v41
	v_cvt_pk_bf16_f32 v2, v48, v49
	v_cvt_pk_bf16_f32 v3, v14, v15
	flat_store_dwordx4 v[6:7], v[0:3]
	v_lshl_add_u64 v[4:5], v[72:73], 0, s[6:7]
	s_nop 0
	v_cvt_pk_bf16_f32 v0, v42, v43
	v_cvt_pk_bf16_f32 v1, v22, v23
	v_cvt_pk_bf16_f32 v2, v38, v39
	v_cvt_pk_bf16_f32 v3, v10, v11
	flat_store_dwordx4 v[4:5], v[0:3]

.LBB0_1067:
	s_or_b64 exec, exec, s[28:29]
	v_lshl_add_u32 v7, v162, 2, v151
	ds_read_b32 v6, v151 offset:17660
	ds_read_b128 v[8:11], v7 offset:17408
	ds_read_b128 v[12:15], v7 offset:17424
	s_waitcnt vmcnt(0)
	v_lshlrev_b32_e32 v17, 16, v176
	v_lshlrev_b32_e32 v16, 16, v173
	v_lshl_add_u64 v[4:5], s[18:19], 0, v[64:65]
	s_waitcnt lgkmcnt(0)
	v_sub_f32_e32 v8, v6, v8
	v_sub_f32_e32 v9, v6, v9
	v_mul_f32_e32 v8, 0x3fb8aa3b, v8
	v_mul_f32_e32 v9, 0x3fb8aa3b, v9
	v_exp_f32_e32 v8, v8
	v_exp_f32_e32 v9, v9
	v_sub_f32_e32 v10, v6, v10
	v_sub_f32_e32 v11, v6, v11
	v_mul_f32_e32 v10, 0x3fb8aa3b, v10
	v_mul_f32 v8, v8, v16
	v_mul_f32 v9, v9, v17
	v_mul_f32_e32 v11, 0x3fb8aa3b, v11
	v_cvt_pk_bf16_f32 v8, v8, v9
	v_sub_f32_e32 v9, v6, v12
	v_mul_f32_e32 v9, 0x3fb8aa3b, v9
	v_exp_f32_e32 v10, v10
	v_exp_f32_e32 v11, v11
	v_exp_f32_e32 v12, v9
	v_sub_f32_e32 v9, v6, v13
	v_mul_f32_e32 v9, 0x3fb8aa3b, v9
	v_exp_f32_e32 v13, v9
	v_lshlrev_b32_e32 v17, 16, v170
	v_lshlrev_b32_e32 v16, 16, v169
	v_mul_f32 v10, v10, v16
	v_mul_f32 v11, v11, v17
	v_lshlrev_b32_e32 v72, 7, v98
	v_cvt_pk_bf16_f32 v9, v10, v11
	v_lshlrev_b32_e32 v11, 16, v166
	v_lshlrev_b32_e32 v10, 16, v165
	v_mul_f32 v10, v12, v10
	v_mul_f32 v11, v13, v11
	v_sub_f32_e32 v12, v6, v14
	v_sub_f32_e32 v13, v6, v15
	v_mul_f32_e32 v12, 0x3fb8aa3b, v12
	v_mul_f32_e32 v13, 0x3fb8aa3b, v13
	v_exp_f32_e32 v12, v12
	v_exp_f32_e32 v13, v13
	v_lshl_add_u64 v[4:5], v[4:5], 0, v[72:73]
	v_lshlrev_b32_e32 v72, 1, v162
	v_lshlrev_b32_e32 v15, 16, v164
	v_lshlrev_b32_e32 v14, 16, v163
	v_lshl_add_u64 v[4:5], v[4:5], 0, v[72:73]
	v_mul_f32 v12, v12, v14
	v_mul_f32 v13, v13, v15
	v_cvt_pk_bf16_f32 v10, v10, v11
	v_cvt_pk_bf16_f32 v11, v12, v13
	flat_store_dwordx2 v[4:5], v[8:9]
	flat_store_dwordx2 v[4:5], v[10:11] offset:16
	ds_read_b128 v[8:11], v7 offset:17440
	ds_read_b128 v[12:15], v7 offset:17456
	v_lshlrev_b32_e32 v17, 16, v182
	v_lshlrev_b32_e32 v16, 16, v181
	s_waitcnt lgkmcnt(0)
	v_sub_f32_e32 v8, v6, v8
	v_sub_f32_e32 v9, v6, v9
	v_mul_f32_e32 v8, 0x3fb8aa3b, v8
	v_mul_f32_e32 v9, 0x3fb8aa3b, v9
	v_exp_f32_e32 v8, v8
	v_exp_f32_e32 v9, v9
	v_sub_f32_e32 v10, v6, v10
	v_sub_f32_e32 v11, v6, v11
	v_mul_f32_e32 v10, 0x3fb8aa3b, v10
	v_mul_f32 v8, v8, v16
	v_mul_f32 v9, v9, v17
	v_mul_f32_e32 v11, 0x3fb8aa3b, v11
	v_cvt_pk_bf16_f32 v8, v8, v9
	v_sub_f32_e32 v9, v6, v12
	v_mul_f32_e32 v9, 0x3fb8aa3b, v9
	v_exp_f32_e32 v10, v10
	v_exp_f32_e32 v11, v11
	v_exp_f32_e32 v12, v9
	v_sub_f32_e32 v9, v6, v13
	v_mul_f32_e32 v9, 0x3fb8aa3b, v9
	v_exp_f32_e32 v13, v9
	v_lshlrev_b32_e32 v17, 16, v178
	v_lshlrev_b32_e32 v16, 16, v177
	v_mul_f32 v10, v10, v16
	v_mul_f32 v11, v11, v17
	v_lshlrev_b32_e32 v17, 16, v191
	v_cvt_pk_bf16_f32 v9, v10, v11
	v_lshlrev_b32_e32 v11, 16, v172
	v_lshlrev_b32_e32 v10, 16, v171
	v_mul_f32 v10, v12, v10
	v_mul_f32 v11, v13, v11
	v_sub_f32_e32 v12, v6, v14
	v_sub_f32_e32 v13, v6, v15
	v_mul_f32_e32 v12, 0x3fb8aa3b, v12
	v_mul_f32_e32 v13, 0x3fb8aa3b, v13
	v_exp_f32_e32 v12, v12
	v_exp_f32_e32 v13, v13
	v_lshlrev_b32_e32 v15, 16, v168
	v_lshlrev_b32_e32 v14, 16, v167
	v_cvt_pk_bf16_f32 v10, v10, v11
	v_mul_f32 v12, v12, v14
	v_mul_f32 v13, v13, v15
	v_lshlrev_b32_e32 v16, 16, v189
	v_cvt_pk_bf16_f32 v11, v12, v13
	flat_store_dwordx2 v[4:5], v[8:9] offset:32
	flat_store_dwordx2 v[4:5], v[10:11] offset:48
	ds_read_b128 v[8:11], v7 offset:17472
	ds_read_b128 v[12:15], v7 offset:17488
	s_waitcnt lgkmcnt(0)
	v_sub_f32_e32 v8, v6, v8
	v_sub_f32_e32 v9, v6, v9
	v_mul_f32_e32 v8, 0x3fb8aa3b, v8
	v_mul_f32_e32 v9, 0x3fb8aa3b, v9
	v_exp_f32_e32 v8, v8
	v_exp_f32_e32 v9, v9
	v_sub_f32_e32 v10, v6, v10
	v_sub_f32_e32 v11, v6, v11
	v_mul_f32_e32 v10, 0x3fb8aa3b, v10
	v_mul_f32 v8, v8, v16
	v_mul_f32 v9, v9, v17
	v_mul_f32_e32 v11, 0x3fb8aa3b, v11
	v_cvt_pk_bf16_f32 v8, v8, v9
	v_sub_f32_e32 v9, v6, v12
	v_mul_f32_e32 v9, 0x3fb8aa3b, v9
	v_exp_f32_e32 v10, v10
	v_exp_f32_e32 v11, v11
	v_exp_f32_e32 v12, v9
	v_sub_f32_e32 v9, v6, v13
	v_mul_f32_e32 v9, 0x3fb8aa3b, v9
	v_exp_f32_e32 v13, v9
	v_lshlrev_b32_e32 v17, 16, v187
	v_lshlrev_b32_e32 v16, 16, v185
	v_mul_f32 v10, v10, v16
	v_mul_f32 v11, v11, v17
	v_lshlrev_b32_e32 v17, 16, v197
	v_cvt_pk_bf16_f32 v9, v10, v11
	v_lshlrev_b32_e32 v11, 16, v184
	v_lshlrev_b32_e32 v10, 16, v183
	v_mul_f32 v10, v12, v10
	v_mul_f32 v11, v13, v11
	v_sub_f32_e32 v12, v6, v14
	v_sub_f32_e32 v13, v6, v15
	v_mul_f32_e32 v12, 0x3fb8aa3b, v12
	v_mul_f32_e32 v13, 0x3fb8aa3b, v13
	v_exp_f32_e32 v12, v12
	v_exp_f32_e32 v13, v13
	v_lshlrev_b32_e32 v15, 16, v180
	v_lshlrev_b32_e32 v14, 16, v179
	v_cvt_pk_bf16_f32 v10, v10, v11
	v_mul_f32 v12, v12, v14
	v_mul_f32 v13, v13, v15
	v_lshlrev_b32_e32 v16, 16, v196
	v_cvt_pk_bf16_f32 v11, v12, v13
	flat_store_dwordx2 v[4:5], v[8:9] offset:8
	flat_store_dwordx2 v[4:5], v[10:11] offset:24
	ds_read_b128 v[8:11], v7 offset:17504
	ds_read_b128 v[12:15], v7 offset:17520
	s_waitcnt lgkmcnt(0)
	v_sub_f32_e32 v7, v6, v8
	v_mul_f32_e32 v7, 0x3fb8aa3b, v7
	v_exp_f32_e32 v8, v7
	v_sub_f32_e32 v7, v6, v9
	v_mul_f32_e32 v7, 0x3fb8aa3b, v7
	v_exp_f32_e32 v9, v7
	v_sub_f32_e32 v10, v6, v10
	v_sub_f32_e32 v11, v6, v11
	v_mul_f32_e32 v10, 0x3fb8aa3b, v10
	v_mul_f32 v8, v8, v16
	v_mul_f32 v9, v9, v17
	v_mul_f32_e32 v11, 0x3fb8aa3b, v11
	v_cvt_pk_bf16_f32 v8, v8, v9
	v_sub_f32_e32 v9, v6, v12
	v_mul_f32_e32 v9, 0x3fb8aa3b, v9
	v_exp_f32_e32 v10, v10
	v_exp_f32_e32 v11, v11
	v_exp_f32_e32 v12, v9
	v_sub_f32_e32 v9, v6, v13
	v_mul_f32_e32 v9, 0x3fb8aa3b, v9
	v_exp_f32_e32 v13, v9
	v_lshlrev_b32_e32 v17, 16, v195
	v_lshlrev_b32_e32 v16, 16, v194
	v_mul_f32 v10, v10, v16
	v_mul_f32 v11, v11, v17
	v_and_b32_e32 v7, 0x7f, v99
	v_cvt_pk_bf16_f32 v9, v10, v11
	v_lshlrev_b32_e32 v11, 16, v192
	v_lshlrev_b32_e32 v10, 16, v190
	v_mul_f32 v10, v12, v10
	v_mul_f32 v11, v13, v11
	v_sub_f32_e32 v12, v6, v14
	v_sub_f32_e32 v13, v6, v15
	v_mul_f32_e32 v12, 0x3fb8aa3b, v12
	v_mul_f32_e32 v13, 0x3fb8aa3b, v13
	v_exp_f32_e32 v12, v12
	v_exp_f32_e32 v13, v13
	v_lshlrev_b32_e32 v15, 16, v188
	v_lshlrev_b32_e32 v14, 16, v186
	v_cmp_gt_u32_e32 vcc, 64, v7
	v_mul_f32 v12, v12, v14
	v_mul_f32 v13, v13, v15
	v_cvt_pk_bf16_f32 v10, v10, v11
	v_cvt_pk_bf16_f32 v11, v12, v13
	flat_store_dwordx2 v[4:5], v[8:9] offset:40
	flat_store_dwordx2 v[4:5], v[10:11] offset:56
	s_and_saveexec_b64 s[28:29], vcc
	s_cbranch_execz .LBB0_1069
	v_lshlrev_b32_e32 v72, 2, v7
	v_add_u32_e32 v4, v151, v72
	ds_read_b32 v4, v4 offset:17408
	s_waitcnt lgkmcnt(0)
	v_mul_f32_e32 v4, 0x3fb8aa3b, v4
	v_exp_f32_e32 v8, v4
	v_lshlrev_b64 v[4:5], 8, v[68:69]
	v_lshl_add_u64 v[4:5], s[20:21], 0, v[4:5]
	v_lshl_add_u64 v[4:5], v[4:5], 0, v[72:73]
	flat_store_dword v[4:5], v8

.LBB0_1210:
	v_add_f32 v142, v142, 0
	v_add_f32 v143, v143, 0
	v_mov_b32_e32 v85, v110
	v_add_f32 v140, v140, v142
	v_add_f32 v141, v141, v143
	v_mov_b32_e32 v173, v80
	v_add_f32 v138, v138, v140
	v_add_f32 v139, v139, v141
	s_cmp_lg_u32 s19, s22
	v_add_f32 v136, v136, v138
	v_add_f32 v137, v137, v139
	s_mov_b32 s10, s22
	v_add_f32 v134, v134, v136
	v_add_f32 v135, v135, v137
	s_waitcnt lgkmcnt(0)
	v_add_f32 v132, v132, v134
	v_add_f32 v133, v133, v135
	s_barrier
	v_add_f32 v130, v130, v132
	v_add_f32 v131, v131, v133
	s_nop 0
	v_add_f32 v128, v128, v130
	v_add_f32 v129, v129, v131
	v_add_f32 v130, v170, 0
	v_add_f32 v131, v171, 0
	v_add_f32 v126, v126, v128
	v_add_f32 v127, v127, v129
	v_add_f32 v130, v168, v130
	v_add_f32 v131, v169, v131
	v_add_f32 v124, v124, v126
	v_add_f32 v125, v125, v127
	v_add_f32 v130, v166, v130
	v_add_f32 v131, v167, v131
	v_add_f32 v122, v122, v124
	v_add_f32 v123, v123, v125
	v_add_f32 v130, v164, v130
	v_add_f32 v131, v165, v131
	v_add_f32 v118, v118, v122
	v_add_f32 v119, v119, v123
	v_add_f32 v130, v162, v130
	v_add_f32 v131, v163, v131
	v_add_f32 v114, v114, v118
	v_add_f32 v115, v115, v119
	v_add_f32 v130, v160, v130
	v_add_f32 v131, v161, v131
	v_add_f32 v112, v112, v114
	v_add_f32 v113, v113, v115
	s_nop 0
	v_add_f32 v112, v120, v112
	v_add_f32 v113, v121, v113
	s_nop 0
	v_add_f32 v112, v116, v112
	v_add_f32 v113, v117, v113
	s_nop 0
	v_fma_f32 v84, v100, v84, v112
	v_fma_f32 v85, v101, v85, v113
	v_add_f32 v100, v158, v130
	v_add_f32 v101, v159, v131
	s_nop 0
	v_add_f32 v100, v156, v100
	v_add_f32 v101, v157, v101
	s_nop 0
	v_add_f32 v100, v154, v100
	v_add_f32 v101, v155, v101
	s_nop 0
	v_add_f32 v100, v152, v100
	v_add_f32 v101, v153, v101
	s_nop 0
	v_add_f32 v100, v150, v100
	v_add_f32 v101, v151, v101
	s_nop 0
	v_add_f32 v100, v146, v100
	v_add_f32 v101, v147, v101
	s_nop 0
	v_add_f32 v86, v86, v100
	v_add_f32 v87, v87, v101
	s_nop 0
	v_add_f32 v82, v82, v86
	v_add_f32 v83, v83, v87
	s_nop 0
	v_add_f32 v82, v148, v82
	v_add_f32 v83, v149, v83
	s_nop 0
	v_add_f32 v82, v144, v82
	v_add_f32 v83, v145, v83
	s_nop 0
	v_fma_f32 v100, v84, v172, v82
	v_fma_f32 v101, v85, v173, v83
	s_cbranch_scc0 .LBB0_1216
.LBB0_1211:
	s_bitcmp1_b32 s10, 0
	s_cselect_b32 s11, 0xb800, 0
	s_setprio 1
	v_or_b32_e32 v80, s11, v94
	v_add_u32_e32 v109, v80, v187
	ds_read_b128 v[220:223], v109
	ds_read_b128 v[224:227], v109 offset:64
	ds_read_b128 v[228:231], v109 offset:3328
	ds_read_b128 v[232:235], v109 offset:6656
	ds_read_b128 v[236:239], v109 offset:9984
	ds_read_b128 v[240:243], v109 offset:3392
	ds_read_b128 v[244:247], v109 offset:6720
	ds_read_b128 v[248:251], v109 offset:10048
	s_waitcnt lgkmcnt(7)
	v_mfma_f32_16x16x32_bf16 v[112:115], v[220:223], v[4:7], v[0:3]
	v_mfma_f32_16x16x32_bf16 v[82:85], v[220:223], v[16:19], v[0:3]
	ds_read_b128 v[220:223], v109 offset:128
	s_waitcnt lgkmcnt(7)
	v_mfma_f32_16x16x32_bf16 v[112:115], v[224:227], v[8:11], v[112:115]
	v_mfma_f32_16x16x32_bf16 v[82:85], v[224:227], v[20:23], v[82:85]
	ds_read_b128 v[224:227], v109 offset:3456
	s_waitcnt lgkmcnt(7)
	v_mfma_f32_16x16x32_bf16 v[120:123], v[228:231], v[4:7], v[0:3]
	v_mfma_f32_16x16x32_bf16 v[116:119], v[228:231], v[16:19], v[0:3]
	ds_read_b128 v[228:231], v109 offset:6784
	s_waitcnt lgkmcnt(5)
	v_mfma_f32_16x16x32_bf16 v[120:123], v[240:243], v[8:11], v[120:123]
	v_mfma_f32_16x16x32_bf16 v[116:119], v[240:243], v[20:23], v[116:119]
	ds_read_b128 v[240:243], v109 offset:10112
	v_mfma_f32_16x16x32_bf16 v[128:131], v[232:235], v[4:7], v[0:3]
	v_mfma_f32_16x16x32_bf16 v[124:127], v[232:235], v[16:19], v[0:3]
	s_waitcnt lgkmcnt(5)
	v_mfma_f32_16x16x32_bf16 v[128:131], v[244:247], v[8:11], v[128:131]
	v_mfma_f32_16x16x32_bf16 v[124:127], v[244:247], v[20:23], v[124:127]
	v_mfma_f32_16x16x32_bf16 v[136:139], v[236:239], v[4:7], v[0:3]
	v_mfma_f32_16x16x32_bf16 v[132:135], v[236:239], v[16:19], v[0:3]
	s_waitcnt lgkmcnt(4)
	v_mfma_f32_16x16x32_bf16 v[136:139], v[248:251], v[8:11], v[136:139]
	v_mfma_f32_16x16x32_bf16 v[132:135], v[248:251], v[20:23], v[132:135]
	s_waitcnt lgkmcnt(3)
	v_mfma_f32_16x16x32_bf16 v[148:151], v[220:223], v[24:27], v[82:85]
	s_waitcnt lgkmcnt(2)
	v_mfma_f32_16x16x32_bf16 v[120:123], v[224:227], v[12:15], v[120:123]
	v_mfma_f32_16x16x32_bf16 v[84:87], v[224:227], v[24:27], v[116:119]
	s_waitcnt lgkmcnt(1)
	v_mfma_f32_16x16x32_bf16 v[152:155], v[228:231], v[12:15], v[128:131]
	v_mfma_f32_16x16x32_bf16 v[156:159], v[228:231], v[24:27], v[124:127]
	v_mfma_f32_16x16x32_bf16 v[112:115], v[220:223], v[12:15], v[112:115]
	s_waitcnt lgkmcnt(0)
	v_mfma_f32_16x16x32_bf16 v[160:163], v[240:243], v[12:15], v[136:139]
	v_mfma_f32_16x16x32_bf16 v[164:167], v[240:243], v[24:27], v[132:135]
	s_nop 2
	s_setprio 0
	s_nop 3
	v_max3_f32 v80, v112, v113, v114
	v_max3_f32 v80, v80, v115, v120
	v_max3_f32 v80, v80, v121, v122
	v_max3_f32 v80, v80, v123, v152
	v_max3_f32 v80, v80, v153, v154
	v_max3_f32 v80, v80, v155, v160
	v_max3_f32 v80, v80, v161, v162
	v_max_f32_e32 v80, v80, v163
	v_mul_f32_e32 v80, 0x3e16c740, v80
	v_max_f32_e32 v80, s71, v80
	v_mov_b32_e32 v82, v80
	s_nop 1
	v_permlane16_swap_b32_e32 v80, v82
	v_max_f32_e32 v80, v80, v82
	v_mov_b32_e32 v82, v80
	s_nop 1
	v_permlane32_swap_b32_e32 v80, v82
	v_max3_f32 v144, v81, v80, v82
	v_sub_f32_e32 v80, v81, v144
	v_fma_f32 v81, v112, s70, -v144
	v_exp_f32_e32 v143, v81
	v_fma_f32 v81, v113, s70, -v144
	v_exp_f32_e32 v141, v81
	v_fma_f32 v81, v114, s70, -v144
	v_max3_f32 v112, v148, v149, v150
	v_max3_f32 v112, v112, v151, v84
	v_max3_f32 v112, v112, v85, v86
	v_max3_f32 v112, v112, v87, v156
	v_max3_f32 v112, v112, v157, v158
	v_max3_f32 v112, v112, v159, v164
	v_max3_f32 v112, v112, v165, v166
	v_max_f32_e32 v112, v112, v167
	v_mul_f32_e32 v112, 0x3e16c740, v112
	v_max_f32_e32 v112, s71, v112
	v_mov_b32_e32 v114, v112
	s_nop 1
	v_permlane16_swap_b32_e32 v112, v114
	v_max_f32_e32 v112, v112, v114
	v_mov_b32_e32 v114, v112
	v_exp_f32_e32 v139, v81
	v_fma_f32 v81, v115, s70, -v144
	v_permlane32_swap_b32_e32 v112, v114
	v_exp_f32_e32 v137, v81
	v_fma_f32 v81, v120, s70, -v144
	v_max3_f32 v146, v190, v112, v114
	v_exp_f32_e32 v135, v81
	v_fma_f32 v81, v121, s70, -v144
	v_fma_f32 v84, v84, s70, -v146
	v_exp_f32_e32 v133, v81
	v_fma_f32 v81, v122, s70, -v144
	v_exp_f32_e32 v134, v84
	v_fma_f32 v84, v85, s70, -v146
	v_exp_f32_e32 v131, v81
	v_fma_f32 v81, v123, s70, -v144
	v_exp_f32_e32 v132, v84
	v_fma_f32 v84, v86, s70, -v146
	v_exp_f32_e32 v129, v81
	v_fma_f32 v81, v152, s70, -v144
	v_exp_f32_e32 v130, v84
	v_fma_f32 v84, v87, s70, -v146
	v_exp_f32_e32 v127, v81
	v_fma_f32 v81, v153, s70, -v144
	v_exp_f32_e32 v128, v84
	v_fma_f32 v84, v156, s70, -v146
	v_exp_f32_e32 v125, v81
	v_fma_f32 v81, v154, s70, -v144
	v_exp_f32_e32 v126, v84
	v_fma_f32 v84, v157, s70, -v146
	v_exp_f32_e32 v123, v81
	v_fma_f32 v81, v155, s70, -v144
	v_fma_f32 v112, v148, s70, -v146
	v_exp_f32_e32 v124, v84
	v_fma_f32 v84, v158, s70, -v146
	v_exp_f32_e32 v119, v81
	v_fma_f32 v81, v160, s70, -v144
	v_exp_f32_e32 v142, v112
	v_fma_f32 v112, v149, s70, -v146
	v_exp_f32_e32 v122, v84
	v_fma_f32 v84, v159, s70, -v146
	v_exp_f32_e32 v115, v81
	v_fma_f32 v81, v161, s70, -v144
	v_exp_f32_e32 v140, v112
	v_fma_f32 v112, v150, s70, -v146
	v_exp_f32_e32 v118, v84
	v_fma_f32 v84, v164, s70, -v146
	v_fma_f32 v85, v166, s70, -v146
	v_exp_f32_e32 v113, v81
	v_fma_f32 v81, v162, s70, -v144
	v_exp_f32_e32 v110, v80
	v_fma_f32 v80, v163, s70, -v144
	v_sub_f32_e32 v116, v190, v146
	v_exp_f32_e32 v138, v112
	v_fma_f32 v112, v151, s70, -v146
	v_exp_f32_e32 v114, v84
	v_fma_f32 v84, v165, s70, -v146
	v_exp_f32_e32 v120, v85
	v_fma_f32 v85, v167, s70, -v146
	v_exp_f32_e32 v121, v81
	v_exp_f32_e32 v117, v80
	v_exp_f32_e32 v136, v112
	v_exp_f32_e32 v112, v84
	v_exp_f32_e32 v84, v116
	v_exp_f32_e32 v116, v85
	v_mul_f32 v70, v70, v110
	v_mul_f32 v71, v71, v110
	v_mul_f32 v68, v68, v110
	v_mul_f32 v69, v69, v110
	v_mul_f32 v66, v66, v110
	v_mul_f32 v67, v67, v110
	v_mul_f32 v64, v64, v110
	v_mul_f32 v65, v65, v110
	v_mul_f32 v74, v74, v110
	v_mul_f32 v75, v75, v110
	v_mul_f32 v72, v72, v110
	v_mul_f32 v73, v73, v110
	v_mul_f32 v82, v78, v110
	v_mul_f32 v83, v79, v110
	v_mul_f32 v80, v76, v110
	v_mul_f32 v81, v77, v110
	v_cvt_pk_bf16_f32 v152, v143, v141
	v_cvt_pk_bf16_f32 v153, v139, v137
	v_cvt_pk_bf16_f32 v154, v135, v133
	v_cvt_pk_bf16_f32 v155, v131, v129
	v_cvt_pk_bf16_f32 v76, v127, v125
	v_cvt_pk_bf16_f32 v77, v123, v119
	v_cvt_pk_bf16_f32 v78, v115, v113
	v_cvt_pk_bf16_f32 v79, v121, v117
	v_mul_f32 v54, v54, v84
	v_mul_f32 v55, v55, v84
	v_mul_f32 v52, v52, v84
	v_mul_f32 v53, v53, v84
	v_mul_f32 v50, v50, v84
	v_mul_f32 v51, v51, v84
	v_mul_f32 v48, v48, v84
	v_mul_f32 v49, v49, v84
	v_mul_f32 v58, v58, v84
	v_mul_f32 v59, v59, v84
	v_mul_f32 v56, v56, v84
	v_mul_f32 v57, v57, v84
	v_mul_f32 v62, v62, v84
	v_mul_f32 v63, v63, v84
	v_mul_f32 v60, v60, v84
	v_mul_f32 v61, v61, v84
	v_cvt_pk_bf16_f32 v148, v142, v140
	v_cvt_pk_bf16_f32 v149, v138, v136
	v_cvt_pk_bf16_f32 v150, v134, v132
	v_cvt_pk_bf16_f32 v151, v130, v128
	v_cvt_pk_bf16_f32 v156, v126, v124
	v_cvt_pk_bf16_f32 v157, v122, v118
	v_cvt_pk_bf16_f32 v158, v114, v112
	v_cvt_pk_bf16_f32 v159, v120, v116
	s_setprio 1
	v_add3_u32 v85, s11, v188, v189
	ds_read_b64_tr_b16 v[222:223], v85 offset:29184
	ds_read_b64_tr_b16 v[220:221], v85 offset:26624
	ds_read_b64_tr_b16 v[224:225], v85 offset:26656
	ds_read_b64_tr_b16 v[226:227], v85 offset:29216
	ds_read_b64_tr_b16 v[228:229], v85 offset:31744
	ds_read_b64_tr_b16 v[230:231], v85 offset:34304
	ds_read_b64_tr_b16 v[232:233], v85 offset:31776
	ds_read_b64_tr_b16 v[234:235], v85 offset:34336
	ds_read_b64_tr_b16 v[236:237], v85 offset:26688
	ds_read_b64_tr_b16 v[238:239], v85 offset:29248
	ds_read_b64_tr_b16 v[240:241], v85 offset:31808
	ds_read_b64_tr_b16 v[242:243], v85 offset:34368
	ds_read_b64_tr_b16 v[244:245], v85 offset:26720
	ds_read_b64_tr_b16 v[246:247], v85 offset:29280
	ds_read_b64_tr_b16 v[248:249], v85 offset:31840
	ds_read_b64_tr_b16 v[250:251], v85 offset:34400
	s_waitcnt lgkmcnt(14)
	v_mfma_f32_16x16x32_bf16 v[68:71], v[220:223], v[152:155], v[68:71]
	v_mfma_f32_16x16x32_bf16 v[52:55], v[220:223], v[148:151], v[52:55]
	s_waitcnt lgkmcnt(10)
	v_mfma_f32_16x16x32_bf16 v[68:71], v[228:231], v[76:79], v[68:71]
	v_mfma_f32_16x16x32_bf16 v[52:55], v[228:231], v[156:159], v[52:55]
	v_mfma_f32_16x16x32_bf16 v[64:67], v[224:227], v[152:155], v[64:67]
	v_mfma_f32_16x16x32_bf16 v[48:51], v[224:227], v[148:151], v[48:51]
	s_waitcnt lgkmcnt(8)
	v_mfma_f32_16x16x32_bf16 v[64:67], v[232:235], v[76:79], v[64:67]
	v_mfma_f32_16x16x32_bf16 v[48:51], v[232:235], v[156:159], v[48:51]
	s_waitcnt lgkmcnt(6)
	v_mfma_f32_16x16x32_bf16 v[72:75], v[236:239], v[152:155], v[72:75]
	v_mfma_f32_16x16x32_bf16 v[56:59], v[236:239], v[148:151], v[56:59]
	s_waitcnt lgkmcnt(4)
	v_mfma_f32_16x16x32_bf16 v[72:75], v[240:243], v[76:79], v[72:75]
	v_mfma_f32_16x16x32_bf16 v[56:59], v[240:243], v[156:159], v[56:59]
	s_waitcnt lgkmcnt(2)
	v_mfma_f32_16x16x32_bf16 v[60:63], v[244:247], v[148:151], v[60:63]
	v_mfma_f32_16x16x32_bf16 v[80:83], v[244:247], v[152:155], v[80:83]
	s_waitcnt lgkmcnt(0)
	v_mfma_f32_16x16x32_bf16 v[76:79], v[248:251], v[76:79], v[80:83]
	v_mfma_f32_16x16x32_bf16 v[60:63], v[248:251], v[156:159], v[60:63]
	s_nop 3
	s_setprio 0
	s_setprio 1
	ds_read_b128 v[220:223], v109 offset:13312
	ds_read_b128 v[224:227], v109 offset:13376
	ds_read_b128 v[228:231], v109 offset:16640
	ds_read_b128 v[232:235], v109 offset:19968
	ds_read_b128 v[236:239], v109 offset:23296
	ds_read_b128 v[240:243], v109 offset:16704
	ds_read_b128 v[244:247], v109 offset:20032
	ds_read_b128 v[248:251], v109 offset:23360
	s_waitcnt lgkmcnt(7)
	v_mfma_f32_16x16x32_bf16 v[148:151], v[220:223], v[4:7], v[0:3]
	v_mfma_f32_16x16x32_bf16 v[80:83], v[220:223], v[16:19], v[0:3]
	ds_read_b128 v[220:223], v109 offset:13440
	s_waitcnt lgkmcnt(7)
	v_mfma_f32_16x16x32_bf16 v[148:151], v[224:227], v[8:11], v[148:151]
	v_mfma_f32_16x16x32_bf16 v[80:83], v[224:227], v[20:23], v[80:83]
	ds_read_b128 v[224:227], v109 offset:16768
	s_waitcnt lgkmcnt(7)
	v_mfma_f32_16x16x32_bf16 v[156:159], v[228:231], v[4:7], v[0:3]
	v_mfma_f32_16x16x32_bf16 v[152:155], v[228:231], v[16:19], v[0:3]
	ds_read_b128 v[228:231], v109 offset:20096
	s_waitcnt lgkmcnt(5)
	v_mfma_f32_16x16x32_bf16 v[156:159], v[240:243], v[8:11], v[156:159]
	v_mfma_f32_16x16x32_bf16 v[152:155], v[240:243], v[20:23], v[152:155]
	ds_read_b128 v[240:243], v109 offset:23424
	v_mfma_f32_16x16x32_bf16 v[164:167], v[232:235], v[4:7], v[0:3]
	v_mfma_f32_16x16x32_bf16 v[160:163], v[232:235], v[16:19], v[0:3]
	s_waitcnt lgkmcnt(5)
	v_mfma_f32_16x16x32_bf16 v[164:167], v[244:247], v[8:11], v[164:167]
	v_mfma_f32_16x16x32_bf16 v[160:163], v[244:247], v[20:23], v[160:163]
	v_mfma_f32_16x16x32_bf16 v[190:193], v[236:239], v[4:7], v[0:3]
	v_mfma_f32_16x16x32_bf16 v[168:171], v[236:239], v[16:19], v[0:3]
	s_waitcnt lgkmcnt(4)
	v_mfma_f32_16x16x32_bf16 v[190:193], v[248:251], v[8:11], v[190:193]
	v_mfma_f32_16x16x32_bf16 v[168:171], v[248:251], v[20:23], v[168:171]
	s_waitcnt lgkmcnt(3)
	v_mfma_f32_16x16x32_bf16 v[148:151], v[220:223], v[12:15], v[148:151]
	v_mfma_f32_16x16x32_bf16 v[194:197], v[220:223], v[24:27], v[80:83]
	s_waitcnt lgkmcnt(2)
	v_mfma_f32_16x16x32_bf16 v[198:201], v[224:227], v[12:15], v[156:159]
	v_mfma_f32_16x16x32_bf16 v[202:205], v[224:227], v[24:27], v[152:155]
	s_waitcnt lgkmcnt(1)
	v_mfma_f32_16x16x32_bf16 v[206:209], v[228:231], v[12:15], v[164:167]
	v_mfma_f32_16x16x32_bf16 v[210:213], v[228:231], v[24:27], v[160:163]
	s_waitcnt lgkmcnt(0)
	v_mfma_f32_16x16x32_bf16 v[190:193], v[240:243], v[12:15], v[190:193]
	v_mfma_f32_16x16x32_bf16 v[214:217], v[240:243], v[24:27], v[168:171]
	s_nop 1
	s_setprio 0
	v_max3_f32 v80, v148, v149, v150
	v_max3_f32 v80, v80, v151, v198
	v_max3_f32 v80, v80, v199, v200
	v_max3_f32 v80, v80, v201, v206
	v_max3_f32 v80, v80, v207, v208
	v_max3_f32 v80, v80, v209, v190
	v_max3_f32 v80, v80, v191, v192
	v_max_f32_e32 v80, v80, v193
	v_mul_f32_e32 v80, 0x3e16c740, v80
	v_max_f32_e32 v80, s71, v80
	v_mov_b32_e32 v81, v80
	s_nop 1
	v_permlane16_swap_b32_e32 v80, v81
	v_max_f32_e32 v80, v80, v81
	v_mov_b32_e32 v81, v80
	s_nop 1
	v_permlane32_swap_b32_e32 v80, v81
	v_max3_f32 v81, v144, v80, v81
	v_fma_f32 v82, v148, s70, -v81
	v_exp_f32_e32 v171, v82
	v_fma_f32 v82, v149, s70, -v81
	v_exp_f32_e32 v169, v82
	v_fma_f32 v82, v150, s70, -v81
	v_exp_f32_e32 v167, v82
	v_fma_f32 v82, v151, s70, -v81
	v_exp_f32_e32 v165, v82
	v_fma_f32 v82, v198, s70, -v81
	v_exp_f32_e32 v163, v82
	v_fma_f32 v82, v199, s70, -v81
	v_exp_f32_e32 v161, v82
	v_fma_f32 v82, v200, s70, -v81
	v_exp_f32_e32 v159, v82
	v_fma_f32 v82, v201, s70, -v81
	v_exp_f32_e32 v157, v82
	v_fma_f32 v82, v206, s70, -v81
	v_exp_f32_e32 v155, v82
	v_fma_f32 v82, v207, s70, -v81
	v_exp_f32_e32 v153, v82
	v_fma_f32 v82, v208, s70, -v81
	v_exp_f32_e32 v151, v82
	v_fma_f32 v82, v209, s70, -v81
	v_exp_f32_e32 v147, v82
	v_fma_f32 v82, v190, s70, -v81
	v_exp_f32_e32 v87, v82
	v_fma_f32 v82, v191, s70, -v81
	v_exp_f32_e32 v83, v82
	v_fma_f32 v82, v192, s70, -v81
	v_exp_f32_e32 v149, v82
	v_fma_f32 v82, v193, s70, -v81
	v_exp_f32_e32 v145, v82
	v_max3_f32 v82, v194, v195, v196
	v_max3_f32 v82, v82, v197, v202
	v_max3_f32 v82, v82, v203, v204
	v_max3_f32 v82, v82, v205, v210
	v_max3_f32 v82, v82, v211, v212
	v_max3_f32 v82, v82, v213, v214
	v_max3_f32 v82, v82, v215, v216
	v_max_f32_e32 v82, v82, v217
	v_mul_f32_e32 v82, 0x3e16c740, v82
	v_max_f32_e32 v82, s71, v82
	v_mov_b32_e32 v86, v82
	s_nop 1
	v_permlane16_swap_b32_e32 v82, v86
	v_max_f32_e32 v82, v82, v86
	v_mov_b32_e32 v86, v82
	s_nop 1
	v_permlane32_swap_b32_e32 v82, v86
	v_max3_f32 v190, v146, v82, v86
	v_fma_f32 v82, v194, s70, -v190
	v_exp_f32_e32 v170, v82
	v_fma_f32 v82, v195, s70, -v190
	v_exp_f32_e32 v168, v82
	v_fma_f32 v82, v196, s70, -v190
	v_exp_f32_e32 v166, v82
	v_fma_f32 v82, v197, s70, -v190
	v_exp_f32_e32 v164, v82
	v_fma_f32 v82, v202, s70, -v190
	v_exp_f32_e32 v162, v82
	v_fma_f32 v82, v203, s70, -v190
	v_exp_f32_e32 v160, v82
	v_fma_f32 v82, v204, s70, -v190
	v_exp_f32_e32 v158, v82
	v_fma_f32 v82, v205, s70, -v190
	v_exp_f32_e32 v156, v82
	v_fma_f32 v82, v210, s70, -v190
	v_exp_f32_e32 v154, v82
	v_fma_f32 v82, v211, s70, -v190
	v_exp_f32_e32 v152, v82
	v_fma_f32 v82, v212, s70, -v190
	v_exp_f32_e32 v150, v82
	v_fma_f32 v82, v213, s70, -v190
	v_sub_f32_e32 v80, v144, v81
	v_sub_f32_e32 v109, v146, v190
	v_exp_f32_e32 v146, v82
	v_fma_f32 v82, v214, s70, -v190
	v_exp_f32_e32 v80, v80
	v_exp_f32_e32 v86, v82
	v_fma_f32 v82, v215, s70, -v190
	v_fma_f32 v144, v216, s70, -v190
	v_exp_f32_e32 v172, v109
	v_fma_f32 v109, v217, s70, -v190
	v_exp_f32_e32 v82, v82
	v_exp_f32_e32 v148, v144
	v_exp_f32_e32 v144, v109
	v_mul_f32 v70, v70, v80
	v_mul_f32 v71, v71, v80
	v_mul_f32 v68, v68, v80
	v_mul_f32 v69, v69, v80
	v_mul_f32 v66, v66, v80
	v_mul_f32 v67, v67, v80
	v_mul_f32 v64, v64, v80
	v_mul_f32 v65, v65, v80
	v_mul_f32 v74, v74, v80
	v_mul_f32 v75, v75, v80
	v_mul_f32 v72, v72, v80
	v_mul_f32 v73, v73, v80
	v_mul_f32 v200, v78, v80
	v_mul_f32 v201, v79, v80
	v_mul_f32 v198, v76, v80
	v_mul_f32 v199, v77, v80
	v_cvt_pk_bf16_f32 v76, v155, v153
	v_cvt_pk_bf16_f32 v77, v151, v147
	v_cvt_pk_bf16_f32 v78, v87, v83
	v_cvt_pk_bf16_f32 v79, v149, v145
	v_mul_f32 v54, v54, v172
	v_mul_f32 v55, v55, v172
	v_mul_f32 v52, v52, v172
	v_mul_f32 v53, v53, v172
	v_mul_f32 v50, v50, v172
	v_mul_f32 v51, v51, v172
	v_mul_f32 v48, v48, v172
	v_mul_f32 v49, v49, v172
	v_mul_f32 v58, v58, v172
	v_mul_f32 v59, v59, v172
	v_mul_f32 v56, v56, v172
	v_mul_f32 v57, v57, v172
	v_mul_f32 v62, v62, v172
	v_mul_f32 v63, v63, v172
	v_mul_f32 v60, v60, v172
	v_mul_f32 v61, v61, v172
	v_cvt_pk_bf16_f32 v206, v171, v169
	v_cvt_pk_bf16_f32 v207, v167, v165
	v_cvt_pk_bf16_f32 v208, v163, v161
	v_cvt_pk_bf16_f32 v209, v159, v157
	v_cvt_pk_bf16_f32 v192, v170, v168
	v_cvt_pk_bf16_f32 v193, v166, v164
	v_cvt_pk_bf16_f32 v194, v162, v160
	v_cvt_pk_bf16_f32 v195, v158, v156
	v_cvt_pk_bf16_f32 v202, v154, v152
	v_cvt_pk_bf16_f32 v203, v150, v146
	v_cvt_pk_bf16_f32 v204, v86, v82
	v_cvt_pk_bf16_f32 v205, v148, v144
	s_setprio 1
	ds_read_b64_tr_b16 v[222:223], v85 offset:39424
	ds_read_b64_tr_b16 v[220:221], v85 offset:36864
	ds_read_b64_tr_b16 v[224:225], v85 offset:36896
	ds_read_b64_tr_b16 v[226:227], v85 offset:39456
	ds_read_b64_tr_b16 v[228:229], v85 offset:41984
	ds_read_b64_tr_b16 v[230:231], v85 offset:44544
	ds_read_b64_tr_b16 v[232:233], v85 offset:42016
	ds_read_b64_tr_b16 v[234:235], v85 offset:44576
	ds_read_b64_tr_b16 v[236:237], v85 offset:36928
	ds_read_b64_tr_b16 v[238:239], v85 offset:39488
	ds_read_b64_tr_b16 v[240:241], v85 offset:42048
	ds_read_b64_tr_b16 v[242:243], v85 offset:44608
	ds_read_b64_tr_b16 v[244:245], v85 offset:36960
	ds_read_b64_tr_b16 v[246:247], v85 offset:39520
	ds_read_b64_tr_b16 v[248:249], v85 offset:42080
	ds_read_b64_tr_b16 v[250:251], v85 offset:44640
	s_waitcnt lgkmcnt(14)
	v_mfma_f32_16x16x32_bf16 v[68:71], v[220:223], v[206:209], v[68:71]
	v_mfma_f32_16x16x32_bf16 v[52:55], v[220:223], v[192:195], v[52:55]
	s_waitcnt lgkmcnt(10)
	v_mfma_f32_16x16x32_bf16 v[68:71], v[228:231], v[76:79], v[68:71]
	v_mfma_f32_16x16x32_bf16 v[52:55], v[228:231], v[202:205], v[52:55]
	v_mfma_f32_16x16x32_bf16 v[64:67], v[224:227], v[206:209], v[64:67]
	v_mfma_f32_16x16x32_bf16 v[48:51], v[224:227], v[192:195], v[48:51]
	s_waitcnt lgkmcnt(8)
	v_mfma_f32_16x16x32_bf16 v[64:67], v[232:235], v[76:79], v[64:67]
	v_mfma_f32_16x16x32_bf16 v[48:51], v[232:235], v[202:205], v[48:51]
	s_waitcnt lgkmcnt(6)
	v_mfma_f32_16x16x32_bf16 v[72:75], v[236:239], v[206:209], v[72:75]
	v_mfma_f32_16x16x32_bf16 v[56:59], v[236:239], v[192:195], v[56:59]
	s_waitcnt lgkmcnt(4)
	v_mfma_f32_16x16x32_bf16 v[72:75], v[240:243], v[76:79], v[72:75]
	v_mfma_f32_16x16x32_bf16 v[56:59], v[240:243], v[202:205], v[56:59]
	s_waitcnt lgkmcnt(2)
	v_mfma_f32_16x16x32_bf16 v[60:63], v[244:247], v[192:195], v[60:63]
	v_mfma_f32_16x16x32_bf16 v[196:199], v[244:247], v[206:209], v[198:201]
	s_waitcnt lgkmcnt(0)
	v_mfma_f32_16x16x32_bf16 v[76:79], v[248:251], v[76:79], v[196:199]
	v_mfma_f32_16x16x32_bf16 v[60:63], v[248:251], v[202:205], v[60:63]
	s_nop 3
	s_setprio 0
	s_add_i32 s22, s10, 1
	s_cmp_ge_u32 s22, s19
	s_cbranch_scc1 .LBB0_1213
	s_bitcmp1_b32 s22, 0
	s_cselect_b32 s11, 0xb800, 0
	v_add3_u32 v85, s11, v95, v96
	s_waitcnt vmcnt(0)
	ds_write_b128 v85, v[28:31]
	v_add3_u32 v85, s11, v99, v96
	ds_write_b128 v85, v[36:39]
	v_add3_u32 v85, s11, v185, v96
	ds_write_b128 v85, v[32:35] offset:26624
	v_add3_u32 v85, s11, v186, v96
	ds_write_b128 v85, v[40:43] offset:26624
	v_add3_u32 v85, s11, v111, v98
	ds_write_b128 v85, v[44:47] offset:128

.LBB0_1216:
	v_mov_b32_e32 v4, v101
	s_nop 1
	v_permlane16_swap_b32_e32 v101, v4
	v_add_f32_e32 v4, v101, v4
	v_mov_b32_e32 v5, v4
	s_nop 1
	v_permlane32_swap_b32_e32 v4, v5
	v_add_f32_e32 v4, v4, v5
	v_div_scale_f32 v5, s[6:7], v4, v4, 1.0
	v_rcp_f32_e32 v6, v5
	v_lshlrev_b32_e32 v88, 1, v97
	v_fma_f32 v7, -v5, v6, 1.0
	v_fmac_f32_e32 v6, v7, v6
	v_div_scale_f32 v7, vcc, 1.0, v4, 1.0
	v_mul_f32_e32 v8, v7, v6
	v_fma_f32 v9, -v5, v8, v7
	v_fmac_f32_e32 v8, v9, v6
	v_fma_f32 v5, -v5, v8, v7
	v_div_fmas_f32 v5, v5, v6, v8
	v_lshlrev_b64 v[6:7], 11, v[92:93]
	v_div_fixup_f32 v4, v5, v4, 1.0
	v_lshl_add_u64 v[6:7], s[48:49], 0, v[6:7]
	v_lshl_add_u64 v[6:7], v[6:7], 0, s[44:45]
	v_mul_f32 v8, v68, v4
	v_mul_f32 v9, v69, v4
	v_mul_f32 v10, v70, v4
	v_mul_f32 v11, v71, v4
	v_lshl_add_u64 v[6:7], v[6:7], 0, v[88:89]
	v_cvt_pk_bf16_f32 v8, v8, v9
	v_cvt_pk_bf16_f32 v9, v10, v11
	flat_store_dwordx2 v[6:7], v[8:9]
	v_mul_f32 v8, v64, v4
	v_mul_f32 v9, v65, v4
	v_mul_f32 v10, v66, v4
	v_mul_f32 v11, v67, v4
	v_cvt_pk_bf16_f32 v8, v8, v9
	v_cvt_pk_bf16_f32 v9, v10, v11
	flat_store_dwordx2 v[6:7], v[8:9] offset:32
	v_mul_f32 v8, v72, v4
	v_mul_f32 v9, v73, v4
	v_mul_f32 v10, v74, v4
	v_mul_f32 v11, v75, v4
	v_cvt_pk_bf16_f32 v8, v8, v9
	v_cvt_pk_bf16_f32 v9, v10, v11
	flat_store_dwordx2 v[6:7], v[8:9] offset:64
	v_mul_f32 v8, v76, v4
	v_mul_f32 v9, v77, v4
	v_mov_b32_e32 v5, v100
	s_nop 1
	v_permlane16_swap_b32_e32 v100, v5
	v_add_f32_e32 v5, v100, v5
	v_cvt_pk_bf16_f32 v8, v8, v9
	v_mov_b32_e32 v9, v5
	s_nop 1
	v_permlane32_swap_b32_e32 v5, v9
	v_add_f32_e32 v10, v5, v9
	v_div_scale_f32 v11, s[6:7], v10, v10, 1.0
	v_rcp_f32_e32 v12, v11
	v_mul_f32 v5, v79, v4
	v_mul_f32 v4, v78, v4
	s_nop 0
	v_cvt_pk_bf16_f32 v9, v4, v5
	v_fma_f32 v4, -v11, v12, 1.0
	v_fmac_f32_e32 v12, v4, v12
	v_div_scale_f32 v4, vcc, 1.0, v10, 1.0
	v_mul_f32_e32 v5, v4, v12
	flat_store_dwordx2 v[6:7], v[8:9] offset:96
	v_fma_f32 v6, -v11, v5, v4
	v_fmac_f32_e32 v5, v6, v12
	v_fma_f32 v4, -v11, v5, v4
	v_div_fmas_f32 v4, v4, v12, v5
	v_lshlrev_b64 v[6:7], 11, v[90:91]
	v_div_fixup_f32 v4, v4, v10, 1.0
	v_lshl_add_u64 v[6:7], s[48:49], 0, v[6:7]
	v_lshl_add_u64 v[6:7], v[6:7], 0, s[44:45]
	v_mul_f32 v8, v52, v4
	v_mul_f32 v9, v53, v4
	v_mul_f32 v10, v54, v4
	v_mul_f32 v11, v55, v4
	v_lshl_add_u64 v[6:7], v[6:7], 0, v[88:89]
	v_cvt_pk_bf16_f32 v8, v8, v9
	v_cvt_pk_bf16_f32 v9, v10, v11
	flat_store_dwordx2 v[6:7], v[8:9]
	v_mul_f32 v8, v48, v4
	v_mul_f32 v9, v49, v4
	v_mul_f32 v10, v50, v4
	v_mul_f32 v11, v51, v4
	v_cvt_pk_bf16_f32 v8, v8, v9
	v_cvt_pk_bf16_f32 v9, v10, v11
	flat_store_dwordx2 v[6:7], v[8:9] offset:32
	v_mul_f32 v8, v56, v4
	v_mul_f32 v9, v57, v4
	v_mul_f32 v10, v58, v4
	v_mul_f32 v11, v59, v4
	v_cvt_pk_bf16_f32 v8, v8, v9
	v_cvt_pk_bf16_f32 v9, v10, v11
	flat_store_dwordx2 v[6:7], v[8:9] offset:64
	v_mul_f32 v8, v60, v4
	v_mul_f32 v9, v61, v4
	v_mul_f32 v5, v63, v4
	v_mul_f32 v4, v62, v4
	v_cvt_pk_bf16_f32 v8, v8, v9
	v_cvt_pk_bf16_f32 v9, v4, v5
	flat_store_dwordx2 v[6:7], v[8:9] offset:96
	s_waitcnt lgkmcnt(0)
	s_barrier
	s_and_saveexec_b64 s[6:7], s[4:5]
	s_cbranch_execz .LBB0_1198
	v_readlane_b32 s2, v252, 23
	v_readlane_b32 s3, v252, 24
	s_nop 1
	v_mov_b64_e32 v[4:5], s[2:3]
	flat_atomic_add v4, v[4:5], v177 sc0
	s_waitcnt vmcnt(0) lgkmcnt(0)
	ds_write_b32 v178, v4
	s_branch .LBB0_1198

.LBB0_1234:
	s_bitcmp1_b32 s25, 0
	s_cselect_b32 s25, 0xb200, 0
	v_or_b32_e32 v102, s25, v68
	s_add_i32 s41, s25, s36
	v_or_b32_e32 v81, s25, v67
	s_add_i32 s41, s41, s37
	v_add_u32_e32 v86, v102, v70
	v_add_u32_e32 v44, s41, v69
	v_add_u32_e32 v106, v81, v70
	v_add_u32_e32 v86, 0x2000, v86
	ds_read_b64 v[46:47], v44 offset:36864
	ds_read_b128 v[90:93], v106
	ds_read2_b64 v[94:97], v86 offset0:128 offset1:132
	s_add_i32 s41, s25, s40
	v_cvt_pk_bf16_f32 v48, v4, v5
	v_cvt_pk_bf16_f32 v49, v6, v7
	v_cvt_pk_bf16_f32 v50, v8, v9
	v_cvt_pk_bf16_f32 v51, v10, v11
	s_waitcnt lgkmcnt(0)
	v_lshlrev_b32_e32 v44, 16, v46
	v_and_b32_e32 v45, 0xffff0000, v46
	v_lshlrev_b32_e32 v46, 16, v47
	v_and_b32_e32 v47, 0xffff0000, v47
	s_add_i32 s41, s41, s37
	v_cvt_pk_bf16_f32 v82, v12, v13
	v_mfma_f32_16x16x32_bf16 v[44:47], v[90:93], v[48:51], v[44:47]
	v_cvt_pk_bf16_f32 v83, v14, v15
	v_cvt_pk_bf16_f32 v84, v16, v17
	v_cvt_pk_bf16_f32 v85, v18, v19
	v_mfma_f32_16x16x32_bf16 v[90:93], v[94:97], v[48:51], v[0:3]
	ds_read_b128 v[94:97], v106 offset:64
	ds_read2_b64 v[98:101], v86 offset0:136 offset1:140
	v_add_u32_e32 v86, s41, v69
	ds_read_b64 v[86:87], v86 offset:36864
	s_waitcnt lgkmcnt(0)
	v_mfma_f32_16x16x32_bf16 v[94:97], v[94:97], v[82:85], v[44:47]
	s_andn2_b64 vcc, exec, s[22:23]
	v_mfma_f32_16x16x32_bf16 v[44:47], v[98:101], v[82:85], v[90:93]
	s_nop 2
	v_lshlrev_b32_e32 v92, 16, v87
	v_and_b32_e32 v93, 0xffff0000, v87
	v_add_u32_e32 v87, v102, v71
	v_lshlrev_b32_e32 v90, 16, v86
	v_and_b32_e32 v91, 0xffff0000, v86
	v_add_u32_e32 v86, v81, v71
	v_add_u32_e32 v87, 0x2000, v87
	ds_read_b128 v[98:101], v86
	ds_read2_b64 v[102:105], v87 offset0:128 offset1:132
	s_waitcnt lgkmcnt(0)
	v_mfma_f32_16x16x32_bf16 v[90:93], v[98:101], v[48:51], v[90:93]
	v_add_u32_e32 v81, v81, v72
	v_mfma_f32_16x16x32_bf16 v[48:51], v[102:105], v[48:51], v[0:3]
	ds_read_b128 v[98:101], v86 offset:64
	ds_read2_b64 v[102:105], v87 offset0:136 offset1:140
	v_mov_b32_e32 v86, s25
	s_waitcnt lgkmcnt(0)
	v_mfma_f32_16x16x32_bf16 v[90:93], v[98:101], v[82:85], v[90:93]
	v_mfma_f32_16x16x32_bf16 v[48:51], v[102:105], v[82:85], v[48:51]
	v_cvt_pk_bf16_f32 v82, v94, v95
	v_cvt_pk_bf16_f32 v83, v96, v97
	s_nop 4
	v_cvt_pk_bf16_f32 v84, v90, v91
	v_cvt_pk_bf16_f32 v85, v92, v93
	ds_write_b128 v79, v[82:85]
	s_waitcnt lgkmcnt(0)
	s_barrier
	ds_read_b128 v[90:93], v80
	s_waitcnt lgkmcnt(0)
	v_cndmask_b32_e64 v97, v93, v85, s[12:13]
	v_cndmask_b32_e64 v96, v92, v84, s[12:13]
	v_cndmask_b32_e64 v95, v91, v83, s[12:13]
	v_cndmask_b32_e64 v94, v90, v82, s[12:13]
	v_cndmask_b32_e64 v85, v85, v93, s[12:13]
	v_cndmask_b32_e64 v84, v84, v92, s[12:13]
	v_cndmask_b32_e64 v83, v83, v91, s[12:13]
	v_cndmask_b32_e64 v82, v82, v90, s[12:13]
	ds_read_b32 v86, v86 offset:45312
	ds_read_b128 v[90:93], v106 offset:18432
	ds_read_b128 v[98:101], v106 offset:18496
	ds_read_b128 v[102:105], v106 offset:20800
	s_waitcnt lgkmcnt(0)
	v_mfma_f32_16x16x32_bf16 v[90:93], v[90:93], v[94:97], v[0:3]
	v_mul_f32_e64 v6, v6, v86
	v_mul_f32_e64 v7, v7, v86
	v_mul_f32 v4, v4, v86
	v_mul_f32 v5, v5, v86
	v_mul_f32 v10, v10, v86
	v_mul_f32 v11, v11, v86
	v_mfma_f32_16x16x32_bf16 v[90:93], v[98:101], v[82:85], v[90:93]
	ds_read_b128 v[98:101], v106 offset:20736
	v_mul_f32 v8, v8, v86
	v_mul_f32 v9, v9, v86
	v_mul_f32 v14, v14, v86
	v_mul_f32 v15, v15, v86
	s_waitcnt lgkmcnt(0)
	v_mfma_f32_16x16x32_bf16 v[98:101], v[98:101], v[94:97], v[0:3]
	v_mul_f32_e64 v12, v12, v86
	v_mul_f32_e64 v13, v13, v86
	v_mul_f32 v18, v18, v86
	v_mul_f32 v19, v19, v86
	v_mul_f32 v16, v16, v86
	v_mul_f32 v17, v17, v86
	v_mfma_f32_16x16x32_bf16 v[98:101], v[102:105], v[82:85], v[98:101]
	ds_read_b128 v[102:105], v81 offset:27648
	v_add_u32_e32 v86, 16, v76
	s_waitcnt lgkmcnt(0)
	v_mfma_f32_16x16x32_bf16 v[4:7], v[102:105], v[94:97], v[4:7]
	ds_read_b128 v[102:105], v81 offset:27712
	s_waitcnt lgkmcnt(0)
	v_mfma_f32_16x16x32_bf16 v[4:7], v[102:105], v[82:85], v[4:7]
	ds_read_b128 v[102:105], v81 offset:29952
	s_waitcnt lgkmcnt(0)
	v_mfma_f32_16x16x32_bf16 v[8:11], v[102:105], v[94:97], v[8:11]
	ds_read_b128 v[102:105], v81 offset:30016
	s_waitcnt lgkmcnt(0)
	v_mfma_f32_16x16x32_bf16 v[8:11], v[102:105], v[82:85], v[8:11]
	ds_read_b128 v[102:105], v81 offset:32256
	s_waitcnt lgkmcnt(0)
	v_mfma_f32_16x16x32_bf16 v[12:15], v[102:105], v[94:97], v[12:15]
	ds_read_b128 v[102:105], v81 offset:32320
	s_waitcnt lgkmcnt(0)
	v_mfma_f32_16x16x32_bf16 v[12:15], v[102:105], v[82:85], v[12:15]
	ds_read_b128 v[102:105], v81 offset:34560
	s_waitcnt lgkmcnt(0)
	v_mfma_f32_16x16x32_bf16 v[16:19], v[102:105], v[94:97], v[16:19]
	ds_read_b128 v[94:97], v81 offset:34624
	v_add_u32_e32 v81, s25, v74
	s_waitcnt lgkmcnt(0)
	v_mfma_f32_16x16x32_bf16 v[16:19], v[94:97], v[82:85], v[16:19]
	ds_read_b128 v[82:85], v81 offset:45056
	v_add_u32_e32 v81, s34, v73
	v_cndmask_b32_e64 v86, v86, v81, s[6:7]
	v_ashrrev_i32_e32 v87, 31, v86
	v_lshl_add_u64 v[86:87], v[86:87], 0, s[20:21]
	s_waitcnt lgkmcnt(0)
	v_fma_f32 v44, v44, v82, v90
	v_bfe_u32 v82, v44, 16, 1
	v_lshlrev_b64 v[86:87], 9, v[86:87]
	v_add3_u32 v44, v44, v82, s60
	v_lshl_add_u64 v[86:87], v[54:55], 0, v[86:87]
	flat_store_short_d16_hi v[86:87], v44
	v_add_u32_e32 v44, 1, v81
	v_xad_u32 v82, v81, -2, s17
	v_cndmask_b32_e64 v86, v82, v44, s[6:7]
	v_ashrrev_i32_e32 v87, 31, v86
	v_fma_f32 v44, v45, v83, v91
	v_lshl_add_u64 v[86:87], v[86:87], 0, s[20:21]
	v_bfe_u32 v45, v44, 16, 1
	v_add3_u32 v82, v44, v45, s60
	v_lshlrev_b64 v[44:45], 9, v[86:87]
	v_lshl_add_u64 v[44:45], v[54:55], 0, v[44:45]
	flat_store_short_d16_hi v[44:45], v82
	v_add_u32_e32 v44, 2, v81
	v_xad_u32 v45, v81, -3, s17
	v_cndmask_b32_e64 v44, v45, v44, s[6:7]
	v_ashrrev_i32_e32 v45, 31, v44
	v_lshl_add_u64 v[44:45], v[44:45], 0, s[20:21]
	v_fma_f32 v46, v46, v84, v92
	v_bfe_u32 v82, v46, 16, 1
	v_lshlrev_b64 v[44:45], 9, v[44:45]
	v_add3_u32 v46, v46, v82, s60
	v_lshl_add_u64 v[44:45], v[54:55], 0, v[44:45]
	flat_store_short_d16_hi v[44:45], v46
	v_add_u32_e32 v44, 3, v81
	v_xad_u32 v45, v81, -4, s17
	v_cndmask_b32_e64 v44, v45, v44, s[6:7]
	v_ashrrev_i32_e32 v45, 31, v44
	v_lshl_add_u64 v[44:45], v[44:45], 0, s[20:21]
	v_fmac_f32_e32 v93, v47, v85
	v_bfe_u32 v46, v93, 16, 1
	v_lshlrev_b64 v[44:45], 9, v[44:45]
	v_add3_u32 v46, v93, v46, s60
	v_lshl_add_u64 v[44:45], v[54:55], 0, v[44:45]
	flat_store_short_d16_hi v[44:45], v46
	v_add_u32_e32 v44, s25, v75
	ds_read_b128 v[44:47], v44 offset:45056
	v_add_u32_e32 v84, 16, v81
	v_cndmask_b32_e64 v82, v76, v84, s[6:7]
	v_ashrrev_i32_e32 v83, 31, v82
	v_lshl_add_u64 v[82:83], v[82:83], 0, s[20:21]
	s_waitcnt lgkmcnt(0)
	v_fma_f32 v44, v48, v44, v98
	v_bfe_u32 v48, v44, 16, 1
	v_lshlrev_b64 v[82:83], 9, v[82:83]
	v_add3_u32 v44, v44, v48, s60
	v_lshl_add_u64 v[82:83], v[54:55], 0, v[82:83]
	flat_store_short_d16_hi v[82:83], v44
	v_add_u32_e32 v44, 17, v81
	v_xad_u32 v48, v84, -2, s17
	v_cndmask_b32_e64 v82, v48, v44, s[6:7]
	v_ashrrev_i32_e32 v83, 31, v82
	v_fma_f32 v44, v49, v45, v99
	v_lshl_add_u64 v[82:83], v[82:83], 0, s[20:21]
	v_bfe_u32 v45, v44, 16, 1
	v_add3_u32 v48, v44, v45, s60
	v_lshlrev_b64 v[44:45], 9, v[82:83]
	v_lshl_add_u64 v[44:45], v[54:55], 0, v[44:45]
	flat_store_short_d16_hi v[44:45], v48
	v_add_u32_e32 v44, 18, v81
	v_xad_u32 v45, v84, -3, s17
	v_cndmask_b32_e64 v44, v45, v44, s[6:7]
	v_ashrrev_i32_e32 v45, 31, v44
	v_lshl_add_u64 v[44:45], v[44:45], 0, s[20:21]
	v_fma_f32 v46, v50, v46, v100
	v_bfe_u32 v48, v46, 16, 1
	v_lshlrev_b64 v[44:45], 9, v[44:45]
	v_add3_u32 v46, v46, v48, s60
	v_lshl_add_u64 v[44:45], v[54:55], 0, v[44:45]
	flat_store_short_d16_hi v[44:45], v46
	v_add_u32_e32 v44, 19, v81
	v_xad_u32 v45, v84, -4, s17
	v_cndmask_b32_e64 v44, v45, v44, s[6:7]
	v_ashrrev_i32_e32 v45, 31, v44
	v_lshl_add_u64 v[44:45], v[44:45], 0, s[20:21]
	v_fmac_f32_e32 v101, v51, v47
	v_bfe_u32 v46, v101, 16, 1
	v_lshlrev_b64 v[44:45], 9, v[44:45]
	v_add3_u32 v46, v101, v46, s60
	v_lshl_add_u64 v[44:45], v[54:55], 0, v[44:45]
	flat_store_short_d16_hi v[44:45], v46
	s_cbranch_vccnz .LBB0_1231
	s_bitcmp1_b32 s24, 0
	s_cselect_b32 s25, 0xb200, 0
	v_add3_u32 v44, s25, v65, v88
	s_waitcnt vmcnt(0)
	ds_write_b128 v44, v[20:23]
	ds_write_b128 v44, v[36:39] offset:9216
	ds_write_b128 v44, v[24:27] offset:18432
	ds_write_b128 v44, v[28:31] offset:27648
	v_add_u32_e32 v44, s25, v64
	ds_write_b128 v44, v[32:35] offset:36864
	s_and_saveexec_b64 s[22:23], s[8:9]
	ds_write_b128 v44, v[40:43] offset:45056
	s_or_b64 exec, exec, s[22:23]
	s_and_saveexec_b64 s[22:23], s[10:11]
	s_cbranch_execz .LBB0_1230
	v_mov_b32_e32 v44, s25
	ds_write_b32 v44, v66 offset:45312
	s_branch .LBB0_1230

.Lhy_lat0_done:
.LBB0_1266:
	s_waitcnt vmcnt(0)
	s_xor_b64 s[12:13], s[6:7], -1
	s_and_b64 s[16:17], s[6:7], exec
	s_cselect_b32 s16, s82, 0xddf2000
	s_add_u32 s16, s8, s16
	s_addc_u32 s17, s9, 0
	v_cndmask_b32_e64 v30, v35, v34, s[6:7]
	s_and_b64 s[6:7], s[6:7], exec
	s_mov_b32 s6, 0x9380
	s_cselect_b32 s6, 0x4380, s6
	v_lshl_add_u64 v[32:33], v[20:21], 1, s[16:17]
	v_lshl_add_u32 v31, v20, 1, s6
	s_movk_i32 s6, 0x2000
	v_add_co_u32_e32 v42, vcc, s6, v32
	ds_read_b64 v[40:41], v31
	s_nop 0
	v_addc_co_u32_e32 v43, vcc, 0, v33, vcc
	v_mov_b32_e32 v49, v18
	s_waitcnt lgkmcnt(0)
	v_lshlrev_b32_e32 v47, 16, v41
	v_lshlrev_b32_e32 v46, 16, v40
	v_and_b32_e32 v41, 0xffff0000, v41
	v_and_b32_e32 v40, 0xffff0000, v40
	v_mov_b32_e32 v18, v17
	v_mov_b32_e32 v48, v16
	v_fma_f32 v16, v30, v40, v18
	v_fma_f32 v17, v30, v41, v19
	v_fma_f32 v46, v30, v46, v48
	v_fma_f32 v47, v30, v47, v49
	s_mov_b64 s[6:7], -1
	s_and_b64 vcc, exec, s[12:13]
	s_waitcnt vmcnt(0)
	v_lshlrev_b32_e32 v45, 16, v141
	v_lshlrev_b32_e32 v44, 16, v140
	v_and_b32_e32 v43, 0xffff0000, v141
	v_and_b32_e32 v42, 0xffff0000, v140
	v_mul_f32 v16, v16, v42
	v_mul_f32 v17, v17, v43
	v_mul_f32 v44, v46, v44
	v_mul_f32 v45, v47, v45
	v_and_b32_sdwa v31, v17, v177 dst_sel:DWORD dst_unused:UNUSED_PAD src0_sel:WORD_1 src1_sel:DWORD
	v_and_b32_sdwa v40, v16, v177 dst_sel:DWORD dst_unused:UNUSED_PAD src0_sel:WORD_1 src1_sel:DWORD
	v_and_b32_sdwa v18, v45, v177 dst_sel:DWORD dst_unused:UNUSED_PAD src0_sel:WORD_1 src1_sel:DWORD
	v_and_b32_sdwa v19, v44, v177 dst_sel:DWORD dst_unused:UNUSED_PAD src0_sel:WORD_1 src1_sel:DWORD
	v_add3_u32 v17, v17, v31, s60
	v_add3_u32 v16, v16, v40, s60
	v_add3_u32 v19, v44, v19, s60
	v_add3_u32 v18, v45, v18, s60
	v_and_b32_e32 v17, 0xffff0000, v17
	v_and_b32_e32 v16, 0xffff0000, v16
	v_or_b32_sdwa v17, v17, v18 dst_sel:DWORD dst_unused:UNUSED_PAD src0_sel:DWORD src1_sel:WORD_1
	v_or_b32_sdwa v16, v16, v19 dst_sel:DWORD dst_unused:UNUSED_PAD src0_sel:DWORD src1_sel:WORD_1
	s_cbranch_vccz .LBB0_1268
	flat_store_dwordx2 v[22:23], v[16:17]
	s_mov_b64 s[6:7], 0

.LBB0_1270:
	v_lshl_add_u64 v[16:17], v[32:33], 0, s[52:53]
	v_add_co_u32_e32 v32, vcc, 0x1000, v16
	v_lshl_add_u32 v18, v20, 1, s6
	s_nop 0
	v_addc_co_u32_e32 v33, vcc, 0, v17, vcc
	ds_read_b64 v[18:19], v18 offset:512
	v_mov_b32_e32 v31, v30
	v_mov_b32_e32 v45, v14
	v_mov_b32_e32 v14, v13
	v_mov_b32_e32 v44, v12
	s_waitcnt lgkmcnt(0)
	v_lshlrev_b32_e32 v43, 16, v19
	v_lshlrev_b32_e32 v42, 16, v18
	v_and_b32_e32 v19, 0xffff0000, v19
	v_and_b32_e32 v18, 0xffff0000, v18
	v_fma_f32 v12, v30, v18, v14
	v_fma_f32 v13, v31, v19, v15
	v_fma_f32 v42, v30, v42, v44
	v_fma_f32 v43, v31, v43, v45
	s_mov_b64 s[16:17], -1
	s_andn2_b64 vcc, exec, s[12:13]
	v_lshlrev_b32_e32 v41, 16, v143
	v_lshlrev_b32_e32 v40, 16, v142
	v_and_b32_e32 v33, 0xffff0000, v143
	v_and_b32_e32 v32, 0xffff0000, v142
	v_mul_f32 v12, v12, v32
	v_mul_f32 v13, v13, v33
	v_mul_f32 v40, v42, v40
	v_mul_f32 v41, v43, v41
	v_and_b32_sdwa v18, v13, v177 dst_sel:DWORD dst_unused:UNUSED_PAD src0_sel:WORD_1 src1_sel:DWORD
	v_and_b32_sdwa v14, v41, v177 dst_sel:DWORD dst_unused:UNUSED_PAD src0_sel:WORD_1 src1_sel:DWORD
	v_and_b32_sdwa v19, v12, v177 dst_sel:DWORD dst_unused:UNUSED_PAD src0_sel:WORD_1 src1_sel:DWORD
	v_add3_u32 v13, v13, v18, s60
	v_and_b32_sdwa v15, v40, v177 dst_sel:DWORD dst_unused:UNUSED_PAD src0_sel:WORD_1 src1_sel:DWORD
	v_add3_u32 v14, v41, v14, s60
	v_add3_u32 v12, v12, v19, s60
	v_and_b32_e32 v13, 0xffff0000, v13
	v_add3_u32 v15, v40, v15, s60
	v_and_b32_e32 v12, 0xffff0000, v12
	v_or_b32_sdwa v13, v13, v14 dst_sel:DWORD dst_unused:UNUSED_PAD src0_sel:DWORD src1_sel:WORD_1
	v_cndmask_b32_e64 v14, 0, 1, s[12:13]
	v_or_b32_sdwa v12, v12, v15 dst_sel:DWORD dst_unused:UNUSED_PAD src0_sel:DWORD src1_sel:WORD_1
	v_cmp_ne_u32_e64 s[6:7], 1, v14
	s_cbranch_vccnz .LBB0_1272
	s_mov_b64 s[16:17], 0
	flat_store_dwordx2 v[24:25], v[12:13]

.LBB0_1274:
	v_add_co_u32_e32 v14, vcc, 0x2000, v16
	v_lshl_add_u32 v12, v20, 1, s12
	s_nop 0
	v_addc_co_u32_e32 v15, vcc, 0, v17, vcc
	ds_read_b64 v[12:13], v12 offset:512
	v_mov_b32_e32 v41, v10
	v_mov_b32_e32 v10, v9
	v_mov_b32_e32 v40, v8
	s_mov_b64 s[12:13], -1
	s_waitcnt lgkmcnt(0)
	v_lshlrev_b32_e32 v33, 16, v13
	v_lshlrev_b32_e32 v32, 16, v12
	v_and_b32_e32 v13, 0xffff0000, v13
	v_and_b32_e32 v12, 0xffff0000, v12
	v_fma_f32 v8, v30, v12, v10
	v_fma_f32 v9, v31, v13, v11
	v_fma_f32 v32, v30, v32, v40
	v_fma_f32 v33, v31, v33, v41
	s_and_b64 vcc, exec, s[6:7]
	v_lshlrev_b32_e32 v19, 16, v145
	v_lshlrev_b32_e32 v18, 16, v144
	v_and_b32_e32 v15, 0xffff0000, v145
	v_and_b32_e32 v14, 0xffff0000, v144
	v_mul_f32 v8, v8, v14
	v_mul_f32 v9, v9, v15
	v_mul_f32 v18, v32, v18
	v_mul_f32 v19, v33, v19
	v_and_b32_sdwa v12, v9, v177 dst_sel:DWORD dst_unused:UNUSED_PAD src0_sel:WORD_1 src1_sel:DWORD
	v_and_b32_sdwa v13, v8, v177 dst_sel:DWORD dst_unused:UNUSED_PAD src0_sel:WORD_1 src1_sel:DWORD
	v_and_b32_sdwa v10, v19, v177 dst_sel:DWORD dst_unused:UNUSED_PAD src0_sel:WORD_1 src1_sel:DWORD
	v_and_b32_sdwa v11, v18, v177 dst_sel:DWORD dst_unused:UNUSED_PAD src0_sel:WORD_1 src1_sel:DWORD
	v_add3_u32 v9, v9, v12, s60
	v_add3_u32 v8, v8, v13, s60
	v_add3_u32 v11, v18, v11, s60
	v_add3_u32 v10, v19, v10, s60
	v_and_b32_e32 v9, 0xffff0000, v9
	v_and_b32_e32 v8, 0xffff0000, v8
	v_or_b32_sdwa v9, v9, v10 dst_sel:DWORD dst_unused:UNUSED_PAD src0_sel:DWORD src1_sel:WORD_1
	v_or_b32_sdwa v8, v8, v11 dst_sel:DWORD dst_unused:UNUSED_PAD src0_sel:DWORD src1_sel:WORD_1
	s_cbranch_vccnz .LBB0_1276
	s_mov_b64 s[12:13], 0
	flat_store_dwordx2 v[26:27], v[8:9]

.LBB0_1278:
	v_add_co_u32_e32 v10, vcc, 0x3000, v16
	v_lshl_add_u32 v8, v20, 1, s12
	s_nop 0
	v_addc_co_u32_e32 v11, vcc, 0, v17, vcc
	ds_read_b64 v[8:9], v8 offset:512
	v_mov_b32_e32 v17, v6
	v_mov_b32_e32 v6, v5
	v_mov_b32_e32 v16, v4
	s_mov_b64 s[12:13], -1
	s_waitcnt lgkmcnt(0)
	v_lshlrev_b32_e32 v15, 16, v9
	v_lshlrev_b32_e32 v14, 16, v8
	v_and_b32_e32 v9, 0xffff0000, v9
	v_and_b32_e32 v8, 0xffff0000, v8
	v_fma_f32 v4, v30, v8, v6
	v_fma_f32 v5, v31, v9, v7
	v_fma_f32 v14, v30, v14, v16
	v_fma_f32 v15, v31, v15, v17
	s_and_b64 vcc, exec, s[6:7]
	v_lshlrev_b32_e32 v13, 16, v147
	v_lshlrev_b32_e32 v12, 16, v146
	v_and_b32_e32 v11, 0xffff0000, v147
	v_and_b32_e32 v10, 0xffff0000, v146
	v_mul_f32 v4, v4, v10
	v_mul_f32 v5, v5, v11
	v_mul_f32 v12, v14, v12
	v_mul_f32 v13, v15, v13
	v_and_b32_sdwa v8, v5, v177 dst_sel:DWORD dst_unused:UNUSED_PAD src0_sel:WORD_1 src1_sel:DWORD
	v_and_b32_sdwa v9, v4, v177 dst_sel:DWORD dst_unused:UNUSED_PAD src0_sel:WORD_1 src1_sel:DWORD
	v_and_b32_sdwa v6, v13, v177 dst_sel:DWORD dst_unused:UNUSED_PAD src0_sel:WORD_1 src1_sel:DWORD
	v_and_b32_sdwa v7, v12, v177 dst_sel:DWORD dst_unused:UNUSED_PAD src0_sel:WORD_1 src1_sel:DWORD
	v_add3_u32 v5, v5, v8, s60
	v_add3_u32 v4, v4, v9, s60
	v_add3_u32 v7, v12, v7, s60
	v_add3_u32 v6, v13, v6, s60
	v_and_b32_e32 v5, 0xffff0000, v5
	v_and_b32_e32 v4, 0xffff0000, v4
	v_or_b32_sdwa v5, v5, v6 dst_sel:DWORD dst_unused:UNUSED_PAD src0_sel:DWORD src1_sel:WORD_1
	v_or_b32_sdwa v4, v4, v7 dst_sel:DWORD dst_unused:UNUSED_PAD src0_sel:DWORD src1_sel:WORD_1
	s_cbranch_vccnz .LBB0_1280
	s_mov_b64 s[12:13], 0
	flat_store_dwordx2 v[28:29], v[4:5]

.LBB0_1301:
	s_bitcmp1_b32 s33, 0
	s_cselect_b32 s78, 0x9800, 0
	s_cmp_lt_i32 s33, s92
	s_cselect_b64 s[6:7], -1, 0
	s_and_b64 s[76:77], s[72:73], s[6:7]
	s_cmp_eq_u64 s[76:77], 0
	s_cbranch_scc1 .Lnm0_entry
	s_setprio 1
	v_or_b32_e32 v68, s78, v94
	v_add_u32_e32 v88, v68, v163
	ds_read_b128 v[204:207], v88 offset:2304
	ds_read_b128 v[208:211], v88
	ds_read_b128 v[212:215], v88 offset:4608
	ds_read_b128 v[216:219], v88 offset:6912
	ds_read_b128 v[220:223], v88 offset:64
	ds_read_b128 v[224:227], v88 offset:2368
	ds_read_b128 v[228:231], v88 offset:4672
	ds_read_b128 v[232:235], v88 offset:6976
	s_waitcnt lgkmcnt(7)
	v_mfma_f32_16x16x32_bf16 v[82:85], v[204:207], v[4:7], v[0:3]
	v_mfma_f32_16x16x32_bf16 v[108:111], v[204:207], v[12:15], v[0:3]
	s_waitcnt lgkmcnt(5)
	v_mfma_f32_16x16x32_bf16 v[112:115], v[212:215], v[4:7], v[0:3]
	v_mfma_f32_16x16x32_bf16 v[116:119], v[212:215], v[12:15], v[0:3]
	s_waitcnt lgkmcnt(4)
	v_mfma_f32_16x16x32_bf16 v[120:123], v[216:219], v[4:7], v[0:3]
	v_mfma_f32_16x16x32_bf16 v[124:127], v[216:219], v[12:15], v[0:3]
	v_mfma_f32_16x16x32_bf16 v[74:77], v[208:211], v[4:7], v[0:3]
	v_mfma_f32_16x16x32_bf16 v[68:71], v[208:211], v[12:15], v[0:3]
	s_waitcnt lgkmcnt(3)
	v_mfma_f32_16x16x32_bf16 v[128:131], v[220:223], v[8:11], v[74:77]
	v_mfma_f32_16x16x32_bf16 v[76:79], v[220:223], v[16:19], v[68:71]
	s_waitcnt lgkmcnt(2)
	v_mfma_f32_16x16x32_bf16 v[132:135], v[224:227], v[8:11], v[82:85]
	v_mfma_f32_16x16x32_bf16 v[80:83], v[224:227], v[16:19], v[108:111]
	s_waitcnt lgkmcnt(1)
	v_mfma_f32_16x16x32_bf16 v[108:111], v[228:231], v[8:11], v[112:115]
	v_mfma_f32_16x16x32_bf16 v[84:87], v[228:231], v[16:19], v[116:119]
	s_waitcnt lgkmcnt(0)
	v_mfma_f32_16x16x32_bf16 v[112:115], v[232:235], v[8:11], v[120:123]
	v_mfma_f32_16x16x32_bf16 v[142:145], v[232:235], v[16:19], v[124:127]
	s_nop 1
	s_setprio 0
	v_add_u32_e32 v69, 0x73, v166
	v_cmp_gt_u32_e32 vcc, s83, v69
	v_add_u32_e32 v70, 0x72, v166
	s_and_b64 s[12:13], s[76:77], vcc
	v_cmp_gt_u32_e32 vcc, s83, v70
	v_add_u32_e32 v72, 0x71, v166
	s_and_b64 s[14:15], s[76:77], vcc
	v_cmp_gt_u32_e32 vcc, s83, v72
	v_add_u32_e32 v74, 0x70, v166
	s_and_b64 s[16:17], s[76:77], vcc
	v_cmp_gt_u32_e32 vcc, s83, v74
	v_add_u32_e32 v75, 0x63, v166
	s_and_b64 s[18:19], s[76:77], vcc
	v_cmp_gt_u32_e32 vcc, s83, v75
	v_add_u32_e32 v106, 0x62, v166
	s_and_b64 s[20:21], s[76:77], vcc
	v_cmp_gt_u32_e32 vcc, s83, v106
	v_add_u32_e32 v116, 0x61, v166
	s_and_b64 s[22:23], s[76:77], vcc
	v_cmp_gt_u32_e32 vcc, s83, v116
	v_add_u32_e32 v117, 0x60, v166
	s_and_b64 s[24:25], s[76:77], vcc
	v_cmp_gt_u32_e32 vcc, s83, v117
	v_add_u32_e32 v117, 0x53, v166
	s_and_b64 s[26:27], s[76:77], vcc
	v_cmp_gt_u32_e32 vcc, s83, v117
	v_add_u32_e32 v117, 0x52, v166
	v_mul_f32_e32 v68, 0x3e38aa3b, v128
	v_mul_f32_e32 v69, 0x3e38aa3b, v129
	s_and_b64 s[28:29], s[76:77], vcc
	v_cmp_gt_u32_e32 vcc, s83, v117
	v_add_u32_e32 v117, 0x51, v166
	v_cndmask_b32_e64 v68, v68, v182, s[12:13]
	v_cndmask_b32_e64 v69, v69, v182, s[14:15]
	v_mul_f32_e32 v71, 0x3e38aa3b, v130
	v_mul_f32_e32 v72, 0x3e38aa3b, v131
	s_and_b64 s[30:31], s[76:77], vcc
	v_cmp_gt_u32_e32 vcc, s83, v117
	v_add_u32_e32 v117, 0x50, v166
	v_max3_f32 v70, v68, s71, v69
	v_cndmask_b32_e64 v71, v71, v182, s[16:17]
	v_cndmask_b32_e64 v72, v72, v182, s[18:19]
	v_mul_f32_e32 v74, 0x3e38aa3b, v132
	v_mul_f32_e32 v75, 0x3e38aa3b, v133
	s_and_b64 s[34:35], s[76:77], vcc
	v_cmp_gt_u32_e32 vcc, s83, v117
	v_add_u32_e32 v117, 0x43, v166
	v_max3_f32 v70, v70, v71, v72
	v_cndmask_b32_e64 v74, v74, v182, s[20:21]
	v_cndmask_b32_e64 v75, v75, v182, s[22:23]
	v_mul_f32_e32 v106, 0x3e38aa3b, v134
	v_mul_f32_e32 v116, 0x3e38aa3b, v135
	s_and_b64 s[36:37], s[76:77], vcc
	v_cmp_gt_u32_e32 vcc, s83, v117
	v_add_u32_e32 v117, 0x42, v166
	v_max3_f32 v70, v70, v74, v75
	v_cndmask_b32_e64 v106, v106, v182, s[24:25]
	v_cndmask_b32_e64 v116, v116, v182, s[26:27]
	v_mul_f32_e32 v108, 0x3e38aa3b, v108
	v_mul_f32_e32 v109, 0x3e38aa3b, v109
	v_cmp_gt_u32_e64 s[6:7], s83, v117
	v_add_u32_e32 v117, 0x41, v166
	v_max3_f32 v70, v70, v106, v116
	v_cndmask_b32_e64 v108, v108, v182, s[28:29]
	v_cndmask_b32_e64 v109, v109, v182, s[30:31]
	v_mul_f32_e32 v110, 0x3e38aa3b, v110
	v_mul_f32_e32 v111, 0x3e38aa3b, v111
	v_cmp_gt_u32_e64 s[8:9], s83, v117
	v_add_u32_e32 v117, 64, v166
	v_max3_f32 v70, v70, v108, v109
	v_cndmask_b32_e64 v110, v110, v182, s[34:35]
	v_cndmask_b32_e64 v111, v111, v182, s[36:37]
	v_mul_f32_e32 v112, 0x3e38aa3b, v112
	s_and_b64 vcc, s[76:77], vcc
	v_mul_f32_e32 v113, 0x3e38aa3b, v113
	s_and_b64 s[6:7], s[76:77], s[6:7]
	v_cmp_gt_u32_e64 s[10:11], s83, v117
	v_max3_f32 v70, v70, v110, v111
	v_cndmask_b32_e32 v112, v112, v182, vcc
	v_cndmask_b32_e64 v113, v113, v182, s[6:7]
	v_mul_f32_e32 v114, 0x3e38aa3b, v114
	s_and_b64 s[8:9], s[76:77], s[8:9]
	v_mul_f32_e32 v115, 0x3e38aa3b, v115
	s_and_b64 s[10:11], s[76:77], s[10:11]
	v_max3_f32 v70, v70, v112, v113
	v_cndmask_b32_e64 v114, v114, v182, s[8:9]
	v_cndmask_b32_e64 v118, v115, v182, s[10:11]
	v_max3_f32 v70, v70, v114, v118
	v_mov_b32_e32 v115, v70
	s_nop 1
	v_permlane16_swap_b32_e32 v70, v115
	v_max_f32_e32 v70, v70, v115
	v_mov_b32_e32 v115, v70
	s_nop 1
	v_permlane32_swap_b32_e32 v70, v115
	v_max3_f32 v140, v73, v70, v115
	v_sub_f32_e32 v68, v68, v140
	v_exp_f32_e32 v139, v68
	v_sub_f32_e32 v68, v69, v140
	v_exp_f32_e32 v137, v68
	v_sub_f32_e32 v68, v71, v140
	v_exp_f32_e32 v135, v68
	v_sub_f32_e32 v68, v72, v140
	v_exp_f32_e32 v133, v68
	v_sub_f32_e32 v68, v74, v140
	v_exp_f32_e32 v131, v68
	v_sub_f32_e32 v68, v75, v140
	v_exp_f32_e32 v129, v68
	v_sub_f32_e32 v68, v106, v140
	v_exp_f32_e32 v127, v68
	v_sub_f32_e32 v68, v116, v140
	v_exp_f32_e32 v125, v68
	v_sub_f32_e32 v68, v108, v140
	v_add_u32_e32 v108, 0x83, v166
	v_cmp_gt_u32_e64 s[40:41], s83, v108
	v_mul_f32_e32 v76, 0x3e38aa3b, v76
	s_and_b64 s[40:41], s[76:77], s[40:41]
	v_add_u32_e32 v108, 0x82, v166
	v_exp_f32_e32 v123, v68
	v_sub_f32_e32 v68, v109, v140
	v_cndmask_b32_e64 v76, v76, v182, s[40:41]
	v_cmp_gt_u32_e64 s[40:41], s83, v108
	v_exp_f32_e32 v121, v68
	v_sub_f32_e32 v68, v110, v140
	v_mul_f32_e32 v77, 0x3e38aa3b, v77
	s_and_b64 s[40:41], s[76:77], s[40:41]
	v_add_u32_e32 v110, 0x81, v166
	v_cndmask_b32_e64 v77, v77, v182, s[40:41]
	v_cmp_gt_u32_e64 s[40:41], s83, v110
	v_mul_f32_e32 v78, 0x3e38aa3b, v78
	s_and_b64 s[40:41], s[76:77], s[40:41]
	v_cndmask_b32_e64 v110, v78, v182, s[40:41]
	v_mul_f32_e32 v78, 0x3e38aa3b, v79
	v_add_u32_e32 v79, 0x80, v166
	v_cmp_gt_u32_e64 s[40:41], s83, v79
	s_and_b64 s[40:41], s[76:77], s[40:41]
	v_max3_f32 v108, v76, s71, v77
	v_cndmask_b32_e64 v79, v78, v182, s[40:41]
	v_mul_f32_e32 v80, 0x3e38aa3b, v80
	v_mul_f32_e32 v81, 0x3e38aa3b, v81
	v_exp_f32_e32 v119, v68
	v_sub_f32_e32 v68, v111, v140
	v_max3_f32 v78, v108, v110, v79
	v_cndmask_b32_e64 v80, v80, v182, s[12:13]
	v_cndmask_b32_e64 v81, v81, v182, s[14:15]
	v_mul_f32_e32 v82, 0x3e38aa3b, v82
	v_mul_f32_e32 v83, 0x3e38aa3b, v83
	v_exp_f32_e32 v115, v68
	v_sub_f32_e32 v68, v112, v140
	v_max3_f32 v78, v78, v80, v81
	v_cndmask_b32_e64 v82, v82, v182, s[16:17]
	v_cndmask_b32_e64 v83, v83, v182, s[18:19]
	v_mul_f32_e32 v84, 0x3e38aa3b, v84
	v_mul_f32_e32 v85, 0x3e38aa3b, v85
	v_exp_f32_e32 v111, v68
	v_sub_f32_e32 v68, v113, v140
	v_max3_f32 v78, v78, v82, v83
	v_cndmask_b32_e64 v84, v84, v182, s[20:21]
	v_cndmask_b32_e64 v85, v85, v182, s[22:23]
	v_mul_f32_e32 v86, 0x3e38aa3b, v86
	v_mul_f32_e32 v87, 0x3e38aa3b, v87
	v_exp_f32_e32 v109, v68
	v_sub_f32_e32 v68, v114, v140
	v_max3_f32 v78, v78, v84, v85
	v_cndmask_b32_e64 v86, v86, v182, s[24:25]
	v_cndmask_b32_e64 v87, v87, v182, s[26:27]
	v_mul_f32_e32 v108, 0x3e38aa3b, v142
	v_mul_f32_e32 v112, 0x3e38aa3b, v143
	v_mul_f32_e32 v114, 0x3e38aa3b, v144
	v_max3_f32 v78, v78, v86, v87
	v_cndmask_b32_e64 v108, v108, v182, s[28:29]
	v_cndmask_b32_e64 v112, v112, v182, s[30:31]
	v_cndmask_b32_e64 v116, v114, v182, s[34:35]
	v_mul_f32_e32 v114, 0x3e38aa3b, v145
	v_max3_f32 v78, v78, v108, v112
	v_cndmask_b32_e64 v141, v114, v182, s[36:37]
	v_max3_f32 v78, v78, v116, v141
	v_mov_b32_e32 v114, v78
	s_nop 1
	v_permlane16_swap_b32_e32 v78, v114
	v_max_f32_e32 v78, v78, v114
	v_mov_b32_e32 v114, v78
	s_nop 1
	v_permlane32_swap_b32_e32 v78, v114
	v_max3_f32 v78, v167, v78, v114
	v_sub_f32_e32 v76, v76, v78
	v_exp_f32_e32 v138, v76
	v_sub_f32_e32 v76, v77, v78
	v_exp_f32_e32 v136, v76
	v_sub_f32_e32 v76, v110, v78
	v_exp_f32_e32 v134, v76
	v_sub_f32_e32 v76, v79, v78
	v_exp_f32_e32 v132, v76
	v_sub_f32_e32 v76, v80, v78
	v_exp_f32_e32 v130, v76
	v_sub_f32_e32 v76, v81, v78
	v_exp_f32_e32 v128, v76
	v_sub_f32_e32 v76, v82, v78
	v_exp_f32_e32 v126, v76
	v_sub_f32_e32 v76, v83, v78
	v_exp_f32_e32 v124, v76
	v_sub_f32_e32 v76, v84, v78
	v_exp_f32_e32 v122, v76
	v_sub_f32_e32 v76, v85, v78
	v_exp_f32_e32 v120, v76
	v_sub_f32_e32 v76, v86, v78
	v_exp_f32_e32 v117, v68
	v_sub_f32_e32 v68, v118, v140
	v_exp_f32_e32 v118, v76
	v_sub_f32_e32 v76, v87, v78
	v_exp_f32_e32 v114, v76
	v_sub_f32_e32 v76, v108, v78
	v_sub_f32_e32 v77, v116, v78
	v_sub_f32_e32 v70, v73, v140
	v_sub_f32_e32 v142, v167, v78
	v_exp_f32_e32 v110, v76
	v_sub_f32_e32 v76, v112, v78
	v_exp_f32_e32 v116, v77
	v_sub_f32_e32 v77, v141, v78
	v_exp_f32_e32 v106, v70
	v_exp_f32_e32 v113, v68
	v_exp_f32_e32 v108, v76
	v_exp_f32_e32 v76, v142
	v_exp_f32_e32 v112, v77
	v_mul_f32 v58, v58, v106
	v_mul_f32 v59, v59, v106
	v_mul_f32 v56, v56, v106
	v_mul_f32 v57, v57, v106
	v_mul_f32 v54, v54, v106
	v_mul_f32 v55, v55, v106
	v_mul_f32 v52, v52, v106
	v_mul_f32 v53, v53, v106
	v_mul_f32 v62, v62, v106
	v_mul_f32 v63, v63, v106
	v_mul_f32 v60, v60, v106
	v_mul_f32 v61, v61, v106
	v_mul_f32 v70, v66, v106
	v_mul_f32 v71, v67, v106
	v_mul_f32 v68, v64, v106
	v_mul_f32 v69, v65, v106
	v_cvt_pk_bf16_f32 v72, v139, v137
	v_cvt_pk_bf16_f32 v73, v135, v133
	v_cvt_pk_bf16_f32 v74, v131, v129
	v_cvt_pk_bf16_f32 v75, v127, v125
	v_cvt_pk_bf16_f32 v64, v123, v121
	v_cvt_pk_bf16_f32 v65, v119, v115
	v_cvt_pk_bf16_f32 v66, v111, v109
	v_cvt_pk_bf16_f32 v67, v117, v113
	v_mul_f32 v42, v42, v76
	v_mul_f32 v43, v43, v76
	v_mul_f32 v40, v40, v76
	v_mul_f32 v41, v41, v76
	v_mul_f32 v38, v38, v76
	v_mul_f32 v39, v39, v76
	v_mul_f32 v36, v36, v76
	v_mul_f32 v37, v37, v76
	v_mul_f32 v46, v46, v76
	v_mul_f32 v47, v47, v76
	v_mul_f32 v44, v44, v76
	v_mul_f32 v45, v45, v76
	v_mul_f32 v50, v50, v76
	v_mul_f32 v51, v51, v76
	v_mul_f32 v48, v48, v76
	v_mul_f32 v49, v49, v76
	v_cvt_pk_bf16_f32 v80, v138, v136
	v_cvt_pk_bf16_f32 v81, v134, v132
	v_cvt_pk_bf16_f32 v82, v130, v128
	v_cvt_pk_bf16_f32 v83, v126, v124
	v_cvt_pk_bf16_f32 v84, v122, v120
	v_cvt_pk_bf16_f32 v85, v118, v114
	v_cvt_pk_bf16_f32 v86, v110, v108
	v_cvt_pk_bf16_f32 v87, v116, v112
	s_setprio 1
	v_add3_u32 v77, s78, v164, v165
	ds_read_b64_tr_b16 v[206:207], v77 offset:20992
	ds_read_b64_tr_b16 v[204:205], v77 offset:18432
	ds_read_b64_tr_b16 v[208:209], v77 offset:18464
	ds_read_b64_tr_b16 v[210:211], v77 offset:21024
	ds_read_b64_tr_b16 v[212:213], v77 offset:23552
	ds_read_b64_tr_b16 v[214:215], v77 offset:26112
	ds_read_b64_tr_b16 v[216:217], v77 offset:23584
	ds_read_b64_tr_b16 v[218:219], v77 offset:26144
	ds_read_b64_tr_b16 v[220:221], v77 offset:18496
	ds_read_b64_tr_b16 v[222:223], v77 offset:21056
	ds_read_b64_tr_b16 v[224:225], v77 offset:23616
	ds_read_b64_tr_b16 v[226:227], v77 offset:26176
	ds_read_b64_tr_b16 v[228:229], v77 offset:18528
	ds_read_b64_tr_b16 v[230:231], v77 offset:21088
	ds_read_b64_tr_b16 v[232:233], v77 offset:23648
	ds_read_b64_tr_b16 v[234:235], v77 offset:26208
	s_waitcnt lgkmcnt(14)
	v_mfma_f32_16x16x32_bf16 v[56:59], v[204:207], v[72:75], v[56:59]
	v_mfma_f32_16x16x32_bf16 v[40:43], v[204:207], v[80:83], v[40:43]
	s_waitcnt lgkmcnt(10)
	v_mfma_f32_16x16x32_bf16 v[56:59], v[212:215], v[64:67], v[56:59]
	v_mfma_f32_16x16x32_bf16 v[40:43], v[212:215], v[84:87], v[40:43]
	v_mfma_f32_16x16x32_bf16 v[52:55], v[208:211], v[72:75], v[52:55]
	v_mfma_f32_16x16x32_bf16 v[36:39], v[208:211], v[80:83], v[36:39]
	s_waitcnt lgkmcnt(8)
	v_mfma_f32_16x16x32_bf16 v[52:55], v[216:219], v[64:67], v[52:55]
	v_mfma_f32_16x16x32_bf16 v[36:39], v[216:219], v[84:87], v[36:39]
	s_waitcnt lgkmcnt(6)
	v_mfma_f32_16x16x32_bf16 v[60:63], v[220:223], v[72:75], v[60:63]
	v_mfma_f32_16x16x32_bf16 v[44:47], v[220:223], v[80:83], v[44:47]
	s_waitcnt lgkmcnt(4)
	v_mfma_f32_16x16x32_bf16 v[60:63], v[224:227], v[64:67], v[60:63]
	v_mfma_f32_16x16x32_bf16 v[44:47], v[224:227], v[84:87], v[44:47]
	s_waitcnt lgkmcnt(2)
	v_mfma_f32_16x16x32_bf16 v[68:71], v[228:231], v[72:75], v[68:71]
	v_mfma_f32_16x16x32_bf16 v[48:51], v[228:231], v[80:83], v[48:51]
	s_waitcnt lgkmcnt(0)
	v_mfma_f32_16x16x32_bf16 v[64:67], v[232:235], v[64:67], v[68:71]
	v_mfma_f32_16x16x32_bf16 v[48:51], v[232:235], v[84:87], v[48:51]
	s_nop 3
	s_setprio 0
	s_setprio 1
	ds_read_b128 v[204:207], v88 offset:9216
	ds_read_b128 v[208:211], v88 offset:9280
	ds_read_b128 v[212:215], v88 offset:11520
	ds_read_b128 v[216:219], v88 offset:13824
	ds_read_b128 v[220:223], v88 offset:16128
	ds_read_b128 v[224:227], v88 offset:11584
	ds_read_b128 v[228:231], v88 offset:13888
	ds_read_b128 v[232:235], v88 offset:16192
	s_waitcnt lgkmcnt(7)
	v_mfma_f32_16x16x32_bf16 v[72:75], v[204:207], v[4:7], v[0:3]
	v_mfma_f32_16x16x32_bf16 v[68:71], v[204:207], v[12:15], v[0:3]
	s_waitcnt lgkmcnt(6)
	v_mfma_f32_16x16x32_bf16 v[168:171], v[208:211], v[16:19], v[68:71]
	v_mfma_f32_16x16x32_bf16 v[72:75], v[208:211], v[8:11], v[72:75]
	s_waitcnt lgkmcnt(5)
	v_mfma_f32_16x16x32_bf16 v[84:87], v[212:215], v[4:7], v[0:3]
	v_mfma_f32_16x16x32_bf16 v[80:83], v[212:215], v[12:15], v[0:3]
	s_waitcnt lgkmcnt(2)
	v_mfma_f32_16x16x32_bf16 v[84:87], v[224:227], v[8:11], v[84:87]
	v_mfma_f32_16x16x32_bf16 v[186:189], v[224:227], v[16:19], v[80:83]
	v_mfma_f32_16x16x32_bf16 v[146:149], v[216:219], v[4:7], v[0:3]
	v_mfma_f32_16x16x32_bf16 v[142:145], v[216:219], v[12:15], v[0:3]
	s_waitcnt lgkmcnt(1)
	v_mfma_f32_16x16x32_bf16 v[80:83], v[228:231], v[8:11], v[146:149]
	v_mfma_f32_16x16x32_bf16 v[190:193], v[228:231], v[16:19], v[142:145]
	v_mfma_f32_16x16x32_bf16 v[154:157], v[220:223], v[4:7], v[0:3]
	v_mfma_f32_16x16x32_bf16 v[150:153], v[220:223], v[12:15], v[0:3]
	s_waitcnt lgkmcnt(0)
	v_mfma_f32_16x16x32_bf16 v[142:145], v[232:235], v[8:11], v[154:157]
	v_mfma_f32_16x16x32_bf16 v[194:197], v[232:235], v[16:19], v[150:153]
	s_nop 0
	s_setprio 0
	v_mul_f32_e32 v68, 0x3e38aa3b, v72
	v_add_u32_e32 v69, 51, v166
	v_mul_f32_e32 v71, 0x3e38aa3b, v74
	v_add_u32_e32 v72, 49, v166
	v_add_u32_e32 v74, 35, v166
	v_cmp_gt_u32_e64 s[12:13], s83, v69
	v_mul_f32_e32 v69, 0x3e38aa3b, v73
	v_cmp_gt_u32_e64 s[16:17], s83, v72
	v_mul_f32_e32 v72, 0x3e38aa3b, v75
	v_add_u32_e32 v73, 48, v166
	v_cmp_gt_u32_e64 s[20:21], s83, v74
	v_add_u32_e32 v75, 34, v166
	v_cmp_gt_u32_e64 s[18:19], s83, v73
	v_mul_f32_e32 v73, 0x3e38aa3b, v84
	s_and_b64 s[20:21], s[76:77], s[20:21]
	v_cmp_gt_u32_e64 s[22:23], s83, v75
	v_add_u32_e32 v79, 33, v166
	v_cndmask_b32_e64 v74, v73, v182, s[20:21]
	v_mul_f32_e32 v73, 0x3e38aa3b, v85
	s_and_b64 s[22:23], s[76:77], s[22:23]
	v_cmp_gt_u32_e64 s[24:25], s83, v79
	v_add_u32_e32 v84, 32, v166
	v_cndmask_b32_e64 v75, v73, v182, s[22:23]
	v_mul_f32_e32 v73, 0x3e38aa3b, v86
	s_and_b64 s[24:25], s[76:77], s[24:25]
	v_cmp_gt_u32_e64 s[26:27], s83, v84
	v_cndmask_b32_e64 v79, v73, v182, s[24:25]
	v_mul_f32_e32 v73, 0x3e38aa3b, v87
	s_and_b64 s[26:27], s[76:77], s[26:27]
	v_cndmask_b32_e64 v84, v73, v182, s[26:27]
	v_mul_f32_e32 v73, 0x3e38aa3b, v80
	v_add_u32_e32 v80, 19, v166
	v_cmp_gt_u32_e64 s[28:29], s83, v80
	s_and_b64 s[28:29], s[76:77], s[28:29]
	v_add_u32_e32 v70, 50, v166
	v_cndmask_b32_e64 v80, v73, v182, s[28:29]
	v_mul_f32_e32 v73, 0x3e38aa3b, v81
	v_add_u32_e32 v81, 18, v166
	v_cmp_gt_u32_e64 s[30:31], s83, v81
	s_and_b64 s[30:31], s[76:77], s[30:31]
	v_cmp_gt_u32_e64 s[14:15], s83, v70
	v_cndmask_b32_e64 v81, v73, v182, s[30:31]
	v_mul_f32_e32 v73, 0x3e38aa3b, v82
	v_add_u32_e32 v82, 17, v166
	v_cmp_gt_u32_e64 s[34:35], s83, v82
	s_and_b64 s[34:35], s[76:77], s[34:35]
	v_add_u32_e32 v85, 3, v166
	v_cndmask_b32_e64 v82, v73, v182, s[34:35]
	v_mul_f32_e32 v73, 0x3e38aa3b, v83
	v_add_u32_e32 v83, 16, v166
	v_cmp_gt_u32_e64 s[36:37], s83, v83
	s_and_b64 s[12:13], s[76:77], s[12:13]
	s_and_b64 s[14:15], s[76:77], s[14:15]
	s_and_b64 s[36:37], s[76:77], s[36:37]
	v_cmp_gt_u32_e64 s[40:41], s83, v85
	v_cndmask_b32_e64 v68, v68, v182, s[12:13]
	v_cndmask_b32_e64 v69, v69, v182, s[14:15]
	s_and_b64 s[16:17], s[76:77], s[16:17]
	s_and_b64 s[18:19], s[76:77], s[18:19]
	v_cndmask_b32_e64 v83, v73, v182, s[36:37]
	v_mul_f32_e32 v73, 0x3e38aa3b, v142
	s_and_b64 s[40:41], s[76:77], s[40:41]
	v_add_u32_e32 v86, 2, v166
	v_max3_f32 v70, v68, s71, v69
	v_cndmask_b32_e64 v71, v71, v182, s[16:17]
	v_cndmask_b32_e64 v72, v72, v182, s[18:19]
	v_cndmask_b32_e64 v85, v73, v182, s[40:41]
	v_cmp_gt_u32_e64 s[40:41], s83, v86
	v_max3_f32 v70, v70, v71, v72
	v_mul_f32_e32 v73, 0x3e38aa3b, v143
	s_and_b64 s[40:41], s[76:77], s[40:41]
	v_add_u32_e32 v87, 1, v166
	v_max3_f32 v70, v70, v74, v75
	v_cndmask_b32_e64 v86, v73, v182, s[40:41]
	v_cmp_gt_u32_e64 s[40:41], s83, v87
	v_max3_f32 v70, v70, v79, v84
	v_mul_f32_e32 v73, 0x3e38aa3b, v144
	s_and_b64 s[40:41], s[76:77], s[40:41]
	v_max3_f32 v70, v70, v80, v81
	v_cndmask_b32_e64 v88, v73, v182, s[40:41]
	v_cmp_gt_u32_e64 s[40:41], s83, v166
	v_max3_f32 v70, v70, v82, v83
	v_mul_f32_e32 v73, 0x3e38aa3b, v145
	s_and_b64 s[40:41], s[76:77], s[40:41]
	v_max3_f32 v70, v70, v85, v86
	v_cndmask_b32_e64 v142, v73, v182, s[40:41]
	v_max3_f32 v70, v70, v88, v142
	v_mov_b32_e32 v73, v70
	s_nop 1
	v_permlane16_swap_b32_e32 v70, v73
	v_max_f32_e32 v70, v70, v73
	v_mov_b32_e32 v73, v70
	s_nop 1
	v_permlane32_swap_b32_e32 v70, v73
	v_max3_f32 v73, v140, v70, v73
	v_sub_f32_e32 v68, v68, v73
	v_exp_f32_e32 v159, v68
	v_sub_f32_e32 v68, v69, v73
	v_exp_f32_e32 v157, v68
	v_sub_f32_e32 v68, v71, v73
	v_exp_f32_e32 v155, v68
	v_sub_f32_e32 v68, v72, v73
	v_exp_f32_e32 v153, v68
	v_sub_f32_e32 v68, v74, v73
	v_exp_f32_e32 v151, v68
	v_sub_f32_e32 v68, v75, v73
	v_exp_f32_e32 v149, v68
	v_sub_f32_e32 v68, v79, v73
	v_exp_f32_e32 v147, v68
	v_sub_f32_e32 v68, v84, v73
	v_exp_f32_e32 v145, v68
	v_sub_f32_e32 v68, v80, v73
	v_exp_f32_e32 v143, v68
	v_sub_f32_e32 v68, v81, v73
	v_exp_f32_e32 v141, v68
	v_sub_f32_e32 v68, v82, v73
	v_sub_f32_e32 v70, v140, v73
	v_exp_f32_e32 v87, v68
	v_sub_f32_e32 v68, v83, v73
	v_exp_f32_e32 v83, v68
	v_sub_f32_e32 v68, v85, v73
	v_exp_f32_e32 v72, v70
	v_exp_f32_e32 v79, v68
	v_sub_f32_e32 v68, v86, v73
	v_exp_f32_e32 v75, v68
	v_sub_f32_e32 v68, v88, v73
	v_exp_f32_e32 v85, v68
	v_sub_f32_e32 v68, v142, v73
	v_exp_f32_e32 v81, v68
	v_mul_f32 v68, v64, v72
	v_mul_f32 v69, v65, v72
	v_mul_f32_e32 v64, 0x3e38aa3b, v168
	v_cndmask_b32_e32 v74, v64, v182, vcc
	v_mul_f32_e32 v64, 0x3e38aa3b, v169
	v_cndmask_b32_e64 v80, v64, v182, s[6:7]
	v_mul_f32_e32 v64, 0x3e38aa3b, v170
	v_cndmask_b32_e64 v82, v64, v182, s[8:9]
	v_mul_f32_e32 v64, 0x3e38aa3b, v171
	v_cndmask_b32_e64 v84, v64, v182, s[10:11]
	v_mul_f32_e32 v64, 0x3e38aa3b, v186
	v_cndmask_b32_e64 v86, v64, v182, s[12:13]
	v_mul_f32_e32 v64, 0x3e38aa3b, v187
	v_cndmask_b32_e64 v88, v64, v182, s[14:15]
	v_mul_f32_e32 v64, 0x3e38aa3b, v188
	v_cndmask_b32_e64 v140, v64, v182, s[16:17]
	v_mul_f32_e32 v64, 0x3e38aa3b, v189
	v_cndmask_b32_e64 v142, v64, v182, s[18:19]
	v_mul_f32_e32 v64, 0x3e38aa3b, v190
	v_cndmask_b32_e64 v160, v64, v182, s[20:21]
	v_mul_f32_e32 v64, 0x3e38aa3b, v191
	v_cndmask_b32_e64 v161, v64, v182, s[22:23]
	v_mul_f32_e32 v64, 0x3e38aa3b, v192
	v_cndmask_b32_e64 v172, v64, v182, s[24:25]
	v_mul_f32_e32 v64, 0x3e38aa3b, v193
	v_cndmask_b32_e64 v173, v64, v182, s[26:27]
	v_mul_f32_e32 v64, 0x3e38aa3b, v194
	v_cndmask_b32_e64 v185, v64, v182, s[28:29]
	v_mul_f32_e32 v64, 0x3e38aa3b, v195
	v_cndmask_b32_e64 v186, v64, v182, s[30:31]
	v_mul_f32_e32 v64, 0x3e38aa3b, v196
	v_cndmask_b32_e64 v187, v64, v182, s[34:35]
	v_mul_f32_e32 v64, 0x3e38aa3b, v197
	v_cndmask_b32_e64 v188, v64, v182, s[36:37]
	v_max3_f32 v64, v74, s71, v80
	v_max3_f32 v64, v64, v82, v84
	v_max3_f32 v64, v64, v86, v88
	v_max3_f32 v64, v64, v140, v142
	v_max3_f32 v64, v64, v160, v161
	v_max3_f32 v64, v64, v172, v173
	v_max3_f32 v144, v64, v185, v186
	v_max3_f32 v144, v144, v187, v188
	v_mov_b32_e32 v146, v144
	s_nop 1
	v_permlane16_swap_b32_e32 v144, v146
	v_max_f32_e32 v144, v144, v146
	v_mov_b32_e32 v146, v144
	s_nop 1
	v_permlane32_swap_b32_e32 v144, v146
	v_max3_f32 v167, v78, v144, v146
	v_sub_f32_e32 v74, v74, v167
	v_exp_f32_e32 v158, v74
	v_sub_f32_e32 v74, v80, v167
	v_exp_f32_e32 v156, v74
	v_sub_f32_e32 v74, v82, v167
	v_exp_f32_e32 v154, v74
	v_sub_f32_e32 v74, v84, v167
	v_exp_f32_e32 v152, v74
	v_sub_f32_e32 v74, v86, v167
	v_exp_f32_e32 v150, v74
	v_sub_f32_e32 v74, v88, v167
	v_exp_f32_e32 v148, v74
	v_sub_f32_e32 v74, v140, v167
	v_exp_f32_e32 v146, v74
	v_sub_f32_e32 v74, v142, v167
	v_exp_f32_e32 v144, v74
	v_sub_f32_e32 v74, v160, v167
	v_exp_f32_e32 v142, v74
	v_sub_f32_e32 v74, v161, v167
	v_exp_f32_e32 v140, v74
	v_sub_f32_e32 v74, v172, v167
	v_exp_f32_e32 v86, v74
	v_sub_f32_e32 v74, v173, v167
	v_sub_f32_e32 v189, v78, v167
	v_exp_f32_e32 v82, v74
	v_sub_f32_e32 v74, v185, v167
	v_sub_f32_e32 v80, v187, v167
	v_exp_f32_e32 v78, v74
	v_sub_f32_e32 v74, v186, v167
	v_exp_f32_e32 v160, v189
	v_exp_f32_e32 v84, v80
	v_sub_f32_e32 v80, v188, v167
	v_exp_f32_e32 v74, v74
	v_exp_f32_e32 v80, v80
	v_mul_f32 v58, v58, v72
	v_mul_f32 v59, v59, v72
	v_mul_f32 v56, v56, v72
	v_mul_f32 v57, v57, v72
	v_mul_f32 v54, v54, v72
	v_mul_f32 v55, v55, v72
	v_mul_f32 v52, v52, v72
	v_mul_f32 v53, v53, v72
	v_mul_f32 v62, v62, v72
	v_mul_f32 v63, v63, v72
	v_mul_f32 v60, v60, v72
	v_mul_f32 v61, v61, v72
	v_mul_f32 v70, v66, v72
	v_mul_f32 v71, v67, v72
	v_cvt_pk_bf16_f32 v64, v143, v141
	v_cvt_pk_bf16_f32 v65, v87, v83
	v_cvt_pk_bf16_f32 v66, v79, v75
	v_cvt_pk_bf16_f32 v67, v85, v81
	v_mul_f32 v42, v42, v160
	v_mul_f32 v43, v43, v160
	v_mul_f32 v40, v40, v160
	v_mul_f32 v41, v41, v160
	v_mul_f32 v38, v38, v160
	v_mul_f32 v39, v39, v160
	v_mul_f32 v36, v36, v160
	v_mul_f32 v37, v37, v160
	v_mul_f32 v46, v46, v160
	v_mul_f32 v47, v47, v160
	v_mul_f32 v44, v44, v160
	v_mul_f32 v45, v45, v160
	v_mul_f32 v50, v50, v160
	v_mul_f32 v51, v51, v160
	v_mul_f32 v48, v48, v160
	v_mul_f32 v49, v49, v160
	v_cvt_pk_bf16_f32 v168, v159, v157
	v_cvt_pk_bf16_f32 v169, v155, v153
	v_cvt_pk_bf16_f32 v170, v151, v149
	v_cvt_pk_bf16_f32 v171, v147, v145
	v_cvt_pk_bf16_f32 v186, v158, v156
	v_cvt_pk_bf16_f32 v187, v154, v152
	v_cvt_pk_bf16_f32 v188, v150, v148
	v_cvt_pk_bf16_f32 v189, v146, v144
	v_cvt_pk_bf16_f32 v190, v142, v140
	v_cvt_pk_bf16_f32 v191, v86, v82
	v_cvt_pk_bf16_f32 v192, v78, v74
	v_cvt_pk_bf16_f32 v193, v84, v80
	s_setprio 1
	ds_read_b64_tr_b16 v[206:207], v77 offset:31232
	ds_read_b64_tr_b16 v[204:205], v77 offset:28672
	ds_read_b64_tr_b16 v[208:209], v77 offset:28704
	ds_read_b64_tr_b16 v[210:211], v77 offset:31264
	ds_read_b64_tr_b16 v[212:213], v77 offset:33792
	ds_read_b64_tr_b16 v[214:215], v77 offset:36352
	ds_read_b64_tr_b16 v[216:217], v77 offset:33824
	ds_read_b64_tr_b16 v[218:219], v77 offset:36384
	ds_read_b64_tr_b16 v[220:221], v77 offset:28736
	ds_read_b64_tr_b16 v[222:223], v77 offset:31296
	ds_read_b64_tr_b16 v[224:225], v77 offset:33856
	ds_read_b64_tr_b16 v[226:227], v77 offset:36416
	ds_read_b64_tr_b16 v[228:229], v77 offset:28768
	ds_read_b64_tr_b16 v[230:231], v77 offset:31328
	ds_read_b64_tr_b16 v[232:233], v77 offset:33888
	ds_read_b64_tr_b16 v[234:235], v77 offset:36448
	s_waitcnt lgkmcnt(14)
	v_mfma_f32_16x16x32_bf16 v[56:59], v[204:207], v[168:171], v[56:59]
	v_mfma_f32_16x16x32_bf16 v[40:43], v[204:207], v[186:189], v[40:43]
	s_waitcnt lgkmcnt(10)
	v_mfma_f32_16x16x32_bf16 v[56:59], v[212:215], v[64:67], v[56:59]
	v_mfma_f32_16x16x32_bf16 v[40:43], v[212:215], v[190:193], v[40:43]
	v_mfma_f32_16x16x32_bf16 v[52:55], v[208:211], v[168:171], v[52:55]
	v_mfma_f32_16x16x32_bf16 v[36:39], v[208:211], v[186:189], v[36:39]
	s_waitcnt lgkmcnt(8)
	v_mfma_f32_16x16x32_bf16 v[52:55], v[216:219], v[64:67], v[52:55]
	v_mfma_f32_16x16x32_bf16 v[36:39], v[216:219], v[190:193], v[36:39]
	s_waitcnt lgkmcnt(6)
	v_mfma_f32_16x16x32_bf16 v[60:63], v[220:223], v[168:171], v[60:63]
	v_mfma_f32_16x16x32_bf16 v[44:47], v[220:223], v[186:189], v[44:47]
	s_waitcnt lgkmcnt(4)
	v_mfma_f32_16x16x32_bf16 v[60:63], v[224:227], v[64:67], v[60:63]
	v_mfma_f32_16x16x32_bf16 v[44:47], v[224:227], v[190:193], v[44:47]
	s_waitcnt lgkmcnt(2)
	v_mfma_f32_16x16x32_bf16 v[68:71], v[228:231], v[168:171], v[68:71]
	v_mfma_f32_16x16x32_bf16 v[48:51], v[228:231], v[186:189], v[48:51]
	s_waitcnt lgkmcnt(0)
	v_mfma_f32_16x16x32_bf16 v[64:67], v[232:235], v[64:67], v[68:71]
	v_mfma_f32_16x16x32_bf16 v[48:51], v[232:235], v[190:193], v[48:51]
	s_nop 3
	s_setprio 0
	s_add_i32 s12, s33, 1
	s_cmp_ge_i32 s12, s44
	s_cbranch_scc1 .LBB0_1303
	s_bitcmp1_b32 s12, 0
	s_cselect_b32 s6, 0x9800, 0
	v_add3_u32 v71, s6, v99, v98
	v_add3_u32 v68, s6, v162, v98
	v_add3_u32 v69, s6, v107, v98
	v_add3_u32 v70, s6, v103, v98
	s_waitcnt vmcnt(0)
	ds_write_b128 v71, v[20:23]
	ds_write_b128 v70, v[24:27]
	ds_write_b128 v69, v[28:31] offset:18432
	ds_write_b128 v68, v[32:35] offset:18432

.LBB0_1308:
	v_add_f32 v68, v138, 0
	v_add_f32 v69, v139, 0
	v_add_f32 v70, v158, 0
	v_add_f32 v71, v159, 0
	v_add_f32 v68, v136, v68
	v_add_f32 v69, v137, v69
	v_add_f32 v70, v156, v70
	v_add_f32 v71, v157, v71
	v_add_f32 v68, v134, v68
	v_add_f32 v69, v135, v69
	v_add_f32 v70, v154, v70
	v_add_f32 v71, v155, v71
	v_add_f32 v68, v132, v68
	v_add_f32 v69, v133, v69
	v_add_f32 v70, v152, v70
	v_add_f32 v71, v153, v71
	v_add_f32 v68, v130, v68
	v_add_f32 v69, v131, v69
	v_add_f32 v70, v150, v70
	v_add_f32 v71, v151, v71
	v_add_f32 v68, v128, v68
	v_add_f32 v69, v129, v69
	v_add_f32 v70, v148, v70
	v_add_f32 v71, v149, v71
	v_add_f32 v68, v126, v68
	v_add_f32 v69, v127, v69
	v_add_f32 v70, v146, v70
	v_add_f32 v71, v147, v71
	v_add_f32 v68, v124, v68
	v_add_f32 v69, v125, v69
	v_add_f32 v70, v144, v70
	v_add_f32 v71, v145, v71
	v_add_f32 v68, v122, v68
	v_add_f32 v69, v123, v69
	v_add_f32 v70, v142, v70
	v_add_f32 v71, v143, v71
	v_add_f32 v68, v120, v68
	v_add_f32 v69, v121, v69
	v_add_f32 v70, v140, v70
	v_add_f32 v71, v141, v71
	v_add_f32 v68, v118, v68
	v_add_f32 v69, v119, v69
	v_add_f32 v70, v86, v70
	v_add_f32 v71, v87, v71
	v_add_f32 v68, v114, v68
	v_add_f32 v69, v115, v69
	v_add_f32 v70, v82, v70
	v_add_f32 v71, v83, v71
	v_add_f32 v68, v110, v68
	v_add_f32 v69, v111, v69
	v_add_f32 v70, v78, v70
	v_add_f32 v71, v79, v71
	v_add_f32 v68, v108, v68
	v_add_f32 v69, v109, v69
	v_add_f32 v70, v74, v70
	v_add_f32 v71, v75, v71
	v_add_f32 v68, v116, v68
	v_add_f32 v69, v117, v69
	s_addk_i32 s97, 0x80
	v_add_f32 v68, v112, v68
	v_add_f32 v69, v113, v69
	v_mov_b32_e32 v77, v106
	v_add_f32 v70, v84, v70
	v_add_f32 v71, v85, v71
	s_add_u32 s74, s74, 0x80
	v_fma_f32 v68, v96, v76, v68
	v_fma_f32 v69, v97, v77, v69
	v_add_f32 v70, v80, v70
	v_add_f32 v71, v81, v71
	v_mov_b32_e32 v161, v72
	s_addc_u32 s75, s75, 0
	v_fma_f32 v96, v68, v160, v70
	v_fma_f32 v97, v69, v161, v71
	s_cmp_lg_u32 s44, s12
	v_add_u32_e32 v166, 0xffffff80, v166
	s_waitcnt lgkmcnt(0)
	s_barrier
	s_cbranch_scc0 .LBB0_1311
	s_mov_b32 s33, s12
	s_branch .LBB0_1301
.Lnm0_entry:
	s_setprio 1
	v_or_b32_e32 v68, s78, v94
	v_add_u32_e32 v88, v68, v163
	ds_read_b128 v[204:207], v88 offset:2304
	ds_read_b128 v[208:211], v88
	ds_read_b128 v[212:215], v88 offset:4608
	ds_read_b128 v[216:219], v88 offset:6912
	ds_read_b128 v[220:223], v88 offset:64
	ds_read_b128 v[224:227], v88 offset:2368
	ds_read_b128 v[228:231], v88 offset:4672
	ds_read_b128 v[232:235], v88 offset:6976
	s_waitcnt lgkmcnt(7)
	v_mfma_f32_16x16x32_bf16 v[82:85], v[204:207], v[4:7], v[0:3]
	v_mfma_f32_16x16x32_bf16 v[108:111], v[204:207], v[12:15], v[0:3]
	s_waitcnt lgkmcnt(5)
	v_mfma_f32_16x16x32_bf16 v[112:115], v[212:215], v[4:7], v[0:3]
	v_mfma_f32_16x16x32_bf16 v[116:119], v[212:215], v[12:15], v[0:3]
	s_waitcnt lgkmcnt(4)
	v_mfma_f32_16x16x32_bf16 v[120:123], v[216:219], v[4:7], v[0:3]
	v_mfma_f32_16x16x32_bf16 v[124:127], v[216:219], v[12:15], v[0:3]
	v_mfma_f32_16x16x32_bf16 v[74:77], v[208:211], v[4:7], v[0:3]
	v_mfma_f32_16x16x32_bf16 v[68:71], v[208:211], v[12:15], v[0:3]
	s_waitcnt lgkmcnt(3)
	v_mfma_f32_16x16x32_bf16 v[128:131], v[220:223], v[8:11], v[74:77]
	v_mfma_f32_16x16x32_bf16 v[76:79], v[220:223], v[16:19], v[68:71]
	s_waitcnt lgkmcnt(2)
	v_mfma_f32_16x16x32_bf16 v[132:135], v[224:227], v[8:11], v[82:85]
	v_mfma_f32_16x16x32_bf16 v[80:83], v[224:227], v[16:19], v[108:111]
	s_waitcnt lgkmcnt(1)
	v_mfma_f32_16x16x32_bf16 v[108:111], v[228:231], v[8:11], v[112:115]
	v_mfma_f32_16x16x32_bf16 v[84:87], v[228:231], v[16:19], v[116:119]
	s_waitcnt lgkmcnt(0)
	v_mfma_f32_16x16x32_bf16 v[112:115], v[232:235], v[8:11], v[120:123]
	v_mfma_f32_16x16x32_bf16 v[142:145], v[232:235], v[16:19], v[124:127]
	s_nop 1
	s_setprio 0
	v_mul_f32_e32 v68, 0x3e38aa3b, v128
	v_mul_f32_e32 v69, 0x3e38aa3b, v129
	v_mul_f32_e32 v71, 0x3e38aa3b, v130
	v_mul_f32_e32 v72, 0x3e38aa3b, v131
	v_max3_f32 v70, v68, s71, v69
	v_mul_f32_e32 v74, 0x3e38aa3b, v132
	v_mul_f32_e32 v75, 0x3e38aa3b, v133
	v_max3_f32 v70, v70, v71, v72
	v_mul_f32_e32 v106, 0x3e38aa3b, v134
	v_mul_f32_e32 v116, 0x3e38aa3b, v135
	v_max3_f32 v70, v70, v74, v75
	v_mul_f32_e32 v108, 0x3e38aa3b, v108
	v_mul_f32_e32 v109, 0x3e38aa3b, v109
	v_max3_f32 v70, v70, v106, v116
	v_mul_f32_e32 v110, 0x3e38aa3b, v110
	v_mul_f32_e32 v111, 0x3e38aa3b, v111
	v_max3_f32 v70, v70, v108, v109
	v_mul_f32_e32 v112, 0x3e38aa3b, v112
	v_mul_f32_e32 v113, 0x3e38aa3b, v113
	v_max3_f32 v70, v70, v110, v111
	v_mul_f32_e32 v114, 0x3e38aa3b, v114
	v_mul_f32_e32 v115, 0x3e38aa3b, v115
	v_max3_f32 v70, v70, v112, v113
	v_mov_b32_e32 v118, v115
	v_max3_f32 v70, v70, v114, v118
	v_mov_b32_e32 v115, v70
	s_nop 1
	v_permlane16_swap_b32_e32 v70, v115
	v_max_f32_e32 v70, v70, v115
	v_mov_b32_e32 v115, v70
	s_nop 1
	v_permlane32_swap_b32_e32 v70, v115
	v_max3_f32 v140, v73, v70, v115
	v_sub_f32_e32 v68, v68, v140
	v_exp_f32_e32 v139, v68
	v_sub_f32_e32 v68, v69, v140
	v_exp_f32_e32 v137, v68
	v_sub_f32_e32 v68, v71, v140
	v_exp_f32_e32 v135, v68
	v_sub_f32_e32 v68, v72, v140
	v_exp_f32_e32 v133, v68
	v_sub_f32_e32 v68, v74, v140
	v_exp_f32_e32 v131, v68
	v_sub_f32_e32 v68, v75, v140
	v_exp_f32_e32 v129, v68
	v_sub_f32_e32 v68, v106, v140
	v_exp_f32_e32 v127, v68
	v_sub_f32_e32 v68, v116, v140
	v_exp_f32_e32 v125, v68
	v_sub_f32_e32 v68, v108, v140
	v_mul_f32_e32 v76, 0x3e38aa3b, v76
	v_exp_f32_e32 v123, v68
	v_sub_f32_e32 v68, v109, v140
	v_exp_f32_e32 v121, v68
	v_sub_f32_e32 v68, v110, v140
	v_mul_f32_e32 v77, 0x3e38aa3b, v77
	v_mul_f32_e32 v78, 0x3e38aa3b, v78
	v_mov_b32_e32 v110, v78
	v_mul_f32_e32 v78, 0x3e38aa3b, v79
	v_max3_f32 v108, v76, s71, v77
	v_mov_b32_e32 v79, v78
	v_mul_f32_e32 v80, 0x3e38aa3b, v80
	v_mul_f32_e32 v81, 0x3e38aa3b, v81
	v_exp_f32_e32 v119, v68
	v_sub_f32_e32 v68, v111, v140
	v_max3_f32 v78, v108, v110, v79
	v_mul_f32_e32 v82, 0x3e38aa3b, v82
	v_mul_f32_e32 v83, 0x3e38aa3b, v83
	v_exp_f32_e32 v115, v68
	v_sub_f32_e32 v68, v112, v140
	v_max3_f32 v78, v78, v80, v81
	v_mul_f32_e32 v84, 0x3e38aa3b, v84
	v_mul_f32_e32 v85, 0x3e38aa3b, v85
	v_exp_f32_e32 v111, v68
	v_sub_f32_e32 v68, v113, v140
	v_max3_f32 v78, v78, v82, v83
	v_mul_f32_e32 v86, 0x3e38aa3b, v86
	v_mul_f32_e32 v87, 0x3e38aa3b, v87
	v_exp_f32_e32 v109, v68
	v_sub_f32_e32 v68, v114, v140
	v_max3_f32 v78, v78, v84, v85
	v_mul_f32_e32 v108, 0x3e38aa3b, v142
	v_mul_f32_e32 v112, 0x3e38aa3b, v143
	v_mul_f32_e32 v114, 0x3e38aa3b, v144
	v_max3_f32 v78, v78, v86, v87
	v_mov_b32_e32 v116, v114
	v_mul_f32_e32 v114, 0x3e38aa3b, v145
	v_max3_f32 v78, v78, v108, v112
	v_mov_b32_e32 v141, v114
	v_max3_f32 v78, v78, v116, v141
	v_mov_b32_e32 v114, v78
	s_nop 1
	v_permlane16_swap_b32_e32 v78, v114
	v_max_f32_e32 v78, v78, v114
	v_mov_b32_e32 v114, v78
	s_nop 1
	v_permlane32_swap_b32_e32 v78, v114
	v_max3_f32 v78, v167, v78, v114
	v_sub_f32_e32 v76, v76, v78
	v_exp_f32_e32 v138, v76
	v_sub_f32_e32 v76, v77, v78
	v_exp_f32_e32 v136, v76
	v_sub_f32_e32 v76, v110, v78
	v_exp_f32_e32 v134, v76
	v_sub_f32_e32 v76, v79, v78
	v_exp_f32_e32 v132, v76
	v_sub_f32_e32 v76, v80, v78
	v_exp_f32_e32 v130, v76
	v_sub_f32_e32 v76, v81, v78
	v_exp_f32_e32 v128, v76
	v_sub_f32_e32 v76, v82, v78
	v_exp_f32_e32 v126, v76
	v_sub_f32_e32 v76, v83, v78
	v_exp_f32_e32 v124, v76
	v_sub_f32_e32 v76, v84, v78
	v_exp_f32_e32 v122, v76
	v_sub_f32_e32 v76, v85, v78
	v_exp_f32_e32 v120, v76
	v_sub_f32_e32 v76, v86, v78
	v_exp_f32_e32 v117, v68
	v_sub_f32_e32 v68, v118, v140
	v_exp_f32_e32 v118, v76
	v_sub_f32_e32 v76, v87, v78
	v_exp_f32_e32 v114, v76
	v_sub_f32_e32 v76, v108, v78
	v_sub_f32_e32 v77, v116, v78
	v_sub_f32_e32 v70, v73, v140
	v_sub_f32_e32 v142, v167, v78
	v_exp_f32_e32 v110, v76
	v_sub_f32_e32 v76, v112, v78
	v_exp_f32_e32 v116, v77
	v_sub_f32_e32 v77, v141, v78
	v_exp_f32_e32 v106, v70
	v_exp_f32_e32 v113, v68
	v_exp_f32_e32 v108, v76
	v_exp_f32_e32 v76, v142
	v_exp_f32_e32 v112, v77
	v_mul_f32 v58, v58, v106
	v_mul_f32 v59, v59, v106
	v_mul_f32 v56, v56, v106
	v_mul_f32 v57, v57, v106
	v_mul_f32 v54, v54, v106
	v_mul_f32 v55, v55, v106
	v_mul_f32 v52, v52, v106
	v_mul_f32 v53, v53, v106
	v_mul_f32 v62, v62, v106
	v_mul_f32 v63, v63, v106
	v_mul_f32 v60, v60, v106
	v_mul_f32 v61, v61, v106
	v_mul_f32 v70, v66, v106
	v_mul_f32 v71, v67, v106
	v_mul_f32 v68, v64, v106
	v_mul_f32 v69, v65, v106
	v_cvt_pk_bf16_f32 v72, v139, v137
	v_cvt_pk_bf16_f32 v73, v135, v133
	v_cvt_pk_bf16_f32 v74, v131, v129
	v_cvt_pk_bf16_f32 v75, v127, v125
	v_cvt_pk_bf16_f32 v64, v123, v121
	v_cvt_pk_bf16_f32 v65, v119, v115
	v_cvt_pk_bf16_f32 v66, v111, v109
	v_cvt_pk_bf16_f32 v67, v117, v113
	v_mul_f32 v42, v42, v76
	v_mul_f32 v43, v43, v76
	v_mul_f32 v40, v40, v76
	v_mul_f32 v41, v41, v76
	v_mul_f32 v38, v38, v76
	v_mul_f32 v39, v39, v76
	v_mul_f32 v36, v36, v76
	v_mul_f32 v37, v37, v76
	v_mul_f32 v46, v46, v76
	v_mul_f32 v47, v47, v76
	v_mul_f32 v44, v44, v76
	v_mul_f32 v45, v45, v76
	v_mul_f32 v50, v50, v76
	v_mul_f32 v51, v51, v76
	v_mul_f32 v48, v48, v76
	v_mul_f32 v49, v49, v76
	v_cvt_pk_bf16_f32 v80, v138, v136
	v_cvt_pk_bf16_f32 v81, v134, v132
	v_cvt_pk_bf16_f32 v82, v130, v128
	v_cvt_pk_bf16_f32 v83, v126, v124
	v_cvt_pk_bf16_f32 v84, v122, v120
	v_cvt_pk_bf16_f32 v85, v118, v114
	v_cvt_pk_bf16_f32 v86, v110, v108
	v_cvt_pk_bf16_f32 v87, v116, v112
	s_setprio 1
	v_add3_u32 v77, s78, v164, v165
	ds_read_b64_tr_b16 v[206:207], v77 offset:20992
	ds_read_b64_tr_b16 v[204:205], v77 offset:18432
	ds_read_b64_tr_b16 v[208:209], v77 offset:18464
	ds_read_b64_tr_b16 v[210:211], v77 offset:21024
	ds_read_b64_tr_b16 v[212:213], v77 offset:23552
	ds_read_b64_tr_b16 v[214:215], v77 offset:26112
	ds_read_b64_tr_b16 v[216:217], v77 offset:23584
	ds_read_b64_tr_b16 v[218:219], v77 offset:26144
	ds_read_b64_tr_b16 v[220:221], v77 offset:18496
	ds_read_b64_tr_b16 v[222:223], v77 offset:21056
	ds_read_b64_tr_b16 v[224:225], v77 offset:23616
	ds_read_b64_tr_b16 v[226:227], v77 offset:26176
	ds_read_b64_tr_b16 v[228:229], v77 offset:18528
	ds_read_b64_tr_b16 v[230:231], v77 offset:21088
	ds_read_b64_tr_b16 v[232:233], v77 offset:23648
	ds_read_b64_tr_b16 v[234:235], v77 offset:26208
	s_waitcnt lgkmcnt(14)
	v_mfma_f32_16x16x32_bf16 v[56:59], v[204:207], v[72:75], v[56:59]
	v_mfma_f32_16x16x32_bf16 v[40:43], v[204:207], v[80:83], v[40:43]
	s_waitcnt lgkmcnt(10)
	v_mfma_f32_16x16x32_bf16 v[56:59], v[212:215], v[64:67], v[56:59]
	v_mfma_f32_16x16x32_bf16 v[40:43], v[212:215], v[84:87], v[40:43]
	v_mfma_f32_16x16x32_bf16 v[52:55], v[208:211], v[72:75], v[52:55]
	v_mfma_f32_16x16x32_bf16 v[36:39], v[208:211], v[80:83], v[36:39]
	s_waitcnt lgkmcnt(8)
	v_mfma_f32_16x16x32_bf16 v[52:55], v[216:219], v[64:67], v[52:55]
	v_mfma_f32_16x16x32_bf16 v[36:39], v[216:219], v[84:87], v[36:39]
	s_waitcnt lgkmcnt(6)
	v_mfma_f32_16x16x32_bf16 v[60:63], v[220:223], v[72:75], v[60:63]
	v_mfma_f32_16x16x32_bf16 v[44:47], v[220:223], v[80:83], v[44:47]
	s_waitcnt lgkmcnt(4)
	v_mfma_f32_16x16x32_bf16 v[60:63], v[224:227], v[64:67], v[60:63]
	v_mfma_f32_16x16x32_bf16 v[44:47], v[224:227], v[84:87], v[44:47]
	s_waitcnt lgkmcnt(2)
	v_mfma_f32_16x16x32_bf16 v[68:71], v[228:231], v[72:75], v[68:71]
	v_mfma_f32_16x16x32_bf16 v[48:51], v[228:231], v[80:83], v[48:51]
	s_waitcnt lgkmcnt(0)
	v_mfma_f32_16x16x32_bf16 v[64:67], v[232:235], v[64:67], v[68:71]
	v_mfma_f32_16x16x32_bf16 v[48:51], v[232:235], v[84:87], v[48:51]
	s_nop 3
	s_setprio 0
	s_setprio 1
	ds_read_b128 v[204:207], v88 offset:9216
	ds_read_b128 v[208:211], v88 offset:9280
	ds_read_b128 v[212:215], v88 offset:11520
	ds_read_b128 v[216:219], v88 offset:13824
	ds_read_b128 v[220:223], v88 offset:16128
	ds_read_b128 v[224:227], v88 offset:11584
	ds_read_b128 v[228:231], v88 offset:13888
	ds_read_b128 v[232:235], v88 offset:16192
	s_waitcnt lgkmcnt(7)
	v_mfma_f32_16x16x32_bf16 v[72:75], v[204:207], v[4:7], v[0:3]
	v_mfma_f32_16x16x32_bf16 v[68:71], v[204:207], v[12:15], v[0:3]
	s_waitcnt lgkmcnt(6)
	v_mfma_f32_16x16x32_bf16 v[168:171], v[208:211], v[16:19], v[68:71]
	v_mfma_f32_16x16x32_bf16 v[72:75], v[208:211], v[8:11], v[72:75]
	s_waitcnt lgkmcnt(5)
	v_mfma_f32_16x16x32_bf16 v[84:87], v[212:215], v[4:7], v[0:3]
	v_mfma_f32_16x16x32_bf16 v[80:83], v[212:215], v[12:15], v[0:3]
	s_waitcnt lgkmcnt(2)
	v_mfma_f32_16x16x32_bf16 v[84:87], v[224:227], v[8:11], v[84:87]
	v_mfma_f32_16x16x32_bf16 v[186:189], v[224:227], v[16:19], v[80:83]
	v_mfma_f32_16x16x32_bf16 v[146:149], v[216:219], v[4:7], v[0:3]
	v_mfma_f32_16x16x32_bf16 v[142:145], v[216:219], v[12:15], v[0:3]
	s_waitcnt lgkmcnt(1)
	v_mfma_f32_16x16x32_bf16 v[80:83], v[228:231], v[8:11], v[146:149]
	v_mfma_f32_16x16x32_bf16 v[190:193], v[228:231], v[16:19], v[142:145]
	v_mfma_f32_16x16x32_bf16 v[154:157], v[220:223], v[4:7], v[0:3]
	v_mfma_f32_16x16x32_bf16 v[150:153], v[220:223], v[12:15], v[0:3]
	s_waitcnt lgkmcnt(0)
	v_mfma_f32_16x16x32_bf16 v[142:145], v[232:235], v[8:11], v[154:157]
	v_mfma_f32_16x16x32_bf16 v[194:197], v[232:235], v[16:19], v[150:153]
	s_nop 0
	s_setprio 0
	v_mul_f32_e32 v68, 0x3e38aa3b, v72
	v_mul_f32_e32 v71, 0x3e38aa3b, v74
	v_mul_f32_e32 v69, 0x3e38aa3b, v73
	v_mul_f32_e32 v72, 0x3e38aa3b, v75
	v_mul_f32_e32 v73, 0x3e38aa3b, v84
	v_mov_b32_e32 v74, v73
	v_mul_f32_e32 v73, 0x3e38aa3b, v85
	v_mov_b32_e32 v75, v73
	v_mul_f32_e32 v73, 0x3e38aa3b, v86
	v_mov_b32_e32 v79, v73
	v_mul_f32_e32 v73, 0x3e38aa3b, v87
	v_mov_b32_e32 v84, v73
	v_mul_f32_e32 v73, 0x3e38aa3b, v80
	v_mov_b32_e32 v80, v73
	v_mul_f32_e32 v73, 0x3e38aa3b, v81
	v_mov_b32_e32 v81, v73
	v_mul_f32_e32 v73, 0x3e38aa3b, v82
	v_mov_b32_e32 v82, v73
	v_mul_f32_e32 v73, 0x3e38aa3b, v83
	v_mov_b32_e32 v83, v73
	v_mul_f32_e32 v73, 0x3e38aa3b, v142
	v_max3_f32 v70, v68, s71, v69
	v_mov_b32_e32 v85, v73
	v_max3_f32 v70, v70, v71, v72
	v_mul_f32_e32 v73, 0x3e38aa3b, v143
	v_max3_f32 v70, v70, v74, v75
	v_mov_b32_e32 v86, v73
	v_max3_f32 v70, v70, v79, v84
	v_mul_f32_e32 v73, 0x3e38aa3b, v144
	v_max3_f32 v70, v70, v80, v81
	v_mov_b32_e32 v88, v73
	v_max3_f32 v70, v70, v82, v83
	v_mul_f32_e32 v73, 0x3e38aa3b, v145
	v_max3_f32 v70, v70, v85, v86
	v_mov_b32_e32 v142, v73
	v_max3_f32 v70, v70, v88, v142
	v_mov_b32_e32 v73, v70
	s_nop 1
	v_permlane16_swap_b32_e32 v70, v73
	v_max_f32_e32 v70, v70, v73
	v_mov_b32_e32 v73, v70
	s_nop 1
	v_permlane32_swap_b32_e32 v70, v73
	v_max3_f32 v73, v140, v70, v73
	v_sub_f32_e32 v68, v68, v73
	v_exp_f32_e32 v159, v68
	v_sub_f32_e32 v68, v69, v73
	v_exp_f32_e32 v157, v68
	v_sub_f32_e32 v68, v71, v73
	v_exp_f32_e32 v155, v68
	v_sub_f32_e32 v68, v72, v73
	v_exp_f32_e32 v153, v68
	v_sub_f32_e32 v68, v74, v73
	v_exp_f32_e32 v151, v68
	v_sub_f32_e32 v68, v75, v73
	v_exp_f32_e32 v149, v68
	v_sub_f32_e32 v68, v79, v73
	v_exp_f32_e32 v147, v68
	v_sub_f32_e32 v68, v84, v73
	v_exp_f32_e32 v145, v68
	v_sub_f32_e32 v68, v80, v73
	v_exp_f32_e32 v143, v68
	v_sub_f32_e32 v68, v81, v73
	v_exp_f32_e32 v141, v68
	v_sub_f32_e32 v68, v82, v73
	v_sub_f32_e32 v70, v140, v73
	v_exp_f32_e32 v87, v68
	v_sub_f32_e32 v68, v83, v73
	v_exp_f32_e32 v83, v68
	v_sub_f32_e32 v68, v85, v73
	v_exp_f32_e32 v72, v70
	v_exp_f32_e32 v79, v68
	v_sub_f32_e32 v68, v86, v73
	v_exp_f32_e32 v75, v68
	v_sub_f32_e32 v68, v88, v73
	v_exp_f32_e32 v85, v68
	v_sub_f32_e32 v68, v142, v73
	v_exp_f32_e32 v81, v68
	v_mul_f32 v68, v64, v72
	v_mul_f32 v69, v65, v72
	v_mul_f32_e32 v64, 0x3e38aa3b, v168
	v_mov_b32_e32 v74, v64
	v_mul_f32_e32 v64, 0x3e38aa3b, v169
	v_mov_b32_e32 v80, v64
	v_mul_f32_e32 v64, 0x3e38aa3b, v170
	v_mov_b32_e32 v82, v64
	v_mul_f32_e32 v64, 0x3e38aa3b, v171
	v_mov_b32_e32 v84, v64
	v_mul_f32_e32 v64, 0x3e38aa3b, v186
	v_mov_b32_e32 v86, v64
	v_mul_f32_e32 v64, 0x3e38aa3b, v187
	v_mov_b32_e32 v88, v64
	v_mul_f32_e32 v64, 0x3e38aa3b, v188
	v_mov_b32_e32 v140, v64
	v_mul_f32_e32 v64, 0x3e38aa3b, v189
	v_mov_b32_e32 v142, v64
	v_mul_f32_e32 v64, 0x3e38aa3b, v190
	v_mov_b32_e32 v160, v64
	v_mul_f32_e32 v64, 0x3e38aa3b, v191
	v_mov_b32_e32 v161, v64
	v_mul_f32_e32 v64, 0x3e38aa3b, v192
	v_mov_b32_e32 v172, v64
	v_mul_f32_e32 v64, 0x3e38aa3b, v193
	v_mov_b32_e32 v173, v64
	v_mul_f32_e32 v64, 0x3e38aa3b, v194
	v_mov_b32_e32 v185, v64
	v_mul_f32_e32 v64, 0x3e38aa3b, v195
	v_mov_b32_e32 v186, v64
	v_mul_f32_e32 v64, 0x3e38aa3b, v196
	v_mov_b32_e32 v187, v64
	v_mul_f32_e32 v64, 0x3e38aa3b, v197
	v_mov_b32_e32 v188, v64
	v_max3_f32 v64, v74, s71, v80
	v_max3_f32 v64, v64, v82, v84
	v_max3_f32 v64, v64, v86, v88
	v_max3_f32 v64, v64, v140, v142
	v_max3_f32 v64, v64, v160, v161
	v_max3_f32 v64, v64, v172, v173
	v_max3_f32 v144, v64, v185, v186
	v_max3_f32 v144, v144, v187, v188
	v_mov_b32_e32 v146, v144
	s_nop 1
	v_permlane16_swap_b32_e32 v144, v146
	v_max_f32_e32 v144, v144, v146
	v_mov_b32_e32 v146, v144
	s_nop 1
	v_permlane32_swap_b32_e32 v144, v146
	v_max3_f32 v167, v78, v144, v146
	v_sub_f32_e32 v74, v74, v167
	v_exp_f32_e32 v158, v74
	v_sub_f32_e32 v74, v80, v167
	v_exp_f32_e32 v156, v74
	v_sub_f32_e32 v74, v82, v167
	v_exp_f32_e32 v154, v74
	v_sub_f32_e32 v74, v84, v167
	v_exp_f32_e32 v152, v74
	v_sub_f32_e32 v74, v86, v167
	v_exp_f32_e32 v150, v74
	v_sub_f32_e32 v74, v88, v167
	v_exp_f32_e32 v148, v74
	v_sub_f32_e32 v74, v140, v167
	v_exp_f32_e32 v146, v74
	v_sub_f32_e32 v74, v142, v167
	v_exp_f32_e32 v144, v74
	v_sub_f32_e32 v74, v160, v167
	v_exp_f32_e32 v142, v74
	v_sub_f32_e32 v74, v161, v167
	v_exp_f32_e32 v140, v74
	v_sub_f32_e32 v74, v172, v167
	v_exp_f32_e32 v86, v74
	v_sub_f32_e32 v74, v173, v167
	v_sub_f32_e32 v189, v78, v167
	v_exp_f32_e32 v82, v74
	v_sub_f32_e32 v74, v185, v167
	v_sub_f32_e32 v80, v187, v167
	v_exp_f32_e32 v78, v74
	v_sub_f32_e32 v74, v186, v167
	v_exp_f32_e32 v160, v189
	v_exp_f32_e32 v84, v80
	v_sub_f32_e32 v80, v188, v167
	v_exp_f32_e32 v74, v74
	v_exp_f32_e32 v80, v80
	v_mul_f32 v58, v58, v72
	v_mul_f32 v59, v59, v72
	v_mul_f32 v56, v56, v72
	v_mul_f32 v57, v57, v72
	v_mul_f32 v54, v54, v72
	v_mul_f32 v55, v55, v72
	v_mul_f32 v52, v52, v72
	v_mul_f32 v53, v53, v72
	v_mul_f32 v62, v62, v72
	v_mul_f32 v63, v63, v72
	v_mul_f32 v60, v60, v72
	v_mul_f32 v61, v61, v72
	v_mul_f32 v70, v66, v72
	v_mul_f32 v71, v67, v72
	v_cvt_pk_bf16_f32 v64, v143, v141
	v_cvt_pk_bf16_f32 v65, v87, v83
	v_cvt_pk_bf16_f32 v66, v79, v75
	v_cvt_pk_bf16_f32 v67, v85, v81
	v_mul_f32 v42, v42, v160
	v_mul_f32 v43, v43, v160
	v_mul_f32 v40, v40, v160
	v_mul_f32 v41, v41, v160
	v_mul_f32 v38, v38, v160
	v_mul_f32 v39, v39, v160
	v_mul_f32 v36, v36, v160
	v_mul_f32 v37, v37, v160
	v_mul_f32 v46, v46, v160
	v_mul_f32 v47, v47, v160
	v_mul_f32 v44, v44, v160
	v_mul_f32 v45, v45, v160
	v_mul_f32 v50, v50, v160
	v_mul_f32 v51, v51, v160
	v_mul_f32 v48, v48, v160
	v_mul_f32 v49, v49, v160
	v_cvt_pk_bf16_f32 v168, v159, v157
	v_cvt_pk_bf16_f32 v169, v155, v153
	v_cvt_pk_bf16_f32 v170, v151, v149
	v_cvt_pk_bf16_f32 v171, v147, v145
	v_cvt_pk_bf16_f32 v186, v158, v156
	v_cvt_pk_bf16_f32 v187, v154, v152
	v_cvt_pk_bf16_f32 v188, v150, v148
	v_cvt_pk_bf16_f32 v189, v146, v144
	v_cvt_pk_bf16_f32 v190, v142, v140
	v_cvt_pk_bf16_f32 v191, v86, v82
	v_cvt_pk_bf16_f32 v192, v78, v74
	v_cvt_pk_bf16_f32 v193, v84, v80
	s_setprio 1
	ds_read_b64_tr_b16 v[206:207], v77 offset:31232
	ds_read_b64_tr_b16 v[204:205], v77 offset:28672
	ds_read_b64_tr_b16 v[208:209], v77 offset:28704
	ds_read_b64_tr_b16 v[210:211], v77 offset:31264
	ds_read_b64_tr_b16 v[212:213], v77 offset:33792
	ds_read_b64_tr_b16 v[214:215], v77 offset:36352
	ds_read_b64_tr_b16 v[216:217], v77 offset:33824
	ds_read_b64_tr_b16 v[218:219], v77 offset:36384
	ds_read_b64_tr_b16 v[220:221], v77 offset:28736
	ds_read_b64_tr_b16 v[222:223], v77 offset:31296
	ds_read_b64_tr_b16 v[224:225], v77 offset:33856
	ds_read_b64_tr_b16 v[226:227], v77 offset:36416
	ds_read_b64_tr_b16 v[228:229], v77 offset:28768
	ds_read_b64_tr_b16 v[230:231], v77 offset:31328
	ds_read_b64_tr_b16 v[232:233], v77 offset:33888
	ds_read_b64_tr_b16 v[234:235], v77 offset:36448
	s_waitcnt lgkmcnt(14)
	v_mfma_f32_16x16x32_bf16 v[56:59], v[204:207], v[168:171], v[56:59]
	v_mfma_f32_16x16x32_bf16 v[40:43], v[204:207], v[186:189], v[40:43]
	s_waitcnt lgkmcnt(10)
	v_mfma_f32_16x16x32_bf16 v[56:59], v[212:215], v[64:67], v[56:59]
	v_mfma_f32_16x16x32_bf16 v[40:43], v[212:215], v[190:193], v[40:43]
	v_mfma_f32_16x16x32_bf16 v[52:55], v[208:211], v[168:171], v[52:55]
	v_mfma_f32_16x16x32_bf16 v[36:39], v[208:211], v[186:189], v[36:39]
	s_waitcnt lgkmcnt(8)
	v_mfma_f32_16x16x32_bf16 v[52:55], v[216:219], v[64:67], v[52:55]
	v_mfma_f32_16x16x32_bf16 v[36:39], v[216:219], v[190:193], v[36:39]
	s_waitcnt lgkmcnt(6)
	v_mfma_f32_16x16x32_bf16 v[60:63], v[220:223], v[168:171], v[60:63]
	v_mfma_f32_16x16x32_bf16 v[44:47], v[220:223], v[186:189], v[44:47]
	s_waitcnt lgkmcnt(4)
	v_mfma_f32_16x16x32_bf16 v[60:63], v[224:227], v[64:67], v[60:63]
	v_mfma_f32_16x16x32_bf16 v[44:47], v[224:227], v[190:193], v[44:47]
	s_waitcnt lgkmcnt(2)
	v_mfma_f32_16x16x32_bf16 v[68:71], v[228:231], v[168:171], v[68:71]
	v_mfma_f32_16x16x32_bf16 v[48:51], v[228:231], v[186:189], v[48:51]
	s_waitcnt lgkmcnt(0)
	v_mfma_f32_16x16x32_bf16 v[64:67], v[232:235], v[64:67], v[68:71]
	v_mfma_f32_16x16x32_bf16 v[48:51], v[232:235], v[190:193], v[48:51]
	s_nop 3
	s_setprio 0
	s_add_i32 s12, s33, 1
	s_cmp_ge_i32 s12, s44
	s_cbranch_scc1 .Lnm0_b1303
	s_bitcmp1_b32 s12, 0
	s_cselect_b32 s6, 0x9800, 0
	v_add3_u32 v71, s6, v99, v98
	v_add3_u32 v68, s6, v162, v98
	v_add3_u32 v69, s6, v107, v98
	v_add3_u32 v70, s6, v103, v98
	s_waitcnt vmcnt(0)
	ds_write_b128 v71, v[20:23]
	ds_write_b128 v70, v[24:27]
	ds_write_b128 v69, v[28:31] offset:18432
	ds_write_b128 v68, v[32:35] offset:18432

.Lnm0_b1308:
	v_add_f32 v68, v138, 0
	v_add_f32 v69, v139, 0
	v_add_f32 v70, v158, 0
	v_add_f32 v71, v159, 0
	v_add_f32 v68, v136, v68
	v_add_f32 v69, v137, v69
	v_add_f32 v70, v156, v70
	v_add_f32 v71, v157, v71
	v_add_f32 v68, v134, v68
	v_add_f32 v69, v135, v69
	v_add_f32 v70, v154, v70
	v_add_f32 v71, v155, v71
	v_add_f32 v68, v132, v68
	v_add_f32 v69, v133, v69
	v_add_f32 v70, v152, v70
	v_add_f32 v71, v153, v71
	v_add_f32 v68, v130, v68
	v_add_f32 v69, v131, v69
	v_add_f32 v70, v150, v70
	v_add_f32 v71, v151, v71
	v_add_f32 v68, v128, v68
	v_add_f32 v69, v129, v69
	v_add_f32 v70, v148, v70
	v_add_f32 v71, v149, v71
	v_add_f32 v68, v126, v68
	v_add_f32 v69, v127, v69
	v_add_f32 v70, v146, v70
	v_add_f32 v71, v147, v71
	v_add_f32 v68, v124, v68
	v_add_f32 v69, v125, v69
	v_add_f32 v70, v144, v70
	v_add_f32 v71, v145, v71
	v_add_f32 v68, v122, v68
	v_add_f32 v69, v123, v69
	v_add_f32 v70, v142, v70
	v_add_f32 v71, v143, v71
	v_add_f32 v68, v120, v68
	v_add_f32 v69, v121, v69
	v_add_f32 v70, v140, v70
	v_add_f32 v71, v141, v71
	v_add_f32 v68, v118, v68
	v_add_f32 v69, v119, v69
	v_add_f32 v70, v86, v70
	v_add_f32 v71, v87, v71
	v_add_f32 v68, v114, v68
	v_add_f32 v69, v115, v69
	v_add_f32 v70, v82, v70
	v_add_f32 v71, v83, v71
	v_add_f32 v68, v110, v68
	v_add_f32 v69, v111, v69
	v_add_f32 v70, v78, v70
	v_add_f32 v71, v79, v71
	v_add_f32 v68, v108, v68
	v_add_f32 v69, v109, v69
	v_add_f32 v70, v74, v70
	v_add_f32 v71, v75, v71
	v_add_f32 v68, v116, v68
	v_add_f32 v69, v117, v69
	s_addk_i32 s97, 0x80
	v_add_f32 v68, v112, v68
	v_add_f32 v69, v113, v69
	v_mov_b32_e32 v77, v106
	v_add_f32 v70, v84, v70
	v_add_f32 v71, v85, v71
	s_add_u32 s74, s74, 0x80
	v_fma_f32 v68, v96, v76, v68
	v_fma_f32 v69, v97, v77, v69
	v_add_f32 v70, v80, v70
	v_add_f32 v71, v81, v71
	v_mov_b32_e32 v161, v72
	s_addc_u32 s75, s75, 0
	v_fma_f32 v96, v68, v160, v70
	v_fma_f32 v97, v69, v161, v71
	s_cmp_lg_u32 s44, s12
	s_waitcnt lgkmcnt(0)
	s_barrier
	s_cbranch_scc0 .LBB0_1311
	s_mov_b32 s33, s12
	s_branch .LBB0_1301

.LBB0_1312:
	v_mov_b32_e32 v4, v97
	s_nop 1
	v_permlane16_swap_b32_e32 v97, v4
	v_add_f32_e32 v4, v97, v4
	v_mov_b32_e32 v5, v4
	s_nop 1
	v_permlane32_swap_b32_e32 v4, v5
	v_add_f32_e32 v4, v4, v5
	v_div_scale_f32 v5, s[6:7], v4, v4, 1.0
	v_rcp_f32_e32 v6, v5
	v_mov_b32_e32 v103, v89
	s_lshl_b32 s44, s94, 1
	s_mov_b64 s[8:9], 0x4552200
	v_fma_f32 v7, -v5, v6, 1.0
	v_fmac_f32_e32 v6, v7, v6
	v_div_scale_f32 v7, vcc, 1.0, v4, 1.0
	v_mul_f32_e32 v8, v7, v6
	v_fma_f32 v9, -v5, v8, v7
	v_fmac_f32_e32 v8, v9, v6
	v_fma_f32 v5, -v5, v8, v7
	v_div_fmas_f32 v5, v5, v6, v8
	v_lshlrev_b64 v[6:7], 11, v[92:93]
	v_lshl_add_u64 v[6:7], s[42:43], 0, v[6:7]
	v_lshl_add_u64 v[6:7], v[6:7], 0, s[44:45]
	v_lshlrev_b64 v[8:9], 1, v[102:103]
	v_div_fixup_f32 v4, v5, v4, 1.0
	v_lshl_add_u64 v[6:7], v[6:7], 0, v[8:9]
	s_mov_b32 s2, 0x4552000
	v_lshl_add_u64 v[10:11], v[6:7], 0, s[8:9]
	v_mul_f32 v12, v56, v4
	v_mul_f32 v13, v57, v4
	v_mul_f32 v14, v58, v4
	v_mul_f32 v15, v59, v4
	v_add_co_u32_e32 v6, vcc, s2, v6
	v_cvt_pk_bf16_f32 v12, v12, v13
	v_cvt_pk_bf16_f32 v13, v14, v15
	v_addc_co_u32_e32 v7, vcc, 0, v7, vcc
	flat_store_dwordx2 v[6:7], v[12:13] offset:512
	v_mul_f32 v6, v52, v4
	v_mul_f32 v7, v53, v4
	v_mul_f32 v12, v54, v4
	v_mul_f32 v13, v55, v4
	v_cvt_pk_bf16_f32 v6, v6, v7
	v_cvt_pk_bf16_f32 v7, v12, v13
	flat_store_dwordx2 v[10:11], v[6:7] offset:32
	v_mul_f32 v6, v60, v4
	v_mul_f32 v7, v61, v4
	v_mul_f32 v12, v62, v4
	v_mul_f32 v13, v63, v4
	v_cvt_pk_bf16_f32 v6, v6, v7
	v_cvt_pk_bf16_f32 v7, v12, v13
	flat_store_dwordx2 v[10:11], v[6:7] offset:64
	v_mul_f32 v6, v64, v4
	v_mul_f32 v7, v65, v4
	v_mov_b32_e32 v5, v96
	s_nop 1
	v_permlane16_swap_b32_e32 v96, v5
	v_add_f32_e32 v5, v96, v5
	v_cvt_pk_bf16_f32 v6, v6, v7
	v_mov_b32_e32 v7, v5
	s_nop 1
	v_permlane32_swap_b32_e32 v5, v7
	v_add_f32_e32 v12, v5, v7
	v_div_scale_f32 v13, s[6:7], v12, v12, 1.0
	v_rcp_f32_e32 v14, v13
	v_mul_f32 v5, v67, v4
	v_mul_f32 v4, v66, v4
	s_mov_b64 s[92:93], s[68:69]
	v_cvt_pk_bf16_f32 v7, v4, v5
	v_fma_f32 v4, -v13, v14, 1.0
	v_fmac_f32_e32 v14, v4, v14
	v_div_scale_f32 v4, vcc, 1.0, v12, 1.0
	v_mul_f32_e32 v5, v4, v14
	flat_store_dwordx2 v[10:11], v[6:7] offset:96
	v_fma_f32 v6, -v13, v5, v4
	v_fmac_f32_e32 v5, v6, v14
	v_lshlrev_b64 v[6:7], 11, v[90:91]
	v_fma_f32 v4, -v13, v5, v4
	v_lshl_add_u64 v[6:7], s[42:43], 0, v[6:7]
	v_div_fmas_f32 v4, v4, v14, v5
	v_lshl_add_u64 v[6:7], v[6:7], 0, s[44:45]
	v_div_fixup_f32 v4, v4, v12, 1.0
	v_lshl_add_u64 v[6:7], v[6:7], 0, v[8:9]
	v_lshl_add_u64 v[8:9], v[6:7], 0, s[8:9]
	v_mul_f32 v10, v40, v4
	v_mul_f32 v11, v41, v4
	v_mul_f32 v12, v42, v4
	v_mul_f32 v13, v43, v4
	v_add_co_u32_e32 v6, vcc, s2, v6
	v_cvt_pk_bf16_f32 v10, v10, v11
	v_cvt_pk_bf16_f32 v11, v12, v13
	v_addc_co_u32_e32 v7, vcc, 0, v7, vcc
	flat_store_dwordx2 v[6:7], v[10:11] offset:512
	v_mul_f32 v6, v36, v4
	v_mul_f32 v7, v37, v4
	v_mul_f32 v10, v38, v4
	v_mul_f32 v11, v39, v4
	v_cvt_pk_bf16_f32 v6, v6, v7
	v_cvt_pk_bf16_f32 v7, v10, v11
	flat_store_dwordx2 v[8:9], v[6:7] offset:32
	v_mul_f32 v6, v44, v4
	v_mul_f32 v7, v45, v4
	v_mul_f32 v10, v46, v4
	v_mul_f32 v11, v47, v4
	v_cvt_pk_bf16_f32 v6, v6, v7
	v_cvt_pk_bf16_f32 v7, v10, v11
	flat_store_dwordx2 v[8:9], v[6:7] offset:64
	v_mul_f32 v6, v48, v4
	v_mul_f32 v7, v49, v4
	v_mul_f32 v5, v51, v4
	v_mul_f32 v4, v50, v4
	v_cvt_pk_bf16_f32 v6, v6, v7
	v_cvt_pk_bf16_f32 v7, v4, v5
	flat_store_dwordx2 v[8:9], v[6:7] offset:96
	s_waitcnt lgkmcnt(0)
	s_barrier
	s_and_saveexec_b64 s[6:7], s[4:5]
	s_cbranch_execz .LBB0_1284
	v_readlane_b32 s2, v252, 23
	v_readlane_b32 s3, v252, 24
	s_nop 1
	v_mov_b64_e32 v[4:5], s[2:3]
	flat_atomic_add v4, v[4:5], v177 sc0
	s_waitcnt vmcnt(0) lgkmcnt(0)
	ds_write_b32 v178, v4
	s_branch .LBB0_1284

.Lhy_ctx0_done:
	s_and_b64 s[18:19], s[6:7], exec
	s_cselect_b32 s44, s82, 0xddf2000
	v_lshl_add_u64 v[20:21], v[12:13], 0, s[44:45]
	v_lshl_add_u64 v[18:19], s[8:9], 1, v[20:21]
	flat_load_dwordx2 v[32:33], v[18:19]
	v_cndmask_b32_e64 v18, v23, v22, s[6:7]
	s_lshl_b32 s6, s14, 1
	s_add_i32 s6, s16, s6
	v_mov_b32_e32 v34, v8
	v_lshl_add_u32 v8, v25, 1, s6
	ds_read_b64 v[36:37], v8 offset:512
	v_mov_b32_e32 v35, v10
	v_mov_b32_e32 v10, v9
	s_mov_b64 s[6:7], -1
	s_and_b64 vcc, exec, s[12:13]
	s_waitcnt lgkmcnt(0)
	v_lshlrev_b32_e32 v9, 16, v37
	v_lshlrev_b32_e32 v8, 16, v36
	v_and_b32_e32 v37, 0xffff0000, v37
	v_and_b32_e32 v36, 0xffff0000, v36
	v_fma_f32 v8, v18, v8, v34
	v_fma_f32 v9, v18, v9, v35
	v_fma_f32 v10, v18, v36, v10
	v_fma_f32 v11, v18, v37, v11
	s_waitcnt vmcnt(0)
	v_lshlrev_b32_e32 v35, 16, v33
	v_lshlrev_b32_e32 v34, 16, v32
	v_and_b32_e32 v33, 0xffff0000, v33
	v_and_b32_e32 v32, 0xffff0000, v32
	v_mul_f32 v10, v10, v32
	v_mul_f32 v11, v11, v33
	v_mul_f32 v8, v8, v34
	v_mul_f32 v9, v9, v35
	v_and_b32_sdwa v32, v11, v177 dst_sel:DWORD dst_unused:UNUSED_PAD src0_sel:WORD_1 src1_sel:DWORD
	v_and_b32_sdwa v33, v10, v177 dst_sel:DWORD dst_unused:UNUSED_PAD src0_sel:WORD_1 src1_sel:DWORD
	v_and_b32_sdwa v19, v9, v177 dst_sel:DWORD dst_unused:UNUSED_PAD src0_sel:WORD_1 src1_sel:DWORD
	v_and_b32_sdwa v31, v8, v177 dst_sel:DWORD dst_unused:UNUSED_PAD src0_sel:WORD_1 src1_sel:DWORD
	v_add3_u32 v11, v11, v32, s60
	v_add3_u32 v10, v10, v33, s60
	v_add3_u32 v8, v8, v31, s60
	v_add3_u32 v9, v9, v19, s60
	v_and_b32_e32 v11, 0xffff0000, v11
	v_and_b32_e32 v10, 0xffff0000, v10
	v_or_b32_sdwa v9, v11, v9 dst_sel:DWORD dst_unused:UNUSED_PAD src0_sel:DWORD src1_sel:WORD_1
	v_or_b32_sdwa v8, v10, v8 dst_sel:DWORD dst_unused:UNUSED_PAD src0_sel:DWORD src1_sel:WORD_1
	s_cbranch_vccz .LBB0_1339
	flat_store_dwordx2 v[14:15], v[8:9]
	s_mov_b64 s[6:7], 0

.LBB0_1341:
	v_lshl_add_u64 v[8:9], s[10:11], 1, v[20:21]
	flat_load_dwordx2 v[8:9], v[8:9]
	s_lshl_b32 s6, s15, 1
	s_add_i32 s16, s16, s6
	v_mov_b32_e32 v10, v4
	v_lshl_add_u32 v4, v25, 1, s16
	ds_read_b64 v[20:21], v4 offset:512
	v_cndmask_b32_e64 v4, 0, 1, s[12:13]
	v_mov_b32_e32 v19, v18
	v_mov_b32_e32 v11, v6
	v_mov_b32_e32 v6, v5
	v_cmp_ne_u32_e64 s[6:7], 1, v4
	s_waitcnt lgkmcnt(0)
	v_lshlrev_b32_e32 v5, 16, v21
	v_lshlrev_b32_e32 v4, 16, v20
	v_and_b32_e32 v21, 0xffff0000, v21
	v_and_b32_e32 v20, 0xffff0000, v20
	v_fma_f32 v4, v18, v4, v10
	v_fma_f32 v5, v19, v5, v11
	v_fma_f32 v6, v18, v20, v6
	v_fma_f32 v7, v19, v21, v7
	s_andn2_b64 vcc, exec, s[12:13]
	s_mov_b64 s[12:13], -1
	s_waitcnt vmcnt(0)
	v_lshlrev_b32_e32 v11, 16, v9
	v_lshlrev_b32_e32 v10, 16, v8
	v_and_b32_e32 v9, 0xffff0000, v9
	v_and_b32_e32 v8, 0xffff0000, v8
	v_mul_f32 v6, v6, v8
	v_mul_f32 v7, v7, v9
	v_mul_f32 v4, v4, v10
	v_mul_f32 v5, v5, v11
	v_and_b32_sdwa v10, v7, v177 dst_sel:DWORD dst_unused:UNUSED_PAD src0_sel:WORD_1 src1_sel:DWORD
	v_and_b32_sdwa v11, v6, v177 dst_sel:DWORD dst_unused:UNUSED_PAD src0_sel:WORD_1 src1_sel:DWORD
	v_and_b32_sdwa v8, v5, v177 dst_sel:DWORD dst_unused:UNUSED_PAD src0_sel:WORD_1 src1_sel:DWORD
	v_and_b32_sdwa v9, v4, v177 dst_sel:DWORD dst_unused:UNUSED_PAD src0_sel:WORD_1 src1_sel:DWORD
	v_add3_u32 v7, v7, v10, s60
	v_add3_u32 v6, v6, v11, s60
	v_add3_u32 v4, v4, v9, s60
	v_add3_u32 v5, v5, v8, s60
	v_and_b32_e32 v7, 0xffff0000, v7
	v_and_b32_e32 v6, 0xffff0000, v6
	v_or_b32_sdwa v5, v7, v5 dst_sel:DWORD dst_unused:UNUSED_PAD src0_sel:DWORD src1_sel:WORD_1
	v_or_b32_sdwa v4, v6, v4 dst_sel:DWORD dst_unused:UNUSED_PAD src0_sel:DWORD src1_sel:WORD_1
	s_cbranch_vccnz .LBB0_1343
	s_mov_b64 s[12:13], 0
	flat_store_dwordx2 v[16:17], v[4:5]

.LBB0_1402:
	s_cmpk_gt_i32 s31, 0xbf
	s_cbranch_scc0 .LBB0_1406
	v_lshl_add_u64 v[20:21], s[20:21], 0, v[0:1]
	v_lshlrev_b64 v[22:23], 9, v[20:21]
	v_lshl_add_u64 v[40:41], v[4:5], 0, v[22:23]
	v_lshl_add_u64 v[42:43], v[6:7], 0, v[22:23]
	v_lshl_add_u64 v[22:23], v[8:9], 0, v[22:23]
	flat_load_dwordx2 v[44:45], v[40:41]
	flat_load_dwordx2 v[46:47], v[42:43]
	s_add_u32 s6, s90, s70
	flat_load_dwordx2 v[22:23], v[22:23]
	s_addc_u32 s7, s91, s24
	s_load_dwordx2 s[6:7], s[6:7], 0xb8
	v_lshlrev_b64 v[40:41], 11, v[20:21]
	v_lshl_add_u64 v[48:49], s[16:17], 0, v[40:41]
	s_waitcnt lgkmcnt(0)
	global_load_dwordx4 v[40:43], v29, s[6:7]
	s_waitcnt vmcnt(0)
	v_lshlrev_b32_e32 v50, 16, v44
	v_lshlrev_b32_e32 v52, 16, v46
	v_and_b32_e32 v51, 0xffff0000, v44
	v_and_b32_e32 v53, 0xffff0000, v46
	v_lshlrev_b32_e32 v44, 16, v45
	v_lshlrev_b32_e32 v46, 16, v47
	v_and_b32_e32 v45, 0xffff0000, v45
	v_and_b32_e32 v47, 0xffff0000, v47
	v_lshlrev_b32_e32 v56, 16, v22
	v_and_b32_e32 v57, 0xffff0000, v22
	v_lshlrev_b32_e32 v58, 16, v23
	v_and_b32_e32 v59, 0xffff0000, v23
	v_add_f32 v22, v44, v46
	v_add_f32 v23, v45, v47
	v_add_f32 v44, v50, v52
	v_add_f32 v45, v51, v53
	v_mul_f32_e32 v52, 0xbfb8aa3b, v56
	v_mul_f32_e32 v53, 0xbfb8aa3b, v57
	v_mul_f32_e32 v54, 0xbfb8aa3b, v58
	v_mul_f32_e32 v55, 0xbfb8aa3b, v59
	v_exp_f32_e32 v52, v52
	v_exp_f32_e32 v53, v53
	v_mul_f32 v50, v44, v44
	v_mul_f32 v51, v45, v45
	v_exp_f32_e32 v54, v54
	v_exp_f32_e32 v55, v55
	v_mul_f32 v46, v22, v22
	v_mul_f32 v47, v23, v23
	v_add_f32_e32 v50, v50, v51
	v_add_f32_e32 v46, v46, v50
	v_add_f32_e32 v50, v47, v46
	v_add_f32 v46, v52, 1.0
	v_add_f32 v47, v53, 1.0
	s_nop 0
	v_add_f32_dpp v52, v50, v50 quad_perm:[1,0,3,2] row_mask:0xf bank_mask:0xf bound_ctrl:1
	v_add_f32 v50, v54, 1.0
	v_add_f32 v51, v55, 1.0
	v_div_scale_f32 v53, s[6:7], v47, v47, v57
	v_div_scale_f32 v55, s[6:7], v46, v46, v56
	v_add_f32_dpp v52, v52, v52 quad_perm:[2,3,0,1] row_mask:0xf bank_mask:0xf bound_ctrl:1
	v_div_scale_f32 v61, s[8:9], v51, v51, v59
	v_rcp_f32_e32 v64, v53
	v_rcp_f32_e32 v65, v55
	v_add_f32_dpp v52, v52, v52 row_half_mirror row_mask:0xf bank_mask:0xf bound_ctrl:1
	v_rcp_f32_e32 v66, v61
	v_div_scale_f32 v63, s[10:11], v50, v50, v58
	v_add_f32_dpp v52, v52, v52 row_mirror row_mask:0xf bank_mask:0xf bound_ctrl:1
	v_fmamk_f32 v52, v52, 0x3c800000, v30
	v_mul_f32_e32 v68, 0x4b800000, v52
	v_fma_f32 v69, -v53, v64, 1.0
	v_cmp_gt_f32_e64 s[10:11], s30, v52
	v_div_scale_f32 v54, vcc, v57, v47, v57
	v_fma_f32 v70, -v55, v65, 1.0
	v_cndmask_b32_e64 v52, v52, v68, s[10:11]
	v_fma_f32 v68, -v61, v66, 1.0
	v_fmac_f32_e32 v64, v69, v64
	v_div_scale_f32 v60, s[6:7], v56, v46, v56
	v_fmac_f32_e32 v65, v70, v65
	v_rsq_f32_e32 v52, v52
	v_fmac_f32_e32 v66, v68, v66
	v_mul_f32_e32 v68, v54, v64
	v_mul_f32_e32 v69, v60, v65
	v_fma_f32 v72, -v53, v68, v54
	v_div_scale_f32 v62, s[8:9], v59, v51, v59
	v_fma_f32 v73, -v55, v69, v60
	v_fmac_f32_e32 v68, v72, v64
	v_rcp_f32_e32 v67, v63
	v_mul_f32_e32 v70, v62, v66
	v_fmac_f32_e32 v69, v73, v65
	v_fma_f32 v53, -v53, v68, v54
	v_fma_f32 v74, -v61, v70, v62
	v_fma_f32 v54, -v55, v69, v60
	v_mul_f32_e32 v55, 0x45800000, v52
	v_div_fmas_f32 v53, v53, v64, v68
	s_mov_b64 vcc, s[6:7]
	v_fmac_f32_e32 v70, v74, v66
	v_cndmask_b32_e64 v52, v52, v55, s[10:11]
	v_div_fixup_f32 v47, v53, v47, v57
	v_div_fmas_f32 v53, v54, v65, v69
	v_fma_f32 v60, -v61, v70, v62
	v_mul_f32 v22, v22, v52
	v_mul_f32 v23, v23, v52
	s_mov_b64 vcc, s[8:9]
	v_fma_f32 v71, -v63, v67, 1.0
	v_mul_f32 v22, v42, v22
	v_mul_f32 v23, v43, v23
	v_div_fmas_f32 v42, v60, v66, v70
	v_mul_f32 v44, v44, v52
	v_mul_f32 v45, v45, v52
	v_div_fixup_f32 v43, v42, v51, v59
	v_fmac_f32_e32 v67, v71, v67
	v_div_scale_f32 v42, vcc, v58, v50, v58
	v_mul_f32 v40, v40, v44
	v_mul_f32 v41, v41, v45
	v_mul_f32_e32 v44, v42, v67
	v_fma_f32 v45, -v63, v44, v42
	v_fmac_f32_e32 v44, v45, v67
	v_fma_f32 v42, -v63, v44, v42
	v_div_fmas_f32 v42, v42, v67, v44
	v_div_fixup_f32 v46, v53, v46, v56
	v_div_fixup_f32 v42, v42, v50, v58
	v_mul_f32 v40, v46, v40
	v_mul_f32 v41, v47, v41
	v_mul_f32 v22, v42, v22
	v_mul_f32 v23, v43, v23
	v_lshl_add_u64 v[42:43], v[48:49], 0, v[2:3]
	v_cvt_pk_bf16_f32 v40, v40, v41
	v_cvt_pk_bf16_f32 v41, v22, v23
	v_add_co_u32_e32 v22, vcc, 0x4552000, v42
	s_mov_b64 s[8:9], 0
	s_nop 0
	v_addc_co_u32_e32 v23, vcc, 0, v43, vcc
	flat_store_dwordx2 v[22:23], v[40:41] offset:1024 sc1
	s_waitcnt vmcnt(0)
	s_mov_b64 s[6:7], 0
	s_and_saveexec_b64 s[10:11], s[4:5]
	s_xor_b64 s[10:11], exec, s[10:11]
	v_ashrrev_i64 v[22:23], 2, v[20:21]
	s_mov_b64 s[6:7], exec
	v_and_b32_e32 v22, 0xffffffc0, v22
	s_or_b64 exec, exec, s[10:11]
	s_and_b64 vcc, exec, s[8:9]
	s_cbranch_vccnz .LBB0_1407
	s_branch .LBB0_1410

.LBB0_1413:
	s_andn2_b64 vcc, exec, s[4:5]
	s_cbranch_vccnz .LBB0_1431
	s_cmpk_gt_i32 s3, 0xbf
	v_ashrrev_i32_e32 v4, 6, v150
	v_and_b32_e32 v74, 63, v150
	s_cbranch_scc0 .LBB0_1420
	s_mul_i32 s4, s3, 0x48
	s_addk_i32 s4, 0xe800
	s_mov_b32 s5, 0
	v_ashrrev_i32_e32 v5, 31, v4
	v_lshlrev_b32_e32 v8, 3, v74
	v_mov_b32_e32 v9, 0
	v_lshl_add_u64 v[6:7], s[4:5], 0, v[4:5]
	v_lshl_add_u64 v[0:1], s[16:17], 0, v[8:9]
	s_mov_b64 s[4:5], 0x6952000
	s_waitcnt vmcnt(0)
	v_lshl_add_u64 v[26:27], v[0:1], 0, s[4:5]
	s_mov_b64 s[4:5], 0x6f52000
	v_lshl_add_u64 v[28:29], v[0:1], 0, s[4:5]
	s_mov_b64 s[4:5], 0xcb32000
	v_lshlrev_b64 v[2:3], 9, v[6:7]
	v_lshl_add_u64 v[30:31], v[0:1], 0, s[4:5]
	v_lshl_add_u64 v[10:11], v[26:27], 0, v[2:3]
	v_lshl_add_u64 v[0:1], v[30:31], 0, v[2:3]
	v_lshl_add_u64 v[12:13], v[28:29], 0, v[2:3]
	flat_load_dwordx2 v[76:77], v[10:11]
	flat_load_dwordx2 v[78:79], v[12:13]
	flat_load_dwordx2 v[80:81], v[0:1]
	v_lshl_add_u64 v[10:11], v[6:7], 0, 8
	v_lshlrev_b64 v[0:1], 9, v[10:11]
	v_lshl_add_u64 v[2:3], v[26:27], 0, v[0:1]
	v_lshl_add_u64 v[12:13], v[6:7], 0, 16
	flat_load_dwordx2 v[70:71], v[2:3]
	v_lshl_add_u64 v[2:3], v[28:29], 0, v[0:1]
	v_lshl_add_u64 v[0:1], v[30:31], 0, v[0:1]
	v_lshlrev_b64 v[14:15], 9, v[12:13]
	v_lshl_add_u64 v[16:17], v[26:27], 0, v[14:15]
	v_lshl_add_u64 v[18:19], v[28:29], 0, v[14:15]
	flat_load_dwordx2 v[72:73], v[2:3]
	flat_load_dwordx2 v[68:69], v[0:1]
	flat_load_dwordx2 v[64:65], v[16:17]
	flat_load_dwordx2 v[66:67], v[18:19]
	v_lshl_add_u64 v[0:1], v[30:31], 0, v[14:15]
	v_lshl_add_u64 v[14:15], v[6:7], 0, 24
	v_lshlrev_b64 v[2:3], 9, v[14:15]
	v_lshl_add_u64 v[16:17], v[26:27], 0, v[2:3]
	v_lshl_add_u64 v[18:19], v[28:29], 0, v[2:3]
	v_lshl_add_u64 v[2:3], v[30:31], 0, v[2:3]
	flat_load_dwordx2 v[44:45], v[0:1]
	flat_load_dwordx2 v[60:61], v[16:17]
	flat_load_dwordx2 v[62:63], v[18:19]
	flat_load_dwordx2 v[58:59], v[2:3]
	v_lshl_add_u64 v[16:17], v[6:7], 0, 32
	v_lshlrev_b64 v[0:1], 9, v[16:17]
	v_lshl_add_u64 v[18:19], v[6:7], 0, 40
	v_lshl_add_u64 v[2:3], v[26:27], 0, v[0:1]
	v_lshl_add_u64 v[20:21], v[28:29], 0, v[0:1]
	v_lshlrev_b64 v[22:23], 9, v[18:19]
	s_ashr_i32 s5, s70, 31
	v_lshl_add_u64 v[0:1], v[30:31], 0, v[0:1]
	v_lshl_add_u64 v[24:25], v[26:27], 0, v[22:23]
	flat_load_dwordx2 v[54:55], v[2:3]
	flat_load_dwordx2 v[56:57], v[20:21]
	flat_load_dwordx2 v[52:53], v[0:1]
	flat_load_dwordx2 v[48:49], v[24:25]
	v_lshl_add_u64 v[20:21], v[6:7], 0, 48
	s_add_u32 s4, s90, s70
	v_lshl_add_u64 v[0:1], v[28:29], 0, v[22:23]
	v_lshl_add_u64 v[2:3], v[30:31], 0, v[22:23]
	v_lshlrev_b64 v[22:23], 9, v[20:21]
	s_addc_u32 s5, s91, s5
	v_lshl_add_u64 v[24:25], v[26:27], 0, v[22:23]
	v_lshl_add_u64 v[32:33], v[28:29], 0, v[22:23]
	flat_load_dwordx2 v[50:51], v[0:1]
	flat_load_dwordx2 v[46:47], v[2:3]
	flat_load_dwordx2 v[38:39], v[24:25]
	flat_load_dwordx2 v[40:41], v[32:33]
	s_load_dwordx2 s[4:5], s[4:5], 0xb8
	v_lshl_add_u64 v[0:1], v[30:31], 0, v[22:23]
	v_lshl_add_u64 v[22:23], v[6:7], 0, 56
	v_lshlrev_b64 v[2:3], 9, v[22:23]
	v_lshl_add_u64 v[24:25], v[26:27], 0, v[2:3]
	v_lshl_add_u64 v[82:83], v[28:29], 0, v[2:3]
	v_lshl_add_u64 v[2:3], v[30:31], 0, v[2:3]
	flat_load_dwordx2 v[42:43], v[0:1]
	flat_load_dwordx2 v[34:35], v[24:25]
	flat_load_dwordx2 v[36:37], v[82:83]
	flat_load_dwordx2 v[32:33], v[2:3]
	v_lshlrev_b32_e32 v0, 4, v150
	v_and_b32_e32 v0, 0xf0, v0
	s_waitcnt lgkmcnt(0)
	global_load_dwordx4 v[0:3], v0, s[4:5]
	v_lshl_add_u64 v[24:25], v[6:7], 0, 64
	v_lshlrev_b64 v[82:83], 9, v[24:25]
	v_lshl_add_u64 v[84:85], v[26:27], 0, v[82:83]
	v_lshl_add_u64 v[86:87], v[28:29], 0, v[82:83]
	v_lshl_add_u64 v[82:83], v[30:31], 0, v[82:83]
	flat_load_dwordx2 v[28:29], v[84:85]
	flat_load_dwordx2 v[30:31], v[86:87]
	flat_load_dwordx2 v[26:27], v[82:83]
	s_mov_b32 s7, 0x800000
	s_mov_b32 s8, 0x4552000
	s_mov_b32 s6, 0x3c800000
	s_mov_b64 s[10:11], 0
	s_waitcnt vmcnt(0)
	v_lshlrev_b32_e32 v82, 16, v76
	v_lshlrev_b32_e32 v84, 16, v78
	v_lshlrev_b32_e32 v5, 16, v80
	v_and_b32_e32 v75, 0xffff0000, v80
	v_mul_f32_e32 v80, 0xbfb8aa3b, v5
	v_exp_f32_e32 v86, v80
	v_mul_f32_e32 v80, 0xbfb8aa3b, v75
	v_exp_f32_e32 v87, v80
	v_and_b32_e32 v83, 0xffff0000, v76
	v_and_b32_e32 v85, 0xffff0000, v78
	v_lshlrev_b32_e32 v76, 16, v77
	v_lshlrev_b32_e32 v78, 16, v79
	v_and_b32_e32 v77, 0xffff0000, v77
	v_and_b32_e32 v79, 0xffff0000, v79
	v_add_f32 v76, v76, v78
	v_add_f32 v77, v77, v79
	v_add_f32 v78, v86, 1.0
	v_add_f32 v79, v87, 1.0
	v_add_f32 v82, v82, v84
	v_add_f32 v83, v83, v85
	v_div_scale_f32 v86, s[4:5], v79, v79, v75
	v_rcp_f32_e32 v87, v86
	v_mul_f32 v84, v82, v82
	v_mul_f32 v85, v83, v83
	v_lshlrev_b32_e32 v88, 16, v81
	v_and_b32_e32 v89, 0xffff0000, v81
	v_fma_f32 v90, -v86, v87, 1.0
	v_fmac_f32_e32 v87, v90, v87
	v_div_scale_f32 v90, vcc, v75, v79, v75
	v_mul_f32_e32 v91, v90, v87
	v_fma_f32 v92, -v86, v91, v90
	v_fmac_f32_e32 v91, v92, v87
	v_fma_f32 v86, -v86, v91, v90
	v_div_scale_f32 v90, s[4:5], v78, v78, v5
	v_rcp_f32_e32 v92, v90
	v_mul_f32 v80, v76, v76
	v_mul_f32 v81, v77, v77
	v_add_f32_e32 v84, v84, v85
	v_div_fmas_f32 v86, v86, v87, v91
	v_add_f32_e32 v80, v84, v80
	v_div_fixup_f32 v79, v86, v79, v75
	v_fma_f32 v75, -v90, v92, 1.0
	v_add_f32_e32 v80, v81, v80
	v_fmac_f32_e32 v92, v75, v92
	v_div_scale_f32 v75, vcc, v5, v78, v5
	v_add_f32_dpp v80, v80, v80 quad_perm:[1,0,3,2] row_mask:0xf bank_mask:0xf bound_ctrl:1
	v_mul_f32_e32 v86, v75, v92
	v_fma_f32 v87, -v90, v86, v75
	v_add_f32_dpp v80, v80, v80 quad_perm:[2,3,0,1] row_mask:0xf bank_mask:0xf bound_ctrl:1
	v_fmac_f32_e32 v86, v87, v92
	v_mov_b32_e32 v81, 0x358637bd
	v_add_f32_dpp v80, v80, v80 row_half_mirror row_mask:0xf bank_mask:0xf bound_ctrl:1
	v_fma_f32 v75, -v90, v86, v75
	v_div_fmas_f32 v75, v75, v92, v86
	v_add_f32_dpp v80, v80, v80 row_mirror row_mask:0xf bank_mask:0xf bound_ctrl:1
	v_fmac_f32_e32 v81, 0x3c800000, v80
	v_mul_f32_e32 v80, 0x4b800000, v81
	v_cmp_gt_f32_e64 s[4:5], s7, v81
	v_div_fixup_f32 v78, v75, v78, v5
	v_mul_f32_e32 v75, 0xbfb8aa3b, v88
	v_cndmask_b32_e64 v80, v81, v80, s[4:5]
	v_rsq_f32_e32 v84, v80
	v_exp_f32_e32 v80, v75
	v_mul_f32_e32 v75, 0xbfb8aa3b, v89
	v_exp_f32_e32 v81, v75
	v_mul_f32_e32 v5, 0x45800000, v84
	v_cndmask_b32_e64 v84, v84, v5, s[4:5]
	v_mul_f32 v82, v82, v84
	v_mul_f32 v83, v83, v84
	v_add_f32 v80, v80, 1.0
	v_add_f32 v81, v81, 1.0
	v_mul_f32 v82, v0, v82
	v_mul_f32 v83, v1, v83
	v_div_scale_f32 v5, s[4:5], v81, v81, v89
	v_rcp_f32_e32 v75, v5
	v_mul_f32 v78, v78, v82
	v_mul_f32 v79, v79, v83
	v_mul_f32 v76, v76, v84
	v_mul_f32 v77, v77, v84
	v_cvt_pk_bf16_f32 v78, v78, v79
	v_fma_f32 v82, -v5, v75, 1.0
	v_fmac_f32_e32 v75, v82, v75
	v_div_scale_f32 v82, vcc, v89, v81, v89
	v_mul_f32_e32 v83, v82, v75
	v_fma_f32 v84, -v5, v83, v82
	v_fmac_f32_e32 v83, v84, v75
	v_fma_f32 v5, -v5, v83, v82
	v_div_scale_f32 v82, s[4:5], v80, v80, v88
	v_rcp_f32_e32 v84, v82
	v_div_fmas_f32 v5, v5, v75, v83
	v_div_fixup_f32 v81, v5, v81, v89
	v_mul_f32 v76, v2, v76
	v_mul_f32 v77, v3, v77
	v_fma_f32 v5, -v82, v84, 1.0
	v_fmac_f32_e32 v84, v5, v84
	v_div_scale_f32 v5, vcc, v88, v80, v88
	v_mul_f32_e32 v75, v5, v84
	v_fma_f32 v83, -v82, v75, v5
	v_fmac_f32_e32 v75, v83, v84
	v_fma_f32 v5, -v82, v75, v5
	v_div_fmas_f32 v5, v5, v84, v75
	v_div_fixup_f32 v80, v5, v80, v88
	v_mul_f32 v76, v80, v76
	v_mul_f32 v77, v81, v77
	v_lshlrev_b32_e32 v5, 16, v68
	v_cvt_pk_bf16_f32 v79, v76, v77
	v_lshlrev_b64 v[76:77], 11, v[6:7]
	v_and_b32_e32 v75, 0xffff0000, v68
	v_mul_f32_e32 v68, 0xbfb8aa3b, v5
	v_lshl_add_u64 v[76:77], s[16:17], 0, v[76:77]
	v_exp_f32_e32 v80, v68
	v_mul_f32_e32 v68, 0xbfb8aa3b, v75
	v_lshl_add_u64 v[76:77], v[76:77], 0, v[8:9]
	v_exp_f32_e32 v81, v68
	v_add_co_u32_e32 v76, vcc, s8, v76
	v_lshlrev_b32_e32 v82, 16, v69
	s_nop 0
	v_addc_co_u32_e32 v77, vcc, 0, v77, vcc
	flat_store_dwordx2 v[76:77], v[78:79] offset:1024 sc1
	v_lshlrev_b32_e32 v76, 16, v70
	v_lshlrev_b32_e32 v78, 16, v72
	v_and_b32_e32 v77, 0xffff0000, v70
	v_and_b32_e32 v79, 0xffff0000, v72
	v_lshlrev_b32_e32 v70, 16, v71
	v_lshlrev_b32_e32 v72, 16, v73
	v_and_b32_e32 v71, 0xffff0000, v71
	v_and_b32_e32 v73, 0xffff0000, v73
	v_and_b32_e32 v83, 0xffff0000, v69
	v_add_f32 v68, v70, v72
	v_add_f32 v69, v71, v73
	v_add_f32 v70, v80, 1.0
	v_add_f32 v71, v81, 1.0
	v_add_f32 v76, v76, v78
	v_add_f32 v77, v77, v79
	v_div_scale_f32 v80, s[4:5], v71, v71, v75
	v_rcp_f32_e32 v81, v80
	v_mul_f32 v78, v76, v76
	v_mul_f32 v79, v77, v77
	v_mul_f32 v72, v68, v68
	v_mul_f32 v73, v69, v69
	v_lshlrev_b32_e32 v90, 16, v45
	v_fma_f32 v84, -v80, v81, 1.0
	v_fmac_f32_e32 v81, v84, v81
	v_div_scale_f32 v84, vcc, v75, v71, v75
	v_mul_f32_e32 v85, v84, v81
	v_fma_f32 v86, -v80, v85, v84
	v_fmac_f32_e32 v85, v86, v81
	v_fma_f32 v80, -v80, v85, v84
	v_div_scale_f32 v84, s[4:5], v70, v70, v5
	v_rcp_f32_e32 v86, v84
	v_div_fmas_f32 v80, v80, v81, v85
	v_div_fixup_f32 v71, v80, v71, v75
	v_mul_f32_e32 v80, 0xbfb8aa3b, v82
	v_mul_f32_e32 v81, 0xbfb8aa3b, v83
	v_fma_f32 v75, -v84, v86, 1.0
	v_exp_f32_e32 v80, v80
	v_exp_f32_e32 v81, v81
	v_fmac_f32_e32 v86, v75, v86
	v_div_scale_f32 v75, vcc, v5, v70, v5
	v_mul_f32_e32 v85, v75, v86
	v_fma_f32 v87, -v84, v85, v75
	v_fmac_f32_e32 v85, v87, v86
	v_add_f32 v80, v80, 1.0
	v_add_f32 v81, v81, 1.0
	v_fma_f32 v75, -v84, v85, v75
	v_div_scale_f32 v84, s[4:5], v81, v81, v83
	v_rcp_f32_e32 v87, v84
	v_div_fmas_f32 v75, v75, v86, v85
	v_div_fixup_f32 v70, v75, v70, v5
	v_lshlrev_b32_e32 v86, 16, v66
	v_fma_f32 v5, -v84, v87, 1.0
	v_fmac_f32_e32 v87, v5, v87
	v_div_scale_f32 v5, vcc, v83, v81, v83
	v_mul_f32_e32 v75, v5, v87
	v_fma_f32 v85, -v84, v75, v5
	v_fmac_f32_e32 v75, v85, v87
	v_fma_f32 v5, -v84, v75, v5
	v_div_scale_f32 v84, s[4:5], v80, v80, v82
	v_rcp_f32_e32 v85, v84
	v_div_fmas_f32 v5, v5, v87, v75
	v_div_fixup_f32 v81, v5, v81, v83
	v_and_b32_e32 v87, 0xffff0000, v66
	v_fma_f32 v5, -v84, v85, 1.0
	v_fmac_f32_e32 v85, v5, v85
	v_div_scale_f32 v5, vcc, v82, v80, v82
	v_mul_f32_e32 v75, v5, v85
	v_fma_f32 v83, -v84, v75, v5
	v_fmac_f32_e32 v75, v83, v85
	v_fma_f32 v5, -v84, v75, v5
	v_div_fmas_f32 v5, v5, v85, v75
	v_div_fixup_f32 v80, v5, v80, v82
	v_lshlrev_b32_e32 v5, 16, v44
	v_and_b32_e32 v75, 0xffff0000, v44
	v_mul_f32_e32 v44, 0xbfb8aa3b, v5
	v_exp_f32_e32 v88, v44
	v_mul_f32_e32 v44, 0xbfb8aa3b, v75
	v_exp_f32_e32 v89, v44
	v_lshlrev_b32_e32 v84, 16, v64
	v_and_b32_e32 v85, 0xffff0000, v64
	v_lshlrev_b32_e32 v64, 16, v65
	v_lshlrev_b32_e32 v66, 16, v67
	v_and_b32_e32 v65, 0xffff0000, v65
	v_and_b32_e32 v67, 0xffff0000, v67
	v_add_f32 v64, v64, v66
	v_add_f32 v65, v65, v67
	v_add_f32 v66, v88, 1.0
	v_add_f32 v67, v89, 1.0
	v_add_f32 v84, v84, v86
	v_add_f32 v85, v85, v87
	v_div_scale_f32 v88, s[4:5], v67, v67, v75
	v_rcp_f32_e32 v89, v88
	v_mul_f32 v86, v84, v84
	v_mul_f32 v87, v85, v85
	v_and_b32_e32 v91, 0xffff0000, v45
	v_mul_f32 v44, v64, v64
	v_mul_f32 v45, v65, v65
	v_fma_f32 v92, -v88, v89, 1.0
	v_fmac_f32_e32 v89, v92, v89
	v_div_scale_f32 v92, vcc, v75, v67, v75
	v_mul_f32_e32 v93, v92, v89
	v_fma_f32 v94, -v88, v93, v92
	v_fmac_f32_e32 v93, v94, v89
	v_fma_f32 v88, -v88, v93, v92
	v_div_scale_f32 v92, s[4:5], v66, v66, v5
	v_rcp_f32_e32 v94, v92
	v_div_fmas_f32 v88, v88, v89, v93
	v_div_fixup_f32 v67, v88, v67, v75
	v_mov_b32_e32 v89, v78
	v_fma_f32 v75, -v92, v94, 1.0
	v_fmac_f32_e32 v94, v75, v94
	v_div_scale_f32 v75, vcc, v5, v66, v5
	v_mul_f32_e32 v93, v75, v94
	v_fma_f32 v88, -v92, v93, v75
	v_fmac_f32_e32 v93, v88, v94
	v_mov_b32_e32 v88, v86
	v_mov_b32_e32 v78, v87
	v_add_f32 v78, v88, v78
	v_add_f32 v79, v89, v79
	v_mov_b32_e32 v86, v44
	v_mov_b32_e32 v87, v72
	v_add_f32 v78, v78, v86
	v_add_f32 v79, v79, v87
	v_mov_b32_e32 v72, v45
	v_add_f32 v44, v72, v78
	v_add_f32 v45, v73, v79
	s_mov_b32 s4, 0x358637bd
	v_fma_f32 v75, -v92, v93, v75
	v_mov_b32_dpp v73, v45 quad_perm:[1,0,3,2] row_mask:0xf bank_mask:0xf bound_ctrl:1
	v_mov_b32_dpp v72, v44 quad_perm:[1,0,3,2] row_mask:0xf bank_mask:0xf bound_ctrl:1
	v_add_f32 v44, v44, v72
	v_add_f32 v45, v45, v73
	v_div_fmas_f32 v75, v75, v94, v93
	v_div_fixup_f32 v66, v75, v66, v5
	v_mov_b32_dpp v73, v45 quad_perm:[2,3,0,1] row_mask:0xf bank_mask:0xf bound_ctrl:1
	v_mov_b32_dpp v72, v44 quad_perm:[2,3,0,1] row_mask:0xf bank_mask:0xf bound_ctrl:1
	v_add_f32 v44, v44, v72
	v_add_f32 v45, v45, v73
	v_lshlrev_b64 v[82:83], 11, v[10:11]
	v_lshl_add_u64 v[82:83], s[16:17], 0, v[82:83]
	v_mov_b32_dpp v73, v45 row_half_mirror row_mask:0xf bank_mask:0xf bound_ctrl:1
	v_mov_b32_dpp v72, v44 row_half_mirror row_mask:0xf bank_mask:0xf bound_ctrl:1
	v_add_f32 v44, v44, v72
	v_add_f32 v45, v45, v73
	v_lshl_add_u64 v[82:83], v[82:83], 0, v[8:9]
	s_nop 0
	v_mov_b32_dpp v73, v45 row_mirror row_mask:0xf bank_mask:0xf bound_ctrl:1
	v_mov_b32_dpp v72, v44 row_mirror row_mask:0xf bank_mask:0xf bound_ctrl:1
	v_add_f32 v72, v44, v72
	v_add_f32 v73, v45, v73
	v_mov_b64_e32 v[44:45], s[4:5]
	v_fma_f32 v72, v72, s6, v44
	v_fma_f32 v73, v73, s6, v44
	s_nop 0
	v_mul_f32_e32 v78, 0x4b800000, v73
	v_cmp_gt_f32_e64 s[4:5], s7, v73
	v_cmp_gt_f32_e32 vcc, s7, v72
	s_nop 0
	v_cndmask_b32_e64 v73, v73, v78, s[4:5]
	v_rsq_f32_e32 v73, v73
	s_nop 0
	v_mul_f32_e32 v5, 0x45800000, v73
	v_cndmask_b32_e64 v78, v73, v5, s[4:5]
	v_mul_f32 v76, v76, v78
	v_mul_f32 v77, v77, v78
	v_mul_f32 v68, v68, v78
	v_mul_f32 v69, v69, v78
	v_mul_f32 v76, v0, v76
	v_mul_f32 v77, v1, v77
	v_mul_f32 v68, v2, v68
	v_mul_f32 v69, v3, v69
	v_mul_f32 v70, v70, v76
	v_mul_f32 v71, v71, v77
	v_mul_f32 v68, v80, v68
	v_mul_f32 v69, v81, v69
	v_cvt_pk_bf16_f32 v70, v70, v71
	v_cvt_pk_bf16_f32 v71, v68, v69
	v_add_co_u32_e64 v68, s[4:5], s8, v82
	v_mul_f32_e32 v5, 0x4b800000, v72
	s_nop 0
	v_addc_co_u32_e64 v69, s[4:5], 0, v83, s[4:5]
	v_cndmask_b32_e32 v5, v72, v5, vcc
	flat_store_dwordx2 v[68:69], v[70:71] offset:1024 sc1
	v_mul_f32_e32 v68, 0xbfb8aa3b, v90
	v_mul_f32_e32 v69, 0xbfb8aa3b, v91
	v_rsq_f32_e32 v5, v5
	v_exp_f32_e32 v68, v68
	v_exp_f32_e32 v69, v69
	v_lshlrev_b32_e32 v80, 16, v53
	v_mul_f32_e32 v70, 0x45800000, v5
	v_cndmask_b32_e32 v70, v5, v70, vcc
	v_add_f32 v68, v68, 1.0
	v_add_f32 v69, v69, 1.0
	v_mul_f32 v72, v84, v70
	v_mul_f32 v73, v85, v70
	v_div_scale_f32 v5, s[4:5], v69, v69, v91
	v_rcp_f32_e32 v71, v5
	v_mul_f32 v72, v0, v72
	v_mul_f32 v73, v1, v73
	v_and_b32_e32 v81, 0xffff0000, v53
	v_mul_f32 v66, v66, v72
	v_mul_f32 v67, v67, v73
	v_mul_f32 v64, v64, v70
	v_mul_f32 v65, v65, v70
	v_fma_f32 v70, -v5, v71, 1.0
	v_fmac_f32_e32 v71, v70, v71
	v_div_scale_f32 v70, vcc, v91, v69, v91
	v_mul_f32_e32 v72, v70, v71
	v_fma_f32 v73, -v5, v72, v70
	v_fmac_f32_e32 v72, v73, v71
	v_fma_f32 v5, -v5, v72, v70
	v_div_scale_f32 v70, s[4:5], v68, v68, v90
	v_rcp_f32_e32 v73, v70
	v_div_fmas_f32 v5, v5, v71, v72
	v_div_fixup_f32 v69, v5, v69, v91
	v_mul_f32 v64, v2, v64
	v_mul_f32 v65, v3, v65
	v_fma_f32 v5, -v70, v73, 1.0
	v_fmac_f32_e32 v73, v5, v73
	v_div_scale_f32 v5, vcc, v90, v68, v90
	v_mul_f32_e32 v71, v5, v73
	v_fma_f32 v72, -v70, v71, v5
	v_fmac_f32_e32 v71, v72, v73
	v_fma_f32 v5, -v70, v71, v5
	v_div_fmas_f32 v5, v5, v73, v71
	v_div_fixup_f32 v68, v5, v68, v90
	v_mul_f32 v64, v68, v64
	v_mul_f32 v65, v69, v65
	v_lshlrev_b32_e32 v5, 16, v58
	v_cvt_pk_bf16_f32 v66, v66, v67
	v_cvt_pk_bf16_f32 v67, v64, v65
	v_lshlrev_b64 v[64:65], 11, v[12:13]
	v_and_b32_e32 v70, 0xffff0000, v58
	v_mul_f32_e32 v58, 0xbfb8aa3b, v5
	v_lshl_add_u64 v[64:65], s[16:17], 0, v[64:65]
	v_exp_f32_e32 v68, v58
	v_mul_f32_e32 v58, 0xbfb8aa3b, v70
	v_lshl_add_u64 v[64:65], v[64:65], 0, v[8:9]
	v_exp_f32_e32 v69, v58
	v_add_co_u32_e32 v64, vcc, s8, v64
	v_lshlrev_b32_e32 v71, 16, v59
	s_nop 0
	v_addc_co_u32_e32 v65, vcc, 0, v65, vcc
	flat_store_dwordx2 v[64:65], v[66:67] offset:1024 sc1
	v_lshlrev_b32_e32 v64, 16, v60
	v_lshlrev_b32_e32 v66, 16, v62
	v_and_b32_e32 v65, 0xffff0000, v60
	v_and_b32_e32 v67, 0xffff0000, v62
	v_lshlrev_b32_e32 v60, 16, v61
	v_lshlrev_b32_e32 v62, 16, v63
	v_and_b32_e32 v61, 0xffff0000, v61
	v_and_b32_e32 v63, 0xffff0000, v63
	v_and_b32_e32 v72, 0xffff0000, v59
	v_add_f32 v58, v60, v62
	v_add_f32 v59, v61, v63
	v_add_f32 v60, v68, 1.0
	v_add_f32 v61, v69, 1.0
	v_add_f32 v64, v64, v66
	v_add_f32 v65, v65, v67
	v_div_scale_f32 v68, s[4:5], v61, v61, v70
	v_rcp_f32_e32 v69, v68
	v_mul_f32 v66, v64, v64
	v_mul_f32 v67, v65, v65
	v_mul_f32 v62, v58, v58
	v_mul_f32 v63, v59, v59
	v_fma_f32 v73, -v68, v69, 1.0
	v_fmac_f32_e32 v69, v73, v69
	v_div_scale_f32 v73, vcc, v70, v61, v70
	v_mul_f32_e32 v75, v73, v69
	v_fma_f32 v76, -v68, v75, v73
	v_fmac_f32_e32 v75, v76, v69
	v_fma_f32 v68, -v68, v75, v73
	v_div_scale_f32 v73, s[4:5], v60, v60, v5
	v_rcp_f32_e32 v76, v73
	v_div_fmas_f32 v68, v68, v69, v75
	v_div_fixup_f32 v61, v68, v61, v70
	v_mul_f32_e32 v69, 0xbfb8aa3b, v72
	v_fma_f32 v68, -v73, v76, 1.0
	v_fmac_f32_e32 v76, v68, v76
	v_mul_f32_e32 v68, 0xbfb8aa3b, v71
	v_exp_f32_e32 v68, v68
	v_exp_f32_e32 v69, v69
	v_div_scale_f32 v70, vcc, v5, v60, v5
	v_mul_f32_e32 v75, v70, v76
	v_fma_f32 v77, -v73, v75, v70
	v_fmac_f32_e32 v75, v77, v76
	v_add_f32 v68, v68, 1.0
	v_add_f32 v69, v69, 1.0
	v_fma_f32 v70, -v73, v75, v70
	v_div_scale_f32 v73, s[4:5], v69, v69, v72
	v_rcp_f32_e32 v77, v73
	v_div_fmas_f32 v70, v70, v76, v75
	v_div_fixup_f32 v60, v70, v60, v5
	v_lshlrev_b32_e32 v76, 16, v56
	v_fma_f32 v5, -v73, v77, 1.0
	v_fmac_f32_e32 v77, v5, v77
	v_div_scale_f32 v5, vcc, v72, v69, v72
	v_mul_f32_e32 v70, v5, v77
	v_fma_f32 v75, -v73, v70, v5
	v_fmac_f32_e32 v70, v75, v77
	v_fma_f32 v5, -v73, v70, v5
	v_div_scale_f32 v73, s[4:5], v68, v68, v71
	v_rcp_f32_e32 v75, v73
	v_div_fmas_f32 v5, v5, v77, v70
	v_div_fixup_f32 v69, v5, v69, v72
	v_and_b32_e32 v77, 0xffff0000, v56
	v_fma_f32 v5, -v73, v75, 1.0
	v_fmac_f32_e32 v75, v5, v75
	v_div_scale_f32 v5, vcc, v71, v68, v71
	v_mul_f32_e32 v70, v5, v75
	v_fma_f32 v72, -v73, v70, v5
	v_fmac_f32_e32 v70, v72, v75
	v_fma_f32 v5, -v73, v70, v5
	v_div_fmas_f32 v5, v5, v75, v70
	v_div_fixup_f32 v68, v5, v68, v71
	v_lshlrev_b32_e32 v5, 16, v52
	v_and_b32_e32 v75, 0xffff0000, v52
	v_mul_f32_e32 v52, 0xbfb8aa3b, v5
	v_exp_f32_e32 v78, v52
	v_mul_f32_e32 v52, 0xbfb8aa3b, v75
	v_exp_f32_e32 v79, v52
	v_lshlrev_b32_e32 v72, 16, v54
	v_and_b32_e32 v73, 0xffff0000, v54
	v_lshlrev_b32_e32 v54, 16, v55
	v_lshlrev_b32_e32 v56, 16, v57
	v_and_b32_e32 v55, 0xffff0000, v55
	v_and_b32_e32 v57, 0xffff0000, v57
	v_add_f32 v52, v54, v56
	v_add_f32 v53, v55, v57
	v_add_f32 v54, v78, 1.0
	v_add_f32 v55, v79, 1.0
	v_add_f32 v72, v72, v76
	v_add_f32 v73, v73, v77
	v_div_scale_f32 v78, s[4:5], v55, v55, v75
	v_rcp_f32_e32 v79, v78
	v_mul_f32 v76, v72, v72
	v_mul_f32 v77, v73, v73
	v_mul_f32 v56, v52, v52
	v_mul_f32 v57, v53, v53
	v_lshlrev_b64 v[70:71], 11, v[14:15]
	v_fma_f32 v82, -v78, v79, 1.0
	v_fmac_f32_e32 v79, v82, v79
	v_div_scale_f32 v82, vcc, v75, v55, v75
	v_mul_f32_e32 v83, v82, v79
	v_fma_f32 v84, -v78, v83, v82
	v_fmac_f32_e32 v83, v84, v79
	v_fma_f32 v78, -v78, v83, v82
	v_div_scale_f32 v82, s[4:5], v54, v54, v5
	v_rcp_f32_e32 v84, v82
	v_div_fmas_f32 v78, v78, v79, v83
	v_div_fixup_f32 v55, v78, v55, v75
	v_mov_b32_e32 v79, v66
	v_fma_f32 v75, -v82, v84, 1.0
	v_fmac_f32_e32 v84, v75, v84
	v_div_scale_f32 v75, vcc, v5, v54, v5
	v_mul_f32_e32 v83, v75, v84
	v_fma_f32 v78, -v82, v83, v75
	v_fmac_f32_e32 v83, v78, v84
	v_mov_b32_e32 v78, v76
	v_mov_b32_e32 v66, v77
	v_add_f32 v66, v78, v66
	v_add_f32 v67, v79, v67
	v_mov_b32_e32 v76, v56
	v_mov_b32_e32 v77, v62
	v_add_f32 v66, v66, v76
	v_add_f32 v67, v67, v77
	v_mov_b32_e32 v62, v57
	v_add_f32 v56, v62, v66
	v_add_f32 v57, v63, v67
	v_fma_f32 v75, -v82, v83, v75
	v_lshl_add_u64 v[70:71], s[16:17], 0, v[70:71]
	v_mov_b32_dpp v63, v57 quad_perm:[1,0,3,2] row_mask:0xf bank_mask:0xf bound_ctrl:1
	v_mov_b32_dpp v62, v56 quad_perm:[1,0,3,2] row_mask:0xf bank_mask:0xf bound_ctrl:1
	v_add_f32 v56, v56, v62
	v_add_f32 v57, v57, v63
	v_lshl_add_u64 v[70:71], v[70:71], 0, v[8:9]
	v_and_b32_e32 v66, 0xffff0000, v42
	v_mov_b32_dpp v63, v57 quad_perm:[2,3,0,1] row_mask:0xf bank_mask:0xf bound_ctrl:1
	v_mov_b32_dpp v62, v56 quad_perm:[2,3,0,1] row_mask:0xf bank_mask:0xf bound_ctrl:1
	v_add_f32 v56, v56, v62
	v_add_f32 v57, v57, v63
	v_lshlrev_b32_e32 v67, 16, v43
	s_nop 0
	v_mov_b32_dpp v63, v57 row_half_mirror row_mask:0xf bank_mask:0xf bound_ctrl:1
	v_mov_b32_dpp v62, v56 row_half_mirror row_mask:0xf bank_mask:0xf bound_ctrl:1
	v_add_f32 v56, v56, v62
	v_add_f32 v57, v57, v63
	s_nop 1
	v_mov_b32_dpp v63, v57 row_mirror row_mask:0xf bank_mask:0xf bound_ctrl:1
	v_mov_b32_dpp v62, v56 row_mirror row_mask:0xf bank_mask:0xf bound_ctrl:1
	v_add_f32 v56, v56, v62
	v_add_f32 v57, v57, v63
	s_nop 0
	v_fma_f32 v56, v56, s6, v44
	v_fma_f32 v57, v57, s6, v44
	s_nop 0
	v_mul_f32_e32 v62, 0x4b800000, v57
	v_cmp_gt_f32_e64 s[4:5], s7, v57
	s_nop 1
	v_cndmask_b32_e64 v57, v57, v62, s[4:5]
	v_rsq_f32_e32 v57, v57
	v_div_fmas_f32 v62, v75, v84, v83
	v_div_fixup_f32 v54, v62, v54, v5
	v_cmp_gt_f32_e32 vcc, s7, v56
	v_mul_f32_e32 v5, 0x45800000, v57
	v_cndmask_b32_e64 v62, v57, v5, s[4:5]
	v_mul_f32 v64, v64, v62
	v_mul_f32 v65, v65, v62
	v_mul_f32 v58, v58, v62
	v_mul_f32 v59, v59, v62
	v_mul_f32 v64, v0, v64
	v_mul_f32 v65, v1, v65
	v_mul_f32 v58, v2, v58
	v_mul_f32 v59, v3, v59
	v_mul_f32_e32 v5, 0x4b800000, v56
	v_mul_f32 v60, v60, v64
	v_mul_f32 v61, v61, v65
	v_mul_f32 v58, v68, v58
	v_mul_f32 v59, v69, v59
	v_cndmask_b32_e32 v5, v56, v5, vcc
	v_add_co_u32_e64 v56, s[4:5], s8, v70
	v_cvt_pk_bf16_f32 v60, v60, v61
	v_cvt_pk_bf16_f32 v61, v58, v59
	v_addc_co_u32_e64 v57, s[4:5], 0, v71, s[4:5]
	flat_store_dwordx2 v[56:57], v[60:61] offset:1024 sc1
	v_mul_f32_e32 v56, 0xbfb8aa3b, v80
	v_mul_f32_e32 v57, 0xbfb8aa3b, v81
	v_rsq_f32_e32 v5, v5
	v_exp_f32_e32 v56, v56
	v_exp_f32_e32 v57, v57
	v_and_b32_e32 v68, 0xffff0000, v43
	v_mul_f32_e32 v58, 0x45800000, v5
	v_cndmask_b32_e32 v58, v5, v58, vcc
	v_add_f32 v56, v56, 1.0
	v_add_f32 v57, v57, 1.0
	v_mul_f32 v60, v72, v58
	v_mul_f32 v61, v73, v58
	v_div_scale_f32 v5, s[4:5], v57, v57, v81
	v_rcp_f32_e32 v59, v5
	v_mul_f32 v60, v0, v60
	v_mul_f32 v61, v1, v61
	v_mul_f32 v52, v52, v58
	v_mul_f32 v53, v53, v58
	v_fma_f32 v58, -v5, v59, 1.0
	v_fmac_f32_e32 v59, v58, v59
	v_div_scale_f32 v58, vcc, v81, v57, v81
	v_mul_f32 v54, v54, v60
	v_mul_f32 v55, v55, v61
	v_mul_f32_e32 v60, v58, v59
	v_fma_f32 v61, -v5, v60, v58
	v_fmac_f32_e32 v60, v61, v59
	v_fma_f32 v5, -v5, v60, v58
	v_div_scale_f32 v58, s[4:5], v56, v56, v80
	v_rcp_f32_e32 v61, v58
	v_div_fmas_f32 v5, v5, v59, v60
	v_div_fixup_f32 v57, v5, v57, v81
	v_mul_f32 v52, v2, v52
	v_mul_f32 v53, v3, v53
	v_fma_f32 v5, -v58, v61, 1.0
	v_fmac_f32_e32 v61, v5, v61
	v_div_scale_f32 v5, vcc, v80, v56, v80
	v_mul_f32_e32 v59, v5, v61
	v_fma_f32 v60, -v58, v59, v5
	v_fmac_f32_e32 v59, v60, v61
	v_fma_f32 v5, -v58, v59, v5
	v_div_fmas_f32 v5, v5, v61, v59
	v_div_fixup_f32 v56, v5, v56, v80
	v_mul_f32 v52, v56, v52
	v_mul_f32 v53, v57, v53
	v_lshlrev_b32_e32 v5, 16, v46
	v_cvt_pk_bf16_f32 v54, v54, v55
	v_cvt_pk_bf16_f32 v55, v52, v53
	v_lshlrev_b64 v[52:53], 11, v[16:17]
	v_and_b32_e32 v58, 0xffff0000, v46
	v_mul_f32_e32 v46, 0xbfb8aa3b, v5
	v_lshl_add_u64 v[52:53], s[16:17], 0, v[52:53]
	v_exp_f32_e32 v56, v46
	v_mul_f32_e32 v46, 0xbfb8aa3b, v58
	v_lshl_add_u64 v[52:53], v[52:53], 0, v[8:9]
	v_exp_f32_e32 v57, v46
	v_add_co_u32_e32 v52, vcc, s8, v52
	v_lshlrev_b32_e32 v59, 16, v47
	s_nop 0
	v_addc_co_u32_e32 v53, vcc, 0, v53, vcc
	flat_store_dwordx2 v[52:53], v[54:55] offset:1024 sc1
	v_lshlrev_b32_e32 v52, 16, v48
	v_lshlrev_b32_e32 v54, 16, v50
	v_and_b32_e32 v53, 0xffff0000, v48
	v_and_b32_e32 v55, 0xffff0000, v50
	v_lshlrev_b32_e32 v48, 16, v49
	v_lshlrev_b32_e32 v50, 16, v51
	v_and_b32_e32 v49, 0xffff0000, v49
	v_and_b32_e32 v51, 0xffff0000, v51
	v_and_b32_e32 v60, 0xffff0000, v47
	v_add_f32 v46, v48, v50
	v_add_f32 v47, v49, v51
	v_add_f32 v48, v56, 1.0
	v_add_f32 v49, v57, 1.0
	v_add_f32 v52, v52, v54
	v_add_f32 v53, v53, v55
	v_div_scale_f32 v56, s[4:5], v49, v49, v58
	v_rcp_f32_e32 v57, v56
	v_mul_f32 v54, v52, v52
	v_mul_f32 v55, v53, v53
	v_mul_f32 v50, v46, v46
	v_mul_f32 v51, v47, v47
	v_fma_f32 v61, -v56, v57, 1.0
	v_fmac_f32_e32 v57, v61, v57
	v_div_scale_f32 v61, vcc, v58, v49, v58
	v_mul_f32_e32 v62, v61, v57
	v_fma_f32 v63, -v56, v62, v61
	v_fmac_f32_e32 v62, v63, v57
	v_fma_f32 v56, -v56, v62, v61
	v_div_scale_f32 v61, s[4:5], v48, v48, v5
	v_rcp_f32_e32 v63, v61
	v_div_fmas_f32 v56, v56, v57, v62
	v_div_fixup_f32 v49, v56, v49, v58
	v_mul_f32_e32 v57, 0xbfb8aa3b, v60
	v_fma_f32 v56, -v61, v63, 1.0
	v_fmac_f32_e32 v63, v56, v63
	v_mul_f32_e32 v56, 0xbfb8aa3b, v59
	v_exp_f32_e32 v56, v56
	v_exp_f32_e32 v57, v57
	v_div_scale_f32 v58, vcc, v5, v48, v5
	v_mul_f32_e32 v62, v58, v63
	v_fma_f32 v64, -v61, v62, v58
	v_fmac_f32_e32 v62, v64, v63
	v_add_f32 v56, v56, 1.0
	v_add_f32 v57, v57, 1.0
	v_fma_f32 v58, -v61, v62, v58
	v_div_scale_f32 v61, s[4:5], v57, v57, v60
	v_rcp_f32_e32 v64, v61
	v_div_fmas_f32 v58, v58, v63, v62
	v_div_fixup_f32 v48, v58, v48, v5
	v_and_b32_e32 v63, 0xffff0000, v40
	v_fma_f32 v5, -v61, v64, 1.0
	v_fmac_f32_e32 v64, v5, v64
	v_div_scale_f32 v5, vcc, v60, v57, v60
	v_mul_f32_e32 v58, v5, v64
	v_fma_f32 v62, -v61, v58, v5
	v_fmac_f32_e32 v58, v62, v64
	v_fma_f32 v5, -v61, v58, v5
	v_div_scale_f32 v61, s[4:5], v56, v56, v59
	v_rcp_f32_e32 v62, v61
	v_div_fmas_f32 v5, v5, v64, v58
	v_div_fixup_f32 v57, v5, v57, v60
	v_fma_f32 v5, -v61, v62, 1.0
	v_fmac_f32_e32 v62, v5, v62
	v_div_scale_f32 v5, vcc, v59, v56, v59
	v_mul_f32_e32 v58, v5, v62
	v_fma_f32 v60, -v61, v58, v5
	v_fmac_f32_e32 v58, v60, v62
	v_fma_f32 v5, -v61, v58, v5
	v_div_fmas_f32 v5, v5, v62, v58
	v_div_fixup_f32 v56, v5, v56, v59
	v_lshlrev_b32_e32 v5, 16, v42
	v_mul_f32_e32 v42, 0xbfb8aa3b, v5
	v_exp_f32_e32 v64, v42
	v_mul_f32_e32 v42, 0xbfb8aa3b, v66
	v_exp_f32_e32 v65, v42
	v_lshlrev_b32_e32 v60, 16, v38
	v_lshlrev_b32_e32 v62, 16, v40
	v_and_b32_e32 v61, 0xffff0000, v38
	v_lshlrev_b32_e32 v38, 16, v39
	v_lshlrev_b32_e32 v40, 16, v41
	v_and_b32_e32 v39, 0xffff0000, v39
	v_and_b32_e32 v41, 0xffff0000, v41
	v_add_f32 v38, v38, v40
	v_add_f32 v39, v39, v41
	v_add_f32 v40, v64, 1.0
	v_add_f32 v41, v65, 1.0
	v_add_f32 v60, v60, v62
	v_add_f32 v61, v61, v63
	v_div_scale_f32 v64, s[4:5], v41, v41, v66
	v_rcp_f32_e32 v65, v64
	v_mul_f32 v62, v60, v60
	v_mul_f32 v63, v61, v61
	v_mul_f32 v42, v38, v38
	v_mul_f32 v43, v39, v39
	v_lshlrev_b64 v[58:59], 11, v[18:19]
	v_fma_f32 v69, -v64, v65, 1.0
	v_fmac_f32_e32 v65, v69, v65
	v_div_scale_f32 v69, vcc, v66, v41, v66
	v_mul_f32_e32 v70, v69, v65
	v_fma_f32 v71, -v64, v70, v69
	v_fmac_f32_e32 v70, v71, v65
	v_fma_f32 v64, -v64, v70, v69
	v_div_scale_f32 v69, s[4:5], v40, v40, v5
	v_rcp_f32_e32 v71, v69
	v_div_fmas_f32 v64, v64, v65, v70
	v_div_fixup_f32 v41, v64, v41, v66
	v_lshl_add_u64 v[58:59], s[16:17], 0, v[58:59]
	v_fma_f32 v64, -v69, v71, 1.0
	v_fmac_f32_e32 v71, v64, v71
	v_div_scale_f32 v64, vcc, v5, v40, v5
	v_mul_f32_e32 v66, v64, v71
	v_fma_f32 v65, -v69, v66, v64
	v_fmac_f32_e32 v66, v65, v71
	v_fma_f32 v69, -v69, v66, v64
	v_mov_b32_e32 v64, v62
	v_mov_b32_e32 v65, v54
	v_mov_b32_e32 v54, v63
	v_add_f32 v54, v64, v54
	v_add_f32 v55, v65, v55
	v_mov_b32_e32 v62, v42
	v_mov_b32_e32 v63, v50
	v_add_f32 v54, v54, v62
	v_add_f32 v55, v55, v63
	v_mov_b32_e32 v50, v43
	v_add_f32 v42, v50, v54
	v_add_f32 v43, v51, v55
	v_lshl_add_u64 v[58:59], v[58:59], 0, v[8:9]
	s_waitcnt lgkmcnt(0)
	v_and_b32_e32 v54, 0xffff0000, v26
	v_mov_b32_dpp v51, v43 quad_perm:[1,0,3,2] row_mask:0xf bank_mask:0xf bound_ctrl:1
	v_mov_b32_dpp v50, v42 quad_perm:[1,0,3,2] row_mask:0xf bank_mask:0xf bound_ctrl:1
	v_add_f32 v42, v42, v50
	v_add_f32 v43, v43, v51
	v_lshlrev_b32_e32 v55, 16, v27
	s_nop 0
	v_mov_b32_dpp v51, v43 quad_perm:[2,3,0,1] row_mask:0xf bank_mask:0xf bound_ctrl:1
	v_mov_b32_dpp v50, v42 quad_perm:[2,3,0,1] row_mask:0xf bank_mask:0xf bound_ctrl:1
	v_add_f32 v42, v42, v50
	v_add_f32 v43, v43, v51
	s_nop 1
	v_mov_b32_dpp v51, v43 row_half_mirror row_mask:0xf bank_mask:0xf bound_ctrl:1
	v_mov_b32_dpp v50, v42 row_half_mirror row_mask:0xf bank_mask:0xf bound_ctrl:1
	v_add_f32 v42, v42, v50
	v_add_f32 v43, v43, v51
	s_nop 1
	v_mov_b32_dpp v51, v43 row_mirror row_mask:0xf bank_mask:0xf bound_ctrl:1
	v_mov_b32_dpp v50, v42 row_mirror row_mask:0xf bank_mask:0xf bound_ctrl:1
	v_add_f32 v42, v42, v50
	v_add_f32 v43, v43, v51
	s_nop 0
	v_fma_f32 v42, v42, s6, v44
	v_fma_f32 v43, v43, s6, v44
	s_nop 0
	v_mul_f32_e32 v50, 0x4b800000, v43
	v_cmp_gt_f32_e64 s[4:5], s7, v43
	s_nop 1
	v_cndmask_b32_e64 v43, v43, v50, s[4:5]
	v_rsq_f32_e32 v43, v43
	v_div_fmas_f32 v50, v69, v71, v66
	v_div_fixup_f32 v40, v50, v40, v5
	v_cmp_gt_f32_e32 vcc, s7, v42
	v_mul_f32_e32 v5, 0x45800000, v43
	v_cndmask_b32_e64 v50, v43, v5, s[4:5]
	v_mul_f32 v52, v52, v50
	v_mul_f32 v53, v53, v50
	v_mul_f32 v46, v46, v50
	v_mul_f32 v47, v47, v50
	v_mul_f32 v52, v0, v52
	v_mul_f32 v53, v1, v53
	v_mul_f32 v46, v2, v46
	v_mul_f32 v47, v3, v47
	v_mul_f32_e32 v5, 0x4b800000, v42
	v_mul_f32 v48, v48, v52
	v_mul_f32 v49, v49, v53
	v_mul_f32 v46, v56, v46
	v_mul_f32 v47, v57, v47
	v_cndmask_b32_e32 v5, v42, v5, vcc
	v_add_co_u32_e64 v42, s[4:5], s8, v58
	v_cvt_pk_bf16_f32 v48, v48, v49
	v_cvt_pk_bf16_f32 v49, v46, v47
	v_addc_co_u32_e64 v43, s[4:5], 0, v59, s[4:5]
	flat_store_dwordx2 v[42:43], v[48:49] offset:1024 sc1
	v_mul_f32_e32 v42, 0xbfb8aa3b, v67
	v_mul_f32_e32 v43, 0xbfb8aa3b, v68
	v_rsq_f32_e32 v5, v5
	v_exp_f32_e32 v42, v42
	v_exp_f32_e32 v43, v43
	v_and_b32_e32 v56, 0xffff0000, v27
	v_mul_f32_e32 v46, 0x45800000, v5
	v_cndmask_b32_e32 v46, v5, v46, vcc
	v_add_f32 v42, v42, 1.0
	v_add_f32 v43, v43, 1.0
	v_mul_f32 v48, v60, v46
	v_mul_f32 v49, v61, v46
	v_div_scale_f32 v5, s[4:5], v43, v43, v68
	v_rcp_f32_e32 v47, v5
	v_mul_f32 v48, v0, v48
	v_mul_f32 v49, v1, v49
	v_mul_f32 v38, v38, v46
	v_mul_f32 v39, v39, v46
	v_fma_f32 v46, -v5, v47, 1.0
	v_fmac_f32_e32 v47, v46, v47
	v_div_scale_f32 v46, vcc, v68, v43, v68
	v_mul_f32 v40, v40, v48
	v_mul_f32 v41, v41, v49
	v_mul_f32_e32 v48, v46, v47
	v_fma_f32 v49, -v5, v48, v46
	v_fmac_f32_e32 v48, v49, v47
	v_fma_f32 v5, -v5, v48, v46
	v_div_scale_f32 v46, s[4:5], v42, v42, v67
	v_rcp_f32_e32 v49, v46
	v_div_fmas_f32 v5, v5, v47, v48
	v_div_fixup_f32 v43, v5, v43, v68
	v_mul_f32 v38, v2, v38
	v_mul_f32 v39, v3, v39
	v_fma_f32 v5, -v46, v49, 1.0
	v_fmac_f32_e32 v49, v5, v49
	v_div_scale_f32 v5, vcc, v67, v42, v67
	v_mul_f32_e32 v47, v5, v49
	v_fma_f32 v48, -v46, v47, v5
	v_fmac_f32_e32 v47, v48, v49
	v_fma_f32 v5, -v46, v47, v5
	v_div_fmas_f32 v5, v5, v49, v47
	v_div_fixup_f32 v42, v5, v42, v67
	v_mul_f32 v38, v42, v38
	v_mul_f32 v39, v43, v39
	v_lshlrev_b32_e32 v5, 16, v32
	v_cvt_pk_bf16_f32 v40, v40, v41
	v_cvt_pk_bf16_f32 v41, v38, v39
	v_lshlrev_b64 v[38:39], 11, v[20:21]
	v_and_b32_e32 v46, 0xffff0000, v32
	v_mul_f32_e32 v32, 0xbfb8aa3b, v5
	v_lshl_add_u64 v[38:39], s[16:17], 0, v[38:39]
	v_exp_f32_e32 v42, v32
	v_mul_f32_e32 v32, 0xbfb8aa3b, v46
	v_lshl_add_u64 v[38:39], v[38:39], 0, v[8:9]
	v_exp_f32_e32 v43, v32
	v_add_co_u32_e32 v38, vcc, s8, v38
	v_lshlrev_b32_e32 v47, 16, v33
	s_nop 0
	v_addc_co_u32_e32 v39, vcc, 0, v39, vcc
	flat_store_dwordx2 v[38:39], v[40:41] offset:1024 sc1
	v_lshlrev_b32_e32 v38, 16, v34
	v_lshlrev_b32_e32 v40, 16, v36
	v_and_b32_e32 v39, 0xffff0000, v34
	v_and_b32_e32 v41, 0xffff0000, v36
	v_lshlrev_b32_e32 v34, 16, v35
	v_lshlrev_b32_e32 v36, 16, v37
	v_and_b32_e32 v35, 0xffff0000, v35
	v_and_b32_e32 v37, 0xffff0000, v37
	v_and_b32_e32 v48, 0xffff0000, v33
	v_add_f32 v32, v34, v36
	v_add_f32 v33, v35, v37
	v_add_f32 v34, v42, 1.0
	v_add_f32 v35, v43, 1.0
	v_add_f32 v38, v38, v40
	v_add_f32 v39, v39, v41
	v_div_scale_f32 v42, s[4:5], v35, v35, v46
	v_rcp_f32_e32 v43, v42
	v_mul_f32 v40, v38, v38
	v_mul_f32 v41, v39, v39
	v_mul_f32 v36, v32, v32
	v_mul_f32 v37, v33, v33
	v_fma_f32 v49, -v42, v43, 1.0
	v_fmac_f32_e32 v43, v49, v43
	v_div_scale_f32 v49, vcc, v46, v35, v46
	v_mul_f32_e32 v50, v49, v43
	v_fma_f32 v51, -v42, v50, v49
	v_fmac_f32_e32 v50, v51, v43
	v_fma_f32 v42, -v42, v50, v49
	v_div_scale_f32 v49, s[4:5], v34, v34, v5
	v_rcp_f32_e32 v51, v49
	v_div_fmas_f32 v42, v42, v43, v50
	v_div_fixup_f32 v35, v42, v35, v46
	v_mul_f32_e32 v43, 0xbfb8aa3b, v48
	v_fma_f32 v42, -v49, v51, 1.0
	v_fmac_f32_e32 v51, v42, v51
	v_mul_f32_e32 v42, 0xbfb8aa3b, v47
	v_exp_f32_e32 v42, v42
	v_exp_f32_e32 v43, v43
	v_div_scale_f32 v46, vcc, v5, v34, v5
	v_mul_f32_e32 v50, v46, v51
	v_fma_f32 v52, -v49, v50, v46
	v_fmac_f32_e32 v50, v52, v51
	v_add_f32 v42, v42, 1.0
	v_add_f32 v43, v43, 1.0
	v_fma_f32 v46, -v49, v50, v46
	v_div_scale_f32 v49, s[4:5], v43, v43, v48
	v_rcp_f32_e32 v52, v49
	v_div_fmas_f32 v46, v46, v51, v50
	v_div_fixup_f32 v34, v46, v34, v5
	v_and_b32_e32 v51, 0xffff0000, v30
	v_fma_f32 v5, -v49, v52, 1.0
	v_fmac_f32_e32 v52, v5, v52
	v_div_scale_f32 v5, vcc, v48, v43, v48
	v_mul_f32_e32 v46, v5, v52
	v_fma_f32 v50, -v49, v46, v5
	v_fmac_f32_e32 v46, v50, v52
	v_fma_f32 v5, -v49, v46, v5
	v_div_scale_f32 v49, s[4:5], v42, v42, v47
	v_rcp_f32_e32 v50, v49
	v_div_fmas_f32 v5, v5, v52, v46
	v_div_fixup_f32 v43, v5, v43, v48
	v_fma_f32 v5, -v49, v50, 1.0
	v_fmac_f32_e32 v50, v5, v50
	v_div_scale_f32 v5, vcc, v47, v42, v47
	v_mul_f32_e32 v46, v5, v50
	v_fma_f32 v48, -v49, v46, v5
	v_fmac_f32_e32 v46, v48, v50
	v_fma_f32 v5, -v49, v46, v5
	v_div_fmas_f32 v5, v5, v50, v46
	v_div_fixup_f32 v42, v5, v42, v47
	v_lshlrev_b32_e32 v5, 16, v26
	v_mul_f32_e32 v26, 0xbfb8aa3b, v5
	v_exp_f32_e32 v52, v26
	v_mul_f32_e32 v26, 0xbfb8aa3b, v54
	v_exp_f32_e32 v53, v26
	v_lshlrev_b32_e32 v48, 16, v28
	v_lshlrev_b32_e32 v50, 16, v30
	v_and_b32_e32 v49, 0xffff0000, v28
	v_lshlrev_b32_e32 v28, 16, v29
	v_lshlrev_b32_e32 v30, 16, v31
	v_and_b32_e32 v29, 0xffff0000, v29
	v_and_b32_e32 v31, 0xffff0000, v31
	v_add_f32 v26, v28, v30
	v_add_f32 v27, v29, v31
	v_add_f32 v28, v52, 1.0
	v_add_f32 v29, v53, 1.0
	v_add_f32 v48, v48, v50
	v_add_f32 v49, v49, v51
	v_div_scale_f32 v52, s[4:5], v29, v29, v54
	v_rcp_f32_e32 v53, v52
	v_mul_f32 v50, v48, v48
	v_mul_f32 v51, v49, v49
	v_mul_f32 v30, v26, v26
	v_mul_f32 v31, v27, v27
	v_lshlrev_b64 v[46:47], 11, v[22:23]
	v_fma_f32 v57, -v52, v53, 1.0
	v_fmac_f32_e32 v53, v57, v53
	v_div_scale_f32 v57, vcc, v54, v29, v54
	v_mul_f32_e32 v58, v57, v53
	v_fma_f32 v59, -v52, v58, v57
	v_fmac_f32_e32 v58, v59, v53
	v_fma_f32 v52, -v52, v58, v57
	v_div_scale_f32 v57, s[4:5], v28, v28, v5
	v_rcp_f32_e32 v59, v57
	v_div_fmas_f32 v52, v52, v53, v58
	v_div_fixup_f32 v29, v52, v29, v54
	v_lshl_add_u64 v[46:47], s[16:17], 0, v[46:47]
	v_fma_f32 v52, -v57, v59, 1.0
	v_fmac_f32_e32 v59, v52, v59
	v_div_scale_f32 v52, vcc, v5, v28, v5
	v_mul_f32_e32 v54, v52, v59
	v_fma_f32 v53, -v57, v54, v52
	v_fmac_f32_e32 v54, v53, v59
	v_fma_f32 v57, -v57, v54, v52
	v_mov_b32_e32 v52, v50
	v_mov_b32_e32 v53, v40
	v_mov_b32_e32 v40, v51
	v_add_f32 v40, v52, v40
	v_add_f32 v41, v53, v41
	v_mov_b32_e32 v50, v30
	v_mov_b32_e32 v51, v36
	v_add_f32 v40, v40, v50
	v_add_f32 v41, v41, v51
	v_mov_b32_e32 v36, v31
	v_add_f32 v30, v36, v40
	v_add_f32 v31, v37, v41
	v_lshl_add_u64 v[46:47], v[46:47], 0, v[8:9]
	s_nop 0
	v_mov_b32_dpp v37, v31 quad_perm:[1,0,3,2] row_mask:0xf bank_mask:0xf bound_ctrl:1
	v_mov_b32_dpp v36, v30 quad_perm:[1,0,3,2] row_mask:0xf bank_mask:0xf bound_ctrl:1
	v_add_f32 v30, v30, v36
	v_add_f32 v31, v31, v37
	s_nop 1
	v_mov_b32_dpp v37, v31 quad_perm:[2,3,0,1] row_mask:0xf bank_mask:0xf bound_ctrl:1
	v_mov_b32_dpp v36, v30 quad_perm:[2,3,0,1] row_mask:0xf bank_mask:0xf bound_ctrl:1
	v_add_f32 v30, v30, v36
	v_add_f32 v31, v31, v37
	s_nop 1
	v_mov_b32_dpp v37, v31 row_half_mirror row_mask:0xf bank_mask:0xf bound_ctrl:1
	v_mov_b32_dpp v36, v30 row_half_mirror row_mask:0xf bank_mask:0xf bound_ctrl:1
	v_add_f32 v30, v30, v36
	v_add_f32 v31, v31, v37
	s_nop 1
	v_mov_b32_dpp v37, v31 row_mirror row_mask:0xf bank_mask:0xf bound_ctrl:1
	v_mov_b32_dpp v36, v30 row_mirror row_mask:0xf bank_mask:0xf bound_ctrl:1
	v_add_f32 v30, v30, v36
	v_add_f32 v31, v31, v37
	s_nop 0
	v_fma_f32 v30, v30, s6, v44
	v_fma_f32 v31, v31, s6, v44
	s_nop 0
	v_mul_f32_e32 v36, 0x4b800000, v31
	v_cmp_gt_f32_e64 s[4:5], s7, v31
	s_nop 1
	v_cndmask_b32_e64 v31, v31, v36, s[4:5]
	v_rsq_f32_e32 v31, v31
	v_div_fmas_f32 v36, v57, v59, v54
	v_div_fixup_f32 v28, v36, v28, v5
	v_cmp_gt_f32_e32 vcc, s7, v30
	v_mul_f32_e32 v5, 0x45800000, v31
	v_cndmask_b32_e64 v36, v31, v5, s[4:5]
	v_mul_f32 v38, v38, v36
	v_mul_f32 v39, v39, v36
	v_mul_f32 v32, v32, v36
	v_mul_f32 v33, v33, v36
	v_mul_f32 v38, v0, v38
	v_mul_f32 v39, v1, v39
	v_mul_f32 v32, v2, v32
	v_mul_f32 v33, v3, v33
	v_mul_f32_e32 v5, 0x4b800000, v30
	v_mul_f32 v34, v34, v38
	v_mul_f32 v35, v35, v39
	v_mul_f32 v32, v42, v32
	v_mul_f32 v33, v43, v33
	v_cndmask_b32_e32 v5, v30, v5, vcc
	v_add_co_u32_e64 v30, s[4:5], s8, v46
	v_cvt_pk_bf16_f32 v34, v34, v35
	v_cvt_pk_bf16_f32 v35, v32, v33
	v_addc_co_u32_e64 v31, s[4:5], 0, v47, s[4:5]
	flat_store_dwordx2 v[30:31], v[34:35] offset:1024 sc1
	v_mul_f32_e32 v30, 0xbfb8aa3b, v55
	v_mul_f32_e32 v31, 0xbfb8aa3b, v56
	v_rsq_f32_e32 v5, v5
	v_exp_f32_e32 v30, v30
	v_exp_f32_e32 v31, v31
	v_mul_f32_e32 v32, 0x45800000, v5
	v_cndmask_b32_e32 v32, v5, v32, vcc
	v_add_f32 v30, v30, 1.0
	v_add_f32 v31, v31, 1.0
	v_mul_f32 v34, v48, v32
	v_mul_f32 v35, v49, v32
	v_div_scale_f32 v5, s[4:5], v31, v31, v56
	v_rcp_f32_e32 v33, v5
	v_mul_f32 v0, v0, v34
	v_mul_f32 v1, v1, v35
	v_mul_f32 v26, v26, v32
	v_mul_f32 v27, v27, v32
	s_nop 0
	v_mul_f32 v2, v2, v26
	v_mul_f32 v3, v3, v27
	v_fma_f32 v26, -v5, v33, 1.0
	v_fmac_f32_e32 v33, v26, v33
	v_div_scale_f32 v26, vcc, v56, v31, v56
	v_mul_f32_e32 v27, v26, v33
	v_mul_f32 v0, v28, v0
	v_mul_f32 v1, v29, v1
	v_fma_f32 v28, -v5, v27, v26
	v_fmac_f32_e32 v27, v28, v33
	v_fma_f32 v5, -v5, v27, v26
	v_div_scale_f32 v26, s[4:5], v30, v30, v55
	v_rcp_f32_e32 v28, v26
	v_div_fmas_f32 v5, v5, v33, v27
	v_div_fixup_f32 v27, v5, v31, v56
	v_cvt_pk_bf16_f32 v0, v0, v1
	v_fma_f32 v5, -v26, v28, 1.0
	v_fmac_f32_e32 v28, v5, v28
	v_div_scale_f32 v5, vcc, v55, v30, v55
	v_mul_f32_e32 v29, v5, v28
	v_fma_f32 v31, -v26, v29, v5
	v_fmac_f32_e32 v29, v31, v28
	v_fma_f32 v5, -v26, v29, v5
	v_div_fmas_f32 v5, v5, v28, v29
	v_div_fixup_f32 v26, v5, v30, v55
	v_mul_f32 v2, v26, v2
	v_mul_f32 v3, v27, v3
	s_mov_b64 s[4:5], 0
	v_cvt_pk_bf16_f32 v1, v2, v3
	v_lshlrev_b64 v[2:3], 11, v[24:25]
	v_lshl_add_u64 v[2:3], s[16:17], 0, v[2:3]
	v_lshl_add_u64 v[2:3], v[2:3], 0, v[8:9]
	v_add_co_u32_e32 v2, vcc, 0x4552000, v2
	s_nop 1
	v_addc_co_u32_e32 v3, vcc, 0, v3, vcc
	flat_store_dwordx2 v[2:3], v[0:1] offset:1024 sc1
	s_waitcnt vmcnt(0)
	v_cmp_eq_u32_e32 vcc, 0, v74
	s_and_saveexec_b64 s[6:7], vcc
	s_cbranch_execz .LBB0_1419
	v_alignbit_b32 v0, v11, v10, 8
	v_alignbit_b32 v1, v7, v6, 8
	v_cmp_eq_u32_e32 vcc, v0, v1
	v_alignbit_b32 v2, v13, v12, 8
	v_alignbit_b32 v3, v17, v16, 8
	v_cndmask_b32_e64 v0, 1, 2, vcc
	v_cmp_eq_u32_e32 vcc, v2, v1
	v_alignbit_b32 v2, v15, v14, 8
	s_mov_b64 s[8:9], 0
	v_addc_co_u32_e32 v0, vcc, 0, v0, vcc
	v_cmp_eq_u32_e32 vcc, v2, v1
	s_nop 1
	v_cndmask_b32_e64 v2, 0, 1, vcc
	v_cmp_eq_u32_e32 vcc, v3, v1
	v_alignbit_b32 v3, v21, v20, 8
	s_nop 0
	v_addc_co_u32_e32 v0, vcc, v0, v2, vcc
	v_alignbit_b32 v2, v19, v18, 8
	v_cmp_eq_u32_e32 vcc, v2, v1
	s_nop 1
	v_cndmask_b32_e64 v2, 0, 1, vcc
	v_cmp_eq_u32_e32 vcc, v3, v1
	v_alignbit_b32 v3, v25, v24, 8
	s_nop 0
	v_addc_co_u32_e32 v0, vcc, v0, v2, vcc
	v_alignbit_b32 v2, v23, v22, 8
	v_cmp_eq_u32_e32 vcc, v2, v1
	s_nop 1
	v_cndmask_b32_e64 v2, 0, 1, vcc
	v_cmp_eq_u32_e32 vcc, v3, v1
	s_nop 1
	v_addc_co_u32_e32 v2, vcc, v0, v2, vcc
	v_lshlrev_b32_e32 v0, 6, v1
	v_ashrrev_i32_e32 v1, 31, v0
	v_lshl_add_u64 v[6:7], v[0:1], 2, s[18:19]
	flat_atomic_add v[6:7], v2
	v_cmp_gt_u32_e32 vcc, 9, v2
	s_and_saveexec_b64 s[10:11], vcc
	s_xor_b64 s[10:11], exec, s[10:11]
	s_mov_b64 s[8:9], exec
	v_sub_u32_e32 v1, 9, v2
	s_or_b64 exec, exec, s[10:11]
	s_and_b64 s[10:11], s[8:9], exec

.LBB0_1423:
	s_or_b64 exec, exec, s[6:7]
	s_mul_i32 s6, s3, 40
	s_ashr_i32 s7, s6, 31
	v_ashrrev_i32_e32 v5, 31, v4
	v_lshlrev_b32_e32 v6, 3, v74
	v_lshl_add_u64 v[4:5], s[6:7], 0, v[4:5]
	v_lshl_add_u64 v[2:3], s[16:17], 0, v[6:7]
	s_mov_b64 s[6:7], 0x6952000
	v_lshl_add_u64 v[16:17], v[2:3], 0, s[6:7]
	s_mov_b64 s[6:7], 0x6f52000
	v_lshl_add_u64 v[18:19], v[2:3], 0, s[6:7]
	s_mov_b64 s[6:7], 0xcb32000
	v_lshlrev_b64 v[8:9], 9, v[4:5]
	v_lshl_add_u64 v[2:3], v[2:3], 0, s[6:7]
	v_lshl_add_u64 v[10:11], v[16:17], 0, v[8:9]
	v_lshl_add_u64 v[12:13], v[18:19], 0, v[8:9]
	v_lshl_add_u64 v[8:9], v[2:3], 0, v[8:9]
	flat_load_dwordx2 v[34:35], v[10:11]
	flat_load_dwordx2 v[36:37], v[12:13]
	flat_load_dwordx2 v[38:39], v[8:9]
	s_ashr_i32 s7, s70, 31
	s_add_u32 s6, s90, s70
	s_addc_u32 s7, s91, s7
	s_load_dwordx2 s[6:7], s[6:7], 0xb8
	v_lshl_add_u64 v[14:15], v[4:5], 0, 8
	v_and_b32_e32 v70, 0xf0, v0
	v_lshl_add_u64 v[12:13], v[4:5], 0, 16
	v_lshl_add_u64 v[10:11], v[4:5], 0, 24
	v_lshl_add_u64 v[8:9], v[4:5], 0, 32
	v_lshlrev_b64 v[0:1], 9, v[14:15]
	v_lshlrev_b64 v[20:21], 9, v[12:13]
	v_lshlrev_b64 v[22:23], 9, v[10:11]
	v_lshlrev_b64 v[24:25], 9, v[8:9]
	v_lshl_add_u64 v[40:41], v[16:17], 0, v[0:1]
	v_lshl_add_u64 v[42:43], v[18:19], 0, v[0:1]
	v_lshl_add_u64 v[44:45], v[2:3], 0, v[0:1]
	v_lshl_add_u64 v[46:47], v[16:17], 0, v[20:21]
	v_lshl_add_u64 v[48:49], v[18:19], 0, v[20:21]
	v_lshl_add_u64 v[50:51], v[2:3], 0, v[20:21]
	v_lshl_add_u64 v[52:53], v[16:17], 0, v[22:23]
	v_lshl_add_u64 v[54:55], v[18:19], 0, v[22:23]
	v_lshl_add_u64 v[56:57], v[2:3], 0, v[22:23]
	v_lshl_add_u64 v[58:59], v[16:17], 0, v[24:25]
	v_lshl_add_u64 v[60:61], v[18:19], 0, v[24:25]
	v_lshl_add_u64 v[62:63], v[2:3], 0, v[24:25]
	flat_load_dwordx2 v[64:65], v[40:41]
	s_waitcnt lgkmcnt(0)
	global_load_dwordx4 v[0:3], v70, s[6:7]
	flat_load_dwordx2 v[66:67], v[42:43]
	flat_load_dwordx2 v[68:69], v[44:45]
	flat_load_dwordx2 v[30:31], v[46:47]
	flat_load_dwordx2 v[32:33], v[48:49]
	flat_load_dwordx2 v[28:29], v[50:51]
	flat_load_dwordx2 v[24:25], v[52:53]
	flat_load_dwordx2 v[26:27], v[54:55]
	flat_load_dwordx2 v[22:23], v[56:57]
	flat_load_dwordx2 v[18:19], v[58:59]
	flat_load_dwordx2 v[20:21], v[60:61]
	flat_load_dwordx2 v[16:17], v[62:63]
	s_mov_b32 s13, 0x800000
	s_mov_b32 s12, 0x3c800000
	s_waitcnt vmcnt(0)
	v_lshlrev_b32_e32 v40, 16, v34
	v_lshlrev_b32_e32 v42, 16, v36
	v_and_b32_e32 v41, 0xffff0000, v34
	v_and_b32_e32 v43, 0xffff0000, v36
	v_lshlrev_b32_e32 v34, 16, v35
	v_lshlrev_b32_e32 v36, 16, v37
	v_and_b32_e32 v35, 0xffff0000, v35
	v_and_b32_e32 v37, 0xffff0000, v37
	v_lshlrev_b32_e32 v44, 16, v38
	v_and_b32_e32 v45, 0xffff0000, v38
	v_add_f32 v34, v34, v36
	v_add_f32 v35, v35, v37
	v_mul_f32_e32 v36, 0xbfb8aa3b, v44
	v_mul_f32_e32 v37, 0xbfb8aa3b, v45
	v_exp_f32_e32 v36, v36
	v_exp_f32_e32 v37, v37
	v_lshlrev_b32_e32 v46, 16, v39
	v_and_b32_e32 v47, 0xffff0000, v39
	v_add_f32 v38, v40, v42
	v_add_f32 v39, v41, v43
	v_add_f32 v36, v36, 1.0
	v_add_f32 v37, v37, 1.0
	v_mul_f32 v42, v38, v38
	v_mul_f32 v43, v39, v39
	v_div_scale_f32 v48, s[6:7], v37, v37, v45
	v_rcp_f32_e32 v51, v48
	v_div_scale_f32 v50, s[6:7], v36, v36, v44
	v_mul_f32 v40, v34, v34
	v_mul_f32 v41, v35, v35
	v_rcp_f32_e32 v52, v50
	v_add_f32_e32 v42, v42, v43
	v_add_f32_e32 v40, v42, v40
	v_fma_f32 v54, -v48, v51, 1.0
	v_add_f32_e32 v40, v41, v40
	v_div_scale_f32 v49, vcc, v45, v37, v45
	v_fmac_f32_e32 v51, v54, v51
	v_add_f32_dpp v40, v40, v40 quad_perm:[1,0,3,2] row_mask:0xf bank_mask:0xf bound_ctrl:1
	v_fma_f32 v55, -v50, v52, 1.0
	v_mul_f32_e32 v54, v49, v51
	v_add_f32_dpp v40, v40, v40 quad_perm:[2,3,0,1] row_mask:0xf bank_mask:0xf bound_ctrl:1
	v_div_scale_f32 v53, s[6:7], v44, v36, v44
	v_fmac_f32_e32 v52, v55, v52
	v_fma_f32 v56, -v48, v54, v49
	v_add_f32_dpp v40, v40, v40 row_half_mirror row_mask:0xf bank_mask:0xf bound_ctrl:1
	v_mul_f32_e32 v55, v53, v52
	v_fmac_f32_e32 v54, v56, v51
	v_add_f32_dpp v40, v40, v40 row_mirror row_mask:0xf bank_mask:0xf bound_ctrl:1
	v_mov_b32_e32 v41, 0x358637bd
	v_fma_f32 v57, -v50, v55, v53
	v_fma_f32 v48, -v48, v54, v49
	v_fmac_f32_e32 v41, 0x3c800000, v40
	v_fmac_f32_e32 v55, v57, v52
	v_div_fmas_f32 v48, v48, v51, v54
	v_mul_f32_e32 v40, 0x4b800000, v41
	v_cmp_gt_f32_e64 s[8:9], s13, v41
	v_div_fixup_f32 v37, v48, v37, v45
	v_fma_f32 v45, -v50, v55, v53
	v_cndmask_b32_e64 v40, v41, v40, s[8:9]
	s_mov_b64 vcc, s[6:7]
	v_rsq_f32_e32 v42, v40
	v_div_fmas_f32 v40, v45, v52, v55
	v_div_fixup_f32 v36, v40, v36, v44
	v_mul_f32_e32 v40, 0xbfb8aa3b, v46
	v_mul_f32_e32 v41, 0xbfb8aa3b, v47
	v_exp_f32_e32 v40, v40
	v_exp_f32_e32 v41, v41
	v_mul_f32_e32 v43, 0x45800000, v42
	v_cndmask_b32_e64 v42, v42, v43, s[8:9]
	v_mul_f32 v38, v38, v42
	v_mul_f32 v39, v39, v42
	v_add_f32 v40, v40, 1.0
	v_add_f32 v41, v41, 1.0
	v_mul_f32 v38, v0, v38
	v_mul_f32 v39, v1, v39
	v_div_scale_f32 v43, s[6:7], v41, v41, v47
	v_rcp_f32_e32 v44, v43
	v_mul_f32 v36, v36, v38
	v_mul_f32 v37, v37, v39
	v_mul_f32 v34, v34, v42
	v_mul_f32 v35, v35, v42
	v_cvt_pk_bf16_f32 v36, v36, v37
	v_fma_f32 v38, -v43, v44, 1.0
	v_fmac_f32_e32 v44, v38, v44
	v_div_scale_f32 v38, vcc, v47, v41, v47
	v_mul_f32_e32 v39, v38, v44
	v_fma_f32 v42, -v43, v39, v38
	v_fmac_f32_e32 v39, v42, v44
	v_div_scale_f32 v42, s[6:7], v40, v40, v46
	v_fma_f32 v38, -v43, v39, v38
	v_rcp_f32_e32 v43, v42
	v_div_fmas_f32 v38, v38, v44, v39
	v_div_fixup_f32 v39, v38, v41, v47
	v_mul_f32 v34, v2, v34
	v_mul_f32 v35, v3, v35
	v_fma_f32 v38, -v42, v43, 1.0
	v_fmac_f32_e32 v43, v38, v43
	v_div_scale_f32 v38, vcc, v46, v40, v46
	v_mul_f32_e32 v41, v38, v43
	v_fma_f32 v44, -v42, v41, v38
	v_fmac_f32_e32 v41, v44, v43
	v_fma_f32 v38, -v42, v41, v38
	v_div_fmas_f32 v38, v38, v43, v41
	v_div_fixup_f32 v38, v38, v40, v46
	s_waitcnt lgkmcnt(0)
	v_lshlrev_b32_e32 v46, 16, v68
	v_and_b32_e32 v44, 0xffff0000, v68
	v_mul_f32_e32 v42, 0xbfb8aa3b, v46
	v_mul_f32_e32 v43, 0xbfb8aa3b, v44
	v_exp_f32_e32 v42, v42
	v_exp_f32_e32 v43, v43
	v_mul_f32 v34, v38, v34
	v_mul_f32 v35, v39, v35
	v_lshlrev_b32_e32 v38, 16, v65
	v_lshlrev_b32_e32 v40, 16, v67
	v_and_b32_e32 v39, 0xffff0000, v65
	v_and_b32_e32 v41, 0xffff0000, v67
	v_add_f32 v38, v38, v40
	v_add_f32 v39, v39, v41
	v_add_f32 v40, v42, 1.0
	v_add_f32 v41, v43, 1.0
	v_cvt_pk_bf16_f32 v37, v34, v35
	v_div_scale_f32 v45, s[6:7], v41, v41, v44
	v_lshlrev_b64 v[34:35], 11, v[4:5]
	v_rcp_f32_e32 v49, v45
	v_lshl_add_u64 v[34:35], s[16:17], 0, v[34:35]
	v_lshl_add_u64 v[34:35], v[34:35], 0, v[6:7]
	s_mov_b32 s8, 0x4552000
	v_add_co_u32_e32 v34, vcc, s8, v34
	v_fma_f32 v50, -v45, v49, 1.0
	s_nop 0
	v_addc_co_u32_e32 v35, vcc, 0, v35, vcc
	v_fmac_f32_e32 v49, v50, v49
	v_div_scale_f32 v50, vcc, v44, v41, v44
	v_mul_f32_e32 v51, v50, v49
	v_fma_f32 v52, -v45, v51, v50
	v_fmac_f32_e32 v51, v52, v49
	v_fma_f32 v45, -v45, v51, v50
	v_div_scale_f32 v50, s[6:7], v40, v40, v46
	v_rcp_f32_e32 v52, v50
	v_div_fmas_f32 v45, v45, v49, v51
	v_lshlrev_b32_e32 v47, 16, v69
	v_and_b32_e32 v48, 0xffff0000, v69
	v_div_fixup_f32 v41, v45, v41, v44
	v_fma_f32 v44, -v50, v52, 1.0
	v_fmac_f32_e32 v52, v44, v52
	v_mul_f32_e32 v44, 0xbfb8aa3b, v47
	v_mul_f32_e32 v45, 0xbfb8aa3b, v48
	v_exp_f32_e32 v44, v44
	v_exp_f32_e32 v45, v45
	v_div_scale_f32 v49, vcc, v46, v40, v46
	v_mul_f32_e32 v51, v49, v52
	v_fma_f32 v53, -v50, v51, v49
	v_fmac_f32_e32 v51, v53, v52
	v_add_f32 v44, v44, 1.0
	v_add_f32 v45, v45, 1.0
	v_fma_f32 v49, -v50, v51, v49
	v_div_scale_f32 v50, s[6:7], v45, v45, v48
	v_rcp_f32_e32 v53, v50
	v_div_fmas_f32 v49, v49, v52, v51
	v_div_fixup_f32 v40, v49, v40, v46
	v_lshlrev_b32_e32 v54, 16, v28
	v_fma_f32 v46, -v50, v53, 1.0
	v_fmac_f32_e32 v53, v46, v53
	v_div_scale_f32 v46, vcc, v48, v45, v48
	v_mul_f32_e32 v49, v46, v53
	v_fma_f32 v51, -v50, v49, v46
	v_fmac_f32_e32 v49, v51, v53
	v_fma_f32 v46, -v50, v49, v46
	v_div_scale_f32 v50, s[6:7], v44, v44, v47
	v_rcp_f32_e32 v51, v50
	v_div_fmas_f32 v46, v46, v53, v49
	v_div_fixup_f32 v45, v46, v45, v48
	v_and_b32_e32 v55, 0xffff0000, v28
	v_fma_f32 v46, -v50, v51, 1.0
	v_fmac_f32_e32 v51, v46, v51
	v_div_scale_f32 v46, vcc, v47, v44, v47
	v_mul_f32_e32 v28, 0xbfb8aa3b, v54
	v_mul_f32_e32 v48, v46, v51
	v_exp_f32_e32 v52, v28
	v_mul_f32_e32 v28, 0xbfb8aa3b, v55
	v_fma_f32 v49, -v50, v48, v46
	v_exp_f32_e32 v53, v28
	v_fmac_f32_e32 v48, v49, v51
	v_fma_f32 v46, -v50, v48, v46
	v_div_fmas_f32 v46, v46, v51, v48
	v_lshlrev_b32_e32 v48, 16, v30
	v_lshlrev_b32_e32 v50, 16, v32
	v_and_b32_e32 v49, 0xffff0000, v30
	v_and_b32_e32 v51, 0xffff0000, v32
	v_lshlrev_b32_e32 v30, 16, v31
	v_lshlrev_b32_e32 v32, 16, v33
	v_and_b32_e32 v31, 0xffff0000, v31
	v_and_b32_e32 v33, 0xffff0000, v33
	v_add_f32 v30, v30, v32
	v_add_f32 v31, v31, v33
	v_add_f32 v32, v52, 1.0
	v_add_f32 v33, v53, 1.0
	flat_store_dwordx2 v[34:35], v[36:37] offset:1024 sc1
	v_div_scale_f32 v52, s[6:7], v33, v33, v55
	v_rcp_f32_e32 v53, v52
	v_lshlrev_b32_e32 v34, 16, v64
	v_lshlrev_b32_e32 v36, 16, v66
	v_and_b32_e32 v35, 0xffff0000, v64
	v_fma_f32 v58, -v52, v53, 1.0
	v_fmac_f32_e32 v53, v58, v53
	v_div_scale_f32 v58, vcc, v55, v33, v55
	v_mul_f32_e32 v59, v58, v53
	v_fma_f32 v60, -v52, v59, v58
	v_fmac_f32_e32 v59, v60, v53
	v_fma_f32 v52, -v52, v59, v58
	v_div_scale_f32 v58, s[6:7], v32, v32, v54
	v_rcp_f32_e32 v60, v58
	v_div_fmas_f32 v52, v52, v53, v59
	v_div_fixup_f32 v33, v52, v33, v55
	v_and_b32_e32 v37, 0xffff0000, v66
	v_fma_f32 v52, -v58, v60, 1.0
	v_fmac_f32_e32 v60, v52, v60
	v_div_scale_f32 v52, vcc, v54, v32, v54
	v_mul_f32_e32 v55, v52, v60
	v_add_f32 v34, v34, v36
	v_add_f32 v35, v35, v37
	v_add_f32 v48, v48, v50
	v_add_f32 v49, v49, v51
	v_fma_f32 v53, -v58, v55, v52
	v_mul_f32 v36, v34, v34
	v_mul_f32 v37, v35, v35
	v_mul_f32 v50, v48, v48
	v_mul_f32 v51, v49, v49
	v_fmac_f32_e32 v55, v53, v60
	v_mul_f32 v42, v38, v38
	v_mul_f32 v43, v39, v39
	v_lshlrev_b32_e32 v56, 16, v29
	v_and_b32_e32 v57, 0xffff0000, v29
	v_mul_f32 v28, v30, v30
	v_mul_f32 v29, v31, v31
	v_fma_f32 v58, -v58, v55, v52
	v_mov_b32_e32 v52, v50
	v_mov_b32_e32 v53, v36
	v_mov_b32_e32 v36, v51
	v_add_f32 v36, v52, v36
	v_add_f32 v37, v53, v37
	v_mov_b32_e32 v50, v28
	v_mov_b32_e32 v51, v42
	v_add_f32 v36, v36, v50
	v_add_f32 v37, v37, v51
	v_mov_b32_e32 v42, v29
	v_add_f32 v28, v42, v36
	v_add_f32 v29, v43, v37
	s_mov_b32 s6, 0x358637bd
	v_div_fixup_f32 v44, v46, v44, v47
	v_mov_b32_dpp v37, v29 quad_perm:[1,0,3,2] row_mask:0xf bank_mask:0xf bound_ctrl:1
	v_mov_b32_dpp v36, v28 quad_perm:[1,0,3,2] row_mask:0xf bank_mask:0xf bound_ctrl:1
	v_add_f32 v28, v28, v36
	v_add_f32 v29, v29, v37
	v_lshlrev_b64 v[46:47], 11, v[14:15]
	v_lshl_add_u64 v[46:47], s[16:17], 0, v[46:47]
	v_mov_b32_dpp v37, v29 quad_perm:[2,3,0,1] row_mask:0xf bank_mask:0xf bound_ctrl:1
	v_mov_b32_dpp v36, v28 quad_perm:[2,3,0,1] row_mask:0xf bank_mask:0xf bound_ctrl:1
	v_add_f32 v28, v28, v36
	v_add_f32 v29, v29, v37
	v_lshl_add_u64 v[46:47], v[46:47], 0, v[6:7]
	s_nop 0
	v_mov_b32_dpp v37, v29 row_half_mirror row_mask:0xf bank_mask:0xf bound_ctrl:1
	v_mov_b32_dpp v36, v28 row_half_mirror row_mask:0xf bank_mask:0xf bound_ctrl:1
	v_add_f32 v28, v28, v36
	v_add_f32 v29, v29, v37
	s_nop 1
	v_mov_b32_dpp v37, v29 row_mirror row_mask:0xf bank_mask:0xf bound_ctrl:1
	v_mov_b32_dpp v36, v28 row_mirror row_mask:0xf bank_mask:0xf bound_ctrl:1
	v_add_f32 v36, v28, v36
	v_add_f32 v37, v29, v37
	v_mov_b64_e32 v[28:29], s[6:7]
	v_fma_f32 v36, v36, s12, v28
	v_fma_f32 v37, v37, s12, v28
	s_nop 0
	v_mul_f32_e32 v42, 0x4b800000, v37
	v_cmp_gt_f32_e64 s[6:7], s13, v37
	s_nop 1
	v_cndmask_b32_e64 v37, v37, v42, s[6:7]
	v_rsq_f32_e32 v37, v37
	v_div_fmas_f32 v42, v58, v60, v55
	v_div_fixup_f32 v32, v42, v32, v54
	v_cmp_gt_f32_e32 vcc, s13, v36
	v_mul_f32_e32 v42, 0x45800000, v37
	v_cndmask_b32_e64 v42, v37, v42, s[6:7]
	v_mul_f32 v34, v34, v42
	v_mul_f32 v35, v35, v42
	v_mul_f32 v38, v38, v42
	v_mul_f32 v39, v39, v42
	v_mul_f32 v34, v0, v34
	v_mul_f32 v35, v1, v35
	v_mul_f32 v38, v2, v38
	v_mul_f32 v39, v3, v39
	v_mul_f32_e32 v37, 0x4b800000, v36
	v_mul_f32 v34, v40, v34
	v_mul_f32 v35, v41, v35
	v_mul_f32 v38, v44, v38
	v_mul_f32 v39, v45, v39
	v_cndmask_b32_e32 v36, v36, v37, vcc
	v_cvt_pk_bf16_f32 v34, v34, v35
	v_cvt_pk_bf16_f32 v35, v38, v39
	v_rsq_f32_e32 v38, v36
	v_add_co_u32_e64 v36, s[6:7], s8, v46
	v_lshlrev_b32_e32 v44, 16, v16
	s_nop 0
	v_addc_co_u32_e64 v37, s[6:7], 0, v47, s[6:7]
	flat_store_dwordx2 v[36:37], v[34:35] offset:1024 sc1
	v_mul_f32_e32 v34, 0xbfb8aa3b, v56
	v_mul_f32_e32 v35, 0xbfb8aa3b, v57
	v_exp_f32_e32 v34, v34
	v_exp_f32_e32 v35, v35
	v_mul_f32_e32 v36, 0x45800000, v38
	v_cndmask_b32_e32 v36, v38, v36, vcc
	v_mul_f32 v38, v48, v36
	v_mul_f32 v39, v49, v36
	v_add_f32 v34, v34, 1.0
	v_add_f32 v35, v35, 1.0
	v_mul_f32 v38, v0, v38
	v_mul_f32 v39, v1, v39
	v_div_scale_f32 v37, s[6:7], v35, v35, v57
	v_rcp_f32_e32 v40, v37
	v_mul_f32 v30, v30, v36
	v_mul_f32 v31, v31, v36
	v_mul_f32 v32, v32, v38
	v_mul_f32 v33, v33, v39
	v_mul_f32 v30, v2, v30
	v_mul_f32 v31, v3, v31
	v_fma_f32 v36, -v37, v40, 1.0
	v_fmac_f32_e32 v40, v36, v40
	v_div_scale_f32 v36, vcc, v57, v35, v57
	v_mul_f32_e32 v38, v36, v40
	v_fma_f32 v39, -v37, v38, v36
	v_fmac_f32_e32 v38, v39, v40
	v_fma_f32 v36, -v37, v38, v36
	v_div_scale_f32 v37, s[6:7], v34, v34, v56
	v_rcp_f32_e32 v39, v37
	v_div_fmas_f32 v36, v36, v40, v38
	v_div_fixup_f32 v35, v36, v35, v57
	v_cvt_pk_bf16_f32 v32, v32, v33
	v_fma_f32 v36, -v37, v39, 1.0
	v_fmac_f32_e32 v39, v36, v39
	v_div_scale_f32 v36, vcc, v56, v34, v56
	v_mul_f32_e32 v38, v36, v39
	v_fma_f32 v40, -v37, v38, v36
	v_fmac_f32_e32 v38, v40, v39
	v_fma_f32 v36, -v37, v38, v36
	v_div_fmas_f32 v36, v36, v39, v38
	v_div_fixup_f32 v34, v36, v34, v56
	v_mul_f32 v30, v34, v30
	v_mul_f32 v31, v35, v31
	v_lshlrev_b32_e32 v36, 16, v22
	v_cvt_pk_bf16_f32 v33, v30, v31
	v_lshlrev_b64 v[30:31], 11, v[12:13]
	v_and_b32_e32 v37, 0xffff0000, v22
	v_mul_f32_e32 v22, 0xbfb8aa3b, v36
	v_lshl_add_u64 v[30:31], s[16:17], 0, v[30:31]
	v_exp_f32_e32 v34, v22
	v_mul_f32_e32 v22, 0xbfb8aa3b, v37
	v_lshl_add_u64 v[30:31], v[30:31], 0, v[6:7]
	v_exp_f32_e32 v35, v22
	v_add_co_u32_e32 v30, vcc, s8, v30
	v_lshlrev_b32_e32 v38, 16, v23
	s_nop 0
	v_addc_co_u32_e32 v31, vcc, 0, v31, vcc
	flat_store_dwordx2 v[30:31], v[32:33] offset:1024 sc1
	v_lshlrev_b32_e32 v30, 16, v24
	v_lshlrev_b32_e32 v32, 16, v26
	v_and_b32_e32 v31, 0xffff0000, v24
	v_and_b32_e32 v33, 0xffff0000, v26
	v_lshlrev_b32_e32 v24, 16, v25
	v_lshlrev_b32_e32 v26, 16, v27
	v_and_b32_e32 v25, 0xffff0000, v25
	v_and_b32_e32 v27, 0xffff0000, v27
	v_and_b32_e32 v39, 0xffff0000, v23
	v_add_f32 v22, v24, v26
	v_add_f32 v23, v25, v27
	v_add_f32 v24, v34, 1.0
	v_add_f32 v25, v35, 1.0
	v_and_b32_e32 v45, 0xffff0000, v16
	v_div_scale_f32 v34, s[6:7], v25, v25, v37
	v_rcp_f32_e32 v35, v34
	v_mul_f32_e32 v16, 0xbfb8aa3b, v44
	v_lshlrev_b32_e32 v46, 16, v17
	v_and_b32_e32 v47, 0xffff0000, v17
	v_fma_f32 v40, -v34, v35, 1.0
	v_fmac_f32_e32 v35, v40, v35
	v_div_scale_f32 v40, vcc, v37, v25, v37
	v_mul_f32_e32 v41, v40, v35
	v_fma_f32 v42, -v34, v41, v40
	v_fmac_f32_e32 v41, v42, v35
	v_fma_f32 v34, -v34, v41, v40
	v_div_scale_f32 v40, s[6:7], v24, v24, v36
	v_rcp_f32_e32 v42, v40
	v_div_fmas_f32 v34, v34, v35, v41
	v_div_fixup_f32 v25, v34, v25, v37
	v_mul_f32_e32 v35, 0xbfb8aa3b, v39
	v_fma_f32 v34, -v40, v42, 1.0
	v_fmac_f32_e32 v42, v34, v42
	v_mul_f32_e32 v34, 0xbfb8aa3b, v38
	v_exp_f32_e32 v34, v34
	v_exp_f32_e32 v35, v35
	v_div_scale_f32 v37, vcc, v36, v24, v36
	v_mul_f32_e32 v41, v37, v42
	v_fma_f32 v43, -v40, v41, v37
	v_fmac_f32_e32 v41, v43, v42
	v_add_f32 v34, v34, 1.0
	v_add_f32 v35, v35, 1.0
	v_fma_f32 v37, -v40, v41, v37
	v_div_scale_f32 v40, s[6:7], v35, v35, v39
	v_rcp_f32_e32 v43, v40
	v_div_fmas_f32 v37, v37, v42, v41
	v_div_fixup_f32 v24, v37, v24, v36
	v_exp_f32_e32 v42, v16
	v_fma_f32 v36, -v40, v43, 1.0
	v_fmac_f32_e32 v43, v36, v43
	v_div_scale_f32 v36, vcc, v39, v35, v39
	v_mul_f32_e32 v37, v36, v43
	v_fma_f32 v41, -v40, v37, v36
	v_fmac_f32_e32 v37, v41, v43
	v_fma_f32 v36, -v40, v37, v36
	v_div_scale_f32 v40, s[6:7], v34, v34, v38
	v_rcp_f32_e32 v41, v40
	v_div_fmas_f32 v36, v36, v43, v37
	v_div_fixup_f32 v35, v36, v35, v39
	v_mul_f32_e32 v16, 0xbfb8aa3b, v45
	v_fma_f32 v36, -v40, v41, 1.0
	v_fmac_f32_e32 v41, v36, v41
	v_div_scale_f32 v36, vcc, v38, v34, v38
	v_mul_f32_e32 v37, v36, v41
	v_fma_f32 v39, -v40, v37, v36
	v_fmac_f32_e32 v37, v39, v41
	v_exp_f32_e32 v43, v16
	v_fma_f32 v36, -v40, v37, v36
	v_div_fmas_f32 v36, v36, v41, v37
	v_div_fixup_f32 v34, v36, v34, v38
	v_lshlrev_b32_e32 v38, 16, v18
	v_lshlrev_b32_e32 v40, 16, v20
	v_and_b32_e32 v39, 0xffff0000, v18
	v_and_b32_e32 v41, 0xffff0000, v20
	v_lshlrev_b32_e32 v18, 16, v19
	v_lshlrev_b32_e32 v20, 16, v21
	v_and_b32_e32 v19, 0xffff0000, v19
	v_and_b32_e32 v21, 0xffff0000, v21
	v_add_f32 v16, v18, v20
	v_add_f32 v17, v19, v21
	v_add_f32 v18, v42, 1.0
	v_add_f32 v19, v43, 1.0
	v_add_f32 v30, v30, v32
	v_add_f32 v31, v31, v33
	v_div_scale_f32 v42, s[6:7], v19, v19, v45
	v_rcp_f32_e32 v43, v42
	v_add_f32 v38, v38, v40
	v_add_f32 v39, v39, v41
	v_mul_f32 v32, v30, v30
	v_mul_f32 v33, v31, v31
	v_mul_f32 v40, v38, v38
	v_mul_f32 v41, v39, v39
	v_fma_f32 v48, -v42, v43, 1.0
	v_fmac_f32_e32 v43, v48, v43
	v_div_scale_f32 v48, vcc, v45, v19, v45
	v_mul_f32_e32 v49, v48, v43
	v_fma_f32 v50, -v42, v49, v48
	v_fmac_f32_e32 v49, v50, v43
	v_fma_f32 v42, -v42, v49, v48
	v_div_scale_f32 v48, s[6:7], v18, v18, v44
	v_rcp_f32_e32 v50, v48
	v_div_fmas_f32 v42, v42, v43, v49
	v_div_fixup_f32 v19, v42, v19, v45
	v_mul_f32 v26, v22, v22
	v_mul_f32 v27, v23, v23
	v_fma_f32 v42, -v48, v50, 1.0
	v_fmac_f32_e32 v50, v42, v50
	v_div_scale_f32 v42, vcc, v44, v18, v44
	v_mul_f32_e32 v45, v42, v50
	v_fma_f32 v43, -v48, v45, v42
	v_fmac_f32_e32 v45, v43, v50
	v_mul_f32 v20, v16, v16
	v_mul_f32 v21, v17, v17
	v_fma_f32 v48, -v48, v45, v42
	v_mov_b32_e32 v42, v40
	v_mov_b32_e32 v43, v32
	v_mov_b32_e32 v32, v41
	v_add_f32 v32, v42, v32
	v_add_f32 v33, v43, v33
	v_mov_b32_e32 v40, v20
	v_mov_b32_e32 v41, v26
	v_add_f32 v32, v32, v40
	v_add_f32 v33, v33, v41
	v_mov_b32_e32 v26, v21
	v_add_f32 v20, v26, v32
	v_add_f32 v21, v27, v33
	v_lshlrev_b64 v[36:37], 11, v[10:11]
	v_lshl_add_u64 v[36:37], s[16:17], 0, v[36:37]
	v_mov_b32_dpp v27, v21 quad_perm:[1,0,3,2] row_mask:0xf bank_mask:0xf bound_ctrl:1
	v_mov_b32_dpp v26, v20 quad_perm:[1,0,3,2] row_mask:0xf bank_mask:0xf bound_ctrl:1
	v_add_f32 v20, v20, v26
	v_add_f32 v21, v21, v27
	v_lshl_add_u64 v[36:37], v[36:37], 0, v[6:7]
	s_nop 0
	v_mov_b32_dpp v27, v21 quad_perm:[2,3,0,1] row_mask:0xf bank_mask:0xf bound_ctrl:1
	v_mov_b32_dpp v26, v20 quad_perm:[2,3,0,1] row_mask:0xf bank_mask:0xf bound_ctrl:1
	v_add_f32 v20, v20, v26
	v_add_f32 v21, v21, v27
	s_nop 1
	v_mov_b32_dpp v27, v21 row_half_mirror row_mask:0xf bank_mask:0xf bound_ctrl:1
	v_mov_b32_dpp v26, v20 row_half_mirror row_mask:0xf bank_mask:0xf bound_ctrl:1
	v_add_f32 v20, v20, v26
	v_add_f32 v21, v21, v27
	s_nop 1
	v_mov_b32_dpp v27, v21 row_mirror row_mask:0xf bank_mask:0xf bound_ctrl:1
	v_mov_b32_dpp v26, v20 row_mirror row_mask:0xf bank_mask:0xf bound_ctrl:1
	v_add_f32 v20, v20, v26
	v_add_f32 v21, v21, v27
	s_nop 0
	v_fma_f32 v20, v20, s12, v28
	v_fma_f32 v21, v21, s12, v28
	s_nop 0
	v_mul_f32_e32 v26, 0x4b800000, v21
	v_cmp_gt_f32_e64 s[6:7], s13, v21
	s_nop 1
	v_cndmask_b32_e64 v21, v21, v26, s[6:7]
	v_rsq_f32_e32 v21, v21
	v_div_fmas_f32 v26, v48, v50, v45
	v_div_fixup_f32 v18, v26, v18, v44
	v_cmp_gt_f32_e32 vcc, s13, v20
	v_mul_f32_e32 v26, 0x45800000, v21
	v_cndmask_b32_e64 v26, v21, v26, s[6:7]
	v_mul_f32 v28, v30, v26
	v_mul_f32 v29, v31, v26
	v_mul_f32 v22, v22, v26
	v_mul_f32 v23, v23, v26
	v_mul_f32 v28, v0, v28
	v_mul_f32 v29, v1, v29
	v_mul_f32 v22, v2, v22
	v_mul_f32 v23, v3, v23
	v_mul_f32_e32 v21, 0x4b800000, v20
	v_mul_f32 v24, v24, v28
	v_mul_f32 v25, v25, v29
	v_mul_f32 v22, v34, v22
	v_mul_f32 v23, v35, v23
	v_cndmask_b32_e32 v20, v20, v21, vcc
	v_cvt_pk_bf16_f32 v24, v24, v25
	v_cvt_pk_bf16_f32 v25, v22, v23
	v_rsq_f32_e32 v22, v20
	v_add_co_u32_e64 v20, s[6:7], s8, v36
	v_mul_f32_e32 v23, 0x45800000, v22
	s_nop 0
	v_addc_co_u32_e64 v21, s[6:7], 0, v37, s[6:7]
	flat_store_dwordx2 v[20:21], v[24:25] offset:1024 sc1
	v_mul_f32_e32 v20, 0xbfb8aa3b, v46
	v_mul_f32_e32 v21, 0xbfb8aa3b, v47
	v_exp_f32_e32 v20, v20
	v_exp_f32_e32 v21, v21
	v_cndmask_b32_e32 v22, v22, v23, vcc
	v_mul_f32 v24, v38, v22
	v_mul_f32 v25, v39, v22
	v_add_f32 v20, v20, 1.0
	v_add_f32 v21, v21, 1.0
	s_nop 0
	v_div_scale_f32 v23, s[6:7], v21, v21, v47
	v_mul_f32 v0, v0, v24
	v_mul_f32 v1, v1, v25
	v_rcp_f32_e32 v24, v23
	v_mul_f32 v16, v16, v22
	v_mul_f32 v17, v17, v22
	v_mul_f32 v0, v18, v0
	v_mul_f32 v1, v19, v1
	v_mul_f32 v2, v2, v16
	v_mul_f32 v3, v3, v17
	v_fma_f32 v16, -v23, v24, 1.0
	v_fmac_f32_e32 v24, v16, v24
	v_div_scale_f32 v16, vcc, v47, v21, v47
	v_mul_f32_e32 v17, v16, v24
	v_fma_f32 v18, -v23, v17, v16
	v_fmac_f32_e32 v17, v18, v24
	v_div_scale_f32 v18, s[6:7], v20, v20, v46
	v_rcp_f32_e32 v19, v18
	v_fma_f32 v16, -v23, v17, v16
	v_div_fmas_f32 v16, v16, v24, v17
	v_div_fixup_f32 v17, v16, v21, v47
	v_fma_f32 v16, -v18, v19, 1.0
	v_fmac_f32_e32 v19, v16, v19
	v_div_scale_f32 v16, vcc, v46, v20, v46
	v_mul_f32_e32 v21, v16, v19
	v_fma_f32 v22, -v18, v21, v16
	v_fmac_f32_e32 v21, v22, v19
	v_fma_f32 v16, -v18, v21, v16
	v_div_fmas_f32 v16, v16, v19, v21
	v_div_fixup_f32 v16, v16, v20, v46
	v_mul_f32 v2, v16, v2
	v_mul_f32 v3, v17, v3
	v_cvt_pk_bf16_f32 v0, v0, v1
	v_cvt_pk_bf16_f32 v1, v2, v3
	v_lshlrev_b64 v[2:3], 11, v[8:9]
	v_lshl_add_u64 v[2:3], s[16:17], 0, v[2:3]
	v_lshl_add_u64 v[2:3], v[2:3], 0, v[6:7]
	v_add_co_u32_e32 v2, vcc, 0x4552000, v2
	s_nop 1
	v_addc_co_u32_e32 v3, vcc, 0, v3, vcc
	flat_store_dwordx2 v[2:3], v[0:1] offset:1024 sc1
	s_waitcnt vmcnt(0)
	s_and_saveexec_b64 s[6:7], s[4:5]
	s_cbranch_execz .LBB0_1427
	v_alignbit_b32 v0, v15, v14, 8
	v_alignbit_b32 v1, v5, v4, 8
	v_cmp_eq_u32_e32 vcc, v0, v1
	v_alignbit_b32 v2, v13, v12, 8
	v_alignbit_b32 v3, v9, v8, 8
	v_cndmask_b32_e64 v0, 1, 2, vcc
	v_cmp_eq_u32_e32 vcc, v2, v1
	v_alignbit_b32 v2, v11, v10, 8
	s_mov_b64 s[4:5], s[10:11]
	v_addc_co_u32_e32 v0, vcc, 0, v0, vcc
	v_cmp_eq_u32_e32 vcc, v2, v1
	s_nop 1
	v_cndmask_b32_e64 v2, 0, 1, vcc
	v_cmp_eq_u32_e32 vcc, v3, v1
	s_nop 1
	v_addc_co_u32_e32 v2, vcc, v0, v2, vcc
	v_lshlrev_b32_e32 v0, 6, v1
	v_ashrrev_i32_e32 v1, 31, v0
	v_lshl_add_u64 v[4:5], v[0:1], 2, s[18:19]
	flat_atomic_add v[4:5], v2
	v_cmp_gt_u32_e32 vcc, 5, v2
	s_and_saveexec_b64 s[8:9], vcc
	v_sub_u32_e32 v1, 5, v2
	s_or_b64 s[4:5], s[10:11], exec
	s_or_b64 exec, exec, s[8:9]
	s_andn2_b64 s[8:9], s[10:11], exec
	s_and_b64 s[4:5], s[4:5], exec
	s_or_b64 s[10:11], s[8:9], s[4:5]

.LBB0_1683:
	v_ashrrev_i32_e32 v75, 31, v74
	v_lshlrev_b64 v[0:1], 12, v[74:75]
	v_lshl_add_u64 v[102:103], s[18:19], 0, v[0:1]
	v_add_u32_e32 v0, 0xfffff000, v74
	v_lshrrev_b32_e32 v0, 11, v0
	v_add_u32_e32 v0, 1, v0
	v_cmp_lt_i32_e32 vcc, s33, v74
	v_lshl_add_u64 v[8:9], v[102:103], 0, v[76:77]
	flat_load_dwordx4 v[10:13], v[8:9] offset:2048
	flat_load_dwordx4 v[40:43], v[8:9] offset:3072
	v_cndmask_b32_e32 v83, 0, v0, vcc
	v_mad_u64_u32 v[0:1], s[6:7], v83, s36, v[66:67]
	flat_load_dwordx4 v[44:47], v[0:1]
	global_load_dwordx4 v[48:51], v[64:65], off
	global_load_dwordx4 v[52:55], v[64:65], off offset:16
	flat_load_dwordx4 v[90:93], v[0:1] offset:16
	flat_load_dwordx4 v[94:97], v[0:1] offset:2048
	global_load_dwordx4 v[98:101], v[64:65], off offset:2048
	global_load_dwordx4 v[104:107], v[64:65], off offset:2064
	flat_load_dwordx4 v[118:121], v[0:1] offset:2064
	v_lshlrev_b64 v[0:1], 11, v[74:75]
	v_lshl_add_u64 v[0:1], v[62:63], 0, v[0:1]
	flat_load_dwordx4 v[122:125], v[0:1]
	flat_load_dwordx4 v[126:129], v[0:1] offset:1024
	v_add_u32_e32 v0, 1, v74
	v_ashrrev_i32_e32 v1, 31, v0
	v_lshlrev_b64 v[6:7], 12, v[0:1]
	v_lshlrev_b64 v[0:1], 11, v[0:1]
	v_lshl_add_u64 v[0:1], v[62:63], 0, v[0:1]
	flat_load_dwordx4 v[130:133], v[0:1]
	flat_load_dwordx4 v[134:137], v[0:1] offset:1024
	v_add_u32_e32 v2, 2, v74
	v_add_u32_e32 v4, 3, v74
	v_ashrrev_i32_e32 v3, 31, v2
	v_ashrrev_i32_e32 v5, 31, v4
	v_lshlrev_b64 v[14:15], 12, v[2:3]
	v_lshlrev_b64 v[2:3], 11, v[2:3]
	v_lshlrev_b64 v[16:17], 12, v[4:5]
	v_lshlrev_b64 v[4:5], 11, v[4:5]
	v_lshl_add_u64 v[112:113], s[18:19], 0, v[6:7]
	v_lshl_add_u64 v[110:111], s[18:19], 0, v[14:15]
	v_lshl_add_u64 v[2:3], v[62:63], 0, v[2:3]
	v_lshl_add_u64 v[88:89], v[72:73], 0, v[16:17]
	v_lshl_add_u64 v[14:15], v[62:63], 0, v[4:5]
	v_lshl_add_u64 v[114:115], v[112:113], 0, v[76:77]
	v_lshl_add_u64 v[116:117], v[110:111], 0, v[76:77]
	flat_load_dwordx4 v[142:145], v[2:3]
	flat_load_dwordx4 v[150:153], v[2:3] offset:1024
	flat_load_dwordx4 v[20:23], v[88:89] offset:2048
	flat_load_dwordx4 v[16:19], v[88:89] offset:3072
	flat_load_dwordx4 v[4:7], v[14:15]
	s_nop 0
	flat_load_dwordx4 v[0:3], v[14:15] offset:1024
	flat_load_dwordx4 v[36:39], v[114:115] offset:2048
	flat_load_dwordx4 v[32:35], v[114:115] offset:3072
	flat_load_dwordx4 v[28:31], v[116:117] offset:2048
	flat_load_dwordx4 v[24:27], v[116:117] offset:3072
	s_waitcnt vmcnt(0) lgkmcnt(0)
	v_lshlrev_b32_e32 v14, 16, v10
	v_lshlrev_b32_e32 v140, 16, v40
	v_and_b32_e32 v141, 0xffff0000, v40
	v_lshlrev_b32_e32 v146, 16, v41
	v_and_b32_e32 v147, 0xffff0000, v41
	v_mul_f32 v40, v50, v46
	v_mul_f32 v41, v51, v47
	v_lshlrev_b32_e32 v148, 16, v42
	v_and_b32_e32 v149, 0xffff0000, v42
	v_lshlrev_b32_e32 v154, 16, v43
	v_and_b32_e32 v155, 0xffff0000, v43
	v_mul_f32 v42, v48, v44
	v_mul_f32 v43, v49, v45
	v_mul_f32 v48, v100, v96
	v_mul_f32 v49, v101, v97
	v_mul_f32 v96, v78, v40
	v_mul_f32 v97, v79, v41
	v_lshlrev_b32_e32 v40, 16, v122
	v_and_b32_e32 v41, 0xffff0000, v122
	v_mul_f32 v44, v54, v92
	v_mul_f32 v45, v55, v93
	v_mul_f32 v46, v52, v90
	v_mul_f32 v47, v53, v91
	v_mul_f32 v100, v70, v42
	v_mul_f32 v101, v71, v43
	v_lshlrev_b32_e32 v42, 16, v123
	v_and_b32_e32 v43, 0xffff0000, v123
	v_mul_f32 v156, v40, v40
	v_mul_f32 v157, v41, v41
	v_mul_f32 v50, v98, v94
	v_mul_f32 v51, v99, v95
	v_mul_f32 v54, v104, v118
	v_mul_f32 v55, v105, v119
	v_mul_f32 v92, v78, v44
	v_mul_f32 v93, v79, v45
	v_mul_f32 v98, v70, v46
	v_mul_f32 v99, v71, v47
	v_lshlrev_b32_e32 v44, 16, v124
	v_and_b32_e32 v45, 0xffff0000, v124
	v_lshlrev_b32_e32 v46, 16, v125
	v_and_b32_e32 v47, 0xffff0000, v125
	v_lshlrev_b32_e32 v118, 16, v128
	v_and_b32_e32 v119, 0xffff0000, v128
	v_lshlrev_b32_e32 v124, 16, v129
	v_and_b32_e32 v125, 0xffff0000, v129
	v_mul_f32 v128, v42, v42
	v_mul_f32 v129, v43, v43
	v_add_f32_e32 v56, v156, v157
	v_add_f32_e32 v56, v128, v56
	v_mul_f32 v90, v78, v48
	v_mul_f32 v91, v79, v49
	v_mul_f32 v94, v70, v50
	v_mul_f32 v95, v71, v51
	v_lshlrev_b32_e32 v48, 16, v126
	v_and_b32_e32 v49, 0xffff0000, v126
	v_lshlrev_b32_e32 v50, 16, v127
	v_and_b32_e32 v51, 0xffff0000, v127
	v_mul_f32 v126, v44, v44
	v_mul_f32 v127, v45, v45
	v_add_f32_e32 v56, v129, v56
	v_add_f32_e32 v56, v126, v56
	v_mul_f32 v122, v46, v46
	v_mul_f32 v123, v47, v47
	v_add_f32_e32 v56, v127, v56
	v_add_f32_e32 v56, v122, v56
	v_mul_f32 v52, v106, v120
	v_mul_f32 v53, v107, v121
	v_mul_f32 v120, v48, v48
	v_mul_f32 v121, v49, v49
	v_add_f32_e32 v56, v123, v56
	v_add_f32_e32 v56, v120, v56
	v_mul_f32 v108, v50, v50
	v_mul_f32 v109, v51, v51
	v_add_f32_e32 v56, v121, v56
	v_add_f32_e32 v56, v108, v56
	v_mul_f32 v106, v118, v118
	v_mul_f32 v107, v119, v119
	v_add_f32_e32 v56, v109, v56
	v_add_f32_e32 v56, v106, v56
	v_mul_f32 v104, v124, v124
	v_mul_f32 v105, v125, v125
	v_add_f32_e32 v56, v107, v56
	v_add_f32_e32 v56, v104, v56
	v_add_f32_e32 v56, v105, v56
	v_lshlrev_b32_e32 v104, 16, v130
	v_and_b32_e32 v105, 0xffff0000, v130
	v_add_f32_dpp v56, v56, v56 quad_perm:[1,0,3,2] row_mask:0xf bank_mask:0xf bound_ctrl:1
	v_lshlrev_b32_e32 v106, 16, v131
	v_and_b32_e32 v107, 0xffff0000, v131
	v_add_f32_dpp v56, v56, v56 quad_perm:[2,3,0,1] row_mask:0xf bank_mask:0xf bound_ctrl:1
	v_mul_f32 v168, v104, v104
	v_mul_f32 v169, v105, v105
	v_mul_f32 v156, v106, v106
	v_mul_f32 v157, v107, v107
	v_add_f32_dpp v56, v56, v56 row_half_mirror row_mask:0xf bank_mask:0xf bound_ctrl:1
	v_lshlrev_b32_e32 v108, 16, v132
	v_and_b32_e32 v109, 0xffff0000, v132
	v_add_f32_dpp v56, v56, v56 row_mirror row_mask:0xf bank_mask:0xf bound_ctrl:1
	v_mov_b32_e32 v75, v56
	s_nop 1
	v_permlane16_swap_b32_e32 v56, v75
	v_add_f32_e32 v121, v56, v75
	v_add_f32_e32 v56, v168, v169
	v_add_f32_e32 v56, v156, v56
	v_lshlrev_b32_e32 v164, 16, v136
	v_and_b32_e32 v165, 0xffff0000, v136
	v_lshlrev_b32_e32 v166, 16, v137
	v_and_b32_e32 v167, 0xffff0000, v137
	v_mul_f32 v136, v108, v108
	v_mul_f32 v137, v109, v109
	v_add_f32_e32 v56, v157, v56
	v_lshlrev_b32_e32 v158, 16, v133
	v_and_b32_e32 v159, 0xffff0000, v133
	v_add_f32_e32 v56, v136, v56
	v_lshlrev_b32_e32 v160, 16, v134
	v_and_b32_e32 v161, 0xffff0000, v134
	v_lshlrev_b32_e32 v162, 16, v135
	v_and_b32_e32 v163, 0xffff0000, v135
	v_mul_f32 v134, v158, v158
	v_mul_f32 v135, v159, v159
	v_add_f32_e32 v56, v137, v56
	v_add_f32_e32 v56, v134, v56
	v_mul_f32 v132, v160, v160
	v_mul_f32 v133, v161, v161
	v_add_f32_e32 v56, v135, v56
	v_add_f32_e32 v56, v132, v56
	v_mul_f32 v130, v162, v162
	v_mul_f32 v131, v163, v163
	v_add_f32_e32 v56, v133, v56
	v_add_f32_e32 v56, v130, v56
	v_mul_f32 v128, v164, v164
	v_mul_f32 v129, v165, v165
	v_add_f32_e32 v56, v131, v56
	v_add_f32_e32 v56, v128, v56
	v_mul_f32 v126, v166, v166
	v_mul_f32 v127, v167, v167
	v_add_f32_e32 v56, v129, v56
	v_add_f32_e32 v56, v126, v56
	v_add_f32_e32 v56, v127, v56
	v_mov_b32_e32 v123, v121
	s_nop 1
	v_permlane32_swap_b32_e32 v121, v123
	v_add_f32_dpp v56, v56, v56 quad_perm:[1,0,3,2] row_mask:0xf bank_mask:0xf bound_ctrl:1
	v_and_b32_e32 v15, 0xffff0000, v10
	v_lshlrev_b32_e32 v10, 16, v11
	v_add_f32_dpp v56, v56, v56 quad_perm:[2,3,0,1] row_mask:0xf bank_mask:0xf bound_ctrl:1
	v_and_b32_e32 v11, 0xffff0000, v11
	v_lshlrev_b32_e32 v138, 16, v12
	v_add_f32_dpp v56, v56, v56 row_half_mirror row_mask:0xf bank_mask:0xf bound_ctrl:1
	v_and_b32_e32 v139, 0xffff0000, v12
	v_lshlrev_b32_e32 v12, 16, v13
	v_add_f32_dpp v56, v56, v56 row_mirror row_mask:0xf bank_mask:0xf bound_ctrl:1
	v_mov_b32_e32 v75, v56
	s_nop 1
	v_permlane16_swap_b32_e32 v56, v75
	v_add_f32_e32 v120, v56, v75
	v_mov_b32_e32 v122, v120
	s_nop 1
	v_permlane32_swap_b32_e32 v120, v122
	v_add_f32 v120, v120, v122
	v_add_f32 v121, v121, v123
	v_mul_f32 v122, v70, v54
	v_mul_f32 v123, v71, v55
	v_fma_f32 v168, v120, s24, v80
	v_fma_f32 v169, v121, s24, v80
	v_mul_f32 v120, v78, v52
	v_mul_f32 v121, v79, v53
	v_mul_f32_e32 v56, 0x4b800000, v169
	v_cmp_gt_f32_e32 vcc, s37, v169
	v_and_b32_e32 v13, 0xffff0000, v13
	v_lshlrev_b32_e32 v134, 16, v1
	v_cndmask_b32_e32 v56, v169, v56, vcc
	v_rsq_f32_e32 v56, v56
	v_and_b32_e32 v135, 0xffff0000, v1
	v_lshlrev_b32_e32 v136, 16, v2
	v_and_b32_e32 v137, 0xffff0000, v2
	v_mul_f32_e32 v52, 0x45800000, v56
	v_cndmask_b32_e32 v54, v56, v52, vcc
	v_mul_f32 v40, v54, v40
	v_mul_f32 v41, v54, v41
	v_fma_f32 v40, v100, v40, v14
	v_fma_f32 v41, v101, v41, v15
	v_mul_f32 v14, v54, v42
	v_mul_f32 v15, v54, v43
	v_fma_f32 v42, v96, v14, v10
	v_fma_f32 v43, v97, v15, v11
	v_mul_f32 v10, v54, v44
	v_mul_f32 v11, v54, v45
	v_fma_f32 v44, v98, v10, v138
	v_fma_f32 v45, v99, v11, v139
	v_mul_f32 v10, v54, v46
	v_mul_f32 v11, v54, v47
	v_fma_f32 v46, v92, v10, v12
	v_fma_f32 v47, v93, v11, v13
	v_mul_f32 v10, v54, v48
	v_mul_f32 v11, v54, v49
	v_fma_f32 v48, v94, v10, v140
	v_fma_f32 v49, v95, v11, v141
	v_mul_f32 v10, v54, v50
	v_mul_f32 v11, v54, v51
	v_fma_f32 v50, v90, v10, v146
	v_fma_f32 v51, v91, v11, v147
	v_mul_f32 v10, v54, v118
	v_mul_f32 v11, v54, v119
	v_lshlrev_b32_e32 v118, 16, v142
	v_and_b32_e32 v119, 0xffff0000, v142
	v_lshlrev_b32_e32 v140, 16, v143
	v_and_b32_e32 v141, 0xffff0000, v143
	v_mul_f32 v132, v118, v118
	v_mul_f32 v133, v119, v119
	v_mul_f32 v130, v140, v140
	v_mul_f32 v131, v141, v141
	v_add_f32_e32 v56, v132, v133
	v_lshlrev_b32_e32 v142, 16, v144
	v_and_b32_e32 v143, 0xffff0000, v144
	v_add_f32_e32 v56, v130, v56
	v_mul_f32 v128, v142, v142
	v_mul_f32 v129, v143, v143
	v_add_f32_e32 v56, v131, v56
	v_lshlrev_b32_e32 v144, 16, v145
	v_and_b32_e32 v145, 0xffff0000, v145
	v_add_f32_e32 v56, v128, v56
	v_mul_f32 v126, v144, v144
	v_mul_f32 v127, v145, v145
	v_add_f32_e32 v56, v129, v56
	v_lshlrev_b32_e32 v146, 16, v150
	v_and_b32_e32 v147, 0xffff0000, v150
	v_add_f32_e32 v56, v126, v56
	v_fma_f32 v52, v122, v10, v148
	v_fma_f32 v53, v123, v11, v149
	v_mul_f32 v10, v54, v124
	v_mul_f32 v11, v54, v125
	v_mul_f32 v124, v146, v146
	v_mul_f32 v125, v147, v147
	v_add_f32_e32 v56, v127, v56
	v_lshlrev_b32_e32 v148, 16, v151
	v_and_b32_e32 v149, 0xffff0000, v151
	v_add_f32_e32 v56, v124, v56
	v_mul_f32 v14, v148, v148
	v_mul_f32 v15, v149, v149
	v_add_f32_e32 v56, v125, v56
	v_lshlrev_b32_e32 v150, 16, v152
	v_and_b32_e32 v151, 0xffff0000, v152
	v_add_f32_e32 v14, v14, v56
	v_mul_f32 v12, v150, v150
	v_mul_f32 v13, v151, v151
	v_add_f32_e32 v14, v15, v14
	v_lshlrev_b32_e32 v152, 16, v153
	v_and_b32_e32 v153, 0xffff0000, v153
	v_add_f32_e32 v12, v12, v14
	v_fma_f32 v54, v120, v10, v154
	v_fma_f32 v55, v121, v11, v155
	v_mul_f32 v10, v152, v152
	v_mul_f32 v11, v153, v153
	v_add_f32_e32 v12, v13, v12
	v_add_f32_e32 v10, v10, v12
	v_add_f32_e32 v10, v11, v10
	v_lshlrev_b32_e32 v124, 16, v4
	v_and_b32_e32 v125, 0xffff0000, v4
	v_add_f32_dpp v10, v10, v10 quad_perm:[1,0,3,2] row_mask:0xf bank_mask:0xf bound_ctrl:1
	v_lshlrev_b32_e32 v126, 16, v5
	v_and_b32_e32 v127, 0xffff0000, v5
	v_add_f32_dpp v10, v10, v10 quad_perm:[2,3,0,1] row_mask:0xf bank_mask:0xf bound_ctrl:1
	v_mul_f32 v172, v124, v124
	v_mul_f32 v173, v125, v125
	v_mul_f32 v14, v126, v126
	v_mul_f32 v15, v127, v127
	v_add_f32_dpp v10, v10, v10 row_half_mirror row_mask:0xf bank_mask:0xf bound_ctrl:1
	v_add_f32_e32 v56, v172, v173
	v_lshlrev_b32_e32 v128, 16, v6
	v_add_f32_dpp v10, v10, v10 row_mirror row_mask:0xf bank_mask:0xf bound_ctrl:1
	v_and_b32_e32 v129, 0xffff0000, v6
	v_add_f32_e32 v14, v14, v56
	v_mov_b32_e32 v11, v10
	v_mul_f32 v12, v128, v128
	v_mul_f32 v13, v129, v129
	v_add_f32_e32 v14, v15, v14
	v_permlane16_swap_b32_e32 v10, v11
	v_lshlrev_b32_e32 v130, 16, v7
	v_and_b32_e32 v131, 0xffff0000, v7
	v_add_f32_e32 v12, v12, v14
	v_add_f32_e32 v155, v10, v11
	v_mul_f32 v10, v130, v130
	v_mul_f32 v11, v131, v131
	v_add_f32_e32 v12, v13, v12
	v_lshlrev_b32_e32 v132, 16, v0
	v_and_b32_e32 v133, 0xffff0000, v0
	v_add_f32_e32 v10, v10, v12
	v_mul_f32 v6, v132, v132
	v_mul_f32 v7, v133, v133
	v_add_f32_e32 v10, v11, v10
	v_add_f32_e32 v6, v6, v10
	v_mul_f32 v4, v134, v134
	v_mul_f32 v5, v135, v135
	v_add_f32_e32 v6, v7, v6
	v_add_f32_e32 v4, v4, v6
	v_lshlrev_b32_e32 v138, 16, v3
	v_and_b32_e32 v139, 0xffff0000, v3
	v_mul_f32 v2, v136, v136
	v_mul_f32 v3, v137, v137
	v_add_f32_e32 v4, v5, v4
	v_add_f32_e32 v2, v2, v4
	v_mul_f32 v0, v138, v138
	v_mul_f32 v1, v139, v139
	v_add_f32_e32 v2, v3, v2
	v_add_f32_e32 v0, v0, v2
	v_add_f32_e32 v0, v1, v0
	v_mov_b32_e32 v157, v155
	v_cmp_gt_f32_e64 s[6:7], s37, v168
	v_add_f32_dpp v0, v0, v0 quad_perm:[1,0,3,2] row_mask:0xf bank_mask:0xf bound_ctrl:1
	v_permlane32_swap_b32_e32 v155, v157
	s_nop 0
	v_add_f32_dpp v0, v0, v0 quad_perm:[2,3,0,1] row_mask:0xf bank_mask:0xf bound_ctrl:1
	s_and_b64 vcc, exec, s[22:23]
	s_nop 0
	v_add_f32_dpp v0, v0, v0 row_half_mirror row_mask:0xf bank_mask:0xf bound_ctrl:1
	s_nop 1
	v_add_f32_dpp v0, v0, v0 row_mirror row_mask:0xf bank_mask:0xf bound_ctrl:1
	v_mov_b32_e32 v1, v0
	s_nop 1
	v_permlane16_swap_b32_e32 v0, v1
	v_add_f32_e32 v154, v0, v1
	v_mov_b32_e32 v156, v154
	s_nop 1
	v_permlane32_swap_b32_e32 v154, v156
	s_cbranch_vccz .LBB0_1698
	v_cvt_pk_bf16_f32 v0, v40, v41
	v_cvt_pk_bf16_f32 v1, v42, v43
	v_cvt_pk_bf16_f32 v2, v44, v45
	v_cvt_pk_bf16_f32 v3, v46, v47
	v_cvt_pk_bf16_f32 v176, v48, v49
	v_cvt_pk_bf16_f32 v177, v50, v51
	v_cvt_pk_bf16_f32 v178, v52, v53
	v_cvt_pk_bf16_f32 v179, v54, v55
	flat_store_dwordx4 v[8:9], v[0:3] offset:2048
	v_lshlrev_b32_e32 v4, 16, v0
	v_and_b32_e32 v5, 0xffff0000, v0
	v_lshlrev_b32_e32 v6, 16, v1
	v_and_b32_e32 v7, 0xffff0000, v1
	v_lshlrev_b32_e32 v12, 16, v2
	v_and_b32_e32 v13, 0xffff0000, v2
	v_lshlrev_b32_e32 v14, 16, v3
	v_and_b32_e32 v15, 0xffff0000, v3
	flat_store_dwordx4 v[8:9], v[176:179] offset:3072
	v_lshlrev_b32_e32 v0, 16, v176
	v_and_b32_e32 v1, 0xffff0000, v176
	v_lshlrev_b32_e32 v2, 16, v177
	v_and_b32_e32 v3, 0xffff0000, v177
	v_lshlrev_b32_e32 v8, 16, v178
	v_and_b32_e32 v9, 0xffff0000, v178
	v_lshlrev_b32_e32 v10, 16, v179
	v_and_b32_e32 v11, 0xffff0000, v179
	v_lshlrev_b32_e32 v56, 2, v58
	s_cbranch_execnz .LBB0_1686

.LBB0_1686:
	v_mul_f32_e32 v44, 0x4b800000, v168
	v_cndmask_b32_e64 v44, v168, v44, s[6:7]
	v_rsq_f32_e32 v44, v44
	v_lshlrev_b32_e32 v40, 16, v36
	v_and_b32_e32 v41, 0xffff0000, v36
	v_lshlrev_b32_e32 v36, 16, v37
	v_mul_f32_e32 v45, 0x45800000, v44
	v_cndmask_b32_e64 v52, v44, v45, s[6:7]
	v_mul_f32 v44, v52, v104
	v_mul_f32 v45, v52, v105
	v_and_b32_e32 v37, 0xffff0000, v37
	v_fma_f32 v44, v100, v44, v40
	v_fma_f32 v45, v101, v45, v41
	v_mul_f32 v40, v52, v106
	v_mul_f32 v41, v52, v107
	v_lshlrev_b32_e32 v42, 16, v38
	v_and_b32_e32 v43, 0xffff0000, v38
	v_fma_f32 v46, v96, v40, v36
	v_fma_f32 v47, v97, v41, v37
	v_mul_f32 v36, v52, v108
	v_mul_f32 v37, v52, v109
	v_lshlrev_b32_e32 v38, 16, v39
	v_and_b32_e32 v39, 0xffff0000, v39
	v_fma_f32 v40, v98, v36, v42
	v_fma_f32 v41, v99, v37, v43
	v_mul_f32 v36, v52, v158
	v_mul_f32 v37, v52, v159
	v_lshlrev_b32_e32 v48, 16, v32
	v_and_b32_e32 v49, 0xffff0000, v32
	v_lshlrev_b32_e32 v32, 16, v33
	v_and_b32_e32 v33, 0xffff0000, v33
	v_fma_f32 v42, v92, v36, v38
	v_fma_f32 v43, v93, v37, v39
	v_mul_f32 v38, v52, v162
	v_mul_f32 v39, v52, v163
	v_lshlrev_b32_e32 v50, 16, v34
	v_and_b32_e32 v51, 0xffff0000, v34
	v_mul_f32 v36, v52, v160
	v_mul_f32 v37, v52, v161
	v_fma_f32 v38, v90, v38, v32
	v_fma_f32 v39, v91, v39, v33
	v_mul_f32 v32, v52, v164
	v_mul_f32 v33, v52, v165
	v_lshlrev_b32_e32 v34, 16, v35
	v_and_b32_e32 v35, 0xffff0000, v35
	v_fma_f32 v36, v94, v36, v48
	v_fma_f32 v37, v95, v37, v49
	v_fma_f32 v32, v122, v32, v50
	v_fma_f32 v33, v123, v33, v51
	v_mul_f32 v48, v52, v166
	v_mul_f32 v49, v52, v167
	v_cndmask_b32_e64 v50, 0, 1, s[22:23]
	v_cmp_ne_u32_e64 s[6:7], 1, v50
	s_andn2_b64 vcc, exec, s[22:23]
	v_fma_f32 v34, v120, v48, v34
	v_fma_f32 v35, v121, v49, v35
	s_cbranch_vccnz .LBB0_1699
	v_cvt_pk_bf16_f32 v48, v44, v45
	v_cvt_pk_bf16_f32 v49, v46, v47
	v_cvt_pk_bf16_f32 v50, v40, v41
	v_cvt_pk_bf16_f32 v51, v42, v43
	v_cvt_pk_bf16_f32 v158, v36, v37
	v_cvt_pk_bf16_f32 v159, v38, v39
	v_cvt_pk_bf16_f32 v160, v32, v33
	v_cvt_pk_bf16_f32 v161, v34, v35
	flat_store_dwordx4 v[114:115], v[48:51] offset:2048
	v_lshlrev_b32_e32 v108, 16, v48
	v_and_b32_e32 v109, 0xffff0000, v48
	v_lshlrev_b32_e32 v104, 16, v49
	v_and_b32_e32 v105, 0xffff0000, v49
	v_lshlrev_b32_e32 v106, 16, v50
	v_and_b32_e32 v107, 0xffff0000, v50
	v_lshlrev_b32_e32 v102, 16, v51
	v_and_b32_e32 v103, 0xffff0000, v51
	v_lshlrev_b32_e32 v54, 16, v158
	v_and_b32_e32 v55, 0xffff0000, v158
	v_lshlrev_b32_e32 v50, 16, v159
	v_and_b32_e32 v51, 0xffff0000, v159
	v_lshlrev_b32_e32 v52, 16, v160
	v_and_b32_e32 v53, 0xffff0000, v160
	v_lshlrev_b32_e32 v48, 16, v161
	v_and_b32_e32 v49, 0xffff0000, v161
	flat_store_dwordx4 v[114:115], v[158:161] offset:3072
	s_cbranch_execnz .LBB0_1689

.LBB0_1689:
	v_add_f32 v36, v154, v156
	v_add_f32 v37, v155, v157
	v_lshlrev_b32_e32 v42, 16, v26
	v_fma_f32 v154, v36, s24, v80
	v_fma_f32 v155, v37, s24, v80
	v_and_b32_e32 v43, 0xffff0000, v26
	v_mul_f32_e32 v26, 0x4b800000, v155
	v_cmp_gt_f32_e32 vcc, s37, v155
	v_lshlrev_b32_e32 v32, 16, v28
	v_and_b32_e32 v33, 0xffff0000, v28
	v_cndmask_b32_e32 v26, v155, v26, vcc
	v_rsq_f32_e32 v36, v26
	v_lshlrev_b32_e32 v28, 16, v29
	v_and_b32_e32 v29, 0xffff0000, v29
	v_lshlrev_b32_e32 v34, 16, v30
	v_mul_f32_e32 v37, 0x45800000, v36
	v_cndmask_b32_e32 v44, v36, v37, vcc
	v_mul_f32 v36, v44, v118
	v_mul_f32 v37, v44, v119
	v_fma_f32 v36, v100, v36, v32
	v_fma_f32 v37, v101, v37, v33
	v_mul_f32 v32, v44, v140
	v_mul_f32 v33, v44, v141
	v_and_b32_e32 v35, 0xffff0000, v30
	v_fma_f32 v38, v96, v32, v28
	v_fma_f32 v39, v97, v33, v29
	v_mul_f32 v28, v44, v142
	v_mul_f32 v29, v44, v143
	v_lshlrev_b32_e32 v30, 16, v31
	v_and_b32_e32 v31, 0xffff0000, v31
	v_fma_f32 v32, v98, v28, v34
	v_fma_f32 v33, v99, v29, v35
	v_mul_f32 v28, v44, v144
	v_mul_f32 v29, v44, v145
	v_lshlrev_b32_e32 v40, 16, v24
	v_and_b32_e32 v41, 0xffff0000, v24
	v_lshlrev_b32_e32 v24, 16, v25
	v_and_b32_e32 v25, 0xffff0000, v25
	v_fma_f32 v34, v92, v28, v30
	v_fma_f32 v35, v93, v29, v31
	v_mul_f32 v28, v44, v146
	v_mul_f32 v29, v44, v147
	v_mul_f32 v30, v44, v148
	v_mul_f32 v31, v44, v149
	v_lshlrev_b32_e32 v26, 16, v27
	v_and_b32_e32 v27, 0xffff0000, v27
	v_fma_f32 v28, v94, v28, v40
	v_fma_f32 v29, v95, v29, v41
	v_fma_f32 v30, v90, v30, v24
	v_fma_f32 v31, v91, v31, v25
	v_mul_f32 v24, v44, v150
	v_mul_f32 v25, v44, v151
	v_mul_f32 v40, v44, v152
	v_mul_f32 v41, v44, v153
	v_cmp_gt_f32_e64 s[8:9], s37, v154
	v_fma_f32 v24, v122, v24, v42
	v_fma_f32 v25, v123, v25, v43
	s_and_b64 vcc, exec, s[6:7]
	v_fma_f32 v26, v120, v40, v26
	v_fma_f32 v27, v121, v41, v27
	s_cbranch_vccnz .LBB0_1700
	v_cvt_pk_bf16_f32 v42, v36, v37
	v_cvt_pk_bf16_f32 v43, v38, v39
	v_cvt_pk_bf16_f32 v44, v32, v33
	v_cvt_pk_bf16_f32 v45, v34, v35
	v_cvt_pk_bf16_f32 v140, v28, v29
	v_cvt_pk_bf16_f32 v141, v30, v31
	v_cvt_pk_bf16_f32 v142, v24, v25
	v_cvt_pk_bf16_f32 v143, v26, v27
	flat_store_dwordx4 v[116:117], v[42:45] offset:2048
	v_lshlrev_b32_e32 v114, 16, v42
	v_and_b32_e32 v115, 0xffff0000, v42
	v_lshlrev_b32_e32 v42, 16, v43
	v_and_b32_e32 v43, 0xffff0000, v43
	v_lshlrev_b32_e32 v118, 16, v44
	v_and_b32_e32 v119, 0xffff0000, v44
	v_lshlrev_b32_e32 v112, 16, v45
	v_and_b32_e32 v113, 0xffff0000, v45
	flat_store_dwordx4 v[116:117], v[140:143] offset:3072
	v_lshlrev_b32_e32 v46, 16, v140
	v_and_b32_e32 v47, 0xffff0000, v140
	v_lshlrev_b32_e32 v40, 16, v141
	v_and_b32_e32 v41, 0xffff0000, v141
	v_lshlrev_b32_e32 v116, 16, v142
	v_and_b32_e32 v117, 0xffff0000, v142
	v_lshlrev_b32_e32 v44, 16, v143
	v_and_b32_e32 v45, 0xffff0000, v143
	s_cbranch_execnz .LBB0_1692

.LBB0_1692:
	v_mul_f32_e32 v28, 0x4b800000, v154
	v_cndmask_b32_e64 v28, v154, v28, s[8:9]
	v_rsq_f32_e32 v28, v28
	v_lshlrev_b32_e32 v24, 16, v20
	v_and_b32_e32 v25, 0xffff0000, v20
	v_lshlrev_b32_e32 v20, 16, v21
	v_mul_f32_e32 v29, 0x45800000, v28
	v_cndmask_b32_e64 v36, v28, v29, s[8:9]
	v_mul_f32 v28, v36, v124
	v_mul_f32 v29, v36, v125
	v_and_b32_e32 v21, 0xffff0000, v21
	v_fma_f32 v28, v100, v28, v24
	v_fma_f32 v29, v101, v29, v25
	v_mul_f32 v24, v36, v126
	v_mul_f32 v25, v36, v127
	v_lshlrev_b32_e32 v26, 16, v22
	v_and_b32_e32 v27, 0xffff0000, v22
	v_fma_f32 v30, v96, v24, v20
	v_fma_f32 v31, v97, v25, v21
	v_mul_f32 v20, v36, v128
	v_mul_f32 v21, v36, v129
	v_lshlrev_b32_e32 v22, 16, v23
	v_and_b32_e32 v23, 0xffff0000, v23
	v_fma_f32 v24, v98, v20, v26
	v_fma_f32 v25, v99, v21, v27
	v_mul_f32 v20, v36, v130
	v_mul_f32 v21, v36, v131
	v_lshlrev_b32_e32 v32, 16, v16
	v_and_b32_e32 v33, 0xffff0000, v16
	v_lshlrev_b32_e32 v16, 16, v17
	v_and_b32_e32 v17, 0xffff0000, v17
	v_fma_f32 v26, v92, v20, v22
	v_fma_f32 v27, v93, v21, v23
	v_mul_f32 v20, v36, v132
	v_mul_f32 v21, v36, v133
	v_mul_f32 v22, v36, v134
	v_mul_f32 v23, v36, v135
	v_lshlrev_b32_e32 v34, 16, v18
	v_and_b32_e32 v35, 0xffff0000, v18
	v_lshlrev_b32_e32 v18, 16, v19
	v_and_b32_e32 v19, 0xffff0000, v19
	v_fma_f32 v20, v94, v20, v32
	v_fma_f32 v21, v95, v21, v33
	v_fma_f32 v22, v90, v22, v16
	v_fma_f32 v23, v91, v23, v17
	v_mul_f32 v16, v36, v136
	v_mul_f32 v17, v36, v137
	v_mul_f32 v32, v36, v138
	v_mul_f32 v33, v36, v139
	v_fma_f32 v16, v122, v16, v34
	v_fma_f32 v17, v123, v17, v35
	s_and_b64 vcc, exec, s[6:7]
	v_fma_f32 v18, v120, v32, v18
	v_fma_f32 v19, v121, v33, v19
	s_cbranch_vccnz .LBB0_1701
	v_cvt_pk_bf16_f32 v32, v28, v29
	v_cvt_pk_bf16_f32 v33, v30, v31
	v_cvt_pk_bf16_f32 v34, v24, v25
	v_cvt_pk_bf16_f32 v35, v26, v27
	v_cvt_pk_bf16_f32 v98, v20, v21
	v_cvt_pk_bf16_f32 v99, v22, v23
	v_cvt_pk_bf16_f32 v100, v16, v17
	v_cvt_pk_bf16_f32 v101, v18, v19
	flat_store_dwordx4 v[88:89], v[32:35] offset:2048
	v_lshlrev_b32_e32 v96, 16, v32
	v_and_b32_e32 v97, 0xffff0000, v32
	v_lshlrev_b32_e32 v92, 16, v33
	v_and_b32_e32 v93, 0xffff0000, v33
	v_lshlrev_b32_e32 v94, 16, v34
	v_and_b32_e32 v95, 0xffff0000, v34
	v_lshlrev_b32_e32 v90, 16, v35
	v_and_b32_e32 v91, 0xffff0000, v35
	v_lshlrev_b32_e32 v38, 16, v98
	v_and_b32_e32 v39, 0xffff0000, v98
	v_lshlrev_b32_e32 v34, 16, v99
	v_and_b32_e32 v35, 0xffff0000, v99
	v_lshlrev_b32_e32 v36, 16, v100
	v_and_b32_e32 v37, 0xffff0000, v100
	v_lshlrev_b32_e32 v32, 16, v101
	v_and_b32_e32 v33, 0xffff0000, v101
	flat_store_dwordx4 v[88:89], v[98:101] offset:3072
	s_cbranch_execnz .LBB0_1695

.LBB0_1695:
	s_and_b64 vcc, exec, s[6:7]
	s_cbranch_vccnz .LBB0_1682
	v_mul_hi_u32_u24_e32 v17, 0x6000, v83
	v_mul_u32_u24_e32 v16, 0x6000, v83
	v_lshl_add_u64 v[16:17], s[20:21], 0, v[16:17]
	v_lshl_add_u64 v[18:19], v[16:17], 0, s[28:29]
	v_lshl_add_u64 v[20:21], v[18:19], 0, v[56:57]
	v_mov_b32_e32 v83, v57
	flat_load_dwordx4 v[98:101], v[20:21]
	v_lshl_add_u64 v[20:21], v[18:19], 0, v[82:83]
	v_mov_b32_e32 v85, v57
	flat_load_dwordx4 v[120:123], v[20:21]
	v_lshl_add_u64 v[20:21], v[18:19], 0, v[84:85]
	v_mov_b32_e32 v87, v57
	flat_load_dwordx4 v[124:127], v[20:21]
	v_lshl_add_u64 v[18:19], v[18:19], 0, v[86:87]
	flat_load_dwordx4 v[128:131], v[18:19]
	global_load_dwordx4 v[132:135], v[68:69], off
	global_load_dwordx4 v[136:139], v[68:69], off offset:16
	global_load_dwordx4 v[140:143], v[68:69], off offset:2048
	global_load_dwordx4 v[144:147], v[68:69], off offset:2064
	v_lshl_add_u64 v[16:17], v[16:17], 0, s[30:31]
	v_lshl_add_u64 v[18:19], v[16:17], 0, v[56:57]
	flat_load_dwordx4 v[28:31], v[18:19]
	v_lshl_add_u64 v[18:19], v[16:17], 0, v[82:83]
	flat_load_dwordx4 v[24:27], v[18:19]
	v_lshl_add_u64 v[18:19], v[16:17], 0, v[84:85]
	flat_load_dwordx4 v[20:23], v[18:19]
	v_lshl_add_u64 v[16:17], v[16:17], 0, v[86:87]
	flat_load_dwordx4 v[16:19], v[16:17]
	v_mul_f32_e32 v75, v5, v5
	v_mul_f32_e32 v88, v13, v13
	v_mul_f32_e32 v89, v1, v1
	v_fmac_f32_e32 v75, v4, v4
	v_fmac_f32_e32 v88, v12, v12
	v_mul_f32_e32 v110, v9, v9
	v_fmac_f32_e32 v89, v0, v0
	v_fmac_f32_e32 v75, v6, v6
	v_fmac_f32_e32 v88, v14, v14
	v_fmac_f32_e32 v110, v8, v8
	v_fmac_f32_e32 v89, v2, v2
	v_fmac_f32_e32 v75, v7, v7
	v_fmac_f32_e32 v88, v15, v15
	v_fmac_f32_e32 v110, v10, v10
	v_fmac_f32_e32 v89, v3, v3
	v_add_f32_e32 v56, v88, v75
	v_fmac_f32_e32 v110, v11, v11
	v_add_f32_e32 v56, v89, v56
	v_add_f32_e32 v56, v110, v56
	v_mul_f32_e32 v111, v109, v109
	v_mul_f32_e32 v148, v107, v107
	v_add_f32_dpp v56, v56, v56 quad_perm:[1,0,3,2] row_mask:0xf bank_mask:0xf bound_ctrl:1
	v_mul_f32_e32 v150, v55, v55
	v_fmac_f32_e32 v111, v108, v108
	v_add_f32_dpp v56, v56, v56 quad_perm:[2,3,0,1] row_mask:0xf bank_mask:0xf bound_ctrl:1
	v_fmac_f32_e32 v148, v106, v106
	v_fmac_f32_e32 v150, v54, v54
	v_add_f32_dpp v56, v56, v56 row_half_mirror row_mask:0xf bank_mask:0xf bound_ctrl:1
	v_fmac_f32_e32 v111, v104, v104
	v_fmac_f32_e32 v148, v102, v102
	v_add_f32_dpp v56, v56, v56 row_mirror row_mask:0xf bank_mask:0xf bound_ctrl:1
	v_fmac_f32_e32 v150, v50, v50
	v_fmac_f32_e32 v111, v105, v105
	v_fmac_f32_e32 v148, v103, v103
	v_mov_b32_e32 v83, v56
	v_fmac_f32_e32 v150, v51, v51
	v_add_f32_e32 v75, v111, v148
	v_permlane16_swap_b32_e32 v56, v83
	v_add_f32_e32 v149, v56, v83
	v_add_f32_e32 v56, v75, v150
	v_mul_f32_e32 v75, v53, v53
	v_fmac_f32_e32 v75, v52, v52
	v_fmac_f32_e32 v75, v48, v48
	v_fmac_f32_e32 v75, v49, v49
	v_add_f32_e32 v56, v56, v75
	v_mov_b32_e32 v151, v149
	s_nop 1
	v_permlane32_swap_b32_e32 v149, v151
	v_add_f32_dpp v56, v56, v56 quad_perm:[1,0,3,2] row_mask:0xf bank_mask:0xf bound_ctrl:1
	v_add_u32_e32 v83, 0xffffe800, v81
	s_waitcnt vmcnt(0) lgkmcnt(0)
	v_add_f32 v88, v100, 1.0
	v_add_f32 v89, v101, 1.0
	v_add_f32_dpp v56, v56, v56 quad_perm:[2,3,0,1] row_mask:0xf bank_mask:0xf bound_ctrl:1
	v_add_f32 v98, v98, 1.0
	v_add_f32 v99, v99, 1.0
	v_add_f32 v130, v130, 1.0
	v_add_f32 v131, v131, 1.0
	v_add_f32_dpp v56, v56, v56 row_half_mirror row_mask:0xf bank_mask:0xf bound_ctrl:1
	v_add_f32 v100, v122, 1.0
	v_add_f32 v101, v123, 1.0
	v_add_f32 v126, v126, 1.0
	v_add_f32 v127, v127, 1.0
	v_add_f32_dpp v56, v56, v56 row_mirror row_mask:0xf bank_mask:0xf bound_ctrl:1
	v_mov_b32_e32 v75, v56
	s_nop 1
	v_permlane16_swap_b32_e32 v56, v75
	v_add_f32_e32 v148, v56, v75
	v_mov_b32_e32 v150, v148
	s_nop 1
	v_permlane32_swap_b32_e32 v148, v150
	v_add_f32 v122, v120, 1.0
	v_add_f32 v123, v121, 1.0
	v_add_f32 v152, v124, 1.0
	v_add_f32 v153, v125, 1.0
	v_mul_f32 v120, v134, v88
	v_mul_f32 v121, v135, v89
	v_mul_f32 v124, v132, v98
	v_mul_f32 v125, v133, v99
	v_mul_f32 v98, v142, v126
	v_mul_f32 v99, v143, v127
	v_mul_f32 v88, v146, v130
	v_mul_f32 v89, v147, v131
	v_add_f32 v126, v148, v150
	v_add_f32 v127, v149, v151
	v_mov_b64_e32 v[130:131], s[26:27]
	v_fma_f32 v132, v126, s24, v130
	v_fma_f32 v133, v127, s24, v130
	v_mul_f32 v110, v138, v100
	v_mul_f32 v111, v139, v101
	v_mul_f32_e32 v56, 0x4b800000, v133
	v_cmp_gt_f32_e32 vcc, s37, v133
	v_mul_f32 v100, v140, v152
	v_mul_f32 v101, v141, v153
	v_mul_f32 v122, v136, v122
	v_mul_f32 v123, v137, v123
	v_cndmask_b32_e32 v56, v133, v56, vcc
	v_rsq_f32_e32 v56, v56
	v_add_u32_e32 v75, 0xffffe400, v81
	v_add_f32 v128, v128, 1.0
	v_add_f32 v129, v129, 1.0
	v_mul_f32_e32 v85, 0x45800000, v56
	v_cndmask_b32_e32 v56, v56, v85, vcc
	v_mul_f32 v0, v0, v56
	v_mul_f32 v1, v1, v56
	v_mul_f32 v2, v2, v56
	v_mul_f32 v3, v3, v56
	v_mul_f32 v4, v4, v56
	v_mul_f32 v5, v5, v56
	v_mul_f32 v12, v12, v56
	v_mul_f32 v13, v13, v56
	v_mul_f32 v6, v6, v56
	v_mul_f32 v7, v7, v56
	v_mul_f32 v14, v14, v56
	v_mul_f32 v15, v15, v56
	v_fma_f32 v0, v100, v0, v20
	v_fma_f32 v1, v101, v1, v21
	v_fma_f32 v2, v98, v2, v22
	v_fma_f32 v3, v99, v3, v23
	v_fma_f32 v4, v124, v4, v28
	v_fma_f32 v5, v125, v5, v29
	v_fma_f32 v12, v122, v12, v24
	v_fma_f32 v13, v123, v13, v25
	v_fma_f32 v6, v120, v6, v30
	v_fma_f32 v7, v121, v7, v31
	v_fma_f32 v14, v110, v14, v26
	v_fma_f32 v15, v111, v15, v27
	v_cvt_pk_bf16_f32 v0, v0, v1
	v_cvt_pk_bf16_f32 v1, v2, v3
	v_mul_f32_e32 v2, 0x4b800000, v132
	v_cmp_gt_f32_e32 vcc, s37, v132
	v_cvt_pk_bf16_f32 v4, v4, v5
	v_cvt_pk_bf16_f32 v5, v6, v7
	v_cvt_pk_bf16_f32 v6, v12, v13
	v_cvt_pk_bf16_f32 v7, v14, v15
	v_cndmask_b32_e32 v2, v132, v2, vcc
	buffer_store_dwordx4 v[4:7], v75, s[12:15], 0 offen sc1
	v_mul_f32 v126, v144, v128
	v_mul_f32 v127, v145, v129
	v_add_u32_e32 v12, 0xfffff800, v81
	v_mul_f32 v4, v8, v56
	v_mul_f32 v5, v9, v56
	v_rsq_f32_e32 v8, v2
	v_mul_f32 v6, v10, v56
	v_mul_f32 v7, v11, v56
	v_fma_f32 v4, v126, v4, v16
	v_fma_f32 v5, v127, v5, v17
	v_fma_f32 v6, v88, v6, v18
	v_fma_f32 v7, v89, v7, v19
	v_cvt_pk_bf16_f32 v2, v4, v5
	v_cvt_pk_bf16_f32 v3, v6, v7
	buffer_store_dwordx4 v[0:3], v83, s[12:15], 0 offen sc1
	s_nop 1
	v_mul_f32_e32 v0, 0x45800000, v8
	v_cndmask_b32_e32 v4, v8, v0, vcc
	v_mul_f32 v0, v108, v4
	v_mul_f32 v1, v109, v4
	v_mul_f32 v2, v106, v4
	v_mul_f32 v3, v107, v4
	v_mul_f32 v6, v104, v4
	v_mul_f32 v7, v105, v4
	v_mul_f32 v8, v102, v4
	v_mul_f32 v9, v103, v4
	v_fma_f32 v0, v124, v0, v28
	v_fma_f32 v1, v125, v1, v29
	v_fma_f32 v2, v122, v2, v24
	v_fma_f32 v3, v123, v3, v25
	v_fma_f32 v6, v120, v6, v30
	v_fma_f32 v7, v121, v7, v31
	v_fma_f32 v8, v110, v8, v26
	v_fma_f32 v9, v111, v9, v27
	v_cvt_pk_bf16_f32 v0, v0, v1
	v_cvt_pk_bf16_f32 v1, v6, v7
	v_cvt_pk_bf16_f32 v2, v2, v3
	v_cvt_pk_bf16_f32 v3, v8, v9
	v_add_u32_e32 v5, 0xffffec00, v81
	buffer_store_dwordx4 v[0:3], v5, s[12:15], 0 offen sc1
	v_mul_f32 v6, v50, v4
	v_mul_f32 v7, v51, v4
	v_add_u32_e32 v8, 0xfffff000, v81
	v_mul_f32 v0, v54, v4
	v_mul_f32 v1, v55, v4
	v_mul_f32 v2, v52, v4
	v_mul_f32 v3, v53, v4
	v_mul_f32 v5, v49, v4
	v_mul_f32 v4, v48, v4
	v_fma_f32 v2, v126, v2, v16
	v_fma_f32 v3, v127, v3, v17
	v_fma_f32 v4, v88, v4, v18
	v_fma_f32 v5, v89, v5, v19
	v_cvt_pk_bf16_f32 v2, v2, v3
	v_cvt_pk_bf16_f32 v3, v4, v5
	v_mul_f32_e32 v4, v115, v115
	v_mul_f32_e32 v5, v119, v119
	v_fmac_f32_e32 v4, v114, v114
	v_fmac_f32_e32 v5, v118, v118
	v_fmac_f32_e32 v4, v42, v42
	v_fmac_f32_e32 v5, v112, v112
	v_fmac_f32_e32 v4, v43, v43
	v_fmac_f32_e32 v5, v113, v113
	v_add_f32_e32 v4, v4, v5
	v_mul_f32_e32 v5, v47, v47
	v_fmac_f32_e32 v5, v46, v46
	v_fmac_f32_e32 v5, v40, v40
	v_fmac_f32_e32 v5, v41, v41
	v_add_f32_e32 v4, v4, v5
	v_mul_f32_e32 v5, v117, v117
	v_fmac_f32_e32 v5, v116, v116
	v_fmac_f32_e32 v5, v44, v44
	v_fmac_f32_e32 v5, v45, v45
	v_add_f32_e32 v4, v4, v5
	v_fma_f32 v0, v100, v0, v20
	v_fma_f32 v1, v101, v1, v21
	v_fma_f32 v6, v98, v6, v22
	v_fma_f32 v7, v99, v7, v23
	v_add_f32_dpp v4, v4, v4 quad_perm:[1,0,3,2] row_mask:0xf bank_mask:0xf bound_ctrl:1
	v_cvt_pk_bf16_f32 v0, v0, v1
	v_cvt_pk_bf16_f32 v1, v6, v7
	v_add_f32_dpp v4, v4, v4 quad_perm:[2,3,0,1] row_mask:0xf bank_mask:0xf bound_ctrl:1
	v_mul_f32_e32 v6, v95, v95
	v_fmac_f32_e32 v6, v94, v94
	v_add_f32_dpp v4, v4, v4 row_half_mirror row_mask:0xf bank_mask:0xf bound_ctrl:1
	v_fmac_f32_e32 v6, v90, v90
	v_fmac_f32_e32 v6, v91, v91
	v_add_f32_dpp v4, v4, v4 row_mirror row_mask:0xf bank_mask:0xf bound_ctrl:1
	v_mov_b32_e32 v5, v4
	s_nop 1
	v_permlane16_swap_b32_e32 v4, v5
	v_add_f32_e32 v5, v4, v5
	v_mul_f32_e32 v4, v97, v97
	v_fmac_f32_e32 v4, v96, v96
	v_fmac_f32_e32 v4, v92, v92
	v_fmac_f32_e32 v4, v93, v93
	v_add_f32_e32 v4, v4, v6
	v_mul_f32_e32 v6, v39, v39
	v_fmac_f32_e32 v6, v38, v38
	v_fmac_f32_e32 v6, v34, v34
	v_fmac_f32_e32 v6, v35, v35
	v_add_f32_e32 v4, v4, v6
	v_mul_f32_e32 v6, v37, v37
	v_fmac_f32_e32 v6, v36, v36
	v_fmac_f32_e32 v6, v32, v32
	v_fmac_f32_e32 v6, v33, v33
	v_add_f32_e32 v4, v4, v6
	v_mov_b32_e32 v7, v5
	s_nop 1
	v_permlane32_swap_b32_e32 v5, v7
	v_add_f32_dpp v4, v4, v4 quad_perm:[1,0,3,2] row_mask:0xf bank_mask:0xf bound_ctrl:1
	buffer_store_dwordx4 v[0:3], v8, s[12:15], 0 offen sc1
	s_nop 0
	v_add_f32_dpp v4, v4, v4 quad_perm:[2,3,0,1] row_mask:0xf bank_mask:0xf bound_ctrl:1
	s_nop 1
	v_add_f32_dpp v4, v4, v4 row_half_mirror row_mask:0xf bank_mask:0xf bound_ctrl:1
	s_nop 1
	v_add_f32_dpp v4, v4, v4 row_mirror row_mask:0xf bank_mask:0xf bound_ctrl:1
	v_mov_b32_e32 v6, v4
	s_nop 1
	v_permlane16_swap_b32_e32 v4, v6
	v_add_f32_e32 v4, v4, v6
	v_mov_b32_e32 v6, v4
	s_nop 1
	v_permlane32_swap_b32_e32 v4, v6
	v_add_f32 v4, v4, v6
	v_add_f32 v5, v5, v7
	v_add_u32_e32 v7, 0xfffff400, v81
	v_fma_f32 v4, v4, s24, v130
	v_fma_f32 v5, v5, s24, v130
	s_nop 0
	v_mul_f32_e32 v6, 0x4b800000, v5
	v_cmp_gt_f32_e32 vcc, s37, v5
	s_nop 1
	v_cndmask_b32_e32 v5, v5, v6, vcc
	v_rsq_f32_e32 v5, v5
	s_nop 0
	v_mul_f32_e32 v0, 0x45800000, v5
	v_cndmask_b32_e32 v6, v5, v0, vcc
	v_mul_f32 v0, v114, v6
	v_mul_f32 v1, v115, v6
	v_mul_f32 v2, v118, v6
	v_mul_f32 v3, v119, v6
	v_mul_f32 v8, v42, v6
	v_mul_f32 v9, v43, v6
	v_mul_f32 v10, v112, v6
	v_mul_f32 v11, v113, v6
	v_mul_f32_e32 v5, 0x4b800000, v4
	v_cmp_gt_f32_e32 vcc, s37, v4
	v_fma_f32 v0, v124, v0, v28
	v_fma_f32 v1, v125, v1, v29
	v_fma_f32 v2, v122, v2, v24
	v_fma_f32 v3, v123, v3, v25
	v_fma_f32 v8, v120, v8, v30
	v_fma_f32 v9, v121, v9, v31
	v_fma_f32 v10, v110, v10, v26
	v_fma_f32 v11, v111, v11, v27
	v_cndmask_b32_e32 v4, v4, v5, vcc
	v_cvt_pk_bf16_f32 v0, v0, v1
	v_cvt_pk_bf16_f32 v1, v8, v9
	v_cvt_pk_bf16_f32 v2, v2, v3
	v_cvt_pk_bf16_f32 v3, v10, v11
	v_rsq_f32_e32 v4, v4
	buffer_store_dwordx4 v[0:3], v7, s[12:15], 0 offen sc1
	v_mul_f32 v8, v40, v6
	v_mul_f32 v9, v41, v6
	s_nop 0
	v_mul_f32 v0, v46, v6
	v_mul_f32 v1, v47, v6
	v_mul_f32 v2, v116, v6
	v_mul_f32 v3, v117, v6
	v_mul_f32 v7, v45, v6
	v_mul_f32 v6, v44, v6
	v_fma_f32 v0, v100, v0, v20
	v_fma_f32 v1, v101, v1, v21
	v_fma_f32 v2, v126, v2, v16
	v_fma_f32 v3, v127, v3, v17
	v_fma_f32 v8, v98, v8, v22
	v_fma_f32 v9, v99, v9, v23
	v_fma_f32 v6, v88, v6, v18
	v_fma_f32 v7, v89, v7, v19
	v_cvt_pk_bf16_f32 v0, v0, v1
	v_cvt_pk_bf16_f32 v1, v8, v9
	v_cvt_pk_bf16_f32 v2, v2, v3
	v_cvt_pk_bf16_f32 v3, v6, v7
	buffer_store_dwordx4 v[0:3], v12, s[12:15], 0 offen sc1
	s_nop 1
	v_mul_f32_e32 v0, 0x45800000, v4
	v_cndmask_b32_e32 v4, v4, v0, vcc
	v_mul_f32 v0, v96, v4
	v_mul_f32 v1, v97, v4
	v_mul_f32 v2, v94, v4
	v_mul_f32 v3, v95, v4
	v_mul_f32 v6, v92, v4
	v_mul_f32 v7, v93, v4
	v_mul_f32 v8, v90, v4
	v_mul_f32 v9, v91, v4
	v_fma_f32 v0, v124, v0, v28
	v_fma_f32 v1, v125, v1, v29
	v_fma_f32 v2, v122, v2, v24
	v_fma_f32 v3, v123, v3, v25
	v_fma_f32 v6, v120, v6, v30
	v_fma_f32 v7, v121, v7, v31
	v_fma_f32 v8, v110, v8, v26
	v_fma_f32 v9, v111, v9, v27
	v_cvt_pk_bf16_f32 v0, v0, v1
	v_cvt_pk_bf16_f32 v1, v6, v7
	v_cvt_pk_bf16_f32 v2, v2, v3
	v_cvt_pk_bf16_f32 v3, v8, v9
	v_add_u32_e32 v5, 0xfffffc00, v81
	buffer_store_dwordx4 v[0:3], v5, s[12:15], 0 offen sc1
	v_mul_f32 v6, v34, v4
	v_mul_f32 v7, v35, v4
	s_nop 0
	v_mul_f32 v0, v38, v4
	v_mul_f32 v1, v39, v4
	v_mul_f32 v2, v36, v4
	v_mul_f32 v3, v37, v4
	v_mul_f32 v5, v33, v4
	v_mul_f32 v4, v32, v4
	v_fma_f32 v0, v100, v0, v20
	v_fma_f32 v1, v101, v1, v21
	v_fma_f32 v2, v126, v2, v16
	v_fma_f32 v3, v127, v3, v17
	v_fma_f32 v6, v98, v6, v22
	v_fma_f32 v7, v99, v7, v23
	v_fma_f32 v4, v88, v4, v18
	v_fma_f32 v5, v89, v5, v19
	v_cvt_pk_bf16_f32 v0, v0, v1
	v_cvt_pk_bf16_f32 v1, v6, v7
	v_cvt_pk_bf16_f32 v2, v2, v3
	v_cvt_pk_bf16_f32 v3, v4, v5
	buffer_store_dwordx4 v[0:3], v81, s[12:15], 0 offen sc1
	s_waitcnt vmcnt(0)
	s_and_saveexec_b64 s[6:7], s[4:5]
	s_cbranch_execz .LBB0_1681
	v_ashrrev_i32_e32 v0, 2, v74
	v_and_b32_e32 v0, 0xffffffc0, v0
	v_ashrrev_i32_e32 v1, 31, v0
	v_lshl_add_u64 v[0:1], v[0:1], 2, s[16:17]
	flat_atomic_add v[0:1], v170
	s_branch .LBB0_1681

.LBB0_1749:
	v_lshl_add_u32 v146, s44, 8, v151
	v_ashrrev_i32_e32 v147, 31, v146
	v_lshl_or_b32 v144, s42, 8, v153
	v_lshlrev_b64 v[148:149], 13, v[146:147]
	v_ashrrev_i32_e32 v145, 31, v144
	v_lshl_add_u64 v[148:149], s[14:15], 0, v[148:149]
	v_lshl_add_u64 v[148:149], v[144:145], 1, v[148:149]
	v_cmp_gt_i32_e32 vcc, s81, v144
	s_and_saveexec_b64 s[10:11], vcc
	s_cbranch_execz .LBB0_1751
	v_max_f32_e32 v124, 0, v124
	v_max_f32_e32 v125, 0, v125
	v_max_f32_e32 v126, 0, v126
	v_max_f32_e32 v127, 0, v127
	v_max_f32_e32 v120, 0, v120
	v_max_f32_e32 v121, 0, v121
	v_max_f32_e32 v122, 0, v122
	v_max_f32_e32 v123, 0, v123
	v_mul_f32 v124, v124, v124
	v_mul_f32 v125, v125, v125
	v_mul_f32 v126, v126, v126
	v_mul_f32 v127, v127, v127
	v_mul_f32 v120, v120, v120
	v_mul_f32 v121, v121, v121
	v_mul_f32 v122, v122, v122
	v_mul_f32 v123, v123, v123
	v_cvt_pk_bf16_f32 v120, v120, v121
	v_cvt_pk_bf16_f32 v121, v122, v123
	v_cvt_pk_bf16_f32 v122, v124, v125
	v_cvt_pk_bf16_f32 v123, v126, v127
	flat_store_dwordx4 v[148:149], v[120:123]
.LBB0_1751:
	s_or_b64 exec, exec, s[10:11]
	s_nop 0
	v_or_b32_e32 v120, 0x80, v144
	v_cmp_gt_i32_e64 s[10:11], s81, v120
	s_and_saveexec_b64 s[42:43], s[10:11]
	s_load_dwordx2 s[84:85], s[90:91], 0x120
	s_cbranch_execz .LBB0_1753
	v_max_f32_e32 v116, 0, v116
	v_max_f32_e32 v117, 0, v117
	v_max_f32_e32 v118, 0, v118
	v_max_f32_e32 v119, 0, v119
	v_max_f32_e32 v112, 0, v112
	v_max_f32_e32 v113, 0, v113
	v_max_f32_e32 v114, 0, v114
	v_max_f32_e32 v115, 0, v115
	v_mul_f32 v116, v116, v116
	v_mul_f32 v117, v117, v117
	v_mul_f32 v118, v118, v118
	v_mul_f32 v119, v119, v119
	v_mul_f32 v112, v112, v112
	v_mul_f32 v113, v113, v113
	v_mul_f32 v114, v114, v114
	v_mul_f32 v115, v115, v115
	v_cvt_pk_bf16_f32 v112, v112, v113
	v_cvt_pk_bf16_f32 v113, v114, v115
	v_cvt_pk_bf16_f32 v114, v116, v117
	v_cvt_pk_bf16_f32 v115, v118, v119
	flat_store_dwordx4 v[148:149], v[112:115] offset:256
.LBB0_1753:
	s_or_b64 exec, exec, s[42:43]
	s_nop 0
	v_or_b32_e32 v112, 16, v146
	v_ashrrev_i32_e32 v113, 31, v112
	v_lshlrev_b64 v[112:113], 13, v[112:113]
	v_lshl_add_u64 v[112:113], s[14:15], 0, v[112:113]
	v_lshl_add_u64 v[112:113], v[144:145], 1, v[112:113]
	s_and_saveexec_b64 s[42:43], vcc
	s_cbranch_execz .LBB0_1755
	v_max_f32_e32 v108, 0, v108
	v_max_f32_e32 v109, 0, v109
	v_max_f32_e32 v110, 0, v110
	v_max_f32_e32 v111, 0, v111
	v_max_f32_e32 v104, 0, v104
	v_max_f32_e32 v105, 0, v105
	v_max_f32_e32 v106, 0, v106
	v_max_f32_e32 v107, 0, v107
	v_mul_f32 v108, v108, v108
	v_mul_f32 v109, v109, v109
	v_mul_f32 v110, v110, v110
	v_mul_f32 v111, v111, v111
	v_mul_f32 v104, v104, v104
	v_mul_f32 v105, v105, v105
	v_mul_f32 v106, v106, v106
	v_mul_f32 v107, v107, v107
	v_cvt_pk_bf16_f32 v104, v104, v105
	v_cvt_pk_bf16_f32 v105, v106, v107
	v_cvt_pk_bf16_f32 v106, v108, v109
	v_cvt_pk_bf16_f32 v107, v110, v111
	flat_store_dwordx4 v[112:113], v[104:107]
.LBB0_1755:
	s_or_b64 exec, exec, s[42:43]
	s_and_saveexec_b64 s[42:43], s[10:11]
	s_cbranch_execz .LBB0_1757
	v_max_f32_e32 v100, 0, v100
	v_max_f32_e32 v101, 0, v101
	v_max_f32_e32 v102, 0, v102
	v_max_f32_e32 v103, 0, v103
	v_max_f32_e32 v96, 0, v96
	v_max_f32_e32 v97, 0, v97
	v_max_f32_e32 v98, 0, v98
	v_max_f32_e32 v99, 0, v99
	v_mul_f32 v100, v100, v100
	v_mul_f32 v101, v101, v101
	v_mul_f32 v102, v102, v102
	v_mul_f32 v103, v103, v103
	v_mul_f32 v96, v96, v96
	v_mul_f32 v97, v97, v97
	v_mul_f32 v98, v98, v98
	v_mul_f32 v99, v99, v99
	v_cvt_pk_bf16_f32 v96, v96, v97
	v_cvt_pk_bf16_f32 v97, v98, v99
	v_cvt_pk_bf16_f32 v98, v100, v101
	v_cvt_pk_bf16_f32 v99, v102, v103
	flat_store_dwordx4 v[112:113], v[96:99] offset:256
.LBB0_1757:
	s_or_b64 exec, exec, s[42:43]
	s_nop 0
	v_or_b32_e32 v96, 32, v146
	v_ashrrev_i32_e32 v97, 31, v96
	v_lshlrev_b64 v[96:97], 13, v[96:97]
	v_lshl_add_u64 v[96:97], s[14:15], 0, v[96:97]
	v_lshl_add_u64 v[96:97], v[144:145], 1, v[96:97]
	s_and_saveexec_b64 s[42:43], vcc
	s_cbranch_execz .LBB0_1759
	v_max_f32_e32 v92, 0, v92
	v_max_f32_e32 v93, 0, v93
	v_max_f32_e32 v94, 0, v94
	v_max_f32_e32 v95, 0, v95
	v_max_f32_e32 v88, 0, v88
	v_max_f32_e32 v89, 0, v89
	v_max_f32_e32 v90, 0, v90
	v_max_f32_e32 v91, 0, v91
	v_mul_f32 v92, v92, v92
	v_mul_f32 v93, v93, v93
	v_mul_f32 v94, v94, v94
	v_mul_f32 v95, v95, v95
	v_mul_f32 v88, v88, v88
	v_mul_f32 v89, v89, v89
	v_mul_f32 v90, v90, v90
	v_mul_f32 v91, v91, v91
	v_cvt_pk_bf16_f32 v88, v88, v89
	v_cvt_pk_bf16_f32 v89, v90, v91
	v_cvt_pk_bf16_f32 v90, v92, v93
	v_cvt_pk_bf16_f32 v91, v94, v95
	flat_store_dwordx4 v[96:97], v[88:91]
.LBB0_1759:
	s_or_b64 exec, exec, s[42:43]
	s_and_saveexec_b64 s[42:43], s[10:11]
	s_cbranch_execz .LBB0_1761
	v_max_f32_e32 v84, 0, v84
	v_max_f32_e32 v85, 0, v85
	v_max_f32_e32 v86, 0, v86
	v_max_f32_e32 v87, 0, v87
	v_max_f32_e32 v80, 0, v80
	v_max_f32_e32 v81, 0, v81
	v_max_f32_e32 v82, 0, v82
	v_max_f32_e32 v83, 0, v83
	v_mul_f32 v84, v84, v84
	v_mul_f32 v85, v85, v85
	v_mul_f32 v86, v86, v86
	v_mul_f32 v87, v87, v87
	v_mul_f32 v80, v80, v80
	v_mul_f32 v81, v81, v81
	v_mul_f32 v82, v82, v82
	v_mul_f32 v83, v83, v83
	v_cvt_pk_bf16_f32 v80, v80, v81
	v_cvt_pk_bf16_f32 v81, v82, v83
	v_cvt_pk_bf16_f32 v82, v84, v85
	v_cvt_pk_bf16_f32 v83, v86, v87
	flat_store_dwordx4 v[96:97], v[80:83] offset:256
.LBB0_1761:
	s_or_b64 exec, exec, s[42:43]
	s_nop 0
	v_or_b32_e32 v80, 48, v146
	v_ashrrev_i32_e32 v81, 31, v80
	v_lshlrev_b64 v[80:81], 13, v[80:81]
	v_lshl_add_u64 v[80:81], s[14:15], 0, v[80:81]
	v_lshl_add_u64 v[80:81], v[144:145], 1, v[80:81]
	s_and_saveexec_b64 s[42:43], vcc
	s_cbranch_execz .LBB0_1763
	v_max_f32_e32 v76, 0, v76
	v_max_f32_e32 v77, 0, v77
	v_max_f32_e32 v78, 0, v78
	v_max_f32_e32 v79, 0, v79
	v_max_f32_e32 v72, 0, v72
	v_max_f32_e32 v73, 0, v73
	v_max_f32_e32 v74, 0, v74
	v_max_f32_e32 v75, 0, v75
	v_mul_f32 v76, v76, v76
	v_mul_f32 v77, v77, v77
	v_mul_f32 v78, v78, v78
	v_mul_f32 v79, v79, v79
	v_mul_f32 v72, v72, v72
	v_mul_f32 v73, v73, v73
	v_mul_f32 v74, v74, v74
	v_mul_f32 v75, v75, v75
	v_cvt_pk_bf16_f32 v72, v72, v73
	v_cvt_pk_bf16_f32 v73, v74, v75
	v_cvt_pk_bf16_f32 v74, v76, v77
	v_cvt_pk_bf16_f32 v75, v78, v79
	flat_store_dwordx4 v[80:81], v[72:75]
.LBB0_1763:
	s_or_b64 exec, exec, s[42:43]
	s_and_saveexec_b64 s[42:43], s[10:11]
	s_cbranch_execz .LBB0_1765
	v_max_f32_e32 v68, 0, v68
	v_max_f32_e32 v69, 0, v69
	v_max_f32_e32 v70, 0, v70
	v_max_f32_e32 v71, 0, v71
	v_max_f32_e32 v64, 0, v64
	v_max_f32_e32 v65, 0, v65
	v_max_f32_e32 v66, 0, v66
	v_max_f32_e32 v67, 0, v67
	v_mul_f32 v68, v68, v68
	v_mul_f32 v69, v69, v69
	v_mul_f32 v70, v70, v70
	v_mul_f32 v71, v71, v71
	v_mul_f32 v64, v64, v64
	v_mul_f32 v65, v65, v65
	v_mul_f32 v66, v66, v66
	v_mul_f32 v67, v67, v67
	v_cvt_pk_bf16_f32 v64, v64, v65
	v_cvt_pk_bf16_f32 v65, v66, v67
	v_cvt_pk_bf16_f32 v66, v68, v69
	v_cvt_pk_bf16_f32 v67, v70, v71
	flat_store_dwordx4 v[80:81], v[64:67] offset:256
.LBB0_1765:
	s_or_b64 exec, exec, s[42:43]
	s_nop 0
	v_lshlrev_b64 v[64:65], 13, v[146:147]
	v_lshl_add_u64 v[64:65], s[14:15], 0, v[64:65]
	v_lshl_add_u64 v[64:65], v[144:145], 1, v[64:65]
	v_lshl_add_u64 v[64:65], v[64:65], 0, s[22:23]
	s_and_saveexec_b64 s[42:43], vcc
	s_cbranch_execz .LBB0_1767
	v_max_f32_e32 v60, 0, v60
	v_max_f32_e32 v61, 0, v61
	v_max_f32_e32 v62, 0, v62
	v_max_f32_e32 v63, 0, v63
	v_max_f32_e32 v56, 0, v56
	v_max_f32_e32 v57, 0, v57
	v_max_f32_e32 v58, 0, v58
	v_max_f32_e32 v59, 0, v59
	v_mul_f32 v60, v60, v60
	v_mul_f32 v61, v61, v61
	v_mul_f32 v62, v62, v62
	v_mul_f32 v63, v63, v63
	v_mul_f32 v56, v56, v56
	v_mul_f32 v57, v57, v57
	v_mul_f32 v58, v58, v58
	v_mul_f32 v59, v59, v59
	v_cvt_pk_bf16_f32 v56, v56, v57
	v_cvt_pk_bf16_f32 v57, v58, v59
	v_cvt_pk_bf16_f32 v58, v60, v61
	v_cvt_pk_bf16_f32 v59, v62, v63
	flat_store_dwordx4 v[64:65], v[56:59]
.LBB0_1767:
	s_or_b64 exec, exec, s[42:43]
	s_and_saveexec_b64 s[42:43], s[10:11]
	s_cbranch_execz .LBB0_1769
	v_max_f32_e32 v52, 0, v52
	v_max_f32_e32 v53, 0, v53
	v_max_f32_e32 v54, 0, v54
	v_max_f32_e32 v55, 0, v55
	v_max_f32_e32 v48, 0, v48
	v_max_f32_e32 v49, 0, v49
	v_max_f32_e32 v50, 0, v50
	v_max_f32_e32 v51, 0, v51
	v_mul_f32 v52, v52, v52
	v_mul_f32 v53, v53, v53
	v_mul_f32 v54, v54, v54
	v_mul_f32 v55, v55, v55
	v_mul_f32 v48, v48, v48
	v_mul_f32 v49, v49, v49
	v_mul_f32 v50, v50, v50
	v_mul_f32 v51, v51, v51
	v_cvt_pk_bf16_f32 v48, v48, v49
	v_cvt_pk_bf16_f32 v49, v50, v51
	v_cvt_pk_bf16_f32 v50, v52, v53
	v_cvt_pk_bf16_f32 v51, v54, v55
	flat_store_dwordx4 v[64:65], v[48:51] offset:256
.LBB0_1769:
	s_or_b64 exec, exec, s[42:43]
	s_nop 0
	v_lshlrev_b64 v[48:49], 13, v[146:147]
	v_lshl_add_u64 v[48:49], s[14:15], 0, v[48:49]
	v_lshl_add_u64 v[48:49], v[144:145], 1, v[48:49]
	v_lshl_add_u64 v[48:49], v[48:49], 0, s[24:25]
	s_and_saveexec_b64 s[42:43], vcc
	s_cbranch_execz .LBB0_1771
	v_max_f32_e32 v44, 0, v44
	v_max_f32_e32 v45, 0, v45
	v_max_f32_e32 v46, 0, v46
	v_max_f32_e32 v47, 0, v47
	v_max_f32_e32 v40, 0, v40
	v_max_f32_e32 v41, 0, v41
	v_max_f32_e32 v42, 0, v42
	v_max_f32_e32 v43, 0, v43
	v_mul_f32 v44, v44, v44
	v_mul_f32 v45, v45, v45
	v_mul_f32 v46, v46, v46
	v_mul_f32 v47, v47, v47
	v_mul_f32 v40, v40, v40
	v_mul_f32 v41, v41, v41
	v_mul_f32 v42, v42, v42
	v_mul_f32 v43, v43, v43
	v_cvt_pk_bf16_f32 v40, v40, v41
	v_cvt_pk_bf16_f32 v41, v42, v43
	v_cvt_pk_bf16_f32 v42, v44, v45
	v_cvt_pk_bf16_f32 v43, v46, v47
	flat_store_dwordx4 v[48:49], v[40:43]
.LBB0_1771:
	s_or_b64 exec, exec, s[42:43]
	s_and_saveexec_b64 s[42:43], s[10:11]
	s_cbranch_execz .LBB0_1773
	v_max_f32_e32 v36, 0, v36
	v_max_f32_e32 v37, 0, v37
	v_max_f32_e32 v38, 0, v38
	v_max_f32_e32 v39, 0, v39
	v_max_f32_e32 v32, 0, v32
	v_max_f32_e32 v33, 0, v33
	v_max_f32_e32 v34, 0, v34
	v_max_f32_e32 v35, 0, v35
	v_mul_f32 v36, v36, v36
	v_mul_f32 v37, v37, v37
	v_mul_f32 v38, v38, v38
	v_mul_f32 v39, v39, v39
	v_mul_f32 v32, v32, v32
	v_mul_f32 v33, v33, v33
	v_mul_f32 v34, v34, v34
	v_mul_f32 v35, v35, v35
	v_cvt_pk_bf16_f32 v32, v32, v33
	v_cvt_pk_bf16_f32 v33, v34, v35
	v_cvt_pk_bf16_f32 v34, v36, v37
	v_cvt_pk_bf16_f32 v35, v38, v39
	flat_store_dwordx4 v[48:49], v[32:35] offset:256
.LBB0_1773:
	s_or_b64 exec, exec, s[42:43]
	s_nop 0
	v_lshlrev_b64 v[32:33], 13, v[146:147]
	v_lshl_add_u64 v[32:33], s[14:15], 0, v[32:33]
	v_lshl_add_u64 v[32:33], v[144:145], 1, v[32:33]
	v_lshl_add_u64 v[32:33], v[32:33], 0, s[26:27]
	s_and_saveexec_b64 s[42:43], vcc
	s_cbranch_execz .LBB0_1775
	v_max_f32_e32 v28, 0, v28
	v_max_f32_e32 v29, 0, v29
	v_max_f32_e32 v30, 0, v30
	v_max_f32_e32 v31, 0, v31
	v_max_f32_e32 v24, 0, v24
	v_max_f32_e32 v25, 0, v25
	v_max_f32_e32 v26, 0, v26
	v_max_f32_e32 v27, 0, v27
	v_mul_f32 v28, v28, v28
	v_mul_f32 v29, v29, v29
	v_mul_f32 v30, v30, v30
	v_mul_f32 v31, v31, v31
	v_mul_f32 v24, v24, v24
	v_mul_f32 v25, v25, v25
	v_mul_f32 v26, v26, v26
	v_mul_f32 v27, v27, v27
	v_cvt_pk_bf16_f32 v24, v24, v25
	v_cvt_pk_bf16_f32 v25, v26, v27
	v_cvt_pk_bf16_f32 v26, v28, v29
	v_cvt_pk_bf16_f32 v27, v30, v31
	flat_store_dwordx4 v[32:33], v[24:27]
.LBB0_1775:
	s_or_b64 exec, exec, s[42:43]
	s_and_saveexec_b64 s[42:43], s[10:11]
	s_cbranch_execz .LBB0_1777
	v_max_f32_e32 v20, 0, v20
	v_max_f32_e32 v21, 0, v21
	v_max_f32_e32 v22, 0, v22
	v_max_f32_e32 v23, 0, v23
	v_max_f32_e32 v16, 0, v16
	v_max_f32_e32 v17, 0, v17
	v_max_f32_e32 v18, 0, v18
	v_max_f32_e32 v19, 0, v19
	v_mul_f32 v20, v20, v20
	v_mul_f32 v21, v21, v21
	v_mul_f32 v22, v22, v22
	v_mul_f32 v23, v23, v23
	v_mul_f32 v16, v16, v16
	v_mul_f32 v17, v17, v17
	v_mul_f32 v18, v18, v18
	v_mul_f32 v19, v19, v19
	v_cvt_pk_bf16_f32 v16, v16, v17
	v_cvt_pk_bf16_f32 v17, v18, v19
	v_cvt_pk_bf16_f32 v18, v20, v21
	v_cvt_pk_bf16_f32 v19, v22, v23
	flat_store_dwordx4 v[32:33], v[16:19] offset:256
.LBB0_1777:
	s_or_b64 exec, exec, s[42:43]
	s_nop 0
	v_lshlrev_b64 v[16:17], 13, v[146:147]
	v_lshl_add_u64 v[16:17], s[14:15], 0, v[16:17]
	v_lshl_add_u64 v[16:17], v[144:145], 1, v[16:17]
	v_lshl_add_u64 v[16:17], v[16:17], 0, s[28:29]
	s_and_saveexec_b64 s[42:43], vcc
	s_cbranch_execz .LBB0_1779
	v_max_f32_e32 v12, 0, v12
	v_max_f32_e32 v13, 0, v13
	v_max_f32_e32 v14, 0, v14
	v_max_f32_e32 v15, 0, v15
	v_max_f32_e32 v8, 0, v8
	v_max_f32_e32 v9, 0, v9
	v_max_f32_e32 v10, 0, v10
	v_max_f32_e32 v11, 0, v11
	v_mul_f32 v12, v12, v12
	v_mul_f32 v13, v13, v13
	v_mul_f32 v14, v14, v14
	v_mul_f32 v15, v15, v15
	v_mul_f32 v8, v8, v8
	v_mul_f32 v9, v9, v9
	v_mul_f32 v10, v10, v10
	v_mul_f32 v11, v11, v11
	v_cvt_pk_bf16_f32 v8, v8, v9
	v_cvt_pk_bf16_f32 v9, v10, v11
	v_cvt_pk_bf16_f32 v10, v12, v13
	v_cvt_pk_bf16_f32 v11, v14, v15
	flat_store_dwordx4 v[16:17], v[8:11]
.LBB0_1779:
	s_or_b64 exec, exec, s[42:43]
	s_and_saveexec_b64 s[42:43], s[10:11]
	s_cbranch_execz .LBB0_1725
	v_max_f32_e32 v4, 0, v4
	v_max_f32_e32 v5, 0, v5
	v_max_f32_e32 v6, 0, v6
	v_max_f32_e32 v7, 0, v7
	v_max_f32_e32 v0, 0, v0
	v_max_f32_e32 v1, 0, v1
	v_max_f32_e32 v2, 0, v2
	v_max_f32_e32 v3, 0, v3
	v_mul_f32 v4, v4, v4
	v_mul_f32 v5, v5, v5
	v_mul_f32 v6, v6, v6
	v_mul_f32 v7, v7, v7
	v_mul_f32 v0, v0, v0
	v_mul_f32 v1, v1, v1
	v_mul_f32 v2, v2, v2
	v_mul_f32 v3, v3, v3
	v_cvt_pk_bf16_f32 v0, v0, v1
	v_cvt_pk_bf16_f32 v1, v2, v3
	v_cvt_pk_bf16_f32 v2, v4, v5
	v_cvt_pk_bf16_f32 v3, v6, v7
	flat_store_dwordx4 v[16:17], v[0:3] offset:256
	s_branch .LBB0_1725

.LBB0_2073:
	v_ashrrev_i32_e32 v77, 31, v76
	v_lshlrev_b64 v[0:1], 12, v[76:77]
	v_lshl_add_u64 v[104:105], s[18:19], 0, v[0:1]
	v_add_u32_e32 v0, 0xfffff000, v76
	v_lshrrev_b32_e32 v0, 11, v0
	v_add_u32_e32 v0, 1, v0
	v_cmp_lt_i32_e32 vcc, s33, v76
	v_lshl_add_u64 v[8:9], v[104:105], 0, v[78:79]
	flat_load_dwordx4 v[10:13], v[8:9] offset:2048
	flat_load_dwordx4 v[40:43], v[8:9] offset:3072
	v_cndmask_b32_e32 v85, 0, v0, vcc
	v_mad_u64_u32 v[0:1], s[6:7], v85, s34, v[66:67]
	flat_load_dwordx4 v[44:47], v[0:1]
	global_load_dwordx4 v[48:51], v[64:65], off
	global_load_dwordx4 v[52:55], v[64:65], off offset:16
	flat_load_dwordx4 v[92:95], v[0:1] offset:16
	flat_load_dwordx4 v[96:99], v[0:1] offset:2048
	global_load_dwordx4 v[100:103], v[64:65], off offset:2048
	global_load_dwordx4 v[106:109], v[64:65], off offset:2064
	flat_load_dwordx4 v[120:123], v[0:1] offset:2064
	v_lshlrev_b64 v[0:1], 11, v[76:77]
	v_lshl_add_u64 v[0:1], v[62:63], 0, v[0:1]
	flat_load_dwordx4 v[124:127], v[0:1]
	flat_load_dwordx4 v[128:131], v[0:1] offset:1024
	v_add_u32_e32 v0, 1, v76
	v_ashrrev_i32_e32 v1, 31, v0
	v_lshlrev_b64 v[6:7], 12, v[0:1]
	v_lshlrev_b64 v[0:1], 11, v[0:1]
	v_lshl_add_u64 v[0:1], v[62:63], 0, v[0:1]
	flat_load_dwordx4 v[132:135], v[0:1]
	flat_load_dwordx4 v[136:139], v[0:1] offset:1024
	v_add_u32_e32 v2, 2, v76
	v_add_u32_e32 v4, 3, v76
	v_ashrrev_i32_e32 v3, 31, v2
	v_ashrrev_i32_e32 v5, 31, v4
	v_lshlrev_b64 v[14:15], 12, v[2:3]
	v_lshlrev_b64 v[2:3], 11, v[2:3]
	v_lshlrev_b64 v[16:17], 12, v[4:5]
	v_lshlrev_b64 v[4:5], 11, v[4:5]
	v_lshl_add_u64 v[114:115], s[18:19], 0, v[6:7]
	v_lshl_add_u64 v[112:113], s[18:19], 0, v[14:15]
	v_lshl_add_u64 v[2:3], v[62:63], 0, v[2:3]
	v_lshl_add_u64 v[90:91], v[74:75], 0, v[16:17]
	v_lshl_add_u64 v[14:15], v[62:63], 0, v[4:5]
	v_lshl_add_u64 v[116:117], v[114:115], 0, v[78:79]
	v_lshl_add_u64 v[118:119], v[112:113], 0, v[78:79]
	flat_load_dwordx4 v[144:147], v[2:3]
	flat_load_dwordx4 v[152:155], v[2:3] offset:1024
	flat_load_dwordx4 v[20:23], v[90:91] offset:2048
	flat_load_dwordx4 v[16:19], v[90:91] offset:3072
	flat_load_dwordx4 v[4:7], v[14:15]
	s_nop 0
	flat_load_dwordx4 v[0:3], v[14:15] offset:1024
	flat_load_dwordx4 v[36:39], v[116:117] offset:2048
	flat_load_dwordx4 v[32:35], v[116:117] offset:3072
	flat_load_dwordx4 v[28:31], v[118:119] offset:2048
	flat_load_dwordx4 v[24:27], v[118:119] offset:3072
	s_waitcnt vmcnt(0) lgkmcnt(0)
	v_lshlrev_b32_e32 v14, 16, v10
	v_lshlrev_b32_e32 v142, 16, v40
	v_and_b32_e32 v143, 0xffff0000, v40
	v_lshlrev_b32_e32 v148, 16, v41
	v_and_b32_e32 v149, 0xffff0000, v41
	v_mul_f32 v40, v50, v46
	v_mul_f32 v41, v51, v47
	v_lshlrev_b32_e32 v150, 16, v42
	v_and_b32_e32 v151, 0xffff0000, v42
	v_lshlrev_b32_e32 v156, 16, v43
	v_and_b32_e32 v157, 0xffff0000, v43
	v_mul_f32 v42, v48, v44
	v_mul_f32 v43, v49, v45
	v_mul_f32 v48, v102, v98
	v_mul_f32 v49, v103, v99
	v_mul_f32 v98, v80, v40
	v_mul_f32 v99, v81, v41
	v_lshlrev_b32_e32 v40, 16, v124
	v_and_b32_e32 v41, 0xffff0000, v124
	v_mul_f32 v44, v54, v94
	v_mul_f32 v45, v55, v95
	v_mul_f32 v46, v52, v92
	v_mul_f32 v47, v53, v93
	v_mul_f32 v102, v72, v42
	v_mul_f32 v103, v73, v43
	v_lshlrev_b32_e32 v42, 16, v125
	v_and_b32_e32 v43, 0xffff0000, v125
	v_mul_f32 v158, v40, v40
	v_mul_f32 v159, v41, v41
	v_mul_f32 v50, v100, v96
	v_mul_f32 v51, v101, v97
	v_mul_f32 v54, v106, v120
	v_mul_f32 v55, v107, v121
	v_mul_f32 v94, v80, v44
	v_mul_f32 v95, v81, v45
	v_mul_f32 v100, v72, v46
	v_mul_f32 v101, v73, v47
	v_lshlrev_b32_e32 v44, 16, v126
	v_and_b32_e32 v45, 0xffff0000, v126
	v_lshlrev_b32_e32 v46, 16, v127
	v_and_b32_e32 v47, 0xffff0000, v127
	v_lshlrev_b32_e32 v120, 16, v130
	v_and_b32_e32 v121, 0xffff0000, v130
	v_lshlrev_b32_e32 v126, 16, v131
	v_and_b32_e32 v127, 0xffff0000, v131
	v_mul_f32 v130, v42, v42
	v_mul_f32 v131, v43, v43
	v_add_f32_e32 v56, v158, v159
	v_add_f32_e32 v56, v130, v56
	v_mul_f32 v92, v80, v48
	v_mul_f32 v93, v81, v49
	v_mul_f32 v96, v72, v50
	v_mul_f32 v97, v73, v51
	v_lshlrev_b32_e32 v48, 16, v128
	v_and_b32_e32 v49, 0xffff0000, v128
	v_lshlrev_b32_e32 v50, 16, v129
	v_and_b32_e32 v51, 0xffff0000, v129
	v_mul_f32 v128, v44, v44
	v_mul_f32 v129, v45, v45
	v_add_f32_e32 v56, v131, v56
	v_add_f32_e32 v56, v128, v56
	v_mul_f32 v124, v46, v46
	v_mul_f32 v125, v47, v47
	v_add_f32_e32 v56, v129, v56
	v_add_f32_e32 v56, v124, v56
	v_mul_f32 v52, v108, v122
	v_mul_f32 v53, v109, v123
	v_mul_f32 v122, v48, v48
	v_mul_f32 v123, v49, v49
	v_add_f32_e32 v56, v125, v56
	v_add_f32_e32 v56, v122, v56
	v_mul_f32 v110, v50, v50
	v_mul_f32 v111, v51, v51
	v_add_f32_e32 v56, v123, v56
	v_add_f32_e32 v56, v110, v56
	v_mul_f32 v108, v120, v120
	v_mul_f32 v109, v121, v121
	v_add_f32_e32 v56, v111, v56
	v_add_f32_e32 v56, v108, v56
	v_mul_f32 v106, v126, v126
	v_mul_f32 v107, v127, v127
	v_add_f32_e32 v56, v109, v56
	v_add_f32_e32 v56, v106, v56
	v_add_f32_e32 v56, v107, v56
	v_lshlrev_b32_e32 v106, 16, v132
	v_and_b32_e32 v107, 0xffff0000, v132
	v_add_f32_dpp v56, v56, v56 quad_perm:[1,0,3,2] row_mask:0xf bank_mask:0xf bound_ctrl:1
	v_lshlrev_b32_e32 v108, 16, v133
	v_and_b32_e32 v109, 0xffff0000, v133
	v_add_f32_dpp v56, v56, v56 quad_perm:[2,3,0,1] row_mask:0xf bank_mask:0xf bound_ctrl:1
	v_mul_f32 v170, v106, v106
	v_mul_f32 v171, v107, v107
	v_mul_f32 v158, v108, v108
	v_mul_f32 v159, v109, v109
	v_add_f32_dpp v56, v56, v56 row_half_mirror row_mask:0xf bank_mask:0xf bound_ctrl:1
	v_lshlrev_b32_e32 v110, 16, v134
	v_and_b32_e32 v111, 0xffff0000, v134
	v_add_f32_dpp v56, v56, v56 row_mirror row_mask:0xf bank_mask:0xf bound_ctrl:1
	v_mov_b32_e32 v77, v56
	s_nop 1
	v_permlane16_swap_b32_e32 v56, v77
	v_add_f32_e32 v123, v56, v77
	v_add_f32_e32 v56, v170, v171
	v_add_f32_e32 v56, v158, v56
	v_lshlrev_b32_e32 v166, 16, v138
	v_and_b32_e32 v167, 0xffff0000, v138
	v_lshlrev_b32_e32 v168, 16, v139
	v_and_b32_e32 v169, 0xffff0000, v139
	v_mul_f32 v138, v110, v110
	v_mul_f32 v139, v111, v111
	v_add_f32_e32 v56, v159, v56
	v_lshlrev_b32_e32 v160, 16, v135
	v_and_b32_e32 v161, 0xffff0000, v135
	v_add_f32_e32 v56, v138, v56
	v_lshlrev_b32_e32 v162, 16, v136
	v_and_b32_e32 v163, 0xffff0000, v136
	v_lshlrev_b32_e32 v164, 16, v137
	v_and_b32_e32 v165, 0xffff0000, v137
	v_mul_f32 v136, v160, v160
	v_mul_f32 v137, v161, v161
	v_add_f32_e32 v56, v139, v56
	v_add_f32_e32 v56, v136, v56
	v_mul_f32 v134, v162, v162
	v_mul_f32 v135, v163, v163
	v_add_f32_e32 v56, v137, v56
	v_add_f32_e32 v56, v134, v56
	v_mul_f32 v132, v164, v164
	v_mul_f32 v133, v165, v165
	v_add_f32_e32 v56, v135, v56
	v_add_f32_e32 v56, v132, v56
	v_mul_f32 v130, v166, v166
	v_mul_f32 v131, v167, v167
	v_add_f32_e32 v56, v133, v56
	v_add_f32_e32 v56, v130, v56
	v_mul_f32 v128, v168, v168
	v_mul_f32 v129, v169, v169
	v_add_f32_e32 v56, v131, v56
	v_add_f32_e32 v56, v128, v56
	v_add_f32_e32 v56, v129, v56
	v_mov_b32_e32 v125, v123
	s_nop 1
	v_permlane32_swap_b32_e32 v123, v125
	v_add_f32_dpp v56, v56, v56 quad_perm:[1,0,3,2] row_mask:0xf bank_mask:0xf bound_ctrl:1
	v_and_b32_e32 v15, 0xffff0000, v10
	v_lshlrev_b32_e32 v10, 16, v11
	v_add_f32_dpp v56, v56, v56 quad_perm:[2,3,0,1] row_mask:0xf bank_mask:0xf bound_ctrl:1
	v_and_b32_e32 v11, 0xffff0000, v11
	v_lshlrev_b32_e32 v140, 16, v12
	v_add_f32_dpp v56, v56, v56 row_half_mirror row_mask:0xf bank_mask:0xf bound_ctrl:1
	v_and_b32_e32 v141, 0xffff0000, v12
	v_lshlrev_b32_e32 v12, 16, v13
	v_add_f32_dpp v56, v56, v56 row_mirror row_mask:0xf bank_mask:0xf bound_ctrl:1
	v_mov_b32_e32 v77, v56
	s_nop 1
	v_permlane16_swap_b32_e32 v56, v77
	v_add_f32_e32 v122, v56, v77
	v_mov_b32_e32 v124, v122
	s_nop 1
	v_permlane32_swap_b32_e32 v122, v124
	v_add_f32 v122, v122, v124
	v_add_f32 v123, v123, v125
	v_mul_f32 v124, v72, v54
	v_mul_f32 v125, v73, v55
	v_fma_f32 v170, v122, s26, v82
	v_fma_f32 v171, v123, s26, v82
	v_mul_f32 v122, v80, v52
	v_mul_f32 v123, v81, v53
	v_mul_f32_e32 v56, 0x4b800000, v171
	v_cmp_gt_f32_e32 vcc, s35, v171
	v_and_b32_e32 v13, 0xffff0000, v13
	v_lshlrev_b32_e32 v136, 16, v1
	v_cndmask_b32_e32 v56, v171, v56, vcc
	v_rsq_f32_e32 v56, v56
	v_and_b32_e32 v137, 0xffff0000, v1
	v_lshlrev_b32_e32 v138, 16, v2
	v_and_b32_e32 v139, 0xffff0000, v2
	v_mul_f32_e32 v52, 0x45800000, v56
	v_cndmask_b32_e32 v54, v56, v52, vcc
	v_mul_f32 v40, v54, v40
	v_mul_f32 v41, v54, v41
	v_fma_f32 v40, v102, v40, v14
	v_fma_f32 v41, v103, v41, v15
	v_mul_f32 v14, v54, v42
	v_mul_f32 v15, v54, v43
	v_fma_f32 v42, v98, v14, v10
	v_fma_f32 v43, v99, v15, v11
	v_mul_f32 v10, v54, v44
	v_mul_f32 v11, v54, v45
	v_fma_f32 v44, v100, v10, v140
	v_fma_f32 v45, v101, v11, v141
	v_mul_f32 v10, v54, v46
	v_mul_f32 v11, v54, v47
	v_fma_f32 v46, v94, v10, v12
	v_fma_f32 v47, v95, v11, v13
	v_mul_f32 v10, v54, v48
	v_mul_f32 v11, v54, v49
	v_fma_f32 v48, v96, v10, v142
	v_fma_f32 v49, v97, v11, v143
	v_mul_f32 v10, v54, v50
	v_mul_f32 v11, v54, v51
	v_fma_f32 v50, v92, v10, v148
	v_fma_f32 v51, v93, v11, v149
	v_mul_f32 v10, v54, v120
	v_mul_f32 v11, v54, v121
	v_lshlrev_b32_e32 v120, 16, v144
	v_and_b32_e32 v121, 0xffff0000, v144
	v_lshlrev_b32_e32 v142, 16, v145
	v_and_b32_e32 v143, 0xffff0000, v145
	v_mul_f32 v134, v120, v120
	v_mul_f32 v135, v121, v121
	v_mul_f32 v132, v142, v142
	v_mul_f32 v133, v143, v143
	v_add_f32_e32 v56, v134, v135
	v_lshlrev_b32_e32 v144, 16, v146
	v_and_b32_e32 v145, 0xffff0000, v146
	v_add_f32_e32 v56, v132, v56
	v_mul_f32 v130, v144, v144
	v_mul_f32 v131, v145, v145
	v_add_f32_e32 v56, v133, v56
	v_lshlrev_b32_e32 v146, 16, v147
	v_and_b32_e32 v147, 0xffff0000, v147
	v_add_f32_e32 v56, v130, v56
	v_mul_f32 v128, v146, v146
	v_mul_f32 v129, v147, v147
	v_add_f32_e32 v56, v131, v56
	v_lshlrev_b32_e32 v148, 16, v152
	v_and_b32_e32 v149, 0xffff0000, v152
	v_add_f32_e32 v56, v128, v56
	v_fma_f32 v52, v124, v10, v150
	v_fma_f32 v53, v125, v11, v151
	v_mul_f32 v10, v54, v126
	v_mul_f32 v11, v54, v127
	v_mul_f32 v126, v148, v148
	v_mul_f32 v127, v149, v149
	v_add_f32_e32 v56, v129, v56
	v_lshlrev_b32_e32 v150, 16, v153
	v_and_b32_e32 v151, 0xffff0000, v153
	v_add_f32_e32 v56, v126, v56
	v_mul_f32 v14, v150, v150
	v_mul_f32 v15, v151, v151
	v_add_f32_e32 v56, v127, v56
	v_lshlrev_b32_e32 v152, 16, v154
	v_and_b32_e32 v153, 0xffff0000, v154
	v_add_f32_e32 v14, v14, v56
	v_mul_f32 v12, v152, v152
	v_mul_f32 v13, v153, v153
	v_add_f32_e32 v14, v15, v14
	v_lshlrev_b32_e32 v154, 16, v155
	v_and_b32_e32 v155, 0xffff0000, v155
	v_add_f32_e32 v12, v12, v14
	v_fma_f32 v54, v122, v10, v156
	v_fma_f32 v55, v123, v11, v157
	v_mul_f32 v10, v154, v154
	v_mul_f32 v11, v155, v155
	v_add_f32_e32 v12, v13, v12
	v_add_f32_e32 v10, v10, v12
	v_add_f32_e32 v10, v11, v10
	v_lshlrev_b32_e32 v126, 16, v4
	v_and_b32_e32 v127, 0xffff0000, v4
	v_add_f32_dpp v10, v10, v10 quad_perm:[1,0,3,2] row_mask:0xf bank_mask:0xf bound_ctrl:1
	v_lshlrev_b32_e32 v128, 16, v5
	v_and_b32_e32 v129, 0xffff0000, v5
	v_add_f32_dpp v10, v10, v10 quad_perm:[2,3,0,1] row_mask:0xf bank_mask:0xf bound_ctrl:1
	v_mul_f32 v176, v126, v126
	v_mul_f32 v177, v127, v127
	v_mul_f32 v14, v128, v128
	v_mul_f32 v15, v129, v129
	v_add_f32_dpp v10, v10, v10 row_half_mirror row_mask:0xf bank_mask:0xf bound_ctrl:1
	v_add_f32_e32 v56, v176, v177
	v_lshlrev_b32_e32 v130, 16, v6
	v_add_f32_dpp v10, v10, v10 row_mirror row_mask:0xf bank_mask:0xf bound_ctrl:1
	v_and_b32_e32 v131, 0xffff0000, v6
	v_add_f32_e32 v14, v14, v56
	v_mov_b32_e32 v11, v10
	v_mul_f32 v12, v130, v130
	v_mul_f32 v13, v131, v131
	v_add_f32_e32 v14, v15, v14
	v_permlane16_swap_b32_e32 v10, v11
	v_lshlrev_b32_e32 v132, 16, v7
	v_and_b32_e32 v133, 0xffff0000, v7
	v_add_f32_e32 v12, v12, v14
	v_add_f32_e32 v157, v10, v11
	v_mul_f32 v10, v132, v132
	v_mul_f32 v11, v133, v133
	v_add_f32_e32 v12, v13, v12
	v_lshlrev_b32_e32 v134, 16, v0
	v_and_b32_e32 v135, 0xffff0000, v0
	v_add_f32_e32 v10, v10, v12
	v_mul_f32 v6, v134, v134
	v_mul_f32 v7, v135, v135
	v_add_f32_e32 v10, v11, v10
	v_add_f32_e32 v6, v6, v10
	v_mul_f32 v4, v136, v136
	v_mul_f32 v5, v137, v137
	v_add_f32_e32 v6, v7, v6
	v_add_f32_e32 v4, v4, v6
	v_lshlrev_b32_e32 v140, 16, v3
	v_and_b32_e32 v141, 0xffff0000, v3
	v_mul_f32 v2, v138, v138
	v_mul_f32 v3, v139, v139
	v_add_f32_e32 v4, v5, v4
	v_add_f32_e32 v2, v2, v4
	v_mul_f32 v0, v140, v140
	v_mul_f32 v1, v141, v141
	v_add_f32_e32 v2, v3, v2
	v_add_f32_e32 v0, v0, v2
	v_add_f32_e32 v0, v1, v0
	v_mov_b32_e32 v159, v157
	v_cmp_gt_f32_e64 s[6:7], s35, v170
	v_add_f32_dpp v0, v0, v0 quad_perm:[1,0,3,2] row_mask:0xf bank_mask:0xf bound_ctrl:1
	v_permlane32_swap_b32_e32 v157, v159
	s_nop 0
	v_add_f32_dpp v0, v0, v0 quad_perm:[2,3,0,1] row_mask:0xf bank_mask:0xf bound_ctrl:1
	s_and_b64 vcc, exec, s[22:23]
	s_nop 0
	v_add_f32_dpp v0, v0, v0 row_half_mirror row_mask:0xf bank_mask:0xf bound_ctrl:1
	s_nop 1
	v_add_f32_dpp v0, v0, v0 row_mirror row_mask:0xf bank_mask:0xf bound_ctrl:1
	v_mov_b32_e32 v1, v0
	s_nop 1
	v_permlane16_swap_b32_e32 v0, v1
	v_add_f32_e32 v156, v0, v1
	v_mov_b32_e32 v158, v156
	s_nop 1
	v_permlane32_swap_b32_e32 v156, v158
	s_cbranch_vccz .LBB0_2088
	v_cvt_pk_bf16_f32 v0, v40, v41
	v_cvt_pk_bf16_f32 v1, v42, v43
	v_cvt_pk_bf16_f32 v2, v44, v45
	v_cvt_pk_bf16_f32 v3, v46, v47
	v_cvt_pk_bf16_f32 v176, v48, v49
	v_cvt_pk_bf16_f32 v177, v50, v51
	v_cvt_pk_bf16_f32 v178, v52, v53
	v_cvt_pk_bf16_f32 v179, v54, v55
	flat_store_dwordx4 v[8:9], v[0:3] offset:2048
	v_lshlrev_b32_e32 v4, 16, v0
	v_and_b32_e32 v5, 0xffff0000, v0
	v_lshlrev_b32_e32 v6, 16, v1
	v_and_b32_e32 v7, 0xffff0000, v1
	v_lshlrev_b32_e32 v12, 16, v2
	v_and_b32_e32 v13, 0xffff0000, v2
	v_lshlrev_b32_e32 v14, 16, v3
	v_and_b32_e32 v15, 0xffff0000, v3
	flat_store_dwordx4 v[8:9], v[176:179] offset:3072
	v_lshlrev_b32_e32 v0, 16, v176
	v_and_b32_e32 v1, 0xffff0000, v176
	v_lshlrev_b32_e32 v2, 16, v177
	v_and_b32_e32 v3, 0xffff0000, v177
	v_lshlrev_b32_e32 v8, 16, v178
	v_and_b32_e32 v9, 0xffff0000, v178
	v_lshlrev_b32_e32 v10, 16, v179
	v_and_b32_e32 v11, 0xffff0000, v179
	v_lshlrev_b32_e32 v56, 2, v58
	s_cbranch_execnz .LBB0_2076

.LBB0_2076:
	v_mul_f32_e32 v44, 0x4b800000, v170
	v_cndmask_b32_e64 v44, v170, v44, s[6:7]
	v_rsq_f32_e32 v44, v44
	v_lshlrev_b32_e32 v40, 16, v36
	v_and_b32_e32 v41, 0xffff0000, v36
	v_lshlrev_b32_e32 v36, 16, v37
	v_mul_f32_e32 v45, 0x45800000, v44
	v_cndmask_b32_e64 v52, v44, v45, s[6:7]
	v_mul_f32 v44, v52, v106
	v_mul_f32 v45, v52, v107
	v_and_b32_e32 v37, 0xffff0000, v37
	v_fma_f32 v44, v102, v44, v40
	v_fma_f32 v45, v103, v45, v41
	v_mul_f32 v40, v52, v108
	v_mul_f32 v41, v52, v109
	v_lshlrev_b32_e32 v42, 16, v38
	v_and_b32_e32 v43, 0xffff0000, v38
	v_fma_f32 v46, v98, v40, v36
	v_fma_f32 v47, v99, v41, v37
	v_mul_f32 v36, v52, v110
	v_mul_f32 v37, v52, v111
	v_lshlrev_b32_e32 v38, 16, v39
	v_and_b32_e32 v39, 0xffff0000, v39
	v_fma_f32 v40, v100, v36, v42
	v_fma_f32 v41, v101, v37, v43
	v_mul_f32 v36, v52, v160
	v_mul_f32 v37, v52, v161
	v_lshlrev_b32_e32 v48, 16, v32
	v_and_b32_e32 v49, 0xffff0000, v32
	v_lshlrev_b32_e32 v32, 16, v33
	v_and_b32_e32 v33, 0xffff0000, v33
	v_fma_f32 v42, v94, v36, v38
	v_fma_f32 v43, v95, v37, v39
	v_mul_f32 v38, v52, v164
	v_mul_f32 v39, v52, v165
	v_lshlrev_b32_e32 v50, 16, v34
	v_and_b32_e32 v51, 0xffff0000, v34
	v_mul_f32 v36, v52, v162
	v_mul_f32 v37, v52, v163
	v_fma_f32 v38, v92, v38, v32
	v_fma_f32 v39, v93, v39, v33
	v_mul_f32 v32, v52, v166
	v_mul_f32 v33, v52, v167
	v_lshlrev_b32_e32 v34, 16, v35
	v_and_b32_e32 v35, 0xffff0000, v35
	v_fma_f32 v36, v96, v36, v48
	v_fma_f32 v37, v97, v37, v49
	v_fma_f32 v32, v124, v32, v50
	v_fma_f32 v33, v125, v33, v51
	v_mul_f32 v48, v52, v168
	v_mul_f32 v49, v52, v169
	v_cndmask_b32_e64 v50, 0, 1, s[22:23]
	v_cmp_ne_u32_e64 s[6:7], 1, v50
	s_andn2_b64 vcc, exec, s[22:23]
	v_fma_f32 v34, v122, v48, v34
	v_fma_f32 v35, v123, v49, v35
	s_cbranch_vccnz .LBB0_2089
	v_cvt_pk_bf16_f32 v48, v44, v45
	v_cvt_pk_bf16_f32 v49, v46, v47
	v_cvt_pk_bf16_f32 v50, v40, v41
	v_cvt_pk_bf16_f32 v51, v42, v43
	v_cvt_pk_bf16_f32 v160, v36, v37
	v_cvt_pk_bf16_f32 v161, v38, v39
	v_cvt_pk_bf16_f32 v162, v32, v33
	v_cvt_pk_bf16_f32 v163, v34, v35
	flat_store_dwordx4 v[116:117], v[48:51] offset:2048
	v_lshlrev_b32_e32 v110, 16, v48
	v_and_b32_e32 v111, 0xffff0000, v48
	v_lshlrev_b32_e32 v106, 16, v49
	v_and_b32_e32 v107, 0xffff0000, v49
	v_lshlrev_b32_e32 v108, 16, v50
	v_and_b32_e32 v109, 0xffff0000, v50
	v_lshlrev_b32_e32 v104, 16, v51
	v_and_b32_e32 v105, 0xffff0000, v51
	v_lshlrev_b32_e32 v54, 16, v160
	v_and_b32_e32 v55, 0xffff0000, v160
	v_lshlrev_b32_e32 v50, 16, v161
	v_and_b32_e32 v51, 0xffff0000, v161
	v_lshlrev_b32_e32 v52, 16, v162
	v_and_b32_e32 v53, 0xffff0000, v162
	v_lshlrev_b32_e32 v48, 16, v163
	v_and_b32_e32 v49, 0xffff0000, v163
	flat_store_dwordx4 v[116:117], v[160:163] offset:3072
	s_cbranch_execnz .LBB0_2079

.LBB0_2079:
	v_add_f32 v36, v156, v158
	v_add_f32 v37, v157, v159
	v_lshlrev_b32_e32 v42, 16, v26
	v_fma_f32 v156, v36, s26, v82
	v_fma_f32 v157, v37, s26, v82
	v_and_b32_e32 v43, 0xffff0000, v26
	v_mul_f32_e32 v26, 0x4b800000, v157
	v_cmp_gt_f32_e32 vcc, s35, v157
	v_lshlrev_b32_e32 v32, 16, v28
	v_and_b32_e32 v33, 0xffff0000, v28
	v_cndmask_b32_e32 v26, v157, v26, vcc
	v_rsq_f32_e32 v36, v26
	v_lshlrev_b32_e32 v28, 16, v29
	v_and_b32_e32 v29, 0xffff0000, v29
	v_lshlrev_b32_e32 v34, 16, v30
	v_mul_f32_e32 v37, 0x45800000, v36
	v_cndmask_b32_e32 v44, v36, v37, vcc
	v_mul_f32 v36, v44, v120
	v_mul_f32 v37, v44, v121
	v_fma_f32 v36, v102, v36, v32
	v_fma_f32 v37, v103, v37, v33
	v_mul_f32 v32, v44, v142
	v_mul_f32 v33, v44, v143
	v_and_b32_e32 v35, 0xffff0000, v30
	v_fma_f32 v38, v98, v32, v28
	v_fma_f32 v39, v99, v33, v29
	v_mul_f32 v28, v44, v144
	v_mul_f32 v29, v44, v145
	v_lshlrev_b32_e32 v30, 16, v31
	v_and_b32_e32 v31, 0xffff0000, v31
	v_fma_f32 v32, v100, v28, v34
	v_fma_f32 v33, v101, v29, v35
	v_mul_f32 v28, v44, v146
	v_mul_f32 v29, v44, v147
	v_lshlrev_b32_e32 v40, 16, v24
	v_and_b32_e32 v41, 0xffff0000, v24
	v_lshlrev_b32_e32 v24, 16, v25
	v_and_b32_e32 v25, 0xffff0000, v25
	v_fma_f32 v34, v94, v28, v30
	v_fma_f32 v35, v95, v29, v31
	v_mul_f32 v28, v44, v148
	v_mul_f32 v29, v44, v149
	v_mul_f32 v30, v44, v150
	v_mul_f32 v31, v44, v151
	v_lshlrev_b32_e32 v26, 16, v27
	v_and_b32_e32 v27, 0xffff0000, v27
	v_fma_f32 v28, v96, v28, v40
	v_fma_f32 v29, v97, v29, v41
	v_fma_f32 v30, v92, v30, v24
	v_fma_f32 v31, v93, v31, v25
	v_mul_f32 v24, v44, v152
	v_mul_f32 v25, v44, v153
	v_mul_f32 v40, v44, v154
	v_mul_f32 v41, v44, v155
	v_cmp_gt_f32_e64 s[8:9], s35, v156
	v_fma_f32 v24, v124, v24, v42
	v_fma_f32 v25, v125, v25, v43
	s_and_b64 vcc, exec, s[6:7]
	v_fma_f32 v26, v122, v40, v26
	v_fma_f32 v27, v123, v41, v27
	s_cbranch_vccnz .LBB0_2090
	v_cvt_pk_bf16_f32 v42, v36, v37
	v_cvt_pk_bf16_f32 v43, v38, v39
	v_cvt_pk_bf16_f32 v44, v32, v33
	v_cvt_pk_bf16_f32 v45, v34, v35
	v_cvt_pk_bf16_f32 v142, v28, v29
	v_cvt_pk_bf16_f32 v143, v30, v31
	v_cvt_pk_bf16_f32 v144, v24, v25
	v_cvt_pk_bf16_f32 v145, v26, v27
	flat_store_dwordx4 v[118:119], v[42:45] offset:2048
	v_lshlrev_b32_e32 v116, 16, v42
	v_and_b32_e32 v117, 0xffff0000, v42
	v_lshlrev_b32_e32 v42, 16, v43
	v_and_b32_e32 v43, 0xffff0000, v43
	v_lshlrev_b32_e32 v120, 16, v44
	v_and_b32_e32 v121, 0xffff0000, v44
	v_lshlrev_b32_e32 v114, 16, v45
	v_and_b32_e32 v115, 0xffff0000, v45
	flat_store_dwordx4 v[118:119], v[142:145] offset:3072
	v_lshlrev_b32_e32 v46, 16, v142
	v_and_b32_e32 v47, 0xffff0000, v142
	v_lshlrev_b32_e32 v40, 16, v143
	v_and_b32_e32 v41, 0xffff0000, v143
	v_lshlrev_b32_e32 v118, 16, v144
	v_and_b32_e32 v119, 0xffff0000, v144
	v_lshlrev_b32_e32 v44, 16, v145
	v_and_b32_e32 v45, 0xffff0000, v145
	s_cbranch_execnz .LBB0_2082

.LBB0_2082:
	v_mul_f32_e32 v28, 0x4b800000, v156
	v_cndmask_b32_e64 v28, v156, v28, s[8:9]
	v_rsq_f32_e32 v28, v28
	v_lshlrev_b32_e32 v24, 16, v20
	v_and_b32_e32 v25, 0xffff0000, v20
	v_lshlrev_b32_e32 v20, 16, v21
	v_mul_f32_e32 v29, 0x45800000, v28
	v_cndmask_b32_e64 v36, v28, v29, s[8:9]
	v_mul_f32 v28, v36, v126
	v_mul_f32 v29, v36, v127
	v_and_b32_e32 v21, 0xffff0000, v21
	v_fma_f32 v28, v102, v28, v24
	v_fma_f32 v29, v103, v29, v25
	v_mul_f32 v24, v36, v128
	v_mul_f32 v25, v36, v129
	v_lshlrev_b32_e32 v26, 16, v22
	v_and_b32_e32 v27, 0xffff0000, v22
	v_fma_f32 v30, v98, v24, v20
	v_fma_f32 v31, v99, v25, v21
	v_mul_f32 v20, v36, v130
	v_mul_f32 v21, v36, v131
	v_lshlrev_b32_e32 v22, 16, v23
	v_and_b32_e32 v23, 0xffff0000, v23
	v_fma_f32 v24, v100, v20, v26
	v_fma_f32 v25, v101, v21, v27
	v_mul_f32 v20, v36, v132
	v_mul_f32 v21, v36, v133
	v_lshlrev_b32_e32 v32, 16, v16
	v_and_b32_e32 v33, 0xffff0000, v16
	v_lshlrev_b32_e32 v16, 16, v17
	v_and_b32_e32 v17, 0xffff0000, v17
	v_fma_f32 v26, v94, v20, v22
	v_fma_f32 v27, v95, v21, v23
	v_mul_f32 v20, v36, v134
	v_mul_f32 v21, v36, v135
	v_mul_f32 v22, v36, v136
	v_mul_f32 v23, v36, v137
	v_lshlrev_b32_e32 v34, 16, v18
	v_and_b32_e32 v35, 0xffff0000, v18
	v_lshlrev_b32_e32 v18, 16, v19
	v_and_b32_e32 v19, 0xffff0000, v19
	v_fma_f32 v20, v96, v20, v32
	v_fma_f32 v21, v97, v21, v33
	v_fma_f32 v22, v92, v22, v16
	v_fma_f32 v23, v93, v23, v17
	v_mul_f32 v16, v36, v138
	v_mul_f32 v17, v36, v139
	v_mul_f32 v32, v36, v140
	v_mul_f32 v33, v36, v141
	v_fma_f32 v16, v124, v16, v34
	v_fma_f32 v17, v125, v17, v35
	s_and_b64 vcc, exec, s[6:7]
	v_fma_f32 v18, v122, v32, v18
	v_fma_f32 v19, v123, v33, v19
	s_cbranch_vccnz .LBB0_2091
	v_cvt_pk_bf16_f32 v32, v28, v29
	v_cvt_pk_bf16_f32 v33, v30, v31
	v_cvt_pk_bf16_f32 v34, v24, v25
	v_cvt_pk_bf16_f32 v35, v26, v27
	v_cvt_pk_bf16_f32 v100, v20, v21
	v_cvt_pk_bf16_f32 v101, v22, v23
	v_cvt_pk_bf16_f32 v102, v16, v17
	v_cvt_pk_bf16_f32 v103, v18, v19
	flat_store_dwordx4 v[90:91], v[32:35] offset:2048
	v_lshlrev_b32_e32 v98, 16, v32
	v_and_b32_e32 v99, 0xffff0000, v32
	v_lshlrev_b32_e32 v94, 16, v33
	v_and_b32_e32 v95, 0xffff0000, v33
	v_lshlrev_b32_e32 v96, 16, v34
	v_and_b32_e32 v97, 0xffff0000, v34
	v_lshlrev_b32_e32 v92, 16, v35
	v_and_b32_e32 v93, 0xffff0000, v35
	v_lshlrev_b32_e32 v38, 16, v100
	v_and_b32_e32 v39, 0xffff0000, v100
	v_lshlrev_b32_e32 v34, 16, v101
	v_and_b32_e32 v35, 0xffff0000, v101
	v_lshlrev_b32_e32 v36, 16, v102
	v_and_b32_e32 v37, 0xffff0000, v102
	v_lshlrev_b32_e32 v32, 16, v103
	v_and_b32_e32 v33, 0xffff0000, v103
	flat_store_dwordx4 v[90:91], v[100:103] offset:3072
	s_cbranch_execnz .LBB0_2085

.LBB0_2085:
	s_and_b64 vcc, exec, s[6:7]
	s_cbranch_vccnz .LBB0_2072
	v_add_u32_e32 v18, 5, v85
	v_mov_b64_e32 v[16:17], s[20:21]
	v_mad_u64_u32 v[16:17], s[6:7], v18, s34, v[16:17]
	v_lshl_add_u64 v[18:19], v[16:17], 0, s[24:25]
	v_lshl_add_u64 v[20:21], v[18:19], 0, v[56:57]
	v_mov_b32_e32 v85, v57
	flat_load_dwordx4 v[100:103], v[20:21]
	v_lshl_add_u64 v[20:21], v[18:19], 0, v[84:85]
	v_mov_b32_e32 v87, v57
	flat_load_dwordx4 v[122:125], v[20:21]
	v_lshl_add_u64 v[20:21], v[18:19], 0, v[86:87]
	v_mov_b32_e32 v89, v57
	flat_load_dwordx4 v[126:129], v[20:21]
	v_lshl_add_u64 v[18:19], v[18:19], 0, v[88:89]
	flat_load_dwordx4 v[130:133], v[18:19]
	global_load_dwordx4 v[134:137], v[68:69], off
	global_load_dwordx4 v[138:141], v[68:69], off offset:16
	global_load_dwordx4 v[142:145], v[70:71], off
	global_load_dwordx4 v[146:149], v[70:71], off offset:16
	v_lshl_add_u64 v[16:17], v[16:17], 0, v[56:57]
	flat_load_dwordx4 v[20:23], v[16:17] offset:2048
	flat_load_dwordx4 v[28:31], v[16:17]
	flat_load_dwordx4 v[24:27], v[16:17] offset:16
	v_mul_f32_e32 v77, v5, v5
	flat_load_dwordx4 v[16:19], v[16:17] offset:2064
	v_mul_f32_e32 v85, v13, v13
	v_mul_f32_e32 v87, v1, v1
	v_fmac_f32_e32 v77, v4, v4
	v_fmac_f32_e32 v85, v12, v12
	v_mul_f32_e32 v89, v9, v9
	v_fmac_f32_e32 v87, v0, v0
	v_fmac_f32_e32 v77, v6, v6
	v_fmac_f32_e32 v85, v14, v14
	v_fmac_f32_e32 v89, v8, v8
	v_fmac_f32_e32 v87, v2, v2
	v_fmac_f32_e32 v77, v7, v7
	v_fmac_f32_e32 v85, v15, v15
	v_fmac_f32_e32 v89, v10, v10
	v_fmac_f32_e32 v87, v3, v3
	v_add_f32_e32 v56, v85, v77
	v_fmac_f32_e32 v89, v11, v11
	v_add_f32_e32 v56, v87, v56
	v_add_f32_e32 v56, v89, v56
	v_mul_f32_e32 v90, v111, v111
	v_mul_f32_e32 v91, v109, v109
	v_add_f32_dpp v56, v56, v56 quad_perm:[1,0,3,2] row_mask:0xf bank_mask:0xf bound_ctrl:1
	v_mul_f32_e32 v112, v55, v55
	v_fmac_f32_e32 v90, v110, v110
	v_fmac_f32_e32 v91, v108, v108
	v_add_f32_dpp v56, v56, v56 quad_perm:[2,3,0,1] row_mask:0xf bank_mask:0xf bound_ctrl:1
	v_mul_f32_e32 v150, v53, v53
	v_fmac_f32_e32 v112, v54, v54
	v_fmac_f32_e32 v90, v106, v106
	v_fmac_f32_e32 v91, v104, v104
	v_add_f32_dpp v56, v56, v56 row_half_mirror row_mask:0xf bank_mask:0xf bound_ctrl:1
	v_fmac_f32_e32 v150, v52, v52
	v_fmac_f32_e32 v112, v50, v50
	v_fmac_f32_e32 v90, v107, v107
	v_fmac_f32_e32 v91, v105, v105
	v_add_f32_dpp v56, v56, v56 row_mirror row_mask:0xf bank_mask:0xf bound_ctrl:1
	v_fmac_f32_e32 v112, v51, v51
	v_add_f32_e32 v77, v90, v91
	v_mov_b32_e32 v85, v56
	v_fmac_f32_e32 v150, v48, v48
	v_add_f32_e32 v77, v77, v112
	v_permlane16_swap_b32_e32 v56, v85
	v_fmac_f32_e32 v150, v49, v49
	v_add_f32_e32 v151, v56, v85
	v_add_f32_e32 v56, v77, v150
	v_mov_b32_e32 v153, v151
	s_nop 1
	v_permlane32_swap_b32_e32 v151, v153
	v_add_f32_dpp v56, v56, v56 quad_perm:[1,0,3,2] row_mask:0xf bank_mask:0xf bound_ctrl:1
	v_add_u32_e32 v85, 0xffffe800, v83
	s_waitcnt vmcnt(0) lgkmcnt(0)
	v_add_f32 v90, v102, 1.0
	v_add_f32 v91, v103, 1.0
	v_add_f32_dpp v56, v56, v56 quad_perm:[2,3,0,1] row_mask:0xf bank_mask:0xf bound_ctrl:1
	v_add_f32 v100, v100, 1.0
	v_add_f32 v101, v101, 1.0
	v_add_f32 v132, v132, 1.0
	v_add_f32 v133, v133, 1.0
	v_add_f32_dpp v56, v56, v56 row_half_mirror row_mask:0xf bank_mask:0xf bound_ctrl:1
	v_add_f32 v102, v124, 1.0
	v_add_f32 v103, v125, 1.0
	v_add_f32 v128, v128, 1.0
	v_add_f32 v129, v129, 1.0
	v_add_f32_dpp v56, v56, v56 row_mirror row_mask:0xf bank_mask:0xf bound_ctrl:1
	v_mov_b32_e32 v77, v56
	s_nop 1
	v_permlane16_swap_b32_e32 v56, v77
	v_add_f32_e32 v150, v56, v77
	v_mov_b32_e32 v152, v150
	s_nop 1
	v_permlane32_swap_b32_e32 v150, v152
	v_add_f32 v124, v122, 1.0
	v_add_f32 v125, v123, 1.0
	v_add_f32 v154, v126, 1.0
	v_add_f32 v155, v127, 1.0
	v_mul_f32 v122, v136, v90
	v_mul_f32 v123, v137, v91
	v_mul_f32 v126, v134, v100
	v_mul_f32 v127, v135, v101
	v_mul_f32 v100, v144, v128
	v_mul_f32 v101, v145, v129
	v_mul_f32 v90, v148, v132
	v_mul_f32 v91, v149, v133
	v_add_f32 v128, v150, v152
	v_add_f32 v129, v151, v153
	v_mov_b64_e32 v[132:133], s[28:29]
	v_fma_f32 v134, v128, s26, v132
	v_fma_f32 v135, v129, s26, v132
	v_mul_f32 v112, v140, v102
	v_mul_f32 v113, v141, v103
	v_mul_f32_e32 v56, 0x4b800000, v135
	v_cmp_gt_f32_e32 vcc, s35, v135
	v_mul_f32 v102, v142, v154
	v_mul_f32 v103, v143, v155
	v_mul_f32 v124, v138, v124
	v_mul_f32 v125, v139, v125
	v_cndmask_b32_e32 v56, v135, v56, vcc
	v_rsq_f32_e32 v56, v56
	v_add_u32_e32 v77, 0xffffe400, v83
	v_add_f32 v130, v130, 1.0
	v_add_f32 v131, v131, 1.0
	v_mul_f32_e32 v87, 0x45800000, v56
	v_cndmask_b32_e32 v56, v56, v87, vcc
	v_mul_f32 v0, v0, v56
	v_mul_f32 v1, v1, v56
	v_mul_f32 v2, v2, v56
	v_mul_f32 v3, v3, v56
	v_mul_f32 v4, v4, v56
	v_mul_f32 v5, v5, v56
	v_mul_f32 v12, v12, v56
	v_mul_f32 v13, v13, v56
	v_mul_f32 v6, v6, v56
	v_mul_f32 v7, v7, v56
	v_mul_f32 v14, v14, v56
	v_mul_f32 v15, v15, v56
	v_fma_f32 v0, v102, v0, v20
	v_fma_f32 v1, v103, v1, v21
	v_fma_f32 v2, v100, v2, v22
	v_fma_f32 v3, v101, v3, v23
	v_fma_f32 v4, v126, v4, v28
	v_fma_f32 v5, v127, v5, v29
	v_fma_f32 v12, v124, v12, v24
	v_fma_f32 v13, v125, v13, v25
	v_fma_f32 v6, v122, v6, v30
	v_fma_f32 v7, v123, v7, v31
	v_fma_f32 v14, v112, v14, v26
	v_fma_f32 v15, v113, v15, v27
	v_cvt_pk_bf16_f32 v0, v0, v1
	v_cvt_pk_bf16_f32 v1, v2, v3
	v_mul_f32_e32 v2, 0x4b800000, v134
	v_cmp_gt_f32_e32 vcc, s35, v134
	v_cvt_pk_bf16_f32 v4, v4, v5
	v_cvt_pk_bf16_f32 v5, v6, v7
	v_cvt_pk_bf16_f32 v6, v12, v13
	v_cvt_pk_bf16_f32 v7, v14, v15
	v_cndmask_b32_e32 v2, v134, v2, vcc
	buffer_store_dwordx4 v[4:7], v77, s[12:15], 0 offen sc1
	v_mul_f32 v128, v146, v130
	v_mul_f32 v129, v147, v131
	v_add_u32_e32 v12, 0xfffff800, v83
	v_mul_f32 v4, v8, v56
	v_mul_f32 v5, v9, v56
	v_rsq_f32_e32 v8, v2
	v_mul_f32 v6, v10, v56
	v_mul_f32 v7, v11, v56
	v_fma_f32 v4, v128, v4, v16
	v_fma_f32 v5, v129, v5, v17
	v_fma_f32 v6, v90, v6, v18
	v_fma_f32 v7, v91, v7, v19
	v_cvt_pk_bf16_f32 v2, v4, v5
	v_cvt_pk_bf16_f32 v3, v6, v7
	buffer_store_dwordx4 v[0:3], v85, s[12:15], 0 offen sc1
	s_nop 1
	v_mul_f32_e32 v0, 0x45800000, v8
	v_cndmask_b32_e32 v4, v8, v0, vcc
	v_mul_f32 v0, v110, v4
	v_mul_f32 v1, v111, v4
	v_mul_f32 v2, v108, v4
	v_mul_f32 v3, v109, v4
	v_mul_f32 v6, v106, v4
	v_mul_f32 v7, v107, v4
	v_mul_f32 v8, v104, v4
	v_mul_f32 v9, v105, v4
	v_fma_f32 v0, v126, v0, v28
	v_fma_f32 v1, v127, v1, v29
	v_fma_f32 v2, v124, v2, v24
	v_fma_f32 v3, v125, v3, v25
	v_fma_f32 v6, v122, v6, v30
	v_fma_f32 v7, v123, v7, v31
	v_fma_f32 v8, v112, v8, v26
	v_fma_f32 v9, v113, v9, v27
	v_cvt_pk_bf16_f32 v0, v0, v1
	v_cvt_pk_bf16_f32 v1, v6, v7
	v_cvt_pk_bf16_f32 v2, v2, v3
	v_cvt_pk_bf16_f32 v3, v8, v9
	v_add_u32_e32 v5, 0xffffec00, v83
	buffer_store_dwordx4 v[0:3], v5, s[12:15], 0 offen sc1
	v_mul_f32 v6, v50, v4
	v_mul_f32 v7, v51, v4
	v_add_u32_e32 v8, 0xfffff000, v83
	v_mul_f32 v0, v54, v4
	v_mul_f32 v1, v55, v4
	v_mul_f32 v2, v52, v4
	v_mul_f32 v3, v53, v4
	v_mul_f32 v5, v49, v4
	v_mul_f32 v4, v48, v4
	v_fma_f32 v2, v128, v2, v16
	v_fma_f32 v3, v129, v3, v17
	v_fma_f32 v4, v90, v4, v18
	v_fma_f32 v5, v91, v5, v19
	v_cvt_pk_bf16_f32 v2, v2, v3
	v_cvt_pk_bf16_f32 v3, v4, v5
	v_mul_f32_e32 v4, v117, v117
	v_mul_f32_e32 v5, v121, v121
	v_fmac_f32_e32 v4, v116, v116
	v_fmac_f32_e32 v5, v120, v120
	v_fmac_f32_e32 v4, v42, v42
	v_fmac_f32_e32 v5, v114, v114
	v_fmac_f32_e32 v4, v43, v43
	v_fmac_f32_e32 v5, v115, v115
	v_add_f32_e32 v4, v4, v5
	v_mul_f32_e32 v5, v47, v47
	v_fmac_f32_e32 v5, v46, v46
	v_fmac_f32_e32 v5, v40, v40
	v_fmac_f32_e32 v5, v41, v41
	v_add_f32_e32 v4, v4, v5
	v_mul_f32_e32 v5, v119, v119
	v_fmac_f32_e32 v5, v118, v118
	v_fmac_f32_e32 v5, v44, v44
	v_fmac_f32_e32 v5, v45, v45
	v_add_f32_e32 v4, v4, v5
	v_fma_f32 v0, v102, v0, v20
	v_fma_f32 v1, v103, v1, v21
	v_fma_f32 v6, v100, v6, v22
	v_fma_f32 v7, v101, v7, v23
	v_add_f32_dpp v4, v4, v4 quad_perm:[1,0,3,2] row_mask:0xf bank_mask:0xf bound_ctrl:1
	v_cvt_pk_bf16_f32 v0, v0, v1
	v_cvt_pk_bf16_f32 v1, v6, v7
	v_add_f32_dpp v4, v4, v4 quad_perm:[2,3,0,1] row_mask:0xf bank_mask:0xf bound_ctrl:1
	v_mul_f32_e32 v6, v97, v97
	v_fmac_f32_e32 v6, v96, v96
	v_add_f32_dpp v4, v4, v4 row_half_mirror row_mask:0xf bank_mask:0xf bound_ctrl:1
	v_fmac_f32_e32 v6, v92, v92
	v_fmac_f32_e32 v6, v93, v93
	v_add_f32_dpp v4, v4, v4 row_mirror row_mask:0xf bank_mask:0xf bound_ctrl:1
	v_mov_b32_e32 v5, v4
	s_nop 1
	v_permlane16_swap_b32_e32 v4, v5
	v_add_f32_e32 v5, v4, v5
	v_mul_f32_e32 v4, v99, v99
	v_fmac_f32_e32 v4, v98, v98
	v_fmac_f32_e32 v4, v94, v94
	v_fmac_f32_e32 v4, v95, v95
	v_add_f32_e32 v4, v4, v6
	v_mul_f32_e32 v6, v39, v39
	v_fmac_f32_e32 v6, v38, v38
	v_fmac_f32_e32 v6, v34, v34
	v_fmac_f32_e32 v6, v35, v35
	v_add_f32_e32 v4, v4, v6
	v_mul_f32_e32 v6, v37, v37
	v_fmac_f32_e32 v6, v36, v36
	v_fmac_f32_e32 v6, v32, v32
	v_fmac_f32_e32 v6, v33, v33
	v_add_f32_e32 v4, v4, v6
	v_mov_b32_e32 v7, v5
	s_nop 1
	v_permlane32_swap_b32_e32 v5, v7
	v_add_f32_dpp v4, v4, v4 quad_perm:[1,0,3,2] row_mask:0xf bank_mask:0xf bound_ctrl:1
	buffer_store_dwordx4 v[0:3], v8, s[12:15], 0 offen sc1
	s_nop 0
	v_add_f32_dpp v4, v4, v4 quad_perm:[2,3,0,1] row_mask:0xf bank_mask:0xf bound_ctrl:1
	s_nop 1
	v_add_f32_dpp v4, v4, v4 row_half_mirror row_mask:0xf bank_mask:0xf bound_ctrl:1
	s_nop 1
	v_add_f32_dpp v4, v4, v4 row_mirror row_mask:0xf bank_mask:0xf bound_ctrl:1
	v_mov_b32_e32 v6, v4
	s_nop 1
	v_permlane16_swap_b32_e32 v4, v6
	v_add_f32_e32 v4, v4, v6
	v_mov_b32_e32 v6, v4
	s_nop 1
	v_permlane32_swap_b32_e32 v4, v6
	v_add_f32 v4, v4, v6
	v_add_f32 v5, v5, v7
	v_add_u32_e32 v7, 0xfffff400, v83
	v_fma_f32 v4, v4, s26, v132
	v_fma_f32 v5, v5, s26, v132
	s_nop 0
	v_mul_f32_e32 v6, 0x4b800000, v5
	v_cmp_gt_f32_e32 vcc, s35, v5
	s_nop 1
	v_cndmask_b32_e32 v5, v5, v6, vcc
	v_rsq_f32_e32 v5, v5
	s_nop 0
	v_mul_f32_e32 v0, 0x45800000, v5
	v_cndmask_b32_e32 v6, v5, v0, vcc
	v_mul_f32 v0, v116, v6
	v_mul_f32 v1, v117, v6
	v_mul_f32 v2, v120, v6
	v_mul_f32 v3, v121, v6
	v_mul_f32 v8, v42, v6
	v_mul_f32 v9, v43, v6
	v_mul_f32 v10, v114, v6
	v_mul_f32 v11, v115, v6
	v_mul_f32_e32 v5, 0x4b800000, v4
	v_cmp_gt_f32_e32 vcc, s35, v4
	v_fma_f32 v0, v126, v0, v28
	v_fma_f32 v1, v127, v1, v29
	v_fma_f32 v2, v124, v2, v24
	v_fma_f32 v3, v125, v3, v25
	v_fma_f32 v8, v122, v8, v30
	v_fma_f32 v9, v123, v9, v31
	v_fma_f32 v10, v112, v10, v26
	v_fma_f32 v11, v113, v11, v27
	v_cndmask_b32_e32 v4, v4, v5, vcc
	v_cvt_pk_bf16_f32 v0, v0, v1
	v_cvt_pk_bf16_f32 v1, v8, v9
	v_cvt_pk_bf16_f32 v2, v2, v3
	v_cvt_pk_bf16_f32 v3, v10, v11
	v_rsq_f32_e32 v4, v4
	buffer_store_dwordx4 v[0:3], v7, s[12:15], 0 offen sc1
	v_mul_f32 v8, v40, v6
	v_mul_f32 v9, v41, v6
	s_nop 0
	v_mul_f32 v0, v46, v6
	v_mul_f32 v1, v47, v6
	v_mul_f32 v2, v118, v6
	v_mul_f32 v3, v119, v6
	v_mul_f32 v7, v45, v6
	v_mul_f32 v6, v44, v6
	v_fma_f32 v0, v102, v0, v20
	v_fma_f32 v1, v103, v1, v21
	v_fma_f32 v2, v128, v2, v16
	v_fma_f32 v3, v129, v3, v17
	v_fma_f32 v8, v100, v8, v22
	v_fma_f32 v9, v101, v9, v23
	v_fma_f32 v6, v90, v6, v18
	v_fma_f32 v7, v91, v7, v19
	v_cvt_pk_bf16_f32 v0, v0, v1
	v_cvt_pk_bf16_f32 v1, v8, v9
	v_cvt_pk_bf16_f32 v2, v2, v3
	v_cvt_pk_bf16_f32 v3, v6, v7
	buffer_store_dwordx4 v[0:3], v12, s[12:15], 0 offen sc1
	s_nop 1
	v_mul_f32_e32 v0, 0x45800000, v4
	v_cndmask_b32_e32 v4, v4, v0, vcc
	v_mul_f32 v0, v98, v4
	v_mul_f32 v1, v99, v4
	v_mul_f32 v2, v96, v4
	v_mul_f32 v3, v97, v4
	v_mul_f32 v6, v94, v4
	v_mul_f32 v7, v95, v4
	v_mul_f32 v8, v92, v4
	v_mul_f32 v9, v93, v4
	v_fma_f32 v0, v126, v0, v28
	v_fma_f32 v1, v127, v1, v29
	v_fma_f32 v2, v124, v2, v24
	v_fma_f32 v3, v125, v3, v25
	v_fma_f32 v6, v122, v6, v30
	v_fma_f32 v7, v123, v7, v31
	v_fma_f32 v8, v112, v8, v26
	v_fma_f32 v9, v113, v9, v27
	v_cvt_pk_bf16_f32 v0, v0, v1
	v_cvt_pk_bf16_f32 v1, v6, v7
	v_cvt_pk_bf16_f32 v2, v2, v3
	v_cvt_pk_bf16_f32 v3, v8, v9
	v_add_u32_e32 v5, 0xfffffc00, v83
	buffer_store_dwordx4 v[0:3], v5, s[12:15], 0 offen sc1
	v_mul_f32 v6, v34, v4
	v_mul_f32 v7, v35, v4
	s_nop 0
	v_mul_f32 v0, v38, v4
	v_mul_f32 v1, v39, v4
	v_mul_f32 v2, v36, v4
	v_mul_f32 v3, v37, v4
	v_mul_f32 v5, v33, v4
	v_mul_f32 v4, v32, v4
	v_fma_f32 v0, v102, v0, v20
	v_fma_f32 v1, v103, v1, v21
	v_fma_f32 v2, v128, v2, v16
	v_fma_f32 v3, v129, v3, v17
	v_fma_f32 v6, v100, v6, v22
	v_fma_f32 v7, v101, v7, v23
	v_fma_f32 v4, v90, v4, v18
	v_fma_f32 v5, v91, v5, v19
	v_cvt_pk_bf16_f32 v0, v0, v1
	v_cvt_pk_bf16_f32 v1, v6, v7
	v_cvt_pk_bf16_f32 v2, v2, v3
	v_cvt_pk_bf16_f32 v3, v4, v5
	buffer_store_dwordx4 v[0:3], v83, s[12:15], 0 offen sc1
	s_waitcnt vmcnt(0)
	s_and_saveexec_b64 s[6:7], s[4:5]
	s_cbranch_execz .LBB0_2071
	v_ashrrev_i32_e32 v0, 2, v76
	v_and_b32_e32 v0, 0xffffffc0, v0
	v_ashrrev_i32_e32 v1, 31, v0
	v_lshl_add_u64 v[0:1], v[0:1], 2, s[16:17]
	flat_atomic_add v[0:1], v172
	s_branch .LBB0_2071

.LBB0_2230:
	s_or_b64 exec, exec, s[4:5]
	v_lshl_add_u64 v[40:41], v[38:39], 2, s[10:11]
	global_load_dwordx4 v[46:49], v[40:41], off
	global_load_dwordx4 v[52:55], v[40:41], off offset:3072
	v_add_co_u32_e32 v38, vcc, s31, v40
	s_waitcnt vmcnt(0) lgkmcnt(0)
	v_lshlrev_b32_e32 v68, 16, v20
	v_addc_co_u32_e32 v39, vcc, 0, v41, vcc
	global_load_dwordx4 v[56:59], v[38:39], off offset:2048
	global_load_dwordx4 v[60:63], v[40:41], off offset:16
	global_load_dwordx4 v[64:67], v[40:41], off offset:3088
	v_and_b32_e32 v69, 0xffff0000, v20
	v_lshlrev_b32_e32 v70, 16, v21
	v_and_b32_e32 v71, 0xffff0000, v21
	v_lshl_add_u64 v[20:21], v[40:41], 0, s[18:19]
	v_mad_u64_u32 v[38:39], s[4:5], v32, s33, v[24:25]
	v_lshlrev_b32_e32 v72, 16, v22
	v_and_b32_e32 v73, 0xffff0000, v22
	v_lshlrev_b32_e32 v24, 16, v23
	v_and_b32_e32 v74, 0xffff0000, v23
	global_load_dwordx4 v[20:23], v[20:21], off offset:16
	v_lshlrev_b32_e32 v76, 16, v16
	v_and_b32_e32 v77, 0xffff0000, v16
	v_lshlrev_b32_e32 v16, 16, v17
	v_and_b32_e32 v17, 0xffff0000, v17
	v_lshlrev_b32_e32 v40, 16, v12
	v_and_b32_e32 v41, 0xffff0000, v12
	v_lshlrev_b32_e32 v12, 16, v13
	v_and_b32_e32 v13, 0xffff0000, v13
	v_and_b32_e32 v75, 0xffff0000, v15
	v_lshlrev_b32_e32 v80, 16, v14
	v_and_b32_e32 v81, 0xffff0000, v14
	v_lshlrev_b32_e32 v78, 16, v18
	v_and_b32_e32 v79, 0xffff0000, v18
	v_lshlrev_b32_e32 v18, 16, v19
	v_and_b32_e32 v19, 0xffff0000, v19
	v_mul_f32 v52, v52, v76
	v_mul_f32 v53, v53, v77
	v_mul_f32 v16, v54, v16
	v_mul_f32 v17, v55, v17
	v_fma_f32 v46, v46, v68, v52
	v_fma_f32 v47, v47, v69, v53
	v_fma_f32 v16, v48, v70, v16
	v_fma_f32 v17, v49, v71, v17
	s_waitcnt vmcnt(3)
	v_fma_f32 v40, v56, v40, v46
	v_fma_f32 v41, v57, v41, v47
	v_fma_f32 v16, v58, v12, v16
	v_fma_f32 v17, v59, v13, v17
	v_mul_f32_e32 v12, 0xbfb8aa3b, v40
	v_mul_f32_e32 v13, 0xbfb8aa3b, v41
	v_exp_f32_e32 v12, v12
	v_exp_f32_e32 v13, v13
	v_mul_f32_e32 v31, 0xbfb8aa3b, v16
	v_mul_f32_e32 v33, 0xbfb8aa3b, v17
	v_exp_f32_e32 v46, v31
	v_exp_f32_e32 v47, v33
	v_add_f32 v12, v12, 1.0
	v_add_f32 v13, v13, 1.0
	v_lshlrev_b32_e32 v31, 16, v15
	v_div_scale_f32 v33, s[4:5], v13, v13, v41
	v_add_f32 v14, v46, 1.0
	v_add_f32 v15, v47, 1.0
	v_div_scale_f32 v46, s[4:5], v12, v12, v40
	v_rcp_f32_e32 v53, v33
	v_div_scale_f32 v48, s[6:7], v15, v15, v17
	v_rcp_f32_e32 v54, v46
	v_rcp_f32_e32 v55, v48
	v_fma_f32 v57, -v33, v53, 1.0
	v_div_scale_f32 v39, vcc, v41, v13, v41
	v_fma_f32 v58, -v46, v54, 1.0
	v_fmac_f32_e32 v53, v57, v53
	v_div_scale_f32 v47, s[4:5], v40, v12, v40
	v_fma_f32 v59, -v48, v55, 1.0
	v_fmac_f32_e32 v54, v58, v54
	v_mul_f32_e32 v57, v39, v53
	v_div_scale_f32 v49, s[6:7], v17, v15, v17
	v_fmac_f32_e32 v55, v59, v55
	v_mul_f32_e32 v58, v47, v54
	v_fma_f32 v69, -v33, v57, v39
	v_mul_f32_e32 v59, v49, v55
	v_fma_f32 v70, -v46, v58, v47
	v_fmac_f32_e32 v57, v69, v53
	v_fma_f32 v71, -v48, v59, v49
	v_fmac_f32_e32 v58, v70, v54
	v_fma_f32 v33, -v33, v57, v39
	v_fmac_f32_e32 v59, v71, v55
	v_fma_f32 v39, -v46, v58, v47
	v_div_fmas_f32 v33, v33, v53, v57
	s_mov_b64 vcc, s[4:5]
	v_fma_f32 v46, -v48, v59, v49
	v_div_fixup_f32 v13, v33, v13, v41
	v_div_fmas_f32 v33, v39, v54, v58
	s_mov_b64 vcc, s[6:7]
	v_div_fixup_f32 v12, v33, v12, v40
	v_div_fmas_f32 v33, v46, v55, v59
	s_waitcnt vmcnt(1)
	v_mul_f32 v46, v64, v78
	v_mul_f32 v47, v65, v79
	v_div_scale_f32 v51, s[8:9], v14, v14, v16
	v_fma_f32 v46, v60, v72, v46
	v_fma_f32 v47, v61, v73, v47
	v_div_fixup_f32 v15, v33, v15, v17
	s_waitcnt vmcnt(0)
	v_fma_f32 v20, v20, v80, v46
	v_fma_f32 v21, v21, v81, v47
	v_rcp_f32_e32 v56, v51
	v_mul_f32_e32 v17, 0xbfb8aa3b, v20
	v_exp_f32_e32 v46, v17
	v_mul_f32_e32 v17, 0xbfb8aa3b, v21
	v_exp_f32_e32 v47, v17
	v_fma_f32 v68, -v51, v56, 1.0
	v_div_scale_f32 v52, s[8:9], v16, v14, v16
	v_fmac_f32_e32 v56, v68, v56
	v_add_f32 v46, v46, 1.0
	v_add_f32 v47, v47, 1.0
	v_mul_f32_e32 v68, v52, v56
	v_div_scale_f32 v33, s[4:5], v47, v47, v21
	v_fma_f32 v17, -v51, v68, v52
	v_rcp_f32_e32 v39, v33
	v_fmac_f32_e32 v68, v17, v56
	v_fma_f32 v17, -v51, v68, v52
	s_mov_b64 vcc, s[8:9]
	v_div_fmas_f32 v17, v17, v56, v68
	v_div_fixup_f32 v14, v17, v14, v16
	v_fma_f32 v16, -v33, v39, 1.0
	v_fmac_f32_e32 v39, v16, v39
	v_div_scale_f32 v16, vcc, v21, v47, v21
	v_mul_f32_e32 v17, v16, v39
	v_fma_f32 v51, -v33, v17, v16
	v_mul_f32_e32 v54, v22, v31
	v_mov_b32_e32 v22, v63
	v_fmac_f32_e32 v17, v51, v39
	v_mul_f32 v22, v22, v74
	v_mul_f32 v23, v23, v75
	v_fma_f32 v16, -v33, v17, v16
	v_div_scale_f32 v33, s[4:5], v46, v46, v20
	v_mul_f32_e32 v52, v62, v24
	v_mov_b32_e32 v53, v22
	v_rcp_f32_e32 v51, v33
	v_fma_f32 v18, v66, v18, v52
	v_fma_f32 v19, v67, v19, v53
	v_mov_b32_e32 v55, v23
	v_add_f32 v18, v18, v54
	v_add_f32 v19, v19, v55
	v_div_fmas_f32 v16, v16, v39, v17
	v_mul_f32_e32 v22, 0xbfb8aa3b, v18
	v_mul_f32_e32 v23, 0xbfb8aa3b, v19
	v_exp_f32_e32 v22, v22
	v_exp_f32_e32 v23, v23
	v_div_fixup_f32 v17, v16, v47, v21
	v_fma_f32 v16, -v33, v51, 1.0
	v_fmac_f32_e32 v51, v16, v51
	v_div_scale_f32 v16, vcc, v20, v46, v20
	v_mul_f32_e32 v21, v16, v51
	v_fma_f32 v24, -v33, v21, v16
	v_add_f32 v22, v22, 1.0
	v_add_f32 v23, v23, 1.0
	v_fmac_f32_e32 v21, v24, v51
	v_div_scale_f32 v24, s[4:5], v23, v23, v19
	v_rcp_f32_e32 v31, v24
	v_fma_f32 v16, -v33, v21, v16
	v_div_fmas_f32 v16, v16, v51, v21
	v_div_fixup_f32 v16, v16, v46, v20
	v_fma_f32 v33, -v24, v31, 1.0
	v_fmac_f32_e32 v31, v33, v31
	v_div_scale_f32 v33, vcc, v19, v23, v19
	v_mul_f32_e32 v39, v33, v31
	v_fma_f32 v46, -v24, v39, v33
	v_fmac_f32_e32 v39, v46, v31
	v_fma_f32 v24, -v24, v39, v33
	v_div_scale_f32 v33, s[4:5], v22, v22, v18
	v_rcp_f32_e32 v46, v33
	v_div_fmas_f32 v24, v24, v31, v39
	v_div_fixup_f32 v19, v24, v23, v19
	v_mul_f32 v40, v12, v12
	v_mul_f32 v41, v13, v13
	v_fma_f32 v23, -v33, v46, 1.0
	v_fmac_f32_e32 v46, v23, v46
	v_div_scale_f32 v23, vcc, v18, v22, v18
	v_mul_f32_e32 v24, v23, v46
	v_fma_f32 v31, -v33, v24, v23
	v_fmac_f32_e32 v24, v31, v46
	v_fma_f32 v23, -v33, v24, v23
	v_mul_f32 v48, v14, v14
	v_mul_f32 v49, v15, v15
	v_div_fmas_f32 v23, v23, v46, v24
	v_add_f32_e32 v24, v40, v41
	v_add_f32_e32 v24, v24, v48
	v_mul_f32 v20, v16, v16
	v_mul_f32 v21, v17, v17
	v_add_f32_e32 v24, v24, v49
	v_div_fixup_f32 v18, v23, v22, v18
	v_add_f32_e32 v20, v24, v20
	v_mul_f32 v22, v18, v18
	v_mul_f32 v23, v19, v19
	v_add_f32_e32 v20, v20, v21
	v_add_f32_e32 v20, v20, v22
	v_add_f32_e32 v20, v20, v23
	v_cmp_gt_i32_e32 vcc, 64, v38
	s_nop 0
	v_add_f32_dpp v20, v20, v20 quad_perm:[1,0,3,2] row_mask:0xf bank_mask:0xf bound_ctrl:1
	s_nop 1
	v_add_f32_dpp v20, v20, v20 quad_perm:[2,3,0,1] row_mask:0xf bank_mask:0xf bound_ctrl:1
	s_nop 1
	v_mov_b32_dpp v21, v20 row_half_mirror row_mask:0xf bank_mask:0xf bound_ctrl:1
	s_and_saveexec_b64 s[6:7], vcc
	s_cbranch_execz .LBB0_2232
	v_add_f32_e32 v20, v20, v21
	v_add_f32_e32 v20, 0x358637bd, v20
	v_mul_f32_e32 v21, 0x4b800000, v20
	v_cmp_gt_f32_e32 vcc, s34, v20
	v_cmp_gt_i32_e64 s[4:5], 32, v38
	s_nop 0
	v_cndmask_b32_e32 v20, v20, v21, vcc
	v_rsq_f32_e32 v20, v20
	v_cndmask_b32_e64 v21, 1.0, v43, s[4:5]
	v_mul_f32_e32 v22, 0x45800000, v20
	v_cndmask_b32_e32 v20, v20, v22, vcc
	v_mul_f32_e32 v20, v21, v20
	v_mul_f32 v18, v18, v20
	v_mul_f32 v19, v19, v20
	v_mul_f32 v16, v16, v20
	v_mul_f32 v17, v17, v20
	v_mul_f32 v14, v14, v20
	v_mul_f32 v15, v15, v20
	v_mul_f32 v12, v12, v20
	v_mul_f32 v13, v13, v20

.LBB0_2241:
	s_or_b64 exec, exec, s[4:5]
	v_lshl_add_u64 v[26:27], v[24:25], 2, s[10:11]
	global_load_dwordx4 v[30:33], v[26:27], off
	global_load_dwordx4 v[34:37], v[26:27], off offset:3072
	v_add_co_u32_e32 v24, vcc, s26, v26
	s_waitcnt vmcnt(0) lgkmcnt(0)
	v_lshlrev_b32_e32 v48, 16, v8
	v_addc_co_u32_e32 v25, vcc, 0, v27, vcc
	global_load_dwordx4 v[38:41], v[24:25], off offset:2048
	global_load_dwordx4 v[44:47], v[26:27], off offset:16
	global_load_dwordx4 v[52:55], v[26:27], off offset:3088
	v_and_b32_e32 v49, 0xffff0000, v8
	v_lshlrev_b32_e32 v56, 16, v9
	v_and_b32_e32 v57, 0xffff0000, v9
	v_lshl_add_u64 v[8:9], v[26:27], 0, s[18:19]
	v_lshlrev_b32_e32 v58, 16, v10
	v_and_b32_e32 v59, 0xffff0000, v10
	v_lshlrev_b32_e32 v23, 16, v11
	v_and_b32_e32 v60, 0xffff0000, v11
	global_load_dwordx4 v[8:11], v[8:9], off offset:16
	v_lshlrev_b32_e32 v62, 16, v4
	v_and_b32_e32 v63, 0xffff0000, v4
	v_lshlrev_b32_e32 v4, 16, v5
	v_and_b32_e32 v5, 0xffff0000, v5
	v_lshlrev_b32_e32 v26, 16, v0
	v_and_b32_e32 v27, 0xffff0000, v0
	v_lshlrev_b32_e32 v0, 16, v1
	v_and_b32_e32 v1, 0xffff0000, v1
	v_mad_u64_u32 v[24:25], s[4:5], v22, s27, v[14:15]
	v_and_b32_e32 v61, 0xffff0000, v3
	v_lshlrev_b32_e32 v66, 16, v2
	v_and_b32_e32 v67, 0xffff0000, v2
	v_lshlrev_b32_e32 v64, 16, v6
	v_and_b32_e32 v65, 0xffff0000, v6
	v_lshlrev_b32_e32 v6, 16, v7
	v_and_b32_e32 v7, 0xffff0000, v7
	v_mul_f32 v34, v34, v62
	v_mul_f32 v35, v35, v63
	v_mul_f32 v4, v36, v4
	v_mul_f32 v5, v37, v5
	v_fma_f32 v30, v30, v48, v34
	v_fma_f32 v31, v31, v49, v35
	v_fma_f32 v4, v32, v56, v4
	v_fma_f32 v5, v33, v57, v5
	s_waitcnt vmcnt(3)
	v_fma_f32 v26, v38, v26, v30
	v_fma_f32 v27, v39, v27, v31
	v_fma_f32 v4, v40, v0, v4
	v_fma_f32 v5, v41, v1, v5
	v_mul_f32_e32 v0, 0xbfb8aa3b, v26
	v_mul_f32_e32 v1, 0xbfb8aa3b, v27
	v_exp_f32_e32 v0, v0
	v_exp_f32_e32 v1, v1
	v_mul_f32_e32 v25, 0xbfb8aa3b, v4
	v_mul_f32_e32 v29, 0xbfb8aa3b, v5
	v_exp_f32_e32 v30, v25
	v_exp_f32_e32 v31, v29
	v_add_f32 v0, v0, 1.0
	v_add_f32 v1, v1, 1.0
	v_lshlrev_b32_e32 v25, 16, v3
	v_div_scale_f32 v29, s[4:5], v1, v1, v27
	v_add_f32 v2, v30, 1.0
	v_add_f32 v3, v31, 1.0
	v_div_scale_f32 v31, s[4:5], v0, v0, v26
	v_rcp_f32_e32 v37, v29
	v_div_scale_f32 v33, s[6:7], v3, v3, v5
	v_rcp_f32_e32 v38, v31
	v_rcp_f32_e32 v39, v33
	v_fma_f32 v41, -v29, v37, 1.0
	v_div_scale_f32 v30, vcc, v27, v1, v27
	v_fma_f32 v43, -v31, v38, 1.0
	v_fmac_f32_e32 v37, v41, v37
	v_div_scale_f32 v32, s[4:5], v26, v0, v26
	v_fma_f32 v48, -v33, v39, 1.0
	v_fmac_f32_e32 v38, v43, v38
	v_mul_f32_e32 v41, v30, v37
	v_div_scale_f32 v34, s[6:7], v5, v3, v5
	v_fmac_f32_e32 v39, v48, v39
	v_mul_f32_e32 v43, v32, v38
	v_fma_f32 v51, -v29, v41, v30
	v_mul_f32_e32 v48, v34, v39
	v_fma_f32 v56, -v31, v43, v32
	v_fmac_f32_e32 v41, v51, v37
	v_fma_f32 v57, -v33, v48, v34
	v_fmac_f32_e32 v43, v56, v38
	v_fma_f32 v29, -v29, v41, v30
	v_fmac_f32_e32 v48, v57, v39
	v_fma_f32 v30, -v31, v43, v32
	v_div_fmas_f32 v29, v29, v37, v41
	s_mov_b64 vcc, s[4:5]
	v_fma_f32 v31, -v33, v48, v34
	v_div_fixup_f32 v1, v29, v1, v27
	v_div_fmas_f32 v27, v30, v38, v43
	s_mov_b64 vcc, s[6:7]
	v_div_fmas_f32 v29, v31, v39, v48
	s_waitcnt vmcnt(1)
	v_mul_f32 v30, v52, v64
	v_mul_f32 v31, v53, v65
	v_div_scale_f32 v35, s[8:9], v2, v2, v4
	v_fma_f32 v30, v44, v58, v30
	v_fma_f32 v31, v45, v59, v31
	v_div_fixup_f32 v3, v29, v3, v5
	s_waitcnt vmcnt(0)
	v_fma_f32 v8, v8, v66, v30
	v_fma_f32 v9, v9, v67, v31
	v_rcp_f32_e32 v40, v35
	v_mul_f32_e32 v5, 0xbfb8aa3b, v8
	v_exp_f32_e32 v30, v5
	v_mul_f32_e32 v5, 0xbfb8aa3b, v9
	v_exp_f32_e32 v31, v5
	v_fma_f32 v49, -v35, v40, 1.0
	v_div_scale_f32 v36, s[8:9], v4, v2, v4
	v_fmac_f32_e32 v40, v49, v40
	v_add_f32 v30, v30, 1.0
	v_add_f32 v31, v31, 1.0
	v_mul_f32_e32 v49, v36, v40
	v_div_scale_f32 v29, s[4:5], v31, v31, v9
	v_fma_f32 v5, -v35, v49, v36
	v_rcp_f32_e32 v34, v29
	v_fmac_f32_e32 v49, v5, v40
	v_fma_f32 v5, -v35, v49, v36
	s_mov_b64 vcc, s[8:9]
	v_div_fmas_f32 v5, v5, v40, v49
	v_div_fixup_f32 v2, v5, v2, v4
	v_fma_f32 v4, -v29, v34, 1.0
	v_fmac_f32_e32 v34, v4, v34
	v_div_scale_f32 v4, vcc, v9, v31, v9
	v_mul_f32_e32 v5, v4, v34
	v_fma_f32 v35, -v29, v5, v4
	v_fmac_f32_e32 v5, v35, v34
	v_mul_f32_e32 v36, v10, v25
	v_mov_b32_e32 v10, v47
	v_fma_f32 v4, -v29, v5, v4
	v_mul_f32 v10, v10, v60
	v_mul_f32 v11, v11, v61
	v_div_scale_f32 v29, s[4:5], v30, v30, v8
	v_div_fmas_f32 v4, v4, v34, v5
	v_mul_f32_e32 v34, v46, v23
	v_mov_b32_e32 v35, v10
	v_rcp_f32_e32 v38, v29
	v_fma_f32 v6, v54, v6, v34
	v_fma_f32 v7, v55, v7, v35
	v_mov_b32_e32 v37, v11
	v_add_f32 v6, v6, v36
	v_add_f32 v7, v7, v37
	v_div_fixup_f32 v5, v4, v31, v9
	v_mul_f32_e32 v10, 0xbfb8aa3b, v6
	v_mul_f32_e32 v11, 0xbfb8aa3b, v7
	v_exp_f32_e32 v10, v10
	v_exp_f32_e32 v11, v11
	v_fma_f32 v4, -v29, v38, 1.0
	v_fmac_f32_e32 v38, v4, v38
	v_div_scale_f32 v4, vcc, v8, v30, v8
	v_mul_f32_e32 v9, v4, v38
	v_fma_f32 v23, -v29, v9, v4
	v_add_f32 v10, v10, 1.0
	v_add_f32 v11, v11, 1.0
	v_fmac_f32_e32 v9, v23, v38
	v_div_scale_f32 v23, s[4:5], v11, v11, v7
	v_rcp_f32_e32 v25, v23
	v_fma_f32 v4, -v29, v9, v4
	v_div_fmas_f32 v4, v4, v38, v9
	v_div_fixup_f32 v4, v4, v30, v8
	v_fma_f32 v29, -v23, v25, 1.0
	v_fmac_f32_e32 v25, v29, v25
	v_div_scale_f32 v29, vcc, v7, v11, v7
	v_mul_f32_e32 v30, v29, v25
	v_fma_f32 v31, -v23, v30, v29
	v_fmac_f32_e32 v30, v31, v25
	v_fma_f32 v23, -v23, v30, v29
	v_div_scale_f32 v29, s[4:5], v10, v10, v6
	v_rcp_f32_e32 v31, v29
	v_div_fmas_f32 v23, v23, v25, v30
	v_div_fixup_f32 v7, v23, v11, v7
	v_div_fixup_f32 v0, v27, v0, v26
	v_fma_f32 v11, -v29, v31, 1.0
	v_fmac_f32_e32 v31, v11, v31
	v_div_scale_f32 v11, vcc, v6, v10, v6
	v_mul_f32_e32 v23, v11, v31
	v_fma_f32 v25, -v29, v23, v11
	v_fmac_f32_e32 v23, v25, v31
	v_mul_f32 v26, v0, v0
	v_mul_f32 v27, v1, v1
	v_fma_f32 v11, -v29, v23, v11
	v_mul_f32 v32, v2, v2
	v_mul_f32 v33, v3, v3
	v_div_fmas_f32 v11, v11, v31, v23
	v_add_f32_e32 v23, v26, v27
	v_add_f32_e32 v23, v23, v32
	v_mul_f32 v8, v4, v4
	v_mul_f32 v9, v5, v5
	v_add_f32_e32 v23, v23, v33
	v_div_fixup_f32 v6, v11, v10, v6
	v_add_f32_e32 v8, v23, v8
	v_mul_f32 v10, v6, v6
	v_mul_f32 v11, v7, v7
	v_add_f32_e32 v8, v8, v9
	v_add_f32_e32 v8, v8, v10
	v_add_f32_e32 v8, v8, v11
	v_cmp_gt_i32_e32 vcc, 64, v24
	s_nop 0
	v_add_f32_dpp v8, v8, v8 quad_perm:[1,0,3,2] row_mask:0xf bank_mask:0xf bound_ctrl:1
	s_nop 1
	v_add_f32_dpp v8, v8, v8 quad_perm:[2,3,0,1] row_mask:0xf bank_mask:0xf bound_ctrl:1
	s_nop 1
	v_mov_b32_dpp v9, v8 row_half_mirror row_mask:0xf bank_mask:0xf bound_ctrl:1
	s_and_saveexec_b64 s[6:7], vcc
	s_cbranch_execz .LBB0_2236
	v_add_f32_e32 v8, v8, v9
	v_add_f32_e32 v8, 0x358637bd, v8
	v_mul_f32_e32 v9, 0x4b800000, v8
	v_cmp_gt_f32_e32 vcc, s28, v8
	v_cmp_gt_i32_e64 s[4:5], 32, v24
	s_nop 0
	v_cndmask_b32_e32 v8, v8, v9, vcc
	v_rsq_f32_e32 v8, v8
	v_cndmask_b32_e64 v9, 1.0, v28, s[4:5]
	v_mul_f32_e32 v10, 0x45800000, v8
	v_cndmask_b32_e32 v8, v8, v10, vcc
	v_mul_f32_e32 v8, v9, v8
	v_mul_f32 v6, v6, v8
	v_mul_f32 v7, v7, v8
	v_mul_f32 v4, v4, v8
	v_mul_f32 v5, v5, v8
	v_mul_f32 v2, v2, v8
	v_mul_f32 v3, v3, v8
	v_mul_f32 v0, v0, v8
	v_mul_f32 v1, v1, v8
	s_branch .LBB0_2236

.LBB0_2246:
	v_add_u32_e32 v20, s13, v50
	v_ashrrev_i32_e32 v36, 4, v20
	v_mad_i64_i32 v[0:1], s[4:5], v36, s17, v[26:27]
	flat_load_dwordx4 v[12:15], v[0:1] offset:768
	v_add_u32_e32 v33, s13, v39
	v_add_u32_e32 v31, s13, v40
	v_add_u32_e32 v43, s13, v38
	v_ashrrev_i32_e32 v34, 4, v33
	global_load_dwordx4 v[44:47], v[24:25], off offset:528
	global_load_dwordx4 v[16:19], v[24:25], off offset:512
	v_ashrrev_i32_e32 v32, 4, v31
	v_ashrrev_i32_e32 v30, 4, v43
	v_mad_i64_i32 v[48:49], s[4:5], v34, s17, v[26:27]
	v_mad_i64_i32 v[52:53], s[4:5], v32, s17, v[26:27]
	v_mad_i64_i32 v[54:55], s[4:5], v30, s17, v[26:27]
	flat_load_dwordx4 v[8:11], v[48:49] offset:768
	flat_load_dwordx4 v[4:7], v[52:53] offset:768
	flat_load_dwordx4 v[0:3], v[54:55] offset:768
	v_ashrrev_i32_e32 v37, 31, v36
	v_cmp_gt_i32_e64 s[4:5], s18, v36
	s_waitcnt vmcnt(0) lgkmcnt(0)
	v_lshlrev_b32_e32 v48, 16, v12
	v_and_b32_e32 v49, 0xffff0000, v12
	v_lshlrev_b32_e32 v12, 16, v13
	v_and_b32_e32 v13, 0xffff0000, v13
	v_mul_f32 v60, v48, v48
	v_mul_f32 v61, v49, v49
	v_mul_f32 v58, v12, v12
	v_mul_f32 v59, v13, v13
	v_add_f32_e32 v29, v60, v61
	v_lshlrev_b32_e32 v52, 16, v14
	v_and_b32_e32 v53, 0xffff0000, v14
	v_add_f32_e32 v29, v29, v58
	v_mul_f32 v56, v52, v52
	v_mul_f32 v57, v53, v53
	v_add_f32_e32 v29, v59, v29
	v_lshlrev_b32_e32 v14, 16, v15
	v_and_b32_e32 v15, 0xffff0000, v15
	v_add_f32_e32 v29, v56, v29
	v_mul_f32 v54, v14, v14
	v_mul_f32 v55, v15, v15
	v_add_f32_e32 v29, v57, v29
	v_add_f32_e32 v29, v54, v29
	v_add_f32_e32 v29, v55, v29
	v_lshlrev_b64 v[54:55], 8, v[36:37]
	s_nop 0
	v_add_f32_dpp v29, v29, v29 quad_perm:[1,0,3,2] row_mask:0xf bank_mask:0xf bound_ctrl:1
	s_nop 1
	v_add_f32_dpp v29, v29, v29 quad_perm:[2,3,0,1] row_mask:0xf bank_mask:0xf bound_ctrl:1
	s_nop 1
	v_add_f32_dpp v29, v29, v29 row_half_mirror row_mask:0xf bank_mask:0xf bound_ctrl:1
	s_nop 1
	v_add_f32_dpp v29, v29, v29 row_mirror row_mask:0xf bank_mask:0xf bound_ctrl:1
	v_fmamk_f32 v29, v29, 0x3c000000, v41
	v_mul_f32_e32 v35, 0x4b800000, v29
	v_cmp_gt_f32_e32 vcc, s19, v29
	s_nop 1
	v_cndmask_b32_e32 v29, v29, v35, vcc
	v_rsq_f32_e32 v29, v29
	s_nop 0
	v_mul_f32_e32 v35, 0x45800000, v29
	v_cndmask_b32_e32 v56, v29, v35, vcc
	v_mul_f32 v48, v56, v48
	v_mul_f32 v49, v56, v49
	v_mul_f32 v12, v56, v12
	v_mul_f32 v13, v56, v13
	v_mul_f32 v52, v56, v52
	v_mul_f32 v53, v56, v53
	v_mul_f32 v14, v56, v14
	v_mul_f32 v15, v56, v15
	v_mul_f32 v16, v16, v48
	v_mul_f32 v17, v17, v49
	v_mul_f32 v18, v18, v12
	v_mul_f32 v19, v19, v13
	v_mul_f32 v12, v44, v52
	v_mul_f32 v13, v45, v53
	v_mul_f32 v14, v46, v14
	v_mul_f32 v15, v47, v15
	v_cvt_pk_bf16_f32 v44, v16, v17
	v_cvt_pk_bf16_f32 v45, v18, v19
	v_cvt_pk_bf16_f32 v46, v12, v13
	v_cvt_pk_bf16_f32 v47, v14, v15
	v_lshl_add_u64 v[48:49], v[22:23], 0, v[54:55]
	flat_store_dwordx4 v[48:49], v[44:47]
	s_and_saveexec_b64 s[10:11], s[4:5]
	s_cbranch_execz .LBB0_2248
	v_ashrrev_i32_e32 v20, 11, v20
	v_or_b32_e32 v44, 1, v20
	v_ashrrev_i32_e32 v45, 31, v44
	v_lshlrev_b64 v[44:45], 17, v[44:45]
	v_lshlrev_b32_e32 v20, 9, v36
	v_lshl_add_u64 v[44:45], s[8:9], 0, v[44:45]
	v_and_b32_e32 v20, 0x1fe00, v20
	v_lshl_add_u64 v[36:37], v[44:45], 0, v[20:21]
	v_mov_b32_e32 v29, v21
	v_lshl_add_u64 v[36:37], v[36:37], 0, v[28:29]
	flat_store_dwordx4 v[36:37], v[16:19]
	flat_store_dwordx4 v[36:37], v[12:15] offset:16
.LBB0_2248:
	s_or_b64 exec, exec, s[10:11]
	global_load_dwordx4 v[12:15], v[24:25], off offset:512
	global_load_dwordx4 v[16:19], v[24:25], off offset:528
	v_lshlrev_b32_e32 v36, 16, v8
	v_and_b32_e32 v37, 0xffff0000, v8
	v_lshlrev_b32_e32 v8, 16, v9
	v_and_b32_e32 v9, 0xffff0000, v9
	v_mul_f32 v54, v36, v36
	v_mul_f32 v55, v37, v37
	v_mul_f32 v52, v8, v8
	v_mul_f32 v53, v9, v9
	v_add_f32_e32 v20, v54, v55
	v_lshlrev_b32_e32 v44, 16, v10
	v_and_b32_e32 v45, 0xffff0000, v10
	v_add_f32_e32 v20, v20, v52
	v_mul_f32 v48, v44, v44
	v_mul_f32 v49, v45, v45
	v_add_f32_e32 v20, v53, v20
	v_lshlrev_b32_e32 v10, 16, v11
	v_and_b32_e32 v11, 0xffff0000, v11
	v_add_f32_e32 v20, v48, v20
	v_mul_f32 v46, v10, v10
	v_mul_f32 v47, v11, v11
	v_add_f32_e32 v20, v49, v20
	v_add_f32_e32 v20, v46, v20
	v_add_f32_e32 v20, v47, v20
	v_ashrrev_i32_e32 v35, 31, v34
	v_lshlrev_b64 v[46:47], 8, v[34:35]
	v_add_f32_dpp v20, v20, v20 quad_perm:[1,0,3,2] row_mask:0xf bank_mask:0xf bound_ctrl:1
	v_cmp_gt_i32_e64 s[4:5], s18, v34
	s_nop 0
	v_add_f32_dpp v20, v20, v20 quad_perm:[2,3,0,1] row_mask:0xf bank_mask:0xf bound_ctrl:1
	s_nop 1
	v_add_f32_dpp v20, v20, v20 row_half_mirror row_mask:0xf bank_mask:0xf bound_ctrl:1
	s_nop 1
	v_add_f32_dpp v20, v20, v20 row_mirror row_mask:0xf bank_mask:0xf bound_ctrl:1
	v_fmamk_f32 v20, v20, 0x3c000000, v41
	v_mul_f32_e32 v29, 0x4b800000, v20
	v_cmp_gt_f32_e32 vcc, s19, v20
	s_nop 1
	v_cndmask_b32_e32 v20, v20, v29, vcc
	v_rsq_f32_e32 v20, v20
	s_nop 0
	v_mul_f32_e32 v29, 0x45800000, v20
	v_cndmask_b32_e32 v20, v20, v29, vcc
	v_mul_f32 v36, v20, v36
	v_mul_f32 v37, v20, v37
	v_mul_f32 v8, v20, v8
	v_mul_f32 v9, v20, v9
	v_mul_f32 v44, v20, v44
	v_mul_f32 v45, v20, v45
	v_mul_f32 v10, v20, v10
	v_mul_f32 v11, v20, v11
	s_waitcnt vmcnt(0)
	v_mul_f32 v12, v12, v36
	v_mul_f32 v13, v13, v37
	v_mul_f32 v14, v14, v8
	v_mul_f32 v15, v15, v9
	v_mul_f32 v8, v16, v44
	v_mul_f32 v9, v17, v45
	v_mul_f32 v10, v18, v10
	v_mul_f32 v11, v19, v11
	v_cvt_pk_bf16_f32 v16, v12, v13
	v_cvt_pk_bf16_f32 v17, v14, v15
	v_cvt_pk_bf16_f32 v18, v8, v9
	v_cvt_pk_bf16_f32 v19, v10, v11
	v_lshl_add_u64 v[36:37], v[22:23], 0, v[46:47]
	flat_store_dwordx4 v[36:37], v[16:19]
	s_and_saveexec_b64 s[10:11], s[4:5]
	s_cbranch_execz .LBB0_2250
	v_ashrrev_i32_e32 v16, 11, v33
	v_or_b32_e32 v16, 1, v16
	v_ashrrev_i32_e32 v17, 31, v16
	v_lshlrev_b64 v[16:17], 17, v[16:17]
	v_lshlrev_b32_e32 v18, 9, v34
	v_lshl_add_u64 v[16:17], s[8:9], 0, v[16:17]
	v_and_b32_e32 v20, 0x1fe00, v18
	v_lshl_add_u64 v[16:17], v[16:17], 0, v[20:21]
	v_mov_b32_e32 v29, v21
	v_lshl_add_u64 v[16:17], v[16:17], 0, v[28:29]
	flat_store_dwordx4 v[16:17], v[12:15]
	flat_store_dwordx4 v[16:17], v[8:11] offset:16
.LBB0_2250:
	s_or_b64 exec, exec, s[10:11]
	global_load_dwordx4 v[8:11], v[24:25], off offset:512
	global_load_dwordx4 v[12:15], v[24:25], off offset:528
	v_lshlrev_b32_e32 v16, 16, v4
	v_and_b32_e32 v17, 0xffff0000, v4
	v_lshlrev_b32_e32 v4, 16, v5
	v_and_b32_e32 v5, 0xffff0000, v5
	v_mul_f32 v46, v16, v16
	v_mul_f32 v47, v17, v17
	v_mul_f32 v44, v4, v4
	v_mul_f32 v45, v5, v5
	v_add_f32_e32 v20, v46, v47
	v_lshlrev_b32_e32 v18, 16, v6
	v_and_b32_e32 v19, 0xffff0000, v6
	v_add_f32_e32 v20, v20, v44
	v_mul_f32 v36, v18, v18
	v_mul_f32 v37, v19, v19
	v_add_f32_e32 v20, v45, v20
	v_lshlrev_b32_e32 v6, 16, v7
	v_and_b32_e32 v7, 0xffff0000, v7
	v_add_f32_e32 v20, v36, v20
	v_mul_f32 v34, v6, v6
	v_mul_f32 v35, v7, v7
	v_add_f32_e32 v20, v37, v20
	v_add_f32_e32 v20, v34, v20
	v_add_f32_e32 v20, v35, v20
	v_ashrrev_i32_e32 v33, 31, v32
	v_lshlrev_b64 v[34:35], 8, v[32:33]
	v_add_f32_dpp v20, v20, v20 quad_perm:[1,0,3,2] row_mask:0xf bank_mask:0xf bound_ctrl:1
	v_cmp_gt_i32_e64 s[4:5], s18, v32
	s_nop 0
	v_add_f32_dpp v20, v20, v20 quad_perm:[2,3,0,1] row_mask:0xf bank_mask:0xf bound_ctrl:1
	s_nop 1
	v_add_f32_dpp v20, v20, v20 row_half_mirror row_mask:0xf bank_mask:0xf bound_ctrl:1
	s_nop 1
	v_add_f32_dpp v20, v20, v20 row_mirror row_mask:0xf bank_mask:0xf bound_ctrl:1
	v_fmamk_f32 v20, v20, 0x3c000000, v41
	v_mul_f32_e32 v29, 0x4b800000, v20
	v_cmp_gt_f32_e32 vcc, s19, v20
	s_nop 1
	v_cndmask_b32_e32 v20, v20, v29, vcc
	v_rsq_f32_e32 v20, v20
	s_nop 0
	v_mul_f32_e32 v29, 0x45800000, v20
	v_cndmask_b32_e32 v20, v20, v29, vcc
	v_mul_f32 v16, v20, v16
	v_mul_f32 v17, v20, v17
	v_mul_f32 v4, v20, v4
	v_mul_f32 v5, v20, v5
	v_mul_f32 v18, v20, v18
	v_mul_f32 v19, v20, v19
	v_mul_f32 v6, v20, v6
	v_mul_f32 v7, v20, v7
	s_waitcnt vmcnt(0)
	v_mul_f32 v8, v8, v16
	v_mul_f32 v9, v9, v17
	v_mul_f32 v10, v10, v4
	v_mul_f32 v11, v11, v5
	v_mul_f32 v4, v12, v18
	v_mul_f32 v5, v13, v19
	v_mul_f32 v6, v14, v6
	v_mul_f32 v7, v15, v7
	v_cvt_pk_bf16_f32 v12, v8, v9
	v_cvt_pk_bf16_f32 v13, v10, v11
	v_cvt_pk_bf16_f32 v14, v4, v5
	v_cvt_pk_bf16_f32 v15, v6, v7
	v_lshl_add_u64 v[16:17], v[22:23], 0, v[34:35]
	flat_store_dwordx4 v[16:17], v[12:15]
	s_and_saveexec_b64 s[10:11], s[4:5]
	s_cbranch_execz .LBB0_2252
	v_ashrrev_i32_e32 v12, 11, v31
	v_or_b32_e32 v12, 1, v12
	v_ashrrev_i32_e32 v13, 31, v12
	v_lshlrev_b64 v[12:13], 17, v[12:13]
	v_lshlrev_b32_e32 v14, 9, v32
	v_lshl_add_u64 v[12:13], s[8:9], 0, v[12:13]
	v_and_b32_e32 v20, 0x1fe00, v14
	v_lshl_add_u64 v[12:13], v[12:13], 0, v[20:21]
	v_mov_b32_e32 v29, v21
	v_lshl_add_u64 v[12:13], v[12:13], 0, v[28:29]
	flat_store_dwordx4 v[12:13], v[8:11]
	flat_store_dwordx4 v[12:13], v[4:7] offset:16
.LBB0_2252:
	s_or_b64 exec, exec, s[10:11]
	global_load_dwordx4 v[4:7], v[24:25], off offset:512
	global_load_dwordx4 v[8:11], v[24:25], off offset:528
	v_lshlrev_b32_e32 v12, 16, v0
	v_and_b32_e32 v13, 0xffff0000, v0
	v_lshlrev_b32_e32 v0, 16, v1
	v_and_b32_e32 v1, 0xffff0000, v1
	v_mul_f32 v34, v12, v12
	v_mul_f32 v35, v13, v13
	v_mul_f32 v32, v0, v0
	v_mul_f32 v33, v1, v1
	v_add_f32_e32 v20, v34, v35
	v_lshlrev_b32_e32 v14, 16, v2
	v_and_b32_e32 v15, 0xffff0000, v2
	v_add_f32_e32 v20, v20, v32
	v_mul_f32 v18, v14, v14
	v_mul_f32 v19, v15, v15
	v_add_f32_e32 v20, v33, v20
	v_lshlrev_b32_e32 v2, 16, v3
	v_and_b32_e32 v3, 0xffff0000, v3
	v_add_f32_e32 v18, v18, v20
	v_mul_f32 v16, v2, v2
	v_mul_f32 v17, v3, v3
	v_add_f32_e32 v18, v19, v18
	v_add_f32_e32 v16, v16, v18
	v_add_f32_e32 v16, v17, v16
	v_ashrrev_i32_e32 v31, 31, v30
	v_cmp_gt_i32_e64 s[4:5], s18, v30
	v_add_f32_dpp v16, v16, v16 quad_perm:[1,0,3,2] row_mask:0xf bank_mask:0xf bound_ctrl:1
	s_nop 1
	v_add_f32_dpp v16, v16, v16 quad_perm:[2,3,0,1] row_mask:0xf bank_mask:0xf bound_ctrl:1
	s_nop 1
	v_add_f32_dpp v16, v16, v16 row_half_mirror row_mask:0xf bank_mask:0xf bound_ctrl:1
	s_nop 1
	v_add_f32_dpp v16, v16, v16 row_mirror row_mask:0xf bank_mask:0xf bound_ctrl:1
	v_fmamk_f32 v16, v16, 0x3c000000, v41
	v_mul_f32_e32 v17, 0x4b800000, v16
	v_cmp_gt_f32_e32 vcc, s19, v16
	s_nop 1
	v_cndmask_b32_e32 v16, v16, v17, vcc
	v_rsq_f32_e32 v18, v16
	v_lshlrev_b64 v[16:17], 8, v[30:31]
	v_mul_f32_e32 v19, 0x45800000, v18
	v_cndmask_b32_e32 v18, v18, v19, vcc
	v_mul_f32 v12, v18, v12
	v_mul_f32 v13, v18, v13
	v_mul_f32 v0, v18, v0
	v_mul_f32 v1, v18, v1
	v_mul_f32 v14, v18, v14
	v_mul_f32 v15, v18, v15
	v_mul_f32 v2, v18, v2
	v_mul_f32 v3, v18, v3
	s_waitcnt vmcnt(0)
	v_mul_f32 v4, v4, v12
	v_mul_f32 v5, v5, v13
	v_mul_f32 v6, v6, v0
	v_mul_f32 v7, v7, v1
	v_mul_f32 v0, v8, v14
	v_mul_f32 v1, v9, v15
	v_mul_f32 v2, v10, v2
	v_mul_f32 v3, v11, v3
	v_cvt_pk_bf16_f32 v8, v4, v5
	v_cvt_pk_bf16_f32 v9, v6, v7
	v_cvt_pk_bf16_f32 v10, v0, v1
	v_cvt_pk_bf16_f32 v11, v2, v3
	v_lshl_add_u64 v[12:13], v[22:23], 0, v[16:17]
	flat_store_dwordx4 v[12:13], v[8:11]
	s_and_saveexec_b64 s[10:11], s[4:5]
	s_cbranch_execz .LBB0_2245
	v_ashrrev_i32_e32 v8, 11, v43
	v_or_b32_e32 v8, 1, v8
	v_ashrrev_i32_e32 v9, 31, v8
	v_lshlrev_b64 v[8:9], 17, v[8:9]
	v_lshlrev_b32_e32 v10, 9, v30
	v_lshl_add_u64 v[8:9], s[8:9], 0, v[8:9]
	v_and_b32_e32 v20, 0x1fe00, v10
	v_lshl_add_u64 v[8:9], v[8:9], 0, v[20:21]
	v_mov_b32_e32 v29, v21
	v_lshl_add_u64 v[8:9], v[8:9], 0, v[28:29]
	flat_store_dwordx4 v[8:9], v[4:7]
	flat_store_dwordx4 v[8:9], v[0:3] offset:16
	s_branch .LBB0_2245

.LBB0_2258:
	v_ashrrev_i32_e32 v24, 4, v26
	v_mad_i64_i32 v[0:1], s[10:11], v24, s16, v[18:19]
	flat_load_dwordx4 v[4:7], v[0:1] offset:768
	global_load_dwordx4 v[8:11], v[16:17], off offset:512
	global_load_dwordx4 v[30:33], v[16:17], off offset:528
	v_lshl_add_u32 v28, s4, 9, v50
	v_ashrrev_i32_e32 v22, 4, v28
	v_mad_i64_i32 v[0:1], s[4:5], v22, s16, v[18:19]
	flat_load_dwordx4 v[0:3], v[0:1] offset:768
	v_ashrrev_i32_e32 v25, 31, v24
	v_cmp_gt_i32_e64 s[4:5], s17, v24
	s_waitcnt vmcnt(0) lgkmcnt(0)
	v_lshlrev_b32_e32 v34, 16, v4
	v_and_b32_e32 v35, 0xffff0000, v4
	v_lshlrev_b32_e32 v4, 16, v5
	v_and_b32_e32 v5, 0xffff0000, v5
	v_mul_f32 v46, v34, v34
	v_mul_f32 v47, v35, v35
	v_mul_f32 v44, v4, v4
	v_mul_f32 v45, v5, v5
	v_add_f32_e32 v12, v46, v47
	v_lshlrev_b32_e32 v36, 16, v6
	v_and_b32_e32 v37, 0xffff0000, v6
	v_add_f32_e32 v12, v12, v44
	v_mul_f32 v40, v36, v36
	v_mul_f32 v41, v37, v37
	v_add_f32_e32 v12, v45, v12
	v_lshlrev_b32_e32 v6, 16, v7
	v_and_b32_e32 v7, 0xffff0000, v7
	v_add_f32_e32 v12, v40, v12
	v_mul_f32 v38, v6, v6
	v_mul_f32 v39, v7, v7
	v_add_f32_e32 v12, v41, v12
	v_add_f32_e32 v12, v38, v12
	v_add_f32_e32 v12, v39, v12
	v_lshlrev_b64 v[38:39], 8, v[24:25]
	s_nop 0
	v_add_f32_dpp v12, v12, v12 quad_perm:[1,0,3,2] row_mask:0xf bank_mask:0xf bound_ctrl:1
	s_nop 1
	v_add_f32_dpp v12, v12, v12 quad_perm:[2,3,0,1] row_mask:0xf bank_mask:0xf bound_ctrl:1
	s_nop 1
	v_add_f32_dpp v12, v12, v12 row_half_mirror row_mask:0xf bank_mask:0xf bound_ctrl:1
	s_nop 1
	v_add_f32_dpp v12, v12, v12 row_mirror row_mask:0xf bank_mask:0xf bound_ctrl:1
	v_fmamk_f32 v12, v12, 0x3c000000, v27
	v_mul_f32_e32 v21, 0x4b800000, v12
	v_cmp_gt_f32_e32 vcc, s18, v12
	s_nop 1
	v_cndmask_b32_e32 v12, v12, v21, vcc
	v_rsq_f32_e32 v12, v12
	s_nop 0
	v_mul_f32_e32 v21, 0x45800000, v12
	v_cndmask_b32_e32 v12, v12, v21, vcc
	v_mul_f32 v34, v12, v34
	v_mul_f32 v35, v12, v35
	v_mul_f32 v4, v12, v4
	v_mul_f32 v5, v12, v5
	v_mul_f32 v36, v12, v36
	v_mul_f32 v37, v12, v37
	v_mul_f32 v6, v12, v6
	v_mul_f32 v7, v12, v7
	v_mul_f32 v8, v8, v34
	v_mul_f32 v9, v9, v35
	v_mul_f32 v10, v10, v4
	v_mul_f32 v11, v11, v5
	v_mul_f32 v4, v30, v36
	v_mul_f32 v5, v31, v37
	v_mul_f32 v6, v32, v6
	v_mul_f32 v7, v33, v7
	v_cvt_pk_bf16_f32 v30, v8, v9
	v_cvt_pk_bf16_f32 v31, v10, v11
	v_cvt_pk_bf16_f32 v32, v4, v5
	v_cvt_pk_bf16_f32 v33, v6, v7
	v_lshl_add_u64 v[34:35], v[14:15], 0, v[38:39]
	flat_store_dwordx4 v[34:35], v[30:33]
	s_and_saveexec_b64 s[10:11], s[4:5]
	s_cbranch_execz .LBB0_2260
	v_ashrrev_i32_e32 v12, 11, v26
	v_or_b32_e32 v30, 1, v12
	v_ashrrev_i32_e32 v31, 31, v30
	v_lshlrev_b64 v[30:31], 17, v[30:31]
	v_lshlrev_b32_e32 v12, 9, v24
	v_lshl_add_u64 v[30:31], s[8:9], 0, v[30:31]
	v_and_b32_e32 v12, 0x1fe00, v12
	v_lshl_add_u64 v[24:25], v[30:31], 0, v[12:13]
	v_mov_b32_e32 v21, v13
	v_lshl_add_u64 v[24:25], v[24:25], 0, v[20:21]
	flat_store_dwordx4 v[24:25], v[8:11]
	flat_store_dwordx4 v[24:25], v[4:7] offset:16
.LBB0_2260:
	s_or_b64 exec, exec, s[10:11]
	global_load_dwordx4 v[4:7], v[16:17], off offset:512
	global_load_dwordx4 v[8:11], v[16:17], off offset:528
	v_lshlrev_b32_e32 v24, 16, v0
	v_and_b32_e32 v25, 0xffff0000, v0
	v_lshlrev_b32_e32 v0, 16, v1
	v_and_b32_e32 v1, 0xffff0000, v1
	v_mul_f32 v38, v24, v24
	v_mul_f32 v39, v25, v25
	v_mul_f32 v36, v0, v0
	v_mul_f32 v37, v1, v1
	v_add_f32_e32 v12, v38, v39
	v_lshlrev_b32_e32 v30, 16, v2
	v_and_b32_e32 v31, 0xffff0000, v2
	v_add_f32_e32 v12, v12, v36
	v_mul_f32 v34, v30, v30
	v_mul_f32 v35, v31, v31
	v_add_f32_e32 v12, v37, v12
	v_lshlrev_b32_e32 v2, 16, v3
	v_and_b32_e32 v3, 0xffff0000, v3
	v_add_f32_e32 v12, v34, v12
	v_mul_f32 v32, v2, v2
	v_mul_f32 v33, v3, v3
	v_add_f32_e32 v12, v35, v12
	v_add_f32_e32 v12, v32, v12
	v_add_f32_e32 v12, v33, v12
	v_ashrrev_i32_e32 v23, 31, v22
	v_lshlrev_b64 v[32:33], 8, v[22:23]
	v_add_f32_dpp v12, v12, v12 quad_perm:[1,0,3,2] row_mask:0xf bank_mask:0xf bound_ctrl:1
	v_cmp_gt_i32_e64 s[4:5], s17, v22
	s_nop 0
	v_add_f32_dpp v12, v12, v12 quad_perm:[2,3,0,1] row_mask:0xf bank_mask:0xf bound_ctrl:1
	s_nop 1
	v_add_f32_dpp v12, v12, v12 row_half_mirror row_mask:0xf bank_mask:0xf bound_ctrl:1
	s_nop 1
	v_add_f32_dpp v12, v12, v12 row_mirror row_mask:0xf bank_mask:0xf bound_ctrl:1
	v_fmamk_f32 v12, v12, 0x3c000000, v27
	v_mul_f32_e32 v21, 0x4b800000, v12
	v_cmp_gt_f32_e32 vcc, s18, v12
	s_nop 1
	v_cndmask_b32_e32 v12, v12, v21, vcc
	v_rsq_f32_e32 v12, v12
	s_nop 0
	v_mul_f32_e32 v21, 0x45800000, v12
	v_cndmask_b32_e32 v12, v12, v21, vcc
	v_mul_f32 v24, v12, v24
	v_mul_f32 v25, v12, v25
	v_mul_f32 v0, v12, v0
	v_mul_f32 v1, v12, v1
	v_mul_f32 v30, v12, v30
	v_mul_f32 v31, v12, v31
	v_mul_f32 v2, v12, v2
	v_mul_f32 v3, v12, v3
	s_waitcnt vmcnt(0)
	v_mul_f32 v4, v4, v24
	v_mul_f32 v5, v5, v25
	v_mul_f32 v6, v6, v0
	v_mul_f32 v7, v7, v1
	v_mul_f32 v0, v8, v30
	v_mul_f32 v1, v9, v31
	v_mul_f32 v2, v10, v2
	v_mul_f32 v3, v11, v3
	v_cvt_pk_bf16_f32 v8, v4, v5
	v_cvt_pk_bf16_f32 v9, v6, v7
	v_cvt_pk_bf16_f32 v10, v0, v1
	v_cvt_pk_bf16_f32 v11, v2, v3
	v_lshl_add_u64 v[24:25], v[14:15], 0, v[32:33]
	flat_store_dwordx4 v[24:25], v[8:11]
	s_and_saveexec_b64 s[10:11], s[4:5]
	s_cbranch_execz .LBB0_2257
	v_ashrrev_i32_e32 v8, 11, v28
	v_or_b32_e32 v8, 1, v8
	v_ashrrev_i32_e32 v9, 31, v8
	v_lshlrev_b64 v[8:9], 17, v[8:9]
	v_lshlrev_b32_e32 v10, 9, v22
	v_lshl_add_u64 v[8:9], s[8:9], 0, v[8:9]
	v_and_b32_e32 v12, 0x1fe00, v10
	v_lshl_add_u64 v[8:9], v[8:9], 0, v[12:13]
	v_mov_b32_e32 v21, v13
	v_lshl_add_u64 v[8:9], v[8:9], 0, v[20:21]
	flat_store_dwordx4 v[8:9], v[4:7]
	flat_store_dwordx4 v[8:9], v[0:3] offset:16
	s_branch .LBB0_2257

.LBB0_2265:
	v_ashrrev_i32_e32 v18, 4, v20
	v_mad_i64_i32 v[26:27], s[4:5], v18, s11, v[14:15]
	flat_load_dwordx4 v[0:3], v[26:27] offset:768
	global_load_dwordx4 v[4:7], v[12:13], off offset:512
	global_load_dwordx4 v[22:25], v[12:13], off offset:528
	v_ashrrev_i32_e32 v19, 31, v18
	v_cmp_gt_i32_e64 s[4:5], s12, v18
	s_waitcnt vmcnt(0) lgkmcnt(0)
	v_lshlrev_b32_e32 v26, 16, v0
	v_and_b32_e32 v27, 0xffff0000, v0
	v_lshlrev_b32_e32 v0, 16, v1
	v_and_b32_e32 v1, 0xffff0000, v1
	v_mul_f32 v36, v26, v26
	v_mul_f32 v37, v27, v27
	v_mul_f32 v34, v0, v0
	v_mul_f32 v35, v1, v1
	v_add_f32_e32 v8, v36, v37
	v_lshlrev_b32_e32 v28, 16, v2
	v_and_b32_e32 v29, 0xffff0000, v2
	v_add_f32_e32 v8, v8, v34
	v_mul_f32 v32, v28, v28
	v_mul_f32 v33, v29, v29
	v_add_f32_e32 v8, v35, v8
	v_lshlrev_b32_e32 v2, 16, v3
	v_and_b32_e32 v3, 0xffff0000, v3
	v_add_f32_e32 v8, v32, v8
	v_mul_f32 v30, v2, v2
	v_mul_f32 v31, v3, v3
	v_add_f32_e32 v8, v33, v8
	v_add_f32_e32 v8, v30, v8
	v_add_f32_e32 v8, v31, v8
	v_lshlrev_b64 v[30:31], 8, v[18:19]
	s_nop 0
	v_add_f32_dpp v8, v8, v8 quad_perm:[1,0,3,2] row_mask:0xf bank_mask:0xf bound_ctrl:1
	s_nop 1
	v_add_f32_dpp v8, v8, v8 quad_perm:[2,3,0,1] row_mask:0xf bank_mask:0xf bound_ctrl:1
	s_nop 1
	v_add_f32_dpp v8, v8, v8 row_half_mirror row_mask:0xf bank_mask:0xf bound_ctrl:1
	s_nop 1
	v_add_f32_dpp v8, v8, v8 row_mirror row_mask:0xf bank_mask:0xf bound_ctrl:1
	v_fmamk_f32 v8, v8, 0x3c000000, v21
	v_mul_f32_e32 v17, 0x4b800000, v8
	v_cmp_gt_f32_e32 vcc, s13, v8
	s_nop 1
	v_cndmask_b32_e32 v8, v8, v17, vcc
	v_rsq_f32_e32 v8, v8
	s_nop 0
	v_mul_f32_e32 v17, 0x45800000, v8
	v_cndmask_b32_e32 v8, v8, v17, vcc
	v_mul_f32 v26, v8, v26
	v_mul_f32 v27, v8, v27
	v_mul_f32 v0, v8, v0
	v_mul_f32 v1, v8, v1
	v_mul_f32 v28, v8, v28
	v_mul_f32 v29, v8, v29
	v_mul_f32 v2, v8, v2
	v_mul_f32 v3, v8, v3
	v_mul_f32 v4, v4, v26
	v_mul_f32 v5, v5, v27
	v_mul_f32 v6, v6, v0
	v_mul_f32 v7, v7, v1
	v_mul_f32 v0, v22, v28
	v_mul_f32 v1, v23, v29
	v_mul_f32 v2, v24, v2
	v_mul_f32 v3, v25, v3
	v_cvt_pk_bf16_f32 v22, v4, v5
	v_cvt_pk_bf16_f32 v23, v6, v7
	v_cvt_pk_bf16_f32 v24, v0, v1
	v_cvt_pk_bf16_f32 v25, v2, v3
	v_lshl_add_u64 v[26:27], v[10:11], 0, v[30:31]
	flat_store_dwordx4 v[26:27], v[22:25]
	s_and_saveexec_b64 s[8:9], s[4:5]
	s_cbranch_execz .LBB0_2264
	v_ashrrev_i32_e32 v8, 11, v20
	v_or_b32_e32 v22, 1, v8
	v_ashrrev_i32_e32 v23, 31, v22
	v_lshlrev_b64 v[22:23], 17, v[22:23]
	v_lshlrev_b32_e32 v8, 9, v18
	v_lshl_add_u64 v[22:23], s[6:7], 0, v[22:23]
	v_and_b32_e32 v8, 0x1fe00, v8
	v_lshl_add_u64 v[18:19], v[22:23], 0, v[8:9]
	v_mov_b32_e32 v17, v9
	v_lshl_add_u64 v[18:19], v[18:19], 0, v[16:17]
	flat_store_dwordx4 v[18:19], v[4:7]
	flat_store_dwordx4 v[18:19], v[0:3] offset:16
	s_branch .LBB0_2264

.LBB0_2376:
	v_cmp_ne_u64_e64 s[8:9], 0, v[32:33]
	s_and_saveexec_b64 s[12:13], s[8:9]
	s_cbranch_execz .LBB0_2378
	flat_load_dwordx4 v[52:55], v[32:33]
	s_nop 0
	flat_load_dwordx4 v[30:33], v[32:33] offset:16
	s_waitcnt vmcnt(0) lgkmcnt(0)
	v_lshlrev_b32_e32 v18, 16, v12
	v_and_b32_e32 v12, 0xffff0000, v12
	v_and_b32_e32 v34, 0xffff0000, v13
	v_lshlrev_b32_e32 v56, 16, v14
	v_and_b32_e32 v14, 0xffff0000, v14
	v_and_b32_e32 v60, 0xffff0000, v15
	v_lshlrev_b32_e32 v26, 16, v13
	v_lshlrev_b32_e32 v58, 16, v15
	v_mul_f32 v13, v52, v12
	v_mul_f32 v12, v53, v12
	v_mul_f32 v35, v54, v34
	v_mul_f32 v34, v55, v34
	v_mul_f32 v15, v30, v14
	v_mul_f32 v14, v31, v14
	v_mul_f32 v61, v32, v60
	v_mul_f32 v60, v33, v60
	v_fma_f32 v62, v52, v18, -v12
	v_fma_f32 v63, v53, v19, -v13
	v_fma_f32 v12, v52, v18, v12
	v_fma_f32 v13, v53, v18, v13
	v_fma_f32 v52, v54, v26, -v34
	v_fma_f32 v53, v55, v27, -v35
	v_fma_f32 v27, v55, v26, v35
	v_fma_f32 v26, v54, v26, v34
	v_fma_f32 v34, v30, v56, -v14
	v_fma_f32 v35, v31, v57, -v15
	v_fma_f32 v14, v30, v56, v14
	v_fma_f32 v15, v31, v56, v15
	v_fma_f32 v30, v32, v58, -v60
	v_fma_f32 v31, v33, v59, -v61
	v_fma_f32 v32, v32, v58, v60
	v_fma_f32 v33, v33, v58, v61
	v_cvt_pk_bf16_f32 v12, v62, v13
	v_cvt_pk_bf16_f32 v13, v52, v27
	v_cvt_pk_bf16_f32 v14, v34, v15
	v_cvt_pk_bf16_f32 v15, v30, v33

.LBB0_2432:
	v_cmp_ne_u64_e64 s[4:5], 0, v[12:13]
	s_and_saveexec_b64 s[8:9], s[4:5]
	s_cbranch_execz .LBB0_2434
	flat_load_dwordx4 v[22:25], v[12:13]
	s_nop 0
	flat_load_dwordx4 v[10:13], v[12:13] offset:16
	v_lshlrev_b32_e32 v14, 16, v4
	v_and_b32_e32 v4, 0xffff0000, v4
	v_and_b32_e32 v26, 0xffff0000, v5
	v_lshlrev_b32_e32 v28, 16, v6
	v_and_b32_e32 v6, 0xffff0000, v6
	v_and_b32_e32 v32, 0xffff0000, v7
	v_lshlrev_b32_e32 v18, 16, v5
	v_lshlrev_b32_e32 v30, 16, v7
	s_waitcnt vmcnt(0) lgkmcnt(0)
	v_mul_f32 v5, v22, v4
	v_mul_f32 v4, v23, v4
	v_mul_f32 v27, v24, v26
	v_mul_f32 v26, v25, v26
	v_mul_f32 v7, v10, v6
	v_mul_f32 v6, v11, v6
	v_mul_f32 v33, v12, v32
	v_mul_f32 v32, v13, v32
	v_fma_f32 v34, v22, v14, -v4
	v_fma_f32 v35, v23, v15, -v5
	v_fma_f32 v4, v22, v14, v4
	v_fma_f32 v5, v23, v14, v5
	v_fma_f32 v14, v24, v18, -v26
	v_fma_f32 v15, v25, v19, -v27
	v_fma_f32 v22, v24, v18, v26
	v_fma_f32 v23, v25, v18, v27
	v_fma_f32 v24, v10, v28, -v6
	v_fma_f32 v25, v11, v29, -v7
	v_fma_f32 v6, v10, v28, v6
	v_fma_f32 v7, v11, v28, v7
	v_fma_f32 v10, v12, v30, -v32
	v_fma_f32 v11, v13, v31, -v33
	v_fma_f32 v12, v12, v30, v32
	v_fma_f32 v13, v13, v30, v33
	v_cvt_pk_bf16_f32 v4, v34, v5
	v_cvt_pk_bf16_f32 v5, v14, v23
	v_cvt_pk_bf16_f32 v6, v24, v7
	v_cvt_pk_bf16_f32 v7, v10, v13

.LBB0_2615:
	v_add_u32_e32 v18, s39, v53
	v_mad_i64_i32 v[22:23], s[4:5], v18, s54, v[16:17]
	s_waitcnt lgkmcnt(0)
	global_load_dwordx4 v[8:11], v51, s[56:57] offset:48
	global_load_dwordx4 v[0:3], v51, s[58:59] offset:48
	global_load_dwordx4 v[12:15], v51, s[56:57] offset:32
	global_load_dwordx4 v[4:7], v51, s[58:59] offset:32
	v_add_co_u32_e32 v36, vcc, 0x1000, v22
	v_add_u32_e32 v20, s2, v53
	s_nop 0
	v_addc_co_u32_e32 v37, vcc, 0, v23, vcc
	v_mad_i64_i32 v[34:35], s[4:5], v20, s54, v[16:17]
	flat_load_dwordx4 v[26:29], v[36:37] offset:64
	flat_load_dwordx4 v[30:33], v[36:37] offset:80
	v_add_co_u32_e32 v42, vcc, s55, v34
	s_add_i32 s3, s3, s33
	s_nop 0
	v_addc_co_u32_e32 v43, vcc, 0, v35, vcc
	flat_load_dwordx4 v[34:37], v[42:43] offset:64
	flat_load_dwordx4 v[38:41], v[42:43] offset:80
	s_add_i32 s4, s79, s3
	s_cmp_gt_i32 s4, 23
	v_ashrrev_i32_e32 v19, 31, v18
	v_lshlrev_b64 v[18:19], 5, v[18:19]
	v_lshl_add_u64 v[24:25], s[72:73], 0, v[18:19]
	v_lshl_add_u64 v[22:23], s[74:75], 0, v[18:19]
	v_ashrrev_i32_e32 v21, 31, v20
	v_lshlrev_b64 v[20:21], 5, v[20:21]
	v_lshl_add_u64 v[18:19], s[72:73], 0, v[20:21]
	v_lshl_add_u64 v[20:21], s[74:75], 0, v[20:21]
	v_add_u32_e32 v53, s38, v53
	s_waitcnt vmcnt(0)
	v_mul_f32_e32 v8, 0x3fb8aa3b, v8
	v_mul_f32_e32 v9, 0x3fb8aa3b, v9
	v_mul_f32_e32 v12, 0x3fb8aa3b, v12
	v_mul_f32_e32 v14, 0x3fb8aa3b, v14
	v_mul_f32_e32 v13, 0x3fb8aa3b, v13
	v_mul_f32_e32 v15, 0x3fb8aa3b, v15
	v_mul_f32_e32 v10, 0x3fb8aa3b, v10
	v_mul_f32_e32 v11, 0x3fb8aa3b, v11
	v_exp_f32_e32 v42, v12
	v_exp_f32_e32 v44, v14
	v_exp_f32_e32 v43, v13
	v_exp_f32_e32 v45, v15
	v_exp_f32_e32 v46, v8
	v_exp_f32_e32 v47, v9
	v_exp_f32_e32 v48, v10
	v_exp_f32_e32 v49, v11
	s_waitcnt lgkmcnt(0)
	v_lshlrev_b32_e32 v8, 16, v26
	v_and_b32_e32 v9, 0xffff0000, v26
	v_lshlrev_b32_e32 v10, 16, v27
	v_and_b32_e32 v11, 0xffff0000, v27
	v_lshlrev_b32_e32 v14, 16, v30
	v_and_b32_e32 v26, 0xffff0000, v30
	v_lshlrev_b32_e32 v27, 16, v31
	v_lshlrev_b32_e32 v12, 16, v28
	v_and_b32_e32 v13, 0xffff0000, v28
	v_lshlrev_b32_e32 v28, 16, v29
	v_and_b32_e32 v29, 0xffff0000, v29
	v_and_b32_e32 v30, 0xffff0000, v31
	v_lshlrev_b32_e32 v31, 16, v32
	v_and_b32_e32 v32, 0xffff0000, v32
	v_mul_f32_e32 v56, 0xbfb8aa3b, v14
	v_add_f32 v14, v4, v8
	v_add_f32 v15, v5, v9
	v_mul_f32_e32 v57, 0xbfb8aa3b, v26
	v_mul_f32_e32 v58, 0xbfb8aa3b, v27
	v_add_f32 v26, v6, v10
	v_add_f32 v27, v7, v11
	v_lshlrev_b32_e32 v54, 16, v33
	v_and_b32_e32 v55, 0xffff0000, v33
	v_xor_b32_e32 v8, 0x80000000, v42
	v_xor_b32_e32 v10, 0x80000000, v44
	v_mul_f32_e32 v42, 0xbfb8aa3b, v30
	v_mul_f32_e32 v44, 0xbfb8aa3b, v32
	v_add_f32 v32, v2, v28
	v_add_f32 v33, v3, v29
	v_lshlrev_b32_e32 v2, 16, v36
	v_and_b32_e32 v3, 0xffff0000, v36
	v_mul_f32_e32 v62, 0x3fb8aa3b, v15
	v_exp_f32_e32 v36, v58
	v_mul_f32_e32 v58, 0x3fb8aa3b, v27
	v_xor_b32_e32 v9, 0x80000000, v43
	v_xor_b32_e32 v11, 0x80000000, v45
	v_mul_f32_e32 v43, 0xbfb8aa3b, v31
	v_add_f32 v30, v0, v12
	v_add_f32 v31, v1, v13
	v_mul_f32_e32 v45, 0xbfb8aa3b, v54
	v_xor_b32_e32 v13, 0x80000000, v47
	v_xor_b32_e32 v12, 0x80000000, v46
	v_xor_b32_e32 v29, 0x80000000, v49
	v_xor_b32_e32 v28, 0x80000000, v48
	v_mul_f32_e32 v46, 0xbfb8aa3b, v55
	v_lshlrev_b32_e32 v6, 16, v34
	v_and_b32_e32 v7, 0xffff0000, v34
	v_lshlrev_b32_e32 v4, 16, v35
	v_and_b32_e32 v5, 0xffff0000, v35
	v_lshlrev_b32_e32 v0, 16, v37
	v_and_b32_e32 v1, 0xffff0000, v37
	v_lshlrev_b32_e32 v47, 16, v38
	v_and_b32_e32 v48, 0xffff0000, v38
	v_lshlrev_b32_e32 v49, 16, v39
	v_and_b32_e32 v54, 0xffff0000, v39
	v_lshlrev_b32_e32 v55, 16, v40
	v_and_b32_e32 v59, 0xffff0000, v40
	v_lshlrev_b32_e32 v60, 16, v41
	v_and_b32_e32 v61, 0xffff0000, v41
	v_exp_f32_e32 v34, v56
	v_mul_f32_e32 v56, 0x3fb8aa3b, v14
	v_exp_f32_e32 v35, v57
	v_mul_f32_e32 v57, 0x3fb8aa3b, v26
	v_exp_f32_e32 v37, v42
	v_exp_f32_e32 v62, v62
	v_exp_f32_e32 v58, v58
	v_exp_f32_e32 v38, v43
	v_mul_f32_e32 v42, 0x3fb8aa3b, v30
	v_mul_f32_e32 v43, 0x3fb8aa3b, v31
	v_exp_f32_e32 v40, v45
	v_exp_f32_e32 v41, v46
	v_mul_f32_e32 v46, 0xbfb8aa3b, v47
	v_mul_f32_e32 v47, 0xbfb8aa3b, v48
	v_mul_f32_e32 v48, 0xbfb8aa3b, v49
	v_mul_f32_e32 v49, 0xbfb8aa3b, v54
	v_mul_f32_e32 v54, 0xbfb8aa3b, v55
	v_mul_f32_e32 v55, 0xbfb8aa3b, v59
	v_mul_f32_e32 v59, 0xbfb8aa3b, v60
	v_mul_f32_e32 v60, 0xbfb8aa3b, v61
	v_exp_f32_e32 v61, v56
	v_exp_f32_e32 v63, v57
	v_exp_f32_e32 v39, v44
	v_mul_f32_e32 v44, 0x3fb8aa3b, v32
	v_mul_f32_e32 v45, 0x3fb8aa3b, v33
	v_exp_f32_e32 v64, v42
	v_exp_f32_e32 v65, v43
	v_exp_f32_e32 v42, v46
	v_exp_f32_e32 v43, v47
	v_exp_f32_e32 v46, v48
	v_exp_f32_e32 v47, v49
	v_exp_f32_e32 v54, v54
	v_exp_f32_e32 v55, v55
	v_exp_f32_e32 v56, v59
	v_exp_f32_e32 v57, v60
	v_exp_f32_e32 v66, v44
	v_exp_f32_e32 v67, v45
	v_add_f32 v48, v36, 1.0
	v_add_f32 v49, v37, 1.0
	v_add_f32_e32 v60, 1.0, v62
	v_add_f32_e32 v58, 1.0, v58
	v_add_f32 v44, v34, 1.0
	v_add_f32 v45, v35, 1.0
	v_add_f32 v40, v40, 1.0
	v_add_f32 v41, v41, 1.0
	v_add_f32_e32 v59, 1.0, v61
	v_add_f32_e32 v61, 1.0, v63
	v_div_scale_f32 v62, s[4:5], v49, v49, 1.0
	v_cmp_gt_f32_e64 s[40:41], s60, v60
	v_cmp_gt_f32_e64 s[44:45], s60, v58
	v_add_f32 v36, v38, 1.0
	v_add_f32 v37, v39, 1.0
	v_div_scale_f32 v68, s[4:5], v48, v48, 1.0
	v_div_scale_f32 v72, s[4:5], v44, v44, 1.0
	v_div_scale_f32 v74, s[4:5], v41, v41, 1.0
	v_add_f32 v42, v42, 1.0
	v_add_f32 v43, v43, 1.0
	v_add_f32 v46, v46, 1.0
	v_add_f32 v47, v47, 1.0
	v_add_f32 v34, v54, 1.0
	v_add_f32 v35, v55, 1.0
	v_add_f32 v38, v56, 1.0
	v_add_f32 v39, v57, 1.0
	v_cndmask_b32_e64 v55, 0, 32, s[40:41]
	v_cmp_gt_f32_e64 s[42:43], s60, v61
	v_cndmask_b32_e64 v57, 0, 32, s[44:45]
	v_rcp_f32_e32 v82, v62
	v_div_scale_f32 v70, s[4:5], v45, v45, 1.0
	v_add_f32_e32 v64, 1.0, v64
	v_add_f32_e32 v65, 1.0, v65
	v_add_f32_e32 v66, 1.0, v66
	v_add_f32_e32 v67, 1.0, v67
	v_div_scale_f32 v76, s[4:5], v40, v40, 1.0
	v_cmp_gt_f32_e64 s[36:37], s60, v59
	v_cndmask_b32_e64 v56, 0, 32, s[42:43]
	v_rcp_f32_e32 v83, v68
	v_rcp_f32_e32 v85, v72
	v_rcp_f32_e32 v90, v74
	v_div_scale_f32 v96, s[16:17], v46, v46, 1.0
	v_div_scale_f32 v100, s[16:17], v42, v42, 1.0
	v_div_scale_f32 v102, s[16:17], v39, v39, 1.0
	v_ldexp_f32 v55, v60, v55
	v_ldexp_f32 v57, v58, v57
	v_cndmask_b32_e64 v54, 0, 32, s[36:37]
	v_rcp_f32_e32 v84, v70
	v_cmp_gt_f32_e64 s[46:47], s60, v64
	v_cmp_gt_f32_e64 s[48:49], s60, v65
	v_cmp_gt_f32_e64 s[50:51], s60, v66
	v_cmp_gt_f32_e64 s[52:53], s60, v67
	v_rcp_f32_e32 v91, v76
	v_div_scale_f32 v98, s[16:17], v43, v43, 1.0
	v_div_scale_f32 v104, s[16:17], v38, v38, 1.0
	v_ldexp_f32 v56, v61, v56
	v_rcp_f32_e32 v111, v96
	v_rcp_f32_e32 v113, v100
	v_rcp_f32_e32 v114, v102
	v_log_f32_e32 v55, v55
	v_log_f32_e32 v57, v57
	v_div_scale_f32 v78, s[4:5], v37, v37, 1.0
	v_cndmask_b32_e64 v86, 0, 32, s[46:47]
	v_cndmask_b32_e64 v87, 0, 32, s[48:49]
	v_cndmask_b32_e64 v88, 0, 32, s[50:51]
	v_cndmask_b32_e64 v89, 0, 32, s[52:53]
	v_div_scale_f32 v94, s[16:17], v47, v47, 1.0
	v_ldexp_f32 v54, v59, v54
	v_rcp_f32_e32 v112, v98
	v_rcp_f32_e32 v115, v104
	v_log_f32_e32 v56, v56
	v_div_scale_f32 v80, s[4:5], v36, v36, 1.0
	v_rcp_f32_e32 v92, v78
	v_div_scale_f32 v106, s[16:17], v35, v35, 1.0
	v_ldexp_f32 v64, v64, v86
	v_ldexp_f32 v65, v65, v87
	v_ldexp_f32 v66, v66, v88
	v_ldexp_f32 v67, v67, v89
	v_rcp_f32_e32 v110, v94
	v_log_f32_e32 v54, v54
	v_fma_f32 v118, -v62, v82, 1.0
	v_div_scale_f32 v63, vcc, 1.0, v49, 1.0
	v_rcp_f32_e32 v93, v80
	v_div_scale_f32 v108, s[16:17], v34, v34, 1.0
	v_rcp_f32_e32 v116, v106
	v_log_f32_e32 v64, v64
	v_log_f32_e32 v65, v65
	v_log_f32_e32 v66, v66
	v_log_f32_e32 v67, v67
	v_fma_f32 v119, -v68, v83, 1.0
	v_fma_f32 v121, -v72, v85, 1.0
	v_fma_f32 v122, -v74, v90, 1.0
	v_fmac_f32_e32 v82, v118, v82
	v_div_scale_f32 v69, s[30:31], 1.0, v48, 1.0
	v_rcp_f32_e32 v117, v108
	v_fma_f32 v120, -v70, v84, 1.0
	v_fma_f32 v123, -v76, v91, 1.0
	v_fmac_f32_e32 v83, v119, v83
	v_fmac_f32_e32 v85, v121, v85
	v_fmac_f32_e32 v90, v122, v90
	v_fma_f32 v119, -v96, v111, 1.0
	v_fma_f32 v121, -v100, v113, 1.0
	v_fma_f32 v122, -v102, v114, 1.0
	v_mul_f32_e32 v127, 0x3f317217, v55
	v_mul_f32_e32 v129, 0x3f317217, v57
	v_mul_f32_e32 v130, v63, v82
	v_fmac_f32_e32 v84, v120, v84
	v_fmac_f32_e32 v91, v123, v91
	v_fma_f32 v120, -v98, v112, 1.0
	v_fma_f32 v123, -v104, v115, 1.0
	v_mul_f32_e32 v128, 0x3f317217, v56
	v_mul_f32_e32 v131, v69, v83
	v_fmac_f32_e32 v111, v119, v111
	v_fmac_f32_e32 v113, v121, v113
	v_fmac_f32_e32 v114, v122, v114
	v_fma_f32 v119, v55, s61, -v127
	v_fma_f32 v121, v57, s61, -v129
	v_fma_f32 v122, -v62, v130, v63
	v_div_scale_f32 v71, s[14:15], 1.0, v45, 1.0
	v_fma_f32 v124, -v78, v92, 1.0
	v_fma_f32 v118, -v94, v110, 1.0
	v_mul_f32_e32 v126, 0x3f317217, v54
	v_fmac_f32_e32 v112, v120, v112
	v_fmac_f32_e32 v115, v123, v115
	v_fma_f32 v120, v56, s61, -v128
	v_fma_f32 v123, -v68, v131, v69
	v_fmac_f32_e32 v119, 0x3377d1cf, v55
	v_fmac_f32_e32 v121, 0x3377d1cf, v57
	v_fmac_f32_e32 v130, v122, v82
	v_div_scale_f32 v73, s[10:11], 1.0, v44, 1.0
	v_cndmask_b32_e64 v59, 0, v52, s[36:37]
	v_cndmask_b32_e64 v61, 0, v52, s[42:43]
	v_fma_f32 v125, -v80, v93, 1.0
	v_fmac_f32_e32 v92, v124, v92
	v_fma_f32 v124, -v106, v116, 1.0
	v_mul_f32_e32 v132, v71, v84
	v_mul_f32_e32 v134, 0x3f317217, v64
	v_mul_f32_e32 v135, 0x3f317217, v65
	v_mul_f32_e32 v136, 0x3f317217, v66
	v_mul_f32_e32 v137, 0x3f317217, v67
	v_fmac_f32_e32 v110, v118, v110
	v_fma_f32 v118, v54, s61, -v126
	v_fmac_f32_e32 v120, 0x3377d1cf, v56
	v_fmac_f32_e32 v131, v123, v83
	v_fmac_f32_e32 v119, 0x3f317217, v55
	v_cmp_lt_f32_e64 s[36:37], |v55|, s62
	v_fmac_f32_e32 v121, 0x3f317217, v57
	v_cmp_lt_f32_e64 s[42:43], |v57|, s62
	v_fma_f32 v62, -v62, v130, v63
	v_div_scale_f32 v75, s[12:13], 1.0, v41, 1.0
	v_cndmask_b32_e64 v60, 0, v52, s[40:41]
	v_cndmask_b32_e64 v58, 0, v52, s[44:45]
	v_fmac_f32_e32 v93, v125, v93
	v_fma_f32 v125, -v108, v117, 1.0
	v_mul_f32_e32 v133, v73, v85
	v_fmac_f32_e32 v116, v124, v116
	v_fma_f32 v124, -v70, v132, v71
	v_fma_f32 v126, v64, s61, -v134
	v_fma_f32 v127, v65, s61, -v135
	v_fma_f32 v128, v66, s61, -v136
	v_fma_f32 v129, v67, s61, -v137
	v_fmac_f32_e32 v118, 0x3377d1cf, v54
	v_fmac_f32_e32 v120, 0x3f317217, v56
	v_cmp_lt_f32_e64 s[40:41], |v56|, s62
	v_fma_f32 v63, -v68, v131, v69
	v_cndmask_b32_e64 v55, v55, v119, s[36:37]
	v_cndmask_b32_e64 v57, v57, v121, s[42:43]
	v_div_fmas_f32 v62, v62, v82, v130
	s_mov_b64 vcc, s[30:31]
	v_div_scale_f32 v77, s[8:9], 1.0, v40, 1.0
	v_cndmask_b32_e64 v89, 0, v52, s[52:53]
	v_mul_f32_e32 v138, v75, v90
	v_fmac_f32_e32 v117, v125, v117
	v_fma_f32 v125, -v72, v133, v73
	v_fmac_f32_e32 v132, v124, v84
	v_fmac_f32_e32 v126, 0x3377d1cf, v64
	v_fmac_f32_e32 v127, 0x3377d1cf, v65
	v_fmac_f32_e32 v128, 0x3377d1cf, v66
	v_fmac_f32_e32 v129, 0x3377d1cf, v67
	v_fmac_f32_e32 v118, 0x3f317217, v54
	v_cmp_lt_f32_e64 s[52:53], |v54|, s62
	v_cndmask_b32_e64 v56, v56, v120, s[40:41]
	v_sub_f32_e32 v55, v55, v60
	v_sub_f32_e32 v58, v57, v58
	v_div_fixup_f32 v57, v62, v49, 1.0
	v_div_fmas_f32 v49, v63, v83, v131
	v_cmp_lt_f32_e32 vcc, s63, v15
	v_div_scale_f32 v79, s[6:7], 1.0, v37, 1.0
	v_cndmask_b32_e64 v86, 0, v52, s[46:47]
	v_cndmask_b32_e64 v87, 0, v52, s[48:49]
	v_cndmask_b32_e64 v88, 0, v52, s[50:51]
	v_mul_f32_e32 v139, v77, v91
	v_fma_f32 v134, -v74, v138, v75
	v_fmac_f32_e32 v133, v125, v85
	v_fma_f32 v68, -v70, v132, v71
	v_fmac_f32_e32 v126, 0x3f317217, v64
	v_cmp_lt_f32_e64 s[44:45], |v64|, s62
	v_fmac_f32_e32 v127, 0x3f317217, v65
	v_cmp_lt_f32_e64 s[46:47], |v65|, s62
	v_fmac_f32_e32 v128, 0x3f317217, v66
	v_cmp_lt_f32_e64 s[48:49], |v66|, s62
	v_fmac_f32_e32 v129, 0x3f317217, v67
	v_cmp_lt_f32_e64 s[50:51], |v67|, s62
	v_cndmask_b32_e64 v54, v54, v118, s[52:53]
	v_sub_f32_e32 v56, v56, v61
	v_cmp_lt_f32_e64 s[36:37], s63, v26
	v_cmp_lt_f32_e64 s[40:41], s63, v27
	v_cndmask_b32_e32 v15, v55, v15, vcc
	s_mov_b64 vcc, s[14:15]
	v_div_scale_f32 v81, s[4:5], 1.0, v36, 1.0
	v_mul_f32_e32 v140, v79, v92
	v_fma_f32 v135, -v76, v139, v77
	v_fmac_f32_e32 v138, v134, v90
	v_fma_f32 v69, -v72, v133, v73
	v_cndmask_b32_e64 v64, v64, v126, s[44:45]
	v_cndmask_b32_e64 v65, v65, v127, s[46:47]
	v_cndmask_b32_e64 v66, v66, v128, s[48:49]
	v_cndmask_b32_e64 v67, v67, v129, s[50:51]
	v_sub_f32_e32 v54, v54, v59
	v_cmp_lt_f32_e64 s[42:43], s63, v14
	v_cndmask_b32_e64 v27, v58, v27, s[40:41]
	v_cndmask_b32_e64 v26, v56, v26, s[36:37]
	v_div_fixup_f32 v56, v49, v48, 1.0
	v_div_fmas_f32 v48, v68, v84, v132
	s_mov_b64 vcc, s[10:11]
	v_mul_f32_e32 v141, v81, v93
	v_fma_f32 v136, -v78, v140, v79
	v_fmac_f32_e32 v139, v135, v91
	v_fma_f32 v70, -v74, v138, v75
	v_sub_f32_e32 v59, v64, v86
	v_sub_f32_e32 v60, v65, v87
	v_sub_f32_e32 v61, v66, v88
	v_sub_f32_e32 v62, v67, v89
	v_cmp_lt_f32_e64 s[30:31], s63, v32
	v_cmp_lt_f32_e64 s[44:45], s63, v33
	v_cmp_lt_f32_e64 s[46:47], s63, v30
	v_cmp_lt_f32_e64 s[48:49], s63, v31
	v_cndmask_b32_e64 v14, v54, v14, s[42:43]
	v_mul_f32 v10, v26, v10
	v_mul_f32 v11, v27, v11
	v_div_fmas_f32 v26, v69, v85, v133
	s_mov_b64 vcc, s[12:13]
	v_div_scale_f32 v95, s[34:35], 1.0, v47, 1.0
	v_fma_f32 v137, -v80, v141, v81
	v_fmac_f32_e32 v140, v136, v92
	v_fma_f32 v71, -v76, v139, v77
	v_cndmask_b32_e64 v31, v60, v31, s[48:49]
	v_cndmask_b32_e64 v30, v59, v30, s[46:47]
	v_cndmask_b32_e64 v33, v62, v33, s[44:45]
	v_cndmask_b32_e64 v32, v61, v32, s[30:31]
	v_mul_f32 v8, v14, v8
	v_mul_f32 v9, v15, v9
	v_div_fixup_f32 v54, v26, v44, 1.0
	v_div_fmas_f32 v26, v70, v90, v138
	s_mov_b64 vcc, s[8:9]
	v_mul_f32_e32 v142, v95, v110
	v_fmac_f32_e32 v141, v137, v93
	v_fma_f32 v72, -v78, v140, v79
	v_mul_f32 v14, v32, v28
	v_mul_f32 v15, v33, v29
	v_mul_f32 v12, v30, v12
	v_mul_f32 v13, v31, v13
	flat_store_dwordx4 v[24:25], v[8:11]
	flat_store_dwordx4 v[24:25], v[12:15] offset:16
	v_fma_f32 v122, -v94, v142, v95
	v_div_fmas_f32 v8, v71, v91, v139
	s_mov_b64 vcc, s[6:7]
	v_fma_f32 v73, -v80, v141, v81
	v_div_fixup_f32 v10, v8, v40, 1.0
	v_div_fmas_f32 v8, v72, v92, v140
	s_mov_b64 vcc, s[4:5]
	v_fmac_f32_e32 v142, v122, v110
	v_div_fixup_f32 v9, v8, v37, 1.0
	v_div_fmas_f32 v8, v73, v93, v141
	v_fma_f32 v74, -v94, v142, v95
	v_div_fixup_f32 v55, v48, v45, 1.0
	v_div_fixup_f32 v11, v26, v41, 1.0
	v_div_fixup_f32 v8, v8, v36, 1.0
	s_mov_b64 vcc, s[34:35]
	flat_store_dwordx4 v[22:23], v[54:57]
	v_div_fmas_f32 v12, v74, v110, v142
	flat_store_dwordx4 v[22:23], v[8:11] offset:16
	v_div_scale_f32 v97, s[28:29], 1.0, v46, 1.0
	s_nop 0
	v_div_fixup_f32 v11, v12, v47, 1.0
	global_load_dwordx4 v[12:15], v51, s[56:57] offset:32
	global_load_dwordx4 v[22:25], v51, s[58:59] offset:32
	global_load_dwordx4 v[26:29], v51, s[56:57] offset:48
	global_load_dwordx4 v[30:33], v51, s[58:59] offset:48
	v_div_scale_f32 v99, s[26:27], 1.0, v43, 1.0
	v_mul_f32_e32 v143, v97, v111
	v_div_scale_f32 v101, s[24:25], 1.0, v42, 1.0
	v_mul_f32_e32 v144, v99, v112
	v_fma_f32 v123, -v96, v143, v97
	v_div_scale_f32 v103, s[22:23], 1.0, v39, 1.0
	v_mul_f32_e32 v145, v101, v113
	v_fma_f32 v124, -v98, v144, v99
	v_fmac_f32_e32 v143, v123, v111
	v_div_scale_f32 v105, s[20:21], 1.0, v38, 1.0
	v_mul_f32_e32 v146, v103, v114
	v_fma_f32 v125, -v100, v145, v101
	v_fmac_f32_e32 v144, v124, v112
	v_fma_f32 v75, -v96, v143, v97
	s_mov_b64 vcc, s[28:29]
	v_div_scale_f32 v107, s[18:19], 1.0, v35, 1.0
	v_mul_f32_e32 v147, v105, v115
	v_fma_f32 v134, -v102, v146, v103
	v_fmac_f32_e32 v145, v125, v113
	v_fma_f32 v76, -v98, v144, v99
	v_div_fmas_f32 v8, v75, v111, v143
	s_mov_b64 vcc, s[26:27]
	v_div_scale_f32 v109, s[16:17], 1.0, v34, 1.0
	v_mul_f32_e32 v148, v107, v116
	v_fma_f32 v135, -v104, v147, v105
	v_fmac_f32_e32 v146, v134, v114
	v_fma_f32 v77, -v100, v145, v101
	v_div_fixup_f32 v10, v8, v46, 1.0
	v_div_fmas_f32 v8, v76, v112, v144
	s_mov_b64 vcc, s[24:25]
	v_mul_f32_e32 v149, v109, v117
	v_fma_f32 v136, -v106, v148, v107
	v_fmac_f32_e32 v147, v135, v115
	v_fma_f32 v78, -v102, v146, v103
	v_div_fixup_f32 v9, v8, v43, 1.0
	v_div_fmas_f32 v8, v77, v113, v145
	s_mov_b64 vcc, s[22:23]
	v_fma_f32 v137, -v108, v149, v109
	v_fmac_f32_e32 v148, v136, v116
	v_fma_f32 v79, -v104, v147, v105
	v_div_fmas_f32 v36, v78, v114, v146
	s_mov_b64 vcc, s[20:21]
	v_fmac_f32_e32 v149, v137, v117
	v_fma_f32 v80, -v106, v148, v107
	v_div_fixup_f32 v8, v8, v42, 1.0
	v_div_fixup_f32 v37, v36, v39, 1.0
	v_div_fmas_f32 v36, v79, v115, v147
	s_mov_b64 vcc, s[18:19]
	v_fma_f32 v81, -v108, v149, v109
	flat_store_dwordx4 v[20:21], v[8:11]
	v_div_fixup_f32 v36, v36, v38, 1.0
	s_waitcnt vmcnt(0)
	v_add_f32 v6, v22, v6
	v_add_f32 v7, v23, v7
	v_div_fmas_f32 v8, v80, v116, v148
	s_mov_b64 vcc, s[16:17]
	v_div_fixup_f32 v35, v8, v35, 1.0
	v_div_fmas_f32 v8, v81, v117, v149
	v_div_fixup_f32 v34, v8, v34, 1.0
	v_mul_f32_e32 v8, 0x3fb8aa3b, v12
	v_mul_f32_e32 v9, 0x3fb8aa3b, v13
	v_add_f32 v4, v24, v4
	v_add_f32 v5, v25, v5
	flat_store_dwordx4 v[20:21], v[34:37] offset:16
	v_mul_f32_e32 v10, 0x3fb8aa3b, v14
	v_mul_f32_e32 v11, 0x3fb8aa3b, v15
	v_mul_f32_e32 v12, 0x3fb8aa3b, v26
	v_mul_f32_e32 v13, 0x3fb8aa3b, v27
	v_add_f32 v2, v30, v2
	v_add_f32 v3, v31, v3
	v_add_f32 v0, v32, v0
	v_add_f32 v1, v33, v1
	v_exp_f32_e32 v20, v8
	v_exp_f32_e32 v21, v9
	v_mul_f32_e32 v8, 0x3fb8aa3b, v6
	v_mul_f32_e32 v9, 0x3fb8aa3b, v7
	v_mul_f32_e32 v22, 0x3fb8aa3b, v4
	v_mul_f32_e32 v23, 0x3fb8aa3b, v5
	v_mul_f32_e32 v14, 0x3fb8aa3b, v28
	v_mul_f32_e32 v15, 0x3fb8aa3b, v29
	v_exp_f32_e32 v10, v10
	v_exp_f32_e32 v11, v11
	v_exp_f32_e32 v24, v12
	v_exp_f32_e32 v25, v13
	v_mul_f32_e32 v12, 0x3fb8aa3b, v2
	v_mul_f32_e32 v13, 0x3fb8aa3b, v3
	v_mul_f32_e32 v26, 0x3fb8aa3b, v0
	v_mul_f32_e32 v27, 0x3fb8aa3b, v1
	v_exp_f32_e32 v28, v8
	v_exp_f32_e32 v29, v9
	v_exp_f32_e32 v22, v22
	v_exp_f32_e32 v23, v23
	v_exp_f32_e32 v14, v14
	v_exp_f32_e32 v15, v15
	v_exp_f32_e32 v30, v12
	v_exp_f32_e32 v31, v13
	v_exp_f32_e32 v26, v26
	v_exp_f32_e32 v27, v27
	v_xor_b32_e32 v9, 0x80000000, v11
	v_xor_b32_e32 v8, 0x80000000, v10
	v_xor_b32_e32 v11, 0x80000000, v21
	v_xor_b32_e32 v10, 0x80000000, v20
	v_add_f32_e32 v20, 1.0, v28
	v_add_f32_e32 v21, 1.0, v29
	v_add_f32_e32 v22, 1.0, v22
	v_add_f32_e32 v23, 1.0, v23
	v_xor_b32_e32 v13, 0x80000000, v15
	v_xor_b32_e32 v12, 0x80000000, v14
	v_xor_b32_e32 v15, 0x80000000, v25
	v_xor_b32_e32 v14, 0x80000000, v24
	v_add_f32_e32 v24, 1.0, v30
	v_add_f32_e32 v25, 1.0, v31
	v_add_f32_e32 v26, 1.0, v26
	v_add_f32_e32 v27, 1.0, v27
	v_cmp_gt_f32_e32 vcc, s60, v20
	v_cmp_gt_f32_e64 s[4:5], s60, v21
	v_cmp_gt_f32_e64 s[6:7], s60, v22
	v_cmp_gt_f32_e64 s[8:9], s60, v23
	v_cndmask_b32_e64 v28, 0, 32, vcc
	v_cndmask_b32_e64 v29, 0, 32, s[4:5]
	v_cndmask_b32_e64 v30, 0, 32, s[6:7]
	v_cndmask_b32_e64 v31, 0, 32, s[8:9]
	v_cmp_gt_f32_e64 s[10:11], s60, v24
	v_cmp_gt_f32_e64 s[12:13], s60, v25
	v_cmp_gt_f32_e64 s[14:15], s60, v26
	v_cmp_gt_f32_e64 s[16:17], s60, v27
	v_cndmask_b32_e64 v32, 0, 32, s[10:11]
	v_cndmask_b32_e64 v33, 0, 32, s[12:13]
	v_cndmask_b32_e64 v34, 0, 32, s[14:15]
	v_cndmask_b32_e64 v35, 0, 32, s[16:17]
	v_ldexp_f32 v20, v20, v28
	v_ldexp_f32 v21, v21, v29
	v_ldexp_f32 v22, v22, v30
	v_ldexp_f32 v23, v23, v31
	v_ldexp_f32 v24, v24, v32
	v_ldexp_f32 v25, v25, v33
	v_ldexp_f32 v26, v26, v34
	v_ldexp_f32 v27, v27, v35
	v_log_f32_e32 v20, v20
	v_log_f32_e32 v21, v21
	v_log_f32_e32 v22, v22
	v_log_f32_e32 v23, v23
	v_log_f32_e32 v24, v24
	v_log_f32_e32 v25, v25
	v_log_f32_e32 v26, v26
	v_log_f32_e32 v27, v27
	v_mul_f32_e32 v36, 0x3f317217, v20
	v_mul_f32_e32 v37, 0x3f317217, v21
	v_mul_f32_e32 v38, 0x3f317217, v22
	v_mul_f32_e32 v39, 0x3f317217, v23
	v_mul_f32_e32 v40, 0x3f317217, v24
	v_mul_f32_e32 v41, 0x3f317217, v25
	v_mul_f32_e32 v42, 0x3f317217, v26
	v_mul_f32_e32 v43, 0x3f317217, v27
	v_fma_f32 v36, v20, s61, -v36
	v_fma_f32 v37, v21, s61, -v37
	v_fma_f32 v38, v22, s61, -v38
	v_fma_f32 v39, v23, s61, -v39
	v_fma_f32 v40, v24, s61, -v40
	v_fma_f32 v41, v25, s61, -v41
	v_fma_f32 v42, v26, s61, -v42
	v_fma_f32 v43, v27, s61, -v43
	v_fmac_f32_e32 v36, 0x3377d1cf, v20
	v_fmac_f32_e32 v37, 0x3377d1cf, v21
	v_fmac_f32_e32 v38, 0x3377d1cf, v22
	v_fmac_f32_e32 v39, 0x3377d1cf, v23
	v_cndmask_b32_e32 v28, 0, v52, vcc
	v_cndmask_b32_e64 v29, 0, v52, s[4:5]
	v_cndmask_b32_e64 v30, 0, v52, s[6:7]
	v_cndmask_b32_e64 v35, 0, v52, s[16:17]
	v_fmac_f32_e32 v40, 0x3377d1cf, v24
	v_fmac_f32_e32 v41, 0x3377d1cf, v25
	v_fmac_f32_e32 v42, 0x3377d1cf, v26
	v_fmac_f32_e32 v43, 0x3377d1cf, v27
	v_fmac_f32_e32 v36, 0x3f317217, v20
	v_fmac_f32_e32 v37, 0x3f317217, v21
	v_cmp_lt_f32_e64 vcc, |v21|, s62
	v_fmac_f32_e32 v38, 0x3f317217, v22
	v_cmp_lt_f32_e64 s[4:5], |v22|, s62
	v_fmac_f32_e32 v39, 0x3f317217, v23
	v_cmp_lt_f32_e64 s[6:7], |v23|, s62
	v_cmp_lt_f32_e64 s[16:17], |v20|, s62
	v_cndmask_b32_e64 v31, 0, v52, s[8:9]
	v_cndmask_b32_e64 v32, 0, v52, s[10:11]
	v_cndmask_b32_e64 v33, 0, v52, s[12:13]
	v_cndmask_b32_e64 v34, 0, v52, s[14:15]
	v_fmac_f32_e32 v40, 0x3f317217, v24
	v_cmp_lt_f32_e64 s[8:9], |v24|, s62
	v_fmac_f32_e32 v41, 0x3f317217, v25
	v_cmp_lt_f32_e64 s[10:11], |v25|, s62
	v_fmac_f32_e32 v42, 0x3f317217, v26
	v_cmp_lt_f32_e64 s[12:13], |v26|, s62
	v_fmac_f32_e32 v43, 0x3f317217, v27
	v_cmp_lt_f32_e64 s[14:15], |v27|, s62
	v_cndmask_b32_e64 v20, v20, v36, s[16:17]
	v_cndmask_b32_e32 v21, v21, v37, vcc
	v_cndmask_b32_e64 v22, v22, v38, s[4:5]
	v_cndmask_b32_e64 v23, v23, v39, s[6:7]
	v_cndmask_b32_e64 v24, v24, v40, s[8:9]
	v_cndmask_b32_e64 v25, v25, v41, s[10:11]
	v_cndmask_b32_e64 v26, v26, v42, s[12:13]
	v_cndmask_b32_e64 v27, v27, v43, s[14:15]
	v_sub_f32_e32 v20, v20, v28
	v_sub_f32_e32 v21, v21, v29
	v_sub_f32_e32 v22, v22, v30
	v_sub_f32_e32 v23, v23, v31
	v_cmp_lt_f32_e32 vcc, s63, v6
	v_cmp_lt_f32_e64 s[4:5], s63, v7
	v_cmp_lt_f32_e64 s[6:7], s63, v4
	v_cmp_lt_f32_e64 s[16:17], s63, v5
	v_sub_f32_e32 v24, v24, v32
	v_sub_f32_e32 v25, v25, v33
	v_sub_f32_e32 v26, v26, v34
	v_sub_f32_e32 v27, v27, v35
	v_cmp_lt_f32_e64 s[8:9], s63, v2
	v_cmp_lt_f32_e64 s[10:11], s63, v3
	v_cmp_lt_f32_e64 s[12:13], s63, v0
	v_cmp_lt_f32_e64 s[14:15], s63, v1
	v_cndmask_b32_e64 v5, v23, v5, s[16:17]
	v_cndmask_b32_e64 v4, v22, v4, s[6:7]
	v_cndmask_b32_e64 v7, v21, v7, s[4:5]
	v_cndmask_b32_e32 v6, v20, v6, vcc
	v_cndmask_b32_e64 v21, v27, v1, s[14:15]
	v_cndmask_b32_e64 v20, v26, v0, s[12:13]
	v_cndmask_b32_e64 v23, v25, v3, s[10:11]
	v_cndmask_b32_e64 v22, v24, v2, s[8:9]
	v_mul_f32 v0, v6, v10
	v_mul_f32 v1, v7, v11
	v_mul_f32 v2, v4, v8
	v_mul_f32 v3, v5, v9
	v_mul_f32 v4, v22, v14
	v_mul_f32 v5, v23, v15
	v_mul_f32 v6, v20, v12
	v_mul_f32 v7, v21, v13
	flat_store_dwordx4 v[18:19], v[0:3]
	flat_store_dwordx4 v[18:19], v[4:7] offset:16
	s_cbranch_scc0 .LBB0_2615

.LBB0_2618:
	v_mad_i64_i32 v[0:1], s[4:5], v16, s10, v[18:19]
	s_waitcnt lgkmcnt(0)
	global_load_dwordx4 v[8:11], v22, s[12:13] offset:32
	v_add_co_u32_e32 v0, vcc, 0x1000, v0
	v_ashrrev_i32_e32 v17, 31, v16
	s_nop 0
	v_addc_co_u32_e32 v1, vcc, 0, v1, vcc
	flat_load_dwordx4 v[12:15], v[0:1] offset:64
	flat_load_dwordx4 v[24:27], v[0:1] offset:80
	global_load_dwordx4 v[28:31], v22, s[14:15] offset:32
	s_nop 0
	global_load_dwordx4 v[0:3], v22, s[12:13] offset:48
	global_load_dwordx4 v[4:7], v22, s[14:15] offset:48
	s_add_i32 s3, s3, s79
	s_cmp_lt_i32 s3, 24
	s_waitcnt vmcnt(0)
	v_mul_f32_e32 v8, 0x3fb8aa3b, v8
	v_mul_f32_e32 v9, 0x3fb8aa3b, v9
	v_exp_f32_e32 v34, v8
	v_exp_f32_e32 v35, v9
	s_waitcnt lgkmcnt(0)
	v_lshlrev_b32_e32 v8, 16, v12
	v_and_b32_e32 v9, 0xffff0000, v12
	v_mul_f32_e32 v10, 0x3fb8aa3b, v10
	v_mul_f32_e32 v11, 0x3fb8aa3b, v11
	v_add_f32 v8, v28, v8
	v_add_f32 v9, v29, v9
	v_exp_f32_e32 v36, v10
	v_exp_f32_e32 v37, v11
	v_lshlrev_b32_e32 v10, 16, v13
	v_and_b32_e32 v11, 0xffff0000, v13
	v_lshlrev_b32_e32 v12, 16, v24
	v_and_b32_e32 v13, 0xffff0000, v24
	v_mul_f32_e32 v24, 0x3fb8aa3b, v8
	v_lshlrev_b32_e32 v32, 16, v14
	v_and_b32_e32 v33, 0xffff0000, v14
	v_lshlrev_b32_e32 v20, 16, v15
	v_and_b32_e32 v21, 0xffff0000, v15
	v_lshlrev_b32_e32 v14, 16, v25
	v_and_b32_e32 v15, 0xffff0000, v25
	v_add_f32 v10, v30, v10
	v_add_f32 v11, v31, v11
	v_mul_f32_e32 v25, 0x3fb8aa3b, v9
	v_exp_f32_e32 v24, v24
	v_lshlrev_b32_e32 v38, 16, v26
	v_and_b32_e32 v39, 0xffff0000, v26
	v_mul_f32_e32 v26, 0x3fb8aa3b, v10
	v_exp_f32_e32 v25, v25
	v_lshlrev_b32_e32 v40, 16, v27
	v_and_b32_e32 v41, 0xffff0000, v27
	v_mul_f32_e32 v27, 0x3fb8aa3b, v11
	v_exp_f32_e32 v26, v26
	v_exp_f32_e32 v27, v27
	v_add_f32_e32 v24, 1.0, v24
	v_add_f32_e32 v25, 1.0, v25
	v_cmp_gt_f32_e32 vcc, s11, v24
	v_add_f32_e32 v26, 1.0, v26
	v_cmp_gt_f32_e64 s[4:5], s11, v25
	v_cndmask_b32_e64 v28, 0, 32, vcc
	v_add_f32_e32 v27, 1.0, v27
	v_cndmask_b32_e64 v29, 0, 32, s[4:5]
	v_cmp_gt_f32_e64 s[6:7], s11, v26
	v_ldexp_f32 v24, v24, v28
	v_cmp_gt_f32_e64 s[8:9], s11, v27
	v_cndmask_b32_e64 v30, 0, 32, s[6:7]
	v_ldexp_f32 v25, v25, v29
	v_log_f32_e32 v24, v24
	v_cndmask_b32_e64 v31, 0, 32, s[8:9]
	v_ldexp_f32 v26, v26, v30
	v_log_f32_e32 v25, v25
	v_ldexp_f32 v27, v27, v31
	v_log_f32_e32 v26, v26
	v_log_f32_e32 v27, v27
	v_mul_f32_e32 v31, 0x3f317217, v24
	v_mul_f32_e32 v42, 0x3f317217, v25
	v_fma_f32 v31, v24, s16, -v31
	v_mul_f32_e32 v14, 0xbfb8aa3b, v14
	v_mul_f32_e32 v43, 0x3f317217, v26
	v_fma_f32 v42, v25, s16, -v42
	v_fmac_f32_e32 v31, 0x3377d1cf, v24
	v_mul_f32_e32 v15, 0xbfb8aa3b, v15
	v_exp_f32_e32 v14, v14
	v_cndmask_b32_e32 v28, 0, v23, vcc
	v_mul_f32_e32 v44, 0x3f317217, v27
	v_fma_f32 v43, v26, s16, -v43
	v_fmac_f32_e32 v42, 0x3377d1cf, v25
	v_fmac_f32_e32 v31, 0x3f317217, v24
	v_cmp_lt_f32_e64 vcc, |v24|, s17
	v_exp_f32_e32 v15, v15
	v_fma_f32 v44, v27, s16, -v44
	v_fmac_f32_e32 v43, 0x3377d1cf, v26
	v_fmac_f32_e32 v42, 0x3f317217, v25
	v_cndmask_b32_e32 v24, v24, v31, vcc
	v_cmp_lt_f32_e64 vcc, |v25|, s17
	v_fmac_f32_e32 v44, 0x3377d1cf, v27
	v_fmac_f32_e32 v43, 0x3f317217, v26
	v_cndmask_b32_e32 v25, v25, v42, vcc
	v_cmp_lt_f32_e64 vcc, |v26|, s17
	v_fmac_f32_e32 v44, 0x3f317217, v27
	v_sub_f32_e32 v24, v24, v28
	v_cndmask_b32_e32 v26, v26, v43, vcc
	v_cmp_lt_f32_e64 vcc, |v27|, s17
	v_cndmask_b32_e64 v28, 0, v23, s[8:9]
	v_add_f32 v14, v14, 1.0
	v_add_f32 v15, v15, 1.0
	v_cndmask_b32_e32 v27, v27, v44, vcc
	v_cndmask_b32_e64 v29, 0, v23, s[4:5]
	v_sub_f32_e32 v27, v27, v28
	v_div_scale_f32 v28, s[4:5], v15, v15, 1.0
	v_sub_f32_e32 v25, v25, v29
	v_rcp_f32_e32 v29, v28
	v_cmp_lt_f32_e32 vcc, s18, v9
	v_cndmask_b32_e64 v30, 0, v23, s[6:7]
	v_sub_f32_e32 v26, v26, v30
	v_cndmask_b32_e32 v9, v25, v9, vcc
	v_cmp_lt_f32_e32 vcc, s18, v8
	v_xor_b32_e32 v25, 0x80000000, v35
	v_mul_f32_e32 v12, 0xbfb8aa3b, v12
	v_cndmask_b32_e32 v8, v24, v8, vcc
	v_cmp_lt_f32_e32 vcc, s18, v11
	v_xor_b32_e32 v24, 0x80000000, v34
	v_mul_f32 v8, v8, v24
	v_mul_f32 v9, v9, v25
	v_cndmask_b32_e32 v11, v27, v11, vcc
	v_cmp_lt_f32_e32 vcc, s18, v10
	v_fma_f32 v24, -v28, v29, 1.0
	v_fmac_f32_e32 v29, v24, v29
	v_cndmask_b32_e32 v10, v26, v10, vcc
	v_div_scale_f32 v24, vcc, 1.0, v15, 1.0
	v_xor_b32_e32 v27, 0x80000000, v37
	v_xor_b32_e32 v26, 0x80000000, v36
	v_mul_f32_e32 v25, v24, v29
	v_mul_f32 v10, v10, v26
	v_mul_f32 v11, v11, v27
	v_fma_f32 v26, -v28, v25, v24
	v_fmac_f32_e32 v25, v26, v29
	v_div_scale_f32 v26, s[4:5], v14, v14, 1.0
	v_rcp_f32_e32 v27, v26
	v_fma_f32 v24, -v28, v25, v24
	v_mul_f32_e32 v13, 0xbfb8aa3b, v13
	v_div_fmas_f32 v24, v24, v29, v25
	v_exp_f32_e32 v12, v12
	v_exp_f32_e32 v13, v13
	v_div_fixup_f32 v15, v24, v15, 1.0
	v_fma_f32 v24, -v26, v27, 1.0
	v_fmac_f32_e32 v27, v24, v27
	v_div_scale_f32 v24, vcc, 1.0, v14, 1.0
	v_mul_f32_e32 v25, v24, v27
	v_fma_f32 v28, -v26, v25, v24
	v_add_f32 v12, v12, 1.0
	v_add_f32 v13, v13, 1.0
	v_fmac_f32_e32 v25, v28, v27
	v_fma_f32 v24, -v26, v25, v24
	v_div_scale_f32 v26, s[4:5], v13, v13, 1.0
	v_rcp_f32_e32 v28, v26
	v_div_fmas_f32 v24, v24, v27, v25
	v_div_fixup_f32 v14, v24, v14, 1.0
	v_add_f32 v4, v4, v32
	v_add_f32 v5, v5, v33
	v_fma_f32 v24, -v26, v28, 1.0
	v_fmac_f32_e32 v28, v24, v28
	v_div_scale_f32 v24, vcc, 1.0, v13, 1.0
	v_mul_f32_e32 v25, v24, v28
	v_fma_f32 v27, -v26, v25, v24
	v_fmac_f32_e32 v25, v27, v28
	v_fma_f32 v24, -v26, v25, v24
	v_div_scale_f32 v26, s[4:5], v12, v12, 1.0
	v_rcp_f32_e32 v27, v26
	v_div_fmas_f32 v24, v24, v28, v25
	v_div_fixup_f32 v13, v24, v13, 1.0
	v_mul_f32_e32 v0, 0x3fb8aa3b, v0
	v_fma_f32 v24, -v26, v27, 1.0
	v_fmac_f32_e32 v27, v24, v27
	v_div_scale_f32 v24, vcc, 1.0, v12, 1.0
	v_mul_f32_e32 v25, v24, v27
	v_fma_f32 v28, -v26, v25, v24
	v_fmac_f32_e32 v25, v28, v27
	v_fma_f32 v24, -v26, v25, v24
	v_div_fmas_f32 v24, v24, v27, v25
	v_div_fixup_f32 v12, v24, v12, 1.0
	v_mul_f32_e32 v24, 0x3fb8aa3b, v4
	v_exp_f32_e32 v24, v24
	v_exp_f32_e32 v26, v0
	v_mul_f32_e32 v0, 0xbfb8aa3b, v38
	v_mul_f32_e32 v3, 0x3fb8aa3b, v3
	v_add_f32_e32 v24, 1.0, v24
	v_cmp_gt_f32_e32 vcc, s11, v24
	v_mul_f32_e32 v2, 0x3fb8aa3b, v2
	s_nop 0
	v_cndmask_b32_e64 v25, 0, 32, vcc
	v_ldexp_f32 v24, v24, v25
	v_log_f32_e32 v25, v24
	v_exp_f32_e32 v24, v0
	v_mul_f32_e32 v0, 0x3fb8aa3b, v1
	v_mul_f32_e32 v1, 0x3fb8aa3b, v5
	v_exp_f32_e32 v1, v1
	v_exp_f32_e32 v27, v0
	v_mul_f32_e32 v0, 0x3f317217, v25
	v_fma_f32 v0, v25, s16, -v0
	v_add_f32_e32 v1, 1.0, v1
	v_cmp_gt_f32_e64 s[4:5], s11, v1
	v_fmac_f32_e32 v0, 0x3377d1cf, v25
	v_fmac_f32_e32 v0, 0x3f317217, v25
	v_cndmask_b32_e64 v28, 0, 32, s[4:5]
	v_ldexp_f32 v1, v1, v28
	v_log_f32_e32 v1, v1
	v_cmp_lt_f32_e64 s[6:7], |v25|, s17
	s_nop 1
	v_cndmask_b32_e64 v0, v25, v0, s[6:7]
	v_cndmask_b32_e32 v25, 0, v23, vcc
	v_sub_f32_e32 v28, v0, v25
	v_mul_f32_e32 v0, 0x3f317217, v1
	v_fma_f32 v0, v1, s16, -v0
	v_fmac_f32_e32 v0, 0x3377d1cf, v1
	v_fmac_f32_e32 v0, 0x3f317217, v1
	v_cmp_lt_f32_e64 vcc, |v1|, s17
	s_nop 1
	v_cndmask_b32_e32 v0, v1, v0, vcc
	v_cndmask_b32_e64 v1, 0, v23, s[4:5]
	v_sub_f32_e32 v29, v0, v1
	v_mul_f32_e32 v0, 0xbfb8aa3b, v39
	v_exp_f32_e32 v25, v0
	v_add_f32 v0, v6, v20
	v_add_f32 v1, v7, v21
	v_exp_f32_e32 v21, v3
	v_mul_f32_e32 v6, 0x3fb8aa3b, v0
	v_exp_f32_e32 v6, v6
	v_exp_f32_e32 v20, v2
	v_mul_f32_e32 v2, 0xbfb8aa3b, v40
	v_exp_f32_e32 v2, v2
	v_add_f32_e32 v6, 1.0, v6
	v_cmp_gt_f32_e32 vcc, s11, v6
	v_xor_b32_e32 v21, 0x80000000, v21
	v_xor_b32_e32 v20, 0x80000000, v20
	v_cndmask_b32_e64 v7, 0, 32, vcc
	v_ldexp_f32 v6, v6, v7
	v_mul_f32_e32 v7, 0x3fb8aa3b, v1
	v_exp_f32_e32 v7, v7
	v_log_f32_e32 v6, v6
	v_add_f32_e32 v7, 1.0, v7
	v_cmp_gt_f32_e64 s[4:5], s11, v7
	v_mul_f32_e32 v3, 0x3f317217, v6
	v_fma_f32 v3, v6, s16, -v3
	v_cndmask_b32_e64 v30, 0, 32, s[4:5]
	v_ldexp_f32 v7, v7, v30
	v_log_f32_e32 v7, v7
	v_fmac_f32_e32 v3, 0x3377d1cf, v6
	v_fmac_f32_e32 v3, 0x3f317217, v6
	v_cmp_lt_f32_e64 s[6:7], |v6|, s17
	s_nop 1
	v_cndmask_b32_e64 v3, v6, v3, s[6:7]
	v_cndmask_b32_e32 v6, 0, v23, vcc
	v_sub_f32_e32 v3, v3, v6
	v_mul_f32_e32 v6, 0x3f317217, v7
	v_fma_f32 v6, v7, s16, -v6
	v_fmac_f32_e32 v6, 0x3377d1cf, v7
	v_fmac_f32_e32 v6, 0x3f317217, v7
	v_cmp_lt_f32_e64 vcc, |v7|, s17
	s_nop 1
	v_cndmask_b32_e32 v6, v7, v6, vcc
	v_cmp_lt_f32_e32 vcc, s18, v5
	v_cndmask_b32_e64 v7, 0, v23, s[4:5]
	v_sub_f32_e32 v6, v6, v7
	v_cndmask_b32_e32 v5, v29, v5, vcc
	v_cmp_lt_f32_e32 vcc, s18, v4
	v_xor_b32_e32 v7, 0x80000000, v27
	s_nop 0
	v_cndmask_b32_e32 v4, v28, v4, vcc
	v_cmp_lt_f32_e32 vcc, s18, v1
	s_nop 1
	v_cndmask_b32_e32 v1, v6, v1, vcc
	v_cmp_lt_f32_e32 vcc, s18, v0
	v_xor_b32_e32 v6, 0x80000000, v26
	s_nop 0
	v_cndmask_b32_e32 v0, v3, v0, vcc
	v_mul_f32_e32 v3, 0xbfb8aa3b, v41
	v_exp_f32_e32 v3, v3
	s_nop 0
	v_add_f32 v26, v2, 1.0
	v_add_f32 v27, v3, 1.0
	s_nop 0
	v_div_scale_f32 v28, s[4:5], v27, v27, 1.0
	v_rcp_f32_e32 v29, v28
	v_mul_f32 v2, v0, v20
	v_mul_f32 v3, v1, v21
	v_mul_f32 v0, v4, v6
	v_mul_f32 v1, v5, v7
	v_add_f32 v4, v24, 1.0
	v_add_f32 v5, v25, 1.0
	v_fma_f32 v6, -v28, v29, 1.0
	v_fmac_f32_e32 v29, v6, v29
	v_div_scale_f32 v6, vcc, 1.0, v27, 1.0
	v_mul_f32_e32 v7, v6, v29
	v_fma_f32 v20, -v28, v7, v6
	v_fmac_f32_e32 v7, v20, v29
	v_div_scale_f32 v20, s[4:5], v26, v26, 1.0
	v_rcp_f32_e32 v21, v20
	v_fma_f32 v6, -v28, v7, v6
	v_div_fmas_f32 v6, v6, v29, v7
	v_div_fixup_f32 v7, v6, v27, 1.0
	v_fma_f32 v6, -v20, v21, 1.0
	v_fmac_f32_e32 v21, v6, v21
	v_div_scale_f32 v6, vcc, 1.0, v26, 1.0
	v_mul_f32_e32 v24, v6, v21
	v_fma_f32 v25, -v20, v24, v6
	v_fmac_f32_e32 v24, v25, v21
	v_fma_f32 v6, -v20, v24, v6
	v_div_scale_f32 v20, s[4:5], v5, v5, 1.0
	v_rcp_f32_e32 v25, v20
	v_div_fmas_f32 v6, v6, v21, v24
	v_div_fixup_f32 v6, v6, v26, 1.0
	v_fma_f32 v21, -v20, v25, 1.0
	v_fmac_f32_e32 v25, v21, v25
	v_div_scale_f32 v21, vcc, 1.0, v5, 1.0
	v_mul_f32_e32 v24, v21, v25
	v_fma_f32 v26, -v20, v24, v21
	v_fmac_f32_e32 v24, v26, v25
	v_fma_f32 v20, -v20, v24, v21
	v_div_scale_f32 v21, s[4:5], v4, v4, 1.0
	v_rcp_f32_e32 v26, v21
	v_div_fmas_f32 v20, v20, v25, v24
	v_div_fixup_f32 v5, v20, v5, 1.0
	v_fma_f32 v20, -v21, v26, 1.0
	v_fmac_f32_e32 v26, v20, v26
	v_div_scale_f32 v20, vcc, 1.0, v4, 1.0
	v_mul_f32_e32 v24, v20, v26
	v_fma_f32 v25, -v21, v24, v20
	v_fmac_f32_e32 v24, v25, v26
	v_fma_f32 v20, -v21, v24, v20
	v_div_fmas_f32 v20, v20, v26, v24
	v_div_fixup_f32 v4, v20, v4, 1.0
	v_lshlrev_b64 v[20:21], 5, v[16:17]
	v_lshl_add_u64 v[24:25], s[72:73], 0, v[20:21]
	flat_store_dwordx4 v[24:25], v[8:11]
	flat_store_dwordx4 v[24:25], v[0:3] offset:16
	v_add_u32_e32 v16, s2, v16
	s_nop 0
	v_lshl_add_u64 v[0:1], s[74:75], 0, v[20:21]
	flat_store_dwordx4 v[0:1], v[12:15]
	flat_store_dwordx4 v[0:1], v[4:7] offset:16
	s_cbranch_scc1 .LBB0_2618

.LBB0_2621:
	s_or_b64 exec, exec, s[6:7]
	s_waitcnt lgkmcnt(0)
	v_lshl_add_u64 v[40:41], v[54:55], 2, s[20:21]
	v_add_co_u32_e32 v82, vcc, 0x2000, v40
	v_lshl_add_u64 v[42:43], v[40:41], 0, s[14:15]
	s_nop 0
	v_addc_co_u32_e32 v83, vcc, 0, v41, vcc
	global_load_dwordx4 v[74:77], v[82:83], off offset:1024
	global_load_dwordx4 v[24:27], v[42:43], off offset:3088
	global_load_dwordx4 v[36:39], v[42:43], off offset:16
	global_load_dwordx4 v[78:81], v[42:43], off offset:3072
	v_add_co_u32_e32 v88, vcc, s2, v40
	v_lshl_add_u64 v[86:87], v[40:41], 0, s[16:17]
	s_nop 0
	v_addc_co_u32_e32 v89, vcc, 0, v41, vcc
	global_load_dwordx4 v[82:85], v[88:89], off offset:3072
	global_load_dwordx4 v[40:43], v[86:87], off offset:16
	s_waitcnt vmcnt(0)
	v_lshlrev_b32_e32 v87, 16, v0
	v_lshlrev_b32_e32 v86, 16, v4
	v_lshlrev_b32_e32 v91, 16, v1
	v_lshlrev_b32_e32 v90, 16, v5
	v_and_b32_e32 v93, 0xffff0000, v1
	v_and_b32_e32 v92, 0xffff0000, v5
	v_lshlrev_b32_e32 v95, 16, v2
	v_and_b32_e32 v97, 0xffff0000, v2
	v_lshlrev_b32_e32 v5, 16, v3
	v_and_b32_e32 v1, 0xffff0000, v3
	v_lshlrev_b32_e32 v3, 16, v20
	v_lshlrev_b32_e32 v2, 16, v16
	v_pk_mov_b32 v[130:131], v[86:87], v[2:3] op_sel:[1,0]
	v_and_b32_e32 v89, 0xffff0000, v0
	v_and_b32_e32 v88, 0xffff0000, v4
	v_lshlrev_b32_e32 v94, 16, v6
	v_and_b32_e32 v96, 0xffff0000, v6
	v_lshlrev_b32_e32 v4, 16, v7
	v_and_b32_e32 v0, 0xffff0000, v7
	v_and_b32_e32 v7, 0xffff0000, v20
	v_and_b32_e32 v6, 0xffff0000, v16
	v_lshlrev_b32_e32 v98, 16, v17
	v_and_b32_e32 v20, 0xffff0000, v17
	v_lshlrev_b32_e32 v17, 16, v22
	v_lshlrev_b32_e32 v16, 16, v18
	v_and_b32_e32 v101, 0xffff0000, v22
	v_and_b32_e32 v100, 0xffff0000, v18
	v_lshlrev_b32_e32 v102, 16, v19
	v_and_b32_e32 v22, 0xffff0000, v19
	v_lshlrev_b32_e32 v19, 16, v32
	v_lshlrev_b32_e32 v18, 16, v28
	v_and_b32_e32 v105, 0xffff0000, v32
	v_and_b32_e32 v104, 0xffff0000, v28
	v_lshlrev_b32_e32 v106, 16, v29
	v_and_b32_e32 v32, 0xffff0000, v29
	v_lshlrev_b32_e32 v29, 16, v34
	v_lshlrev_b32_e32 v28, 16, v30
	v_and_b32_e32 v109, 0xffff0000, v34
	v_and_b32_e32 v108, 0xffff0000, v30
	v_lshlrev_b32_e32 v110, 16, v31
	v_and_b32_e32 v34, 0xffff0000, v31
	v_lshlrev_b32_e32 v30, 16, v48
	v_lshlrev_b32_e32 v31, 16, v44
	v_lshlrev_b32_e32 v129, 16, v12
	v_mov_b32_e32 v128, v31
	v_mov_b32_e32 v126, v129
	v_and_b32_e32 v113, 0xffff0000, v44
	v_and_b32_e32 v112, 0xffff0000, v48
	v_lshlrev_b32_e32 v99, 16, v21
	v_lshlrev_b32_e32 v44, 16, v49
	v_and_b32_e32 v114, 0xffff0000, v49
	v_lshlrev_b32_e32 v48, 16, v50
	v_lshlrev_b32_e32 v49, 16, v46
	v_and_b32_e32 v117, 0xffff0000, v46
	v_and_b32_e32 v116, 0xffff0000, v50
	v_lshlrev_b32_e32 v46, 16, v51
	v_and_b32_e32 v118, 0xffff0000, v51
	v_and_b32_e32 v51, 0xffff0000, v12
	v_mov_b32_e32 v50, v113
	v_lshlrev_b32_e32 v127, 16, v8
	v_lshlrev_b32_e32 v107, 16, v33
	v_and_b32_e32 v115, 0xffff0000, v45
	v_lshlrev_b32_e32 v45, 16, v45
	v_and_b32_e32 v121, 0xffff0000, v13
	v_lshlrev_b32_e32 v13, 16, v13
	v_mov_b32_e32 v12, v45
	v_and_b32_e32 v21, 0xffff0000, v21
	v_and_b32_e32 v33, 0xffff0000, v33
	v_mov_b32_e32 v120, v115
	v_and_b32_e32 v123, 0xffff0000, v14
	v_mov_b32_e32 v122, v117
	v_lshlrev_b32_e32 v103, 16, v23
	v_and_b32_e32 v119, 0xffff0000, v47
	v_mul_f32 v130, v78, v130
	v_mul_f32 v131, v78, v131
	v_fma_f32 v86, v74, v86, v130
	v_fma_f32 v87, v74, v87, v131
	v_pk_mov_b32 v[130:131], v[2:3], v[18:19] op_sel:[1,0]
	v_mul_f32 v128, v78, v128
	v_mul_f32 v129, v78, v129
	v_mul_f32 v130, v78, v130
	v_mul_f32 v131, v78, v131
	v_fma_f32 v86, v82, v2, v86
	v_fma_f32 v87, v82, v3, v87
	v_fma_f32 v2, v74, v2, v130
	v_fma_f32 v3, v74, v3, v131
	v_pk_mov_b32 v[130:131], v[18:19], v[30:31] op_sel:[1,0]
	v_fma_f32 v2, v82, v18, v2
	v_fma_f32 v3, v82, v19, v3
	v_mul_f32 v130, v78, v130
	v_mul_f32 v131, v78, v131
	v_fma_f32 v18, v74, v18, v130
	v_fma_f32 v19, v74, v19, v131
	v_fma_f32 v18, v82, v30, v18
	v_fma_f32 v19, v82, v31, v19
	v_fma_f32 v30, v74, v30, v128
	v_fma_f32 v31, v74, v31, v129
	v_pk_mov_b32 v[128:129], v[88:89], v[6:7] op_sel:[1,0]
	v_fma_f32 v30, v82, v126, v30
	v_fma_f32 v31, v82, v127, v31
	v_mul_f32 v128, v79, v128
	v_mul_f32 v129, v79, v129
	v_mov_b32_e32 v126, v51
	v_fma_f32 v88, v75, v88, v128
	v_fma_f32 v89, v75, v89, v129
	v_pk_mov_b32 v[128:129], v[6:7], v[104:105] op_sel:[1,0]
	v_fma_f32 v88, v83, v6, v88
	v_fma_f32 v89, v83, v7, v89
	v_mul_f32 v128, v79, v128
	v_mul_f32 v129, v79, v129
	v_mul_f32 v50, v79, v50
	v_mul_f32 v51, v79, v51
	v_fma_f32 v6, v75, v6, v128
	v_fma_f32 v7, v75, v7, v129
	v_pk_mov_b32 v[128:129], v[104:105], v[112:113] op_sel:[1,0]
	v_and_b32_e32 v127, 0xffff0000, v8
	v_mul_f32 v128, v79, v128
	v_mul_f32 v129, v79, v129
	v_pk_mov_b32 v[78:79], v[90:91], v[98:99] op_sel:[1,0]
	v_fma_f32 v6, v83, v104, v6
	v_fma_f32 v7, v83, v105, v7
	v_mul_f32 v78, v80, v78
	v_mul_f32 v79, v80, v79
	v_fma_f32 v104, v75, v104, v128
	v_fma_f32 v105, v75, v105, v129
	v_fma_f32 v50, v75, v112, v50
	v_fma_f32 v51, v75, v113, v51
	v_fma_f32 v78, v76, v90, v78
	v_fma_f32 v79, v76, v91, v79
	v_pk_mov_b32 v[90:91], v[106:107], v[44:45] op_sel:[1,0]
	v_fma_f32 v104, v83, v112, v104
	v_fma_f32 v105, v83, v113, v105
	v_fma_f32 v50, v83, v126, v50
	v_fma_f32 v51, v83, v127, v51
	v_pk_mov_b32 v[82:83], v[98:99], v[106:107] op_sel:[1,0]
	v_mul_f32 v90, v80, v90
	v_mul_f32 v91, v80, v91
	v_mov_b32_e32 v74, v13
	v_mul_f32 v12, v80, v12
	v_mul_f32 v13, v80, v13
	v_lshlrev_b32_e32 v75, 16, v9
	v_mul_f32 v82, v80, v82
	v_mul_f32 v83, v80, v83
	v_fma_f32 v90, v76, v106, v90
	v_fma_f32 v91, v76, v107, v91
	v_fma_f32 v12, v76, v44, v12
	v_fma_f32 v13, v76, v45, v13
	v_fma_f32 v82, v76, v98, v82
	v_fma_f32 v83, v76, v99, v83
	v_fma_f32 v90, v84, v44, v90
	v_fma_f32 v91, v84, v45, v91
	v_fma_f32 v12, v84, v74, v12
	v_fma_f32 v13, v84, v75, v13
	v_mov_b32_e32 v44, v77
	v_mov_b32_e32 v74, v81
	v_pk_mov_b32 v[76:77], v[92:93], v[20:21] op_sel:[1,0]
	v_fma_f32 v78, v84, v98, v78
	v_fma_f32 v79, v84, v99, v79
	v_fma_f32 v82, v84, v106, v82
	v_fma_f32 v83, v84, v107, v83
	v_mul_f32 v76, v74, v76
	v_mul_f32 v77, v74, v77
	v_mov_b32_e32 v80, v85
	v_pk_mov_b32 v[84:85], v[20:21], v[32:33] op_sel:[1,0]
	v_fma_f32 v76, v44, v92, v76
	v_fma_f32 v77, v44, v93, v77
	v_mul_f32 v84, v74, v84
	v_mul_f32 v85, v74, v85
	v_fma_f32 v76, v80, v20, v76
	v_fma_f32 v77, v80, v21, v77
	v_fma_f32 v20, v44, v20, v84
	v_fma_f32 v21, v44, v21, v85
	v_pk_mov_b32 v[84:85], v[32:33], v[114:115] op_sel:[1,0]
	v_and_b32_e32 v9, 0xffff0000, v9
	v_mul_f32 v84, v74, v84
	v_mul_f32 v85, v74, v85
	v_mul_f32 v75, v74, v121
	v_mul_f32 v74, v74, v120
	v_mov_b32_e32 v8, v121
	v_fma_f32 v20, v80, v32, v20
	v_fma_f32 v21, v80, v33, v21
	v_fma_f32 v32, v44, v32, v84
	v_fma_f32 v33, v44, v33, v85
	v_fma_f32 v45, v44, v115, v75
	v_fma_f32 v44, v44, v114, v74
	v_fma_f32 v32, v80, v114, v32
	v_fma_f32 v33, v80, v115, v33
	v_fma_f32 v8, v80, v8, v44
	v_fma_f32 v9, v80, v9, v45
	v_pk_mov_b32 v[80:81], v[94:95], v[16:17] op_sel:[1,0]
	v_pk_mov_b32 v[84:85], v[16:17], v[28:29] op_sel:[1,0]
	v_mul_f32 v80, v24, v80
	v_mul_f32 v81, v24, v81
	v_fma_f32 v80, v36, v94, v80
	v_fma_f32 v81, v36, v95, v81
	v_mul_f32 v84, v24, v84
	v_mul_f32 v85, v24, v85
	v_fma_f32 v80, v40, v16, v80
	v_fma_f32 v81, v40, v17, v81
	v_fma_f32 v16, v36, v16, v84
	v_fma_f32 v17, v36, v17, v85
	v_pk_mov_b32 v[84:85], v[28:29], v[48:49] op_sel:[1,0]
	v_lshlrev_b32_e32 v75, 16, v14
	v_mov_b32_e32 v74, v49
	v_mul_f32 v84, v24, v84
	v_mul_f32 v85, v24, v85
	v_fma_f32 v16, v40, v28, v16
	v_fma_f32 v17, v40, v29, v17
	v_fma_f32 v28, v36, v28, v84
	v_fma_f32 v29, v36, v29, v85
	v_mov_b32_e32 v44, v75
	v_mul_f32 v74, v24, v74
	v_mul_f32 v75, v24, v75
	v_fma_f32 v28, v40, v48, v28
	v_fma_f32 v29, v40, v49, v29
	v_fma_f32 v48, v36, v48, v74
	v_fma_f32 v49, v36, v49, v75
	v_pk_mov_b32 v[74:75], v[96:97], v[100:101] op_sel:[1,0]
	v_pk_mov_b32 v[84:85], v[100:101], v[108:109] op_sel:[1,0]
	v_pk_mov_b32 v[92:93], v[108:109], v[116:117] op_sel:[1,0]
	v_lshlrev_b32_e32 v45, 16, v10
	v_mul_f32 v74, v25, v74
	v_mul_f32 v75, v25, v75
	v_mul_f32 v84, v25, v84
	v_mul_f32 v85, v25, v85
	v_mul_f32 v92, v25, v92
	v_mul_f32 v93, v25, v93
	v_mul_f32 v24, v25, v122
	v_mul_f32 v25, v25, v123
	v_fma_f32 v44, v40, v44, v48
	v_fma_f32 v45, v40, v45, v49
	v_and_b32_e32 v49, 0xffff0000, v10
	v_mov_b32_e32 v48, v123
	v_fma_f32 v74, v37, v96, v74
	v_fma_f32 v75, v37, v97, v75
	v_fma_f32 v84, v37, v100, v84
	v_fma_f32 v85, v37, v101, v85
	v_fma_f32 v92, v37, v108, v92
	v_fma_f32 v93, v37, v109, v93
	v_fma_f32 v24, v37, v116, v24
	v_fma_f32 v25, v37, v117, v25
	v_lshlrev_b32_e32 v47, 16, v47
	v_fma_f32 v74, v41, v100, v74
	v_fma_f32 v75, v41, v101, v75
	v_fma_f32 v84, v41, v108, v84
	v_fma_f32 v85, v41, v109, v85
	v_fma_f32 v92, v41, v116, v92
	v_fma_f32 v93, v41, v117, v93
	v_fma_f32 v24, v41, v48, v24
	v_fma_f32 v25, v41, v49, v25
	v_pk_mov_b32 v[40:41], v[4:5], v[102:103] op_sel:[1,0]
	v_lshlrev_b32_e32 v111, 16, v35
	v_and_b32_e32 v125, 0xffff0000, v15
	v_lshlrev_b32_e32 v15, 16, v15
	v_mov_b32_e32 v14, v47
	v_mul_f32 v40, v26, v40
	v_mul_f32 v41, v26, v41
	v_fma_f32 v4, v38, v4, v40
	v_fma_f32 v5, v38, v5, v41
	v_pk_mov_b32 v[40:41], v[102:103], v[110:111] op_sel:[1,0]
	v_pk_mov_b32 v[48:49], v[110:111], v[46:47] op_sel:[1,0]
	v_mov_b32_e32 v36, v15
	v_mul_f32 v14, v26, v14
	v_mul_f32 v15, v26, v15
	v_and_b32_e32 v23, 0xffff0000, v23
	v_lshlrev_b32_e32 v37, 16, v11
	v_mul_f32 v40, v26, v40
	v_mul_f32 v41, v26, v41
	v_mul_f32 v48, v26, v48
	v_mul_f32 v49, v26, v49
	v_fma_f32 v14, v38, v46, v14
	v_fma_f32 v15, v38, v47, v15
	v_fma_f32 v40, v38, v102, v40
	v_fma_f32 v41, v38, v103, v41
	v_fma_f32 v48, v38, v110, v48
	v_fma_f32 v49, v38, v111, v49
	v_fma_f32 v14, v42, v36, v14
	v_fma_f32 v15, v42, v37, v15
	v_mov_b32_e32 v26, v39
	v_mov_b32_e32 v36, v27
	v_pk_mov_b32 v[38:39], v[0:1], v[22:23] op_sel:[1,0]
	v_and_b32_e32 v35, 0xffff0000, v35
	v_mul_f32 v38, v36, v38
	v_mul_f32 v39, v36, v39
	v_fma_f32 v0, v26, v0, v38
	v_fma_f32 v1, v26, v1, v39
	v_mov_b32_e32 v38, v43
	v_fma_f32 v4, v42, v102, v4
	v_fma_f32 v5, v42, v103, v5
	v_fma_f32 v40, v42, v110, v40
	v_fma_f32 v41, v42, v111, v41
	v_fma_f32 v48, v42, v46, v48
	v_fma_f32 v49, v42, v47, v49
	v_fma_f32 v42, v38, v22, v0
	v_fma_f32 v43, v38, v23, v1
	v_pk_mov_b32 v[0:1], v[22:23], v[34:35] op_sel:[1,0]
	v_mov_b32_e32 v124, v119
	v_mul_f32 v0, v36, v0
	v_mul_f32 v1, v36, v1
	v_fma_f32 v0, v26, v22, v0
	v_fma_f32 v1, v26, v23, v1
	v_fma_f32 v22, v38, v34, v0
	v_fma_f32 v23, v38, v35, v1
	v_pk_mov_b32 v[0:1], v[34:35], v[118:119] op_sel:[1,0]
	s_ashr_i32 s13, s12, 31
	v_mul_f32 v0, v36, v0
	v_mul_f32 v1, v36, v1
	v_fma_f32 v0, v26, v34, v0
	v_fma_f32 v1, v26, v35, v1
	v_fma_f32 v34, v38, v118, v0
	v_fma_f32 v35, v38, v119, v1
	v_mul_f32 v0, v36, v124
	v_mul_f32 v1, v36, v125
	v_and_b32_e32 v11, 0xffff0000, v11
	v_mov_b32_e32 v10, v125
	v_fma_f32 v0, v26, v118, v0
	v_fma_f32 v1, v26, v119, v1
	s_lshl_b64 s[6:7], s[12:13], 1
	v_fma_f32 v10, v38, v10, v0
	v_fma_f32 v11, v38, v11, v1
	v_lshl_add_u64 v[26:27], v[58:59], 0, s[6:7]
	v_cvt_pk_bf16_f32 v0, v86, v87
	v_cvt_pk_bf16_f32 v1, v2, v3
	v_cvt_pk_bf16_f32 v2, v18, v19
	v_cvt_pk_bf16_f32 v3, v30, v31
	flat_store_dwordx4 v[26:27], v[0:3]
	v_lshl_add_u64 v[18:19], v[60:61], 0, s[6:7]
	s_nop 0
	v_cvt_pk_bf16_f32 v0, v88, v89
	v_cvt_pk_bf16_f32 v1, v6, v7
	v_cvt_pk_bf16_f32 v2, v104, v105
	v_cvt_pk_bf16_f32 v3, v50, v51
	flat_store_dwordx4 v[18:19], v[0:3]
	v_lshl_add_u64 v[6:7], v[62:63], 0, s[6:7]
	s_nop 0
	v_cvt_pk_bf16_f32 v0, v78, v79
	v_cvt_pk_bf16_f32 v1, v82, v83
	v_cvt_pk_bf16_f32 v2, v90, v91
	v_cvt_pk_bf16_f32 v3, v12, v13
	flat_store_dwordx4 v[6:7], v[0:3]
	v_lshl_add_u64 v[6:7], v[64:65], 0, s[6:7]
	s_nop 0
	v_cvt_pk_bf16_f32 v0, v76, v77
	v_cvt_pk_bf16_f32 v1, v20, v21
	v_cvt_pk_bf16_f32 v2, v32, v33
	v_cvt_pk_bf16_f32 v3, v8, v9
	flat_store_dwordx4 v[6:7], v[0:3]
	v_lshl_add_u64 v[6:7], v[66:67], 0, s[6:7]
	s_nop 0
	v_cvt_pk_bf16_f32 v0, v80, v81
	v_cvt_pk_bf16_f32 v1, v16, v17
	v_cvt_pk_bf16_f32 v2, v28, v29
	v_cvt_pk_bf16_f32 v3, v44, v45
	flat_store_dwordx4 v[6:7], v[0:3]
	v_lshl_add_u64 v[6:7], v[68:69], 0, s[6:7]
	s_nop 0
	v_cvt_pk_bf16_f32 v0, v74, v75
	v_cvt_pk_bf16_f32 v1, v84, v85
	v_cvt_pk_bf16_f32 v2, v92, v93
	v_cvt_pk_bf16_f32 v3, v24, v25
	flat_store_dwordx4 v[6:7], v[0:3]
	v_lshl_add_u64 v[6:7], v[70:71], 0, s[6:7]
	s_nop 0
	v_cvt_pk_bf16_f32 v0, v4, v5
	v_cvt_pk_bf16_f32 v1, v40, v41
	v_cvt_pk_bf16_f32 v2, v48, v49
	v_cvt_pk_bf16_f32 v3, v14, v15
	flat_store_dwordx4 v[6:7], v[0:3]
	v_lshl_add_u64 v[4:5], v[72:73], 0, s[6:7]
	s_nop 0
	v_cvt_pk_bf16_f32 v0, v42, v43
	v_cvt_pk_bf16_f32 v1, v22, v23
	v_cvt_pk_bf16_f32 v2, v34, v35
	v_cvt_pk_bf16_f32 v3, v10, v11
	flat_store_dwordx4 v[4:5], v[0:3]

.LBB0_2824:
	s_or_b64 exec, exec, s[28:29]
	v_lshl_add_u32 v7, v162, 2, v151
	ds_read_b32 v6, v151 offset:17660
	ds_read_b128 v[8:11], v7 offset:17408
	ds_read_b128 v[12:15], v7 offset:17424
	s_waitcnt vmcnt(0)
	v_lshlrev_b32_e32 v17, 16, v175
	v_lshlrev_b32_e32 v16, 16, v173
	v_lshl_add_u64 v[4:5], s[18:19], 0, v[64:65]
	s_waitcnt lgkmcnt(0)
	v_sub_f32_e32 v8, v6, v8
	v_sub_f32_e32 v9, v6, v9
	v_mul_f32_e32 v8, 0x3fb8aa3b, v8
	v_mul_f32_e32 v9, 0x3fb8aa3b, v9
	v_exp_f32_e32 v8, v8
	v_exp_f32_e32 v9, v9
	v_sub_f32_e32 v10, v6, v10
	v_sub_f32_e32 v11, v6, v11
	v_mul_f32_e32 v10, 0x3fb8aa3b, v10
	v_mul_f32 v8, v8, v16
	v_mul_f32 v9, v9, v17
	v_mul_f32_e32 v11, 0x3fb8aa3b, v11
	v_cvt_pk_bf16_f32 v8, v8, v9
	v_sub_f32_e32 v9, v6, v12
	v_mul_f32_e32 v9, 0x3fb8aa3b, v9
	v_exp_f32_e32 v10, v10
	v_exp_f32_e32 v11, v11
	v_exp_f32_e32 v12, v9
	v_sub_f32_e32 v9, v6, v13
	v_mul_f32_e32 v9, 0x3fb8aa3b, v9
	v_exp_f32_e32 v13, v9
	v_lshlrev_b32_e32 v17, 16, v170
	v_lshlrev_b32_e32 v16, 16, v169
	v_mul_f32 v10, v10, v16
	v_mul_f32 v11, v11, v17
	v_lshlrev_b32_e32 v72, 7, v98
	v_cvt_pk_bf16_f32 v9, v10, v11
	v_lshlrev_b32_e32 v11, 16, v166
	v_lshlrev_b32_e32 v10, 16, v165
	v_mul_f32 v10, v12, v10
	v_mul_f32 v11, v13, v11
	v_sub_f32_e32 v12, v6, v14
	v_sub_f32_e32 v13, v6, v15
	v_mul_f32_e32 v12, 0x3fb8aa3b, v12
	v_mul_f32_e32 v13, 0x3fb8aa3b, v13
	v_exp_f32_e32 v12, v12
	v_exp_f32_e32 v13, v13
	v_lshl_add_u64 v[4:5], v[4:5], 0, v[72:73]
	v_lshlrev_b32_e32 v72, 1, v162
	v_lshlrev_b32_e32 v15, 16, v164
	v_lshlrev_b32_e32 v14, 16, v163
	v_lshl_add_u64 v[4:5], v[4:5], 0, v[72:73]
	v_mul_f32 v12, v12, v14
	v_mul_f32 v13, v13, v15
	v_cvt_pk_bf16_f32 v10, v10, v11
	v_cvt_pk_bf16_f32 v11, v12, v13
	flat_store_dwordx2 v[4:5], v[8:9]
	flat_store_dwordx2 v[4:5], v[10:11] offset:16
	ds_read_b128 v[8:11], v7 offset:17440
	ds_read_b128 v[12:15], v7 offset:17456
	v_lshlrev_b32_e32 v17, 16, v181
	v_lshlrev_b32_e32 v16, 16, v180
	s_waitcnt lgkmcnt(0)
	v_sub_f32_e32 v8, v6, v8
	v_sub_f32_e32 v9, v6, v9
	v_mul_f32_e32 v8, 0x3fb8aa3b, v8
	v_mul_f32_e32 v9, 0x3fb8aa3b, v9
	v_exp_f32_e32 v8, v8
	v_exp_f32_e32 v9, v9
	v_sub_f32_e32 v10, v6, v10
	v_sub_f32_e32 v11, v6, v11
	v_mul_f32_e32 v10, 0x3fb8aa3b, v10
	v_mul_f32 v8, v8, v16
	v_mul_f32 v9, v9, v17
	v_mul_f32_e32 v11, 0x3fb8aa3b, v11
	v_cvt_pk_bf16_f32 v8, v8, v9
	v_sub_f32_e32 v9, v6, v12
	v_mul_f32_e32 v9, 0x3fb8aa3b, v9
	v_exp_f32_e32 v10, v10
	v_exp_f32_e32 v11, v11
	v_exp_f32_e32 v12, v9
	v_sub_f32_e32 v9, v6, v13
	v_mul_f32_e32 v9, 0x3fb8aa3b, v9
	v_exp_f32_e32 v13, v9
	v_lshlrev_b32_e32 v17, 16, v177
	v_lshlrev_b32_e32 v16, 16, v176
	v_mul_f32 v10, v10, v16
	v_mul_f32 v11, v11, v17
	v_lshlrev_b32_e32 v17, 16, v190
	v_cvt_pk_bf16_f32 v9, v10, v11
	v_lshlrev_b32_e32 v11, 16, v172
	v_lshlrev_b32_e32 v10, 16, v171
	v_mul_f32 v10, v12, v10
	v_mul_f32 v11, v13, v11
	v_sub_f32_e32 v12, v6, v14
	v_sub_f32_e32 v13, v6, v15
	v_mul_f32_e32 v12, 0x3fb8aa3b, v12
	v_mul_f32_e32 v13, 0x3fb8aa3b, v13
	v_exp_f32_e32 v12, v12
	v_exp_f32_e32 v13, v13
	v_lshlrev_b32_e32 v15, 16, v168
	v_lshlrev_b32_e32 v14, 16, v167
	v_cvt_pk_bf16_f32 v10, v10, v11
	v_mul_f32 v12, v12, v14
	v_mul_f32 v13, v13, v15
	v_lshlrev_b32_e32 v16, 16, v188
	v_cvt_pk_bf16_f32 v11, v12, v13
	flat_store_dwordx2 v[4:5], v[8:9] offset:32
	flat_store_dwordx2 v[4:5], v[10:11] offset:48
	ds_read_b128 v[8:11], v7 offset:17472
	ds_read_b128 v[12:15], v7 offset:17488
	s_waitcnt lgkmcnt(0)
	v_sub_f32_e32 v8, v6, v8
	v_sub_f32_e32 v9, v6, v9
	v_mul_f32_e32 v8, 0x3fb8aa3b, v8
	v_mul_f32_e32 v9, 0x3fb8aa3b, v9
	v_exp_f32_e32 v8, v8
	v_exp_f32_e32 v9, v9
	v_sub_f32_e32 v10, v6, v10
	v_sub_f32_e32 v11, v6, v11
	v_mul_f32_e32 v10, 0x3fb8aa3b, v10
	v_mul_f32 v8, v8, v16
	v_mul_f32 v9, v9, v17
	v_mul_f32_e32 v11, 0x3fb8aa3b, v11
	v_cvt_pk_bf16_f32 v8, v8, v9
	v_sub_f32_e32 v9, v6, v12
	v_mul_f32_e32 v9, 0x3fb8aa3b, v9
	v_exp_f32_e32 v10, v10
	v_exp_f32_e32 v11, v11
	v_exp_f32_e32 v12, v9
	v_sub_f32_e32 v9, v6, v13
	v_mul_f32_e32 v9, 0x3fb8aa3b, v9
	v_exp_f32_e32 v13, v9
	v_lshlrev_b32_e32 v17, 16, v186
	v_lshlrev_b32_e32 v16, 16, v184
	v_mul_f32 v10, v10, v16
	v_mul_f32 v11, v11, v17
	v_lshlrev_b32_e32 v17, 16, v196
	v_cvt_pk_bf16_f32 v9, v10, v11
	v_lshlrev_b32_e32 v11, 16, v183
	v_lshlrev_b32_e32 v10, 16, v182
	v_mul_f32 v10, v12, v10
	v_mul_f32 v11, v13, v11
	v_sub_f32_e32 v12, v6, v14
	v_sub_f32_e32 v13, v6, v15
	v_mul_f32_e32 v12, 0x3fb8aa3b, v12
	v_mul_f32_e32 v13, 0x3fb8aa3b, v13
	v_exp_f32_e32 v12, v12
	v_exp_f32_e32 v13, v13
	v_lshlrev_b32_e32 v15, 16, v179
	v_lshlrev_b32_e32 v14, 16, v178
	v_cvt_pk_bf16_f32 v10, v10, v11
	v_mul_f32 v12, v12, v14
	v_mul_f32 v13, v13, v15
	v_lshlrev_b32_e32 v16, 16, v195
	v_cvt_pk_bf16_f32 v11, v12, v13
	flat_store_dwordx2 v[4:5], v[8:9] offset:8
	flat_store_dwordx2 v[4:5], v[10:11] offset:24
	ds_read_b128 v[8:11], v7 offset:17504
	ds_read_b128 v[12:15], v7 offset:17520
	s_waitcnt lgkmcnt(0)
	v_sub_f32_e32 v7, v6, v8
	v_mul_f32_e32 v7, 0x3fb8aa3b, v7
	v_exp_f32_e32 v8, v7
	v_sub_f32_e32 v7, v6, v9
	v_mul_f32_e32 v7, 0x3fb8aa3b, v7
	v_exp_f32_e32 v9, v7
	v_sub_f32_e32 v10, v6, v10
	v_sub_f32_e32 v11, v6, v11
	v_mul_f32_e32 v10, 0x3fb8aa3b, v10
	v_mul_f32 v8, v8, v16
	v_mul_f32 v9, v9, v17
	v_mul_f32_e32 v11, 0x3fb8aa3b, v11
	v_cvt_pk_bf16_f32 v8, v8, v9
	v_sub_f32_e32 v9, v6, v12
	v_mul_f32_e32 v9, 0x3fb8aa3b, v9
	v_exp_f32_e32 v10, v10
	v_exp_f32_e32 v11, v11
	v_exp_f32_e32 v12, v9
	v_sub_f32_e32 v9, v6, v13
	v_mul_f32_e32 v9, 0x3fb8aa3b, v9
	v_exp_f32_e32 v13, v9
	v_lshlrev_b32_e32 v17, 16, v194
	v_lshlrev_b32_e32 v16, 16, v193
	v_mul_f32 v10, v10, v16
	v_mul_f32 v11, v11, v17
	v_and_b32_e32 v7, 0x7f, v99
	v_cvt_pk_bf16_f32 v9, v10, v11
	v_lshlrev_b32_e32 v11, 16, v191
	v_lshlrev_b32_e32 v10, 16, v189
	v_mul_f32 v10, v12, v10
	v_mul_f32 v11, v13, v11
	v_sub_f32_e32 v12, v6, v14
	v_sub_f32_e32 v13, v6, v15
	v_mul_f32_e32 v12, 0x3fb8aa3b, v12
	v_mul_f32_e32 v13, 0x3fb8aa3b, v13
	v_exp_f32_e32 v12, v12
	v_exp_f32_e32 v13, v13
	v_lshlrev_b32_e32 v15, 16, v187
	v_lshlrev_b32_e32 v14, 16, v185
	v_cmp_gt_u32_e32 vcc, 64, v7
	v_mul_f32 v12, v12, v14
	v_mul_f32 v13, v13, v15
	v_cvt_pk_bf16_f32 v10, v10, v11
	v_cvt_pk_bf16_f32 v11, v12, v13
	flat_store_dwordx2 v[4:5], v[8:9] offset:40
	flat_store_dwordx2 v[4:5], v[10:11] offset:56
	s_and_saveexec_b64 s[28:29], vcc
	s_cbranch_execz .LBB0_2826
	v_lshlrev_b32_e32 v72, 2, v7
	v_add_u32_e32 v4, v151, v72
	ds_read_b32 v4, v4 offset:17408
	s_waitcnt lgkmcnt(0)
	v_mul_f32_e32 v4, 0x3fb8aa3b, v4
	v_exp_f32_e32 v8, v4
	v_lshlrev_b64 v[4:5], 8, v[68:69]
	v_lshl_add_u64 v[4:5], s[20:21], 0, v[4:5]
	v_lshl_add_u64 v[4:5], v[4:5], 0, v[72:73]
	flat_store_dword v[4:5], v8

.LBB0_2967:
	v_add_f32 v142, v142, 0
	v_add_f32 v143, v143, 0
	v_mov_b32_e32 v85, v110
	v_add_f32 v140, v140, v142
	v_add_f32 v141, v141, v143
	v_mov_b32_e32 v173, v80
	v_add_f32 v138, v138, v140
	v_add_f32 v139, v139, v141
	s_addk_i32 s20, 0x80
	v_add_f32 v136, v136, v138
	v_add_f32 v137, v137, v139
	s_cmp_lg_u32 s19, s22
	v_add_f32 v134, v134, v136
	v_add_f32 v135, v135, v137
	s_mov_b32 s10, s22
	v_add_f32 v132, v132, v134
	v_add_f32 v133, v133, v135
	s_waitcnt lgkmcnt(0)
	v_add_f32 v130, v130, v132
	v_add_f32 v131, v131, v133
	s_barrier
	v_add_f32 v128, v128, v130
	v_add_f32 v129, v129, v131
	v_add_f32 v130, v170, 0
	v_add_f32 v131, v171, 0
	v_add_f32 v126, v126, v128
	v_add_f32 v127, v127, v129
	v_add_f32 v130, v168, v130
	v_add_f32 v131, v169, v131
	v_add_f32 v124, v124, v126
	v_add_f32 v125, v125, v127
	v_add_f32 v130, v166, v130
	v_add_f32 v131, v167, v131
	v_add_f32 v122, v122, v124
	v_add_f32 v123, v123, v125
	v_add_f32 v130, v164, v130
	v_add_f32 v131, v165, v131
	v_add_f32 v118, v118, v122
	v_add_f32 v119, v119, v123
	v_add_f32 v130, v162, v130
	v_add_f32 v131, v163, v131
	v_add_f32 v114, v114, v118
	v_add_f32 v115, v115, v119
	v_add_f32 v130, v160, v130
	v_add_f32 v131, v161, v131
	v_add_f32 v112, v112, v114
	v_add_f32 v113, v113, v115
	s_nop 0
	v_add_f32 v112, v120, v112
	v_add_f32 v113, v121, v113
	s_nop 0
	v_add_f32 v112, v116, v112
	v_add_f32 v113, v117, v113
	s_nop 0
	v_fma_f32 v84, v100, v84, v112
	v_fma_f32 v85, v101, v85, v113
	v_add_f32 v100, v158, v130
	v_add_f32 v101, v159, v131
	s_nop 0
	v_add_f32 v100, v156, v100
	v_add_f32 v101, v157, v101
	s_nop 0
	v_add_f32 v100, v154, v100
	v_add_f32 v101, v155, v101
	s_nop 0
	v_add_f32 v100, v152, v100
	v_add_f32 v101, v153, v101
	s_nop 0
	v_add_f32 v100, v150, v100
	v_add_f32 v101, v151, v101
	s_nop 0
	v_add_f32 v100, v146, v100
	v_add_f32 v101, v147, v101
	s_nop 0
	v_add_f32 v86, v86, v100
	v_add_f32 v87, v87, v101
	s_nop 0
	v_add_f32 v82, v82, v86
	v_add_f32 v83, v83, v87
	s_nop 0
	v_add_f32 v82, v148, v82
	v_add_f32 v83, v149, v83
	s_nop 0
	v_add_f32 v82, v144, v82
	v_add_f32 v83, v145, v83
	s_nop 0
	v_fma_f32 v100, v84, v172, v82
	v_fma_f32 v101, v85, v173, v83
	s_cbranch_scc0 .LBB0_2973
.LBB0_2968:
	s_bitcmp1_b32 s10, 0
	s_cselect_b32 s11, 0xb800, 0
	s_setprio 1
	v_or_b32_e32 v80, s11, v94
	v_add_u32_e32 v109, v80, v186
	ds_read_b128 v[220:223], v109
	ds_read_b128 v[224:227], v109 offset:64
	ds_read_b128 v[228:231], v109 offset:3328
	ds_read_b128 v[232:235], v109 offset:6656
	ds_read_b128 v[236:239], v109 offset:9984
	ds_read_b128 v[240:243], v109 offset:3392
	ds_read_b128 v[244:247], v109 offset:6720
	ds_read_b128 v[248:251], v109 offset:10048
	s_waitcnt lgkmcnt(7)
	v_mfma_f32_16x16x32_bf16 v[112:115], v[220:223], v[4:7], v[0:3]
	v_mfma_f32_16x16x32_bf16 v[82:85], v[220:223], v[16:19], v[0:3]
	ds_read_b128 v[220:223], v109 offset:128
	s_waitcnt lgkmcnt(7)
	v_mfma_f32_16x16x32_bf16 v[112:115], v[224:227], v[8:11], v[112:115]
	v_mfma_f32_16x16x32_bf16 v[82:85], v[224:227], v[20:23], v[82:85]
	ds_read_b128 v[224:227], v109 offset:3456
	s_waitcnt lgkmcnt(7)
	v_mfma_f32_16x16x32_bf16 v[120:123], v[228:231], v[4:7], v[0:3]
	v_mfma_f32_16x16x32_bf16 v[116:119], v[228:231], v[16:19], v[0:3]
	ds_read_b128 v[228:231], v109 offset:6784
	s_waitcnt lgkmcnt(5)
	v_mfma_f32_16x16x32_bf16 v[120:123], v[240:243], v[8:11], v[120:123]
	v_mfma_f32_16x16x32_bf16 v[116:119], v[240:243], v[20:23], v[116:119]
	ds_read_b128 v[240:243], v109 offset:10112
	v_mfma_f32_16x16x32_bf16 v[128:131], v[232:235], v[4:7], v[0:3]
	v_mfma_f32_16x16x32_bf16 v[124:127], v[232:235], v[16:19], v[0:3]
	s_waitcnt lgkmcnt(5)
	v_mfma_f32_16x16x32_bf16 v[128:131], v[244:247], v[8:11], v[128:131]
	v_mfma_f32_16x16x32_bf16 v[124:127], v[244:247], v[20:23], v[124:127]
	v_mfma_f32_16x16x32_bf16 v[136:139], v[236:239], v[4:7], v[0:3]
	v_mfma_f32_16x16x32_bf16 v[132:135], v[236:239], v[16:19], v[0:3]
	s_waitcnt lgkmcnt(4)
	v_mfma_f32_16x16x32_bf16 v[136:139], v[248:251], v[8:11], v[136:139]
	v_mfma_f32_16x16x32_bf16 v[132:135], v[248:251], v[20:23], v[132:135]
	s_waitcnt lgkmcnt(3)
	v_mfma_f32_16x16x32_bf16 v[148:151], v[220:223], v[24:27], v[82:85]
	s_waitcnt lgkmcnt(2)
	v_mfma_f32_16x16x32_bf16 v[120:123], v[224:227], v[12:15], v[120:123]
	v_mfma_f32_16x16x32_bf16 v[84:87], v[224:227], v[24:27], v[116:119]
	s_waitcnt lgkmcnt(1)
	v_mfma_f32_16x16x32_bf16 v[152:155], v[228:231], v[12:15], v[128:131]
	v_mfma_f32_16x16x32_bf16 v[156:159], v[228:231], v[24:27], v[124:127]
	v_mfma_f32_16x16x32_bf16 v[112:115], v[220:223], v[12:15], v[112:115]
	s_waitcnt lgkmcnt(0)
	v_mfma_f32_16x16x32_bf16 v[160:163], v[240:243], v[12:15], v[136:139]
	v_mfma_f32_16x16x32_bf16 v[164:167], v[240:243], v[24:27], v[132:135]
	s_nop 2
	s_setprio 0
	s_nop 3
	v_max3_f32 v80, v112, v113, v114
	v_max3_f32 v80, v80, v115, v120
	v_max3_f32 v80, v80, v121, v122
	v_max3_f32 v80, v80, v123, v152
	v_max3_f32 v80, v80, v153, v154
	v_max3_f32 v80, v80, v155, v160
	v_max3_f32 v80, v80, v161, v162
	v_max_f32_e32 v80, v80, v163
	v_mul_f32_e32 v80, 0x3e16c740, v80
	v_max_f32_e32 v80, s68, v80
	v_mov_b32_e32 v82, v80
	s_nop 1
	v_permlane16_swap_b32_e32 v80, v82
	v_max_f32_e32 v80, v80, v82
	v_mov_b32_e32 v82, v80
	s_nop 1
	v_permlane32_swap_b32_e32 v80, v82
	v_max3_f32 v144, v81, v80, v82
	v_sub_f32_e32 v80, v81, v144
	v_fma_f32 v81, v112, s38, -v144
	v_exp_f32_e32 v143, v81
	v_fma_f32 v81, v113, s38, -v144
	v_exp_f32_e32 v141, v81
	v_fma_f32 v81, v114, s38, -v144
	v_max3_f32 v112, v148, v149, v150
	v_max3_f32 v112, v112, v151, v84
	v_max3_f32 v112, v112, v85, v86
	v_max3_f32 v112, v112, v87, v156
	v_max3_f32 v112, v112, v157, v158
	v_max3_f32 v112, v112, v159, v164
	v_max3_f32 v112, v112, v165, v166
	v_max_f32_e32 v112, v112, v167
	v_mul_f32_e32 v112, 0x3e16c740, v112
	v_max_f32_e32 v112, s68, v112
	v_mov_b32_e32 v114, v112
	s_nop 1
	v_permlane16_swap_b32_e32 v112, v114
	v_max_f32_e32 v112, v112, v114
	v_mov_b32_e32 v114, v112
	v_exp_f32_e32 v139, v81
	v_fma_f32 v81, v115, s38, -v144
	v_permlane32_swap_b32_e32 v112, v114
	v_exp_f32_e32 v137, v81
	v_fma_f32 v81, v120, s38, -v144
	v_max3_f32 v146, v189, v112, v114
	v_exp_f32_e32 v135, v81
	v_fma_f32 v81, v121, s38, -v144
	v_fma_f32 v84, v84, s38, -v146
	v_exp_f32_e32 v133, v81
	v_fma_f32 v81, v122, s38, -v144
	v_exp_f32_e32 v134, v84
	v_fma_f32 v84, v85, s38, -v146
	v_exp_f32_e32 v131, v81
	v_fma_f32 v81, v123, s38, -v144
	v_exp_f32_e32 v132, v84
	v_fma_f32 v84, v86, s38, -v146
	v_exp_f32_e32 v129, v81
	v_fma_f32 v81, v152, s38, -v144
	v_exp_f32_e32 v130, v84
	v_fma_f32 v84, v87, s38, -v146
	v_exp_f32_e32 v127, v81
	v_fma_f32 v81, v153, s38, -v144
	v_exp_f32_e32 v128, v84
	v_fma_f32 v84, v156, s38, -v146
	v_exp_f32_e32 v125, v81
	v_fma_f32 v81, v154, s38, -v144
	v_exp_f32_e32 v126, v84
	v_fma_f32 v84, v157, s38, -v146
	v_exp_f32_e32 v123, v81
	v_fma_f32 v81, v155, s38, -v144
	v_fma_f32 v112, v148, s38, -v146
	v_exp_f32_e32 v124, v84
	v_fma_f32 v84, v158, s38, -v146
	v_exp_f32_e32 v119, v81
	v_fma_f32 v81, v160, s38, -v144
	v_exp_f32_e32 v142, v112
	v_fma_f32 v112, v149, s38, -v146
	v_exp_f32_e32 v122, v84
	v_fma_f32 v84, v159, s38, -v146
	v_exp_f32_e32 v115, v81
	v_fma_f32 v81, v161, s38, -v144
	v_exp_f32_e32 v140, v112
	v_fma_f32 v112, v150, s38, -v146
	v_exp_f32_e32 v118, v84
	v_fma_f32 v84, v164, s38, -v146
	v_fma_f32 v85, v166, s38, -v146
	v_exp_f32_e32 v113, v81
	v_fma_f32 v81, v162, s38, -v144
	v_exp_f32_e32 v110, v80
	v_fma_f32 v80, v163, s38, -v144
	v_sub_f32_e32 v116, v189, v146
	v_exp_f32_e32 v138, v112
	v_fma_f32 v112, v151, s38, -v146
	v_exp_f32_e32 v114, v84
	v_fma_f32 v84, v165, s38, -v146
	v_exp_f32_e32 v120, v85
	v_fma_f32 v85, v167, s38, -v146
	v_exp_f32_e32 v121, v81
	v_exp_f32_e32 v117, v80
	v_exp_f32_e32 v136, v112
	v_exp_f32_e32 v112, v84
	v_exp_f32_e32 v84, v116
	v_exp_f32_e32 v116, v85
	v_mul_f32 v70, v70, v110
	v_mul_f32 v71, v71, v110
	v_mul_f32 v68, v68, v110
	v_mul_f32 v69, v69, v110
	v_mul_f32 v66, v66, v110
	v_mul_f32 v67, v67, v110
	v_mul_f32 v64, v64, v110
	v_mul_f32 v65, v65, v110
	v_mul_f32 v74, v74, v110
	v_mul_f32 v75, v75, v110
	v_mul_f32 v72, v72, v110
	v_mul_f32 v73, v73, v110
	v_mul_f32 v82, v78, v110
	v_mul_f32 v83, v79, v110
	v_mul_f32 v80, v76, v110
	v_mul_f32 v81, v77, v110
	v_cvt_pk_bf16_f32 v152, v143, v141
	v_cvt_pk_bf16_f32 v153, v139, v137
	v_cvt_pk_bf16_f32 v154, v135, v133
	v_cvt_pk_bf16_f32 v155, v131, v129
	v_cvt_pk_bf16_f32 v76, v127, v125
	v_cvt_pk_bf16_f32 v77, v123, v119
	v_cvt_pk_bf16_f32 v78, v115, v113
	v_cvt_pk_bf16_f32 v79, v121, v117
	v_mul_f32 v54, v54, v84
	v_mul_f32 v55, v55, v84
	v_mul_f32 v52, v52, v84
	v_mul_f32 v53, v53, v84
	v_mul_f32 v50, v50, v84
	v_mul_f32 v51, v51, v84
	v_mul_f32 v48, v48, v84
	v_mul_f32 v49, v49, v84
	v_mul_f32 v58, v58, v84
	v_mul_f32 v59, v59, v84
	v_mul_f32 v56, v56, v84
	v_mul_f32 v57, v57, v84
	v_mul_f32 v62, v62, v84
	v_mul_f32 v63, v63, v84
	v_mul_f32 v60, v60, v84
	v_mul_f32 v61, v61, v84
	v_cvt_pk_bf16_f32 v148, v142, v140
	v_cvt_pk_bf16_f32 v149, v138, v136
	v_cvt_pk_bf16_f32 v150, v134, v132
	v_cvt_pk_bf16_f32 v151, v130, v128
	v_cvt_pk_bf16_f32 v156, v126, v124
	v_cvt_pk_bf16_f32 v157, v122, v118
	v_cvt_pk_bf16_f32 v158, v114, v112
	v_cvt_pk_bf16_f32 v159, v120, v116
	s_setprio 1
	v_add3_u32 v85, s11, v187, v188
	ds_read_b64_tr_b16 v[222:223], v85 offset:29184
	ds_read_b64_tr_b16 v[220:221], v85 offset:26624
	ds_read_b64_tr_b16 v[224:225], v85 offset:26656
	ds_read_b64_tr_b16 v[226:227], v85 offset:29216
	ds_read_b64_tr_b16 v[228:229], v85 offset:31744
	ds_read_b64_tr_b16 v[230:231], v85 offset:34304
	ds_read_b64_tr_b16 v[232:233], v85 offset:31776
	ds_read_b64_tr_b16 v[234:235], v85 offset:34336
	ds_read_b64_tr_b16 v[236:237], v85 offset:26688
	ds_read_b64_tr_b16 v[238:239], v85 offset:29248
	ds_read_b64_tr_b16 v[240:241], v85 offset:31808
	ds_read_b64_tr_b16 v[242:243], v85 offset:34368
	ds_read_b64_tr_b16 v[244:245], v85 offset:26720
	ds_read_b64_tr_b16 v[246:247], v85 offset:29280
	ds_read_b64_tr_b16 v[248:249], v85 offset:31840
	ds_read_b64_tr_b16 v[250:251], v85 offset:34400
	s_waitcnt lgkmcnt(14)
	v_mfma_f32_16x16x32_bf16 v[68:71], v[220:223], v[152:155], v[68:71]
	v_mfma_f32_16x16x32_bf16 v[52:55], v[220:223], v[148:151], v[52:55]
	s_waitcnt lgkmcnt(10)
	v_mfma_f32_16x16x32_bf16 v[68:71], v[228:231], v[76:79], v[68:71]
	v_mfma_f32_16x16x32_bf16 v[52:55], v[228:231], v[156:159], v[52:55]
	v_mfma_f32_16x16x32_bf16 v[64:67], v[224:227], v[152:155], v[64:67]
	v_mfma_f32_16x16x32_bf16 v[48:51], v[224:227], v[148:151], v[48:51]
	s_waitcnt lgkmcnt(8)
	v_mfma_f32_16x16x32_bf16 v[64:67], v[232:235], v[76:79], v[64:67]
	v_mfma_f32_16x16x32_bf16 v[48:51], v[232:235], v[156:159], v[48:51]
	s_waitcnt lgkmcnt(6)
	v_mfma_f32_16x16x32_bf16 v[72:75], v[236:239], v[152:155], v[72:75]
	v_mfma_f32_16x16x32_bf16 v[56:59], v[236:239], v[148:151], v[56:59]
	s_waitcnt lgkmcnt(4)
	v_mfma_f32_16x16x32_bf16 v[72:75], v[240:243], v[76:79], v[72:75]
	v_mfma_f32_16x16x32_bf16 v[56:59], v[240:243], v[156:159], v[56:59]
	s_waitcnt lgkmcnt(2)
	v_mfma_f32_16x16x32_bf16 v[60:63], v[244:247], v[148:151], v[60:63]
	v_mfma_f32_16x16x32_bf16 v[80:83], v[244:247], v[152:155], v[80:83]
	s_waitcnt lgkmcnt(0)
	v_mfma_f32_16x16x32_bf16 v[76:79], v[248:251], v[76:79], v[80:83]
	v_mfma_f32_16x16x32_bf16 v[60:63], v[248:251], v[156:159], v[60:63]
	s_nop 3
	s_setprio 0
	s_setprio 1
	ds_read_b128 v[220:223], v109 offset:13312
	ds_read_b128 v[224:227], v109 offset:13376
	ds_read_b128 v[228:231], v109 offset:16640
	ds_read_b128 v[232:235], v109 offset:19968
	ds_read_b128 v[236:239], v109 offset:23296
	ds_read_b128 v[240:243], v109 offset:16704
	ds_read_b128 v[244:247], v109 offset:20032
	ds_read_b128 v[248:251], v109 offset:23360
	s_waitcnt lgkmcnt(7)
	v_mfma_f32_16x16x32_bf16 v[148:151], v[220:223], v[4:7], v[0:3]
	v_mfma_f32_16x16x32_bf16 v[80:83], v[220:223], v[16:19], v[0:3]
	ds_read_b128 v[220:223], v109 offset:13440
	s_waitcnt lgkmcnt(7)
	v_mfma_f32_16x16x32_bf16 v[148:151], v[224:227], v[8:11], v[148:151]
	v_mfma_f32_16x16x32_bf16 v[80:83], v[224:227], v[20:23], v[80:83]
	ds_read_b128 v[224:227], v109 offset:16768
	s_waitcnt lgkmcnt(7)
	v_mfma_f32_16x16x32_bf16 v[156:159], v[228:231], v[4:7], v[0:3]
	v_mfma_f32_16x16x32_bf16 v[152:155], v[228:231], v[16:19], v[0:3]
	ds_read_b128 v[228:231], v109 offset:20096
	s_waitcnt lgkmcnt(5)
	v_mfma_f32_16x16x32_bf16 v[156:159], v[240:243], v[8:11], v[156:159]
	v_mfma_f32_16x16x32_bf16 v[152:155], v[240:243], v[20:23], v[152:155]
	ds_read_b128 v[240:243], v109 offset:23424
	v_mfma_f32_16x16x32_bf16 v[164:167], v[232:235], v[4:7], v[0:3]
	v_mfma_f32_16x16x32_bf16 v[160:163], v[232:235], v[16:19], v[0:3]
	s_waitcnt lgkmcnt(5)
	v_mfma_f32_16x16x32_bf16 v[164:167], v[244:247], v[8:11], v[164:167]
	v_mfma_f32_16x16x32_bf16 v[160:163], v[244:247], v[20:23], v[160:163]
	v_mfma_f32_16x16x32_bf16 v[190:193], v[236:239], v[4:7], v[0:3]
	v_mfma_f32_16x16x32_bf16 v[168:171], v[236:239], v[16:19], v[0:3]
	s_waitcnt lgkmcnt(4)
	v_mfma_f32_16x16x32_bf16 v[190:193], v[248:251], v[8:11], v[190:193]
	v_mfma_f32_16x16x32_bf16 v[168:171], v[248:251], v[20:23], v[168:171]
	s_waitcnt lgkmcnt(3)
	v_mfma_f32_16x16x32_bf16 v[148:151], v[220:223], v[12:15], v[148:151]
	v_mfma_f32_16x16x32_bf16 v[194:197], v[220:223], v[24:27], v[80:83]
	s_waitcnt lgkmcnt(2)
	v_mfma_f32_16x16x32_bf16 v[198:201], v[224:227], v[12:15], v[156:159]
	v_mfma_f32_16x16x32_bf16 v[202:205], v[224:227], v[24:27], v[152:155]
	s_waitcnt lgkmcnt(1)
	v_mfma_f32_16x16x32_bf16 v[206:209], v[228:231], v[12:15], v[164:167]
	v_mfma_f32_16x16x32_bf16 v[210:213], v[228:231], v[24:27], v[160:163]
	s_waitcnt lgkmcnt(0)
	v_mfma_f32_16x16x32_bf16 v[190:193], v[240:243], v[12:15], v[190:193]
	v_mfma_f32_16x16x32_bf16 v[214:217], v[240:243], v[24:27], v[168:171]
	s_nop 1
	s_setprio 0
	v_max3_f32 v80, v148, v149, v150
	v_max3_f32 v80, v80, v151, v198
	v_max3_f32 v80, v80, v199, v200
	v_max3_f32 v80, v80, v201, v206
	v_max3_f32 v80, v80, v207, v208
	v_max3_f32 v80, v80, v209, v190
	v_max3_f32 v80, v80, v191, v192
	v_max_f32_e32 v80, v80, v193
	v_mul_f32_e32 v80, 0x3e16c740, v80
	v_max_f32_e32 v80, s68, v80
	v_mov_b32_e32 v81, v80
	s_nop 1
	v_permlane16_swap_b32_e32 v80, v81
	v_max_f32_e32 v80, v80, v81
	v_mov_b32_e32 v81, v80
	s_nop 1
	v_permlane32_swap_b32_e32 v80, v81
	v_max3_f32 v81, v144, v80, v81
	v_fma_f32 v82, v148, s38, -v81
	v_exp_f32_e32 v171, v82
	v_fma_f32 v82, v149, s38, -v81
	v_exp_f32_e32 v169, v82
	v_fma_f32 v82, v150, s38, -v81
	v_exp_f32_e32 v167, v82
	v_fma_f32 v82, v151, s38, -v81
	v_exp_f32_e32 v165, v82
	v_fma_f32 v82, v198, s38, -v81
	v_exp_f32_e32 v163, v82
	v_fma_f32 v82, v199, s38, -v81
	v_exp_f32_e32 v161, v82
	v_fma_f32 v82, v200, s38, -v81
	v_exp_f32_e32 v159, v82
	v_fma_f32 v82, v201, s38, -v81
	v_exp_f32_e32 v157, v82
	v_fma_f32 v82, v206, s38, -v81
	v_exp_f32_e32 v155, v82
	v_fma_f32 v82, v207, s38, -v81
	v_exp_f32_e32 v153, v82
	v_fma_f32 v82, v208, s38, -v81
	v_exp_f32_e32 v151, v82
	v_fma_f32 v82, v209, s38, -v81
	v_exp_f32_e32 v147, v82
	v_fma_f32 v82, v190, s38, -v81
	v_exp_f32_e32 v87, v82
	v_fma_f32 v82, v191, s38, -v81
	v_exp_f32_e32 v83, v82
	v_fma_f32 v82, v192, s38, -v81
	v_exp_f32_e32 v149, v82
	v_fma_f32 v82, v193, s38, -v81
	v_exp_f32_e32 v145, v82
	v_max3_f32 v82, v194, v195, v196
	v_max3_f32 v82, v82, v197, v202
	v_max3_f32 v82, v82, v203, v204
	v_max3_f32 v82, v82, v205, v210
	v_max3_f32 v82, v82, v211, v212
	v_max3_f32 v82, v82, v213, v214
	v_max3_f32 v82, v82, v215, v216
	v_max_f32_e32 v82, v82, v217
	v_mul_f32_e32 v82, 0x3e16c740, v82
	v_max_f32_e32 v82, s68, v82
	v_mov_b32_e32 v86, v82
	s_nop 1
	v_permlane16_swap_b32_e32 v82, v86
	v_max_f32_e32 v82, v82, v86
	v_mov_b32_e32 v86, v82
	s_nop 1
	v_permlane32_swap_b32_e32 v82, v86
	v_max3_f32 v189, v146, v82, v86
	v_fma_f32 v82, v194, s38, -v189
	v_exp_f32_e32 v170, v82
	v_fma_f32 v82, v195, s38, -v189
	v_exp_f32_e32 v168, v82
	v_fma_f32 v82, v196, s38, -v189
	v_exp_f32_e32 v166, v82
	v_fma_f32 v82, v197, s38, -v189
	v_exp_f32_e32 v164, v82
	v_fma_f32 v82, v202, s38, -v189
	v_exp_f32_e32 v162, v82
	v_fma_f32 v82, v203, s38, -v189
	v_exp_f32_e32 v160, v82
	v_fma_f32 v82, v204, s38, -v189
	v_exp_f32_e32 v158, v82
	v_fma_f32 v82, v205, s38, -v189
	v_exp_f32_e32 v156, v82
	v_fma_f32 v82, v210, s38, -v189
	v_exp_f32_e32 v154, v82
	v_fma_f32 v82, v211, s38, -v189
	v_exp_f32_e32 v152, v82
	v_fma_f32 v82, v212, s38, -v189
	v_exp_f32_e32 v150, v82
	v_fma_f32 v82, v213, s38, -v189
	v_sub_f32_e32 v80, v144, v81
	v_sub_f32_e32 v109, v146, v189
	v_exp_f32_e32 v146, v82
	v_fma_f32 v82, v214, s38, -v189
	v_exp_f32_e32 v80, v80
	v_exp_f32_e32 v86, v82
	v_fma_f32 v82, v215, s38, -v189
	v_fma_f32 v144, v216, s38, -v189
	v_exp_f32_e32 v172, v109
	v_fma_f32 v109, v217, s38, -v189
	v_exp_f32_e32 v82, v82
	v_exp_f32_e32 v148, v144
	v_exp_f32_e32 v144, v109
	v_mul_f32 v70, v70, v80
	v_mul_f32 v71, v71, v80
	v_mul_f32 v68, v68, v80
	v_mul_f32 v69, v69, v80
	v_mul_f32 v66, v66, v80
	v_mul_f32 v67, v67, v80
	v_mul_f32 v64, v64, v80
	v_mul_f32 v65, v65, v80
	v_mul_f32 v74, v74, v80
	v_mul_f32 v75, v75, v80
	v_mul_f32 v72, v72, v80
	v_mul_f32 v73, v73, v80
	v_mul_f32 v192, v78, v80
	v_mul_f32 v193, v79, v80
	v_mul_f32 v190, v76, v80
	v_mul_f32 v191, v77, v80
	v_cvt_pk_bf16_f32 v76, v155, v153
	v_cvt_pk_bf16_f32 v77, v151, v147
	v_cvt_pk_bf16_f32 v78, v87, v83
	v_cvt_pk_bf16_f32 v79, v149, v145
	v_mul_f32 v54, v54, v172
	v_mul_f32 v55, v55, v172
	v_mul_f32 v52, v52, v172
	v_mul_f32 v53, v53, v172
	v_mul_f32 v50, v50, v172
	v_mul_f32 v51, v51, v172
	v_mul_f32 v48, v48, v172
	v_mul_f32 v49, v49, v172
	v_mul_f32 v58, v58, v172
	v_mul_f32 v59, v59, v172
	v_mul_f32 v56, v56, v172
	v_mul_f32 v57, v57, v172
	v_mul_f32 v62, v62, v172
	v_mul_f32 v63, v63, v172
	v_mul_f32 v60, v60, v172
	v_mul_f32 v61, v61, v172
	v_cvt_pk_bf16_f32 v198, v171, v169
	v_cvt_pk_bf16_f32 v199, v167, v165
	v_cvt_pk_bf16_f32 v200, v163, v161
	v_cvt_pk_bf16_f32 v201, v159, v157
	v_cvt_pk_bf16_f32 v194, v170, v168
	v_cvt_pk_bf16_f32 v195, v166, v164
	v_cvt_pk_bf16_f32 v196, v162, v160
	v_cvt_pk_bf16_f32 v197, v158, v156
	v_cvt_pk_bf16_f32 v202, v154, v152
	v_cvt_pk_bf16_f32 v203, v150, v146
	v_cvt_pk_bf16_f32 v204, v86, v82
	v_cvt_pk_bf16_f32 v205, v148, v144
	s_setprio 1
	ds_read_b64_tr_b16 v[222:223], v85 offset:39424
	ds_read_b64_tr_b16 v[220:221], v85 offset:36864
	ds_read_b64_tr_b16 v[224:225], v85 offset:36896
	ds_read_b64_tr_b16 v[226:227], v85 offset:39456
	ds_read_b64_tr_b16 v[228:229], v85 offset:41984
	ds_read_b64_tr_b16 v[230:231], v85 offset:44544
	ds_read_b64_tr_b16 v[232:233], v85 offset:42016
	ds_read_b64_tr_b16 v[234:235], v85 offset:44576
	ds_read_b64_tr_b16 v[236:237], v85 offset:36928
	ds_read_b64_tr_b16 v[238:239], v85 offset:39488
	ds_read_b64_tr_b16 v[240:241], v85 offset:42048
	ds_read_b64_tr_b16 v[242:243], v85 offset:44608
	ds_read_b64_tr_b16 v[244:245], v85 offset:36960
	ds_read_b64_tr_b16 v[246:247], v85 offset:39520
	ds_read_b64_tr_b16 v[248:249], v85 offset:42080
	ds_read_b64_tr_b16 v[250:251], v85 offset:44640
	s_waitcnt lgkmcnt(14)
	v_mfma_f32_16x16x32_bf16 v[68:71], v[220:223], v[198:201], v[68:71]
	v_mfma_f32_16x16x32_bf16 v[52:55], v[220:223], v[194:197], v[52:55]
	s_waitcnt lgkmcnt(10)
	v_mfma_f32_16x16x32_bf16 v[68:71], v[228:231], v[76:79], v[68:71]
	v_mfma_f32_16x16x32_bf16 v[52:55], v[228:231], v[202:205], v[52:55]
	v_mfma_f32_16x16x32_bf16 v[64:67], v[224:227], v[198:201], v[64:67]
	v_mfma_f32_16x16x32_bf16 v[48:51], v[224:227], v[194:197], v[48:51]
	s_waitcnt lgkmcnt(8)
	v_mfma_f32_16x16x32_bf16 v[64:67], v[232:235], v[76:79], v[64:67]
	v_mfma_f32_16x16x32_bf16 v[48:51], v[232:235], v[202:205], v[48:51]
	s_waitcnt lgkmcnt(6)
	v_mfma_f32_16x16x32_bf16 v[72:75], v[236:239], v[198:201], v[72:75]
	v_mfma_f32_16x16x32_bf16 v[56:59], v[236:239], v[194:197], v[56:59]
	s_waitcnt lgkmcnt(4)
	v_mfma_f32_16x16x32_bf16 v[72:75], v[240:243], v[76:79], v[72:75]
	v_mfma_f32_16x16x32_bf16 v[56:59], v[240:243], v[202:205], v[56:59]
	s_waitcnt lgkmcnt(2)
	v_mfma_f32_16x16x32_bf16 v[60:63], v[244:247], v[194:197], v[60:63]
	v_mfma_f32_16x16x32_bf16 v[190:193], v[244:247], v[198:201], v[190:193]
	s_waitcnt lgkmcnt(0)
	v_mfma_f32_16x16x32_bf16 v[76:79], v[248:251], v[76:79], v[190:193]
	v_mfma_f32_16x16x32_bf16 v[60:63], v[248:251], v[202:205], v[60:63]
	s_nop 3
	s_setprio 0
	s_add_i32 s22, s10, 1
	s_cmp_ge_u32 s22, s19
	s_cbranch_scc1 .LBB0_2970
	s_bitcmp1_b32 s22, 0
	s_cselect_b32 s11, 0xb800, 0
	v_add3_u32 v85, s11, v95, v96
	s_waitcnt vmcnt(0)
	ds_write_b128 v85, v[28:31]
	v_add3_u32 v85, s11, v99, v96
	ds_write_b128 v85, v[36:39]
	v_add3_u32 v85, s11, v184, v96
	ds_write_b128 v85, v[32:35] offset:26624
	v_add3_u32 v85, s11, v185, v96
	ds_write_b128 v85, v[40:43] offset:26624
	v_add3_u32 v85, s11, v111, v98
	ds_write_b128 v85, v[44:47] offset:128

.LBB0_2973:
	v_mov_b32_e32 v4, v101
	s_nop 1
	v_permlane16_swap_b32_e32 v101, v4
	v_add_f32_e32 v4, v101, v4
	v_mov_b32_e32 v5, v4
	s_nop 1
	v_permlane32_swap_b32_e32 v4, v5
	v_add_f32_e32 v4, v4, v5
	v_div_scale_f32 v5, s[6:7], v4, v4, 1.0
	v_rcp_f32_e32 v6, v5
	v_lshlrev_b32_e32 v88, 1, v97
	v_fma_f32 v7, -v5, v6, 1.0
	v_fmac_f32_e32 v6, v7, v6
	v_div_scale_f32 v7, vcc, 1.0, v4, 1.0
	v_mul_f32_e32 v8, v7, v6
	v_fma_f32 v9, -v5, v8, v7
	v_fmac_f32_e32 v8, v9, v6
	v_fma_f32 v5, -v5, v8, v7
	v_div_fmas_f32 v5, v5, v6, v8
	v_lshlrev_b64 v[6:7], 11, v[92:93]
	v_div_fixup_f32 v4, v5, v4, 1.0
	v_lshl_add_u64 v[6:7], s[48:49], 0, v[6:7]
	v_lshl_add_u64 v[6:7], v[6:7], 0, s[44:45]
	v_mul_f32 v8, v68, v4
	v_mul_f32 v9, v69, v4
	v_mul_f32 v10, v70, v4
	v_mul_f32 v11, v71, v4
	v_lshl_add_u64 v[6:7], v[6:7], 0, v[88:89]
	v_cvt_pk_bf16_f32 v8, v8, v9
	v_cvt_pk_bf16_f32 v9, v10, v11
	flat_store_dwordx2 v[6:7], v[8:9]
	v_mul_f32 v8, v64, v4
	v_mul_f32 v9, v65, v4
	v_mul_f32 v10, v66, v4
	v_mul_f32 v11, v67, v4
	v_cvt_pk_bf16_f32 v8, v8, v9
	v_cvt_pk_bf16_f32 v9, v10, v11
	flat_store_dwordx2 v[6:7], v[8:9] offset:32
	v_mul_f32 v8, v72, v4
	v_mul_f32 v9, v73, v4
	v_mul_f32 v10, v74, v4
	v_mul_f32 v11, v75, v4
	v_cvt_pk_bf16_f32 v8, v8, v9
	v_cvt_pk_bf16_f32 v9, v10, v11
	flat_store_dwordx2 v[6:7], v[8:9] offset:64
	v_mul_f32 v8, v76, v4
	v_mul_f32 v9, v77, v4
	v_mov_b32_e32 v5, v100
	s_nop 1
	v_permlane16_swap_b32_e32 v100, v5
	v_add_f32_e32 v5, v100, v5
	v_cvt_pk_bf16_f32 v8, v8, v9
	v_mov_b32_e32 v9, v5
	s_nop 1
	v_permlane32_swap_b32_e32 v5, v9
	v_add_f32_e32 v10, v5, v9
	v_div_scale_f32 v11, s[6:7], v10, v10, 1.0
	v_rcp_f32_e32 v12, v11
	v_mul_f32 v5, v79, v4
	v_mul_f32 v4, v78, v4
	s_nop 0
	v_cvt_pk_bf16_f32 v9, v4, v5
	v_fma_f32 v4, -v11, v12, 1.0
	v_fmac_f32_e32 v12, v4, v12
	v_div_scale_f32 v4, vcc, 1.0, v10, 1.0
	v_mul_f32_e32 v5, v4, v12
	flat_store_dwordx2 v[6:7], v[8:9] offset:96
	v_fma_f32 v6, -v11, v5, v4
	v_fmac_f32_e32 v5, v6, v12
	v_fma_f32 v4, -v11, v5, v4
	v_div_fmas_f32 v4, v4, v12, v5
	v_lshlrev_b64 v[6:7], 11, v[90:91]
	v_div_fixup_f32 v4, v4, v10, 1.0
	v_lshl_add_u64 v[6:7], s[48:49], 0, v[6:7]
	v_lshl_add_u64 v[6:7], v[6:7], 0, s[44:45]
	v_mul_f32 v8, v52, v4
	v_mul_f32 v9, v53, v4
	v_mul_f32 v10, v54, v4
	v_mul_f32 v11, v55, v4
	v_lshl_add_u64 v[6:7], v[6:7], 0, v[88:89]
	v_cvt_pk_bf16_f32 v8, v8, v9
	v_cvt_pk_bf16_f32 v9, v10, v11
	flat_store_dwordx2 v[6:7], v[8:9]
	v_mul_f32 v8, v48, v4
	v_mul_f32 v9, v49, v4
	v_mul_f32 v10, v50, v4
	v_mul_f32 v11, v51, v4
	v_cvt_pk_bf16_f32 v8, v8, v9
	v_cvt_pk_bf16_f32 v9, v10, v11
	flat_store_dwordx2 v[6:7], v[8:9] offset:32
	v_mul_f32 v8, v56, v4
	v_mul_f32 v9, v57, v4
	v_mul_f32 v10, v58, v4
	v_mul_f32 v11, v59, v4
	v_cvt_pk_bf16_f32 v8, v8, v9
	v_cvt_pk_bf16_f32 v9, v10, v11
	flat_store_dwordx2 v[6:7], v[8:9] offset:64
	v_mul_f32 v8, v60, v4
	v_mul_f32 v9, v61, v4
	v_mul_f32 v5, v63, v4
	v_mul_f32 v4, v62, v4
	v_cvt_pk_bf16_f32 v8, v8, v9
	v_cvt_pk_bf16_f32 v9, v4, v5
	flat_store_dwordx2 v[6:7], v[8:9] offset:96
	s_waitcnt lgkmcnt(0)
	s_barrier
	s_and_saveexec_b64 s[6:7], s[4:5]
	s_cbranch_execz .LBB0_2955
	v_readlane_b32 s8, v252, 23
	v_readlane_b32 s9, v252, 24
	s_nop 1
	v_mov_b64_e32 v[4:5], s[8:9]
	flat_atomic_add v4, v[4:5], v176 sc0
	s_waitcnt vmcnt(0) lgkmcnt(0)
	ds_write_b32 v177, v4
	s_branch .LBB0_2955

.LBB0_2991:
	s_bitcmp1_b32 s25, 0
	s_cselect_b32 s25, 0xb200, 0
	v_or_b32_e32 v102, s25, v68
	s_add_i32 s44, s25, s37
	v_or_b32_e32 v81, s25, v67
	s_add_i32 s44, s44, s40
	v_add_u32_e32 v86, v102, v70
	v_add_u32_e32 v44, s44, v69
	v_add_u32_e32 v106, v81, v70
	v_add_u32_e32 v86, 0x2000, v86
	ds_read_b64 v[46:47], v44 offset:36864
	ds_read_b128 v[90:93], v106
	ds_read2_b64 v[94:97], v86 offset0:128 offset1:132
	s_add_i32 s44, s25, s41
	v_cvt_pk_bf16_f32 v48, v8, v9
	v_cvt_pk_bf16_f32 v49, v10, v11
	v_cvt_pk_bf16_f32 v50, v4, v5
	v_cvt_pk_bf16_f32 v51, v6, v7
	s_waitcnt lgkmcnt(0)
	v_lshlrev_b32_e32 v44, 16, v46
	v_and_b32_e32 v45, 0xffff0000, v46
	v_lshlrev_b32_e32 v46, 16, v47
	v_and_b32_e32 v47, 0xffff0000, v47
	s_add_i32 s44, s44, s40
	v_cvt_pk_bf16_f32 v82, v12, v13
	v_mfma_f32_16x16x32_bf16 v[44:47], v[90:93], v[48:51], v[44:47]
	v_cvt_pk_bf16_f32 v83, v14, v15
	v_cvt_pk_bf16_f32 v84, v16, v17
	v_cvt_pk_bf16_f32 v85, v18, v19
	v_mfma_f32_16x16x32_bf16 v[90:93], v[94:97], v[48:51], v[0:3]
	ds_read_b128 v[94:97], v106 offset:64
	ds_read2_b64 v[98:101], v86 offset0:136 offset1:140
	v_add_u32_e32 v86, s44, v69
	ds_read_b64 v[86:87], v86 offset:36864
	s_waitcnt lgkmcnt(0)
	v_mfma_f32_16x16x32_bf16 v[94:97], v[94:97], v[82:85], v[44:47]
	s_andn2_b64 vcc, exec, s[22:23]
	v_mfma_f32_16x16x32_bf16 v[44:47], v[98:101], v[82:85], v[90:93]
	s_nop 2
	v_lshlrev_b32_e32 v92, 16, v87
	v_and_b32_e32 v93, 0xffff0000, v87
	v_add_u32_e32 v87, v102, v71
	v_lshlrev_b32_e32 v90, 16, v86
	v_and_b32_e32 v91, 0xffff0000, v86
	v_add_u32_e32 v86, v81, v71
	v_add_u32_e32 v87, 0x2000, v87
	ds_read_b128 v[98:101], v86
	ds_read2_b64 v[102:105], v87 offset0:128 offset1:132
	s_waitcnt lgkmcnt(0)
	v_mfma_f32_16x16x32_bf16 v[90:93], v[98:101], v[48:51], v[90:93]
	v_add_u32_e32 v81, v81, v72
	v_mfma_f32_16x16x32_bf16 v[48:51], v[102:105], v[48:51], v[0:3]
	ds_read_b128 v[98:101], v86 offset:64
	ds_read2_b64 v[102:105], v87 offset0:136 offset1:140
	v_mov_b32_e32 v86, s25
	s_waitcnt lgkmcnt(0)
	v_mfma_f32_16x16x32_bf16 v[90:93], v[98:101], v[82:85], v[90:93]
	v_mfma_f32_16x16x32_bf16 v[48:51], v[102:105], v[82:85], v[48:51]
	v_cvt_pk_bf16_f32 v82, v94, v95
	v_cvt_pk_bf16_f32 v83, v96, v97
	s_nop 4
	v_cvt_pk_bf16_f32 v84, v90, v91
	v_cvt_pk_bf16_f32 v85, v92, v93
	ds_write_b128 v79, v[82:85]
	s_waitcnt lgkmcnt(0)
	s_barrier
	ds_read_b128 v[90:93], v80
	s_waitcnt lgkmcnt(0)
	v_cndmask_b32_e64 v97, v93, v85, s[12:13]
	v_cndmask_b32_e64 v96, v92, v84, s[12:13]
	v_cndmask_b32_e64 v95, v91, v83, s[12:13]
	v_cndmask_b32_e64 v94, v90, v82, s[12:13]
	v_cndmask_b32_e64 v85, v85, v93, s[12:13]
	v_cndmask_b32_e64 v84, v84, v92, s[12:13]
	v_cndmask_b32_e64 v83, v83, v91, s[12:13]
	v_cndmask_b32_e64 v82, v82, v90, s[12:13]
	ds_read_b32 v86, v86 offset:45312
	ds_read_b128 v[90:93], v106 offset:18432
	ds_read_b128 v[98:101], v106 offset:18496
	ds_read_b128 v[102:105], v106 offset:20800
	s_waitcnt lgkmcnt(0)
	v_mfma_f32_16x16x32_bf16 v[90:93], v[90:93], v[94:97], v[0:3]
	v_mul_f32_e64 v10, v10, v86
	v_mul_f32_e64 v11, v11, v86
	v_mul_f32 v8, v8, v86
	v_mul_f32 v9, v9, v86
	v_mul_f32 v6, v6, v86
	v_mul_f32 v7, v7, v86
	v_mfma_f32_16x16x32_bf16 v[90:93], v[98:101], v[82:85], v[90:93]
	ds_read_b128 v[98:101], v106 offset:20736
	v_mul_f32 v4, v4, v86
	v_mul_f32 v5, v5, v86
	v_mul_f32 v14, v14, v86
	v_mul_f32 v15, v15, v86
	s_waitcnt lgkmcnt(0)
	v_mfma_f32_16x16x32_bf16 v[98:101], v[98:101], v[94:97], v[0:3]
	v_mul_f32_e64 v12, v12, v86
	v_mul_f32_e64 v13, v13, v86
	v_mul_f32 v18, v18, v86
	v_mul_f32 v19, v19, v86
	v_mul_f32 v16, v16, v86
	v_mul_f32 v17, v17, v86
	v_mfma_f32_16x16x32_bf16 v[98:101], v[102:105], v[82:85], v[98:101]
	ds_read_b128 v[102:105], v81 offset:27648
	v_add_u32_e32 v86, 16, v76
	s_waitcnt lgkmcnt(0)
	v_mfma_f32_16x16x32_bf16 v[8:11], v[102:105], v[94:97], v[8:11]
	ds_read_b128 v[102:105], v81 offset:27712
	s_waitcnt lgkmcnt(0)
	v_mfma_f32_16x16x32_bf16 v[8:11], v[102:105], v[82:85], v[8:11]
	ds_read_b128 v[102:105], v81 offset:29952
	s_waitcnt lgkmcnt(0)
	v_mfma_f32_16x16x32_bf16 v[4:7], v[102:105], v[94:97], v[4:7]
	ds_read_b128 v[102:105], v81 offset:30016
	s_waitcnt lgkmcnt(0)
	v_mfma_f32_16x16x32_bf16 v[4:7], v[102:105], v[82:85], v[4:7]
	ds_read_b128 v[102:105], v81 offset:32256
	s_waitcnt lgkmcnt(0)
	v_mfma_f32_16x16x32_bf16 v[12:15], v[102:105], v[94:97], v[12:15]
	ds_read_b128 v[102:105], v81 offset:32320
	s_waitcnt lgkmcnt(0)
	v_mfma_f32_16x16x32_bf16 v[12:15], v[102:105], v[82:85], v[12:15]
	ds_read_b128 v[102:105], v81 offset:34560
	s_waitcnt lgkmcnt(0)
	v_mfma_f32_16x16x32_bf16 v[16:19], v[102:105], v[94:97], v[16:19]
	ds_read_b128 v[94:97], v81 offset:34624
	v_add_u32_e32 v81, s25, v74
	s_waitcnt lgkmcnt(0)
	v_mfma_f32_16x16x32_bf16 v[16:19], v[94:97], v[82:85], v[16:19]
	ds_read_b128 v[82:85], v81 offset:45056
	v_add_u32_e32 v81, s35, v73
	v_cndmask_b32_e64 v86, v86, v81, s[6:7]
	v_ashrrev_i32_e32 v87, 31, v86
	v_lshl_add_u64 v[86:87], v[86:87], 0, s[20:21]
	s_waitcnt lgkmcnt(0)
	v_fma_f32 v44, v44, v82, v90
	v_bfe_u32 v82, v44, 16, 1
	v_lshlrev_b64 v[86:87], 9, v[86:87]
	v_add3_u32 v44, v44, v82, s93
	v_lshl_add_u64 v[86:87], v[54:55], 0, v[86:87]
	flat_store_short_d16_hi v[86:87], v44
	v_add_u32_e32 v44, 1, v81
	v_xad_u32 v82, v81, -2, s17
	v_cndmask_b32_e64 v86, v82, v44, s[6:7]
	v_ashrrev_i32_e32 v87, 31, v86
	v_fma_f32 v44, v45, v83, v91
	v_lshl_add_u64 v[86:87], v[86:87], 0, s[20:21]
	v_bfe_u32 v45, v44, 16, 1
	v_add3_u32 v82, v44, v45, s93
	v_lshlrev_b64 v[44:45], 9, v[86:87]
	v_lshl_add_u64 v[44:45], v[54:55], 0, v[44:45]
	flat_store_short_d16_hi v[44:45], v82
	v_add_u32_e32 v44, 2, v81
	v_xad_u32 v45, v81, -3, s17
	v_cndmask_b32_e64 v44, v45, v44, s[6:7]
	v_ashrrev_i32_e32 v45, 31, v44
	v_lshl_add_u64 v[44:45], v[44:45], 0, s[20:21]
	v_fma_f32 v46, v46, v84, v92
	v_bfe_u32 v82, v46, 16, 1
	v_lshlrev_b64 v[44:45], 9, v[44:45]
	v_add3_u32 v46, v46, v82, s93
	v_lshl_add_u64 v[44:45], v[54:55], 0, v[44:45]
	flat_store_short_d16_hi v[44:45], v46
	v_add_u32_e32 v44, 3, v81
	v_xad_u32 v45, v81, -4, s17
	v_cndmask_b32_e64 v44, v45, v44, s[6:7]
	v_ashrrev_i32_e32 v45, 31, v44
	v_lshl_add_u64 v[44:45], v[44:45], 0, s[20:21]
	v_fmac_f32_e32 v93, v47, v85
	v_bfe_u32 v46, v93, 16, 1
	v_lshlrev_b64 v[44:45], 9, v[44:45]
	v_add3_u32 v46, v93, v46, s93
	v_lshl_add_u64 v[44:45], v[54:55], 0, v[44:45]
	flat_store_short_d16_hi v[44:45], v46
	v_add_u32_e32 v44, s25, v75
	ds_read_b128 v[44:47], v44 offset:45056
	v_add_u32_e32 v84, 16, v81
	v_cndmask_b32_e64 v82, v76, v84, s[6:7]
	v_ashrrev_i32_e32 v83, 31, v82
	v_lshl_add_u64 v[82:83], v[82:83], 0, s[20:21]
	s_waitcnt lgkmcnt(0)
	v_fma_f32 v44, v48, v44, v98
	v_bfe_u32 v48, v44, 16, 1
	v_lshlrev_b64 v[82:83], 9, v[82:83]
	v_add3_u32 v44, v44, v48, s93
	v_lshl_add_u64 v[82:83], v[54:55], 0, v[82:83]
	flat_store_short_d16_hi v[82:83], v44
	v_add_u32_e32 v44, 17, v81
	v_xad_u32 v48, v84, -2, s17
	v_cndmask_b32_e64 v82, v48, v44, s[6:7]
	v_ashrrev_i32_e32 v83, 31, v82
	v_fma_f32 v44, v49, v45, v99
	v_lshl_add_u64 v[82:83], v[82:83], 0, s[20:21]
	v_bfe_u32 v45, v44, 16, 1
	v_add3_u32 v48, v44, v45, s93
	v_lshlrev_b64 v[44:45], 9, v[82:83]
	v_lshl_add_u64 v[44:45], v[54:55], 0, v[44:45]
	flat_store_short_d16_hi v[44:45], v48
	v_add_u32_e32 v44, 18, v81
	v_xad_u32 v45, v84, -3, s17
	v_cndmask_b32_e64 v44, v45, v44, s[6:7]
	v_ashrrev_i32_e32 v45, 31, v44
	v_lshl_add_u64 v[44:45], v[44:45], 0, s[20:21]
	v_fma_f32 v46, v50, v46, v100
	v_bfe_u32 v48, v46, 16, 1
	v_lshlrev_b64 v[44:45], 9, v[44:45]
	v_add3_u32 v46, v46, v48, s93
	v_lshl_add_u64 v[44:45], v[54:55], 0, v[44:45]
	flat_store_short_d16_hi v[44:45], v46
	v_add_u32_e32 v44, 19, v81
	v_xad_u32 v45, v84, -4, s17
	v_cndmask_b32_e64 v44, v45, v44, s[6:7]
	v_ashrrev_i32_e32 v45, 31, v44
	v_lshl_add_u64 v[44:45], v[44:45], 0, s[20:21]
	v_fmac_f32_e32 v101, v51, v47
	v_bfe_u32 v46, v101, 16, 1
	v_lshlrev_b64 v[44:45], 9, v[44:45]
	v_add3_u32 v46, v101, v46, s93
	v_lshl_add_u64 v[44:45], v[54:55], 0, v[44:45]
	flat_store_short_d16_hi v[44:45], v46
	s_cbranch_vccnz .LBB0_2988
	s_bitcmp1_b32 s24, 0
	s_cselect_b32 s25, 0xb200, 0
	v_add3_u32 v44, s25, v65, v88
	s_waitcnt vmcnt(0)
	ds_write_b128 v44, v[20:23]
	ds_write_b128 v44, v[36:39] offset:9216
	ds_write_b128 v44, v[24:27] offset:18432
	ds_write_b128 v44, v[28:31] offset:27648
	v_add_u32_e32 v44, s25, v64
	ds_write_b128 v44, v[32:35] offset:36864
	s_and_saveexec_b64 s[22:23], s[8:9]
	ds_write_b128 v44, v[40:43] offset:45056
	s_or_b64 exec, exec, s[22:23]
	s_and_saveexec_b64 s[22:23], s[10:11]
	s_cbranch_execz .LBB0_2987
	v_mov_b32_e32 v44, s25
	ds_write_b32 v44, v66 offset:45312
	s_branch .LBB0_2987

.Lhy_lat1_done:
.LBB0_3023:
	s_waitcnt vmcnt(0)
	s_xor_b64 s[12:13], s[6:7], -1
	s_and_b64 s[18:19], s[6:7], exec
	s_cselect_b32 s18, s2, 0xddf2000
	s_add_u32 s18, s8, s18
	s_addc_u32 s19, s9, 0
	v_cndmask_b32_e64 v30, v35, v34, s[6:7]
	s_and_b64 s[6:7], s[6:7], exec
	s_mov_b32 s6, 0x9380
	s_cselect_b32 s6, 0x4380, s6
	v_lshl_add_u64 v[32:33], v[20:21], 1, s[18:19]
	v_lshl_add_u32 v31, v20, 1, s6
	s_movk_i32 s6, 0x2000
	v_add_co_u32_e32 v42, vcc, s6, v32
	ds_read_b64 v[40:41], v31
	s_nop 0
	v_addc_co_u32_e32 v43, vcc, 0, v33, vcc
	v_mov_b32_e32 v49, v18
	s_waitcnt lgkmcnt(0)
	v_lshlrev_b32_e32 v47, 16, v41
	v_lshlrev_b32_e32 v46, 16, v40
	v_and_b32_e32 v41, 0xffff0000, v41
	v_and_b32_e32 v40, 0xffff0000, v40
	v_mov_b32_e32 v18, v17
	v_mov_b32_e32 v48, v16
	v_fma_f32 v16, v30, v40, v18
	v_fma_f32 v17, v30, v41, v19
	v_fma_f32 v46, v30, v46, v48
	v_fma_f32 v47, v30, v47, v49
	s_mov_b64 s[6:7], -1
	s_and_b64 vcc, exec, s[12:13]
	s_waitcnt vmcnt(0)
	v_lshlrev_b32_e32 v45, 16, v141
	v_lshlrev_b32_e32 v44, 16, v140
	v_and_b32_e32 v43, 0xffff0000, v141
	v_and_b32_e32 v42, 0xffff0000, v140
	v_mul_f32 v16, v16, v42
	v_mul_f32 v17, v17, v43
	v_mul_f32 v44, v46, v44
	v_mul_f32 v45, v47, v45
	v_and_b32_sdwa v31, v17, v176 dst_sel:DWORD dst_unused:UNUSED_PAD src0_sel:WORD_1 src1_sel:DWORD
	v_and_b32_sdwa v40, v16, v176 dst_sel:DWORD dst_unused:UNUSED_PAD src0_sel:WORD_1 src1_sel:DWORD
	v_and_b32_sdwa v18, v45, v176 dst_sel:DWORD dst_unused:UNUSED_PAD src0_sel:WORD_1 src1_sel:DWORD
	v_and_b32_sdwa v19, v44, v176 dst_sel:DWORD dst_unused:UNUSED_PAD src0_sel:WORD_1 src1_sel:DWORD
	v_add3_u32 v17, v17, v31, s93
	v_add3_u32 v16, v16, v40, s93
	v_add3_u32 v19, v44, v19, s93
	v_add3_u32 v18, v45, v18, s93
	v_and_b32_e32 v17, 0xffff0000, v17
	v_and_b32_e32 v16, 0xffff0000, v16
	v_or_b32_sdwa v17, v17, v18 dst_sel:DWORD dst_unused:UNUSED_PAD src0_sel:DWORD src1_sel:WORD_1
	v_or_b32_sdwa v16, v16, v19 dst_sel:DWORD dst_unused:UNUSED_PAD src0_sel:DWORD src1_sel:WORD_1
	s_cbranch_vccz .LBB0_3025
	flat_store_dwordx2 v[22:23], v[16:17]
	s_mov_b64 s[6:7], 0

.LBB0_3027:
	v_lshl_add_u64 v[16:17], v[32:33], 0, s[52:53]
	v_add_co_u32_e32 v18, vcc, 0x1000, v16
	v_lshl_add_u32 v40, v20, 1, s6
	s_nop 0
	v_addc_co_u32_e32 v19, vcc, 0, v17, vcc
	ds_read_b64 v[40:41], v40 offset:512
	v_mov_b32_e32 v32, v12
	v_cndmask_b32_e64 v12, 0, 1, s[12:13]
	v_mov_b32_e32 v31, v30
	v_mov_b32_e32 v33, v14
	v_mov_b32_e32 v14, v13
	v_cmp_ne_u32_e64 s[6:7], 1, v12
	s_waitcnt lgkmcnt(0)
	v_lshlrev_b32_e32 v13, 16, v41
	v_lshlrev_b32_e32 v12, 16, v40
	v_and_b32_e32 v41, 0xffff0000, v41
	v_and_b32_e32 v40, 0xffff0000, v40
	v_fma_f32 v12, v30, v12, v32
	v_fma_f32 v13, v31, v13, v33
	v_fma_f32 v14, v30, v40, v14
	v_fma_f32 v15, v31, v41, v15
	s_andn2_b64 vcc, exec, s[12:13]
	s_mov_b64 s[12:13], -1
	v_lshlrev_b32_e32 v33, 16, v143
	v_lshlrev_b32_e32 v32, 16, v142
	v_and_b32_e32 v19, 0xffff0000, v143
	v_and_b32_e32 v18, 0xffff0000, v142
	v_mul_f32 v14, v14, v18
	v_mul_f32 v15, v15, v19
	v_mul_f32 v12, v12, v32
	v_mul_f32 v13, v13, v33
	v_and_b32_sdwa v32, v15, v176 dst_sel:DWORD dst_unused:UNUSED_PAD src0_sel:WORD_1 src1_sel:DWORD
	v_and_b32_sdwa v33, v14, v176 dst_sel:DWORD dst_unused:UNUSED_PAD src0_sel:WORD_1 src1_sel:DWORD
	v_and_b32_sdwa v18, v13, v176 dst_sel:DWORD dst_unused:UNUSED_PAD src0_sel:WORD_1 src1_sel:DWORD
	v_and_b32_sdwa v19, v12, v176 dst_sel:DWORD dst_unused:UNUSED_PAD src0_sel:WORD_1 src1_sel:DWORD
	v_add3_u32 v15, v15, v32, s93
	v_add3_u32 v14, v14, v33, s93
	v_add3_u32 v12, v12, v19, s93
	v_add3_u32 v13, v13, v18, s93
	v_and_b32_e32 v15, 0xffff0000, v15
	v_and_b32_e32 v14, 0xffff0000, v14
	v_or_b32_sdwa v13, v15, v13 dst_sel:DWORD dst_unused:UNUSED_PAD src0_sel:DWORD src1_sel:WORD_1
	v_or_b32_sdwa v12, v14, v12 dst_sel:DWORD dst_unused:UNUSED_PAD src0_sel:DWORD src1_sel:WORD_1
	s_cbranch_vccnz .LBB0_3029
	s_mov_b64 s[12:13], 0
	flat_store_dwordx2 v[24:25], v[12:13]

.LBB0_3031:
	v_add_co_u32_e32 v12, vcc, 0x2000, v16
	v_lshl_add_u32 v14, v20, 1, s12
	s_nop 0
	v_addc_co_u32_e32 v13, vcc, 0, v17, vcc
	ds_read_b64 v[14:15], v14 offset:512
	v_mov_b32_e32 v18, v8
	v_mov_b32_e32 v19, v10
	v_mov_b32_e32 v10, v9
	s_and_b64 vcc, exec, s[6:7]
	s_waitcnt lgkmcnt(0)
	v_lshlrev_b32_e32 v9, 16, v15
	v_lshlrev_b32_e32 v8, 16, v14
	v_and_b32_e32 v15, 0xffff0000, v15
	v_and_b32_e32 v14, 0xffff0000, v14
	v_fma_f32 v10, v30, v14, v10
	v_fma_f32 v11, v31, v15, v11
	v_fma_f32 v8, v30, v8, v18
	v_fma_f32 v9, v31, v9, v19
	s_mov_b64 s[12:13], -1
	v_lshlrev_b32_e32 v15, 16, v145
	v_lshlrev_b32_e32 v14, 16, v144
	v_and_b32_e32 v13, 0xffff0000, v145
	v_and_b32_e32 v12, 0xffff0000, v144
	v_mul_f32 v10, v10, v12
	v_mul_f32 v11, v11, v13
	v_mul_f32 v8, v8, v14
	v_mul_f32 v9, v9, v15
	v_and_b32_sdwa v14, v11, v176 dst_sel:DWORD dst_unused:UNUSED_PAD src0_sel:WORD_1 src1_sel:DWORD
	v_and_b32_sdwa v15, v10, v176 dst_sel:DWORD dst_unused:UNUSED_PAD src0_sel:WORD_1 src1_sel:DWORD
	v_and_b32_sdwa v12, v9, v176 dst_sel:DWORD dst_unused:UNUSED_PAD src0_sel:WORD_1 src1_sel:DWORD
	v_and_b32_sdwa v13, v8, v176 dst_sel:DWORD dst_unused:UNUSED_PAD src0_sel:WORD_1 src1_sel:DWORD
	v_add3_u32 v11, v11, v14, s93
	v_add3_u32 v10, v10, v15, s93
	v_add3_u32 v8, v8, v13, s93
	v_add3_u32 v9, v9, v12, s93
	v_and_b32_e32 v11, 0xffff0000, v11
	v_and_b32_e32 v10, 0xffff0000, v10
	v_or_b32_sdwa v9, v11, v9 dst_sel:DWORD dst_unused:UNUSED_PAD src0_sel:DWORD src1_sel:WORD_1
	v_or_b32_sdwa v8, v10, v8 dst_sel:DWORD dst_unused:UNUSED_PAD src0_sel:DWORD src1_sel:WORD_1
	s_cbranch_vccnz .LBB0_3033
	s_mov_b64 s[12:13], 0
	flat_store_dwordx2 v[26:27], v[8:9]

.LBB0_3035:
	v_add_co_u32_e32 v8, vcc, 0x3000, v16
	v_lshl_add_u32 v10, v20, 1, s12
	s_nop 0
	v_addc_co_u32_e32 v9, vcc, 0, v17, vcc
	ds_read_b64 v[10:11], v10 offset:512
	v_mov_b32_e32 v12, v4
	v_mov_b32_e32 v13, v6
	v_mov_b32_e32 v6, v5
	s_and_b64 vcc, exec, s[6:7]
	s_waitcnt lgkmcnt(0)
	v_lshlrev_b32_e32 v5, 16, v11
	v_lshlrev_b32_e32 v4, 16, v10
	v_and_b32_e32 v11, 0xffff0000, v11
	v_and_b32_e32 v10, 0xffff0000, v10
	v_fma_f32 v6, v30, v10, v6
	v_fma_f32 v7, v31, v11, v7
	v_fma_f32 v4, v30, v4, v12
	v_fma_f32 v5, v31, v5, v13
	s_mov_b64 s[12:13], -1
	v_lshlrev_b32_e32 v11, 16, v147
	v_lshlrev_b32_e32 v10, 16, v146
	v_and_b32_e32 v9, 0xffff0000, v147
	v_and_b32_e32 v8, 0xffff0000, v146
	v_mul_f32 v6, v6, v8
	v_mul_f32 v7, v7, v9
	v_mul_f32 v4, v4, v10
	v_mul_f32 v5, v5, v11
	v_and_b32_sdwa v10, v7, v176 dst_sel:DWORD dst_unused:UNUSED_PAD src0_sel:WORD_1 src1_sel:DWORD
	v_and_b32_sdwa v11, v6, v176 dst_sel:DWORD dst_unused:UNUSED_PAD src0_sel:WORD_1 src1_sel:DWORD
	v_and_b32_sdwa v8, v5, v176 dst_sel:DWORD dst_unused:UNUSED_PAD src0_sel:WORD_1 src1_sel:DWORD
	v_and_b32_sdwa v9, v4, v176 dst_sel:DWORD dst_unused:UNUSED_PAD src0_sel:WORD_1 src1_sel:DWORD
	v_add3_u32 v7, v7, v10, s93
	v_add3_u32 v6, v6, v11, s93
	v_add3_u32 v4, v4, v9, s93
	v_add3_u32 v5, v5, v8, s93
	v_and_b32_e32 v7, 0xffff0000, v7
	v_and_b32_e32 v6, 0xffff0000, v6
	v_or_b32_sdwa v5, v7, v5 dst_sel:DWORD dst_unused:UNUSED_PAD src0_sel:DWORD src1_sel:WORD_1
	v_or_b32_sdwa v4, v6, v4 dst_sel:DWORD dst_unused:UNUSED_PAD src0_sel:DWORD src1_sel:WORD_1
	s_cbranch_vccnz .LBB0_3037
	s_mov_b64 s[12:13], 0
	flat_store_dwordx2 v[28:29], v[4:5]

.LBB0_3058:
	s_bitcmp1_b32 s82, 0
	s_cselect_b32 s83, 0x9800, 0
	s_cmp_lt_i32 s82, s76
	s_cselect_b64 s[6:7], -1, 0
	s_and_b64 s[74:75], s[70:71], s[6:7]
	s_cmp_eq_u64 s[74:75], 0
	s_cbranch_scc1 .Lnm1_entry
	s_setprio 1
	v_or_b32_e32 v68, s83, v94
	v_add_u32_e32 v88, v68, v163
	ds_read_b128 v[204:207], v88 offset:2304
	ds_read_b128 v[208:211], v88
	ds_read_b128 v[212:215], v88 offset:4608
	ds_read_b128 v[216:219], v88 offset:6912
	ds_read_b128 v[220:223], v88 offset:64
	ds_read_b128 v[224:227], v88 offset:2368
	ds_read_b128 v[228:231], v88 offset:4672
	ds_read_b128 v[232:235], v88 offset:6976
	s_waitcnt lgkmcnt(7)
	v_mfma_f32_16x16x32_bf16 v[82:85], v[204:207], v[4:7], v[0:3]
	v_mfma_f32_16x16x32_bf16 v[108:111], v[204:207], v[12:15], v[0:3]
	s_waitcnt lgkmcnt(5)
	v_mfma_f32_16x16x32_bf16 v[112:115], v[212:215], v[4:7], v[0:3]
	v_mfma_f32_16x16x32_bf16 v[116:119], v[212:215], v[12:15], v[0:3]
	s_waitcnt lgkmcnt(4)
	v_mfma_f32_16x16x32_bf16 v[120:123], v[216:219], v[4:7], v[0:3]
	v_mfma_f32_16x16x32_bf16 v[124:127], v[216:219], v[12:15], v[0:3]
	v_mfma_f32_16x16x32_bf16 v[74:77], v[208:211], v[4:7], v[0:3]
	v_mfma_f32_16x16x32_bf16 v[68:71], v[208:211], v[12:15], v[0:3]
	s_waitcnt lgkmcnt(3)
	v_mfma_f32_16x16x32_bf16 v[128:131], v[220:223], v[8:11], v[74:77]
	v_mfma_f32_16x16x32_bf16 v[76:79], v[220:223], v[16:19], v[68:71]
	s_waitcnt lgkmcnt(2)
	v_mfma_f32_16x16x32_bf16 v[132:135], v[224:227], v[8:11], v[82:85]
	v_mfma_f32_16x16x32_bf16 v[80:83], v[224:227], v[16:19], v[108:111]
	s_waitcnt lgkmcnt(1)
	v_mfma_f32_16x16x32_bf16 v[108:111], v[228:231], v[8:11], v[112:115]
	v_mfma_f32_16x16x32_bf16 v[84:87], v[228:231], v[16:19], v[116:119]
	s_waitcnt lgkmcnt(0)
	v_mfma_f32_16x16x32_bf16 v[112:115], v[232:235], v[8:11], v[120:123]
	v_mfma_f32_16x16x32_bf16 v[142:145], v[232:235], v[16:19], v[124:127]
	s_nop 1
	s_setprio 0
	v_add_u32_e32 v69, 0x73, v166
	v_cmp_gt_u32_e32 vcc, s39, v69
	v_add_u32_e32 v70, 0x72, v166
	s_and_b64 s[12:13], s[74:75], vcc
	v_cmp_gt_u32_e32 vcc, s39, v70
	v_add_u32_e32 v72, 0x71, v166
	s_and_b64 s[14:15], s[74:75], vcc
	v_cmp_gt_u32_e32 vcc, s39, v72
	v_add_u32_e32 v74, 0x70, v166
	s_and_b64 s[16:17], s[74:75], vcc
	v_cmp_gt_u32_e32 vcc, s39, v74
	v_add_u32_e32 v75, 0x63, v166
	s_and_b64 s[18:19], s[74:75], vcc
	v_cmp_gt_u32_e32 vcc, s39, v75
	v_add_u32_e32 v106, 0x62, v166
	s_and_b64 s[20:21], s[74:75], vcc
	v_cmp_gt_u32_e32 vcc, s39, v106
	v_add_u32_e32 v116, 0x61, v166
	s_and_b64 s[22:23], s[74:75], vcc
	v_cmp_gt_u32_e32 vcc, s39, v116
	v_add_u32_e32 v117, 0x60, v166
	s_and_b64 s[24:25], s[74:75], vcc
	v_cmp_gt_u32_e32 vcc, s39, v117
	v_add_u32_e32 v117, 0x53, v166
	s_and_b64 s[26:27], s[74:75], vcc
	v_cmp_gt_u32_e32 vcc, s39, v117
	v_add_u32_e32 v117, 0x52, v166
	v_mul_f32_e32 v68, 0x3e38aa3b, v128
	v_mul_f32_e32 v69, 0x3e38aa3b, v129
	s_and_b64 s[28:29], s[74:75], vcc
	v_cmp_gt_u32_e32 vcc, s39, v117
	v_add_u32_e32 v117, 0x51, v166
	v_cndmask_b32_e64 v68, v68, v181, s[12:13]
	v_cndmask_b32_e64 v69, v69, v181, s[14:15]
	v_mul_f32_e32 v71, 0x3e38aa3b, v130
	v_mul_f32_e32 v72, 0x3e38aa3b, v131
	s_and_b64 s[30:31], s[74:75], vcc
	v_cmp_gt_u32_e32 vcc, s39, v117
	v_add_u32_e32 v117, 0x50, v166
	v_max3_f32 v70, v68, s68, v69
	v_cndmask_b32_e64 v71, v71, v181, s[16:17]
	v_cndmask_b32_e64 v72, v72, v181, s[18:19]
	v_mul_f32_e32 v74, 0x3e38aa3b, v132
	v_mul_f32_e32 v75, 0x3e38aa3b, v133
	s_and_b64 s[34:35], s[74:75], vcc
	v_cmp_gt_u32_e32 vcc, s39, v117
	v_add_u32_e32 v117, 0x43, v166
	v_max3_f32 v70, v70, v71, v72
	v_cndmask_b32_e64 v74, v74, v181, s[20:21]
	v_cndmask_b32_e64 v75, v75, v181, s[22:23]
	v_mul_f32_e32 v106, 0x3e38aa3b, v134
	v_mul_f32_e32 v116, 0x3e38aa3b, v135
	s_and_b64 s[36:37], s[74:75], vcc
	v_cmp_gt_u32_e32 vcc, s39, v117
	v_add_u32_e32 v117, 0x42, v166
	v_max3_f32 v70, v70, v74, v75
	v_cndmask_b32_e64 v106, v106, v181, s[24:25]
	v_cndmask_b32_e64 v116, v116, v181, s[26:27]
	v_mul_f32_e32 v108, 0x3e38aa3b, v108
	v_mul_f32_e32 v109, 0x3e38aa3b, v109
	v_cmp_gt_u32_e64 s[6:7], s39, v117
	v_add_u32_e32 v117, 0x41, v166
	v_max3_f32 v70, v70, v106, v116
	v_cndmask_b32_e64 v108, v108, v181, s[28:29]
	v_cndmask_b32_e64 v109, v109, v181, s[30:31]
	v_mul_f32_e32 v110, 0x3e38aa3b, v110
	v_mul_f32_e32 v111, 0x3e38aa3b, v111
	v_cmp_gt_u32_e64 s[8:9], s39, v117
	v_add_u32_e32 v117, 64, v166
	v_max3_f32 v70, v70, v108, v109
	v_cndmask_b32_e64 v110, v110, v181, s[34:35]
	v_cndmask_b32_e64 v111, v111, v181, s[36:37]
	v_mul_f32_e32 v112, 0x3e38aa3b, v112
	s_and_b64 vcc, s[74:75], vcc
	v_mul_f32_e32 v113, 0x3e38aa3b, v113
	s_and_b64 s[6:7], s[74:75], s[6:7]
	v_cmp_gt_u32_e64 s[10:11], s39, v117
	v_max3_f32 v70, v70, v110, v111
	v_cndmask_b32_e32 v112, v112, v181, vcc
	v_cndmask_b32_e64 v113, v113, v181, s[6:7]
	v_mul_f32_e32 v114, 0x3e38aa3b, v114
	s_and_b64 s[8:9], s[74:75], s[8:9]
	v_mul_f32_e32 v115, 0x3e38aa3b, v115
	s_and_b64 s[10:11], s[74:75], s[10:11]
	v_max3_f32 v70, v70, v112, v113
	v_cndmask_b32_e64 v114, v114, v181, s[8:9]
	v_cndmask_b32_e64 v118, v115, v181, s[10:11]
	v_max3_f32 v70, v70, v114, v118
	v_mov_b32_e32 v115, v70
	s_nop 1
	v_permlane16_swap_b32_e32 v70, v115
	v_max_f32_e32 v70, v70, v115
	v_mov_b32_e32 v115, v70
	s_nop 1
	v_permlane32_swap_b32_e32 v70, v115
	v_max3_f32 v140, v73, v70, v115
	v_sub_f32_e32 v68, v68, v140
	v_exp_f32_e32 v139, v68
	v_sub_f32_e32 v68, v69, v140
	v_exp_f32_e32 v137, v68
	v_sub_f32_e32 v68, v71, v140
	v_exp_f32_e32 v135, v68
	v_sub_f32_e32 v68, v72, v140
	v_exp_f32_e32 v133, v68
	v_sub_f32_e32 v68, v74, v140
	v_exp_f32_e32 v131, v68
	v_sub_f32_e32 v68, v75, v140
	v_exp_f32_e32 v129, v68
	v_sub_f32_e32 v68, v106, v140
	v_exp_f32_e32 v127, v68
	v_sub_f32_e32 v68, v116, v140
	v_exp_f32_e32 v125, v68
	v_sub_f32_e32 v68, v108, v140
	v_add_u32_e32 v108, 0x83, v166
	v_cmp_gt_u32_e64 s[40:41], s39, v108
	v_mul_f32_e32 v76, 0x3e38aa3b, v76
	s_and_b64 s[40:41], s[74:75], s[40:41]
	v_add_u32_e32 v108, 0x82, v166
	v_exp_f32_e32 v123, v68
	v_sub_f32_e32 v68, v109, v140
	v_cndmask_b32_e64 v76, v76, v181, s[40:41]
	v_cmp_gt_u32_e64 s[40:41], s39, v108
	v_exp_f32_e32 v121, v68
	v_sub_f32_e32 v68, v110, v140
	v_mul_f32_e32 v77, 0x3e38aa3b, v77
	s_and_b64 s[40:41], s[74:75], s[40:41]
	v_add_u32_e32 v110, 0x81, v166
	v_cndmask_b32_e64 v77, v77, v181, s[40:41]
	v_cmp_gt_u32_e64 s[40:41], s39, v110
	v_mul_f32_e32 v78, 0x3e38aa3b, v78
	s_and_b64 s[40:41], s[74:75], s[40:41]
	v_cndmask_b32_e64 v110, v78, v181, s[40:41]
	v_mul_f32_e32 v78, 0x3e38aa3b, v79
	v_add_u32_e32 v79, 0x80, v166
	v_cmp_gt_u32_e64 s[40:41], s39, v79
	s_and_b64 s[40:41], s[74:75], s[40:41]
	v_max3_f32 v108, v76, s68, v77
	v_cndmask_b32_e64 v79, v78, v181, s[40:41]
	v_mul_f32_e32 v80, 0x3e38aa3b, v80
	v_mul_f32_e32 v81, 0x3e38aa3b, v81
	v_exp_f32_e32 v119, v68
	v_sub_f32_e32 v68, v111, v140
	v_max3_f32 v78, v108, v110, v79
	v_cndmask_b32_e64 v80, v80, v181, s[12:13]
	v_cndmask_b32_e64 v81, v81, v181, s[14:15]
	v_mul_f32_e32 v82, 0x3e38aa3b, v82
	v_mul_f32_e32 v83, 0x3e38aa3b, v83
	v_exp_f32_e32 v115, v68
	v_sub_f32_e32 v68, v112, v140
	v_max3_f32 v78, v78, v80, v81
	v_cndmask_b32_e64 v82, v82, v181, s[16:17]
	v_cndmask_b32_e64 v83, v83, v181, s[18:19]
	v_mul_f32_e32 v84, 0x3e38aa3b, v84
	v_mul_f32_e32 v85, 0x3e38aa3b, v85
	v_exp_f32_e32 v111, v68
	v_sub_f32_e32 v68, v113, v140
	v_max3_f32 v78, v78, v82, v83
	v_cndmask_b32_e64 v84, v84, v181, s[20:21]
	v_cndmask_b32_e64 v85, v85, v181, s[22:23]
	v_mul_f32_e32 v86, 0x3e38aa3b, v86
	v_mul_f32_e32 v87, 0x3e38aa3b, v87
	v_exp_f32_e32 v109, v68
	v_sub_f32_e32 v68, v114, v140
	v_max3_f32 v78, v78, v84, v85
	v_cndmask_b32_e64 v86, v86, v181, s[24:25]
	v_cndmask_b32_e64 v87, v87, v181, s[26:27]
	v_mul_f32_e32 v108, 0x3e38aa3b, v142
	v_mul_f32_e32 v112, 0x3e38aa3b, v143
	v_mul_f32_e32 v114, 0x3e38aa3b, v144
	v_max3_f32 v78, v78, v86, v87
	v_cndmask_b32_e64 v108, v108, v181, s[28:29]
	v_cndmask_b32_e64 v112, v112, v181, s[30:31]
	v_cndmask_b32_e64 v116, v114, v181, s[34:35]
	v_mul_f32_e32 v114, 0x3e38aa3b, v145
	v_max3_f32 v78, v78, v108, v112
	v_cndmask_b32_e64 v141, v114, v181, s[36:37]
	v_max3_f32 v78, v78, v116, v141
	v_mov_b32_e32 v114, v78
	s_nop 1
	v_permlane16_swap_b32_e32 v78, v114
	v_max_f32_e32 v78, v78, v114
	v_mov_b32_e32 v114, v78
	s_nop 1
	v_permlane32_swap_b32_e32 v78, v114
	v_max3_f32 v78, v167, v78, v114
	v_sub_f32_e32 v76, v76, v78
	v_exp_f32_e32 v138, v76
	v_sub_f32_e32 v76, v77, v78
	v_exp_f32_e32 v136, v76
	v_sub_f32_e32 v76, v110, v78
	v_exp_f32_e32 v134, v76
	v_sub_f32_e32 v76, v79, v78
	v_exp_f32_e32 v132, v76
	v_sub_f32_e32 v76, v80, v78
	v_exp_f32_e32 v130, v76
	v_sub_f32_e32 v76, v81, v78
	v_exp_f32_e32 v128, v76
	v_sub_f32_e32 v76, v82, v78
	v_exp_f32_e32 v126, v76
	v_sub_f32_e32 v76, v83, v78
	v_exp_f32_e32 v124, v76
	v_sub_f32_e32 v76, v84, v78
	v_exp_f32_e32 v122, v76
	v_sub_f32_e32 v76, v85, v78
	v_exp_f32_e32 v120, v76
	v_sub_f32_e32 v76, v86, v78
	v_exp_f32_e32 v117, v68
	v_sub_f32_e32 v68, v118, v140
	v_exp_f32_e32 v118, v76
	v_sub_f32_e32 v76, v87, v78
	v_exp_f32_e32 v114, v76
	v_sub_f32_e32 v76, v108, v78
	v_sub_f32_e32 v77, v116, v78
	v_sub_f32_e32 v70, v73, v140
	v_sub_f32_e32 v142, v167, v78
	v_exp_f32_e32 v110, v76
	v_sub_f32_e32 v76, v112, v78
	v_exp_f32_e32 v116, v77
	v_sub_f32_e32 v77, v141, v78
	v_exp_f32_e32 v106, v70
	v_exp_f32_e32 v113, v68
	v_exp_f32_e32 v108, v76
	v_exp_f32_e32 v76, v142
	v_exp_f32_e32 v112, v77
	v_mul_f32 v58, v58, v106
	v_mul_f32 v59, v59, v106
	v_mul_f32 v56, v56, v106
	v_mul_f32 v57, v57, v106
	v_mul_f32 v54, v54, v106
	v_mul_f32 v55, v55, v106
	v_mul_f32 v52, v52, v106
	v_mul_f32 v53, v53, v106
	v_mul_f32 v62, v62, v106
	v_mul_f32 v63, v63, v106
	v_mul_f32 v60, v60, v106
	v_mul_f32 v61, v61, v106
	v_mul_f32 v70, v66, v106
	v_mul_f32 v71, v67, v106
	v_mul_f32 v68, v64, v106
	v_mul_f32 v69, v65, v106
	v_cvt_pk_bf16_f32 v72, v139, v137
	v_cvt_pk_bf16_f32 v73, v135, v133
	v_cvt_pk_bf16_f32 v74, v131, v129
	v_cvt_pk_bf16_f32 v75, v127, v125
	v_cvt_pk_bf16_f32 v64, v123, v121
	v_cvt_pk_bf16_f32 v65, v119, v115
	v_cvt_pk_bf16_f32 v66, v111, v109
	v_cvt_pk_bf16_f32 v67, v117, v113
	v_mul_f32 v42, v42, v76
	v_mul_f32 v43, v43, v76
	v_mul_f32 v40, v40, v76
	v_mul_f32 v41, v41, v76
	v_mul_f32 v38, v38, v76
	v_mul_f32 v39, v39, v76
	v_mul_f32 v36, v36, v76
	v_mul_f32 v37, v37, v76
	v_mul_f32 v46, v46, v76
	v_mul_f32 v47, v47, v76
	v_mul_f32 v44, v44, v76
	v_mul_f32 v45, v45, v76
	v_mul_f32 v50, v50, v76
	v_mul_f32 v51, v51, v76
	v_mul_f32 v48, v48, v76
	v_mul_f32 v49, v49, v76
	v_cvt_pk_bf16_f32 v80, v138, v136
	v_cvt_pk_bf16_f32 v81, v134, v132
	v_cvt_pk_bf16_f32 v82, v130, v128
	v_cvt_pk_bf16_f32 v83, v126, v124
	v_cvt_pk_bf16_f32 v84, v122, v120
	v_cvt_pk_bf16_f32 v85, v118, v114
	v_cvt_pk_bf16_f32 v86, v110, v108
	v_cvt_pk_bf16_f32 v87, v116, v112
	s_setprio 1
	v_add3_u32 v77, s83, v164, v165
	ds_read_b64_tr_b16 v[206:207], v77 offset:20992
	ds_read_b64_tr_b16 v[204:205], v77 offset:18432
	ds_read_b64_tr_b16 v[208:209], v77 offset:18464
	ds_read_b64_tr_b16 v[210:211], v77 offset:21024
	ds_read_b64_tr_b16 v[212:213], v77 offset:23552
	ds_read_b64_tr_b16 v[214:215], v77 offset:26112
	ds_read_b64_tr_b16 v[216:217], v77 offset:23584
	ds_read_b64_tr_b16 v[218:219], v77 offset:26144
	ds_read_b64_tr_b16 v[220:221], v77 offset:18496
	ds_read_b64_tr_b16 v[222:223], v77 offset:21056
	ds_read_b64_tr_b16 v[224:225], v77 offset:23616
	ds_read_b64_tr_b16 v[226:227], v77 offset:26176
	ds_read_b64_tr_b16 v[228:229], v77 offset:18528
	ds_read_b64_tr_b16 v[230:231], v77 offset:21088
	ds_read_b64_tr_b16 v[232:233], v77 offset:23648
	ds_read_b64_tr_b16 v[234:235], v77 offset:26208
	s_waitcnt lgkmcnt(14)
	v_mfma_f32_16x16x32_bf16 v[56:59], v[204:207], v[72:75], v[56:59]
	v_mfma_f32_16x16x32_bf16 v[40:43], v[204:207], v[80:83], v[40:43]
	s_waitcnt lgkmcnt(10)
	v_mfma_f32_16x16x32_bf16 v[56:59], v[212:215], v[64:67], v[56:59]
	v_mfma_f32_16x16x32_bf16 v[40:43], v[212:215], v[84:87], v[40:43]
	v_mfma_f32_16x16x32_bf16 v[52:55], v[208:211], v[72:75], v[52:55]
	v_mfma_f32_16x16x32_bf16 v[36:39], v[208:211], v[80:83], v[36:39]
	s_waitcnt lgkmcnt(8)
	v_mfma_f32_16x16x32_bf16 v[52:55], v[216:219], v[64:67], v[52:55]
	v_mfma_f32_16x16x32_bf16 v[36:39], v[216:219], v[84:87], v[36:39]
	s_waitcnt lgkmcnt(6)
	v_mfma_f32_16x16x32_bf16 v[60:63], v[220:223], v[72:75], v[60:63]
	v_mfma_f32_16x16x32_bf16 v[44:47], v[220:223], v[80:83], v[44:47]
	s_waitcnt lgkmcnt(4)
	v_mfma_f32_16x16x32_bf16 v[60:63], v[224:227], v[64:67], v[60:63]
	v_mfma_f32_16x16x32_bf16 v[44:47], v[224:227], v[84:87], v[44:47]
	s_waitcnt lgkmcnt(2)
	v_mfma_f32_16x16x32_bf16 v[68:71], v[228:231], v[72:75], v[68:71]
	v_mfma_f32_16x16x32_bf16 v[48:51], v[228:231], v[80:83], v[48:51]
	s_waitcnt lgkmcnt(0)
	v_mfma_f32_16x16x32_bf16 v[64:67], v[232:235], v[64:67], v[68:71]
	v_mfma_f32_16x16x32_bf16 v[48:51], v[232:235], v[84:87], v[48:51]
	s_nop 3
	s_setprio 0
	s_setprio 1
	ds_read_b128 v[204:207], v88 offset:9216
	ds_read_b128 v[208:211], v88 offset:9280
	ds_read_b128 v[212:215], v88 offset:11520
	ds_read_b128 v[216:219], v88 offset:13824
	ds_read_b128 v[220:223], v88 offset:16128
	ds_read_b128 v[224:227], v88 offset:11584
	ds_read_b128 v[228:231], v88 offset:13888
	ds_read_b128 v[232:235], v88 offset:16192
	s_waitcnt lgkmcnt(7)
	v_mfma_f32_16x16x32_bf16 v[72:75], v[204:207], v[4:7], v[0:3]
	v_mfma_f32_16x16x32_bf16 v[68:71], v[204:207], v[12:15], v[0:3]
	s_waitcnt lgkmcnt(6)
	v_mfma_f32_16x16x32_bf16 v[168:171], v[208:211], v[16:19], v[68:71]
	v_mfma_f32_16x16x32_bf16 v[72:75], v[208:211], v[8:11], v[72:75]
	s_waitcnt lgkmcnt(5)
	v_mfma_f32_16x16x32_bf16 v[84:87], v[212:215], v[4:7], v[0:3]
	v_mfma_f32_16x16x32_bf16 v[80:83], v[212:215], v[12:15], v[0:3]
	s_waitcnt lgkmcnt(2)
	v_mfma_f32_16x16x32_bf16 v[84:87], v[224:227], v[8:11], v[84:87]
	v_mfma_f32_16x16x32_bf16 v[184:187], v[224:227], v[16:19], v[80:83]
	v_mfma_f32_16x16x32_bf16 v[146:149], v[216:219], v[4:7], v[0:3]
	v_mfma_f32_16x16x32_bf16 v[142:145], v[216:219], v[12:15], v[0:3]
	s_waitcnt lgkmcnt(1)
	v_mfma_f32_16x16x32_bf16 v[80:83], v[228:231], v[8:11], v[146:149]
	v_mfma_f32_16x16x32_bf16 v[188:191], v[228:231], v[16:19], v[142:145]
	v_mfma_f32_16x16x32_bf16 v[154:157], v[220:223], v[4:7], v[0:3]
	v_mfma_f32_16x16x32_bf16 v[150:153], v[220:223], v[12:15], v[0:3]
	s_waitcnt lgkmcnt(0)
	v_mfma_f32_16x16x32_bf16 v[142:145], v[232:235], v[8:11], v[154:157]
	v_mfma_f32_16x16x32_bf16 v[192:195], v[232:235], v[16:19], v[150:153]
	s_nop 0
	s_setprio 0
	v_mul_f32_e32 v68, 0x3e38aa3b, v72
	v_add_u32_e32 v69, 51, v166
	v_mul_f32_e32 v71, 0x3e38aa3b, v74
	v_add_u32_e32 v72, 49, v166
	v_add_u32_e32 v74, 35, v166
	v_cmp_gt_u32_e64 s[12:13], s39, v69
	v_mul_f32_e32 v69, 0x3e38aa3b, v73
	v_cmp_gt_u32_e64 s[16:17], s39, v72
	v_mul_f32_e32 v72, 0x3e38aa3b, v75
	v_add_u32_e32 v73, 48, v166
	v_cmp_gt_u32_e64 s[20:21], s39, v74
	v_add_u32_e32 v75, 34, v166
	v_cmp_gt_u32_e64 s[18:19], s39, v73
	v_mul_f32_e32 v73, 0x3e38aa3b, v84
	s_and_b64 s[20:21], s[74:75], s[20:21]
	v_cmp_gt_u32_e64 s[22:23], s39, v75
	v_add_u32_e32 v79, 33, v166
	v_cndmask_b32_e64 v74, v73, v181, s[20:21]
	v_mul_f32_e32 v73, 0x3e38aa3b, v85
	s_and_b64 s[22:23], s[74:75], s[22:23]
	v_cmp_gt_u32_e64 s[24:25], s39, v79
	v_add_u32_e32 v84, 32, v166
	v_cndmask_b32_e64 v75, v73, v181, s[22:23]
	v_mul_f32_e32 v73, 0x3e38aa3b, v86
	s_and_b64 s[24:25], s[74:75], s[24:25]
	v_cmp_gt_u32_e64 s[26:27], s39, v84
	v_cndmask_b32_e64 v79, v73, v181, s[24:25]
	v_mul_f32_e32 v73, 0x3e38aa3b, v87
	s_and_b64 s[26:27], s[74:75], s[26:27]
	v_cndmask_b32_e64 v84, v73, v181, s[26:27]
	v_mul_f32_e32 v73, 0x3e38aa3b, v80
	v_add_u32_e32 v80, 19, v166
	v_cmp_gt_u32_e64 s[28:29], s39, v80
	s_and_b64 s[28:29], s[74:75], s[28:29]
	v_add_u32_e32 v70, 50, v166
	v_cndmask_b32_e64 v80, v73, v181, s[28:29]
	v_mul_f32_e32 v73, 0x3e38aa3b, v81
	v_add_u32_e32 v81, 18, v166
	v_cmp_gt_u32_e64 s[30:31], s39, v81
	s_and_b64 s[30:31], s[74:75], s[30:31]
	v_cmp_gt_u32_e64 s[14:15], s39, v70
	v_cndmask_b32_e64 v81, v73, v181, s[30:31]
	v_mul_f32_e32 v73, 0x3e38aa3b, v82
	v_add_u32_e32 v82, 17, v166
	v_cmp_gt_u32_e64 s[34:35], s39, v82
	s_and_b64 s[34:35], s[74:75], s[34:35]
	v_add_u32_e32 v85, 3, v166
	v_cndmask_b32_e64 v82, v73, v181, s[34:35]
	v_mul_f32_e32 v73, 0x3e38aa3b, v83
	v_add_u32_e32 v83, 16, v166
	v_cmp_gt_u32_e64 s[36:37], s39, v83
	s_and_b64 s[12:13], s[74:75], s[12:13]
	s_and_b64 s[14:15], s[74:75], s[14:15]
	s_and_b64 s[36:37], s[74:75], s[36:37]
	v_cmp_gt_u32_e64 s[40:41], s39, v85
	v_cndmask_b32_e64 v68, v68, v181, s[12:13]
	v_cndmask_b32_e64 v69, v69, v181, s[14:15]
	s_and_b64 s[16:17], s[74:75], s[16:17]
	s_and_b64 s[18:19], s[74:75], s[18:19]
	v_cndmask_b32_e64 v83, v73, v181, s[36:37]
	v_mul_f32_e32 v73, 0x3e38aa3b, v142
	s_and_b64 s[40:41], s[74:75], s[40:41]
	v_add_u32_e32 v86, 2, v166
	v_max3_f32 v70, v68, s68, v69
	v_cndmask_b32_e64 v71, v71, v181, s[16:17]
	v_cndmask_b32_e64 v72, v72, v181, s[18:19]
	v_cndmask_b32_e64 v85, v73, v181, s[40:41]
	v_cmp_gt_u32_e64 s[40:41], s39, v86
	v_max3_f32 v70, v70, v71, v72
	v_mul_f32_e32 v73, 0x3e38aa3b, v143
	s_and_b64 s[40:41], s[74:75], s[40:41]
	v_add_u32_e32 v87, 1, v166
	v_max3_f32 v70, v70, v74, v75
	v_cndmask_b32_e64 v86, v73, v181, s[40:41]
	v_cmp_gt_u32_e64 s[40:41], s39, v87
	v_max3_f32 v70, v70, v79, v84
	v_mul_f32_e32 v73, 0x3e38aa3b, v144
	s_and_b64 s[40:41], s[74:75], s[40:41]
	v_max3_f32 v70, v70, v80, v81
	v_cndmask_b32_e64 v88, v73, v181, s[40:41]
	v_cmp_gt_u32_e64 s[40:41], s39, v166
	v_max3_f32 v70, v70, v82, v83
	v_mul_f32_e32 v73, 0x3e38aa3b, v145
	s_and_b64 s[40:41], s[74:75], s[40:41]
	v_max3_f32 v70, v70, v85, v86
	v_cndmask_b32_e64 v142, v73, v181, s[40:41]
	v_max3_f32 v70, v70, v88, v142
	v_mov_b32_e32 v73, v70
	s_nop 1
	v_permlane16_swap_b32_e32 v70, v73
	v_max_f32_e32 v70, v70, v73
	v_mov_b32_e32 v73, v70
	s_nop 1
	v_permlane32_swap_b32_e32 v70, v73
	v_max3_f32 v73, v140, v70, v73
	v_sub_f32_e32 v68, v68, v73
	v_exp_f32_e32 v159, v68
	v_sub_f32_e32 v68, v69, v73
	v_exp_f32_e32 v157, v68
	v_sub_f32_e32 v68, v71, v73
	v_exp_f32_e32 v155, v68
	v_sub_f32_e32 v68, v72, v73
	v_exp_f32_e32 v153, v68
	v_sub_f32_e32 v68, v74, v73
	v_exp_f32_e32 v151, v68
	v_sub_f32_e32 v68, v75, v73
	v_exp_f32_e32 v149, v68
	v_sub_f32_e32 v68, v79, v73
	v_exp_f32_e32 v147, v68
	v_sub_f32_e32 v68, v84, v73
	v_exp_f32_e32 v145, v68
	v_sub_f32_e32 v68, v80, v73
	v_exp_f32_e32 v143, v68
	v_sub_f32_e32 v68, v81, v73
	v_exp_f32_e32 v141, v68
	v_sub_f32_e32 v68, v82, v73
	v_sub_f32_e32 v70, v140, v73
	v_exp_f32_e32 v87, v68
	v_sub_f32_e32 v68, v83, v73
	v_exp_f32_e32 v83, v68
	v_sub_f32_e32 v68, v85, v73
	v_exp_f32_e32 v72, v70
	v_exp_f32_e32 v79, v68
	v_sub_f32_e32 v68, v86, v73
	v_exp_f32_e32 v75, v68
	v_sub_f32_e32 v68, v88, v73
	v_exp_f32_e32 v85, v68
	v_sub_f32_e32 v68, v142, v73
	v_exp_f32_e32 v81, v68
	v_mul_f32 v68, v64, v72
	v_mul_f32 v69, v65, v72
	v_mul_f32_e32 v64, 0x3e38aa3b, v168
	v_cndmask_b32_e32 v74, v64, v181, vcc
	v_mul_f32_e32 v64, 0x3e38aa3b, v169
	v_cndmask_b32_e64 v80, v64, v181, s[6:7]
	v_mul_f32_e32 v64, 0x3e38aa3b, v170
	v_cndmask_b32_e64 v82, v64, v181, s[8:9]
	v_mul_f32_e32 v64, 0x3e38aa3b, v171
	v_cndmask_b32_e64 v84, v64, v181, s[10:11]
	v_mul_f32_e32 v64, 0x3e38aa3b, v184
	v_cndmask_b32_e64 v86, v64, v181, s[12:13]
	v_mul_f32_e32 v64, 0x3e38aa3b, v185
	v_cndmask_b32_e64 v88, v64, v181, s[14:15]
	v_mul_f32_e32 v64, 0x3e38aa3b, v186
	v_cndmask_b32_e64 v140, v64, v181, s[16:17]
	v_mul_f32_e32 v64, 0x3e38aa3b, v187
	v_cndmask_b32_e64 v142, v64, v181, s[18:19]
	v_mul_f32_e32 v64, 0x3e38aa3b, v188
	v_cndmask_b32_e64 v160, v64, v181, s[20:21]
	v_mul_f32_e32 v64, 0x3e38aa3b, v189
	v_cndmask_b32_e64 v161, v64, v181, s[22:23]
	v_mul_f32_e32 v64, 0x3e38aa3b, v190
	v_cndmask_b32_e64 v172, v64, v181, s[24:25]
	v_mul_f32_e32 v64, 0x3e38aa3b, v191
	v_cndmask_b32_e64 v173, v64, v181, s[26:27]
	v_mul_f32_e32 v64, 0x3e38aa3b, v192
	v_cndmask_b32_e64 v184, v64, v181, s[28:29]
	v_mul_f32_e32 v64, 0x3e38aa3b, v193
	v_cndmask_b32_e64 v185, v64, v181, s[30:31]
	v_mul_f32_e32 v64, 0x3e38aa3b, v194
	v_cndmask_b32_e64 v186, v64, v181, s[34:35]
	v_mul_f32_e32 v64, 0x3e38aa3b, v195
	v_cndmask_b32_e64 v187, v64, v181, s[36:37]
	v_max3_f32 v64, v74, s68, v80
	v_max3_f32 v64, v64, v82, v84
	v_max3_f32 v64, v64, v86, v88
	v_max3_f32 v64, v64, v140, v142
	v_max3_f32 v64, v64, v160, v161
	v_max3_f32 v64, v64, v172, v173
	v_max3_f32 v144, v64, v184, v185
	v_max3_f32 v144, v144, v186, v187
	v_mov_b32_e32 v146, v144
	s_nop 1
	v_permlane16_swap_b32_e32 v144, v146
	v_max_f32_e32 v144, v144, v146
	v_mov_b32_e32 v146, v144
	s_nop 1
	v_permlane32_swap_b32_e32 v144, v146
	v_max3_f32 v167, v78, v144, v146
	v_sub_f32_e32 v74, v74, v167
	v_exp_f32_e32 v158, v74
	v_sub_f32_e32 v74, v80, v167
	v_exp_f32_e32 v156, v74
	v_sub_f32_e32 v74, v82, v167
	v_exp_f32_e32 v154, v74
	v_sub_f32_e32 v74, v84, v167
	v_exp_f32_e32 v152, v74
	v_sub_f32_e32 v74, v86, v167
	v_exp_f32_e32 v150, v74
	v_sub_f32_e32 v74, v88, v167
	v_exp_f32_e32 v148, v74
	v_sub_f32_e32 v74, v140, v167
	v_exp_f32_e32 v146, v74
	v_sub_f32_e32 v74, v142, v167
	v_exp_f32_e32 v144, v74
	v_sub_f32_e32 v74, v160, v167
	v_exp_f32_e32 v142, v74
	v_sub_f32_e32 v74, v161, v167
	v_exp_f32_e32 v140, v74
	v_sub_f32_e32 v74, v172, v167
	v_exp_f32_e32 v86, v74
	v_sub_f32_e32 v74, v173, v167
	v_sub_f32_e32 v188, v78, v167
	v_exp_f32_e32 v82, v74
	v_sub_f32_e32 v74, v184, v167
	v_sub_f32_e32 v80, v186, v167
	v_exp_f32_e32 v78, v74
	v_sub_f32_e32 v74, v185, v167
	v_exp_f32_e32 v160, v188
	v_exp_f32_e32 v84, v80
	v_sub_f32_e32 v80, v187, v167
	v_exp_f32_e32 v74, v74
	v_exp_f32_e32 v80, v80
	v_mul_f32 v58, v58, v72
	v_mul_f32 v59, v59, v72
	v_mul_f32 v56, v56, v72
	v_mul_f32 v57, v57, v72
	v_mul_f32 v54, v54, v72
	v_mul_f32 v55, v55, v72
	v_mul_f32 v52, v52, v72
	v_mul_f32 v53, v53, v72
	v_mul_f32 v62, v62, v72
	v_mul_f32 v63, v63, v72
	v_mul_f32 v60, v60, v72
	v_mul_f32 v61, v61, v72
	v_mul_f32 v70, v66, v72
	v_mul_f32 v71, v67, v72
	v_cvt_pk_bf16_f32 v64, v143, v141
	v_cvt_pk_bf16_f32 v65, v87, v83
	v_cvt_pk_bf16_f32 v66, v79, v75
	v_cvt_pk_bf16_f32 v67, v85, v81
	v_mul_f32 v42, v42, v160
	v_mul_f32 v43, v43, v160
	v_mul_f32 v40, v40, v160
	v_mul_f32 v41, v41, v160
	v_mul_f32 v38, v38, v160
	v_mul_f32 v39, v39, v160
	v_mul_f32 v36, v36, v160
	v_mul_f32 v37, v37, v160
	v_mul_f32 v46, v46, v160
	v_mul_f32 v47, v47, v160
	v_mul_f32 v44, v44, v160
	v_mul_f32 v45, v45, v160
	v_mul_f32 v50, v50, v160
	v_mul_f32 v51, v51, v160
	v_mul_f32 v48, v48, v160
	v_mul_f32 v49, v49, v160
	v_cvt_pk_bf16_f32 v168, v159, v157
	v_cvt_pk_bf16_f32 v169, v155, v153
	v_cvt_pk_bf16_f32 v170, v151, v149
	v_cvt_pk_bf16_f32 v171, v147, v145
	v_cvt_pk_bf16_f32 v184, v158, v156
	v_cvt_pk_bf16_f32 v185, v154, v152
	v_cvt_pk_bf16_f32 v186, v150, v148
	v_cvt_pk_bf16_f32 v187, v146, v144
	v_cvt_pk_bf16_f32 v188, v142, v140
	v_cvt_pk_bf16_f32 v189, v86, v82
	v_cvt_pk_bf16_f32 v190, v78, v74
	v_cvt_pk_bf16_f32 v191, v84, v80
	s_setprio 1
	ds_read_b64_tr_b16 v[206:207], v77 offset:31232
	ds_read_b64_tr_b16 v[204:205], v77 offset:28672
	ds_read_b64_tr_b16 v[208:209], v77 offset:28704
	ds_read_b64_tr_b16 v[210:211], v77 offset:31264
	ds_read_b64_tr_b16 v[212:213], v77 offset:33792
	ds_read_b64_tr_b16 v[214:215], v77 offset:36352
	ds_read_b64_tr_b16 v[216:217], v77 offset:33824
	ds_read_b64_tr_b16 v[218:219], v77 offset:36384
	ds_read_b64_tr_b16 v[220:221], v77 offset:28736
	ds_read_b64_tr_b16 v[222:223], v77 offset:31296
	ds_read_b64_tr_b16 v[224:225], v77 offset:33856
	ds_read_b64_tr_b16 v[226:227], v77 offset:36416
	ds_read_b64_tr_b16 v[228:229], v77 offset:28768
	ds_read_b64_tr_b16 v[230:231], v77 offset:31328
	ds_read_b64_tr_b16 v[232:233], v77 offset:33888
	ds_read_b64_tr_b16 v[234:235], v77 offset:36448
	s_waitcnt lgkmcnt(14)
	v_mfma_f32_16x16x32_bf16 v[56:59], v[204:207], v[168:171], v[56:59]
	v_mfma_f32_16x16x32_bf16 v[40:43], v[204:207], v[184:187], v[40:43]
	s_waitcnt lgkmcnt(10)
	v_mfma_f32_16x16x32_bf16 v[56:59], v[212:215], v[64:67], v[56:59]
	v_mfma_f32_16x16x32_bf16 v[40:43], v[212:215], v[188:191], v[40:43]
	v_mfma_f32_16x16x32_bf16 v[52:55], v[208:211], v[168:171], v[52:55]
	v_mfma_f32_16x16x32_bf16 v[36:39], v[208:211], v[184:187], v[36:39]
	s_waitcnt lgkmcnt(8)
	v_mfma_f32_16x16x32_bf16 v[52:55], v[216:219], v[64:67], v[52:55]
	v_mfma_f32_16x16x32_bf16 v[36:39], v[216:219], v[188:191], v[36:39]
	s_waitcnt lgkmcnt(6)
	v_mfma_f32_16x16x32_bf16 v[60:63], v[220:223], v[168:171], v[60:63]
	v_mfma_f32_16x16x32_bf16 v[44:47], v[220:223], v[184:187], v[44:47]
	s_waitcnt lgkmcnt(4)
	v_mfma_f32_16x16x32_bf16 v[60:63], v[224:227], v[64:67], v[60:63]
	v_mfma_f32_16x16x32_bf16 v[44:47], v[224:227], v[188:191], v[44:47]
	s_waitcnt lgkmcnt(2)
	v_mfma_f32_16x16x32_bf16 v[68:71], v[228:231], v[168:171], v[68:71]
	v_mfma_f32_16x16x32_bf16 v[48:51], v[228:231], v[184:187], v[48:51]
	s_waitcnt lgkmcnt(0)
	v_mfma_f32_16x16x32_bf16 v[64:67], v[232:235], v[64:67], v[68:71]
	v_mfma_f32_16x16x32_bf16 v[48:51], v[232:235], v[188:191], v[48:51]
	s_nop 3
	s_setprio 0
	s_add_i32 s12, s82, 1
	s_cmp_ge_i32 s12, s44
	s_cbranch_scc1 .LBB0_3060
	s_bitcmp1_b32 s12, 0
	s_cselect_b32 s6, 0x9800, 0
	v_add3_u32 v71, s6, v99, v98
	v_add3_u32 v68, s6, v162, v98
	v_add3_u32 v69, s6, v107, v98
	v_add3_u32 v70, s6, v105, v98
	s_waitcnt vmcnt(0)
	ds_write_b128 v71, v[20:23]
	ds_write_b128 v70, v[24:27]
	ds_write_b128 v69, v[28:31] offset:18432
	ds_write_b128 v68, v[32:35] offset:18432

.LBB0_3065:
	v_add_f32 v68, v138, 0
	v_add_f32 v69, v139, 0
	v_add_f32 v70, v158, 0
	v_add_f32 v71, v159, 0
	v_add_f32 v68, v136, v68
	v_add_f32 v69, v137, v69
	v_add_f32 v70, v156, v70
	v_add_f32 v71, v157, v71
	v_add_f32 v68, v134, v68
	v_add_f32 v69, v135, v69
	v_add_f32 v70, v154, v70
	v_add_f32 v71, v155, v71
	v_add_f32 v68, v132, v68
	v_add_f32 v69, v133, v69
	v_add_f32 v70, v152, v70
	v_add_f32 v71, v153, v71
	v_add_f32 v68, v130, v68
	v_add_f32 v69, v131, v69
	v_add_f32 v70, v150, v70
	v_add_f32 v71, v151, v71
	v_add_f32 v68, v128, v68
	v_add_f32 v69, v129, v69
	v_add_f32 v70, v148, v70
	v_add_f32 v71, v149, v71
	v_add_f32 v68, v126, v68
	v_add_f32 v69, v127, v69
	v_add_f32 v70, v146, v70
	v_add_f32 v71, v147, v71
	v_add_f32 v68, v124, v68
	v_add_f32 v69, v125, v69
	v_add_f32 v70, v144, v70
	v_add_f32 v71, v145, v71
	v_add_f32 v68, v122, v68
	v_add_f32 v69, v123, v69
	v_add_f32 v70, v142, v70
	v_add_f32 v71, v143, v71
	v_add_f32 v68, v120, v68
	v_add_f32 v69, v121, v69
	v_add_f32 v70, v140, v70
	v_add_f32 v71, v141, v71
	v_add_f32 v68, v118, v68
	v_add_f32 v69, v119, v69
	v_add_f32 v70, v86, v70
	v_add_f32 v71, v87, v71
	v_add_f32 v68, v114, v68
	v_add_f32 v69, v115, v69
	v_add_f32 v70, v82, v70
	v_add_f32 v71, v83, v71
	v_add_f32 v68, v110, v68
	v_add_f32 v69, v111, v69
	v_add_f32 v70, v78, v70
	v_add_f32 v71, v79, v71
	v_add_f32 v68, v108, v68
	v_add_f32 v69, v109, v69
	v_add_f32 v70, v74, v70
	v_add_f32 v71, v75, v71
	v_add_f32 v68, v116, v68
	v_add_f32 v69, v117, v69
	s_addk_i32 s81, 0x80
	v_add_f32 v68, v112, v68
	v_add_f32 v69, v113, v69
	v_mov_b32_e32 v77, v106
	v_add_f32 v70, v84, v70
	v_add_f32 v71, v85, v71
	s_add_u32 s72, s72, 0x80
	v_fma_f32 v68, v96, v76, v68
	v_fma_f32 v69, v97, v77, v69
	v_add_f32 v70, v80, v70
	v_add_f32 v71, v81, v71
	v_mov_b32_e32 v161, v72
	s_addc_u32 s73, s73, 0
	v_fma_f32 v96, v68, v160, v70
	v_fma_f32 v97, v69, v161, v71
	s_cmp_lg_u32 s44, s12
	v_add_u32_e32 v166, 0xffffff80, v166
	s_waitcnt lgkmcnt(0)
	s_barrier
	s_cbranch_scc0 .LBB0_3068
	s_mov_b32 s82, s12
	s_branch .LBB0_3058
.Lnm1_entry:
	s_setprio 1
	v_or_b32_e32 v68, s83, v94
	v_add_u32_e32 v88, v68, v163
	ds_read_b128 v[204:207], v88 offset:2304
	ds_read_b128 v[208:211], v88
	ds_read_b128 v[212:215], v88 offset:4608
	ds_read_b128 v[216:219], v88 offset:6912
	ds_read_b128 v[220:223], v88 offset:64
	ds_read_b128 v[224:227], v88 offset:2368
	ds_read_b128 v[228:231], v88 offset:4672
	ds_read_b128 v[232:235], v88 offset:6976
	s_waitcnt lgkmcnt(7)
	v_mfma_f32_16x16x32_bf16 v[82:85], v[204:207], v[4:7], v[0:3]
	v_mfma_f32_16x16x32_bf16 v[108:111], v[204:207], v[12:15], v[0:3]
	s_waitcnt lgkmcnt(5)
	v_mfma_f32_16x16x32_bf16 v[112:115], v[212:215], v[4:7], v[0:3]
	v_mfma_f32_16x16x32_bf16 v[116:119], v[212:215], v[12:15], v[0:3]
	s_waitcnt lgkmcnt(4)
	v_mfma_f32_16x16x32_bf16 v[120:123], v[216:219], v[4:7], v[0:3]
	v_mfma_f32_16x16x32_bf16 v[124:127], v[216:219], v[12:15], v[0:3]
	v_mfma_f32_16x16x32_bf16 v[74:77], v[208:211], v[4:7], v[0:3]
	v_mfma_f32_16x16x32_bf16 v[68:71], v[208:211], v[12:15], v[0:3]
	s_waitcnt lgkmcnt(3)
	v_mfma_f32_16x16x32_bf16 v[128:131], v[220:223], v[8:11], v[74:77]
	v_mfma_f32_16x16x32_bf16 v[76:79], v[220:223], v[16:19], v[68:71]
	s_waitcnt lgkmcnt(2)
	v_mfma_f32_16x16x32_bf16 v[132:135], v[224:227], v[8:11], v[82:85]
	v_mfma_f32_16x16x32_bf16 v[80:83], v[224:227], v[16:19], v[108:111]
	s_waitcnt lgkmcnt(1)
	v_mfma_f32_16x16x32_bf16 v[108:111], v[228:231], v[8:11], v[112:115]
	v_mfma_f32_16x16x32_bf16 v[84:87], v[228:231], v[16:19], v[116:119]
	s_waitcnt lgkmcnt(0)
	v_mfma_f32_16x16x32_bf16 v[112:115], v[232:235], v[8:11], v[120:123]
	v_mfma_f32_16x16x32_bf16 v[142:145], v[232:235], v[16:19], v[124:127]
	s_nop 1
	s_setprio 0
	v_mul_f32_e32 v68, 0x3e38aa3b, v128
	v_mul_f32_e32 v69, 0x3e38aa3b, v129
	v_mul_f32_e32 v71, 0x3e38aa3b, v130
	v_mul_f32_e32 v72, 0x3e38aa3b, v131
	v_max3_f32 v70, v68, s68, v69
	v_mul_f32_e32 v74, 0x3e38aa3b, v132
	v_mul_f32_e32 v75, 0x3e38aa3b, v133
	v_max3_f32 v70, v70, v71, v72
	v_mul_f32_e32 v106, 0x3e38aa3b, v134
	v_mul_f32_e32 v116, 0x3e38aa3b, v135
	v_max3_f32 v70, v70, v74, v75
	v_mul_f32_e32 v108, 0x3e38aa3b, v108
	v_mul_f32_e32 v109, 0x3e38aa3b, v109
	v_max3_f32 v70, v70, v106, v116
	v_mul_f32_e32 v110, 0x3e38aa3b, v110
	v_mul_f32_e32 v111, 0x3e38aa3b, v111
	v_max3_f32 v70, v70, v108, v109
	v_mul_f32_e32 v112, 0x3e38aa3b, v112
	v_mul_f32_e32 v113, 0x3e38aa3b, v113
	v_max3_f32 v70, v70, v110, v111
	v_mul_f32_e32 v114, 0x3e38aa3b, v114
	v_mul_f32_e32 v115, 0x3e38aa3b, v115
	v_max3_f32 v70, v70, v112, v113
	v_mov_b32_e32 v118, v115
	v_max3_f32 v70, v70, v114, v118
	v_mov_b32_e32 v115, v70
	s_nop 1
	v_permlane16_swap_b32_e32 v70, v115
	v_max_f32_e32 v70, v70, v115
	v_mov_b32_e32 v115, v70
	s_nop 1
	v_permlane32_swap_b32_e32 v70, v115
	v_max3_f32 v140, v73, v70, v115
	v_sub_f32_e32 v68, v68, v140
	v_exp_f32_e32 v139, v68
	v_sub_f32_e32 v68, v69, v140
	v_exp_f32_e32 v137, v68
	v_sub_f32_e32 v68, v71, v140
	v_exp_f32_e32 v135, v68
	v_sub_f32_e32 v68, v72, v140
	v_exp_f32_e32 v133, v68
	v_sub_f32_e32 v68, v74, v140
	v_exp_f32_e32 v131, v68
	v_sub_f32_e32 v68, v75, v140
	v_exp_f32_e32 v129, v68
	v_sub_f32_e32 v68, v106, v140
	v_exp_f32_e32 v127, v68
	v_sub_f32_e32 v68, v116, v140
	v_exp_f32_e32 v125, v68
	v_sub_f32_e32 v68, v108, v140
	v_mul_f32_e32 v76, 0x3e38aa3b, v76
	v_exp_f32_e32 v123, v68
	v_sub_f32_e32 v68, v109, v140
	v_exp_f32_e32 v121, v68
	v_sub_f32_e32 v68, v110, v140
	v_mul_f32_e32 v77, 0x3e38aa3b, v77
	v_mul_f32_e32 v78, 0x3e38aa3b, v78
	v_mov_b32_e32 v110, v78
	v_mul_f32_e32 v78, 0x3e38aa3b, v79
	v_max3_f32 v108, v76, s68, v77
	v_mov_b32_e32 v79, v78
	v_mul_f32_e32 v80, 0x3e38aa3b, v80
	v_mul_f32_e32 v81, 0x3e38aa3b, v81
	v_exp_f32_e32 v119, v68
	v_sub_f32_e32 v68, v111, v140
	v_max3_f32 v78, v108, v110, v79
	v_mul_f32_e32 v82, 0x3e38aa3b, v82
	v_mul_f32_e32 v83, 0x3e38aa3b, v83
	v_exp_f32_e32 v115, v68
	v_sub_f32_e32 v68, v112, v140
	v_max3_f32 v78, v78, v80, v81
	v_mul_f32_e32 v84, 0x3e38aa3b, v84
	v_mul_f32_e32 v85, 0x3e38aa3b, v85
	v_exp_f32_e32 v111, v68
	v_sub_f32_e32 v68, v113, v140
	v_max3_f32 v78, v78, v82, v83
	v_mul_f32_e32 v86, 0x3e38aa3b, v86
	v_mul_f32_e32 v87, 0x3e38aa3b, v87
	v_exp_f32_e32 v109, v68
	v_sub_f32_e32 v68, v114, v140
	v_max3_f32 v78, v78, v84, v85
	v_mul_f32_e32 v108, 0x3e38aa3b, v142
	v_mul_f32_e32 v112, 0x3e38aa3b, v143
	v_mul_f32_e32 v114, 0x3e38aa3b, v144
	v_max3_f32 v78, v78, v86, v87
	v_mov_b32_e32 v116, v114
	v_mul_f32_e32 v114, 0x3e38aa3b, v145
	v_max3_f32 v78, v78, v108, v112
	v_mov_b32_e32 v141, v114
	v_max3_f32 v78, v78, v116, v141
	v_mov_b32_e32 v114, v78
	s_nop 1
	v_permlane16_swap_b32_e32 v78, v114
	v_max_f32_e32 v78, v78, v114
	v_mov_b32_e32 v114, v78
	s_nop 1
	v_permlane32_swap_b32_e32 v78, v114
	v_max3_f32 v78, v167, v78, v114
	v_sub_f32_e32 v76, v76, v78
	v_exp_f32_e32 v138, v76
	v_sub_f32_e32 v76, v77, v78
	v_exp_f32_e32 v136, v76
	v_sub_f32_e32 v76, v110, v78
	v_exp_f32_e32 v134, v76
	v_sub_f32_e32 v76, v79, v78
	v_exp_f32_e32 v132, v76
	v_sub_f32_e32 v76, v80, v78
	v_exp_f32_e32 v130, v76
	v_sub_f32_e32 v76, v81, v78
	v_exp_f32_e32 v128, v76
	v_sub_f32_e32 v76, v82, v78
	v_exp_f32_e32 v126, v76
	v_sub_f32_e32 v76, v83, v78
	v_exp_f32_e32 v124, v76
	v_sub_f32_e32 v76, v84, v78
	v_exp_f32_e32 v122, v76
	v_sub_f32_e32 v76, v85, v78
	v_exp_f32_e32 v120, v76
	v_sub_f32_e32 v76, v86, v78
	v_exp_f32_e32 v117, v68
	v_sub_f32_e32 v68, v118, v140
	v_exp_f32_e32 v118, v76
	v_sub_f32_e32 v76, v87, v78
	v_exp_f32_e32 v114, v76
	v_sub_f32_e32 v76, v108, v78
	v_sub_f32_e32 v77, v116, v78
	v_sub_f32_e32 v70, v73, v140
	v_sub_f32_e32 v142, v167, v78
	v_exp_f32_e32 v110, v76
	v_sub_f32_e32 v76, v112, v78
	v_exp_f32_e32 v116, v77
	v_sub_f32_e32 v77, v141, v78
	v_exp_f32_e32 v106, v70
	v_exp_f32_e32 v113, v68
	v_exp_f32_e32 v108, v76
	v_exp_f32_e32 v76, v142
	v_exp_f32_e32 v112, v77
	v_mul_f32 v58, v58, v106
	v_mul_f32 v59, v59, v106
	v_mul_f32 v56, v56, v106
	v_mul_f32 v57, v57, v106
	v_mul_f32 v54, v54, v106
	v_mul_f32 v55, v55, v106
	v_mul_f32 v52, v52, v106
	v_mul_f32 v53, v53, v106
	v_mul_f32 v62, v62, v106
	v_mul_f32 v63, v63, v106
	v_mul_f32 v60, v60, v106
	v_mul_f32 v61, v61, v106
	v_mul_f32 v70, v66, v106
	v_mul_f32 v71, v67, v106
	v_mul_f32 v68, v64, v106
	v_mul_f32 v69, v65, v106
	v_cvt_pk_bf16_f32 v72, v139, v137
	v_cvt_pk_bf16_f32 v73, v135, v133
	v_cvt_pk_bf16_f32 v74, v131, v129
	v_cvt_pk_bf16_f32 v75, v127, v125
	v_cvt_pk_bf16_f32 v64, v123, v121
	v_cvt_pk_bf16_f32 v65, v119, v115
	v_cvt_pk_bf16_f32 v66, v111, v109
	v_cvt_pk_bf16_f32 v67, v117, v113
	v_mul_f32 v42, v42, v76
	v_mul_f32 v43, v43, v76
	v_mul_f32 v40, v40, v76
	v_mul_f32 v41, v41, v76
	v_mul_f32 v38, v38, v76
	v_mul_f32 v39, v39, v76
	v_mul_f32 v36, v36, v76
	v_mul_f32 v37, v37, v76
	v_mul_f32 v46, v46, v76
	v_mul_f32 v47, v47, v76
	v_mul_f32 v44, v44, v76
	v_mul_f32 v45, v45, v76
	v_mul_f32 v50, v50, v76
	v_mul_f32 v51, v51, v76
	v_mul_f32 v48, v48, v76
	v_mul_f32 v49, v49, v76
	v_cvt_pk_bf16_f32 v80, v138, v136
	v_cvt_pk_bf16_f32 v81, v134, v132
	v_cvt_pk_bf16_f32 v82, v130, v128
	v_cvt_pk_bf16_f32 v83, v126, v124
	v_cvt_pk_bf16_f32 v84, v122, v120
	v_cvt_pk_bf16_f32 v85, v118, v114
	v_cvt_pk_bf16_f32 v86, v110, v108
	v_cvt_pk_bf16_f32 v87, v116, v112
	s_setprio 1
	v_add3_u32 v77, s83, v164, v165
	ds_read_b64_tr_b16 v[206:207], v77 offset:20992
	ds_read_b64_tr_b16 v[204:205], v77 offset:18432
	ds_read_b64_tr_b16 v[208:209], v77 offset:18464
	ds_read_b64_tr_b16 v[210:211], v77 offset:21024
	ds_read_b64_tr_b16 v[212:213], v77 offset:23552
	ds_read_b64_tr_b16 v[214:215], v77 offset:26112
	ds_read_b64_tr_b16 v[216:217], v77 offset:23584
	ds_read_b64_tr_b16 v[218:219], v77 offset:26144
	ds_read_b64_tr_b16 v[220:221], v77 offset:18496
	ds_read_b64_tr_b16 v[222:223], v77 offset:21056
	ds_read_b64_tr_b16 v[224:225], v77 offset:23616
	ds_read_b64_tr_b16 v[226:227], v77 offset:26176
	ds_read_b64_tr_b16 v[228:229], v77 offset:18528
	ds_read_b64_tr_b16 v[230:231], v77 offset:21088
	ds_read_b64_tr_b16 v[232:233], v77 offset:23648
	ds_read_b64_tr_b16 v[234:235], v77 offset:26208
	s_waitcnt lgkmcnt(14)
	v_mfma_f32_16x16x32_bf16 v[56:59], v[204:207], v[72:75], v[56:59]
	v_mfma_f32_16x16x32_bf16 v[40:43], v[204:207], v[80:83], v[40:43]
	s_waitcnt lgkmcnt(10)
	v_mfma_f32_16x16x32_bf16 v[56:59], v[212:215], v[64:67], v[56:59]
	v_mfma_f32_16x16x32_bf16 v[40:43], v[212:215], v[84:87], v[40:43]
	v_mfma_f32_16x16x32_bf16 v[52:55], v[208:211], v[72:75], v[52:55]
	v_mfma_f32_16x16x32_bf16 v[36:39], v[208:211], v[80:83], v[36:39]
	s_waitcnt lgkmcnt(8)
	v_mfma_f32_16x16x32_bf16 v[52:55], v[216:219], v[64:67], v[52:55]
	v_mfma_f32_16x16x32_bf16 v[36:39], v[216:219], v[84:87], v[36:39]
	s_waitcnt lgkmcnt(6)
	v_mfma_f32_16x16x32_bf16 v[60:63], v[220:223], v[72:75], v[60:63]
	v_mfma_f32_16x16x32_bf16 v[44:47], v[220:223], v[80:83], v[44:47]
	s_waitcnt lgkmcnt(4)
	v_mfma_f32_16x16x32_bf16 v[60:63], v[224:227], v[64:67], v[60:63]
	v_mfma_f32_16x16x32_bf16 v[44:47], v[224:227], v[84:87], v[44:47]
	s_waitcnt lgkmcnt(2)
	v_mfma_f32_16x16x32_bf16 v[68:71], v[228:231], v[72:75], v[68:71]
	v_mfma_f32_16x16x32_bf16 v[48:51], v[228:231], v[80:83], v[48:51]
	s_waitcnt lgkmcnt(0)
	v_mfma_f32_16x16x32_bf16 v[64:67], v[232:235], v[64:67], v[68:71]
	v_mfma_f32_16x16x32_bf16 v[48:51], v[232:235], v[84:87], v[48:51]
	s_nop 3
	s_setprio 0
	s_setprio 1
	ds_read_b128 v[204:207], v88 offset:9216
	ds_read_b128 v[208:211], v88 offset:9280
	ds_read_b128 v[212:215], v88 offset:11520
	ds_read_b128 v[216:219], v88 offset:13824
	ds_read_b128 v[220:223], v88 offset:16128
	ds_read_b128 v[224:227], v88 offset:11584
	ds_read_b128 v[228:231], v88 offset:13888
	ds_read_b128 v[232:235], v88 offset:16192
	s_waitcnt lgkmcnt(7)
	v_mfma_f32_16x16x32_bf16 v[72:75], v[204:207], v[4:7], v[0:3]
	v_mfma_f32_16x16x32_bf16 v[68:71], v[204:207], v[12:15], v[0:3]
	s_waitcnt lgkmcnt(6)
	v_mfma_f32_16x16x32_bf16 v[168:171], v[208:211], v[16:19], v[68:71]
	v_mfma_f32_16x16x32_bf16 v[72:75], v[208:211], v[8:11], v[72:75]
	s_waitcnt lgkmcnt(5)
	v_mfma_f32_16x16x32_bf16 v[84:87], v[212:215], v[4:7], v[0:3]
	v_mfma_f32_16x16x32_bf16 v[80:83], v[212:215], v[12:15], v[0:3]
	s_waitcnt lgkmcnt(2)
	v_mfma_f32_16x16x32_bf16 v[84:87], v[224:227], v[8:11], v[84:87]
	v_mfma_f32_16x16x32_bf16 v[184:187], v[224:227], v[16:19], v[80:83]
	v_mfma_f32_16x16x32_bf16 v[146:149], v[216:219], v[4:7], v[0:3]
	v_mfma_f32_16x16x32_bf16 v[142:145], v[216:219], v[12:15], v[0:3]
	s_waitcnt lgkmcnt(1)
	v_mfma_f32_16x16x32_bf16 v[80:83], v[228:231], v[8:11], v[146:149]
	v_mfma_f32_16x16x32_bf16 v[188:191], v[228:231], v[16:19], v[142:145]
	v_mfma_f32_16x16x32_bf16 v[154:157], v[220:223], v[4:7], v[0:3]
	v_mfma_f32_16x16x32_bf16 v[150:153], v[220:223], v[12:15], v[0:3]
	s_waitcnt lgkmcnt(0)
	v_mfma_f32_16x16x32_bf16 v[142:145], v[232:235], v[8:11], v[154:157]
	v_mfma_f32_16x16x32_bf16 v[192:195], v[232:235], v[16:19], v[150:153]
	s_nop 0
	s_setprio 0
	v_mul_f32_e32 v68, 0x3e38aa3b, v72
	v_mul_f32_e32 v71, 0x3e38aa3b, v74
	v_mul_f32_e32 v69, 0x3e38aa3b, v73
	v_mul_f32_e32 v72, 0x3e38aa3b, v75
	v_mul_f32_e32 v73, 0x3e38aa3b, v84
	v_mov_b32_e32 v74, v73
	v_mul_f32_e32 v73, 0x3e38aa3b, v85
	v_mov_b32_e32 v75, v73
	v_mul_f32_e32 v73, 0x3e38aa3b, v86
	v_mov_b32_e32 v79, v73
	v_mul_f32_e32 v73, 0x3e38aa3b, v87
	v_mov_b32_e32 v84, v73
	v_mul_f32_e32 v73, 0x3e38aa3b, v80
	v_mov_b32_e32 v80, v73
	v_mul_f32_e32 v73, 0x3e38aa3b, v81
	v_mov_b32_e32 v81, v73
	v_mul_f32_e32 v73, 0x3e38aa3b, v82
	v_mov_b32_e32 v82, v73
	v_mul_f32_e32 v73, 0x3e38aa3b, v83
	v_mov_b32_e32 v83, v73
	v_mul_f32_e32 v73, 0x3e38aa3b, v142
	v_max3_f32 v70, v68, s68, v69
	v_mov_b32_e32 v85, v73
	v_max3_f32 v70, v70, v71, v72
	v_mul_f32_e32 v73, 0x3e38aa3b, v143
	v_max3_f32 v70, v70, v74, v75
	v_mov_b32_e32 v86, v73
	v_max3_f32 v70, v70, v79, v84
	v_mul_f32_e32 v73, 0x3e38aa3b, v144
	v_max3_f32 v70, v70, v80, v81
	v_mov_b32_e32 v88, v73
	v_max3_f32 v70, v70, v82, v83
	v_mul_f32_e32 v73, 0x3e38aa3b, v145
	v_max3_f32 v70, v70, v85, v86
	v_mov_b32_e32 v142, v73
	v_max3_f32 v70, v70, v88, v142
	v_mov_b32_e32 v73, v70
	s_nop 1
	v_permlane16_swap_b32_e32 v70, v73
	v_max_f32_e32 v70, v70, v73
	v_mov_b32_e32 v73, v70
	s_nop 1
	v_permlane32_swap_b32_e32 v70, v73
	v_max3_f32 v73, v140, v70, v73
	v_sub_f32_e32 v68, v68, v73
	v_exp_f32_e32 v159, v68
	v_sub_f32_e32 v68, v69, v73
	v_exp_f32_e32 v157, v68
	v_sub_f32_e32 v68, v71, v73
	v_exp_f32_e32 v155, v68
	v_sub_f32_e32 v68, v72, v73
	v_exp_f32_e32 v153, v68
	v_sub_f32_e32 v68, v74, v73
	v_exp_f32_e32 v151, v68
	v_sub_f32_e32 v68, v75, v73
	v_exp_f32_e32 v149, v68
	v_sub_f32_e32 v68, v79, v73
	v_exp_f32_e32 v147, v68
	v_sub_f32_e32 v68, v84, v73
	v_exp_f32_e32 v145, v68
	v_sub_f32_e32 v68, v80, v73
	v_exp_f32_e32 v143, v68
	v_sub_f32_e32 v68, v81, v73
	v_exp_f32_e32 v141, v68
	v_sub_f32_e32 v68, v82, v73
	v_sub_f32_e32 v70, v140, v73
	v_exp_f32_e32 v87, v68
	v_sub_f32_e32 v68, v83, v73
	v_exp_f32_e32 v83, v68
	v_sub_f32_e32 v68, v85, v73
	v_exp_f32_e32 v72, v70
	v_exp_f32_e32 v79, v68
	v_sub_f32_e32 v68, v86, v73
	v_exp_f32_e32 v75, v68
	v_sub_f32_e32 v68, v88, v73
	v_exp_f32_e32 v85, v68
	v_sub_f32_e32 v68, v142, v73
	v_exp_f32_e32 v81, v68
	v_mul_f32 v68, v64, v72
	v_mul_f32 v69, v65, v72
	v_mul_f32_e32 v64, 0x3e38aa3b, v168
	v_mov_b32_e32 v74, v64
	v_mul_f32_e32 v64, 0x3e38aa3b, v169
	v_mov_b32_e32 v80, v64
	v_mul_f32_e32 v64, 0x3e38aa3b, v170
	v_mov_b32_e32 v82, v64
	v_mul_f32_e32 v64, 0x3e38aa3b, v171
	v_mov_b32_e32 v84, v64
	v_mul_f32_e32 v64, 0x3e38aa3b, v184
	v_mov_b32_e32 v86, v64
	v_mul_f32_e32 v64, 0x3e38aa3b, v185
	v_mov_b32_e32 v88, v64
	v_mul_f32_e32 v64, 0x3e38aa3b, v186
	v_mov_b32_e32 v140, v64
	v_mul_f32_e32 v64, 0x3e38aa3b, v187
	v_mov_b32_e32 v142, v64
	v_mul_f32_e32 v64, 0x3e38aa3b, v188
	v_mov_b32_e32 v160, v64
	v_mul_f32_e32 v64, 0x3e38aa3b, v189
	v_mov_b32_e32 v161, v64
	v_mul_f32_e32 v64, 0x3e38aa3b, v190
	v_mov_b32_e32 v172, v64
	v_mul_f32_e32 v64, 0x3e38aa3b, v191
	v_mov_b32_e32 v173, v64
	v_mul_f32_e32 v64, 0x3e38aa3b, v192
	v_mov_b32_e32 v184, v64
	v_mul_f32_e32 v64, 0x3e38aa3b, v193
	v_mov_b32_e32 v185, v64
	v_mul_f32_e32 v64, 0x3e38aa3b, v194
	v_mov_b32_e32 v186, v64
	v_mul_f32_e32 v64, 0x3e38aa3b, v195
	v_mov_b32_e32 v187, v64
	v_max3_f32 v64, v74, s68, v80
	v_max3_f32 v64, v64, v82, v84
	v_max3_f32 v64, v64, v86, v88
	v_max3_f32 v64, v64, v140, v142
	v_max3_f32 v64, v64, v160, v161
	v_max3_f32 v64, v64, v172, v173
	v_max3_f32 v144, v64, v184, v185
	v_max3_f32 v144, v144, v186, v187
	v_mov_b32_e32 v146, v144
	s_nop 1
	v_permlane16_swap_b32_e32 v144, v146
	v_max_f32_e32 v144, v144, v146
	v_mov_b32_e32 v146, v144
	s_nop 1
	v_permlane32_swap_b32_e32 v144, v146
	v_max3_f32 v167, v78, v144, v146
	v_sub_f32_e32 v74, v74, v167
	v_exp_f32_e32 v158, v74
	v_sub_f32_e32 v74, v80, v167
	v_exp_f32_e32 v156, v74
	v_sub_f32_e32 v74, v82, v167
	v_exp_f32_e32 v154, v74
	v_sub_f32_e32 v74, v84, v167
	v_exp_f32_e32 v152, v74
	v_sub_f32_e32 v74, v86, v167
	v_exp_f32_e32 v150, v74
	v_sub_f32_e32 v74, v88, v167
	v_exp_f32_e32 v148, v74
	v_sub_f32_e32 v74, v140, v167
	v_exp_f32_e32 v146, v74
	v_sub_f32_e32 v74, v142, v167
	v_exp_f32_e32 v144, v74
	v_sub_f32_e32 v74, v160, v167
	v_exp_f32_e32 v142, v74
	v_sub_f32_e32 v74, v161, v167
	v_exp_f32_e32 v140, v74
	v_sub_f32_e32 v74, v172, v167
	v_exp_f32_e32 v86, v74
	v_sub_f32_e32 v74, v173, v167
	v_sub_f32_e32 v188, v78, v167
	v_exp_f32_e32 v82, v74
	v_sub_f32_e32 v74, v184, v167
	v_sub_f32_e32 v80, v186, v167
	v_exp_f32_e32 v78, v74
	v_sub_f32_e32 v74, v185, v167
	v_exp_f32_e32 v160, v188
	v_exp_f32_e32 v84, v80
	v_sub_f32_e32 v80, v187, v167
	v_exp_f32_e32 v74, v74
	v_exp_f32_e32 v80, v80
	v_mul_f32 v58, v58, v72
	v_mul_f32 v59, v59, v72
	v_mul_f32 v56, v56, v72
	v_mul_f32 v57, v57, v72
	v_mul_f32 v54, v54, v72
	v_mul_f32 v55, v55, v72
	v_mul_f32 v52, v52, v72
	v_mul_f32 v53, v53, v72
	v_mul_f32 v62, v62, v72
	v_mul_f32 v63, v63, v72
	v_mul_f32 v60, v60, v72
	v_mul_f32 v61, v61, v72
	v_mul_f32 v70, v66, v72
	v_mul_f32 v71, v67, v72
	v_cvt_pk_bf16_f32 v64, v143, v141
	v_cvt_pk_bf16_f32 v65, v87, v83
	v_cvt_pk_bf16_f32 v66, v79, v75
	v_cvt_pk_bf16_f32 v67, v85, v81
	v_mul_f32 v42, v42, v160
	v_mul_f32 v43, v43, v160
	v_mul_f32 v40, v40, v160
	v_mul_f32 v41, v41, v160
	v_mul_f32 v38, v38, v160
	v_mul_f32 v39, v39, v160
	v_mul_f32 v36, v36, v160
	v_mul_f32 v37, v37, v160
	v_mul_f32 v46, v46, v160
	v_mul_f32 v47, v47, v160
	v_mul_f32 v44, v44, v160
	v_mul_f32 v45, v45, v160
	v_mul_f32 v50, v50, v160
	v_mul_f32 v51, v51, v160
	v_mul_f32 v48, v48, v160
	v_mul_f32 v49, v49, v160
	v_cvt_pk_bf16_f32 v168, v159, v157
	v_cvt_pk_bf16_f32 v169, v155, v153
	v_cvt_pk_bf16_f32 v170, v151, v149
	v_cvt_pk_bf16_f32 v171, v147, v145
	v_cvt_pk_bf16_f32 v184, v158, v156
	v_cvt_pk_bf16_f32 v185, v154, v152
	v_cvt_pk_bf16_f32 v186, v150, v148
	v_cvt_pk_bf16_f32 v187, v146, v144
	v_cvt_pk_bf16_f32 v188, v142, v140
	v_cvt_pk_bf16_f32 v189, v86, v82
	v_cvt_pk_bf16_f32 v190, v78, v74
	v_cvt_pk_bf16_f32 v191, v84, v80
	s_setprio 1
	ds_read_b64_tr_b16 v[206:207], v77 offset:31232
	ds_read_b64_tr_b16 v[204:205], v77 offset:28672
	ds_read_b64_tr_b16 v[208:209], v77 offset:28704
	ds_read_b64_tr_b16 v[210:211], v77 offset:31264
	ds_read_b64_tr_b16 v[212:213], v77 offset:33792
	ds_read_b64_tr_b16 v[214:215], v77 offset:36352
	ds_read_b64_tr_b16 v[216:217], v77 offset:33824
	ds_read_b64_tr_b16 v[218:219], v77 offset:36384
	ds_read_b64_tr_b16 v[220:221], v77 offset:28736
	ds_read_b64_tr_b16 v[222:223], v77 offset:31296
	ds_read_b64_tr_b16 v[224:225], v77 offset:33856
	ds_read_b64_tr_b16 v[226:227], v77 offset:36416
	ds_read_b64_tr_b16 v[228:229], v77 offset:28768
	ds_read_b64_tr_b16 v[230:231], v77 offset:31328
	ds_read_b64_tr_b16 v[232:233], v77 offset:33888
	ds_read_b64_tr_b16 v[234:235], v77 offset:36448
	s_waitcnt lgkmcnt(14)
	v_mfma_f32_16x16x32_bf16 v[56:59], v[204:207], v[168:171], v[56:59]
	v_mfma_f32_16x16x32_bf16 v[40:43], v[204:207], v[184:187], v[40:43]
	s_waitcnt lgkmcnt(10)
	v_mfma_f32_16x16x32_bf16 v[56:59], v[212:215], v[64:67], v[56:59]
	v_mfma_f32_16x16x32_bf16 v[40:43], v[212:215], v[188:191], v[40:43]
	v_mfma_f32_16x16x32_bf16 v[52:55], v[208:211], v[168:171], v[52:55]
	v_mfma_f32_16x16x32_bf16 v[36:39], v[208:211], v[184:187], v[36:39]
	s_waitcnt lgkmcnt(8)
	v_mfma_f32_16x16x32_bf16 v[52:55], v[216:219], v[64:67], v[52:55]
	v_mfma_f32_16x16x32_bf16 v[36:39], v[216:219], v[188:191], v[36:39]
	s_waitcnt lgkmcnt(6)
	v_mfma_f32_16x16x32_bf16 v[60:63], v[220:223], v[168:171], v[60:63]
	v_mfma_f32_16x16x32_bf16 v[44:47], v[220:223], v[184:187], v[44:47]
	s_waitcnt lgkmcnt(4)
	v_mfma_f32_16x16x32_bf16 v[60:63], v[224:227], v[64:67], v[60:63]
	v_mfma_f32_16x16x32_bf16 v[44:47], v[224:227], v[188:191], v[44:47]
	s_waitcnt lgkmcnt(2)
	v_mfma_f32_16x16x32_bf16 v[68:71], v[228:231], v[168:171], v[68:71]
	v_mfma_f32_16x16x32_bf16 v[48:51], v[228:231], v[184:187], v[48:51]
	s_waitcnt lgkmcnt(0)
	v_mfma_f32_16x16x32_bf16 v[64:67], v[232:235], v[64:67], v[68:71]
	v_mfma_f32_16x16x32_bf16 v[48:51], v[232:235], v[188:191], v[48:51]
	s_nop 3
	s_setprio 0
	s_add_i32 s12, s82, 1
	s_cmp_ge_i32 s12, s44
	s_cbranch_scc1 .Lnm1_b3060
	s_bitcmp1_b32 s12, 0
	s_cselect_b32 s6, 0x9800, 0
	v_add3_u32 v71, s6, v99, v98
	v_add3_u32 v68, s6, v162, v98
	v_add3_u32 v69, s6, v107, v98
	v_add3_u32 v70, s6, v105, v98
	s_waitcnt vmcnt(0)
	ds_write_b128 v71, v[20:23]
	ds_write_b128 v70, v[24:27]
	ds_write_b128 v69, v[28:31] offset:18432
	ds_write_b128 v68, v[32:35] offset:18432

.Lnm1_b3065:
	v_add_f32 v68, v138, 0
	v_add_f32 v69, v139, 0
	v_add_f32 v70, v158, 0
	v_add_f32 v71, v159, 0
	v_add_f32 v68, v136, v68
	v_add_f32 v69, v137, v69
	v_add_f32 v70, v156, v70
	v_add_f32 v71, v157, v71
	v_add_f32 v68, v134, v68
	v_add_f32 v69, v135, v69
	v_add_f32 v70, v154, v70
	v_add_f32 v71, v155, v71
	v_add_f32 v68, v132, v68
	v_add_f32 v69, v133, v69
	v_add_f32 v70, v152, v70
	v_add_f32 v71, v153, v71
	v_add_f32 v68, v130, v68
	v_add_f32 v69, v131, v69
	v_add_f32 v70, v150, v70
	v_add_f32 v71, v151, v71
	v_add_f32 v68, v128, v68
	v_add_f32 v69, v129, v69
	v_add_f32 v70, v148, v70
	v_add_f32 v71, v149, v71
	v_add_f32 v68, v126, v68
	v_add_f32 v69, v127, v69
	v_add_f32 v70, v146, v70
	v_add_f32 v71, v147, v71
	v_add_f32 v68, v124, v68
	v_add_f32 v69, v125, v69
	v_add_f32 v70, v144, v70
	v_add_f32 v71, v145, v71
	v_add_f32 v68, v122, v68
	v_add_f32 v69, v123, v69
	v_add_f32 v70, v142, v70
	v_add_f32 v71, v143, v71
	v_add_f32 v68, v120, v68
	v_add_f32 v69, v121, v69
	v_add_f32 v70, v140, v70
	v_add_f32 v71, v141, v71
	v_add_f32 v68, v118, v68
	v_add_f32 v69, v119, v69
	v_add_f32 v70, v86, v70
	v_add_f32 v71, v87, v71
	v_add_f32 v68, v114, v68
	v_add_f32 v69, v115, v69
	v_add_f32 v70, v82, v70
	v_add_f32 v71, v83, v71
	v_add_f32 v68, v110, v68
	v_add_f32 v69, v111, v69
	v_add_f32 v70, v78, v70
	v_add_f32 v71, v79, v71
	v_add_f32 v68, v108, v68
	v_add_f32 v69, v109, v69
	v_add_f32 v70, v74, v70
	v_add_f32 v71, v75, v71
	v_add_f32 v68, v116, v68
	v_add_f32 v69, v117, v69
	s_addk_i32 s81, 0x80
	v_add_f32 v68, v112, v68
	v_add_f32 v69, v113, v69
	v_mov_b32_e32 v77, v106
	v_add_f32 v70, v84, v70
	v_add_f32 v71, v85, v71
	s_add_u32 s72, s72, 0x80
	v_fma_f32 v68, v96, v76, v68
	v_fma_f32 v69, v97, v77, v69
	v_add_f32 v70, v80, v70
	v_add_f32 v71, v81, v71
	v_mov_b32_e32 v161, v72
	s_addc_u32 s73, s73, 0
	v_fma_f32 v96, v68, v160, v70
	v_fma_f32 v97, v69, v161, v71
	s_cmp_lg_u32 s44, s12
	s_waitcnt lgkmcnt(0)
	s_barrier
	s_cbranch_scc0 .LBB0_3068
	s_mov_b32 s82, s12
	s_branch .LBB0_3058

.LBB0_3069:
	v_mov_b32_e32 v4, v97
	s_nop 1
	v_permlane16_swap_b32_e32 v97, v4
	v_add_f32_e32 v4, v97, v4
	v_mov_b32_e32 v5, v4
	s_nop 1
	v_permlane32_swap_b32_e32 v4, v5
	v_add_f32_e32 v4, v4, v5
	v_div_scale_f32 v5, s[6:7], v4, v4, 1.0
	v_rcp_f32_e32 v6, v5
	v_mov_b32_e32 v105, v89
	s_lshl_b32 s44, s78, 1
	s_mov_b64 s[76:77], s[66:67]
	v_fma_f32 v7, -v5, v6, 1.0
	v_fmac_f32_e32 v6, v7, v6
	v_div_scale_f32 v7, vcc, 1.0, v4, 1.0
	v_mul_f32_e32 v8, v7, v6
	v_fma_f32 v9, -v5, v8, v7
	v_fmac_f32_e32 v8, v9, v6
	v_fma_f32 v5, -v5, v8, v7
	v_div_fmas_f32 v5, v5, v6, v8
	v_lshlrev_b64 v[6:7], 11, v[92:93]
	v_lshl_add_u64 v[6:7], s[42:43], 0, v[6:7]
	v_lshl_add_u64 v[6:7], v[6:7], 0, s[44:45]
	v_lshlrev_b64 v[8:9], 1, v[104:105]
	v_div_fixup_f32 v4, v5, v4, 1.0
	v_lshl_add_u64 v[6:7], v[6:7], 0, v[8:9]
	v_lshl_add_u64 v[10:11], v[6:7], 0, s[96:97]
	v_mul_f32 v12, v56, v4
	v_mul_f32 v13, v57, v4
	v_mul_f32 v14, v58, v4
	v_mul_f32 v15, v59, v4
	v_add_co_u32_e32 v6, vcc, s94, v6
	v_cvt_pk_bf16_f32 v12, v12, v13
	v_cvt_pk_bf16_f32 v13, v14, v15
	v_addc_co_u32_e32 v7, vcc, 0, v7, vcc
	flat_store_dwordx2 v[6:7], v[12:13] offset:512
	v_mul_f32 v6, v52, v4
	v_mul_f32 v7, v53, v4
	v_mul_f32 v12, v54, v4
	v_mul_f32 v13, v55, v4
	v_cvt_pk_bf16_f32 v6, v6, v7
	v_cvt_pk_bf16_f32 v7, v12, v13
	flat_store_dwordx2 v[10:11], v[6:7] offset:32
	v_mul_f32 v6, v60, v4
	v_mul_f32 v7, v61, v4
	v_mul_f32 v12, v62, v4
	v_mul_f32 v13, v63, v4
	v_cvt_pk_bf16_f32 v6, v6, v7
	v_cvt_pk_bf16_f32 v7, v12, v13
	flat_store_dwordx2 v[10:11], v[6:7] offset:64
	v_mul_f32 v6, v64, v4
	v_mul_f32 v7, v65, v4
	v_mov_b32_e32 v5, v96
	s_nop 1
	v_permlane16_swap_b32_e32 v96, v5
	v_add_f32_e32 v5, v96, v5
	v_cvt_pk_bf16_f32 v6, v6, v7
	v_mov_b32_e32 v7, v5
	s_nop 1
	v_permlane32_swap_b32_e32 v5, v7
	v_add_f32_e32 v12, v5, v7
	v_div_scale_f32 v13, s[6:7], v12, v12, 1.0
	v_rcp_f32_e32 v14, v13
	v_mul_f32 v5, v67, v4
	v_mul_f32 v4, v66, v4
	s_nop 0
	v_cvt_pk_bf16_f32 v7, v4, v5
	v_fma_f32 v4, -v13, v14, 1.0
	v_fmac_f32_e32 v14, v4, v14
	v_div_scale_f32 v4, vcc, 1.0, v12, 1.0
	v_mul_f32_e32 v5, v4, v14
	flat_store_dwordx2 v[10:11], v[6:7] offset:96
	v_fma_f32 v6, -v13, v5, v4
	v_fmac_f32_e32 v5, v6, v14
	v_lshlrev_b64 v[6:7], 11, v[90:91]
	v_fma_f32 v4, -v13, v5, v4
	v_lshl_add_u64 v[6:7], s[42:43], 0, v[6:7]
	v_div_fmas_f32 v4, v4, v14, v5
	v_lshl_add_u64 v[6:7], v[6:7], 0, s[44:45]
	v_div_fixup_f32 v4, v4, v12, 1.0
	v_lshl_add_u64 v[6:7], v[6:7], 0, v[8:9]
	v_lshl_add_u64 v[8:9], v[6:7], 0, s[96:97]
	v_mul_f32 v10, v40, v4
	v_mul_f32 v11, v41, v4
	v_mul_f32 v12, v42, v4
	v_mul_f32 v13, v43, v4
	v_add_co_u32_e32 v6, vcc, s94, v6
	v_cvt_pk_bf16_f32 v10, v10, v11
	v_cvt_pk_bf16_f32 v11, v12, v13
	v_addc_co_u32_e32 v7, vcc, 0, v7, vcc
	flat_store_dwordx2 v[6:7], v[10:11] offset:512
	v_mul_f32 v6, v36, v4
	v_mul_f32 v7, v37, v4
	v_mul_f32 v10, v38, v4
	v_mul_f32 v11, v39, v4
	v_cvt_pk_bf16_f32 v6, v6, v7
	v_cvt_pk_bf16_f32 v7, v10, v11
	flat_store_dwordx2 v[8:9], v[6:7] offset:32
	v_mul_f32 v6, v44, v4
	v_mul_f32 v7, v45, v4
	v_mul_f32 v10, v46, v4
	v_mul_f32 v11, v47, v4
	v_cvt_pk_bf16_f32 v6, v6, v7
	v_cvt_pk_bf16_f32 v7, v10, v11
	flat_store_dwordx2 v[8:9], v[6:7] offset:64
	v_mul_f32 v6, v48, v4
	v_mul_f32 v7, v49, v4
	v_mul_f32 v5, v51, v4
	v_mul_f32 v4, v50, v4
	v_cvt_pk_bf16_f32 v6, v6, v7
	v_cvt_pk_bf16_f32 v7, v4, v5
	flat_store_dwordx2 v[8:9], v[6:7] offset:96
	s_waitcnt lgkmcnt(0)
	s_barrier
	s_and_saveexec_b64 s[6:7], s[4:5]
	s_cbranch_execz .LBB0_3041
	v_readlane_b32 s8, v252, 23
	v_readlane_b32 s9, v252, 24
	s_nop 1
	v_mov_b64_e32 v[4:5], s[8:9]
	flat_atomic_add v4, v[4:5], v176 sc0
	s_waitcnt vmcnt(0) lgkmcnt(0)
	ds_write_b32 v177, v4
	s_branch .LBB0_3041

.Lhy_ctx1_done:
	s_and_b64 s[18:19], s[6:7], exec
	s_cselect_b32 s44, s2, 0xddf2000
	v_lshl_add_u64 v[20:21], v[12:13], 0, s[44:45]
	v_lshl_add_u64 v[18:19], s[8:9], 1, v[20:21]
	flat_load_dwordx2 v[32:33], v[18:19]
	v_cndmask_b32_e64 v18, v23, v22, s[6:7]
	s_lshl_b32 s6, s14, 1
	s_add_i32 s6, s16, s6
	v_mov_b32_e32 v34, v8
	v_lshl_add_u32 v8, v25, 1, s6
	ds_read_b64 v[36:37], v8 offset:512
	v_mov_b32_e32 v35, v10
	v_mov_b32_e32 v10, v9
	s_mov_b64 s[6:7], -1
	s_and_b64 vcc, exec, s[12:13]
	s_waitcnt lgkmcnt(0)
	v_lshlrev_b32_e32 v9, 16, v37
	v_lshlrev_b32_e32 v8, 16, v36
	v_and_b32_e32 v37, 0xffff0000, v37
	v_and_b32_e32 v36, 0xffff0000, v36
	v_fma_f32 v8, v18, v8, v34
	v_fma_f32 v9, v18, v9, v35
	v_fma_f32 v10, v18, v36, v10
	v_fma_f32 v11, v18, v37, v11
	s_waitcnt vmcnt(0)
	v_lshlrev_b32_e32 v35, 16, v33
	v_lshlrev_b32_e32 v34, 16, v32
	v_and_b32_e32 v33, 0xffff0000, v33
	v_and_b32_e32 v32, 0xffff0000, v32
	v_mul_f32 v10, v10, v32
	v_mul_f32 v11, v11, v33
	v_mul_f32 v8, v8, v34
	v_mul_f32 v9, v9, v35
	v_and_b32_sdwa v32, v11, v176 dst_sel:DWORD dst_unused:UNUSED_PAD src0_sel:WORD_1 src1_sel:DWORD
	v_and_b32_sdwa v33, v10, v176 dst_sel:DWORD dst_unused:UNUSED_PAD src0_sel:WORD_1 src1_sel:DWORD
	v_and_b32_sdwa v19, v9, v176 dst_sel:DWORD dst_unused:UNUSED_PAD src0_sel:WORD_1 src1_sel:DWORD
	v_and_b32_sdwa v31, v8, v176 dst_sel:DWORD dst_unused:UNUSED_PAD src0_sel:WORD_1 src1_sel:DWORD
	v_add3_u32 v11, v11, v32, s93
	v_add3_u32 v10, v10, v33, s93
	v_add3_u32 v8, v8, v31, s93
	v_add3_u32 v9, v9, v19, s93
	v_and_b32_e32 v11, 0xffff0000, v11
	v_and_b32_e32 v10, 0xffff0000, v10
	v_or_b32_sdwa v9, v11, v9 dst_sel:DWORD dst_unused:UNUSED_PAD src0_sel:DWORD src1_sel:WORD_1
	v_or_b32_sdwa v8, v10, v8 dst_sel:DWORD dst_unused:UNUSED_PAD src0_sel:DWORD src1_sel:WORD_1
	s_cbranch_vccz .LBB0_3096
	flat_store_dwordx2 v[14:15], v[8:9]
	s_mov_b64 s[6:7], 0

.LBB0_3098:
	v_lshl_add_u64 v[8:9], s[10:11], 1, v[20:21]
	flat_load_dwordx2 v[8:9], v[8:9]
	s_lshl_b32 s6, s15, 1
	s_add_i32 s16, s16, s6
	v_mov_b32_e32 v10, v4
	v_lshl_add_u32 v4, v25, 1, s16
	ds_read_b64 v[20:21], v4 offset:512
	v_cndmask_b32_e64 v4, 0, 1, s[12:13]
	v_mov_b32_e32 v19, v18
	v_mov_b32_e32 v11, v6
	v_mov_b32_e32 v6, v5
	v_cmp_ne_u32_e64 s[6:7], 1, v4
	s_waitcnt lgkmcnt(0)
	v_lshlrev_b32_e32 v5, 16, v21
	v_lshlrev_b32_e32 v4, 16, v20
	v_and_b32_e32 v21, 0xffff0000, v21
	v_and_b32_e32 v20, 0xffff0000, v20
	v_fma_f32 v4, v18, v4, v10
	v_fma_f32 v5, v19, v5, v11
	v_fma_f32 v6, v18, v20, v6
	v_fma_f32 v7, v19, v21, v7
	s_andn2_b64 vcc, exec, s[12:13]
	s_mov_b64 s[12:13], -1
	s_waitcnt vmcnt(0)
	v_lshlrev_b32_e32 v11, 16, v9
	v_lshlrev_b32_e32 v10, 16, v8
	v_and_b32_e32 v9, 0xffff0000, v9
	v_and_b32_e32 v8, 0xffff0000, v8
	v_mul_f32 v6, v6, v8
	v_mul_f32 v7, v7, v9
	v_mul_f32 v4, v4, v10
	v_mul_f32 v5, v5, v11
	v_and_b32_sdwa v10, v7, v176 dst_sel:DWORD dst_unused:UNUSED_PAD src0_sel:WORD_1 src1_sel:DWORD
	v_and_b32_sdwa v11, v6, v176 dst_sel:DWORD dst_unused:UNUSED_PAD src0_sel:WORD_1 src1_sel:DWORD
	v_and_b32_sdwa v8, v5, v176 dst_sel:DWORD dst_unused:UNUSED_PAD src0_sel:WORD_1 src1_sel:DWORD
	v_and_b32_sdwa v9, v4, v176 dst_sel:DWORD dst_unused:UNUSED_PAD src0_sel:WORD_1 src1_sel:DWORD
	v_add3_u32 v7, v7, v10, s93
	v_add3_u32 v6, v6, v11, s93
	v_add3_u32 v4, v4, v9, s93
	v_add3_u32 v5, v5, v8, s93
	v_and_b32_e32 v7, 0xffff0000, v7
	v_and_b32_e32 v6, 0xffff0000, v6
	v_or_b32_sdwa v5, v7, v5 dst_sel:DWORD dst_unused:UNUSED_PAD src0_sel:DWORD src1_sel:WORD_1
	v_or_b32_sdwa v4, v6, v4 dst_sel:DWORD dst_unused:UNUSED_PAD src0_sel:DWORD src1_sel:WORD_1
	s_cbranch_vccnz .LBB0_3100
	s_mov_b64 s[12:13], 0
	flat_store_dwordx2 v[16:17], v[4:5]

.LBB0_3159:
	s_cmpk_gt_i32 s33, 0xbf
	s_cbranch_scc0 .LBB0_3163
	v_lshl_add_u64 v[20:21], s[20:21], 0, v[0:1]
	v_lshlrev_b64 v[22:23], 9, v[20:21]
	v_lshl_add_u64 v[40:41], v[4:5], 0, v[22:23]
	v_lshl_add_u64 v[42:43], v[6:7], 0, v[22:23]
	v_lshl_add_u64 v[22:23], v[8:9], 0, v[22:23]
	flat_load_dwordx2 v[44:45], v[40:41]
	flat_load_dwordx2 v[46:47], v[42:43]
	s_add_u32 s6, s0, s24
	flat_load_dwordx2 v[22:23], v[22:23]
	s_addc_u32 s7, s1, s25
	s_load_dwordx2 s[6:7], s[6:7], 0xb8
	v_lshlrev_b64 v[40:41], 11, v[20:21]
	v_lshl_add_u64 v[48:49], s[18:19], 0, v[40:41]
	s_waitcnt lgkmcnt(0)
	global_load_dwordx4 v[40:43], v29, s[6:7] offset:256
	s_waitcnt vmcnt(0)
	v_lshlrev_b32_e32 v50, 16, v44
	v_lshlrev_b32_e32 v52, 16, v46
	v_and_b32_e32 v51, 0xffff0000, v44
	v_and_b32_e32 v53, 0xffff0000, v46
	v_lshlrev_b32_e32 v44, 16, v45
	v_lshlrev_b32_e32 v46, 16, v47
	v_and_b32_e32 v45, 0xffff0000, v45
	v_and_b32_e32 v47, 0xffff0000, v47
	v_lshlrev_b32_e32 v56, 16, v22
	v_and_b32_e32 v57, 0xffff0000, v22
	v_lshlrev_b32_e32 v58, 16, v23
	v_and_b32_e32 v59, 0xffff0000, v23
	v_add_f32 v22, v44, v46
	v_add_f32 v23, v45, v47
	v_add_f32 v44, v50, v52
	v_add_f32 v45, v51, v53
	v_mul_f32_e32 v52, 0xbfb8aa3b, v56
	v_mul_f32_e32 v53, 0xbfb8aa3b, v57
	v_mul_f32_e32 v54, 0xbfb8aa3b, v58
	v_mul_f32_e32 v55, 0xbfb8aa3b, v59
	v_exp_f32_e32 v52, v52
	v_exp_f32_e32 v53, v53
	v_mul_f32 v50, v44, v44
	v_mul_f32 v51, v45, v45
	v_exp_f32_e32 v54, v54
	v_exp_f32_e32 v55, v55
	v_mul_f32 v46, v22, v22
	v_mul_f32 v47, v23, v23
	v_add_f32_e32 v50, v50, v51
	v_add_f32_e32 v46, v46, v50
	v_add_f32_e32 v50, v47, v46
	v_add_f32 v46, v52, 1.0
	v_add_f32 v47, v53, 1.0
	s_nop 0
	v_add_f32_dpp v52, v50, v50 quad_perm:[1,0,3,2] row_mask:0xf bank_mask:0xf bound_ctrl:1
	v_add_f32 v50, v54, 1.0
	v_add_f32 v51, v55, 1.0
	v_div_scale_f32 v53, s[6:7], v47, v47, v57
	v_div_scale_f32 v55, s[6:7], v46, v46, v56
	v_add_f32_dpp v52, v52, v52 quad_perm:[2,3,0,1] row_mask:0xf bank_mask:0xf bound_ctrl:1
	v_div_scale_f32 v61, s[8:9], v51, v51, v59
	v_rcp_f32_e32 v64, v53
	v_rcp_f32_e32 v65, v55
	v_add_f32_dpp v52, v52, v52 row_half_mirror row_mask:0xf bank_mask:0xf bound_ctrl:1
	v_rcp_f32_e32 v66, v61
	v_div_scale_f32 v63, s[10:11], v50, v50, v58
	v_add_f32_dpp v52, v52, v52 row_mirror row_mask:0xf bank_mask:0xf bound_ctrl:1
	v_fmamk_f32 v52, v52, 0x3c800000, v30
	v_mul_f32_e32 v68, 0x4b800000, v52
	v_fma_f32 v69, -v53, v64, 1.0
	v_cmp_gt_f32_e64 s[10:11], s31, v52
	v_div_scale_f32 v54, vcc, v57, v47, v57
	v_fma_f32 v70, -v55, v65, 1.0
	v_cndmask_b32_e64 v52, v52, v68, s[10:11]
	v_fma_f32 v68, -v61, v66, 1.0
	v_fmac_f32_e32 v64, v69, v64
	v_div_scale_f32 v60, s[6:7], v56, v46, v56
	v_fmac_f32_e32 v65, v70, v65
	v_rsq_f32_e32 v52, v52
	v_fmac_f32_e32 v66, v68, v66
	v_mul_f32_e32 v68, v54, v64
	v_mul_f32_e32 v69, v60, v65
	v_fma_f32 v72, -v53, v68, v54
	v_div_scale_f32 v62, s[8:9], v59, v51, v59
	v_fma_f32 v73, -v55, v69, v60
	v_fmac_f32_e32 v68, v72, v64
	v_rcp_f32_e32 v67, v63
	v_mul_f32_e32 v70, v62, v66
	v_fmac_f32_e32 v69, v73, v65
	v_fma_f32 v53, -v53, v68, v54
	v_fma_f32 v75, -v61, v70, v62
	v_fma_f32 v54, -v55, v69, v60
	v_mul_f32_e32 v55, 0x45800000, v52
	v_div_fmas_f32 v53, v53, v64, v68
	s_mov_b64 vcc, s[6:7]
	v_fmac_f32_e32 v70, v75, v66
	v_cndmask_b32_e64 v52, v52, v55, s[10:11]
	v_div_fixup_f32 v47, v53, v47, v57
	v_div_fmas_f32 v53, v54, v65, v69
	v_fma_f32 v60, -v61, v70, v62
	v_mul_f32 v22, v22, v52
	v_mul_f32 v23, v23, v52
	s_mov_b64 vcc, s[8:9]
	v_fma_f32 v71, -v63, v67, 1.0
	v_mul_f32 v22, v42, v22
	v_mul_f32 v23, v43, v23
	v_div_fmas_f32 v42, v60, v66, v70
	v_mul_f32 v44, v44, v52
	v_mul_f32 v45, v45, v52
	v_div_fixup_f32 v43, v42, v51, v59
	v_fmac_f32_e32 v67, v71, v67
	v_div_scale_f32 v42, vcc, v58, v50, v58
	v_mul_f32 v40, v40, v44
	v_mul_f32 v41, v41, v45
	v_mul_f32_e32 v44, v42, v67
	v_fma_f32 v45, -v63, v44, v42
	v_fmac_f32_e32 v44, v45, v67
	v_fma_f32 v42, -v63, v44, v42
	v_div_fmas_f32 v42, v42, v67, v44
	v_div_fixup_f32 v46, v53, v46, v56
	v_div_fixup_f32 v42, v42, v50, v58
	v_mul_f32 v40, v46, v40
	v_mul_f32 v41, v47, v41
	v_mul_f32 v22, v42, v22
	v_mul_f32 v23, v43, v23
	v_lshl_add_u64 v[42:43], v[48:49], 0, v[2:3]
	v_cvt_pk_bf16_f32 v40, v40, v41
	v_cvt_pk_bf16_f32 v41, v22, v23
	v_add_co_u32_e32 v22, vcc, 0x4552000, v42
	s_mov_b64 s[8:9], 0
	s_nop 0
	v_addc_co_u32_e32 v23, vcc, 0, v43, vcc
	flat_store_dwordx2 v[22:23], v[40:41] offset:1024 sc1
	s_waitcnt vmcnt(0)
	s_mov_b64 s[6:7], 0
	s_and_saveexec_b64 s[10:11], s[4:5]
	s_xor_b64 s[10:11], exec, s[10:11]
	v_ashrrev_i64 v[22:23], 2, v[20:21]
	s_mov_b64 s[6:7], exec
	v_and_b32_e32 v22, 0xffffffc0, v22
	s_or_b64 exec, exec, s[10:11]
	s_and_b64 vcc, exec, s[8:9]
	s_cbranch_vccnz .LBB0_3164
	s_branch .LBB0_3167

.LBB0_3170:
	s_andn2_b64 vcc, exec, s[4:5]
	s_cbranch_vccnz .LBB0_3188
	s_cmpk_gt_i32 s2, 0xbf
	v_ashrrev_i32_e32 v4, 6, v74
	v_and_b32_e32 v75, 63, v74
	s_cbranch_scc0 .LBB0_3177
	s_mul_i32 s4, s2, 0x48
	s_addk_i32 s4, 0xe800
	s_mov_b32 s5, 0
	v_ashrrev_i32_e32 v5, 31, v4
	v_lshlrev_b32_e32 v8, 3, v75
	v_mov_b32_e32 v9, 0
	v_lshl_add_u64 v[6:7], s[4:5], 0, v[4:5]
	v_lshl_add_u64 v[0:1], s[18:19], 0, v[8:9]
	s_mov_b64 s[4:5], 0x6952000
	s_waitcnt vmcnt(0)
	v_lshl_add_u64 v[26:27], v[0:1], 0, s[4:5]
	s_mov_b64 s[4:5], 0x6f52000
	v_lshl_add_u64 v[28:29], v[0:1], 0, s[4:5]
	s_mov_b64 s[4:5], 0xcb32000
	v_lshlrev_b64 v[2:3], 9, v[6:7]
	v_lshl_add_u64 v[30:31], v[0:1], 0, s[4:5]
	v_lshl_add_u64 v[10:11], v[26:27], 0, v[2:3]
	v_lshl_add_u64 v[0:1], v[30:31], 0, v[2:3]
	v_lshl_add_u64 v[12:13], v[28:29], 0, v[2:3]
	flat_load_dwordx2 v[76:77], v[10:11]
	flat_load_dwordx2 v[78:79], v[12:13]
	flat_load_dwordx2 v[80:81], v[0:1]
	v_lshl_add_u64 v[10:11], v[6:7], 0, 8
	v_lshlrev_b64 v[0:1], 9, v[10:11]
	v_lshl_add_u64 v[2:3], v[26:27], 0, v[0:1]
	v_lshl_add_u64 v[12:13], v[6:7], 0, 16
	flat_load_dwordx2 v[70:71], v[2:3]
	v_lshl_add_u64 v[2:3], v[28:29], 0, v[0:1]
	v_lshl_add_u64 v[0:1], v[30:31], 0, v[0:1]
	v_lshlrev_b64 v[14:15], 9, v[12:13]
	v_lshl_add_u64 v[16:17], v[26:27], 0, v[14:15]
	v_lshl_add_u64 v[18:19], v[28:29], 0, v[14:15]
	flat_load_dwordx2 v[72:73], v[2:3]
	flat_load_dwordx2 v[68:69], v[0:1]
	flat_load_dwordx2 v[64:65], v[16:17]
	flat_load_dwordx2 v[66:67], v[18:19]
	v_lshl_add_u64 v[0:1], v[30:31], 0, v[14:15]
	v_lshl_add_u64 v[14:15], v[6:7], 0, 24
	v_lshlrev_b64 v[2:3], 9, v[14:15]
	v_lshl_add_u64 v[16:17], v[26:27], 0, v[2:3]
	v_lshl_add_u64 v[18:19], v[28:29], 0, v[2:3]
	v_lshl_add_u64 v[2:3], v[30:31], 0, v[2:3]
	flat_load_dwordx2 v[44:45], v[0:1]
	flat_load_dwordx2 v[60:61], v[16:17]
	flat_load_dwordx2 v[62:63], v[18:19]
	flat_load_dwordx2 v[58:59], v[2:3]
	v_lshl_add_u64 v[16:17], v[6:7], 0, 32
	v_lshlrev_b64 v[0:1], 9, v[16:17]
	v_lshl_add_u64 v[18:19], v[6:7], 0, 40
	v_lshl_add_u64 v[2:3], v[26:27], 0, v[0:1]
	v_lshl_add_u64 v[20:21], v[28:29], 0, v[0:1]
	v_lshlrev_b64 v[22:23], 9, v[18:19]
	s_ashr_i32 s5, s24, 31
	v_lshl_add_u64 v[0:1], v[30:31], 0, v[0:1]
	v_lshl_add_u64 v[24:25], v[26:27], 0, v[22:23]
	flat_load_dwordx2 v[54:55], v[2:3]
	flat_load_dwordx2 v[56:57], v[20:21]
	flat_load_dwordx2 v[52:53], v[0:1]
	flat_load_dwordx2 v[48:49], v[24:25]
	v_lshl_add_u64 v[20:21], v[6:7], 0, 48
	s_add_u32 s4, s0, s24
	v_lshl_add_u64 v[0:1], v[28:29], 0, v[22:23]
	v_lshl_add_u64 v[2:3], v[30:31], 0, v[22:23]
	v_lshlrev_b64 v[22:23], 9, v[20:21]
	s_addc_u32 s5, s1, s5
	v_lshl_add_u64 v[24:25], v[26:27], 0, v[22:23]
	v_lshl_add_u64 v[32:33], v[28:29], 0, v[22:23]
	flat_load_dwordx2 v[50:51], v[0:1]
	flat_load_dwordx2 v[46:47], v[2:3]
	flat_load_dwordx2 v[38:39], v[24:25]
	flat_load_dwordx2 v[40:41], v[32:33]
	s_load_dwordx2 s[4:5], s[4:5], 0xb8
	v_lshl_add_u64 v[0:1], v[30:31], 0, v[22:23]
	v_lshl_add_u64 v[22:23], v[6:7], 0, 56
	v_lshlrev_b64 v[2:3], 9, v[22:23]
	v_lshl_add_u64 v[24:25], v[26:27], 0, v[2:3]
	v_lshl_add_u64 v[82:83], v[28:29], 0, v[2:3]
	v_lshl_add_u64 v[2:3], v[30:31], 0, v[2:3]
	flat_load_dwordx2 v[42:43], v[0:1]
	flat_load_dwordx2 v[34:35], v[24:25]
	flat_load_dwordx2 v[36:37], v[82:83]
	flat_load_dwordx2 v[32:33], v[2:3]
	v_lshlrev_b32_e32 v0, 4, v74
	v_and_b32_e32 v0, 0xf0, v0
	s_waitcnt lgkmcnt(0)
	global_load_dwordx4 v[0:3], v0, s[4:5] offset:256
	v_lshl_add_u64 v[24:25], v[6:7], 0, 64
	v_lshlrev_b64 v[82:83], 9, v[24:25]
	v_lshl_add_u64 v[84:85], v[26:27], 0, v[82:83]
	v_lshl_add_u64 v[86:87], v[28:29], 0, v[82:83]
	v_lshl_add_u64 v[82:83], v[30:31], 0, v[82:83]
	flat_load_dwordx2 v[28:29], v[84:85]
	flat_load_dwordx2 v[30:31], v[86:87]
	flat_load_dwordx2 v[26:27], v[82:83]
	s_mov_b32 s7, 0x800000
	s_mov_b32 s8, 0x4552000
	s_mov_b32 s6, 0x3c800000
	s_mov_b64 s[10:11], 0
	s_waitcnt vmcnt(0)
	v_lshlrev_b32_e32 v82, 16, v76
	v_lshlrev_b32_e32 v84, 16, v78
	v_lshlrev_b32_e32 v5, 16, v80
	v_and_b32_e32 v88, 0xffff0000, v80
	v_mul_f32_e32 v80, 0xbfb8aa3b, v5
	v_exp_f32_e32 v86, v80
	v_mul_f32_e32 v80, 0xbfb8aa3b, v88
	v_exp_f32_e32 v87, v80
	v_and_b32_e32 v83, 0xffff0000, v76
	v_and_b32_e32 v85, 0xffff0000, v78
	v_lshlrev_b32_e32 v76, 16, v77
	v_lshlrev_b32_e32 v78, 16, v79
	v_and_b32_e32 v77, 0xffff0000, v77
	v_and_b32_e32 v79, 0xffff0000, v79
	v_add_f32 v76, v76, v78
	v_add_f32 v77, v77, v79
	v_add_f32 v78, v86, 1.0
	v_add_f32 v79, v87, 1.0
	v_add_f32 v82, v82, v84
	v_add_f32 v83, v83, v85
	v_div_scale_f32 v86, s[4:5], v79, v79, v88
	v_rcp_f32_e32 v87, v86
	v_mul_f32 v84, v82, v82
	v_mul_f32 v85, v83, v83
	v_lshlrev_b32_e32 v89, 16, v81
	v_and_b32_e32 v90, 0xffff0000, v81
	v_fma_f32 v91, -v86, v87, 1.0
	v_fmac_f32_e32 v87, v91, v87
	v_div_scale_f32 v91, vcc, v88, v79, v88
	v_mul_f32_e32 v92, v91, v87
	v_fma_f32 v93, -v86, v92, v91
	v_fmac_f32_e32 v92, v93, v87
	v_fma_f32 v86, -v86, v92, v91
	v_div_scale_f32 v91, s[4:5], v78, v78, v5
	v_mul_f32 v80, v76, v76
	v_mul_f32 v81, v77, v77
	v_rcp_f32_e32 v93, v91
	v_add_f32_e32 v84, v84, v85
	v_add_f32_e32 v80, v84, v80
	v_add_f32_e32 v80, v81, v80
	v_div_fmas_f32 v86, v86, v87, v92
	v_div_fixup_f32 v79, v86, v79, v88
	v_add_f32_dpp v80, v80, v80 quad_perm:[1,0,3,2] row_mask:0xf bank_mask:0xf bound_ctrl:1
	v_fma_f32 v86, -v91, v93, 1.0
	v_fmac_f32_e32 v93, v86, v93
	v_add_f32_dpp v80, v80, v80 quad_perm:[2,3,0,1] row_mask:0xf bank_mask:0xf bound_ctrl:1
	v_div_scale_f32 v86, vcc, v5, v78, v5
	s_nop 0
	v_add_f32_dpp v80, v80, v80 row_half_mirror row_mask:0xf bank_mask:0xf bound_ctrl:1
	v_mul_f32_e32 v87, v86, v93
	v_mov_b32_e32 v81, 0x358637bd
	v_add_f32_dpp v80, v80, v80 row_mirror row_mask:0xf bank_mask:0xf bound_ctrl:1
	v_fma_f32 v88, -v91, v87, v86
	v_fmac_f32_e32 v81, 0x3c800000, v80
	v_fmac_f32_e32 v87, v88, v93
	v_mul_f32_e32 v80, 0x4b800000, v81
	v_cmp_gt_f32_e64 s[4:5], s7, v81
	v_fma_f32 v86, -v91, v87, v86
	v_lshlrev_b32_e32 v91, 16, v45
	v_cndmask_b32_e64 v80, v81, v80, s[4:5]
	v_rsq_f32_e32 v84, v80
	v_div_fmas_f32 v80, v86, v93, v87
	v_div_fixup_f32 v78, v80, v78, v5
	v_mul_f32_e32 v80, 0xbfb8aa3b, v89
	v_mul_f32_e32 v81, 0xbfb8aa3b, v90
	v_exp_f32_e32 v80, v80
	v_exp_f32_e32 v81, v81
	v_mul_f32_e32 v5, 0x45800000, v84
	v_cndmask_b32_e64 v84, v84, v5, s[4:5]
	v_mul_f32 v82, v82, v84
	v_mul_f32 v83, v83, v84
	v_add_f32 v80, v80, 1.0
	v_add_f32 v81, v81, 1.0
	v_mul_f32 v82, v0, v82
	v_mul_f32 v83, v1, v83
	v_div_scale_f32 v5, s[4:5], v81, v81, v90
	v_rcp_f32_e32 v85, v5
	v_mul_f32 v78, v78, v82
	v_mul_f32 v79, v79, v83
	v_and_b32_e32 v92, 0xffff0000, v45
	v_cvt_pk_bf16_f32 v78, v78, v79
	v_fma_f32 v82, -v5, v85, 1.0
	v_mul_f32 v76, v76, v84
	v_mul_f32 v77, v77, v84
	v_fmac_f32_e32 v85, v82, v85
	v_div_scale_f32 v82, vcc, v90, v81, v90
	v_mul_f32_e32 v83, v82, v85
	v_fma_f32 v84, -v5, v83, v82
	v_fmac_f32_e32 v83, v84, v85
	v_fma_f32 v5, -v5, v83, v82
	v_div_scale_f32 v82, s[4:5], v80, v80, v89
	v_rcp_f32_e32 v84, v82
	v_div_fmas_f32 v5, v5, v85, v83
	v_div_fixup_f32 v81, v5, v81, v90
	v_mul_f32 v76, v2, v76
	v_mul_f32 v77, v3, v77
	v_fma_f32 v5, -v82, v84, 1.0
	v_fmac_f32_e32 v84, v5, v84
	v_div_scale_f32 v5, vcc, v89, v80, v89
	v_mul_f32_e32 v83, v5, v84
	v_fma_f32 v85, -v82, v83, v5
	v_fmac_f32_e32 v83, v85, v84
	v_fma_f32 v5, -v82, v83, v5
	v_div_fmas_f32 v5, v5, v84, v83
	v_div_fixup_f32 v80, v5, v80, v89
	v_mul_f32 v76, v80, v76
	v_mul_f32 v77, v81, v77
	v_lshlrev_b32_e32 v5, 16, v68
	v_cvt_pk_bf16_f32 v79, v76, v77
	v_lshlrev_b64 v[76:77], 11, v[6:7]
	v_and_b32_e32 v82, 0xffff0000, v68
	v_mul_f32_e32 v68, 0xbfb8aa3b, v5
	v_lshl_add_u64 v[76:77], s[18:19], 0, v[76:77]
	v_exp_f32_e32 v80, v68
	v_mul_f32_e32 v68, 0xbfb8aa3b, v82
	v_lshl_add_u64 v[76:77], v[76:77], 0, v[8:9]
	v_exp_f32_e32 v81, v68
	v_add_co_u32_e32 v76, vcc, s8, v76
	v_lshlrev_b32_e32 v83, 16, v69
	s_nop 0
	v_addc_co_u32_e32 v77, vcc, 0, v77, vcc
	flat_store_dwordx2 v[76:77], v[78:79] offset:1024 sc1
	v_lshlrev_b32_e32 v76, 16, v70
	v_lshlrev_b32_e32 v78, 16, v72
	v_and_b32_e32 v77, 0xffff0000, v70
	v_and_b32_e32 v79, 0xffff0000, v72
	v_lshlrev_b32_e32 v70, 16, v71
	v_lshlrev_b32_e32 v72, 16, v73
	v_and_b32_e32 v71, 0xffff0000, v71
	v_and_b32_e32 v73, 0xffff0000, v73
	v_and_b32_e32 v84, 0xffff0000, v69
	v_add_f32 v68, v70, v72
	v_add_f32 v69, v71, v73
	v_add_f32 v70, v80, 1.0
	v_add_f32 v71, v81, 1.0
	v_and_b32_e32 v90, 0xffff0000, v44
	v_div_scale_f32 v80, s[4:5], v71, v71, v82
	v_rcp_f32_e32 v81, v80
	v_add_f32 v76, v76, v78
	v_add_f32 v77, v77, v79
	v_mul_f32 v72, v68, v68
	v_mul_f32 v73, v69, v69
	v_mul_f32 v78, v76, v76
	v_mul_f32 v79, v77, v77
	v_fma_f32 v85, -v80, v81, 1.0
	v_fmac_f32_e32 v81, v85, v81
	v_div_scale_f32 v85, vcc, v82, v71, v82
	v_mul_f32_e32 v86, v85, v81
	v_fma_f32 v87, -v80, v86, v85
	v_fmac_f32_e32 v86, v87, v81
	v_fma_f32 v80, -v80, v86, v85
	v_div_scale_f32 v85, s[4:5], v70, v70, v5
	v_rcp_f32_e32 v87, v85
	v_div_fmas_f32 v80, v80, v81, v86
	v_div_fixup_f32 v71, v80, v71, v82
	v_mul_f32_e32 v81, 0xbfb8aa3b, v84
	v_fma_f32 v80, -v85, v87, 1.0
	v_fmac_f32_e32 v87, v80, v87
	v_mul_f32_e32 v80, 0xbfb8aa3b, v83
	v_exp_f32_e32 v80, v80
	v_exp_f32_e32 v81, v81
	v_div_scale_f32 v82, vcc, v5, v70, v5
	v_mul_f32_e32 v86, v82, v87
	v_fma_f32 v88, -v85, v86, v82
	v_fmac_f32_e32 v86, v88, v87
	v_add_f32 v80, v80, 1.0
	v_add_f32 v81, v81, 1.0
	v_fma_f32 v82, -v85, v86, v82
	v_div_scale_f32 v85, s[4:5], v81, v81, v84
	v_rcp_f32_e32 v88, v85
	v_div_fmas_f32 v82, v82, v87, v86
	v_div_fixup_f32 v70, v82, v70, v5
	v_and_b32_e32 v87, 0xffff0000, v66
	v_fma_f32 v5, -v85, v88, 1.0
	v_fmac_f32_e32 v88, v5, v88
	v_div_scale_f32 v5, vcc, v84, v81, v84
	v_mul_f32_e32 v82, v5, v88
	v_fma_f32 v86, -v85, v82, v5
	v_fmac_f32_e32 v82, v86, v88
	v_fma_f32 v5, -v85, v82, v5
	v_div_scale_f32 v85, s[4:5], v80, v80, v83
	v_rcp_f32_e32 v86, v85
	v_div_fmas_f32 v5, v5, v88, v82
	v_div_fixup_f32 v81, v5, v81, v84
	v_fma_f32 v5, -v85, v86, 1.0
	v_fmac_f32_e32 v86, v5, v86
	v_div_scale_f32 v5, vcc, v83, v80, v83
	v_mul_f32_e32 v82, v5, v86
	v_fma_f32 v84, -v85, v82, v5
	v_fmac_f32_e32 v82, v84, v86
	v_fma_f32 v5, -v85, v82, v5
	v_div_fmas_f32 v5, v5, v86, v82
	v_div_fixup_f32 v80, v5, v80, v83
	v_lshlrev_b32_e32 v5, 16, v44
	v_mul_f32_e32 v44, 0xbfb8aa3b, v5
	v_exp_f32_e32 v88, v44
	v_mul_f32_e32 v44, 0xbfb8aa3b, v90
	v_exp_f32_e32 v89, v44
	v_lshlrev_b32_e32 v84, 16, v64
	v_lshlrev_b32_e32 v86, 16, v66
	v_and_b32_e32 v85, 0xffff0000, v64
	v_lshlrev_b32_e32 v64, 16, v65
	v_lshlrev_b32_e32 v66, 16, v67
	v_and_b32_e32 v65, 0xffff0000, v65
	v_and_b32_e32 v67, 0xffff0000, v67
	v_add_f32 v64, v64, v66
	v_add_f32 v65, v65, v67
	v_add_f32 v66, v88, 1.0
	v_add_f32 v67, v89, 1.0
	v_add_f32 v84, v84, v86
	v_add_f32 v85, v85, v87
	v_div_scale_f32 v88, s[4:5], v67, v67, v90
	v_rcp_f32_e32 v89, v88
	v_mul_f32 v86, v84, v84
	v_mul_f32 v87, v85, v85
	v_mul_f32 v44, v64, v64
	v_mul_f32 v45, v65, v65
	v_lshlrev_b64 v[82:83], 11, v[10:11]
	v_fma_f32 v93, -v88, v89, 1.0
	v_fmac_f32_e32 v89, v93, v89
	v_div_scale_f32 v93, vcc, v90, v67, v90
	v_mul_f32_e32 v94, v93, v89
	v_fma_f32 v95, -v88, v94, v93
	v_fmac_f32_e32 v94, v95, v89
	v_fma_f32 v88, -v88, v94, v93
	v_div_scale_f32 v93, s[4:5], v66, v66, v5
	v_rcp_f32_e32 v95, v93
	v_div_fmas_f32 v88, v88, v89, v94
	v_div_fixup_f32 v67, v88, v67, v90
	s_mov_b32 s4, 0x358637bd
	v_fma_f32 v88, -v93, v95, 1.0
	v_fmac_f32_e32 v95, v88, v95
	v_div_scale_f32 v88, vcc, v5, v66, v5
	v_mul_f32_e32 v90, v88, v95
	v_fma_f32 v89, -v93, v90, v88
	v_fmac_f32_e32 v90, v89, v95
	v_fma_f32 v93, -v93, v90, v88
	v_mov_b32_e32 v88, v86
	v_mov_b32_e32 v89, v78
	v_mov_b32_e32 v78, v87
	v_add_f32 v78, v88, v78
	v_add_f32 v79, v89, v79
	v_mov_b32_e32 v86, v44
	v_mov_b32_e32 v87, v72
	v_add_f32 v78, v78, v86
	v_add_f32 v79, v79, v87
	v_mov_b32_e32 v72, v45
	v_add_f32 v44, v72, v78
	v_add_f32 v45, v73, v79
	v_lshl_add_u64 v[82:83], s[18:19], 0, v[82:83]
	v_lshl_add_u64 v[82:83], v[82:83], 0, v[8:9]
	v_mov_b32_dpp v73, v45 quad_perm:[1,0,3,2] row_mask:0xf bank_mask:0xf bound_ctrl:1
	v_mov_b32_dpp v72, v44 quad_perm:[1,0,3,2] row_mask:0xf bank_mask:0xf bound_ctrl:1
	v_add_f32 v44, v44, v72
	v_add_f32 v45, v45, v73
	s_nop 1
	v_mov_b32_dpp v73, v45 quad_perm:[2,3,0,1] row_mask:0xf bank_mask:0xf bound_ctrl:1
	v_mov_b32_dpp v72, v44 quad_perm:[2,3,0,1] row_mask:0xf bank_mask:0xf bound_ctrl:1
	v_add_f32 v44, v44, v72
	v_add_f32 v45, v45, v73
	s_nop 1
	v_mov_b32_dpp v73, v45 row_half_mirror row_mask:0xf bank_mask:0xf bound_ctrl:1
	v_mov_b32_dpp v72, v44 row_half_mirror row_mask:0xf bank_mask:0xf bound_ctrl:1
	v_add_f32 v44, v44, v72
	v_add_f32 v45, v45, v73
	s_nop 1
	v_mov_b32_dpp v73, v45 row_mirror row_mask:0xf bank_mask:0xf bound_ctrl:1
	v_mov_b32_dpp v72, v44 row_mirror row_mask:0xf bank_mask:0xf bound_ctrl:1
	v_add_f32 v72, v44, v72
	v_add_f32 v73, v45, v73
	v_mov_b64_e32 v[44:45], s[4:5]
	v_fma_f32 v72, v72, s6, v44
	v_fma_f32 v73, v73, s6, v44
	s_nop 0
	v_mul_f32_e32 v78, 0x4b800000, v73
	v_cmp_gt_f32_e64 s[4:5], s7, v73
	s_nop 1
	v_cndmask_b32_e64 v73, v73, v78, s[4:5]
	v_rsq_f32_e32 v73, v73
	v_div_fmas_f32 v78, v93, v95, v90
	v_div_fixup_f32 v66, v78, v66, v5
	v_cmp_gt_f32_e32 vcc, s7, v72
	v_mul_f32_e32 v5, 0x45800000, v73
	v_cndmask_b32_e64 v78, v73, v5, s[4:5]
	v_mul_f32 v76, v76, v78
	v_mul_f32 v77, v77, v78
	v_mul_f32 v68, v68, v78
	v_mul_f32 v69, v69, v78
	v_mul_f32 v76, v0, v76
	v_mul_f32 v77, v1, v77
	v_mul_f32 v68, v2, v68
	v_mul_f32 v69, v3, v69
	v_mul_f32 v70, v70, v76
	v_mul_f32 v71, v71, v77
	v_mul_f32 v68, v80, v68
	v_mul_f32 v69, v81, v69
	v_cvt_pk_bf16_f32 v70, v70, v71
	v_cvt_pk_bf16_f32 v71, v68, v69
	v_add_co_u32_e64 v68, s[4:5], s8, v82
	v_mul_f32_e32 v5, 0x4b800000, v72
	s_nop 0
	v_addc_co_u32_e64 v69, s[4:5], 0, v83, s[4:5]
	v_cndmask_b32_e32 v5, v72, v5, vcc
	flat_store_dwordx2 v[68:69], v[70:71] offset:1024 sc1
	v_mul_f32_e32 v68, 0xbfb8aa3b, v91
	v_mul_f32_e32 v69, 0xbfb8aa3b, v92
	v_rsq_f32_e32 v5, v5
	v_exp_f32_e32 v68, v68
	v_exp_f32_e32 v69, v69
	v_and_b32_e32 v80, 0xffff0000, v52
	v_mul_f32_e32 v70, 0x45800000, v5
	v_cndmask_b32_e32 v70, v5, v70, vcc
	v_add_f32 v68, v68, 1.0
	v_add_f32 v69, v69, 1.0
	v_mul_f32 v72, v84, v70
	v_mul_f32 v73, v85, v70
	v_div_scale_f32 v5, s[4:5], v69, v69, v92
	v_rcp_f32_e32 v71, v5
	v_mul_f32 v72, v0, v72
	v_mul_f32 v73, v1, v73
	v_lshlrev_b32_e32 v81, 16, v53
	v_mul_f32 v66, v66, v72
	v_mul_f32 v67, v67, v73
	v_mul_f32 v64, v64, v70
	v_mul_f32 v65, v65, v70
	v_fma_f32 v70, -v5, v71, 1.0
	v_fmac_f32_e32 v71, v70, v71
	v_div_scale_f32 v70, vcc, v92, v69, v92
	v_mul_f32_e32 v72, v70, v71
	v_fma_f32 v73, -v5, v72, v70
	v_fmac_f32_e32 v72, v73, v71
	v_fma_f32 v5, -v5, v72, v70
	v_div_scale_f32 v70, s[4:5], v68, v68, v91
	v_rcp_f32_e32 v73, v70
	v_div_fmas_f32 v5, v5, v71, v72
	v_div_fixup_f32 v69, v5, v69, v92
	v_mul_f32 v64, v2, v64
	v_mul_f32 v65, v3, v65
	v_fma_f32 v5, -v70, v73, 1.0
	v_fmac_f32_e32 v73, v5, v73
	v_div_scale_f32 v5, vcc, v91, v68, v91
	v_mul_f32_e32 v71, v5, v73
	v_fma_f32 v72, -v70, v71, v5
	v_fmac_f32_e32 v71, v72, v73
	v_fma_f32 v5, -v70, v71, v5
	v_div_fmas_f32 v5, v5, v73, v71
	v_div_fixup_f32 v68, v5, v68, v91
	v_mul_f32 v64, v68, v64
	v_mul_f32 v65, v69, v65
	v_lshlrev_b32_e32 v5, 16, v58
	v_cvt_pk_bf16_f32 v66, v66, v67
	v_cvt_pk_bf16_f32 v67, v64, v65
	v_lshlrev_b64 v[64:65], 11, v[12:13]
	v_and_b32_e32 v70, 0xffff0000, v58
	v_mul_f32_e32 v58, 0xbfb8aa3b, v5
	v_lshl_add_u64 v[64:65], s[18:19], 0, v[64:65]
	v_exp_f32_e32 v68, v58
	v_mul_f32_e32 v58, 0xbfb8aa3b, v70
	v_lshl_add_u64 v[64:65], v[64:65], 0, v[8:9]
	v_exp_f32_e32 v69, v58
	v_add_co_u32_e32 v64, vcc, s8, v64
	v_lshlrev_b32_e32 v71, 16, v59
	s_nop 0
	v_addc_co_u32_e32 v65, vcc, 0, v65, vcc
	flat_store_dwordx2 v[64:65], v[66:67] offset:1024 sc1
	v_lshlrev_b32_e32 v64, 16, v60
	v_lshlrev_b32_e32 v66, 16, v62
	v_and_b32_e32 v65, 0xffff0000, v60
	v_and_b32_e32 v67, 0xffff0000, v62
	v_lshlrev_b32_e32 v60, 16, v61
	v_lshlrev_b32_e32 v62, 16, v63
	v_and_b32_e32 v61, 0xffff0000, v61
	v_and_b32_e32 v63, 0xffff0000, v63
	v_and_b32_e32 v72, 0xffff0000, v59
	v_add_f32 v58, v60, v62
	v_add_f32 v59, v61, v63
	v_add_f32 v60, v68, 1.0
	v_add_f32 v61, v69, 1.0
	v_and_b32_e32 v82, 0xffff0000, v53
	v_div_scale_f32 v68, s[4:5], v61, v61, v70
	v_rcp_f32_e32 v69, v68
	v_add_f32 v64, v64, v66
	v_add_f32 v65, v65, v67
	v_mul_f32 v62, v58, v58
	v_mul_f32 v63, v59, v59
	v_mul_f32 v66, v64, v64
	v_mul_f32 v67, v65, v65
	v_fma_f32 v73, -v68, v69, 1.0
	v_fmac_f32_e32 v69, v73, v69
	v_div_scale_f32 v73, vcc, v70, v61, v70
	v_mul_f32_e32 v76, v73, v69
	v_fma_f32 v77, -v68, v76, v73
	v_fmac_f32_e32 v76, v77, v69
	v_fma_f32 v68, -v68, v76, v73
	v_div_scale_f32 v73, s[4:5], v60, v60, v5
	v_rcp_f32_e32 v77, v73
	v_div_fmas_f32 v68, v68, v69, v76
	v_div_fixup_f32 v61, v68, v61, v70
	v_mul_f32_e32 v69, 0xbfb8aa3b, v72
	v_fma_f32 v68, -v73, v77, 1.0
	v_fmac_f32_e32 v77, v68, v77
	v_mul_f32_e32 v68, 0xbfb8aa3b, v71
	v_exp_f32_e32 v68, v68
	v_exp_f32_e32 v69, v69
	v_div_scale_f32 v70, vcc, v5, v60, v5
	v_mul_f32_e32 v76, v70, v77
	v_fma_f32 v78, -v73, v76, v70
	v_fmac_f32_e32 v76, v78, v77
	v_add_f32 v68, v68, 1.0
	v_add_f32 v69, v69, 1.0
	v_fma_f32 v70, -v73, v76, v70
	v_div_scale_f32 v73, s[4:5], v69, v69, v72
	v_rcp_f32_e32 v78, v73
	v_div_fmas_f32 v70, v70, v77, v76
	v_div_fixup_f32 v60, v70, v60, v5
	v_and_b32_e32 v77, 0xffff0000, v56
	v_fma_f32 v5, -v73, v78, 1.0
	v_fmac_f32_e32 v78, v5, v78
	v_div_scale_f32 v5, vcc, v72, v69, v72
	v_mul_f32_e32 v70, v5, v78
	v_fma_f32 v76, -v73, v70, v5
	v_fmac_f32_e32 v70, v76, v78
	v_fma_f32 v5, -v73, v70, v5
	v_div_scale_f32 v73, s[4:5], v68, v68, v71
	v_rcp_f32_e32 v76, v73
	v_div_fmas_f32 v5, v5, v78, v70
	v_div_fixup_f32 v69, v5, v69, v72
	v_fma_f32 v5, -v73, v76, 1.0
	v_fmac_f32_e32 v76, v5, v76
	v_div_scale_f32 v5, vcc, v71, v68, v71
	v_mul_f32_e32 v70, v5, v76
	v_fma_f32 v72, -v73, v70, v5
	v_fmac_f32_e32 v70, v72, v76
	v_fma_f32 v5, -v73, v70, v5
	v_div_fmas_f32 v5, v5, v76, v70
	v_div_fixup_f32 v68, v5, v68, v71
	v_lshlrev_b32_e32 v5, 16, v52
	v_mul_f32_e32 v52, 0xbfb8aa3b, v5
	v_exp_f32_e32 v78, v52
	v_mul_f32_e32 v52, 0xbfb8aa3b, v80
	v_exp_f32_e32 v79, v52
	v_lshlrev_b32_e32 v72, 16, v54
	v_lshlrev_b32_e32 v76, 16, v56
	v_and_b32_e32 v73, 0xffff0000, v54
	v_lshlrev_b32_e32 v54, 16, v55
	v_lshlrev_b32_e32 v56, 16, v57
	v_and_b32_e32 v55, 0xffff0000, v55
	v_and_b32_e32 v57, 0xffff0000, v57
	v_add_f32 v52, v54, v56
	v_add_f32 v53, v55, v57
	v_add_f32 v54, v78, 1.0
	v_add_f32 v55, v79, 1.0
	v_add_f32 v72, v72, v76
	v_add_f32 v73, v73, v77
	v_div_scale_f32 v78, s[4:5], v55, v55, v80
	v_rcp_f32_e32 v79, v78
	v_mul_f32 v76, v72, v72
	v_mul_f32 v77, v73, v73
	v_mul_f32 v56, v52, v52
	v_mul_f32 v57, v53, v53
	v_lshlrev_b64 v[70:71], 11, v[14:15]
	v_fma_f32 v83, -v78, v79, 1.0
	v_fmac_f32_e32 v79, v83, v79
	v_div_scale_f32 v83, vcc, v80, v55, v80
	v_mul_f32_e32 v84, v83, v79
	v_fma_f32 v85, -v78, v84, v83
	v_fmac_f32_e32 v84, v85, v79
	v_fma_f32 v78, -v78, v84, v83
	v_div_scale_f32 v83, s[4:5], v54, v54, v5
	v_rcp_f32_e32 v85, v83
	v_div_fmas_f32 v78, v78, v79, v84
	v_div_fixup_f32 v55, v78, v55, v80
	v_lshl_add_u64 v[70:71], s[18:19], 0, v[70:71]
	v_fma_f32 v78, -v83, v85, 1.0
	v_fmac_f32_e32 v85, v78, v85
	v_div_scale_f32 v78, vcc, v5, v54, v5
	v_mul_f32_e32 v80, v78, v85
	v_fma_f32 v79, -v83, v80, v78
	v_fmac_f32_e32 v80, v79, v85
	v_fma_f32 v83, -v83, v80, v78
	v_mov_b32_e32 v78, v76
	v_mov_b32_e32 v79, v66
	v_mov_b32_e32 v66, v77
	v_add_f32 v66, v78, v66
	v_add_f32 v67, v79, v67
	v_mov_b32_e32 v76, v56
	v_mov_b32_e32 v77, v62
	v_add_f32 v66, v66, v76
	v_add_f32 v67, v67, v77
	v_mov_b32_e32 v62, v57
	v_add_f32 v56, v62, v66
	v_add_f32 v57, v63, v67
	v_lshl_add_u64 v[70:71], v[70:71], 0, v[8:9]
	v_and_b32_e32 v66, 0xffff0000, v42
	v_mov_b32_dpp v63, v57 quad_perm:[1,0,3,2] row_mask:0xf bank_mask:0xf bound_ctrl:1
	v_mov_b32_dpp v62, v56 quad_perm:[1,0,3,2] row_mask:0xf bank_mask:0xf bound_ctrl:1
	v_add_f32 v56, v56, v62
	v_add_f32 v57, v57, v63
	v_lshlrev_b32_e32 v67, 16, v43
	s_nop 0
	v_mov_b32_dpp v63, v57 quad_perm:[2,3,0,1] row_mask:0xf bank_mask:0xf bound_ctrl:1
	v_mov_b32_dpp v62, v56 quad_perm:[2,3,0,1] row_mask:0xf bank_mask:0xf bound_ctrl:1
	v_add_f32 v56, v56, v62
	v_add_f32 v57, v57, v63
	s_nop 1
	v_mov_b32_dpp v63, v57 row_half_mirror row_mask:0xf bank_mask:0xf bound_ctrl:1
	v_mov_b32_dpp v62, v56 row_half_mirror row_mask:0xf bank_mask:0xf bound_ctrl:1
	v_add_f32 v56, v56, v62
	v_add_f32 v57, v57, v63
	s_nop 1
	v_mov_b32_dpp v63, v57 row_mirror row_mask:0xf bank_mask:0xf bound_ctrl:1
	v_mov_b32_dpp v62, v56 row_mirror row_mask:0xf bank_mask:0xf bound_ctrl:1
	v_add_f32 v56, v56, v62
	v_add_f32 v57, v57, v63
	s_nop 0
	v_fma_f32 v56, v56, s6, v44
	v_fma_f32 v57, v57, s6, v44
	s_nop 0
	v_mul_f32_e32 v62, 0x4b800000, v57
	v_cmp_gt_f32_e64 s[4:5], s7, v57
	s_nop 1
	v_cndmask_b32_e64 v57, v57, v62, s[4:5]
	v_rsq_f32_e32 v57, v57
	v_div_fmas_f32 v62, v83, v85, v80
	v_div_fixup_f32 v54, v62, v54, v5
	v_cmp_gt_f32_e32 vcc, s7, v56
	v_mul_f32_e32 v5, 0x45800000, v57
	v_cndmask_b32_e64 v62, v57, v5, s[4:5]
	v_mul_f32 v64, v64, v62
	v_mul_f32 v65, v65, v62
	v_mul_f32 v58, v58, v62
	v_mul_f32 v59, v59, v62
	v_mul_f32 v64, v0, v64
	v_mul_f32 v65, v1, v65
	v_mul_f32 v58, v2, v58
	v_mul_f32 v59, v3, v59
	v_mul_f32_e32 v5, 0x4b800000, v56
	v_mul_f32 v60, v60, v64
	v_mul_f32 v61, v61, v65
	v_mul_f32 v58, v68, v58
	v_mul_f32 v59, v69, v59
	v_cndmask_b32_e32 v5, v56, v5, vcc
	v_add_co_u32_e64 v56, s[4:5], s8, v70
	v_cvt_pk_bf16_f32 v60, v60, v61
	v_cvt_pk_bf16_f32 v61, v58, v59
	v_addc_co_u32_e64 v57, s[4:5], 0, v71, s[4:5]
	flat_store_dwordx2 v[56:57], v[60:61] offset:1024 sc1
	v_mul_f32_e32 v56, 0xbfb8aa3b, v81
	v_mul_f32_e32 v57, 0xbfb8aa3b, v82
	v_rsq_f32_e32 v5, v5
	v_exp_f32_e32 v56, v56
	v_exp_f32_e32 v57, v57
	v_and_b32_e32 v68, 0xffff0000, v43
	v_mul_f32_e32 v58, 0x45800000, v5
	v_cndmask_b32_e32 v58, v5, v58, vcc
	v_add_f32 v56, v56, 1.0
	v_add_f32 v57, v57, 1.0
	v_mul_f32 v60, v72, v58
	v_mul_f32 v61, v73, v58
	v_div_scale_f32 v5, s[4:5], v57, v57, v82
	v_rcp_f32_e32 v59, v5
	v_mul_f32 v60, v0, v60
	v_mul_f32 v61, v1, v61
	v_mul_f32 v52, v52, v58
	v_mul_f32 v53, v53, v58
	v_fma_f32 v58, -v5, v59, 1.0
	v_fmac_f32_e32 v59, v58, v59
	v_div_scale_f32 v58, vcc, v82, v57, v82
	v_mul_f32 v54, v54, v60
	v_mul_f32 v55, v55, v61
	v_mul_f32_e32 v60, v58, v59
	v_fma_f32 v61, -v5, v60, v58
	v_fmac_f32_e32 v60, v61, v59
	v_fma_f32 v5, -v5, v60, v58
	v_div_scale_f32 v58, s[4:5], v56, v56, v81
	v_rcp_f32_e32 v61, v58
	v_div_fmas_f32 v5, v5, v59, v60
	v_div_fixup_f32 v57, v5, v57, v82
	v_mul_f32 v52, v2, v52
	v_mul_f32 v53, v3, v53
	v_fma_f32 v5, -v58, v61, 1.0
	v_fmac_f32_e32 v61, v5, v61
	v_div_scale_f32 v5, vcc, v81, v56, v81
	v_mul_f32_e32 v59, v5, v61
	v_fma_f32 v60, -v58, v59, v5
	v_fmac_f32_e32 v59, v60, v61
	v_fma_f32 v5, -v58, v59, v5
	v_div_fmas_f32 v5, v5, v61, v59
	v_div_fixup_f32 v56, v5, v56, v81
	v_mul_f32 v52, v56, v52
	v_mul_f32 v53, v57, v53
	v_lshlrev_b32_e32 v5, 16, v46
	v_cvt_pk_bf16_f32 v54, v54, v55
	v_cvt_pk_bf16_f32 v55, v52, v53
	v_lshlrev_b64 v[52:53], 11, v[16:17]
	v_and_b32_e32 v58, 0xffff0000, v46
	v_mul_f32_e32 v46, 0xbfb8aa3b, v5
	v_lshl_add_u64 v[52:53], s[18:19], 0, v[52:53]
	v_exp_f32_e32 v56, v46
	v_mul_f32_e32 v46, 0xbfb8aa3b, v58
	v_lshl_add_u64 v[52:53], v[52:53], 0, v[8:9]
	v_exp_f32_e32 v57, v46
	v_add_co_u32_e32 v52, vcc, s8, v52
	v_lshlrev_b32_e32 v59, 16, v47
	s_nop 0
	v_addc_co_u32_e32 v53, vcc, 0, v53, vcc
	flat_store_dwordx2 v[52:53], v[54:55] offset:1024 sc1
	v_lshlrev_b32_e32 v52, 16, v48
	v_lshlrev_b32_e32 v54, 16, v50
	v_and_b32_e32 v53, 0xffff0000, v48
	v_and_b32_e32 v55, 0xffff0000, v50
	v_lshlrev_b32_e32 v48, 16, v49
	v_lshlrev_b32_e32 v50, 16, v51
	v_and_b32_e32 v49, 0xffff0000, v49
	v_and_b32_e32 v51, 0xffff0000, v51
	v_and_b32_e32 v60, 0xffff0000, v47
	v_add_f32 v46, v48, v50
	v_add_f32 v47, v49, v51
	v_add_f32 v48, v56, 1.0
	v_add_f32 v49, v57, 1.0
	v_add_f32 v52, v52, v54
	v_add_f32 v53, v53, v55
	v_div_scale_f32 v56, s[4:5], v49, v49, v58
	v_rcp_f32_e32 v57, v56
	v_mul_f32 v54, v52, v52
	v_mul_f32 v55, v53, v53
	v_mul_f32 v50, v46, v46
	v_mul_f32 v51, v47, v47
	v_fma_f32 v61, -v56, v57, 1.0
	v_fmac_f32_e32 v57, v61, v57
	v_div_scale_f32 v61, vcc, v58, v49, v58
	v_mul_f32_e32 v62, v61, v57
	v_fma_f32 v63, -v56, v62, v61
	v_fmac_f32_e32 v62, v63, v57
	v_fma_f32 v56, -v56, v62, v61
	v_div_scale_f32 v61, s[4:5], v48, v48, v5
	v_rcp_f32_e32 v63, v61
	v_div_fmas_f32 v56, v56, v57, v62
	v_div_fixup_f32 v49, v56, v49, v58
	v_mul_f32_e32 v57, 0xbfb8aa3b, v60
	v_fma_f32 v56, -v61, v63, 1.0
	v_fmac_f32_e32 v63, v56, v63
	v_mul_f32_e32 v56, 0xbfb8aa3b, v59
	v_exp_f32_e32 v56, v56
	v_exp_f32_e32 v57, v57
	v_div_scale_f32 v58, vcc, v5, v48, v5
	v_mul_f32_e32 v62, v58, v63
	v_fma_f32 v64, -v61, v62, v58
	v_fmac_f32_e32 v62, v64, v63
	v_add_f32 v56, v56, 1.0
	v_add_f32 v57, v57, 1.0
	v_fma_f32 v58, -v61, v62, v58
	v_div_scale_f32 v61, s[4:5], v57, v57, v60
	v_rcp_f32_e32 v64, v61
	v_div_fmas_f32 v58, v58, v63, v62
	v_div_fixup_f32 v48, v58, v48, v5
	v_and_b32_e32 v63, 0xffff0000, v40
	v_fma_f32 v5, -v61, v64, 1.0
	v_fmac_f32_e32 v64, v5, v64
	v_div_scale_f32 v5, vcc, v60, v57, v60
	v_mul_f32_e32 v58, v5, v64
	v_fma_f32 v62, -v61, v58, v5
	v_fmac_f32_e32 v58, v62, v64
	v_fma_f32 v5, -v61, v58, v5
	v_div_scale_f32 v61, s[4:5], v56, v56, v59
	v_rcp_f32_e32 v62, v61
	v_div_fmas_f32 v5, v5, v64, v58
	v_div_fixup_f32 v57, v5, v57, v60
	v_fma_f32 v5, -v61, v62, 1.0
	v_fmac_f32_e32 v62, v5, v62
	v_div_scale_f32 v5, vcc, v59, v56, v59
	v_mul_f32_e32 v58, v5, v62
	v_fma_f32 v60, -v61, v58, v5
	v_fmac_f32_e32 v58, v60, v62
	v_fma_f32 v5, -v61, v58, v5
	v_div_fmas_f32 v5, v5, v62, v58
	v_div_fixup_f32 v56, v5, v56, v59
	v_lshlrev_b32_e32 v5, 16, v42
	v_mul_f32_e32 v42, 0xbfb8aa3b, v5
	v_exp_f32_e32 v64, v42
	v_mul_f32_e32 v42, 0xbfb8aa3b, v66
	v_exp_f32_e32 v65, v42
	v_lshlrev_b32_e32 v60, 16, v38
	v_lshlrev_b32_e32 v62, 16, v40
	v_and_b32_e32 v61, 0xffff0000, v38
	v_lshlrev_b32_e32 v38, 16, v39
	v_lshlrev_b32_e32 v40, 16, v41
	v_and_b32_e32 v39, 0xffff0000, v39
	v_and_b32_e32 v41, 0xffff0000, v41
	v_add_f32 v38, v38, v40
	v_add_f32 v39, v39, v41
	v_add_f32 v40, v64, 1.0
	v_add_f32 v41, v65, 1.0
	v_add_f32 v60, v60, v62
	v_add_f32 v61, v61, v63
	v_div_scale_f32 v64, s[4:5], v41, v41, v66
	v_rcp_f32_e32 v65, v64
	v_mul_f32 v62, v60, v60
	v_mul_f32 v63, v61, v61
	v_mul_f32 v42, v38, v38
	v_mul_f32 v43, v39, v39
	v_lshlrev_b64 v[58:59], 11, v[18:19]
	v_fma_f32 v69, -v64, v65, 1.0
	v_fmac_f32_e32 v65, v69, v65
	v_div_scale_f32 v69, vcc, v66, v41, v66
	v_mul_f32_e32 v70, v69, v65
	v_fma_f32 v71, -v64, v70, v69
	v_fmac_f32_e32 v70, v71, v65
	v_fma_f32 v64, -v64, v70, v69
	v_div_scale_f32 v69, s[4:5], v40, v40, v5
	v_rcp_f32_e32 v71, v69
	v_div_fmas_f32 v64, v64, v65, v70
	v_div_fixup_f32 v41, v64, v41, v66
	v_lshl_add_u64 v[58:59], s[18:19], 0, v[58:59]
	v_fma_f32 v64, -v69, v71, 1.0
	v_fmac_f32_e32 v71, v64, v71
	v_div_scale_f32 v64, vcc, v5, v40, v5
	v_mul_f32_e32 v66, v64, v71
	v_fma_f32 v65, -v69, v66, v64
	v_fmac_f32_e32 v66, v65, v71
	v_fma_f32 v69, -v69, v66, v64
	v_mov_b32_e32 v64, v62
	v_mov_b32_e32 v65, v54
	v_mov_b32_e32 v54, v63
	v_add_f32 v54, v64, v54
	v_add_f32 v55, v65, v55
	v_mov_b32_e32 v62, v42
	v_mov_b32_e32 v63, v50
	v_add_f32 v54, v54, v62
	v_add_f32 v55, v55, v63
	v_mov_b32_e32 v50, v43
	v_add_f32 v42, v50, v54
	v_add_f32 v43, v51, v55
	v_lshl_add_u64 v[58:59], v[58:59], 0, v[8:9]
	s_waitcnt lgkmcnt(0)
	v_and_b32_e32 v54, 0xffff0000, v26
	v_mov_b32_dpp v51, v43 quad_perm:[1,0,3,2] row_mask:0xf bank_mask:0xf bound_ctrl:1
	v_mov_b32_dpp v50, v42 quad_perm:[1,0,3,2] row_mask:0xf bank_mask:0xf bound_ctrl:1
	v_add_f32 v42, v42, v50
	v_add_f32 v43, v43, v51
	v_lshlrev_b32_e32 v55, 16, v27
	s_nop 0
	v_mov_b32_dpp v51, v43 quad_perm:[2,3,0,1] row_mask:0xf bank_mask:0xf bound_ctrl:1
	v_mov_b32_dpp v50, v42 quad_perm:[2,3,0,1] row_mask:0xf bank_mask:0xf bound_ctrl:1
	v_add_f32 v42, v42, v50
	v_add_f32 v43, v43, v51
	s_nop 1
	v_mov_b32_dpp v51, v43 row_half_mirror row_mask:0xf bank_mask:0xf bound_ctrl:1
	v_mov_b32_dpp v50, v42 row_half_mirror row_mask:0xf bank_mask:0xf bound_ctrl:1
	v_add_f32 v42, v42, v50
	v_add_f32 v43, v43, v51
	s_nop 1
	v_mov_b32_dpp v51, v43 row_mirror row_mask:0xf bank_mask:0xf bound_ctrl:1
	v_mov_b32_dpp v50, v42 row_mirror row_mask:0xf bank_mask:0xf bound_ctrl:1
	v_add_f32 v42, v42, v50
	v_add_f32 v43, v43, v51
	s_nop 0
	v_fma_f32 v42, v42, s6, v44
	v_fma_f32 v43, v43, s6, v44
	s_nop 0
	v_mul_f32_e32 v50, 0x4b800000, v43
	v_cmp_gt_f32_e64 s[4:5], s7, v43
	s_nop 1
	v_cndmask_b32_e64 v43, v43, v50, s[4:5]
	v_rsq_f32_e32 v43, v43
	v_div_fmas_f32 v50, v69, v71, v66
	v_div_fixup_f32 v40, v50, v40, v5
	v_cmp_gt_f32_e32 vcc, s7, v42
	v_mul_f32_e32 v5, 0x45800000, v43
	v_cndmask_b32_e64 v50, v43, v5, s[4:5]
	v_mul_f32 v52, v52, v50
	v_mul_f32 v53, v53, v50
	v_mul_f32 v46, v46, v50
	v_mul_f32 v47, v47, v50
	v_mul_f32 v52, v0, v52
	v_mul_f32 v53, v1, v53
	v_mul_f32 v46, v2, v46
	v_mul_f32 v47, v3, v47
	v_mul_f32_e32 v5, 0x4b800000, v42
	v_mul_f32 v48, v48, v52
	v_mul_f32 v49, v49, v53
	v_mul_f32 v46, v56, v46
	v_mul_f32 v47, v57, v47
	v_cndmask_b32_e32 v5, v42, v5, vcc
	v_add_co_u32_e64 v42, s[4:5], s8, v58
	v_cvt_pk_bf16_f32 v48, v48, v49
	v_cvt_pk_bf16_f32 v49, v46, v47
	v_addc_co_u32_e64 v43, s[4:5], 0, v59, s[4:5]
	flat_store_dwordx2 v[42:43], v[48:49] offset:1024 sc1
	v_mul_f32_e32 v42, 0xbfb8aa3b, v67
	v_mul_f32_e32 v43, 0xbfb8aa3b, v68
	v_rsq_f32_e32 v5, v5
	v_exp_f32_e32 v42, v42
	v_exp_f32_e32 v43, v43
	v_and_b32_e32 v56, 0xffff0000, v27
	v_mul_f32_e32 v46, 0x45800000, v5
	v_cndmask_b32_e32 v46, v5, v46, vcc
	v_add_f32 v42, v42, 1.0
	v_add_f32 v43, v43, 1.0
	v_mul_f32 v48, v60, v46
	v_mul_f32 v49, v61, v46
	v_div_scale_f32 v5, s[4:5], v43, v43, v68
	v_rcp_f32_e32 v47, v5
	v_mul_f32 v48, v0, v48
	v_mul_f32 v49, v1, v49
	v_mul_f32 v38, v38, v46
	v_mul_f32 v39, v39, v46
	v_fma_f32 v46, -v5, v47, 1.0
	v_fmac_f32_e32 v47, v46, v47
	v_div_scale_f32 v46, vcc, v68, v43, v68
	v_mul_f32 v40, v40, v48
	v_mul_f32 v41, v41, v49
	v_mul_f32_e32 v48, v46, v47
	v_fma_f32 v49, -v5, v48, v46
	v_fmac_f32_e32 v48, v49, v47
	v_fma_f32 v5, -v5, v48, v46
	v_div_scale_f32 v46, s[4:5], v42, v42, v67
	v_rcp_f32_e32 v49, v46
	v_div_fmas_f32 v5, v5, v47, v48
	v_div_fixup_f32 v43, v5, v43, v68
	v_mul_f32 v38, v2, v38
	v_mul_f32 v39, v3, v39
	v_fma_f32 v5, -v46, v49, 1.0
	v_fmac_f32_e32 v49, v5, v49
	v_div_scale_f32 v5, vcc, v67, v42, v67
	v_mul_f32_e32 v47, v5, v49
	v_fma_f32 v48, -v46, v47, v5
	v_fmac_f32_e32 v47, v48, v49
	v_fma_f32 v5, -v46, v47, v5
	v_div_fmas_f32 v5, v5, v49, v47
	v_div_fixup_f32 v42, v5, v42, v67
	v_mul_f32 v38, v42, v38
	v_mul_f32 v39, v43, v39
	v_lshlrev_b32_e32 v5, 16, v32
	v_cvt_pk_bf16_f32 v40, v40, v41
	v_cvt_pk_bf16_f32 v41, v38, v39
	v_lshlrev_b64 v[38:39], 11, v[20:21]
	v_and_b32_e32 v46, 0xffff0000, v32
	v_mul_f32_e32 v32, 0xbfb8aa3b, v5
	v_lshl_add_u64 v[38:39], s[18:19], 0, v[38:39]
	v_exp_f32_e32 v42, v32
	v_mul_f32_e32 v32, 0xbfb8aa3b, v46
	v_lshl_add_u64 v[38:39], v[38:39], 0, v[8:9]
	v_exp_f32_e32 v43, v32
	v_add_co_u32_e32 v38, vcc, s8, v38
	v_lshlrev_b32_e32 v47, 16, v33
	s_nop 0
	v_addc_co_u32_e32 v39, vcc, 0, v39, vcc
	flat_store_dwordx2 v[38:39], v[40:41] offset:1024 sc1
	v_lshlrev_b32_e32 v38, 16, v34
	v_lshlrev_b32_e32 v40, 16, v36
	v_and_b32_e32 v39, 0xffff0000, v34
	v_and_b32_e32 v41, 0xffff0000, v36
	v_lshlrev_b32_e32 v34, 16, v35
	v_lshlrev_b32_e32 v36, 16, v37
	v_and_b32_e32 v35, 0xffff0000, v35
	v_and_b32_e32 v37, 0xffff0000, v37
	v_and_b32_e32 v48, 0xffff0000, v33
	v_add_f32 v32, v34, v36
	v_add_f32 v33, v35, v37
	v_add_f32 v34, v42, 1.0
	v_add_f32 v35, v43, 1.0
	v_add_f32 v38, v38, v40
	v_add_f32 v39, v39, v41
	v_div_scale_f32 v42, s[4:5], v35, v35, v46
	v_rcp_f32_e32 v43, v42
	v_mul_f32 v40, v38, v38
	v_mul_f32 v41, v39, v39
	v_mul_f32 v36, v32, v32
	v_mul_f32 v37, v33, v33
	v_fma_f32 v49, -v42, v43, 1.0
	v_fmac_f32_e32 v43, v49, v43
	v_div_scale_f32 v49, vcc, v46, v35, v46
	v_mul_f32_e32 v50, v49, v43
	v_fma_f32 v51, -v42, v50, v49
	v_fmac_f32_e32 v50, v51, v43
	v_fma_f32 v42, -v42, v50, v49
	v_div_scale_f32 v49, s[4:5], v34, v34, v5
	v_rcp_f32_e32 v51, v49
	v_div_fmas_f32 v42, v42, v43, v50
	v_div_fixup_f32 v35, v42, v35, v46
	v_mul_f32_e32 v43, 0xbfb8aa3b, v48
	v_fma_f32 v42, -v49, v51, 1.0
	v_fmac_f32_e32 v51, v42, v51
	v_mul_f32_e32 v42, 0xbfb8aa3b, v47
	v_exp_f32_e32 v42, v42
	v_exp_f32_e32 v43, v43
	v_div_scale_f32 v46, vcc, v5, v34, v5
	v_mul_f32_e32 v50, v46, v51
	v_fma_f32 v52, -v49, v50, v46
	v_fmac_f32_e32 v50, v52, v51
	v_add_f32 v42, v42, 1.0
	v_add_f32 v43, v43, 1.0
	v_fma_f32 v46, -v49, v50, v46
	v_div_scale_f32 v49, s[4:5], v43, v43, v48
	v_rcp_f32_e32 v52, v49
	v_div_fmas_f32 v46, v46, v51, v50
	v_div_fixup_f32 v34, v46, v34, v5
	v_and_b32_e32 v51, 0xffff0000, v30
	v_fma_f32 v5, -v49, v52, 1.0
	v_fmac_f32_e32 v52, v5, v52
	v_div_scale_f32 v5, vcc, v48, v43, v48
	v_mul_f32_e32 v46, v5, v52
	v_fma_f32 v50, -v49, v46, v5
	v_fmac_f32_e32 v46, v50, v52
	v_fma_f32 v5, -v49, v46, v5
	v_div_scale_f32 v49, s[4:5], v42, v42, v47
	v_rcp_f32_e32 v50, v49
	v_div_fmas_f32 v5, v5, v52, v46
	v_div_fixup_f32 v43, v5, v43, v48
	v_fma_f32 v5, -v49, v50, 1.0
	v_fmac_f32_e32 v50, v5, v50
	v_div_scale_f32 v5, vcc, v47, v42, v47
	v_mul_f32_e32 v46, v5, v50
	v_fma_f32 v48, -v49, v46, v5
	v_fmac_f32_e32 v46, v48, v50
	v_fma_f32 v5, -v49, v46, v5
	v_div_fmas_f32 v5, v5, v50, v46
	v_div_fixup_f32 v42, v5, v42, v47
	v_lshlrev_b32_e32 v5, 16, v26
	v_mul_f32_e32 v26, 0xbfb8aa3b, v5
	v_exp_f32_e32 v52, v26
	v_mul_f32_e32 v26, 0xbfb8aa3b, v54
	v_exp_f32_e32 v53, v26
	v_lshlrev_b32_e32 v48, 16, v28
	v_lshlrev_b32_e32 v50, 16, v30
	v_and_b32_e32 v49, 0xffff0000, v28
	v_lshlrev_b32_e32 v28, 16, v29
	v_lshlrev_b32_e32 v30, 16, v31
	v_and_b32_e32 v29, 0xffff0000, v29
	v_and_b32_e32 v31, 0xffff0000, v31
	v_add_f32 v26, v28, v30
	v_add_f32 v27, v29, v31
	v_add_f32 v28, v52, 1.0
	v_add_f32 v29, v53, 1.0
	v_add_f32 v48, v48, v50
	v_add_f32 v49, v49, v51
	v_div_scale_f32 v52, s[4:5], v29, v29, v54
	v_rcp_f32_e32 v53, v52
	v_mul_f32 v50, v48, v48
	v_mul_f32 v51, v49, v49
	v_mul_f32 v30, v26, v26
	v_mul_f32 v31, v27, v27
	v_lshlrev_b64 v[46:47], 11, v[22:23]
	v_fma_f32 v57, -v52, v53, 1.0
	v_fmac_f32_e32 v53, v57, v53
	v_div_scale_f32 v57, vcc, v54, v29, v54
	v_mul_f32_e32 v58, v57, v53
	v_fma_f32 v59, -v52, v58, v57
	v_fmac_f32_e32 v58, v59, v53
	v_fma_f32 v52, -v52, v58, v57
	v_div_scale_f32 v57, s[4:5], v28, v28, v5
	v_rcp_f32_e32 v59, v57
	v_div_fmas_f32 v52, v52, v53, v58
	v_div_fixup_f32 v29, v52, v29, v54
	v_lshl_add_u64 v[46:47], s[18:19], 0, v[46:47]
	v_fma_f32 v52, -v57, v59, 1.0
	v_fmac_f32_e32 v59, v52, v59
	v_div_scale_f32 v52, vcc, v5, v28, v5
	v_mul_f32_e32 v54, v52, v59
	v_fma_f32 v53, -v57, v54, v52
	v_fmac_f32_e32 v54, v53, v59
	v_fma_f32 v57, -v57, v54, v52
	v_mov_b32_e32 v52, v50
	v_mov_b32_e32 v53, v40
	v_mov_b32_e32 v40, v51
	v_add_f32 v40, v52, v40
	v_add_f32 v41, v53, v41
	v_mov_b32_e32 v50, v30
	v_mov_b32_e32 v51, v36
	v_add_f32 v40, v40, v50
	v_add_f32 v41, v41, v51
	v_mov_b32_e32 v36, v31
	v_add_f32 v30, v36, v40
	v_add_f32 v31, v37, v41
	v_lshl_add_u64 v[46:47], v[46:47], 0, v[8:9]
	s_nop 0
	v_mov_b32_dpp v37, v31 quad_perm:[1,0,3,2] row_mask:0xf bank_mask:0xf bound_ctrl:1
	v_mov_b32_dpp v36, v30 quad_perm:[1,0,3,2] row_mask:0xf bank_mask:0xf bound_ctrl:1
	v_add_f32 v30, v30, v36
	v_add_f32 v31, v31, v37
	s_nop 1
	v_mov_b32_dpp v37, v31 quad_perm:[2,3,0,1] row_mask:0xf bank_mask:0xf bound_ctrl:1
	v_mov_b32_dpp v36, v30 quad_perm:[2,3,0,1] row_mask:0xf bank_mask:0xf bound_ctrl:1
	v_add_f32 v30, v30, v36
	v_add_f32 v31, v31, v37
	s_nop 1
	v_mov_b32_dpp v37, v31 row_half_mirror row_mask:0xf bank_mask:0xf bound_ctrl:1
	v_mov_b32_dpp v36, v30 row_half_mirror row_mask:0xf bank_mask:0xf bound_ctrl:1
	v_add_f32 v30, v30, v36
	v_add_f32 v31, v31, v37
	s_nop 1
	v_mov_b32_dpp v37, v31 row_mirror row_mask:0xf bank_mask:0xf bound_ctrl:1
	v_mov_b32_dpp v36, v30 row_mirror row_mask:0xf bank_mask:0xf bound_ctrl:1
	v_add_f32 v30, v30, v36
	v_add_f32 v31, v31, v37
	s_nop 0
	v_fma_f32 v30, v30, s6, v44
	v_fma_f32 v31, v31, s6, v44
	s_nop 0
	v_mul_f32_e32 v36, 0x4b800000, v31
	v_cmp_gt_f32_e64 s[4:5], s7, v31
	s_nop 1
	v_cndmask_b32_e64 v31, v31, v36, s[4:5]
	v_rsq_f32_e32 v31, v31
	v_div_fmas_f32 v36, v57, v59, v54
	v_div_fixup_f32 v28, v36, v28, v5
	v_cmp_gt_f32_e32 vcc, s7, v30
	v_mul_f32_e32 v5, 0x45800000, v31
	v_cndmask_b32_e64 v36, v31, v5, s[4:5]
	v_mul_f32 v38, v38, v36
	v_mul_f32 v39, v39, v36
	v_mul_f32 v32, v32, v36
	v_mul_f32 v33, v33, v36
	v_mul_f32 v38, v0, v38
	v_mul_f32 v39, v1, v39
	v_mul_f32 v32, v2, v32
	v_mul_f32 v33, v3, v33
	v_mul_f32_e32 v5, 0x4b800000, v30
	v_mul_f32 v34, v34, v38
	v_mul_f32 v35, v35, v39
	v_mul_f32 v32, v42, v32
	v_mul_f32 v33, v43, v33
	v_cndmask_b32_e32 v5, v30, v5, vcc
	v_add_co_u32_e64 v30, s[4:5], s8, v46
	v_cvt_pk_bf16_f32 v34, v34, v35
	v_cvt_pk_bf16_f32 v35, v32, v33
	v_addc_co_u32_e64 v31, s[4:5], 0, v47, s[4:5]
	flat_store_dwordx2 v[30:31], v[34:35] offset:1024 sc1
	v_mul_f32_e32 v30, 0xbfb8aa3b, v55
	v_mul_f32_e32 v31, 0xbfb8aa3b, v56
	v_rsq_f32_e32 v5, v5
	v_exp_f32_e32 v30, v30
	v_exp_f32_e32 v31, v31
	v_mul_f32_e32 v32, 0x45800000, v5
	v_cndmask_b32_e32 v32, v5, v32, vcc
	v_add_f32 v30, v30, 1.0
	v_add_f32 v31, v31, 1.0
	v_mul_f32 v34, v48, v32
	v_mul_f32 v35, v49, v32
	v_div_scale_f32 v5, s[4:5], v31, v31, v56
	v_rcp_f32_e32 v33, v5
	v_mul_f32 v0, v0, v34
	v_mul_f32 v1, v1, v35
	v_mul_f32 v26, v26, v32
	v_mul_f32 v27, v27, v32
	s_nop 0
	v_mul_f32 v2, v2, v26
	v_mul_f32 v3, v3, v27
	v_fma_f32 v26, -v5, v33, 1.0
	v_fmac_f32_e32 v33, v26, v33
	v_div_scale_f32 v26, vcc, v56, v31, v56
	v_mul_f32_e32 v27, v26, v33
	v_mul_f32 v0, v28, v0
	v_mul_f32 v1, v29, v1
	v_fma_f32 v28, -v5, v27, v26
	v_fmac_f32_e32 v27, v28, v33
	v_fma_f32 v5, -v5, v27, v26
	v_div_scale_f32 v26, s[4:5], v30, v30, v55
	v_rcp_f32_e32 v28, v26
	v_div_fmas_f32 v5, v5, v33, v27
	v_div_fixup_f32 v27, v5, v31, v56
	v_cvt_pk_bf16_f32 v0, v0, v1
	v_fma_f32 v5, -v26, v28, 1.0
	v_fmac_f32_e32 v28, v5, v28
	v_div_scale_f32 v5, vcc, v55, v30, v55
	v_mul_f32_e32 v29, v5, v28
	v_fma_f32 v31, -v26, v29, v5
	v_fmac_f32_e32 v29, v31, v28
	v_fma_f32 v5, -v26, v29, v5
	v_div_fmas_f32 v5, v5, v28, v29
	v_div_fixup_f32 v26, v5, v30, v55
	v_mul_f32 v2, v26, v2
	v_mul_f32 v3, v27, v3
	s_mov_b64 s[4:5], 0
	v_cvt_pk_bf16_f32 v1, v2, v3
	v_lshlrev_b64 v[2:3], 11, v[24:25]
	v_lshl_add_u64 v[2:3], s[18:19], 0, v[2:3]
	v_lshl_add_u64 v[2:3], v[2:3], 0, v[8:9]
	v_add_co_u32_e32 v2, vcc, 0x4552000, v2
	s_nop 1
	v_addc_co_u32_e32 v3, vcc, 0, v3, vcc
	flat_store_dwordx2 v[2:3], v[0:1] offset:1024 sc1
	s_waitcnt vmcnt(0)
	v_cmp_eq_u32_e32 vcc, 0, v75
	s_and_saveexec_b64 s[6:7], vcc
	s_cbranch_execz .LBB0_3176
	v_alignbit_b32 v0, v11, v10, 8
	v_alignbit_b32 v1, v7, v6, 8
	v_cmp_eq_u32_e32 vcc, v0, v1
	v_alignbit_b32 v2, v13, v12, 8
	v_alignbit_b32 v3, v17, v16, 8
	v_cndmask_b32_e64 v0, 1, 2, vcc
	v_cmp_eq_u32_e32 vcc, v2, v1
	v_alignbit_b32 v2, v15, v14, 8
	s_mov_b64 s[8:9], 0
	v_addc_co_u32_e32 v0, vcc, 0, v0, vcc
	v_cmp_eq_u32_e32 vcc, v2, v1
	s_nop 1
	v_cndmask_b32_e64 v2, 0, 1, vcc
	v_cmp_eq_u32_e32 vcc, v3, v1
	v_alignbit_b32 v3, v21, v20, 8
	s_nop 0
	v_addc_co_u32_e32 v0, vcc, v0, v2, vcc
	v_alignbit_b32 v2, v19, v18, 8
	v_cmp_eq_u32_e32 vcc, v2, v1
	s_nop 1
	v_cndmask_b32_e64 v2, 0, 1, vcc
	v_cmp_eq_u32_e32 vcc, v3, v1
	v_alignbit_b32 v3, v25, v24, 8
	s_nop 0
	v_addc_co_u32_e32 v0, vcc, v0, v2, vcc
	v_alignbit_b32 v2, v23, v22, 8
	v_cmp_eq_u32_e32 vcc, v2, v1
	s_nop 1
	v_cndmask_b32_e64 v2, 0, 1, vcc
	v_cmp_eq_u32_e32 vcc, v3, v1
	s_nop 1
	v_addc_co_u32_e32 v2, vcc, v0, v2, vcc
	v_lshlrev_b32_e32 v0, 6, v1
	v_ashrrev_i32_e32 v1, 31, v0
	v_lshl_add_u64 v[6:7], v[0:1], 2, s[16:17]
	flat_atomic_add v[6:7], v2
	v_cmp_gt_u32_e32 vcc, 9, v2
	s_and_saveexec_b64 s[10:11], vcc
	s_xor_b64 s[10:11], exec, s[10:11]
	s_mov_b64 s[8:9], exec
	v_sub_u32_e32 v1, 9, v2
	s_or_b64 exec, exec, s[10:11]
	s_and_b64 s[10:11], s[8:9], exec

.LBB0_3180:
	s_or_b64 exec, exec, s[6:7]
	s_mul_i32 s6, s2, 40
	s_ashr_i32 s7, s6, 31
	v_ashrrev_i32_e32 v5, 31, v4
	v_lshlrev_b32_e32 v6, 3, v75
	v_lshl_add_u64 v[4:5], s[6:7], 0, v[4:5]
	v_lshl_add_u64 v[2:3], s[18:19], 0, v[6:7]
	s_mov_b64 s[6:7], 0x6952000
	v_lshl_add_u64 v[16:17], v[2:3], 0, s[6:7]
	s_mov_b64 s[6:7], 0x6f52000
	v_lshl_add_u64 v[18:19], v[2:3], 0, s[6:7]
	s_mov_b64 s[6:7], 0xcb32000
	v_lshlrev_b64 v[8:9], 9, v[4:5]
	v_lshl_add_u64 v[2:3], v[2:3], 0, s[6:7]
	v_lshl_add_u64 v[10:11], v[16:17], 0, v[8:9]
	v_lshl_add_u64 v[12:13], v[18:19], 0, v[8:9]
	v_lshl_add_u64 v[8:9], v[2:3], 0, v[8:9]
	flat_load_dwordx2 v[34:35], v[10:11]
	flat_load_dwordx2 v[36:37], v[12:13]
	flat_load_dwordx2 v[38:39], v[8:9]
	s_ashr_i32 s7, s24, 31
	s_add_u32 s6, s0, s24
	s_addc_u32 s7, s1, s7
	s_load_dwordx2 s[6:7], s[6:7], 0xb8
	v_lshl_add_u64 v[14:15], v[4:5], 0, 8
	v_and_b32_e32 v70, 0xf0, v0
	v_lshl_add_u64 v[12:13], v[4:5], 0, 16
	v_lshl_add_u64 v[10:11], v[4:5], 0, 24
	v_lshl_add_u64 v[8:9], v[4:5], 0, 32
	v_lshlrev_b64 v[0:1], 9, v[14:15]
	v_lshlrev_b64 v[20:21], 9, v[12:13]
	v_lshlrev_b64 v[22:23], 9, v[10:11]
	v_lshlrev_b64 v[24:25], 9, v[8:9]
	v_lshl_add_u64 v[40:41], v[16:17], 0, v[0:1]
	v_lshl_add_u64 v[42:43], v[18:19], 0, v[0:1]
	v_lshl_add_u64 v[44:45], v[2:3], 0, v[0:1]
	v_lshl_add_u64 v[46:47], v[16:17], 0, v[20:21]
	v_lshl_add_u64 v[48:49], v[18:19], 0, v[20:21]
	v_lshl_add_u64 v[50:51], v[2:3], 0, v[20:21]
	v_lshl_add_u64 v[52:53], v[16:17], 0, v[22:23]
	v_lshl_add_u64 v[54:55], v[18:19], 0, v[22:23]
	v_lshl_add_u64 v[56:57], v[2:3], 0, v[22:23]
	v_lshl_add_u64 v[58:59], v[16:17], 0, v[24:25]
	v_lshl_add_u64 v[60:61], v[18:19], 0, v[24:25]
	v_lshl_add_u64 v[62:63], v[2:3], 0, v[24:25]
	flat_load_dwordx2 v[64:65], v[40:41]
	s_waitcnt lgkmcnt(0)
	global_load_dwordx4 v[0:3], v70, s[6:7] offset:256
	flat_load_dwordx2 v[66:67], v[42:43]
	flat_load_dwordx2 v[68:69], v[44:45]
	flat_load_dwordx2 v[30:31], v[46:47]
	flat_load_dwordx2 v[32:33], v[48:49]
	flat_load_dwordx2 v[28:29], v[50:51]
	flat_load_dwordx2 v[24:25], v[52:53]
	flat_load_dwordx2 v[26:27], v[54:55]
	flat_load_dwordx2 v[22:23], v[56:57]
	flat_load_dwordx2 v[18:19], v[58:59]
	flat_load_dwordx2 v[20:21], v[60:61]
	flat_load_dwordx2 v[16:17], v[62:63]
	s_mov_b32 s13, 0x800000
	s_mov_b32 s12, 0x3c800000
	s_waitcnt vmcnt(0)
	v_lshlrev_b32_e32 v40, 16, v34
	v_lshlrev_b32_e32 v42, 16, v36
	v_and_b32_e32 v41, 0xffff0000, v34
	v_and_b32_e32 v43, 0xffff0000, v36
	v_lshlrev_b32_e32 v34, 16, v35
	v_lshlrev_b32_e32 v36, 16, v37
	v_and_b32_e32 v35, 0xffff0000, v35
	v_and_b32_e32 v37, 0xffff0000, v37
	v_lshlrev_b32_e32 v44, 16, v38
	v_and_b32_e32 v45, 0xffff0000, v38
	v_add_f32 v34, v34, v36
	v_add_f32 v35, v35, v37
	v_mul_f32_e32 v36, 0xbfb8aa3b, v44
	v_mul_f32_e32 v37, 0xbfb8aa3b, v45
	v_exp_f32_e32 v36, v36
	v_exp_f32_e32 v37, v37
	v_lshlrev_b32_e32 v46, 16, v39
	v_and_b32_e32 v47, 0xffff0000, v39
	v_add_f32 v38, v40, v42
	v_add_f32 v39, v41, v43
	v_add_f32 v36, v36, 1.0
	v_add_f32 v37, v37, 1.0
	v_mul_f32 v42, v38, v38
	v_mul_f32 v43, v39, v39
	v_div_scale_f32 v48, s[6:7], v37, v37, v45
	v_rcp_f32_e32 v51, v48
	v_div_scale_f32 v50, s[6:7], v36, v36, v44
	v_mul_f32 v40, v34, v34
	v_mul_f32 v41, v35, v35
	v_rcp_f32_e32 v52, v50
	v_add_f32_e32 v42, v42, v43
	v_add_f32_e32 v40, v42, v40
	v_fma_f32 v54, -v48, v51, 1.0
	v_add_f32_e32 v40, v41, v40
	v_div_scale_f32 v49, vcc, v45, v37, v45
	v_fmac_f32_e32 v51, v54, v51
	v_add_f32_dpp v40, v40, v40 quad_perm:[1,0,3,2] row_mask:0xf bank_mask:0xf bound_ctrl:1
	v_fma_f32 v55, -v50, v52, 1.0
	v_mul_f32_e32 v54, v49, v51
	v_add_f32_dpp v40, v40, v40 quad_perm:[2,3,0,1] row_mask:0xf bank_mask:0xf bound_ctrl:1
	v_div_scale_f32 v53, s[6:7], v44, v36, v44
	v_fmac_f32_e32 v52, v55, v52
	v_fma_f32 v56, -v48, v54, v49
	v_add_f32_dpp v40, v40, v40 row_half_mirror row_mask:0xf bank_mask:0xf bound_ctrl:1
	v_mul_f32_e32 v55, v53, v52
	v_fmac_f32_e32 v54, v56, v51
	v_add_f32_dpp v40, v40, v40 row_mirror row_mask:0xf bank_mask:0xf bound_ctrl:1
	v_mov_b32_e32 v41, 0x358637bd
	v_fma_f32 v57, -v50, v55, v53
	v_fma_f32 v48, -v48, v54, v49
	v_fmac_f32_e32 v41, 0x3c800000, v40
	v_fmac_f32_e32 v55, v57, v52
	v_div_fmas_f32 v48, v48, v51, v54
	v_mul_f32_e32 v40, 0x4b800000, v41
	v_cmp_gt_f32_e64 s[8:9], s13, v41
	v_div_fixup_f32 v37, v48, v37, v45
	v_fma_f32 v45, -v50, v55, v53
	v_cndmask_b32_e64 v40, v41, v40, s[8:9]
	s_mov_b64 vcc, s[6:7]
	v_rsq_f32_e32 v42, v40
	v_div_fmas_f32 v40, v45, v52, v55
	v_div_fixup_f32 v36, v40, v36, v44
	v_mul_f32_e32 v40, 0xbfb8aa3b, v46
	v_mul_f32_e32 v41, 0xbfb8aa3b, v47
	v_exp_f32_e32 v40, v40
	v_exp_f32_e32 v41, v41
	v_mul_f32_e32 v43, 0x45800000, v42
	v_cndmask_b32_e64 v42, v42, v43, s[8:9]
	v_mul_f32 v38, v38, v42
	v_mul_f32 v39, v39, v42
	v_add_f32 v40, v40, 1.0
	v_add_f32 v41, v41, 1.0
	v_mul_f32 v38, v0, v38
	v_mul_f32 v39, v1, v39
	v_div_scale_f32 v43, s[6:7], v41, v41, v47
	v_rcp_f32_e32 v44, v43
	v_mul_f32 v36, v36, v38
	v_mul_f32 v37, v37, v39
	v_mul_f32 v34, v34, v42
	v_mul_f32 v35, v35, v42
	v_cvt_pk_bf16_f32 v36, v36, v37
	v_fma_f32 v38, -v43, v44, 1.0
	v_fmac_f32_e32 v44, v38, v44
	v_div_scale_f32 v38, vcc, v47, v41, v47
	v_mul_f32_e32 v39, v38, v44
	v_fma_f32 v42, -v43, v39, v38
	v_fmac_f32_e32 v39, v42, v44
	v_div_scale_f32 v42, s[6:7], v40, v40, v46
	v_fma_f32 v38, -v43, v39, v38
	v_rcp_f32_e32 v43, v42
	v_div_fmas_f32 v38, v38, v44, v39
	v_div_fixup_f32 v39, v38, v41, v47
	v_mul_f32 v34, v2, v34
	v_mul_f32 v35, v3, v35
	v_fma_f32 v38, -v42, v43, 1.0
	v_fmac_f32_e32 v43, v38, v43
	v_div_scale_f32 v38, vcc, v46, v40, v46
	v_mul_f32_e32 v41, v38, v43
	v_fma_f32 v44, -v42, v41, v38
	v_fmac_f32_e32 v41, v44, v43
	v_fma_f32 v38, -v42, v41, v38
	v_div_fmas_f32 v38, v38, v43, v41
	v_div_fixup_f32 v38, v38, v40, v46
	s_waitcnt lgkmcnt(0)
	v_lshlrev_b32_e32 v46, 16, v68
	v_and_b32_e32 v44, 0xffff0000, v68
	v_mul_f32_e32 v42, 0xbfb8aa3b, v46
	v_mul_f32_e32 v43, 0xbfb8aa3b, v44
	v_exp_f32_e32 v42, v42
	v_exp_f32_e32 v43, v43
	v_mul_f32 v34, v38, v34
	v_mul_f32 v35, v39, v35
	v_lshlrev_b32_e32 v38, 16, v65
	v_lshlrev_b32_e32 v40, 16, v67
	v_and_b32_e32 v39, 0xffff0000, v65
	v_and_b32_e32 v41, 0xffff0000, v67
	v_add_f32 v38, v38, v40
	v_add_f32 v39, v39, v41
	v_add_f32 v40, v42, 1.0
	v_add_f32 v41, v43, 1.0
	v_cvt_pk_bf16_f32 v37, v34, v35
	v_div_scale_f32 v45, s[6:7], v41, v41, v44
	v_lshlrev_b64 v[34:35], 11, v[4:5]
	v_rcp_f32_e32 v49, v45
	v_lshl_add_u64 v[34:35], s[18:19], 0, v[34:35]
	v_lshl_add_u64 v[34:35], v[34:35], 0, v[6:7]
	s_mov_b32 s8, 0x4552000
	v_add_co_u32_e32 v34, vcc, s8, v34
	v_fma_f32 v50, -v45, v49, 1.0
	s_nop 0
	v_addc_co_u32_e32 v35, vcc, 0, v35, vcc
	v_fmac_f32_e32 v49, v50, v49
	v_div_scale_f32 v50, vcc, v44, v41, v44
	v_mul_f32_e32 v51, v50, v49
	v_fma_f32 v52, -v45, v51, v50
	v_fmac_f32_e32 v51, v52, v49
	v_fma_f32 v45, -v45, v51, v50
	v_div_scale_f32 v50, s[6:7], v40, v40, v46
	v_rcp_f32_e32 v52, v50
	v_div_fmas_f32 v45, v45, v49, v51
	v_lshlrev_b32_e32 v47, 16, v69
	v_and_b32_e32 v48, 0xffff0000, v69
	v_div_fixup_f32 v41, v45, v41, v44
	v_fma_f32 v44, -v50, v52, 1.0
	v_fmac_f32_e32 v52, v44, v52
	v_mul_f32_e32 v44, 0xbfb8aa3b, v47
	v_mul_f32_e32 v45, 0xbfb8aa3b, v48
	v_exp_f32_e32 v44, v44
	v_exp_f32_e32 v45, v45
	v_div_scale_f32 v49, vcc, v46, v40, v46
	v_mul_f32_e32 v51, v49, v52
	v_fma_f32 v53, -v50, v51, v49
	v_fmac_f32_e32 v51, v53, v52
	v_add_f32 v44, v44, 1.0
	v_add_f32 v45, v45, 1.0
	v_fma_f32 v49, -v50, v51, v49
	v_div_scale_f32 v50, s[6:7], v45, v45, v48
	v_rcp_f32_e32 v53, v50
	v_div_fmas_f32 v49, v49, v52, v51
	v_div_fixup_f32 v40, v49, v40, v46
	v_lshlrev_b32_e32 v54, 16, v28
	v_fma_f32 v46, -v50, v53, 1.0
	v_fmac_f32_e32 v53, v46, v53
	v_div_scale_f32 v46, vcc, v48, v45, v48
	v_mul_f32_e32 v49, v46, v53
	v_fma_f32 v51, -v50, v49, v46
	v_fmac_f32_e32 v49, v51, v53
	v_fma_f32 v46, -v50, v49, v46
	v_div_scale_f32 v50, s[6:7], v44, v44, v47
	v_rcp_f32_e32 v51, v50
	v_div_fmas_f32 v46, v46, v53, v49
	v_div_fixup_f32 v45, v46, v45, v48
	v_and_b32_e32 v55, 0xffff0000, v28
	v_fma_f32 v46, -v50, v51, 1.0
	v_fmac_f32_e32 v51, v46, v51
	v_div_scale_f32 v46, vcc, v47, v44, v47
	v_mul_f32_e32 v28, 0xbfb8aa3b, v54
	v_mul_f32_e32 v48, v46, v51
	v_exp_f32_e32 v52, v28
	v_mul_f32_e32 v28, 0xbfb8aa3b, v55
	v_fma_f32 v49, -v50, v48, v46
	v_exp_f32_e32 v53, v28
	v_fmac_f32_e32 v48, v49, v51
	v_fma_f32 v46, -v50, v48, v46
	v_div_fmas_f32 v46, v46, v51, v48
	v_lshlrev_b32_e32 v48, 16, v30
	v_lshlrev_b32_e32 v50, 16, v32
	v_and_b32_e32 v49, 0xffff0000, v30
	v_and_b32_e32 v51, 0xffff0000, v32
	v_lshlrev_b32_e32 v30, 16, v31
	v_lshlrev_b32_e32 v32, 16, v33
	v_and_b32_e32 v31, 0xffff0000, v31
	v_and_b32_e32 v33, 0xffff0000, v33
	v_add_f32 v30, v30, v32
	v_add_f32 v31, v31, v33
	v_add_f32 v32, v52, 1.0
	v_add_f32 v33, v53, 1.0
	flat_store_dwordx2 v[34:35], v[36:37] offset:1024 sc1
	v_div_scale_f32 v52, s[6:7], v33, v33, v55
	v_rcp_f32_e32 v53, v52
	v_lshlrev_b32_e32 v34, 16, v64
	v_lshlrev_b32_e32 v36, 16, v66
	v_and_b32_e32 v35, 0xffff0000, v64
	v_fma_f32 v58, -v52, v53, 1.0
	v_fmac_f32_e32 v53, v58, v53
	v_div_scale_f32 v58, vcc, v55, v33, v55
	v_mul_f32_e32 v59, v58, v53
	v_fma_f32 v60, -v52, v59, v58
	v_fmac_f32_e32 v59, v60, v53
	v_fma_f32 v52, -v52, v59, v58
	v_div_scale_f32 v58, s[6:7], v32, v32, v54
	v_rcp_f32_e32 v60, v58
	v_div_fmas_f32 v52, v52, v53, v59
	v_div_fixup_f32 v33, v52, v33, v55
	v_and_b32_e32 v37, 0xffff0000, v66
	v_fma_f32 v52, -v58, v60, 1.0
	v_fmac_f32_e32 v60, v52, v60
	v_div_scale_f32 v52, vcc, v54, v32, v54
	v_mul_f32_e32 v55, v52, v60
	v_add_f32 v34, v34, v36
	v_add_f32 v35, v35, v37
	v_add_f32 v48, v48, v50
	v_add_f32 v49, v49, v51
	v_fma_f32 v53, -v58, v55, v52
	v_mul_f32 v36, v34, v34
	v_mul_f32 v37, v35, v35
	v_mul_f32 v50, v48, v48
	v_mul_f32 v51, v49, v49
	v_fmac_f32_e32 v55, v53, v60
	v_mul_f32 v42, v38, v38
	v_mul_f32 v43, v39, v39
	v_lshlrev_b32_e32 v56, 16, v29
	v_and_b32_e32 v57, 0xffff0000, v29
	v_mul_f32 v28, v30, v30
	v_mul_f32 v29, v31, v31
	v_fma_f32 v58, -v58, v55, v52
	v_mov_b32_e32 v52, v50
	v_mov_b32_e32 v53, v36
	v_mov_b32_e32 v36, v51
	v_add_f32 v36, v52, v36
	v_add_f32 v37, v53, v37
	v_mov_b32_e32 v50, v28
	v_mov_b32_e32 v51, v42
	v_add_f32 v36, v36, v50
	v_add_f32 v37, v37, v51
	v_mov_b32_e32 v42, v29
	v_add_f32 v28, v42, v36
	v_add_f32 v29, v43, v37
	s_mov_b32 s6, 0x358637bd
	v_div_fixup_f32 v44, v46, v44, v47
	v_mov_b32_dpp v37, v29 quad_perm:[1,0,3,2] row_mask:0xf bank_mask:0xf bound_ctrl:1
	v_mov_b32_dpp v36, v28 quad_perm:[1,0,3,2] row_mask:0xf bank_mask:0xf bound_ctrl:1
	v_add_f32 v28, v28, v36
	v_add_f32 v29, v29, v37
	v_lshlrev_b64 v[46:47], 11, v[14:15]
	v_lshl_add_u64 v[46:47], s[18:19], 0, v[46:47]
	v_mov_b32_dpp v37, v29 quad_perm:[2,3,0,1] row_mask:0xf bank_mask:0xf bound_ctrl:1
	v_mov_b32_dpp v36, v28 quad_perm:[2,3,0,1] row_mask:0xf bank_mask:0xf bound_ctrl:1
	v_add_f32 v28, v28, v36
	v_add_f32 v29, v29, v37
	v_lshl_add_u64 v[46:47], v[46:47], 0, v[6:7]
	s_nop 0
	v_mov_b32_dpp v37, v29 row_half_mirror row_mask:0xf bank_mask:0xf bound_ctrl:1
	v_mov_b32_dpp v36, v28 row_half_mirror row_mask:0xf bank_mask:0xf bound_ctrl:1
	v_add_f32 v28, v28, v36
	v_add_f32 v29, v29, v37
	s_nop 1
	v_mov_b32_dpp v37, v29 row_mirror row_mask:0xf bank_mask:0xf bound_ctrl:1
	v_mov_b32_dpp v36, v28 row_mirror row_mask:0xf bank_mask:0xf bound_ctrl:1
	v_add_f32 v36, v28, v36
	v_add_f32 v37, v29, v37
	v_mov_b64_e32 v[28:29], s[6:7]
	v_fma_f32 v36, v36, s12, v28
	v_fma_f32 v37, v37, s12, v28
	s_nop 0
	v_mul_f32_e32 v42, 0x4b800000, v37
	v_cmp_gt_f32_e64 s[6:7], s13, v37
	s_nop 1
	v_cndmask_b32_e64 v37, v37, v42, s[6:7]
	v_rsq_f32_e32 v37, v37
	v_div_fmas_f32 v42, v58, v60, v55
	v_div_fixup_f32 v32, v42, v32, v54
	v_cmp_gt_f32_e32 vcc, s13, v36
	v_mul_f32_e32 v42, 0x45800000, v37
	v_cndmask_b32_e64 v42, v37, v42, s[6:7]
	v_mul_f32 v34, v34, v42
	v_mul_f32 v35, v35, v42
	v_mul_f32 v38, v38, v42
	v_mul_f32 v39, v39, v42
	v_mul_f32 v34, v0, v34
	v_mul_f32 v35, v1, v35
	v_mul_f32 v38, v2, v38
	v_mul_f32 v39, v3, v39
	v_mul_f32_e32 v37, 0x4b800000, v36
	v_mul_f32 v34, v40, v34
	v_mul_f32 v35, v41, v35
	v_mul_f32 v38, v44, v38
	v_mul_f32 v39, v45, v39
	v_cndmask_b32_e32 v36, v36, v37, vcc
	v_cvt_pk_bf16_f32 v34, v34, v35
	v_cvt_pk_bf16_f32 v35, v38, v39
	v_rsq_f32_e32 v38, v36
	v_add_co_u32_e64 v36, s[6:7], s8, v46
	v_lshlrev_b32_e32 v44, 16, v16
	s_nop 0
	v_addc_co_u32_e64 v37, s[6:7], 0, v47, s[6:7]
	flat_store_dwordx2 v[36:37], v[34:35] offset:1024 sc1
	v_mul_f32_e32 v34, 0xbfb8aa3b, v56
	v_mul_f32_e32 v35, 0xbfb8aa3b, v57
	v_exp_f32_e32 v34, v34
	v_exp_f32_e32 v35, v35
	v_mul_f32_e32 v36, 0x45800000, v38
	v_cndmask_b32_e32 v36, v38, v36, vcc
	v_mul_f32 v38, v48, v36
	v_mul_f32 v39, v49, v36
	v_add_f32 v34, v34, 1.0
	v_add_f32 v35, v35, 1.0
	v_mul_f32 v38, v0, v38
	v_mul_f32 v39, v1, v39
	v_div_scale_f32 v37, s[6:7], v35, v35, v57
	v_rcp_f32_e32 v40, v37
	v_mul_f32 v30, v30, v36
	v_mul_f32 v31, v31, v36
	v_mul_f32 v32, v32, v38
	v_mul_f32 v33, v33, v39
	v_mul_f32 v30, v2, v30
	v_mul_f32 v31, v3, v31
	v_fma_f32 v36, -v37, v40, 1.0
	v_fmac_f32_e32 v40, v36, v40
	v_div_scale_f32 v36, vcc, v57, v35, v57
	v_mul_f32_e32 v38, v36, v40
	v_fma_f32 v39, -v37, v38, v36
	v_fmac_f32_e32 v38, v39, v40
	v_fma_f32 v36, -v37, v38, v36
	v_div_scale_f32 v37, s[6:7], v34, v34, v56
	v_rcp_f32_e32 v39, v37
	v_div_fmas_f32 v36, v36, v40, v38
	v_div_fixup_f32 v35, v36, v35, v57
	v_cvt_pk_bf16_f32 v32, v32, v33
	v_fma_f32 v36, -v37, v39, 1.0
	v_fmac_f32_e32 v39, v36, v39
	v_div_scale_f32 v36, vcc, v56, v34, v56
	v_mul_f32_e32 v38, v36, v39
	v_fma_f32 v40, -v37, v38, v36
	v_fmac_f32_e32 v38, v40, v39
	v_fma_f32 v36, -v37, v38, v36
	v_div_fmas_f32 v36, v36, v39, v38
	v_div_fixup_f32 v34, v36, v34, v56
	v_mul_f32 v30, v34, v30
	v_mul_f32 v31, v35, v31
	v_lshlrev_b32_e32 v36, 16, v22
	v_cvt_pk_bf16_f32 v33, v30, v31
	v_lshlrev_b64 v[30:31], 11, v[12:13]
	v_and_b32_e32 v37, 0xffff0000, v22
	v_mul_f32_e32 v22, 0xbfb8aa3b, v36
	v_lshl_add_u64 v[30:31], s[18:19], 0, v[30:31]
	v_exp_f32_e32 v34, v22
	v_mul_f32_e32 v22, 0xbfb8aa3b, v37
	v_lshl_add_u64 v[30:31], v[30:31], 0, v[6:7]
	v_exp_f32_e32 v35, v22
	v_add_co_u32_e32 v30, vcc, s8, v30
	v_lshlrev_b32_e32 v38, 16, v23
	s_nop 0
	v_addc_co_u32_e32 v31, vcc, 0, v31, vcc
	flat_store_dwordx2 v[30:31], v[32:33] offset:1024 sc1
	v_lshlrev_b32_e32 v30, 16, v24
	v_lshlrev_b32_e32 v32, 16, v26
	v_and_b32_e32 v31, 0xffff0000, v24
	v_and_b32_e32 v33, 0xffff0000, v26
	v_lshlrev_b32_e32 v24, 16, v25
	v_lshlrev_b32_e32 v26, 16, v27
	v_and_b32_e32 v25, 0xffff0000, v25
	v_and_b32_e32 v27, 0xffff0000, v27
	v_and_b32_e32 v39, 0xffff0000, v23
	v_add_f32 v22, v24, v26
	v_add_f32 v23, v25, v27
	v_add_f32 v24, v34, 1.0
	v_add_f32 v25, v35, 1.0
	v_and_b32_e32 v45, 0xffff0000, v16
	v_div_scale_f32 v34, s[6:7], v25, v25, v37
	v_rcp_f32_e32 v35, v34
	v_mul_f32_e32 v16, 0xbfb8aa3b, v44
	v_lshlrev_b32_e32 v46, 16, v17
	v_and_b32_e32 v47, 0xffff0000, v17
	v_fma_f32 v40, -v34, v35, 1.0
	v_fmac_f32_e32 v35, v40, v35
	v_div_scale_f32 v40, vcc, v37, v25, v37
	v_mul_f32_e32 v41, v40, v35
	v_fma_f32 v42, -v34, v41, v40
	v_fmac_f32_e32 v41, v42, v35
	v_fma_f32 v34, -v34, v41, v40
	v_div_scale_f32 v40, s[6:7], v24, v24, v36
	v_rcp_f32_e32 v42, v40
	v_div_fmas_f32 v34, v34, v35, v41
	v_div_fixup_f32 v25, v34, v25, v37
	v_mul_f32_e32 v35, 0xbfb8aa3b, v39
	v_fma_f32 v34, -v40, v42, 1.0
	v_fmac_f32_e32 v42, v34, v42
	v_mul_f32_e32 v34, 0xbfb8aa3b, v38
	v_exp_f32_e32 v34, v34
	v_exp_f32_e32 v35, v35
	v_div_scale_f32 v37, vcc, v36, v24, v36
	v_mul_f32_e32 v41, v37, v42
	v_fma_f32 v43, -v40, v41, v37
	v_fmac_f32_e32 v41, v43, v42
	v_add_f32 v34, v34, 1.0
	v_add_f32 v35, v35, 1.0
	v_fma_f32 v37, -v40, v41, v37
	v_div_scale_f32 v40, s[6:7], v35, v35, v39
	v_rcp_f32_e32 v43, v40
	v_div_fmas_f32 v37, v37, v42, v41
	v_div_fixup_f32 v24, v37, v24, v36
	v_exp_f32_e32 v42, v16
	v_fma_f32 v36, -v40, v43, 1.0
	v_fmac_f32_e32 v43, v36, v43
	v_div_scale_f32 v36, vcc, v39, v35, v39
	v_mul_f32_e32 v37, v36, v43
	v_fma_f32 v41, -v40, v37, v36
	v_fmac_f32_e32 v37, v41, v43
	v_fma_f32 v36, -v40, v37, v36
	v_div_scale_f32 v40, s[6:7], v34, v34, v38
	v_rcp_f32_e32 v41, v40
	v_div_fmas_f32 v36, v36, v43, v37
	v_div_fixup_f32 v35, v36, v35, v39
	v_mul_f32_e32 v16, 0xbfb8aa3b, v45
	v_fma_f32 v36, -v40, v41, 1.0
	v_fmac_f32_e32 v41, v36, v41
	v_div_scale_f32 v36, vcc, v38, v34, v38
	v_mul_f32_e32 v37, v36, v41
	v_fma_f32 v39, -v40, v37, v36
	v_fmac_f32_e32 v37, v39, v41
	v_exp_f32_e32 v43, v16
	v_fma_f32 v36, -v40, v37, v36
	v_div_fmas_f32 v36, v36, v41, v37
	v_div_fixup_f32 v34, v36, v34, v38
	v_lshlrev_b32_e32 v38, 16, v18
	v_lshlrev_b32_e32 v40, 16, v20
	v_and_b32_e32 v39, 0xffff0000, v18
	v_and_b32_e32 v41, 0xffff0000, v20
	v_lshlrev_b32_e32 v18, 16, v19
	v_lshlrev_b32_e32 v20, 16, v21
	v_and_b32_e32 v19, 0xffff0000, v19
	v_and_b32_e32 v21, 0xffff0000, v21
	v_add_f32 v16, v18, v20
	v_add_f32 v17, v19, v21
	v_add_f32 v18, v42, 1.0
	v_add_f32 v19, v43, 1.0
	v_add_f32 v30, v30, v32
	v_add_f32 v31, v31, v33
	v_div_scale_f32 v42, s[6:7], v19, v19, v45
	v_rcp_f32_e32 v43, v42
	v_add_f32 v38, v38, v40
	v_add_f32 v39, v39, v41
	v_mul_f32 v32, v30, v30
	v_mul_f32 v33, v31, v31
	v_mul_f32 v40, v38, v38
	v_mul_f32 v41, v39, v39
	v_fma_f32 v48, -v42, v43, 1.0
	v_fmac_f32_e32 v43, v48, v43
	v_div_scale_f32 v48, vcc, v45, v19, v45
	v_mul_f32_e32 v49, v48, v43
	v_fma_f32 v50, -v42, v49, v48
	v_fmac_f32_e32 v49, v50, v43
	v_fma_f32 v42, -v42, v49, v48
	v_div_scale_f32 v48, s[6:7], v18, v18, v44
	v_rcp_f32_e32 v50, v48
	v_div_fmas_f32 v42, v42, v43, v49
	v_div_fixup_f32 v19, v42, v19, v45
	v_mul_f32 v26, v22, v22
	v_mul_f32 v27, v23, v23
	v_fma_f32 v42, -v48, v50, 1.0
	v_fmac_f32_e32 v50, v42, v50
	v_div_scale_f32 v42, vcc, v44, v18, v44
	v_mul_f32_e32 v45, v42, v50
	v_fma_f32 v43, -v48, v45, v42
	v_fmac_f32_e32 v45, v43, v50
	v_mul_f32 v20, v16, v16
	v_mul_f32 v21, v17, v17
	v_fma_f32 v48, -v48, v45, v42
	v_mov_b32_e32 v42, v40
	v_mov_b32_e32 v43, v32
	v_mov_b32_e32 v32, v41
	v_add_f32 v32, v42, v32
	v_add_f32 v33, v43, v33
	v_mov_b32_e32 v40, v20
	v_mov_b32_e32 v41, v26
	v_add_f32 v32, v32, v40
	v_add_f32 v33, v33, v41
	v_mov_b32_e32 v26, v21
	v_add_f32 v20, v26, v32
	v_add_f32 v21, v27, v33
	v_lshlrev_b64 v[36:37], 11, v[10:11]
	v_lshl_add_u64 v[36:37], s[18:19], 0, v[36:37]
	v_mov_b32_dpp v27, v21 quad_perm:[1,0,3,2] row_mask:0xf bank_mask:0xf bound_ctrl:1
	v_mov_b32_dpp v26, v20 quad_perm:[1,0,3,2] row_mask:0xf bank_mask:0xf bound_ctrl:1
	v_add_f32 v20, v20, v26
	v_add_f32 v21, v21, v27
	v_lshl_add_u64 v[36:37], v[36:37], 0, v[6:7]
	s_nop 0
	v_mov_b32_dpp v27, v21 quad_perm:[2,3,0,1] row_mask:0xf bank_mask:0xf bound_ctrl:1
	v_mov_b32_dpp v26, v20 quad_perm:[2,3,0,1] row_mask:0xf bank_mask:0xf bound_ctrl:1
	v_add_f32 v20, v20, v26
	v_add_f32 v21, v21, v27
	s_nop 1
	v_mov_b32_dpp v27, v21 row_half_mirror row_mask:0xf bank_mask:0xf bound_ctrl:1
	v_mov_b32_dpp v26, v20 row_half_mirror row_mask:0xf bank_mask:0xf bound_ctrl:1
	v_add_f32 v20, v20, v26
	v_add_f32 v21, v21, v27
	s_nop 1
	v_mov_b32_dpp v27, v21 row_mirror row_mask:0xf bank_mask:0xf bound_ctrl:1
	v_mov_b32_dpp v26, v20 row_mirror row_mask:0xf bank_mask:0xf bound_ctrl:1
	v_add_f32 v20, v20, v26
	v_add_f32 v21, v21, v27
	s_nop 0
	v_fma_f32 v20, v20, s12, v28
	v_fma_f32 v21, v21, s12, v28
	s_nop 0
	v_mul_f32_e32 v26, 0x4b800000, v21
	v_cmp_gt_f32_e64 s[6:7], s13, v21
	s_nop 1
	v_cndmask_b32_e64 v21, v21, v26, s[6:7]
	v_rsq_f32_e32 v21, v21
	v_div_fmas_f32 v26, v48, v50, v45
	v_div_fixup_f32 v18, v26, v18, v44
	v_cmp_gt_f32_e32 vcc, s13, v20
	v_mul_f32_e32 v26, 0x45800000, v21
	v_cndmask_b32_e64 v26, v21, v26, s[6:7]
	v_mul_f32 v28, v30, v26
	v_mul_f32 v29, v31, v26
	v_mul_f32 v22, v22, v26
	v_mul_f32 v23, v23, v26
	v_mul_f32 v28, v0, v28
	v_mul_f32 v29, v1, v29
	v_mul_f32 v22, v2, v22
	v_mul_f32 v23, v3, v23
	v_mul_f32_e32 v21, 0x4b800000, v20
	v_mul_f32 v24, v24, v28
	v_mul_f32 v25, v25, v29
	v_mul_f32 v22, v34, v22
	v_mul_f32 v23, v35, v23
	v_cndmask_b32_e32 v20, v20, v21, vcc
	v_cvt_pk_bf16_f32 v24, v24, v25
	v_cvt_pk_bf16_f32 v25, v22, v23
	v_rsq_f32_e32 v22, v20
	v_add_co_u32_e64 v20, s[6:7], s8, v36
	v_mul_f32_e32 v23, 0x45800000, v22
	s_nop 0
	v_addc_co_u32_e64 v21, s[6:7], 0, v37, s[6:7]
	flat_store_dwordx2 v[20:21], v[24:25] offset:1024 sc1
	v_mul_f32_e32 v20, 0xbfb8aa3b, v46
	v_mul_f32_e32 v21, 0xbfb8aa3b, v47
	v_exp_f32_e32 v20, v20
	v_exp_f32_e32 v21, v21
	v_cndmask_b32_e32 v22, v22, v23, vcc
	v_mul_f32 v24, v38, v22
	v_mul_f32 v25, v39, v22
	v_add_f32 v20, v20, 1.0
	v_add_f32 v21, v21, 1.0
	s_nop 0
	v_div_scale_f32 v23, s[6:7], v21, v21, v47
	v_mul_f32 v0, v0, v24
	v_mul_f32 v1, v1, v25
	v_rcp_f32_e32 v24, v23
	v_mul_f32 v16, v16, v22
	v_mul_f32 v17, v17, v22
	v_mul_f32 v0, v18, v0
	v_mul_f32 v1, v19, v1
	v_mul_f32 v2, v2, v16
	v_mul_f32 v3, v3, v17
	v_fma_f32 v16, -v23, v24, 1.0
	v_fmac_f32_e32 v24, v16, v24
	v_div_scale_f32 v16, vcc, v47, v21, v47
	v_mul_f32_e32 v17, v16, v24
	v_fma_f32 v18, -v23, v17, v16
	v_fmac_f32_e32 v17, v18, v24
	v_div_scale_f32 v18, s[6:7], v20, v20, v46
	v_rcp_f32_e32 v19, v18
	v_fma_f32 v16, -v23, v17, v16
	v_div_fmas_f32 v16, v16, v24, v17
	v_div_fixup_f32 v17, v16, v21, v47
	v_fma_f32 v16, -v18, v19, 1.0
	v_fmac_f32_e32 v19, v16, v19
	v_div_scale_f32 v16, vcc, v46, v20, v46
	v_mul_f32_e32 v21, v16, v19
	v_fma_f32 v22, -v18, v21, v16
	v_fmac_f32_e32 v21, v22, v19
	v_fma_f32 v16, -v18, v21, v16
	v_div_fmas_f32 v16, v16, v19, v21
	v_div_fixup_f32 v16, v16, v20, v46
	v_mul_f32 v2, v16, v2
	v_mul_f32 v3, v17, v3
	v_cvt_pk_bf16_f32 v0, v0, v1
	v_cvt_pk_bf16_f32 v1, v2, v3
	v_lshlrev_b64 v[2:3], 11, v[8:9]
	v_lshl_add_u64 v[2:3], s[18:19], 0, v[2:3]
	v_lshl_add_u64 v[2:3], v[2:3], 0, v[6:7]
	v_add_co_u32_e32 v2, vcc, 0x4552000, v2
	s_nop 1
	v_addc_co_u32_e32 v3, vcc, 0, v3, vcc
	flat_store_dwordx2 v[2:3], v[0:1] offset:1024 sc1
	s_waitcnt vmcnt(0)
	s_and_saveexec_b64 s[6:7], s[4:5]
	s_cbranch_execz .LBB0_3184
	v_alignbit_b32 v0, v15, v14, 8
	v_alignbit_b32 v1, v5, v4, 8
	v_cmp_eq_u32_e32 vcc, v0, v1
	v_alignbit_b32 v2, v13, v12, 8
	v_alignbit_b32 v3, v9, v8, 8
	v_cndmask_b32_e64 v0, 1, 2, vcc
	v_cmp_eq_u32_e32 vcc, v2, v1
	v_alignbit_b32 v2, v11, v10, 8
	s_mov_b64 s[4:5], s[10:11]
	v_addc_co_u32_e32 v0, vcc, 0, v0, vcc
	v_cmp_eq_u32_e32 vcc, v2, v1
	s_nop 1
	v_cndmask_b32_e64 v2, 0, 1, vcc
	v_cmp_eq_u32_e32 vcc, v3, v1
	s_nop 1
	v_addc_co_u32_e32 v2, vcc, v0, v2, vcc
	v_lshlrev_b32_e32 v0, 6, v1
	v_ashrrev_i32_e32 v1, 31, v0
	v_lshl_add_u64 v[4:5], v[0:1], 2, s[16:17]
	flat_atomic_add v[4:5], v2
	v_cmp_gt_u32_e32 vcc, 5, v2
	s_and_saveexec_b64 s[8:9], vcc
	v_sub_u32_e32 v1, 5, v2
	s_or_b64 s[4:5], s[10:11], exec
	s_or_b64 exec, exec, s[8:9]
	s_andn2_b64 s[8:9], s[10:11], exec
	s_and_b64 s[4:5], s[4:5], exec
	s_or_b64 s[10:11], s[8:9], s[4:5]

.LBB0_3319:
	v_ashrrev_i32_e32 v77, 31, v76
	v_lshlrev_b64 v[0:1], 12, v[76:77]
	v_lshl_add_u64 v[104:105], s[18:19], 0, v[0:1]
	v_add_u32_e32 v0, 0xfffff000, v76
	v_lshrrev_b32_e32 v0, 11, v0
	v_add_u32_e32 v0, 6, v0
	v_cmp_lt_i32_e32 vcc, s33, v76
	v_lshl_add_u64 v[8:9], v[104:105], 0, v[78:79]
	flat_load_dwordx4 v[10:13], v[8:9] offset:2048
	flat_load_dwordx4 v[40:43], v[8:9] offset:3072
	v_cndmask_b32_e32 v85, 5, v0, vcc
	v_mad_u64_u32 v[0:1], s[6:7], v85, s36, v[66:67]
	flat_load_dwordx4 v[44:47], v[0:1]
	global_load_dwordx4 v[48:51], v[64:65], off
	global_load_dwordx4 v[52:55], v[64:65], off offset:16
	flat_load_dwordx4 v[92:95], v[0:1] offset:16
	flat_load_dwordx4 v[96:99], v[0:1] offset:2048
	global_load_dwordx4 v[100:103], v[64:65], off offset:2048
	global_load_dwordx4 v[106:109], v[64:65], off offset:2064
	flat_load_dwordx4 v[120:123], v[0:1] offset:2064
	v_lshlrev_b64 v[0:1], 11, v[76:77]
	v_lshl_add_u64 v[0:1], v[62:63], 0, v[0:1]
	flat_load_dwordx4 v[124:127], v[0:1]
	flat_load_dwordx4 v[128:131], v[0:1] offset:1024
	v_add_u32_e32 v0, 1, v76
	v_ashrrev_i32_e32 v1, 31, v0
	v_lshlrev_b64 v[6:7], 12, v[0:1]
	v_lshlrev_b64 v[0:1], 11, v[0:1]
	v_lshl_add_u64 v[0:1], v[62:63], 0, v[0:1]
	flat_load_dwordx4 v[132:135], v[0:1]
	flat_load_dwordx4 v[136:139], v[0:1] offset:1024
	v_add_u32_e32 v2, 2, v76
	v_add_u32_e32 v4, 3, v76
	v_ashrrev_i32_e32 v3, 31, v2
	v_ashrrev_i32_e32 v5, 31, v4
	v_lshlrev_b64 v[14:15], 12, v[2:3]
	v_lshlrev_b64 v[2:3], 11, v[2:3]
	v_lshlrev_b64 v[16:17], 12, v[4:5]
	v_lshlrev_b64 v[4:5], 11, v[4:5]
	v_lshl_add_u64 v[114:115], s[18:19], 0, v[6:7]
	v_lshl_add_u64 v[112:113], s[18:19], 0, v[14:15]
	v_lshl_add_u64 v[2:3], v[62:63], 0, v[2:3]
	v_lshl_add_u64 v[90:91], v[74:75], 0, v[16:17]
	v_lshl_add_u64 v[14:15], v[62:63], 0, v[4:5]
	v_lshl_add_u64 v[116:117], v[114:115], 0, v[78:79]
	v_lshl_add_u64 v[118:119], v[112:113], 0, v[78:79]
	flat_load_dwordx4 v[144:147], v[2:3]
	flat_load_dwordx4 v[152:155], v[2:3] offset:1024
	flat_load_dwordx4 v[20:23], v[90:91] offset:2048
	flat_load_dwordx4 v[16:19], v[90:91] offset:3072
	flat_load_dwordx4 v[4:7], v[14:15]
	s_nop 0
	flat_load_dwordx4 v[0:3], v[14:15] offset:1024
	flat_load_dwordx4 v[36:39], v[116:117] offset:2048
	flat_load_dwordx4 v[32:35], v[116:117] offset:3072
	flat_load_dwordx4 v[28:31], v[118:119] offset:2048
	flat_load_dwordx4 v[24:27], v[118:119] offset:3072
	s_waitcnt vmcnt(0) lgkmcnt(0)
	v_lshlrev_b32_e32 v14, 16, v10
	v_lshlrev_b32_e32 v142, 16, v40
	v_and_b32_e32 v143, 0xffff0000, v40
	v_lshlrev_b32_e32 v148, 16, v41
	v_and_b32_e32 v149, 0xffff0000, v41
	v_mul_f32 v40, v50, v46
	v_mul_f32 v41, v51, v47
	v_lshlrev_b32_e32 v150, 16, v42
	v_and_b32_e32 v151, 0xffff0000, v42
	v_lshlrev_b32_e32 v156, 16, v43
	v_and_b32_e32 v157, 0xffff0000, v43
	v_mul_f32 v42, v48, v44
	v_mul_f32 v43, v49, v45
	v_mul_f32 v48, v102, v98
	v_mul_f32 v49, v103, v99
	v_mul_f32 v98, v80, v40
	v_mul_f32 v99, v81, v41
	v_lshlrev_b32_e32 v40, 16, v124
	v_and_b32_e32 v41, 0xffff0000, v124
	v_mul_f32 v44, v54, v94
	v_mul_f32 v45, v55, v95
	v_mul_f32 v46, v52, v92
	v_mul_f32 v47, v53, v93
	v_mul_f32 v102, v72, v42
	v_mul_f32 v103, v73, v43
	v_lshlrev_b32_e32 v42, 16, v125
	v_and_b32_e32 v43, 0xffff0000, v125
	v_mul_f32 v158, v40, v40
	v_mul_f32 v159, v41, v41
	v_mul_f32 v50, v100, v96
	v_mul_f32 v51, v101, v97
	v_mul_f32 v54, v106, v120
	v_mul_f32 v55, v107, v121
	v_mul_f32 v94, v80, v44
	v_mul_f32 v95, v81, v45
	v_mul_f32 v100, v72, v46
	v_mul_f32 v101, v73, v47
	v_lshlrev_b32_e32 v44, 16, v126
	v_and_b32_e32 v45, 0xffff0000, v126
	v_lshlrev_b32_e32 v46, 16, v127
	v_and_b32_e32 v47, 0xffff0000, v127
	v_lshlrev_b32_e32 v120, 16, v130
	v_and_b32_e32 v121, 0xffff0000, v130
	v_lshlrev_b32_e32 v126, 16, v131
	v_and_b32_e32 v127, 0xffff0000, v131
	v_mul_f32 v130, v42, v42
	v_mul_f32 v131, v43, v43
	v_add_f32_e32 v56, v158, v159
	v_add_f32_e32 v56, v130, v56
	v_mul_f32 v92, v80, v48
	v_mul_f32 v93, v81, v49
	v_mul_f32 v96, v72, v50
	v_mul_f32 v97, v73, v51
	v_lshlrev_b32_e32 v48, 16, v128
	v_and_b32_e32 v49, 0xffff0000, v128
	v_lshlrev_b32_e32 v50, 16, v129
	v_and_b32_e32 v51, 0xffff0000, v129
	v_mul_f32 v128, v44, v44
	v_mul_f32 v129, v45, v45
	v_add_f32_e32 v56, v131, v56
	v_add_f32_e32 v56, v128, v56
	v_mul_f32 v124, v46, v46
	v_mul_f32 v125, v47, v47
	v_add_f32_e32 v56, v129, v56
	v_add_f32_e32 v56, v124, v56
	v_mul_f32 v52, v108, v122
	v_mul_f32 v53, v109, v123
	v_mul_f32 v122, v48, v48
	v_mul_f32 v123, v49, v49
	v_add_f32_e32 v56, v125, v56
	v_add_f32_e32 v56, v122, v56
	v_mul_f32 v110, v50, v50
	v_mul_f32 v111, v51, v51
	v_add_f32_e32 v56, v123, v56
	v_add_f32_e32 v56, v110, v56
	v_mul_f32 v108, v120, v120
	v_mul_f32 v109, v121, v121
	v_add_f32_e32 v56, v111, v56
	v_add_f32_e32 v56, v108, v56
	v_mul_f32 v106, v126, v126
	v_mul_f32 v107, v127, v127
	v_add_f32_e32 v56, v109, v56
	v_add_f32_e32 v56, v106, v56
	v_add_f32_e32 v56, v107, v56
	v_lshlrev_b32_e32 v106, 16, v132
	v_and_b32_e32 v107, 0xffff0000, v132
	v_add_f32_dpp v56, v56, v56 quad_perm:[1,0,3,2] row_mask:0xf bank_mask:0xf bound_ctrl:1
	v_lshlrev_b32_e32 v108, 16, v133
	v_and_b32_e32 v109, 0xffff0000, v133
	v_add_f32_dpp v56, v56, v56 quad_perm:[2,3,0,1] row_mask:0xf bank_mask:0xf bound_ctrl:1
	v_mul_f32 v170, v106, v106
	v_mul_f32 v171, v107, v107
	v_mul_f32 v158, v108, v108
	v_mul_f32 v159, v109, v109
	v_add_f32_dpp v56, v56, v56 row_half_mirror row_mask:0xf bank_mask:0xf bound_ctrl:1
	v_lshlrev_b32_e32 v110, 16, v134
	v_and_b32_e32 v111, 0xffff0000, v134
	v_add_f32_dpp v56, v56, v56 row_mirror row_mask:0xf bank_mask:0xf bound_ctrl:1
	v_mov_b32_e32 v77, v56
	s_nop 1
	v_permlane16_swap_b32_e32 v56, v77
	v_add_f32_e32 v123, v56, v77
	v_add_f32_e32 v56, v170, v171
	v_add_f32_e32 v56, v158, v56
	v_lshlrev_b32_e32 v166, 16, v138
	v_and_b32_e32 v167, 0xffff0000, v138
	v_lshlrev_b32_e32 v168, 16, v139
	v_and_b32_e32 v169, 0xffff0000, v139
	v_mul_f32 v138, v110, v110
	v_mul_f32 v139, v111, v111
	v_add_f32_e32 v56, v159, v56
	v_lshlrev_b32_e32 v160, 16, v135
	v_and_b32_e32 v161, 0xffff0000, v135
	v_add_f32_e32 v56, v138, v56
	v_lshlrev_b32_e32 v162, 16, v136
	v_and_b32_e32 v163, 0xffff0000, v136
	v_lshlrev_b32_e32 v164, 16, v137
	v_and_b32_e32 v165, 0xffff0000, v137
	v_mul_f32 v136, v160, v160
	v_mul_f32 v137, v161, v161
	v_add_f32_e32 v56, v139, v56
	v_add_f32_e32 v56, v136, v56
	v_mul_f32 v134, v162, v162
	v_mul_f32 v135, v163, v163
	v_add_f32_e32 v56, v137, v56
	v_add_f32_e32 v56, v134, v56
	v_mul_f32 v132, v164, v164
	v_mul_f32 v133, v165, v165
	v_add_f32_e32 v56, v135, v56
	v_add_f32_e32 v56, v132, v56
	v_mul_f32 v130, v166, v166
	v_mul_f32 v131, v167, v167
	v_add_f32_e32 v56, v133, v56
	v_add_f32_e32 v56, v130, v56
	v_mul_f32 v128, v168, v168
	v_mul_f32 v129, v169, v169
	v_add_f32_e32 v56, v131, v56
	v_add_f32_e32 v56, v128, v56
	v_add_f32_e32 v56, v129, v56
	v_mov_b32_e32 v125, v123
	s_nop 1
	v_permlane32_swap_b32_e32 v123, v125
	v_add_f32_dpp v56, v56, v56 quad_perm:[1,0,3,2] row_mask:0xf bank_mask:0xf bound_ctrl:1
	v_and_b32_e32 v15, 0xffff0000, v10
	v_lshlrev_b32_e32 v10, 16, v11
	v_add_f32_dpp v56, v56, v56 quad_perm:[2,3,0,1] row_mask:0xf bank_mask:0xf bound_ctrl:1
	v_and_b32_e32 v11, 0xffff0000, v11
	v_lshlrev_b32_e32 v140, 16, v12
	v_add_f32_dpp v56, v56, v56 row_half_mirror row_mask:0xf bank_mask:0xf bound_ctrl:1
	v_and_b32_e32 v141, 0xffff0000, v12
	v_lshlrev_b32_e32 v12, 16, v13
	v_add_f32_dpp v56, v56, v56 row_mirror row_mask:0xf bank_mask:0xf bound_ctrl:1
	v_mov_b32_e32 v77, v56
	s_nop 1
	v_permlane16_swap_b32_e32 v56, v77
	v_add_f32_e32 v122, v56, v77
	v_mov_b32_e32 v124, v122
	s_nop 1
	v_permlane32_swap_b32_e32 v122, v124
	v_add_f32 v122, v122, v124
	v_add_f32 v123, v123, v125
	v_mul_f32 v124, v72, v54
	v_mul_f32 v125, v73, v55
	v_fma_f32 v170, v122, s24, v82
	v_fma_f32 v171, v123, s24, v82
	v_mul_f32 v122, v80, v52
	v_mul_f32 v123, v81, v53
	v_mul_f32_e32 v56, 0x4b800000, v171
	v_cmp_gt_f32_e32 vcc, s37, v171
	v_and_b32_e32 v13, 0xffff0000, v13
	v_lshlrev_b32_e32 v136, 16, v1
	v_cndmask_b32_e32 v56, v171, v56, vcc
	v_rsq_f32_e32 v56, v56
	v_and_b32_e32 v137, 0xffff0000, v1
	v_lshlrev_b32_e32 v138, 16, v2
	v_and_b32_e32 v139, 0xffff0000, v2
	v_mul_f32_e32 v52, 0x45800000, v56
	v_cndmask_b32_e32 v54, v56, v52, vcc
	v_mul_f32 v40, v54, v40
	v_mul_f32 v41, v54, v41
	v_fma_f32 v40, v102, v40, v14
	v_fma_f32 v41, v103, v41, v15
	v_mul_f32 v14, v54, v42
	v_mul_f32 v15, v54, v43
	v_fma_f32 v42, v98, v14, v10
	v_fma_f32 v43, v99, v15, v11
	v_mul_f32 v10, v54, v44
	v_mul_f32 v11, v54, v45
	v_fma_f32 v44, v100, v10, v140
	v_fma_f32 v45, v101, v11, v141
	v_mul_f32 v10, v54, v46
	v_mul_f32 v11, v54, v47
	v_fma_f32 v46, v94, v10, v12
	v_fma_f32 v47, v95, v11, v13
	v_mul_f32 v10, v54, v48
	v_mul_f32 v11, v54, v49
	v_fma_f32 v48, v96, v10, v142
	v_fma_f32 v49, v97, v11, v143
	v_mul_f32 v10, v54, v50
	v_mul_f32 v11, v54, v51
	v_fma_f32 v50, v92, v10, v148
	v_fma_f32 v51, v93, v11, v149
	v_mul_f32 v10, v54, v120
	v_mul_f32 v11, v54, v121
	v_lshlrev_b32_e32 v120, 16, v144
	v_and_b32_e32 v121, 0xffff0000, v144
	v_lshlrev_b32_e32 v142, 16, v145
	v_and_b32_e32 v143, 0xffff0000, v145
	v_mul_f32 v134, v120, v120
	v_mul_f32 v135, v121, v121
	v_mul_f32 v132, v142, v142
	v_mul_f32 v133, v143, v143
	v_add_f32_e32 v56, v134, v135
	v_lshlrev_b32_e32 v144, 16, v146
	v_and_b32_e32 v145, 0xffff0000, v146
	v_add_f32_e32 v56, v132, v56
	v_mul_f32 v130, v144, v144
	v_mul_f32 v131, v145, v145
	v_add_f32_e32 v56, v133, v56
	v_lshlrev_b32_e32 v146, 16, v147
	v_and_b32_e32 v147, 0xffff0000, v147
	v_add_f32_e32 v56, v130, v56
	v_mul_f32 v128, v146, v146
	v_mul_f32 v129, v147, v147
	v_add_f32_e32 v56, v131, v56
	v_lshlrev_b32_e32 v148, 16, v152
	v_and_b32_e32 v149, 0xffff0000, v152
	v_add_f32_e32 v56, v128, v56
	v_fma_f32 v52, v124, v10, v150
	v_fma_f32 v53, v125, v11, v151
	v_mul_f32 v10, v54, v126
	v_mul_f32 v11, v54, v127
	v_mul_f32 v126, v148, v148
	v_mul_f32 v127, v149, v149
	v_add_f32_e32 v56, v129, v56
	v_lshlrev_b32_e32 v150, 16, v153
	v_and_b32_e32 v151, 0xffff0000, v153
	v_add_f32_e32 v56, v126, v56
	v_mul_f32 v14, v150, v150
	v_mul_f32 v15, v151, v151
	v_add_f32_e32 v56, v127, v56
	v_lshlrev_b32_e32 v152, 16, v154
	v_and_b32_e32 v153, 0xffff0000, v154
	v_add_f32_e32 v14, v14, v56
	v_mul_f32 v12, v152, v152
	v_mul_f32 v13, v153, v153
	v_add_f32_e32 v14, v15, v14
	v_lshlrev_b32_e32 v154, 16, v155
	v_and_b32_e32 v155, 0xffff0000, v155
	v_add_f32_e32 v12, v12, v14
	v_fma_f32 v54, v122, v10, v156
	v_fma_f32 v55, v123, v11, v157
	v_mul_f32 v10, v154, v154
	v_mul_f32 v11, v155, v155
	v_add_f32_e32 v12, v13, v12
	v_add_f32_e32 v10, v10, v12
	v_add_f32_e32 v10, v11, v10
	v_lshlrev_b32_e32 v126, 16, v4
	v_and_b32_e32 v127, 0xffff0000, v4
	v_add_f32_dpp v10, v10, v10 quad_perm:[1,0,3,2] row_mask:0xf bank_mask:0xf bound_ctrl:1
	v_lshlrev_b32_e32 v128, 16, v5
	v_and_b32_e32 v129, 0xffff0000, v5
	v_add_f32_dpp v10, v10, v10 quad_perm:[2,3,0,1] row_mask:0xf bank_mask:0xf bound_ctrl:1
	v_mul_f32 v176, v126, v126
	v_mul_f32 v177, v127, v127
	v_mul_f32 v14, v128, v128
	v_mul_f32 v15, v129, v129
	v_add_f32_dpp v10, v10, v10 row_half_mirror row_mask:0xf bank_mask:0xf bound_ctrl:1
	v_add_f32_e32 v56, v176, v177
	v_lshlrev_b32_e32 v130, 16, v6
	v_add_f32_dpp v10, v10, v10 row_mirror row_mask:0xf bank_mask:0xf bound_ctrl:1
	v_and_b32_e32 v131, 0xffff0000, v6
	v_add_f32_e32 v14, v14, v56
	v_mov_b32_e32 v11, v10
	v_mul_f32 v12, v130, v130
	v_mul_f32 v13, v131, v131
	v_add_f32_e32 v14, v15, v14
	v_permlane16_swap_b32_e32 v10, v11
	v_lshlrev_b32_e32 v132, 16, v7
	v_and_b32_e32 v133, 0xffff0000, v7
	v_add_f32_e32 v12, v12, v14
	v_add_f32_e32 v157, v10, v11
	v_mul_f32 v10, v132, v132
	v_mul_f32 v11, v133, v133
	v_add_f32_e32 v12, v13, v12
	v_lshlrev_b32_e32 v134, 16, v0
	v_and_b32_e32 v135, 0xffff0000, v0
	v_add_f32_e32 v10, v10, v12
	v_mul_f32 v6, v134, v134
	v_mul_f32 v7, v135, v135
	v_add_f32_e32 v10, v11, v10
	v_add_f32_e32 v6, v6, v10
	v_mul_f32 v4, v136, v136
	v_mul_f32 v5, v137, v137
	v_add_f32_e32 v6, v7, v6
	v_add_f32_e32 v4, v4, v6
	v_lshlrev_b32_e32 v140, 16, v3
	v_and_b32_e32 v141, 0xffff0000, v3
	v_mul_f32 v2, v138, v138
	v_mul_f32 v3, v139, v139
	v_add_f32_e32 v4, v5, v4
	v_add_f32_e32 v2, v2, v4
	v_mul_f32 v0, v140, v140
	v_mul_f32 v1, v141, v141
	v_add_f32_e32 v2, v3, v2
	v_add_f32_e32 v0, v0, v2
	v_add_f32_e32 v0, v1, v0
	v_mov_b32_e32 v159, v157
	v_cmp_gt_f32_e64 s[6:7], s37, v170
	v_add_f32_dpp v0, v0, v0 quad_perm:[1,0,3,2] row_mask:0xf bank_mask:0xf bound_ctrl:1
	v_permlane32_swap_b32_e32 v157, v159
	s_nop 0
	v_add_f32_dpp v0, v0, v0 quad_perm:[2,3,0,1] row_mask:0xf bank_mask:0xf bound_ctrl:1
	s_and_b64 vcc, exec, s[22:23]
	s_nop 0
	v_add_f32_dpp v0, v0, v0 row_half_mirror row_mask:0xf bank_mask:0xf bound_ctrl:1
	s_nop 1
	v_add_f32_dpp v0, v0, v0 row_mirror row_mask:0xf bank_mask:0xf bound_ctrl:1
	v_mov_b32_e32 v1, v0
	s_nop 1
	v_permlane16_swap_b32_e32 v0, v1
	v_add_f32_e32 v156, v0, v1
	v_mov_b32_e32 v158, v156
	s_nop 1
	v_permlane32_swap_b32_e32 v156, v158
	s_cbranch_vccz .LBB0_3334
	v_cvt_pk_bf16_f32 v0, v40, v41
	v_cvt_pk_bf16_f32 v1, v42, v43
	v_cvt_pk_bf16_f32 v2, v44, v45
	v_cvt_pk_bf16_f32 v3, v46, v47
	v_cvt_pk_bf16_f32 v176, v48, v49
	v_cvt_pk_bf16_f32 v177, v50, v51
	v_cvt_pk_bf16_f32 v178, v52, v53
	v_cvt_pk_bf16_f32 v179, v54, v55
	flat_store_dwordx4 v[8:9], v[0:3] offset:2048
	v_lshlrev_b32_e32 v4, 16, v0
	v_and_b32_e32 v5, 0xffff0000, v0
	v_lshlrev_b32_e32 v6, 16, v1
	v_and_b32_e32 v7, 0xffff0000, v1
	v_lshlrev_b32_e32 v12, 16, v2
	v_and_b32_e32 v13, 0xffff0000, v2
	v_lshlrev_b32_e32 v14, 16, v3
	v_and_b32_e32 v15, 0xffff0000, v3
	flat_store_dwordx4 v[8:9], v[176:179] offset:3072
	v_lshlrev_b32_e32 v0, 16, v176
	v_and_b32_e32 v1, 0xffff0000, v176
	v_lshlrev_b32_e32 v2, 16, v177
	v_and_b32_e32 v3, 0xffff0000, v177
	v_lshlrev_b32_e32 v8, 16, v178
	v_and_b32_e32 v9, 0xffff0000, v178
	v_lshlrev_b32_e32 v10, 16, v179
	v_and_b32_e32 v11, 0xffff0000, v179
	v_lshlrev_b32_e32 v56, 2, v58
	s_cbranch_execnz .LBB0_3322

.LBB0_3325:
	v_add_f32 v36, v156, v158
	v_add_f32 v37, v157, v159
	v_lshlrev_b32_e32 v42, 16, v26
	v_fma_f32 v156, v36, s24, v82
	v_fma_f32 v157, v37, s24, v82
	v_and_b32_e32 v43, 0xffff0000, v26
	v_mul_f32_e32 v26, 0x4b800000, v157
	v_cmp_gt_f32_e32 vcc, s37, v157
	v_lshlrev_b32_e32 v32, 16, v28
	v_and_b32_e32 v33, 0xffff0000, v28
	v_cndmask_b32_e32 v26, v157, v26, vcc
	v_rsq_f32_e32 v36, v26
	v_lshlrev_b32_e32 v28, 16, v29
	v_and_b32_e32 v29, 0xffff0000, v29
	v_lshlrev_b32_e32 v34, 16, v30
	v_mul_f32_e32 v37, 0x45800000, v36
	v_cndmask_b32_e32 v44, v36, v37, vcc
	v_mul_f32 v36, v44, v120
	v_mul_f32 v37, v44, v121
	v_fma_f32 v36, v102, v36, v32
	v_fma_f32 v37, v103, v37, v33
	v_mul_f32 v32, v44, v142
	v_mul_f32 v33, v44, v143
	v_and_b32_e32 v35, 0xffff0000, v30
	v_fma_f32 v38, v98, v32, v28
	v_fma_f32 v39, v99, v33, v29
	v_mul_f32 v28, v44, v144
	v_mul_f32 v29, v44, v145
	v_lshlrev_b32_e32 v30, 16, v31
	v_and_b32_e32 v31, 0xffff0000, v31
	v_fma_f32 v32, v100, v28, v34
	v_fma_f32 v33, v101, v29, v35
	v_mul_f32 v28, v44, v146
	v_mul_f32 v29, v44, v147
	v_lshlrev_b32_e32 v40, 16, v24
	v_and_b32_e32 v41, 0xffff0000, v24
	v_lshlrev_b32_e32 v24, 16, v25
	v_and_b32_e32 v25, 0xffff0000, v25
	v_fma_f32 v34, v94, v28, v30
	v_fma_f32 v35, v95, v29, v31
	v_mul_f32 v28, v44, v148
	v_mul_f32 v29, v44, v149
	v_mul_f32 v30, v44, v150
	v_mul_f32 v31, v44, v151
	v_lshlrev_b32_e32 v26, 16, v27
	v_and_b32_e32 v27, 0xffff0000, v27
	v_fma_f32 v28, v96, v28, v40
	v_fma_f32 v29, v97, v29, v41
	v_fma_f32 v30, v92, v30, v24
	v_fma_f32 v31, v93, v31, v25
	v_mul_f32 v24, v44, v152
	v_mul_f32 v25, v44, v153
	v_mul_f32 v40, v44, v154
	v_mul_f32 v41, v44, v155
	v_cmp_gt_f32_e64 s[8:9], s37, v156
	v_fma_f32 v24, v124, v24, v42
	v_fma_f32 v25, v125, v25, v43
	s_and_b64 vcc, exec, s[6:7]
	v_fma_f32 v26, v122, v40, v26
	v_fma_f32 v27, v123, v41, v27
	s_cbranch_vccnz .LBB0_3336
	v_cvt_pk_bf16_f32 v42, v36, v37
	v_cvt_pk_bf16_f32 v43, v38, v39
	v_cvt_pk_bf16_f32 v44, v32, v33
	v_cvt_pk_bf16_f32 v45, v34, v35
	v_cvt_pk_bf16_f32 v142, v28, v29
	v_cvt_pk_bf16_f32 v143, v30, v31
	v_cvt_pk_bf16_f32 v144, v24, v25
	v_cvt_pk_bf16_f32 v145, v26, v27
	flat_store_dwordx4 v[118:119], v[42:45] offset:2048
	v_lshlrev_b32_e32 v116, 16, v42
	v_and_b32_e32 v117, 0xffff0000, v42
	v_lshlrev_b32_e32 v42, 16, v43
	v_and_b32_e32 v43, 0xffff0000, v43
	v_lshlrev_b32_e32 v120, 16, v44
	v_and_b32_e32 v121, 0xffff0000, v44
	v_lshlrev_b32_e32 v114, 16, v45
	v_and_b32_e32 v115, 0xffff0000, v45
	flat_store_dwordx4 v[118:119], v[142:145] offset:3072
	v_lshlrev_b32_e32 v46, 16, v142
	v_and_b32_e32 v47, 0xffff0000, v142
	v_lshlrev_b32_e32 v40, 16, v143
	v_and_b32_e32 v41, 0xffff0000, v143
	v_lshlrev_b32_e32 v118, 16, v144
	v_and_b32_e32 v119, 0xffff0000, v144
	v_lshlrev_b32_e32 v44, 16, v145
	v_and_b32_e32 v45, 0xffff0000, v145
	s_cbranch_execnz .LBB0_3328

.LBB0_3331:
	s_and_b64 vcc, exec, s[6:7]
	s_cbranch_vccnz .LBB0_3318
	v_mul_hi_u32_u24_e32 v17, 0x6000, v85
	v_mul_u32_u24_e32 v16, 0x6000, v85
	v_lshl_add_u64 v[16:17], s[20:21], 0, v[16:17]
	v_lshl_add_u64 v[18:19], v[16:17], 0, s[28:29]
	v_lshl_add_u64 v[20:21], v[18:19], 0, v[56:57]
	v_mov_b32_e32 v85, v57
	flat_load_dwordx4 v[100:103], v[20:21]
	v_lshl_add_u64 v[20:21], v[18:19], 0, v[84:85]
	v_mov_b32_e32 v87, v57
	flat_load_dwordx4 v[122:125], v[20:21]
	v_lshl_add_u64 v[20:21], v[18:19], 0, v[86:87]
	v_mov_b32_e32 v89, v57
	flat_load_dwordx4 v[126:129], v[20:21]
	v_lshl_add_u64 v[18:19], v[18:19], 0, v[88:89]
	flat_load_dwordx4 v[130:133], v[18:19]
	global_load_dwordx4 v[134:137], v[68:69], off
	global_load_dwordx4 v[138:141], v[68:69], off offset:16
	global_load_dwordx4 v[142:145], v[70:71], off
	global_load_dwordx4 v[146:149], v[70:71], off offset:16
	v_lshl_add_u64 v[16:17], v[16:17], 0, s[30:31]
	v_lshl_add_u64 v[18:19], v[16:17], 0, v[56:57]
	flat_load_dwordx4 v[28:31], v[18:19]
	v_lshl_add_u64 v[18:19], v[16:17], 0, v[84:85]
	flat_load_dwordx4 v[24:27], v[18:19]
	v_lshl_add_u64 v[18:19], v[16:17], 0, v[86:87]
	flat_load_dwordx4 v[20:23], v[18:19]
	v_lshl_add_u64 v[16:17], v[16:17], 0, v[88:89]
	flat_load_dwordx4 v[16:19], v[16:17]
	v_mul_f32_e32 v77, v5, v5
	v_mul_f32_e32 v90, v13, v13
	v_mul_f32_e32 v91, v1, v1
	v_fmac_f32_e32 v77, v4, v4
	v_fmac_f32_e32 v90, v12, v12
	v_mul_f32_e32 v112, v9, v9
	v_fmac_f32_e32 v91, v0, v0
	v_fmac_f32_e32 v77, v6, v6
	v_fmac_f32_e32 v90, v14, v14
	v_fmac_f32_e32 v112, v8, v8
	v_fmac_f32_e32 v91, v2, v2
	v_fmac_f32_e32 v77, v7, v7
	v_fmac_f32_e32 v90, v15, v15
	v_fmac_f32_e32 v112, v10, v10
	v_fmac_f32_e32 v91, v3, v3
	v_add_f32_e32 v56, v90, v77
	v_fmac_f32_e32 v112, v11, v11
	v_add_f32_e32 v56, v91, v56
	v_add_f32_e32 v56, v112, v56
	v_mul_f32_e32 v113, v111, v111
	v_mul_f32_e32 v150, v109, v109
	v_add_f32_dpp v56, v56, v56 quad_perm:[1,0,3,2] row_mask:0xf bank_mask:0xf bound_ctrl:1
	v_mul_f32_e32 v152, v55, v55
	v_fmac_f32_e32 v113, v110, v110
	v_add_f32_dpp v56, v56, v56 quad_perm:[2,3,0,1] row_mask:0xf bank_mask:0xf bound_ctrl:1
	v_fmac_f32_e32 v150, v108, v108
	v_fmac_f32_e32 v152, v54, v54
	v_add_f32_dpp v56, v56, v56 row_half_mirror row_mask:0xf bank_mask:0xf bound_ctrl:1
	v_fmac_f32_e32 v113, v106, v106
	v_fmac_f32_e32 v150, v104, v104
	v_add_f32_dpp v56, v56, v56 row_mirror row_mask:0xf bank_mask:0xf bound_ctrl:1
	v_fmac_f32_e32 v152, v50, v50
	v_fmac_f32_e32 v113, v107, v107
	v_fmac_f32_e32 v150, v105, v105
	v_mov_b32_e32 v85, v56
	v_fmac_f32_e32 v152, v51, v51
	v_add_f32_e32 v77, v113, v150
	v_permlane16_swap_b32_e32 v56, v85
	v_add_f32_e32 v151, v56, v85
	v_add_f32_e32 v56, v77, v152
	v_mul_f32_e32 v77, v53, v53
	v_fmac_f32_e32 v77, v52, v52
	v_fmac_f32_e32 v77, v48, v48
	v_fmac_f32_e32 v77, v49, v49
	v_add_f32_e32 v56, v56, v77
	v_mov_b32_e32 v153, v151
	s_nop 1
	v_permlane32_swap_b32_e32 v151, v153
	v_add_f32_dpp v56, v56, v56 quad_perm:[1,0,3,2] row_mask:0xf bank_mask:0xf bound_ctrl:1
	v_add_u32_e32 v85, 0xffffe800, v83
	s_waitcnt vmcnt(0) lgkmcnt(0)
	v_add_f32 v90, v102, 1.0
	v_add_f32 v91, v103, 1.0
	v_add_f32_dpp v56, v56, v56 quad_perm:[2,3,0,1] row_mask:0xf bank_mask:0xf bound_ctrl:1
	v_add_f32 v100, v100, 1.0
	v_add_f32 v101, v101, 1.0
	v_add_f32 v132, v132, 1.0
	v_add_f32 v133, v133, 1.0
	v_add_f32_dpp v56, v56, v56 row_half_mirror row_mask:0xf bank_mask:0xf bound_ctrl:1
	v_add_f32 v102, v124, 1.0
	v_add_f32 v103, v125, 1.0
	v_add_f32 v128, v128, 1.0
	v_add_f32 v129, v129, 1.0
	v_add_f32_dpp v56, v56, v56 row_mirror row_mask:0xf bank_mask:0xf bound_ctrl:1
	v_mov_b32_e32 v77, v56
	s_nop 1
	v_permlane16_swap_b32_e32 v56, v77
	v_add_f32_e32 v150, v56, v77
	v_mov_b32_e32 v152, v150
	s_nop 1
	v_permlane32_swap_b32_e32 v150, v152
	v_add_f32 v124, v122, 1.0
	v_add_f32 v125, v123, 1.0
	v_add_f32 v154, v126, 1.0
	v_add_f32 v155, v127, 1.0
	v_mul_f32 v122, v136, v90
	v_mul_f32 v123, v137, v91
	v_mul_f32 v126, v134, v100
	v_mul_f32 v127, v135, v101
	v_mul_f32 v100, v144, v128
	v_mul_f32 v101, v145, v129
	v_mul_f32 v90, v148, v132
	v_mul_f32 v91, v149, v133
	v_add_f32 v128, v150, v152
	v_add_f32 v129, v151, v153
	v_mov_b64_e32 v[132:133], s[26:27]
	v_fma_f32 v134, v128, s24, v132
	v_fma_f32 v135, v129, s24, v132
	v_mul_f32 v112, v140, v102
	v_mul_f32 v113, v141, v103
	v_mul_f32_e32 v56, 0x4b800000, v135
	v_cmp_gt_f32_e32 vcc, s37, v135
	v_mul_f32 v102, v142, v154
	v_mul_f32 v103, v143, v155
	v_mul_f32 v124, v138, v124
	v_mul_f32 v125, v139, v125
	v_cndmask_b32_e32 v56, v135, v56, vcc
	v_rsq_f32_e32 v56, v56
	v_add_u32_e32 v77, 0xffffe400, v83
	v_add_f32 v130, v130, 1.0
	v_add_f32 v131, v131, 1.0
	v_mul_f32_e32 v87, 0x45800000, v56
	v_cndmask_b32_e32 v56, v56, v87, vcc
	v_mul_f32 v0, v0, v56
	v_mul_f32 v1, v1, v56
	v_mul_f32 v2, v2, v56
	v_mul_f32 v3, v3, v56
	v_mul_f32 v4, v4, v56
	v_mul_f32 v5, v5, v56
	v_mul_f32 v12, v12, v56
	v_mul_f32 v13, v13, v56
	v_mul_f32 v6, v6, v56
	v_mul_f32 v7, v7, v56
	v_mul_f32 v14, v14, v56
	v_mul_f32 v15, v15, v56
	v_fma_f32 v0, v102, v0, v20
	v_fma_f32 v1, v103, v1, v21
	v_fma_f32 v2, v100, v2, v22
	v_fma_f32 v3, v101, v3, v23
	v_fma_f32 v4, v126, v4, v28
	v_fma_f32 v5, v127, v5, v29
	v_fma_f32 v12, v124, v12, v24
	v_fma_f32 v13, v125, v13, v25
	v_fma_f32 v6, v122, v6, v30
	v_fma_f32 v7, v123, v7, v31
	v_fma_f32 v14, v112, v14, v26
	v_fma_f32 v15, v113, v15, v27
	v_cvt_pk_bf16_f32 v0, v0, v1
	v_cvt_pk_bf16_f32 v1, v2, v3
	v_mul_f32_e32 v2, 0x4b800000, v134
	v_cmp_gt_f32_e32 vcc, s37, v134
	v_cvt_pk_bf16_f32 v4, v4, v5
	v_cvt_pk_bf16_f32 v5, v6, v7
	v_cvt_pk_bf16_f32 v6, v12, v13
	v_cvt_pk_bf16_f32 v7, v14, v15
	v_cndmask_b32_e32 v2, v134, v2, vcc
	buffer_store_dwordx4 v[4:7], v77, s[12:15], 0 offen sc1
	v_mul_f32 v128, v146, v130
	v_mul_f32 v129, v147, v131
	v_add_u32_e32 v12, 0xfffff800, v83
	v_mul_f32 v4, v8, v56
	v_mul_f32 v5, v9, v56
	v_rsq_f32_e32 v8, v2
	v_mul_f32 v6, v10, v56
	v_mul_f32 v7, v11, v56
	v_fma_f32 v4, v128, v4, v16
	v_fma_f32 v5, v129, v5, v17
	v_fma_f32 v6, v90, v6, v18
	v_fma_f32 v7, v91, v7, v19
	v_cvt_pk_bf16_f32 v2, v4, v5
	v_cvt_pk_bf16_f32 v3, v6, v7
	buffer_store_dwordx4 v[0:3], v85, s[12:15], 0 offen sc1
	s_nop 1
	v_mul_f32_e32 v0, 0x45800000, v8
	v_cndmask_b32_e32 v4, v8, v0, vcc
	v_mul_f32 v0, v110, v4
	v_mul_f32 v1, v111, v4
	v_mul_f32 v2, v108, v4
	v_mul_f32 v3, v109, v4
	v_mul_f32 v6, v106, v4
	v_mul_f32 v7, v107, v4
	v_mul_f32 v8, v104, v4
	v_mul_f32 v9, v105, v4
	v_fma_f32 v0, v126, v0, v28
	v_fma_f32 v1, v127, v1, v29
	v_fma_f32 v2, v124, v2, v24
	v_fma_f32 v3, v125, v3, v25
	v_fma_f32 v6, v122, v6, v30
	v_fma_f32 v7, v123, v7, v31
	v_fma_f32 v8, v112, v8, v26
	v_fma_f32 v9, v113, v9, v27
	v_cvt_pk_bf16_f32 v0, v0, v1
	v_cvt_pk_bf16_f32 v1, v6, v7
	v_cvt_pk_bf16_f32 v2, v2, v3
	v_cvt_pk_bf16_f32 v3, v8, v9
	v_add_u32_e32 v5, 0xffffec00, v83
	buffer_store_dwordx4 v[0:3], v5, s[12:15], 0 offen sc1
	v_mul_f32 v6, v50, v4
	v_mul_f32 v7, v51, v4
	v_add_u32_e32 v8, 0xfffff000, v83
	v_mul_f32 v0, v54, v4
	v_mul_f32 v1, v55, v4
	v_mul_f32 v2, v52, v4
	v_mul_f32 v3, v53, v4
	v_mul_f32 v5, v49, v4
	v_mul_f32 v4, v48, v4
	v_fma_f32 v2, v128, v2, v16
	v_fma_f32 v3, v129, v3, v17
	v_fma_f32 v4, v90, v4, v18
	v_fma_f32 v5, v91, v5, v19
	v_cvt_pk_bf16_f32 v2, v2, v3
	v_cvt_pk_bf16_f32 v3, v4, v5
	v_mul_f32_e32 v4, v117, v117
	v_mul_f32_e32 v5, v121, v121
	v_fmac_f32_e32 v4, v116, v116
	v_fmac_f32_e32 v5, v120, v120
	v_fmac_f32_e32 v4, v42, v42
	v_fmac_f32_e32 v5, v114, v114
	v_fmac_f32_e32 v4, v43, v43
	v_fmac_f32_e32 v5, v115, v115
	v_add_f32_e32 v4, v4, v5
	v_mul_f32_e32 v5, v47, v47
	v_fmac_f32_e32 v5, v46, v46
	v_fmac_f32_e32 v5, v40, v40
	v_fmac_f32_e32 v5, v41, v41
	v_add_f32_e32 v4, v4, v5
	v_mul_f32_e32 v5, v119, v119
	v_fmac_f32_e32 v5, v118, v118
	v_fmac_f32_e32 v5, v44, v44
	v_fmac_f32_e32 v5, v45, v45
	v_add_f32_e32 v4, v4, v5
	v_fma_f32 v0, v102, v0, v20
	v_fma_f32 v1, v103, v1, v21
	v_fma_f32 v6, v100, v6, v22
	v_fma_f32 v7, v101, v7, v23
	v_add_f32_dpp v4, v4, v4 quad_perm:[1,0,3,2] row_mask:0xf bank_mask:0xf bound_ctrl:1
	v_cvt_pk_bf16_f32 v0, v0, v1
	v_cvt_pk_bf16_f32 v1, v6, v7
	v_add_f32_dpp v4, v4, v4 quad_perm:[2,3,0,1] row_mask:0xf bank_mask:0xf bound_ctrl:1
	v_mul_f32_e32 v6, v97, v97
	v_fmac_f32_e32 v6, v96, v96
	v_add_f32_dpp v4, v4, v4 row_half_mirror row_mask:0xf bank_mask:0xf bound_ctrl:1
	v_fmac_f32_e32 v6, v92, v92
	v_fmac_f32_e32 v6, v93, v93
	v_add_f32_dpp v4, v4, v4 row_mirror row_mask:0xf bank_mask:0xf bound_ctrl:1
	v_mov_b32_e32 v5, v4
	s_nop 1
	v_permlane16_swap_b32_e32 v4, v5
	v_add_f32_e32 v5, v4, v5
	v_mul_f32_e32 v4, v99, v99
	v_fmac_f32_e32 v4, v98, v98
	v_fmac_f32_e32 v4, v94, v94
	v_fmac_f32_e32 v4, v95, v95
	v_add_f32_e32 v4, v4, v6
	v_mul_f32_e32 v6, v39, v39
	v_fmac_f32_e32 v6, v38, v38
	v_fmac_f32_e32 v6, v34, v34
	v_fmac_f32_e32 v6, v35, v35
	v_add_f32_e32 v4, v4, v6
	v_mul_f32_e32 v6, v37, v37
	v_fmac_f32_e32 v6, v36, v36
	v_fmac_f32_e32 v6, v32, v32
	v_fmac_f32_e32 v6, v33, v33
	v_add_f32_e32 v4, v4, v6
	v_mov_b32_e32 v7, v5
	s_nop 1
	v_permlane32_swap_b32_e32 v5, v7
	v_add_f32_dpp v4, v4, v4 quad_perm:[1,0,3,2] row_mask:0xf bank_mask:0xf bound_ctrl:1
	buffer_store_dwordx4 v[0:3], v8, s[12:15], 0 offen sc1
	s_nop 0
	v_add_f32_dpp v4, v4, v4 quad_perm:[2,3,0,1] row_mask:0xf bank_mask:0xf bound_ctrl:1
	s_nop 1
	v_add_f32_dpp v4, v4, v4 row_half_mirror row_mask:0xf bank_mask:0xf bound_ctrl:1
	s_nop 1
	v_add_f32_dpp v4, v4, v4 row_mirror row_mask:0xf bank_mask:0xf bound_ctrl:1
	v_mov_b32_e32 v6, v4
	s_nop 1
	v_permlane16_swap_b32_e32 v4, v6
	v_add_f32_e32 v4, v4, v6
	v_mov_b32_e32 v6, v4
	s_nop 1
	v_permlane32_swap_b32_e32 v4, v6
	v_add_f32 v4, v4, v6
	v_add_f32 v5, v5, v7
	v_add_u32_e32 v7, 0xfffff400, v83
	v_fma_f32 v4, v4, s24, v132
	v_fma_f32 v5, v5, s24, v132
	s_nop 0
	v_mul_f32_e32 v6, 0x4b800000, v5
	v_cmp_gt_f32_e32 vcc, s37, v5
	s_nop 1
	v_cndmask_b32_e32 v5, v5, v6, vcc
	v_rsq_f32_e32 v5, v5
	s_nop 0
	v_mul_f32_e32 v0, 0x45800000, v5
	v_cndmask_b32_e32 v6, v5, v0, vcc
	v_mul_f32 v0, v116, v6
	v_mul_f32 v1, v117, v6
	v_mul_f32 v2, v120, v6
	v_mul_f32 v3, v121, v6
	v_mul_f32 v8, v42, v6
	v_mul_f32 v9, v43, v6
	v_mul_f32 v10, v114, v6
	v_mul_f32 v11, v115, v6
	v_mul_f32_e32 v5, 0x4b800000, v4
	v_cmp_gt_f32_e32 vcc, s37, v4
	v_fma_f32 v0, v126, v0, v28
	v_fma_f32 v1, v127, v1, v29
	v_fma_f32 v2, v124, v2, v24
	v_fma_f32 v3, v125, v3, v25
	v_fma_f32 v8, v122, v8, v30
	v_fma_f32 v9, v123, v9, v31
	v_fma_f32 v10, v112, v10, v26
	v_fma_f32 v11, v113, v11, v27
	v_cndmask_b32_e32 v4, v4, v5, vcc
	v_cvt_pk_bf16_f32 v0, v0, v1
	v_cvt_pk_bf16_f32 v1, v8, v9
	v_cvt_pk_bf16_f32 v2, v2, v3
	v_cvt_pk_bf16_f32 v3, v10, v11
	v_rsq_f32_e32 v4, v4
	buffer_store_dwordx4 v[0:3], v7, s[12:15], 0 offen sc1
	v_mul_f32 v8, v40, v6
	v_mul_f32 v9, v41, v6
	s_nop 0
	v_mul_f32 v0, v46, v6
	v_mul_f32 v1, v47, v6
	v_mul_f32 v2, v118, v6
	v_mul_f32 v3, v119, v6
	v_mul_f32 v7, v45, v6
	v_mul_f32 v6, v44, v6
	v_fma_f32 v0, v102, v0, v20
	v_fma_f32 v1, v103, v1, v21
	v_fma_f32 v2, v128, v2, v16
	v_fma_f32 v3, v129, v3, v17
	v_fma_f32 v8, v100, v8, v22
	v_fma_f32 v9, v101, v9, v23
	v_fma_f32 v6, v90, v6, v18
	v_fma_f32 v7, v91, v7, v19
	v_cvt_pk_bf16_f32 v0, v0, v1
	v_cvt_pk_bf16_f32 v1, v8, v9
	v_cvt_pk_bf16_f32 v2, v2, v3
	v_cvt_pk_bf16_f32 v3, v6, v7
	buffer_store_dwordx4 v[0:3], v12, s[12:15], 0 offen sc1
	s_nop 1
	v_mul_f32_e32 v0, 0x45800000, v4
	v_cndmask_b32_e32 v4, v4, v0, vcc
	v_mul_f32 v0, v98, v4
	v_mul_f32 v1, v99, v4
	v_mul_f32 v2, v96, v4
	v_mul_f32 v3, v97, v4
	v_mul_f32 v6, v94, v4
	v_mul_f32 v7, v95, v4
	v_mul_f32 v8, v92, v4
	v_mul_f32 v9, v93, v4
	v_fma_f32 v0, v126, v0, v28
	v_fma_f32 v1, v127, v1, v29
	v_fma_f32 v2, v124, v2, v24
	v_fma_f32 v3, v125, v3, v25
	v_fma_f32 v6, v122, v6, v30
	v_fma_f32 v7, v123, v7, v31
	v_fma_f32 v8, v112, v8, v26
	v_fma_f32 v9, v113, v9, v27
	v_cvt_pk_bf16_f32 v0, v0, v1
	v_cvt_pk_bf16_f32 v1, v6, v7
	v_cvt_pk_bf16_f32 v2, v2, v3
	v_cvt_pk_bf16_f32 v3, v8, v9
	v_add_u32_e32 v5, 0xfffffc00, v83
	buffer_store_dwordx4 v[0:3], v5, s[12:15], 0 offen sc1
	v_mul_f32 v6, v34, v4
	v_mul_f32 v7, v35, v4
	s_nop 0
	v_mul_f32 v0, v38, v4
	v_mul_f32 v1, v39, v4
	v_mul_f32 v2, v36, v4
	v_mul_f32 v3, v37, v4
	v_mul_f32 v5, v33, v4
	v_mul_f32 v4, v32, v4
	v_fma_f32 v0, v102, v0, v20
	v_fma_f32 v1, v103, v1, v21
	v_fma_f32 v2, v128, v2, v16
	v_fma_f32 v3, v129, v3, v17
	v_fma_f32 v6, v100, v6, v22
	v_fma_f32 v7, v101, v7, v23
	v_fma_f32 v4, v90, v4, v18
	v_fma_f32 v5, v91, v5, v19
	v_cvt_pk_bf16_f32 v0, v0, v1
	v_cvt_pk_bf16_f32 v1, v6, v7
	v_cvt_pk_bf16_f32 v2, v2, v3
	v_cvt_pk_bf16_f32 v3, v4, v5
	buffer_store_dwordx4 v[0:3], v83, s[12:15], 0 offen sc1
	s_waitcnt vmcnt(0)
	s_and_saveexec_b64 s[6:7], s[4:5]
	s_cbranch_execz .LBB0_3317
	v_ashrrev_i32_e32 v0, 2, v76
	v_and_b32_e32 v0, 0xffffffc0, v0
	v_ashrrev_i32_e32 v1, 31, v0
	v_lshl_add_u64 v[0:1], v[0:1], 2, s[16:17]
	flat_atomic_add v[0:1], v172
	s_branch .LBB0_3317

.LBB0_3387:
	s_or_b64 exec, exec, s[10:11]
	s_nop 0
	v_or_b32_e32 v120, 0x80, v144
	v_cmp_gt_i32_e64 s[10:11], s81, v120
	s_and_saveexec_b64 s[42:43], s[10:11]
	s_cbranch_execz .LBB0_3389
	v_max_f32_e32 v116, 0, v116
	v_max_f32_e32 v117, 0, v117
	v_max_f32_e32 v118, 0, v118
	v_max_f32_e32 v119, 0, v119
	v_max_f32_e32 v112, 0, v112
	v_max_f32_e32 v113, 0, v113
	v_max_f32_e32 v114, 0, v114
	v_max_f32_e32 v115, 0, v115
	v_mul_f32 v116, v116, v116
	v_mul_f32 v117, v117, v117
	v_mul_f32 v118, v118, v118
	v_mul_f32 v119, v119, v119
	v_mul_f32 v112, v112, v112
	v_mul_f32 v113, v113, v113
	v_mul_f32 v114, v114, v114
	v_mul_f32 v115, v115, v115
	v_cvt_pk_bf16_f32 v112, v112, v113
	v_cvt_pk_bf16_f32 v113, v114, v115
	v_cvt_pk_bf16_f32 v114, v116, v117
	v_cvt_pk_bf16_f32 v115, v118, v119
	flat_store_dwordx4 v[148:149], v[112:115] offset:256

.LBB0_3564:
	v_add_u32_e32 v39, 0xfffff000, v28
	v_ashrrev_i32_e32 v29, 31, v28
	v_add_u32_e32 v38, 1, v28
	v_add_u32_e32 v40, 2, v28
	v_add_u32_e32 v42, 3, v28
	v_lshrrev_b32_e32 v48, 11, v39
	v_lshlrev_b64 v[44:45], 12, v[28:29]
	v_ashrrev_i32_e32 v39, 31, v38
	v_lshlrev_b64 v[46:47], 11, v[28:29]
	v_ashrrev_i32_e32 v41, 31, v40
	v_ashrrev_i32_e32 v43, 31, v42
	v_lshl_add_u64 v[44:45], s[88:89], 0, v[44:45]
	v_lshlrev_b64 v[54:55], 12, v[38:39]
	v_lshl_add_u64 v[50:51], v[18:19], 0, v[46:47]
	v_lshlrev_b64 v[38:39], 11, v[38:39]
	v_lshlrev_b64 v[56:57], 12, v[40:41]
	v_lshlrev_b64 v[40:41], 11, v[40:41]
	v_lshlrev_b64 v[58:59], 12, v[42:43]
	v_add_u32_e32 v29, 6, v48
	v_cmp_lt_i32_e32 vcc, s3, v28
	v_lshl_add_u64 v[60:61], v[44:45], 0, v[30:31]
	v_lshl_add_u64 v[62:63], s[88:89], 0, v[54:55]
	global_load_dwordx4 v[0:3], v[20:21], off offset:16
	global_load_dwordx4 v[4:7], v[20:21], off
	global_load_dwordx4 v[8:11], v[20:21], off offset:2064
	global_load_dwordx4 v[12:15], v[20:21], off offset:2048
	v_lshlrev_b64 v[42:43], 11, v[42:43]
	flat_load_dwordx4 v[46:49], v[50:51]
	v_lshl_add_u64 v[64:65], v[18:19], 0, v[38:39]
	flat_load_dwordx4 v[50:53], v[50:51] offset:1024
	v_lshl_add_u64 v[66:67], s[88:89], 0, v[56:57]
	v_lshl_add_u64 v[40:41], v[18:19], 0, v[40:41]
	v_lshl_add_u64 v[58:59], v[26:27], 0, v[58:59]
	v_cndmask_b32_e32 v29, 5, v29, vcc
	flat_load_dwordx4 v[54:57], v[60:61] offset:2048
	flat_load_dwordx4 v[74:77], v[60:61] offset:3072
	flat_load_dwordx4 v[94:97], v[58:59] offset:2048
	flat_load_dwordx4 v[98:101], v[58:59] offset:3072
	flat_load_dwordx4 v[102:105], v[64:65]
	v_lshl_add_u64 v[60:61], v[62:63], 0, v[30:31]
	v_lshl_add_u64 v[42:43], v[18:19], 0, v[42:43]
	flat_load_dwordx4 v[106:109], v[64:65] offset:1024
	v_lshl_add_u64 v[64:65], v[66:67], 0, v[30:31]
	flat_load_dwordx4 v[110:113], v[40:41]
	flat_load_dwordx4 v[114:117], v[40:41] offset:1024
	flat_load_dwordx4 v[118:121], v[42:43]
	flat_load_dwordx4 v[122:125], v[42:43] offset:1024
	v_mad_u64_u32 v[68:69], s[0:1], v29, s9, v[22:23]
	flat_load_dwordx4 v[126:129], v[60:61] offset:2048
	flat_load_dwordx4 v[130:133], v[60:61] offset:3072
	flat_load_dwordx4 v[134:137], v[64:65] offset:2048
	flat_load_dwordx4 v[138:141], v[64:65] offset:3072
	flat_load_dwordx4 v[142:145], v[68:69]
	flat_load_dwordx4 v[146:149], v[68:69] offset:16
	flat_load_dwordx4 v[150:153], v[68:69] offset:2048
	flat_load_dwordx4 v[154:157], v[68:69] offset:2064
	v_lshl_add_u64 v[40:41], v[58:59], 0, v[16:17]
	v_lshl_add_u64 v[38:39], v[44:45], 0, v[36:37]
	v_lshl_add_u64 v[44:45], v[62:63], 0, v[36:37]
	v_lshl_add_u64 v[42:43], v[66:67], 0, v[36:37]
	s_add_i32 s85, s85, s86
	s_cmpk_lt_i32 s85, 0x180
	v_add_u32_e32 v28, s2, v28
	s_waitcnt vmcnt(0) lgkmcnt(0)
	v_lshlrev_b32_e32 v78, 16, v46
	v_and_b32_e32 v79, 0xffff0000, v46
	v_lshlrev_b32_e32 v80, 16, v47
	v_and_b32_e32 v81, 0xffff0000, v47
	v_mul_f32 v162, v78, v78
	v_mul_f32 v163, v79, v79
	v_mul_f32 v164, v80, v80
	v_mul_f32 v165, v81, v81
	v_add_f32_e32 v29, v162, v163
	v_lshlrev_b32_e32 v166, 16, v102
	v_and_b32_e32 v167, 0xffff0000, v102
	v_lshlrev_b32_e32 v102, 16, v103
	v_and_b32_e32 v103, 0xffff0000, v103
	v_lshlrev_b32_e32 v174, 16, v110
	v_and_b32_e32 v175, 0xffff0000, v110
	v_lshlrev_b32_e32 v182, 16, v118
	v_and_b32_e32 v183, 0xffff0000, v118
	v_mul_f32 v0, v0, v146
	v_mul_f32 v1, v1, v147
	v_mul_f32 v8, v8, v154
	v_mul_f32 v9, v9, v155
	v_mul_f32 v154, v166, v166
	v_mul_f32 v155, v167, v167
	v_lshlrev_b32_e32 v110, 16, v111
	v_and_b32_e32 v111, 0xffff0000, v111
	v_lshlrev_b32_e32 v118, 16, v119
	v_and_b32_e32 v119, 0xffff0000, v119
	v_mul_f32 v2, v2, v148
	v_mul_f32 v3, v3, v149
	v_mul_f32 v10, v10, v156
	v_mul_f32 v11, v11, v157
	v_mul_f32 v156, v102, v102
	v_mul_f32 v157, v103, v103
	v_mul_f32 v216, v174, v174
	v_mul_f32 v217, v175, v175
	v_mul_f32 v232, v182, v182
	v_mul_f32 v233, v183, v183
	v_mul_f32 v242, v24, v0
	v_mul_f32 v243, v25, v1
	v_add_f32_e32 v1, v154, v155
	v_lshlrev_b32_e32 v82, 16, v48
	v_and_b32_e32 v83, 0xffff0000, v48
	v_lshlrev_b32_e32 v168, 16, v104
	v_and_b32_e32 v169, 0xffff0000, v104
	v_mul_f32 v218, v110, v110
	v_mul_f32 v219, v111, v111
	v_mul_f32 v234, v118, v118
	v_mul_f32 v235, v119, v119
	v_mul_f32 v240, v32, v2
	v_mul_f32 v241, v33, v3
	v_add_f32_e32 v0, v164, v29
	v_add_f32_e32 v2, v216, v217
	v_add_f32_e32 v3, v232, v233
	v_add_f32_e32 v1, v156, v1
	v_mul_f32 v158, v82, v82
	v_mul_f32 v159, v83, v83
	v_lshlrev_b32_e32 v176, 16, v112
	v_and_b32_e32 v177, 0xffff0000, v112
	v_lshlrev_b32_e32 v184, 16, v120
	v_and_b32_e32 v185, 0xffff0000, v120
	v_mul_f32 v12, v12, v150
	v_mul_f32 v13, v13, v151
	v_mul_f32 v150, v168, v168
	v_mul_f32 v151, v169, v169
	v_add_f32_e32 v0, v165, v0
	v_add_f32_e32 v2, v218, v2
	v_add_f32_e32 v3, v234, v3
	v_add_f32_e32 v1, v157, v1
	v_lshlrev_b32_e32 v84, 16, v49
	v_and_b32_e32 v85, 0xffff0000, v49
	v_lshlrev_b32_e32 v104, 16, v105
	v_and_b32_e32 v105, 0xffff0000, v105
	v_mul_f32 v212, v176, v176
	v_mul_f32 v213, v177, v177
	v_mul_f32 v228, v184, v184
	v_mul_f32 v229, v185, v185
	v_add_f32_e32 v0, v158, v0
	v_add_f32_e32 v2, v219, v2
	v_add_f32_e32 v3, v235, v3
	v_add_f32_e32 v1, v150, v1
	v_mul_f32 v160, v84, v84
	v_mul_f32 v161, v85, v85
	v_lshlrev_b32_e32 v112, 16, v113
	v_and_b32_e32 v113, 0xffff0000, v113
	v_lshlrev_b32_e32 v120, 16, v121
	v_and_b32_e32 v121, 0xffff0000, v121
	v_mul_f32 v14, v14, v152
	v_mul_f32 v15, v15, v153
	v_mul_f32 v152, v104, v104
	v_mul_f32 v153, v105, v105
	v_add_f32_e32 v0, v159, v0
	v_add_f32_e32 v2, v212, v2
	v_add_f32_e32 v3, v228, v3
	v_add_f32_e32 v1, v151, v1
	v_lshlrev_b32_e32 v86, 16, v50
	v_and_b32_e32 v87, 0xffff0000, v50
	v_lshlrev_b32_e32 v170, 16, v106
	v_and_b32_e32 v171, 0xffff0000, v106
	v_mul_f32 v214, v112, v112
	v_mul_f32 v215, v113, v113
	v_mul_f32 v230, v120, v120
	v_mul_f32 v231, v121, v121
	v_add_f32_e32 v0, v160, v0
	v_add_f32_e32 v2, v213, v2
	v_add_f32_e32 v3, v229, v3
	v_add_f32_e32 v1, v152, v1
	v_lshlrev_b32_e32 v90, 16, v52
	v_and_b32_e32 v91, 0xffff0000, v52
	v_lshlrev_b32_e32 v92, 16, v53
	v_and_b32_e32 v93, 0xffff0000, v53
	v_lshlrev_b32_e32 v52, 16, v98
	v_and_b32_e32 v53, 0xffff0000, v98
	v_lshlrev_b32_e32 v58, 16, v99
	v_and_b32_e32 v59, 0xffff0000, v99
	v_mul_f32 v98, v86, v86
	v_mul_f32 v99, v87, v87
	v_lshlrev_b32_e32 v178, 16, v114
	v_and_b32_e32 v179, 0xffff0000, v114
	v_lshlrev_b32_e32 v186, 16, v122
	v_and_b32_e32 v187, 0xffff0000, v122
	v_mul_f32 v146, v170, v170
	v_mul_f32 v147, v171, v171
	v_add_f32_e32 v0, v161, v0
	v_add_f32_e32 v2, v214, v2
	v_add_f32_e32 v3, v230, v3
	v_add_f32_e32 v1, v153, v1
	v_lshlrev_b32_e32 v88, 16, v51
	v_and_b32_e32 v89, 0xffff0000, v51
	v_lshlrev_b32_e32 v106, 16, v107
	v_and_b32_e32 v107, 0xffff0000, v107
	v_mul_f32 v208, v178, v178
	v_mul_f32 v209, v179, v179
	v_mul_f32 v224, v186, v186
	v_mul_f32 v225, v187, v187
	v_add_f32_e32 v0, v98, v0
	v_add_f32_e32 v2, v215, v2
	v_add_f32_e32 v3, v231, v3
	v_add_f32_e32 v1, v146, v1
	v_lshlrev_b32_e32 v64, 16, v56
	v_and_b32_e32 v65, 0xffff0000, v56
	v_lshlrev_b32_e32 v70, 16, v57
	v_and_b32_e32 v71, 0xffff0000, v57
	v_lshlrev_b32_e32 v56, 16, v100
	v_and_b32_e32 v57, 0xffff0000, v100
	v_lshlrev_b32_e32 v62, 16, v101
	v_and_b32_e32 v63, 0xffff0000, v101
	v_mul_f32 v100, v88, v88
	v_mul_f32 v101, v89, v89
	v_lshlrev_b32_e32 v114, 16, v115
	v_and_b32_e32 v115, 0xffff0000, v115
	v_lshlrev_b32_e32 v122, 16, v123
	v_and_b32_e32 v123, 0xffff0000, v123
	v_mul_f32 v148, v106, v106
	v_mul_f32 v149, v107, v107
	v_add_f32_e32 v0, v99, v0
	v_add_f32_e32 v2, v208, v2
	v_add_f32_e32 v3, v224, v3
	v_add_f32_e32 v1, v147, v1
	v_lshlrev_b32_e32 v172, 16, v108
	v_and_b32_e32 v173, 0xffff0000, v108
	v_mul_f32 v210, v114, v114
	v_mul_f32 v211, v115, v115
	v_mul_f32 v226, v122, v122
	v_mul_f32 v227, v123, v123
	v_add_f32_e32 v0, v100, v0
	v_add_f32_e32 v2, v209, v2
	v_add_f32_e32 v3, v225, v3
	v_add_f32_e32 v1, v148, v1
	v_lshlrev_b32_e32 v46, 16, v94
	v_and_b32_e32 v47, 0xffff0000, v94
	v_lshlrev_b32_e32 v50, 16, v95
	v_and_b32_e32 v51, 0xffff0000, v95
	v_mul_f32 v94, v90, v90
	v_mul_f32 v95, v91, v91
	v_lshlrev_b32_e32 v180, 16, v116
	v_and_b32_e32 v181, 0xffff0000, v116
	v_lshlrev_b32_e32 v188, 16, v124
	v_and_b32_e32 v189, 0xffff0000, v124
	v_mul_f32 v4, v4, v142
	v_mul_f32 v5, v5, v143
	v_mul_f32 v142, v172, v172
	v_mul_f32 v143, v173, v173
	v_add_f32_e32 v0, v101, v0
	v_add_f32_e32 v2, v210, v2
	v_add_f32_e32 v3, v226, v3
	v_add_f32_e32 v1, v149, v1
	v_lshlrev_b32_e32 v108, 16, v109
	v_and_b32_e32 v109, 0xffff0000, v109
	v_mul_f32 v162, v180, v180
	v_mul_f32 v163, v181, v181
	v_mul_f32 v220, v188, v188
	v_mul_f32 v221, v189, v189
	v_add_f32_e32 v0, v94, v0
	v_add_f32_e32 v2, v211, v2
	v_add_f32_e32 v3, v227, v3
	v_add_f32_e32 v1, v142, v1
	v_lshlrev_b32_e32 v60, 16, v54
	v_and_b32_e32 v61, 0xffff0000, v54
	v_lshlrev_b32_e32 v66, 16, v55
	v_and_b32_e32 v67, 0xffff0000, v55
	v_lshlrev_b32_e32 v48, 16, v96
	v_and_b32_e32 v49, 0xffff0000, v96
	v_lshlrev_b32_e32 v54, 16, v97
	v_and_b32_e32 v55, 0xffff0000, v97
	v_mul_f32 v96, v92, v92
	v_mul_f32 v97, v93, v93
	v_lshlrev_b32_e32 v116, 16, v117
	v_and_b32_e32 v117, 0xffff0000, v117
	v_lshlrev_b32_e32 v124, 16, v125
	v_and_b32_e32 v125, 0xffff0000, v125
	v_mul_f32 v6, v6, v144
	v_mul_f32 v7, v7, v145
	v_mul_f32 v144, v108, v108
	v_mul_f32 v145, v109, v109
	v_add_f32_e32 v0, v95, v0
	v_add_f32_e32 v2, v162, v2
	v_add_f32_e32 v3, v220, v3
	v_add_f32_e32 v1, v143, v1
	v_mul_f32 v206, v116, v116
	v_mul_f32 v207, v117, v117
	v_mul_f32 v222, v124, v124
	v_mul_f32 v223, v125, v125
	v_add_f32_e32 v0, v96, v0
	v_add_f32_e32 v2, v163, v2
	v_add_f32_e32 v3, v221, v3
	v_add_f32_e32 v1, v144, v1
	v_add_f32_e32 v0, v97, v0
	v_add_f32_e32 v2, v206, v2
	v_add_f32_e32 v3, v222, v3
	v_add_f32_e32 v1, v145, v1
	v_add_f32_dpp v0, v0, v0 quad_perm:[1,0,3,2] row_mask:0xf bank_mask:0xf bound_ctrl:1
	v_add_f32_e32 v2, v207, v2
	v_add_f32_e32 v3, v223, v3
	v_add_f32_dpp v1, v1, v1 quad_perm:[1,0,3,2] row_mask:0xf bank_mask:0xf bound_ctrl:1
	v_add_f32_dpp v0, v0, v0 quad_perm:[2,3,0,1] row_mask:0xf bank_mask:0xf bound_ctrl:1
	v_add_f32_dpp v2, v2, v2 quad_perm:[1,0,3,2] row_mask:0xf bank_mask:0xf bound_ctrl:1
	v_add_f32_dpp v3, v3, v3 quad_perm:[1,0,3,2] row_mask:0xf bank_mask:0xf bound_ctrl:1
	v_add_f32_dpp v1, v1, v1 quad_perm:[2,3,0,1] row_mask:0xf bank_mask:0xf bound_ctrl:1
	v_add_f32_dpp v0, v0, v0 row_half_mirror row_mask:0xf bank_mask:0xf bound_ctrl:1
	v_add_f32_dpp v2, v2, v2 quad_perm:[2,3,0,1] row_mask:0xf bank_mask:0xf bound_ctrl:1
	v_add_f32_dpp v3, v3, v3 quad_perm:[2,3,0,1] row_mask:0xf bank_mask:0xf bound_ctrl:1
	v_add_f32_dpp v1, v1, v1 row_half_mirror row_mask:0xf bank_mask:0xf bound_ctrl:1
	v_mul_f32 v238, v24, v4
	v_mul_f32 v239, v25, v5
	v_add_f32_dpp v0, v0, v0 row_mirror row_mask:0xf bank_mask:0xf bound_ctrl:1
	v_add_f32_dpp v2, v2, v2 row_half_mirror row_mask:0xf bank_mask:0xf bound_ctrl:1
	v_add_f32_dpp v3, v3, v3 row_half_mirror row_mask:0xf bank_mask:0xf bound_ctrl:1
	v_add_f32_dpp v5, v1, v1 row_mirror row_mask:0xf bank_mask:0xf bound_ctrl:1
	v_mul_f32 v236, v32, v6
	v_mul_f32 v237, v33, v7
	v_mov_b32_e32 v4, v0
	v_add_f32_dpp v2, v2, v2 row_mirror row_mask:0xf bank_mask:0xf bound_ctrl:1
	v_add_f32_dpp v6, v3, v3 row_mirror row_mask:0xf bank_mask:0xf bound_ctrl:1
	v_mov_b32_e32 v7, v5
	v_mul_f32 v250, v24, v8
	v_mul_f32 v251, v25, v9
	v_permlane16_swap_b32_e32 v0, v4
	v_mov_b32_e32 v8, v2
	v_mov_b32_e32 v9, v6
	v_permlane16_swap_b32_e32 v5, v7
	v_add_f32_e32 v1, v0, v4
	v_permlane16_swap_b32_e32 v2, v8
	v_permlane16_swap_b32_e32 v6, v9
	v_add_f32_e32 v0, v5, v7
	v_mov_b32_e32 v3, v1
	v_add_f32_e32 v5, v2, v8
	v_add_f32_e32 v4, v6, v9
	v_mov_b32_e32 v2, v0
	v_permlane32_swap_b32_e32 v1, v3
	v_mov_b32_e32 v7, v5
	v_mov_b32_e32 v6, v4
	v_permlane32_swap_b32_e32 v0, v2
	v_permlane32_swap_b32_e32 v5, v7
	v_permlane32_swap_b32_e32 v4, v6
	v_add_f32 v0, v0, v2
	v_add_f32 v1, v1, v3
	v_add_f32 v2, v4, v6
	v_add_f32 v3, v5, v7
	v_fma_f32 v0, v0, s8, v34
	v_fma_f32 v1, v1, s8, v34
	v_fma_f32 v2, v2, s8, v34
	v_fma_f32 v3, v3, s8, v34
	v_mul_f32_e32 v4, 0x4b800000, v1
	v_cmp_gt_f32_e64 s[6:7], s10, v1
	v_mul_f32_e32 v5, 0x4b800000, v0
	v_cmp_gt_f32_e32 vcc, s10, v0
	v_mul_f32_e32 v6, 0x4b800000, v3
	v_mul_f32_e32 v7, 0x4b800000, v2
	v_cmp_gt_f32_e64 s[0:1], s10, v2
	v_cmp_gt_f32_e64 s[4:5], s10, v3
	v_cndmask_b32_e64 v1, v1, v4, s[6:7]
	v_cndmask_b32_e32 v0, v0, v5, vcc
	v_cndmask_b32_e64 v3, v3, v6, s[4:5]
	v_cndmask_b32_e64 v2, v2, v7, s[0:1]
	v_rsq_f32_e32 v1, v1
	v_rsq_f32_e32 v4, v0
	v_rsq_f32_e32 v3, v3
	v_rsq_f32_e32 v5, v2
	v_mul_f32_e32 v0, 0x45800000, v1
	v_mul_f32_e32 v2, 0x45800000, v4
	v_mul_f32_e32 v6, 0x45800000, v3
	v_mul_f32_e32 v7, 0x45800000, v5
	v_cndmask_b32_e64 v0, v1, v0, s[6:7]
	v_mul_f32 v248, v32, v10
	v_mul_f32 v249, v33, v11
	v_cndmask_b32_e32 v2, v4, v2, vcc
	v_cndmask_b32_e64 v4, v3, v6, s[4:5]
	v_cndmask_b32_e64 v6, v5, v7, s[0:1]
	v_mul_f32 v8, v0, v78
	v_mul_f32 v9, v0, v79
	v_mul_f32 v10, v0, v80
	v_mul_f32 v11, v0, v81
	v_lshlrev_b32_e32 v68, 16, v74
	v_and_b32_e32 v69, 0xffff0000, v74
	v_lshlrev_b32_e32 v74, 16, v75
	v_and_b32_e32 v75, 0xffff0000, v75
	v_lshlrev_b32_e32 v72, 16, v76
	v_and_b32_e32 v73, 0xffff0000, v76
	v_lshlrev_b32_e32 v76, 16, v77
	v_and_b32_e32 v77, 0xffff0000, v77
	v_lshlrev_b32_e32 v190, 16, v126
	v_and_b32_e32 v191, 0xffff0000, v126
	v_lshlrev_b32_e32 v126, 16, v127
	v_and_b32_e32 v127, 0xffff0000, v127
	v_lshlrev_b32_e32 v192, 16, v128
	v_and_b32_e32 v193, 0xffff0000, v128
	v_lshlrev_b32_e32 v128, 16, v129
	v_and_b32_e32 v129, 0xffff0000, v129
	v_lshlrev_b32_e32 v194, 16, v130
	v_and_b32_e32 v195, 0xffff0000, v130
	v_lshlrev_b32_e32 v130, 16, v131
	v_and_b32_e32 v131, 0xffff0000, v131
	v_lshlrev_b32_e32 v196, 16, v132
	v_and_b32_e32 v197, 0xffff0000, v132
	v_lshlrev_b32_e32 v132, 16, v133
	v_and_b32_e32 v133, 0xffff0000, v133
	v_lshlrev_b32_e32 v198, 16, v134
	v_and_b32_e32 v199, 0xffff0000, v134
	v_lshlrev_b32_e32 v134, 16, v135
	v_and_b32_e32 v135, 0xffff0000, v135
	v_lshlrev_b32_e32 v200, 16, v136
	v_and_b32_e32 v201, 0xffff0000, v136
	v_lshlrev_b32_e32 v136, 16, v137
	v_and_b32_e32 v137, 0xffff0000, v137
	v_lshlrev_b32_e32 v202, 16, v138
	v_and_b32_e32 v203, 0xffff0000, v138
	v_lshlrev_b32_e32 v138, 16, v139
	v_and_b32_e32 v139, 0xffff0000, v139
	v_lshlrev_b32_e32 v204, 16, v140
	v_and_b32_e32 v205, 0xffff0000, v140
	v_lshlrev_b32_e32 v140, 16, v141
	v_and_b32_e32 v141, 0xffff0000, v141
	v_mul_f32 v244, v32, v14
	v_mul_f32 v245, v33, v15
	v_mul_f32 v246, v24, v12
	v_mul_f32 v247, v25, v13
	v_mul_f32 v12, v0, v82
	v_mul_f32 v13, v0, v83
	v_mul_f32 v14, v0, v84
	v_mul_f32 v15, v0, v85
	v_mul_f32 v78, v0, v86
	v_mul_f32 v79, v0, v87
	v_mul_f32 v80, v0, v88
	v_mul_f32 v81, v0, v89
	v_mul_f32 v82, v0, v90
	v_mul_f32 v83, v0, v91
	v_mul_f32 v84, v0, v92
	v_mul_f32 v85, v0, v93
	v_mul_f32 v86, v2, v166
	v_mul_f32 v87, v2, v167
	v_mul_f32 v88, v2, v102
	v_mul_f32 v89, v2, v103
	v_mul_f32 v90, v2, v168
	v_mul_f32 v91, v2, v169
	v_mul_f32 v92, v2, v104
	v_mul_f32 v93, v2, v105
	v_mul_f32 v94, v2, v170
	v_mul_f32 v95, v2, v171
	v_mul_f32 v96, v2, v106
	v_mul_f32 v97, v2, v107
	v_mul_f32 v98, v2, v172
	v_mul_f32 v99, v2, v173
	v_mul_f32 v100, v2, v108
	v_mul_f32 v101, v2, v109
	v_mul_f32 v102, v4, v174
	v_mul_f32 v103, v4, v175
	v_mul_f32 v104, v4, v110
	v_mul_f32 v105, v4, v111
	v_mul_f32 v106, v4, v176
	v_mul_f32 v107, v4, v177
	v_mul_f32 v108, v4, v112
	v_mul_f32 v109, v4, v113
	v_mul_f32 v110, v4, v178
	v_mul_f32 v111, v4, v179
	v_mul_f32 v112, v4, v114
	v_mul_f32 v113, v4, v115
	v_mul_f32 v114, v4, v180
	v_mul_f32 v115, v4, v181
	v_mul_f32 v116, v4, v116
	v_mul_f32 v117, v4, v117
	v_mul_f32 v142, v6, v182
	v_mul_f32 v143, v6, v183
	v_mul_f32 v118, v6, v118
	v_mul_f32 v119, v6, v119
	v_mul_f32 v144, v6, v184
	v_mul_f32 v145, v6, v185
	v_mul_f32 v120, v6, v120
	v_mul_f32 v121, v6, v121
	v_mul_f32 v146, v6, v186
	v_mul_f32 v147, v6, v187
	v_mul_f32 v122, v6, v122
	v_mul_f32 v123, v6, v123
	v_mul_f32 v148, v6, v188
	v_mul_f32 v149, v6, v189
	v_mul_f32 v124, v6, v124
	v_mul_f32 v125, v6, v125
	v_fma_f32 v2, v236, v10, v66
	v_fma_f32 v3, v237, v11, v67
	v_fma_f32 v0, v238, v8, v60
	v_fma_f32 v1, v239, v9, v61
	v_fma_f32 v6, v240, v14, v70
	v_fma_f32 v7, v241, v15, v71
	v_fma_f32 v4, v242, v12, v64
	v_fma_f32 v5, v243, v13, v65
	v_fma_f32 v10, v244, v80, v74
	v_fma_f32 v11, v245, v81, v75
	v_fma_f32 v8, v246, v78, v68
	v_fma_f32 v9, v247, v79, v69
	v_fma_f32 v14, v248, v84, v76
	v_fma_f32 v15, v249, v85, v77
	v_fma_f32 v12, v250, v82, v72
	v_fma_f32 v13, v251, v83, v73
	v_fma_f32 v66, v236, v88, v126
	v_fma_f32 v67, v237, v89, v127
	v_fma_f32 v64, v238, v86, v190
	v_fma_f32 v65, v239, v87, v191
	v_fma_f32 v70, v240, v92, v128
	v_fma_f32 v71, v241, v93, v129
	v_fma_f32 v68, v242, v90, v192
	v_fma_f32 v69, v243, v91, v193
	v_fma_f32 v74, v244, v96, v130
	v_fma_f32 v75, v245, v97, v131
	v_fma_f32 v72, v246, v94, v194
	v_fma_f32 v73, v247, v95, v195
	v_fma_f32 v78, v248, v100, v132
	v_fma_f32 v79, v249, v101, v133
	v_fma_f32 v76, v250, v98, v196
	v_fma_f32 v77, v251, v99, v197
	v_fma_f32 v82, v236, v104, v134
	v_fma_f32 v83, v237, v105, v135
	v_fma_f32 v80, v238, v102, v198
	v_fma_f32 v81, v239, v103, v199
	v_fma_f32 v86, v240, v108, v136
	v_fma_f32 v87, v241, v109, v137
	v_fma_f32 v84, v242, v106, v200
	v_fma_f32 v85, v243, v107, v201
	v_fma_f32 v90, v244, v112, v138
	v_fma_f32 v91, v245, v113, v139
	v_fma_f32 v88, v246, v110, v202
	v_fma_f32 v89, v247, v111, v203
	v_fma_f32 v94, v248, v116, v140
	v_fma_f32 v95, v249, v117, v141
	v_fma_f32 v92, v250, v114, v204
	v_fma_f32 v93, v251, v115, v205
	v_fma_f32 v98, v236, v118, v50
	v_fma_f32 v99, v237, v119, v51
	v_fma_f32 v96, v238, v142, v46
	v_fma_f32 v97, v239, v143, v47
	v_fma_f32 v50, v240, v120, v54
	v_fma_f32 v51, v241, v121, v55
	v_fma_f32 v48, v242, v144, v48
	v_fma_f32 v49, v243, v145, v49
	v_fma_f32 v54, v244, v122, v58
	v_fma_f32 v55, v245, v123, v59
	v_fma_f32 v52, v246, v146, v52
	v_fma_f32 v53, v247, v147, v53
	v_fma_f32 v58, v248, v124, v62
	v_fma_f32 v59, v249, v125, v63
	v_fma_f32 v56, v250, v148, v56
	v_fma_f32 v57, v251, v149, v57
	flat_store_dwordx4 v[38:39], v[0:3]
	flat_store_dwordx4 v[38:39], v[4:7] offset:16
	flat_store_dwordx4 v[38:39], v[8:11] offset:2048
	flat_store_dwordx4 v[38:39], v[12:15] offset:2064
	flat_store_dwordx4 v[44:45], v[64:67]
	flat_store_dwordx4 v[44:45], v[68:71] offset:16
	flat_store_dwordx4 v[44:45], v[72:75] offset:2048
	flat_store_dwordx4 v[44:45], v[76:79] offset:2064
	flat_store_dwordx4 v[42:43], v[80:83]
	flat_store_dwordx4 v[42:43], v[84:87] offset:16
	flat_store_dwordx4 v[42:43], v[88:91] offset:2048
	flat_store_dwordx4 v[42:43], v[92:95] offset:2064
	flat_store_dwordx4 v[40:41], v[96:99]
	flat_store_dwordx4 v[40:41], v[48:51] offset:16
	flat_store_dwordx4 v[40:41], v[52:55] offset:2048
	flat_store_dwordx4 v[40:41], v[56:59] offset:2064
	s_cbranch_scc1 .LBB0_3564
